# v93 + GEMM K-loops: back edge rotated in front of the loop-back barrier (barrier is the loop head, exit path has its own barrier copy)
# speedup vs baseline: 1.0017x; 1.0017x over previous
; #define PG8_STAGE(bufoff, gbase, voff) do { _Pragma("unroll") for (int _i = 0; _i < 2; ++_i) \
;         __builtin_amdgcn_global_load_lds((const unsigned*)((const char*)(gbase) + (voff)[_i]), (LAS unsigned*)(lds + (bufoff) + ldsw + _i * 8192), 16, 0, 0); } while (0)
; #define PG8_LDA(dst, b, h) do { _Pragma("unroll") for (int m = 0; m < 4; ++m) _Pragma("unroll") for (int k = 0; k < 2; ++k) dst[m][k] = *(const LAS bf16x8*)(lds + PG8_SA(b, h) + aoff + m * 2048 + k * 1024); } while (0)
; #define PG8_LDB(dst, b, h) do { _Pragma("unroll") for (int n = 0; n < 2; ++n) _Pragma("unroll") for (int k = 0; k < 2; ++k) dst[n][k] = *(const LAS bf16x8*)(lds + PG8_SB(b, h) + boff + n * 2048 + k * 1024); } while (0)
; #define PG8_SCHED __builtin_amdgcn_sched_barrier(0)
; template <class Epi>
; DI void gemm_phase(LAS unsigned char* lds, int wid, int K, int lda, int ldb, bool bperm, const Sched3& S, const Epi& E) {
;     ...
;         const char* nA = has_next ? nxt.A : cA; const char* nB = has_next ? nxt.B : cB; const size_t nhA = has_next ? (nxt.half ? (size_t)0 : hstepA) : hA; const bool full = (cur.half == 0);
;         for (int t = 0; t < nt; t += 2) {
;             const bool last = (t == nt - 2);
;             const char* a1 = cA + (size_t)(t + 1) * kstep;
;             const char* a2 = last ? nA : cA + (size_t)(t + 2) * kstep; const char* b2 = last ? nB : cB + (size_t)(t + 2) * kstep;
;             const char* a3 = a2 + kstep; const char* b3 = b2 + kstep; const size_t h2 = last ? nhA : hA;
;             PG8_LDB(B0, 0, 0); PG8_SCHED; PG8_LDA(At, 0, 0); PG8_STAGE(PG8_SA(1, 1), a1 + hA, voffA);
.LBB0_326:
	s_xor_b64 s[44:45], s[52:53], -1
	s_and_b64 s[50:51], s[52:53], exec
	s_cselect_b32 s5, s41, s47
	s_cselect_b32 s37, s40, s46
	s_cselect_b32 s39, s43, s49
	s_cselect_b32 s52, s42, s48
	s_add_u32 s46, s46, 0x80080
	s_addc_u32 s47, s47, 0
	s_add_u32 s53, s48, 0x100
	s_nop 0
	s_addc_u32 s54, s49, 0
	s_mov_b32 s55, -2
	s_waitcnt lgkmcnt(0)
	ds_read_b128 v[128:131], v230
	ds_read_b128 v[132:135], v230 offset:1024
	ds_read_b128 v[136:139], v230 offset:2048
	ds_read_b128 v[156:159], v230 offset:3072
	s_add_u32 s48, s46, 0xfff80080
	s_addc_u32 s49, s47, -1
	s_cmp_eq_u32 s55, 28
	s_cselect_b32 s51, s5, s49
	s_cselect_b32 s50, s37, s48
	s_cselect_b32 s49, s39, s54
	s_cselect_b32 s48, s52, s53

; #define PG8_STAGE(bufoff, gbase, voff) do { _Pragma("unroll") for (int _i = 0; _i < 2; ++_i) \
;         __builtin_amdgcn_global_load_lds((const unsigned*)((const char*)(gbase) + (voff)[_i]), (LAS unsigned*)(lds + (bufoff) + ldsw + _i * 8192), 16, 0, 0); } while (0)
; #define PG8_LDA(dst, b, h) do { _Pragma("unroll") for (int m = 0; m < 4; ++m) _Pragma("unroll") for (int k = 0; k < 2; ++k) dst[m][k] = *(const LAS bf16x8*)(lds + PG8_SA(b, h) + aoff + m * 2048 + k * 1024); } while (0)
; #define PG8_LDB(dst, b, h) do { _Pragma("unroll") for (int n = 0; n < 2; ++n) _Pragma("unroll") for (int k = 0; k < 2; ++k) dst[n][k] = *(const LAS bf16x8*)(lds + PG8_SB(b, h) + boff + n * 2048 + k * 1024); } while (0)
; #define PG8_SCHED __builtin_amdgcn_sched_barrier(0)
; template <class Epi>
; DI void gemm_phase(LAS unsigned char* lds, int wid, int K, int lda, int ldb, bool bperm, const Sched3& S, const Epi& E) {
;     ...
;             PG8_LDB(B0, 0, 0); PG8_SCHED; PG8_LDA(At, 0, 0); PG8_STAGE(PG8_SA(1, 1), a1 + hA, voffA);
	s_add_i32 m0, s58, 0xc000
	ds_read_b128 v[160:163], v231
	ds_read_b128 v[164:167], v231 offset:1024
	ds_read_b128 v[168:171], v231 offset:2048
	ds_read_b128 v[172:175], v231 offset:3072
	ds_read_b128 v[176:179], v231 offset:4096
	ds_read_b128 v[180:183], v231 offset:5120
	ds_read_b128 v[184:187], v231 offset:6144
	ds_read_b128 v[188:191], v231 offset:7168
	global_load_lds_dwordx4 v148, s[46:47]

; #define PG8_STAGE(bufoff, gbase, voff) do { _Pragma("unroll") for (int _i = 0; _i < 2; ++_i) \
;         __builtin_amdgcn_global_load_lds((const unsigned*)((const char*)(gbase) + (voff)[_i]), (LAS unsigned*)(lds + (bufoff) + ldsw + _i * 8192), 16, 0, 0); } while (0)
; #define PG8_LDA(dst, b, h) do { _Pragma("unroll") for (int m = 0; m < 4; ++m) _Pragma("unroll") for (int k = 0; k < 2; ++k) dst[m][k] = *(const LAS bf16x8*)(lds + PG8_SA(b, h) + aoff + m * 2048 + k * 1024); } while (0)
; #define PG8_LDB(dst, b, h) do { _Pragma("unroll") for (int n = 0; n < 2; ++n) _Pragma("unroll") for (int k = 0; k < 2; ++k) dst[n][k] = *(const LAS bf16x8*)(lds + PG8_SB(b, h) + boff + n * 2048 + k * 1024); } while (0)
; #define PG8_MMA(ai, bj, At, Bt) do { __builtin_amdgcn_s_setprio(1); _Pragma("unroll") for (int m = 0; m < 4; ++m) _Pragma("unroll") for (int n = 0; n < 2; ++n) _Pragma("unroll") for (int k = 0; k < 2; ++k) \
;         acc[ai][bj][m][n] = __builtin_amdgcn_mfma_f32_16x16x32_bf16(Bt[n][k], At[m][k], acc[ai][bj][m][n], 0, 0, 0); __builtin_amdgcn_s_setprio(0); } while (0)
; #define PG8_WAIT_L(n) asm volatile("s_waitcnt lgkmcnt(" #n ")" ::: "memory")
; #define PG8_BAR __builtin_amdgcn_s_barrier()
; #define PG8_SCHED __builtin_amdgcn_sched_barrier(0)
; template <class Epi>
; DI void gemm_phase(LAS unsigned char* lds, int wid, int K, int lda, int ldb, bool bperm, const Sched3& S, const Epi& E) {
;     ...
;             PG8_LDB(B0, 0, 0); PG8_SCHED; PG8_LDA(At, 0, 0); PG8_STAGE(PG8_SA(1, 1), a1 + hA, voffA);
;             PG8_WAIT_L(8); PG8_BAR; PG8_WAIT_L(0); PG8_MMA(0, 0, At, B0); PG8_BAR; PG8_SCHED;
	s_add_i32 m0, s58, 0xe000
	s_nop 0
	global_load_lds_dwordx4 v150, s[46:47]
	s_waitcnt lgkmcnt(8)
	s_barrier
	s_waitcnt lgkmcnt(0)
	s_setprio 1
	s_waitcnt lgkmcnt(0)
	v_mfma_f32_16x16x32_bf16 v[124:127], v[128:131], v[160:163], 0
	v_mfma_f32_16x16x32_bf16 v[120:123], v[136:139], v[160:163], 0
	v_mfma_f32_16x16x32_bf16 v[108:111], v[128:131], v[168:171], 0
	v_mfma_f32_16x16x32_bf16 v[104:107], v[136:139], v[168:171], 0
	v_mfma_f32_16x16x32_bf16 v[92:95], v[128:131], v[176:179], 0
	v_mfma_f32_16x16x32_bf16 v[88:91], v[136:139], v[176:179], 0
	v_mfma_f32_16x16x32_bf16 v[76:79], v[128:131], v[184:187], 0
	v_mfma_f32_16x16x32_bf16 v[72:75], v[136:139], v[184:187], 0
	v_mfma_f32_16x16x32_bf16 v[124:127], v[132:135], v[164:167], v[124:127]
	v_mfma_f32_16x16x32_bf16 v[120:123], v[156:159], v[164:167], v[120:123]
	v_mfma_f32_16x16x32_bf16 v[108:111], v[132:135], v[172:175], v[108:111]
	v_mfma_f32_16x16x32_bf16 v[104:107], v[156:159], v[172:175], v[104:107]
	v_mfma_f32_16x16x32_bf16 v[92:95], v[132:135], v[180:183], v[92:95]
	v_mfma_f32_16x16x32_bf16 v[88:91], v[156:159], v[180:183], v[88:91]
	v_mfma_f32_16x16x32_bf16 v[76:79], v[132:135], v[188:191], v[76:79]
	v_mfma_f32_16x16x32_bf16 v[72:75], v[156:159], v[188:191], v[72:75]
	s_setprio 0
	s_barrier
	s_add_i32 s75, s67, s57

; #define PG8_STAGE(bufoff, gbase, voff) do { _Pragma("unroll") for (int _i = 0; _i < 2; ++_i) \
;         __builtin_amdgcn_global_load_lds((const unsigned*)((const char*)(gbase) + (voff)[_i]), (LAS unsigned*)(lds + (bufoff) + ldsw + _i * 8192), 16, 0, 0); } while (0)
; #define PG8_LDB(dst, b, h) do { _Pragma("unroll") for (int n = 0; n < 2; ++n) _Pragma("unroll") for (int k = 0; k < 2; ++k) dst[n][k] = *(const LAS bf16x8*)(lds + PG8_SB(b, h) + boff + n * 2048 + k * 1024); } while (0)
; template <class Epi>
; DI void gemm_phase(LAS unsigned char* lds, int wid, int K, int lda, int ldb, bool bperm, const Sched3& S, const Epi& E) {
;     ...
;             PG8_LDB(B1, 0, 1); PG8_STAGE(PG8_SB(0, 0), b2, voffB);
	s_mov_b32 m0, s75
	ds_read_b128 v[192:195], v232
	ds_read_b128 v[196:199], v232 offset:1024
	ds_read_b128 v[200:203], v232 offset:2048
	ds_read_b128 v[204:207], v232 offset:3072
	global_load_lds_dwordx4 v142, s[48:49]

; #define PG8_STAGE(bufoff, gbase, voff) do { _Pragma("unroll") for (int _i = 0; _i < 2; ++_i) \
;         __builtin_amdgcn_global_load_lds((const unsigned*)((const char*)(gbase) + (voff)[_i]), (LAS unsigned*)(lds + (bufoff) + ldsw + _i * 8192), 16, 0, 0); } while (0)
; #define PG8_LDA(dst, b, h) do { _Pragma("unroll") for (int m = 0; m < 4; ++m) _Pragma("unroll") for (int k = 0; k < 2; ++k) dst[m][k] = *(const LAS bf16x8*)(lds + PG8_SA(b, h) + aoff + m * 2048 + k * 1024); } while (0)
; #define PG8_LDB(dst, b, h) do { _Pragma("unroll") for (int n = 0; n < 2; ++n) _Pragma("unroll") for (int k = 0; k < 2; ++k) dst[n][k] = *(const LAS bf16x8*)(lds + PG8_SB(b, h) + boff + n * 2048 + k * 1024); } while (0)
; #define PG8_MMA(ai, bj, At, Bt) do { __builtin_amdgcn_s_setprio(1); _Pragma("unroll") for (int m = 0; m < 4; ++m) _Pragma("unroll") for (int n = 0; n < 2; ++n) _Pragma("unroll") for (int k = 0; k < 2; ++k) \
;         acc[ai][bj][m][n] = __builtin_amdgcn_mfma_f32_16x16x32_bf16(Bt[n][k], At[m][k], acc[ai][bj][m][n], 0, 0, 0); __builtin_amdgcn_s_setprio(0); } while (0)
; #define PG8_WAIT_L(n) asm volatile("s_waitcnt lgkmcnt(" #n ")" ::: "memory")
; #define PG8_BAR __builtin_amdgcn_s_barrier()
; #define PG8_SCHED __builtin_amdgcn_sched_barrier(0)
; template <class Epi>
; DI void gemm_phase(LAS unsigned char* lds, int wid, int K, int lda, int ldb, bool bperm, const Sched3& S, const Epi& E) {
;     ...
;             PG8_LDB(B1, 0, 1); PG8_STAGE(PG8_SB(0, 0), b2, voffB);
;             PG8_BAR; PG8_WAIT_L(0); PG8_MMA(0, 1, At, B1); PG8_BAR;
;             PG8_LDA(At, 0, 1); PG8_STAGE(PG8_SA(0, 0), a2, voffA);
;             PG8_BAR; PG8_WAIT_L(0); if (full) PG8_MMA(1, 0, At, B0); PG8_BAR; PG8_SCHED;
;             PG8_STAGE(PG8_SB(0, 1), b2 + hstepB, voffB);
	s_add_i32 m0, s75, 0x2000
	s_nop 0
	global_load_lds_dwordx4 v146, s[48:49]
	s_barrier
	s_waitcnt lgkmcnt(0)
	s_setprio 1
	s_waitcnt lgkmcnt(0)
	v_mfma_f32_16x16x32_bf16 v[116:119], v[192:195], v[160:163], 0
	v_mfma_f32_16x16x32_bf16 v[112:115], v[200:203], v[160:163], 0
	v_mfma_f32_16x16x32_bf16 v[100:103], v[192:195], v[168:171], 0
	v_mfma_f32_16x16x32_bf16 v[96:99], v[200:203], v[168:171], 0
	v_mfma_f32_16x16x32_bf16 v[84:87], v[192:195], v[176:179], 0
	v_mfma_f32_16x16x32_bf16 v[80:83], v[200:203], v[176:179], 0
	v_mfma_f32_16x16x32_bf16 v[68:71], v[192:195], v[184:187], 0
	v_mfma_f32_16x16x32_bf16 v[64:67], v[200:203], v[184:187], 0
	v_mfma_f32_16x16x32_bf16 v[116:119], v[196:199], v[164:167], v[116:119]
	v_mfma_f32_16x16x32_bf16 v[112:115], v[204:207], v[164:167], v[112:115]
	v_mfma_f32_16x16x32_bf16 v[100:103], v[196:199], v[172:175], v[100:103]
	v_mfma_f32_16x16x32_bf16 v[96:99], v[204:207], v[172:175], v[96:99]
	v_mfma_f32_16x16x32_bf16 v[84:87], v[196:199], v[180:183], v[84:87]
	v_mfma_f32_16x16x32_bf16 v[80:83], v[204:207], v[180:183], v[80:83]
	v_mfma_f32_16x16x32_bf16 v[68:71], v[196:199], v[188:191], v[68:71]
	v_mfma_f32_16x16x32_bf16 v[64:67], v[204:207], v[188:191], v[64:67]
	s_setprio 0
	s_mov_b32 m0, s58
	s_mov_b64 s[100:101], s[50:51]
	s_barrier
	ds_read_b128 v[160:163], v231 offset:16384
	ds_read_b128 v[164:167], v231 offset:17408
	ds_read_b128 v[168:171], v231 offset:18432
	ds_read_b128 v[172:175], v231 offset:19456
	ds_read_b128 v[176:179], v231 offset:20480
	ds_read_b128 v[180:183], v231 offset:21504
	ds_read_b128 v[184:187], v231 offset:22528
	ds_read_b128 v[188:191], v231 offset:23552
	global_load_lds_dwordx4 v140, s[50:51]
	s_mov_b64 s[100:101], s[50:51]
	s_mov_b32 m0, s59
	s_nop 0
	global_load_lds_dwordx4 v144, s[50:51]
	s_barrier
	s_waitcnt lgkmcnt(0)
	s_setprio 1
	s_waitcnt lgkmcnt(0)
	v_mfma_f32_16x16x32_bf16 v[60:63], v[128:131], v[160:163], 0
	v_mfma_f32_16x16x32_bf16 v[56:59], v[136:139], v[160:163], 0
	v_mfma_f32_16x16x32_bf16 v[44:47], v[128:131], v[168:171], 0
	v_mfma_f32_16x16x32_bf16 v[40:43], v[136:139], v[168:171], 0
	v_mfma_f32_16x16x32_bf16 v[28:31], v[128:131], v[176:179], 0
	v_mfma_f32_16x16x32_bf16 v[24:27], v[136:139], v[176:179], 0
	v_mfma_f32_16x16x32_bf16 v[12:15], v[128:131], v[184:187], 0
	v_mfma_f32_16x16x32_bf16 v[8:11], v[136:139], v[184:187], 0
	v_mfma_f32_16x16x32_bf16 v[60:63], v[132:135], v[164:167], v[60:63]
	v_mfma_f32_16x16x32_bf16 v[56:59], v[156:159], v[164:167], v[56:59]
	v_mfma_f32_16x16x32_bf16 v[44:47], v[132:135], v[172:175], v[44:47]
	v_mfma_f32_16x16x32_bf16 v[40:43], v[156:159], v[172:175], v[40:43]
	v_mfma_f32_16x16x32_bf16 v[28:31], v[132:135], v[180:183], v[28:31]
	v_mfma_f32_16x16x32_bf16 v[24:27], v[156:159], v[180:183], v[24:27]
	v_mfma_f32_16x16x32_bf16 v[12:15], v[132:135], v[188:191], v[12:15]
	v_mfma_f32_16x16x32_bf16 v[8:11], v[156:159], v[188:191], v[8:11]
	s_setprio 0
	s_barrier
	s_add_u32 s76, s48, 0x80000
	s_addc_u32 s77, s49, 0
	s_add_i32 s75, s68, s57

; #define PG8_STAGE(bufoff, gbase, voff) do { _Pragma("unroll") for (int _i = 0; _i < 2; ++_i) \
;         __builtin_amdgcn_global_load_lds((const unsigned*)((const char*)(gbase) + (voff)[_i]), (LAS unsigned*)(lds + (bufoff) + ldsw + _i * 8192), 16, 0, 0); } while (0)
; template <class Epi>
; DI void gemm_phase(LAS unsigned char* lds, int wid, int K, int lda, int ldb, bool bperm, const Sched3& S, const Epi& E) {
;     ...
;             PG8_STAGE(PG8_SB(0, 1), b2 + hstepB, voffB);
	s_mov_b32 m0, s75
	s_nop 0
	global_load_lds_dwordx4 v142, s[76:77]

; #define PG8_STAGE(bufoff, gbase, voff) do { _Pragma("unroll") for (int _i = 0; _i < 2; ++_i) \
;         __builtin_amdgcn_global_load_lds((const unsigned*)((const char*)(gbase) + (voff)[_i]), (LAS unsigned*)(lds + (bufoff) + ldsw + _i * 8192), 16, 0, 0); } while (0)
; #define PG8_LDA(dst, b, h) do { _Pragma("unroll") for (int m = 0; m < 4; ++m) _Pragma("unroll") for (int k = 0; k < 2; ++k) dst[m][k] = *(const LAS bf16x8*)(lds + PG8_SA(b, h) + aoff + m * 2048 + k * 1024); } while (0)
; #define PG8_LDB(dst, b, h) do { _Pragma("unroll") for (int n = 0; n < 2; ++n) _Pragma("unroll") for (int k = 0; k < 2; ++k) dst[n][k] = *(const LAS bf16x8*)(lds + PG8_SB(b, h) + boff + n * 2048 + k * 1024); } while (0)
; #define PG8_MMA(ai, bj, At, Bt) do { __builtin_amdgcn_s_setprio(1); _Pragma("unroll") for (int m = 0; m < 4; ++m) _Pragma("unroll") for (int n = 0; n < 2; ++n) _Pragma("unroll") for (int k = 0; k < 2; ++k) \
;         acc[ai][bj][m][n] = __builtin_amdgcn_mfma_f32_16x16x32_bf16(Bt[n][k], At[m][k], acc[ai][bj][m][n], 0, 0, 0); __builtin_amdgcn_s_setprio(0); } while (0)
; #define PG8_WAIT_V(n) asm volatile("s_waitcnt vmcnt(" #n ")" ::: "memory")
; #define PG8_BAR __builtin_amdgcn_s_barrier()
; #define PG8_SCHED __builtin_amdgcn_sched_barrier(0)
; template <class Epi>
; DI void gemm_phase(LAS unsigned char* lds, int wid, int K, int lda, int ldb, bool bperm, const Sched3& S, const Epi& E) {
;     ...
;             PG8_STAGE(PG8_SB(0, 1), b2 + hstepB, voffB);
;             PG8_WAIT_V(6); PG8_BAR; if (full) PG8_MMA(1, 1, At, B1); PG8_BAR;
;             PG8_LDB(B0, 1, 0); PG8_SCHED; PG8_LDA(At, 1, 0); PG8_STAGE(PG8_SA(0, 1), a2 + h2, voffA);
	s_add_i32 m0, s75, 0x2000
	s_nop 0
	global_load_lds_dwordx4 v146, s[76:77]
	s_waitcnt vmcnt(6)
	s_barrier
	s_setprio 1
	v_mfma_f32_16x16x32_bf16 v[52:55], v[192:195], v[160:163], 0
	v_mfma_f32_16x16x32_bf16 v[48:51], v[200:203], v[160:163], 0
	v_mfma_f32_16x16x32_bf16 v[36:39], v[192:195], v[168:171], 0
	v_mfma_f32_16x16x32_bf16 v[32:35], v[200:203], v[168:171], 0
	v_mfma_f32_16x16x32_bf16 v[20:23], v[192:195], v[176:179], 0
	v_mfma_f32_16x16x32_bf16 v[16:19], v[200:203], v[176:179], 0
	v_mfma_f32_16x16x32_bf16 v[4:7], v[192:195], v[184:187], 0
	v_mfma_f32_16x16x32_bf16 v[0:3], v[200:203], v[184:187], 0
	v_mfma_f32_16x16x32_bf16 v[52:55], v[196:199], v[164:167], v[52:55]
	v_mfma_f32_16x16x32_bf16 v[48:51], v[204:207], v[164:167], v[48:51]
	v_mfma_f32_16x16x32_bf16 v[36:39], v[196:199], v[172:175], v[36:39]
	v_mfma_f32_16x16x32_bf16 v[32:35], v[204:207], v[172:175], v[32:35]
	v_mfma_f32_16x16x32_bf16 v[20:23], v[196:199], v[180:183], v[20:23]
	v_mfma_f32_16x16x32_bf16 v[16:19], v[204:207], v[180:183], v[16:19]
	v_mfma_f32_16x16x32_bf16 v[4:7], v[196:199], v[188:191], v[4:7]
	v_mfma_f32_16x16x32_bf16 v[0:3], v[204:207], v[188:191], v[0:3]
	s_setprio 0
	s_add_i32 s75, 0, 0x18000
	v_add_u32_e32 v156, s75, v224
	s_barrier
	ds_read_b128 v[128:131], v156
	ds_read_b128 v[132:135], v156 offset:1024
	ds_read_b128 v[136:139], v156 offset:2048
	ds_read_b128 v[156:159], v156 offset:3072
	s_add_u32 s50, s50, 0x80000
	s_addc_u32 s51, s51, 0
	s_mov_b32 m0, s60

; #define PG8_STAGE(bufoff, gbase, voff) do { _Pragma("unroll") for (int _i = 0; _i < 2; ++_i) \
;         __builtin_amdgcn_global_load_lds((const unsigned*)((const char*)(gbase) + (voff)[_i]), (LAS unsigned*)(lds + (bufoff) + ldsw + _i * 8192), 16, 0, 0); } while (0)
; #define PG8_LDA(dst, b, h) do { _Pragma("unroll") for (int m = 0; m < 4; ++m) _Pragma("unroll") for (int k = 0; k < 2; ++k) dst[m][k] = *(const LAS bf16x8*)(lds + PG8_SA(b, h) + aoff + m * 2048 + k * 1024); } while (0)
; #define PG8_LDB(dst, b, h) do { _Pragma("unroll") for (int n = 0; n < 2; ++n) _Pragma("unroll") for (int k = 0; k < 2; ++k) dst[n][k] = *(const LAS bf16x8*)(lds + PG8_SB(b, h) + boff + n * 2048 + k * 1024); } while (0)
; #define PG8_SCHED __builtin_amdgcn_sched_barrier(0)
; template <class Epi>
; DI void gemm_phase(LAS unsigned char* lds, int wid, int K, int lda, int ldb, bool bperm, const Sched3& S, const Epi& E) {
;     ...
;             PG8_LDB(B0, 1, 0); PG8_SCHED; PG8_LDA(At, 1, 0); PG8_STAGE(PG8_SA(0, 1), a2 + h2, voffA);
	ds_read_b128 v[160:163], v231 offset:32768
	ds_read_b128 v[164:167], v231 offset:33792
	ds_read_b128 v[168:171], v231 offset:34816
	ds_read_b128 v[172:175], v231 offset:35840
	ds_read_b128 v[176:179], v231 offset:36864
	ds_read_b128 v[180:183], v231 offset:37888
	ds_read_b128 v[184:187], v231 offset:38912
	ds_read_b128 v[188:191], v231 offset:39936
	global_load_lds_dwordx4 v140, s[50:51]

; #define PG8_STAGE(bufoff, gbase, voff) do { _Pragma("unroll") for (int _i = 0; _i < 2; ++_i) \
;         __builtin_amdgcn_global_load_lds((const unsigned*)((const char*)(gbase) + (voff)[_i]), (LAS unsigned*)(lds + (bufoff) + ldsw + _i * 8192), 16, 0, 0); } while (0)
; #define PG8_LDA(dst, b, h) do { _Pragma("unroll") for (int m = 0; m < 4; ++m) _Pragma("unroll") for (int k = 0; k < 2; ++k) dst[m][k] = *(const LAS bf16x8*)(lds + PG8_SA(b, h) + aoff + m * 2048 + k * 1024); } while (0)
; #define PG8_LDB(dst, b, h) do { _Pragma("unroll") for (int n = 0; n < 2; ++n) _Pragma("unroll") for (int k = 0; k < 2; ++k) dst[n][k] = *(const LAS bf16x8*)(lds + PG8_SB(b, h) + boff + n * 2048 + k * 1024); } while (0)
; #define PG8_MMA(ai, bj, At, Bt) do { __builtin_amdgcn_s_setprio(1); _Pragma("unroll") for (int m = 0; m < 4; ++m) _Pragma("unroll") for (int n = 0; n < 2; ++n) _Pragma("unroll") for (int k = 0; k < 2; ++k) \
;         acc[ai][bj][m][n] = __builtin_amdgcn_mfma_f32_16x16x32_bf16(Bt[n][k], At[m][k], acc[ai][bj][m][n], 0, 0, 0); __builtin_amdgcn_s_setprio(0); } while (0)
; #define PG8_WAIT_L(n) asm volatile("s_waitcnt lgkmcnt(" #n ")" ::: "memory")
; #define PG8_BAR __builtin_amdgcn_s_barrier()
; #define PG8_SCHED __builtin_amdgcn_sched_barrier(0)
; template <class Epi>
; DI void gemm_phase(LAS unsigned char* lds, int wid, int K, int lda, int ldb, bool bperm, const Sched3& S, const Epi& E) {
;     ...
;             PG8_LDB(B0, 1, 0); PG8_SCHED; PG8_LDA(At, 1, 0); PG8_STAGE(PG8_SA(0, 1), a2 + h2, voffA);
;             PG8_WAIT_L(8); PG8_BAR; PG8_WAIT_L(0); PG8_MMA(0, 0, At, B0); PG8_BAR; PG8_SCHED;
	s_mov_b32 m0, s61
	s_nop 0
	global_load_lds_dwordx4 v144, s[50:51]
	s_waitcnt lgkmcnt(8)
	s_barrier
	s_waitcnt lgkmcnt(0)
	s_setprio 1
	s_waitcnt lgkmcnt(0)
	v_mfma_f32_16x16x32_bf16 v[124:127], v[128:131], v[160:163], v[124:127]
	v_mfma_f32_16x16x32_bf16 v[120:123], v[136:139], v[160:163], v[120:123]
	v_mfma_f32_16x16x32_bf16 v[108:111], v[128:131], v[168:171], v[108:111]
	v_mfma_f32_16x16x32_bf16 v[104:107], v[136:139], v[168:171], v[104:107]
	v_mfma_f32_16x16x32_bf16 v[92:95], v[128:131], v[176:179], v[92:95]
	v_mfma_f32_16x16x32_bf16 v[88:91], v[136:139], v[176:179], v[88:91]
	v_mfma_f32_16x16x32_bf16 v[76:79], v[128:131], v[184:187], v[76:79]
	v_mfma_f32_16x16x32_bf16 v[72:75], v[136:139], v[184:187], v[72:75]
	v_mfma_f32_16x16x32_bf16 v[124:127], v[132:135], v[164:167], v[124:127]
	v_mfma_f32_16x16x32_bf16 v[120:123], v[156:159], v[164:167], v[120:123]
	v_mfma_f32_16x16x32_bf16 v[108:111], v[132:135], v[172:175], v[108:111]
	v_mfma_f32_16x16x32_bf16 v[104:107], v[156:159], v[172:175], v[104:107]
	v_mfma_f32_16x16x32_bf16 v[92:95], v[132:135], v[180:183], v[92:95]
	v_mfma_f32_16x16x32_bf16 v[88:91], v[156:159], v[180:183], v[88:91]
	v_mfma_f32_16x16x32_bf16 v[76:79], v[132:135], v[188:191], v[76:79]
	v_mfma_f32_16x16x32_bf16 v[72:75], v[156:159], v[188:191], v[72:75]
	s_setprio 0
	s_barrier
	s_add_i32 s50, 0, 0x1c000
	s_add_i32 s51, s75, s57
	v_add_u32_e32 v204, s50, v224

; #define PG8_STAGE(bufoff, gbase, voff) do { _Pragma("unroll") for (int _i = 0; _i < 2; ++_i) \
;         __builtin_amdgcn_global_load_lds((const unsigned*)((const char*)(gbase) + (voff)[_i]), (LAS unsigned*)(lds + (bufoff) + ldsw + _i * 8192), 16, 0, 0); } while (0)
; #define PG8_LDB(dst, b, h) do { _Pragma("unroll") for (int n = 0; n < 2; ++n) _Pragma("unroll") for (int k = 0; k < 2; ++k) dst[n][k] = *(const LAS bf16x8*)(lds + PG8_SB(b, h) + boff + n * 2048 + k * 1024); } while (0)
; template <class Epi>
; DI void gemm_phase(LAS unsigned char* lds, int wid, int K, int lda, int ldb, bool bperm, const Sched3& S, const Epi& E) {
;     ...
;             PG8_LDB(B1, 1, 1); PG8_STAGE(PG8_SB(1, 0), b3, voffB);
	s_sub_i32 m0, s51, 0x80
	ds_read_b128 v[192:195], v204
	ds_read_b128 v[196:199], v204 offset:1024
	ds_read_b128 v[200:203], v204 offset:2048
	ds_read_b128 v[204:207], v204 offset:3072
	global_load_lds_dwordx4 v142, s[48:49] offset:128

; #define PG8_STAGE(bufoff, gbase, voff) do { _Pragma("unroll") for (int _i = 0; _i < 2; ++_i) \
;         __builtin_amdgcn_global_load_lds((const unsigned*)((const char*)(gbase) + (voff)[_i]), (LAS unsigned*)(lds + (bufoff) + ldsw + _i * 8192), 16, 0, 0); } while (0)
; #define PG8_LDB(dst, b, h) do { _Pragma("unroll") for (int n = 0; n < 2; ++n) _Pragma("unroll") for (int k = 0; k < 2; ++k) dst[n][k] = *(const LAS bf16x8*)(lds + PG8_SB(b, h) + boff + n * 2048 + k * 1024); } while (0)
; #define PG8_MMA(ai, bj, At, Bt) do { __builtin_amdgcn_s_setprio(1); _Pragma("unroll") for (int m = 0; m < 4; ++m) _Pragma("unroll") for (int n = 0; n < 2; ++n) _Pragma("unroll") for (int k = 0; k < 2; ++k) \
;         acc[ai][bj][m][n] = __builtin_amdgcn_mfma_f32_16x16x32_bf16(Bt[n][k], At[m][k], acc[ai][bj][m][n], 0, 0, 0); __builtin_amdgcn_s_setprio(0); } while (0)
; #define PG8_WAIT_L(n) asm volatile("s_waitcnt lgkmcnt(" #n ")" ::: "memory")
; #define PG8_BAR __builtin_amdgcn_s_barrier()
; template <class Epi>
; DI void gemm_phase(LAS unsigned char* lds, int wid, int K, int lda, int ldb, bool bperm, const Sched3& S, const Epi& E) {
;     ...
;             PG8_LDB(B1, 1, 1); PG8_STAGE(PG8_SB(1, 0), b3, voffB);
;             PG8_BAR; PG8_WAIT_L(0); PG8_MMA(0, 1, At, B1); PG8_BAR;
	s_add_i32 m0, s51, 0x1f80
	s_nop 0
	global_load_lds_dwordx4 v146, s[48:49] offset:128
	s_barrier
	s_waitcnt lgkmcnt(0)
	s_setprio 1
	s_waitcnt lgkmcnt(0)
	v_mfma_f32_16x16x32_bf16 v[116:119], v[192:195], v[160:163], v[116:119]
	v_mfma_f32_16x16x32_bf16 v[112:115], v[200:203], v[160:163], v[112:115]
	v_mfma_f32_16x16x32_bf16 v[100:103], v[192:195], v[168:171], v[100:103]
	v_mfma_f32_16x16x32_bf16 v[96:99], v[200:203], v[168:171], v[96:99]
	v_mfma_f32_16x16x32_bf16 v[84:87], v[192:195], v[176:179], v[84:87]
	v_mfma_f32_16x16x32_bf16 v[80:83], v[200:203], v[176:179], v[80:83]
	v_mfma_f32_16x16x32_bf16 v[68:71], v[192:195], v[184:187], v[68:71]
	v_mfma_f32_16x16x32_bf16 v[64:67], v[200:203], v[184:187], v[64:67]
	v_mfma_f32_16x16x32_bf16 v[116:119], v[196:199], v[164:167], v[116:119]
	v_mfma_f32_16x16x32_bf16 v[112:115], v[204:207], v[164:167], v[112:115]
	v_mfma_f32_16x16x32_bf16 v[100:103], v[196:199], v[172:175], v[100:103]
	v_mfma_f32_16x16x32_bf16 v[96:99], v[204:207], v[172:175], v[96:99]
	v_mfma_f32_16x16x32_bf16 v[84:87], v[196:199], v[180:183], v[84:87]
	v_mfma_f32_16x16x32_bf16 v[80:83], v[204:207], v[180:183], v[80:83]
	v_mfma_f32_16x16x32_bf16 v[68:71], v[196:199], v[188:191], v[68:71]
	v_mfma_f32_16x16x32_bf16 v[64:67], v[204:207], v[188:191], v[64:67]
	s_setprio 0
	s_sub_i32 m0, s63, 0x80

; #define PG8_STAGE(bufoff, gbase, voff) do { _Pragma("unroll") for (int _i = 0; _i < 2; ++_i) \
;         __builtin_amdgcn_global_load_lds((const unsigned*)((const char*)(gbase) + (voff)[_i]), (LAS unsigned*)(lds + (bufoff) + ldsw + _i * 8192), 16, 0, 0); } while (0)
; #define PG8_LDA(dst, b, h) do { _Pragma("unroll") for (int m = 0; m < 4; ++m) _Pragma("unroll") for (int k = 0; k < 2; ++k) dst[m][k] = *(const LAS bf16x8*)(lds + PG8_SA(b, h) + aoff + m * 2048 + k * 1024); } while (0)
; #define PG8_MMA(ai, bj, At, Bt) do { __builtin_amdgcn_s_setprio(1); _Pragma("unroll") for (int m = 0; m < 4; ++m) _Pragma("unroll") for (int n = 0; n < 2; ++n) _Pragma("unroll") for (int k = 0; k < 2; ++k) \
;         acc[ai][bj][m][n] = __builtin_amdgcn_mfma_f32_16x16x32_bf16(Bt[n][k], At[m][k], acc[ai][bj][m][n], 0, 0, 0); __builtin_amdgcn_s_setprio(0); } while (0)
; #define PG8_WAIT_L(n) asm volatile("s_waitcnt lgkmcnt(" #n ")" ::: "memory")
; #define PG8_BAR __builtin_amdgcn_s_barrier()
; template <class Epi>
; DI void gemm_phase(LAS unsigned char* lds, int wid, int K, int lda, int ldb, bool bperm, const Sched3& S, const Epi& E) {
;     ...
;             PG8_BAR; PG8_WAIT_L(0); PG8_MMA(0, 1, At, B1); PG8_BAR;
;             PG8_LDA(At, 1, 1); PG8_STAGE(PG8_SA(1, 0), a3, voffA);
	s_barrier
	ds_read_b128 v[160:163], v231 offset:49152
	ds_read_b128 v[164:167], v231 offset:50176
	ds_read_b128 v[168:171], v231 offset:51200
	ds_read_b128 v[172:175], v231 offset:52224
	ds_read_b128 v[176:179], v231 offset:53248
	ds_read_b128 v[180:183], v231 offset:54272
	ds_read_b128 v[184:187], v231 offset:55296
	ds_read_b128 v[188:191], v231 offset:56320
	global_load_lds_dwordx4 v140, s[100:101] offset:128

; #define PG8_STAGE(bufoff, gbase, voff) do { _Pragma("unroll") for (int _i = 0; _i < 2; ++_i) \
;         __builtin_amdgcn_global_load_lds((const unsigned*)((const char*)(gbase) + (voff)[_i]), (LAS unsigned*)(lds + (bufoff) + ldsw + _i * 8192), 16, 0, 0); } while (0)
; #define PG8_LDA(dst, b, h) do { _Pragma("unroll") for (int m = 0; m < 4; ++m) _Pragma("unroll") for (int k = 0; k < 2; ++k) dst[m][k] = *(const LAS bf16x8*)(lds + PG8_SA(b, h) + aoff + m * 2048 + k * 1024); } while (0)
; #define PG8_MMA(ai, bj, At, Bt) do { __builtin_amdgcn_s_setprio(1); _Pragma("unroll") for (int m = 0; m < 4; ++m) _Pragma("unroll") for (int n = 0; n < 2; ++n) _Pragma("unroll") for (int k = 0; k < 2; ++k) \
;         acc[ai][bj][m][n] = __builtin_amdgcn_mfma_f32_16x16x32_bf16(Bt[n][k], At[m][k], acc[ai][bj][m][n], 0, 0, 0); __builtin_amdgcn_s_setprio(0); } while (0)
; #define PG8_WAIT_L(n) asm volatile("s_waitcnt lgkmcnt(" #n ")" ::: "memory")
; #define PG8_BAR __builtin_amdgcn_s_barrier()
; #define PG8_SCHED __builtin_amdgcn_sched_barrier(0)
; template <class Epi>
; DI void gemm_phase(LAS unsigned char* lds, int wid, int K, int lda, int ldb, bool bperm, const Sched3& S, const Epi& E) {
;     ...
;             PG8_LDA(At, 1, 1); PG8_STAGE(PG8_SA(1, 0), a3, voffA);
;             PG8_BAR; PG8_WAIT_L(0); if (full) PG8_MMA(1, 0, At, B0); PG8_BAR; PG8_SCHED;
;             PG8_STAGE(PG8_SB(1, 1), b3 + hstepB, voffB);
	s_sub_i32 m0, s64, 0x80
	s_nop 0
	global_load_lds_dwordx4 v144, s[100:101] offset:128
	s_barrier
	s_waitcnt lgkmcnt(0)
	s_setprio 1
	s_waitcnt lgkmcnt(0)
	v_mfma_f32_16x16x32_bf16 v[60:63], v[128:131], v[160:163], v[60:63]
	v_mfma_f32_16x16x32_bf16 v[56:59], v[136:139], v[160:163], v[56:59]
	v_mfma_f32_16x16x32_bf16 v[44:47], v[128:131], v[168:171], v[44:47]
	v_mfma_f32_16x16x32_bf16 v[40:43], v[136:139], v[168:171], v[40:43]
	v_mfma_f32_16x16x32_bf16 v[28:31], v[128:131], v[176:179], v[28:31]
	v_mfma_f32_16x16x32_bf16 v[24:27], v[136:139], v[176:179], v[24:27]
	v_mfma_f32_16x16x32_bf16 v[12:15], v[128:131], v[184:187], v[12:15]
	v_mfma_f32_16x16x32_bf16 v[8:11], v[136:139], v[184:187], v[8:11]
	v_mfma_f32_16x16x32_bf16 v[60:63], v[132:135], v[164:167], v[60:63]
	v_mfma_f32_16x16x32_bf16 v[56:59], v[156:159], v[164:167], v[56:59]
	v_mfma_f32_16x16x32_bf16 v[44:47], v[132:135], v[172:175], v[44:47]
	v_mfma_f32_16x16x32_bf16 v[40:43], v[156:159], v[172:175], v[40:43]
	v_mfma_f32_16x16x32_bf16 v[28:31], v[132:135], v[180:183], v[28:31]
	v_mfma_f32_16x16x32_bf16 v[24:27], v[156:159], v[180:183], v[24:27]
	v_mfma_f32_16x16x32_bf16 v[12:15], v[132:135], v[188:191], v[12:15]
	v_mfma_f32_16x16x32_bf16 v[8:11], v[156:159], v[188:191], v[8:11]
	s_setprio 0
	s_barrier
	s_add_u32 s48, s48, 0x80080
	s_addc_u32 s49, s49, 0
	s_add_i32 s50, s50, s57

; #define PG8_STAGE(bufoff, gbase, voff) do { _Pragma("unroll") for (int _i = 0; _i < 2; ++_i) \
;         __builtin_amdgcn_global_load_lds((const unsigned*)((const char*)(gbase) + (voff)[_i]), (LAS unsigned*)(lds + (bufoff) + ldsw + _i * 8192), 16, 0, 0); } while (0)
; template <class Epi>
; DI void gemm_phase(LAS unsigned char* lds, int wid, int K, int lda, int ldb, bool bperm, const Sched3& S, const Epi& E) {
;     ...
;             PG8_STAGE(PG8_SB(1, 1), b3 + hstepB, voffB);
	s_mov_b32 m0, s50
	s_nop 0
	global_load_lds_dwordx4 v142, s[48:49]

; #define PG8_STAGE(bufoff, gbase, voff) do { _Pragma("unroll") for (int _i = 0; _i < 2; ++_i) \
;         __builtin_amdgcn_global_load_lds((const unsigned*)((const char*)(gbase) + (voff)[_i]), (LAS unsigned*)(lds + (bufoff) + ldsw + _i * 8192), 16, 0, 0); } while (0)
; #define PG8_MMA(ai, bj, At, Bt) do { __builtin_amdgcn_s_setprio(1); _Pragma("unroll") for (int m = 0; m < 4; ++m) _Pragma("unroll") for (int n = 0; n < 2; ++n) _Pragma("unroll") for (int k = 0; k < 2; ++k) \
;         acc[ai][bj][m][n] = __builtin_amdgcn_mfma_f32_16x16x32_bf16(Bt[n][k], At[m][k], acc[ai][bj][m][n], 0, 0, 0); __builtin_amdgcn_s_setprio(0); } while (0)
; #define PG8_WAIT_V(n) asm volatile("s_waitcnt vmcnt(" #n ")" ::: "memory")
; #define PG8_BAR __builtin_amdgcn_s_barrier()
; template <class Epi>
; DI void gemm_phase(LAS unsigned char* lds, int wid, int K, int lda, int ldb, bool bperm, const Sched3& S, const Epi& E) {
;     ...
;             PG8_STAGE(PG8_SB(1, 1), b3 + hstepB, voffB);
;             PG8_WAIT_V(6); PG8_BAR; if (full) PG8_MMA(1, 1, At, B1); PG8_BAR;
;         }
	s_add_i32 m0, s50, 0x2000
	s_nop 0
	global_load_lds_dwordx4 v146, s[48:49]
	s_waitcnt vmcnt(6)
	s_barrier
	s_setprio 1
	v_mfma_f32_16x16x32_bf16 v[52:55], v[192:195], v[160:163], v[52:55]
	v_mfma_f32_16x16x32_bf16 v[48:51], v[200:203], v[160:163], v[48:51]
	v_mfma_f32_16x16x32_bf16 v[36:39], v[192:195], v[168:171], v[36:39]
	v_mfma_f32_16x16x32_bf16 v[32:35], v[200:203], v[168:171], v[32:35]
	v_mfma_f32_16x16x32_bf16 v[20:23], v[192:195], v[176:179], v[20:23]
	v_mfma_f32_16x16x32_bf16 v[16:19], v[200:203], v[176:179], v[16:19]
	v_mfma_f32_16x16x32_bf16 v[4:7], v[192:195], v[184:187], v[4:7]
	v_mfma_f32_16x16x32_bf16 v[0:3], v[200:203], v[184:187], v[0:3]
	v_mfma_f32_16x16x32_bf16 v[52:55], v[196:199], v[164:167], v[52:55]
	v_mfma_f32_16x16x32_bf16 v[48:51], v[204:207], v[164:167], v[48:51]
	v_mfma_f32_16x16x32_bf16 v[36:39], v[196:199], v[172:175], v[36:39]
	v_mfma_f32_16x16x32_bf16 v[32:35], v[204:207], v[172:175], v[32:35]
	v_mfma_f32_16x16x32_bf16 v[20:23], v[196:199], v[180:183], v[20:23]
	v_mfma_f32_16x16x32_bf16 v[16:19], v[204:207], v[180:183], v[16:19]
	v_mfma_f32_16x16x32_bf16 v[4:7], v[196:199], v[188:191], v[4:7]
	v_mfma_f32_16x16x32_bf16 v[0:3], v[204:207], v[188:191], v[0:3]
	s_setprio 0
	s_add_i32 s55, s55, 2
	s_add_u32 s46, s46, 0x100
	s_addc_u32 s47, s47, 0
	s_add_u32 s53, s53, 0x100
	s_addc_u32 s54, s54, 0
	s_cmp_gt_u32 s55, 29
	s_cbranch_scc1 .Lkrot_0_exit

; #define PG8_STAGE(bufoff, gbase, voff) do { _Pragma("unroll") for (int _i = 0; _i < 2; ++_i) \
;         __builtin_amdgcn_global_load_lds((const unsigned*)((const char*)(gbase) + (voff)[_i]), (LAS unsigned*)(lds + (bufoff) + ldsw + _i * 8192), 16, 0, 0); } while (0)
; #define PG8_LDA(dst, b, h) do { _Pragma("unroll") for (int m = 0; m < 4; ++m) _Pragma("unroll") for (int k = 0; k < 2; ++k) dst[m][k] = *(const LAS bf16x8*)(lds + PG8_SA(b, h) + aoff + m * 2048 + k * 1024); } while (0)
; #define PG8_LDB(dst, b, h) do { _Pragma("unroll") for (int n = 0; n < 2; ++n) _Pragma("unroll") for (int k = 0; k < 2; ++k) dst[n][k] = *(const LAS bf16x8*)(lds + PG8_SB(b, h) + boff + n * 2048 + k * 1024); } while (0)
; #define PG8_SCHED __builtin_amdgcn_sched_barrier(0)
; template <class Epi>
; DI void gemm_phase(LAS unsigned char* lds, int wid, int K, int lda, int ldb, bool bperm, const Sched3& S, const Epi& E) {
;     ...
;             const char* a1 = cA + (size_t)(t + 1) * kstep;
;             const char* a2 = last ? nA : cA + (size_t)(t + 2) * kstep; const char* b2 = last ? nB : cB + (size_t)(t + 2) * kstep;
;             const char* a3 = a2 + kstep; const char* b3 = b2 + kstep; const size_t h2 = last ? nhA : hA;
;             PG8_LDB(B0, 0, 0); PG8_SCHED; PG8_LDA(At, 0, 0); PG8_STAGE(PG8_SA(1, 1), a1 + hA, voffA);
.LBB0_327:
	s_waitcnt lgkmcnt(0)
	ds_read_b128 v[128:131], v230
	ds_read_b128 v[132:135], v230 offset:1024
	ds_read_b128 v[136:139], v230 offset:2048
	ds_read_b128 v[156:159], v230 offset:3072
	s_add_u32 s48, s46, 0xfff80080
	s_addc_u32 s49, s47, -1
	s_cmp_eq_u32 s55, 28
	s_cselect_b32 s51, s5, s49
	s_cselect_b32 s50, s37, s48
	s_cselect_b32 s49, s39, s54
	s_cselect_b32 s48, s52, s53

; #define PG8_STAGE(bufoff, gbase, voff) do { _Pragma("unroll") for (int _i = 0; _i < 2; ++_i) \
;         __builtin_amdgcn_global_load_lds((const unsigned*)((const char*)(gbase) + (voff)[_i]), (LAS unsigned*)(lds + (bufoff) + ldsw + _i * 8192), 16, 0, 0); } while (0)
; #define PG8_LDA(dst, b, h) do { _Pragma("unroll") for (int m = 0; m < 4; ++m) _Pragma("unroll") for (int k = 0; k < 2; ++k) dst[m][k] = *(const LAS bf16x8*)(lds + PG8_SA(b, h) + aoff + m * 2048 + k * 1024); } while (0)
; #define PG8_LDB(dst, b, h) do { _Pragma("unroll") for (int n = 0; n < 2; ++n) _Pragma("unroll") for (int k = 0; k < 2; ++k) dst[n][k] = *(const LAS bf16x8*)(lds + PG8_SB(b, h) + boff + n * 2048 + k * 1024); } while (0)
; #define PG8_SCHED __builtin_amdgcn_sched_barrier(0)
; template <class Epi>
; DI void gemm_phase(LAS unsigned char* lds, int wid, int K, int lda, int ldb, bool bperm, const Sched3& S, const Epi& E) {
;     ...
;             PG8_LDB(B0, 0, 0); PG8_SCHED; PG8_LDA(At, 0, 0); PG8_STAGE(PG8_SA(1, 1), a1 + hA, voffA);
	s_add_i32 m0, s58, 0xc000
	ds_read_b128 v[160:163], v231
	ds_read_b128 v[164:167], v231 offset:1024
	ds_read_b128 v[168:171], v231 offset:2048
	ds_read_b128 v[172:175], v231 offset:3072
	ds_read_b128 v[176:179], v231 offset:4096
	ds_read_b128 v[180:183], v231 offset:5120
	ds_read_b128 v[184:187], v231 offset:6144
	ds_read_b128 v[188:191], v231 offset:7168
	global_load_lds_dwordx4 v148, s[46:47]

; #define PG8_STAGE(bufoff, gbase, voff) do { _Pragma("unroll") for (int _i = 0; _i < 2; ++_i) \
;         __builtin_amdgcn_global_load_lds((const unsigned*)((const char*)(gbase) + (voff)[_i]), (LAS unsigned*)(lds + (bufoff) + ldsw + _i * 8192), 16, 0, 0); } while (0)
; #define PG8_LDA(dst, b, h) do { _Pragma("unroll") for (int m = 0; m < 4; ++m) _Pragma("unroll") for (int k = 0; k < 2; ++k) dst[m][k] = *(const LAS bf16x8*)(lds + PG8_SA(b, h) + aoff + m * 2048 + k * 1024); } while (0)
; #define PG8_LDB(dst, b, h) do { _Pragma("unroll") for (int n = 0; n < 2; ++n) _Pragma("unroll") for (int k = 0; k < 2; ++k) dst[n][k] = *(const LAS bf16x8*)(lds + PG8_SB(b, h) + boff + n * 2048 + k * 1024); } while (0)
; #define PG8_MMA(ai, bj, At, Bt) do { __builtin_amdgcn_s_setprio(1); _Pragma("unroll") for (int m = 0; m < 4; ++m) _Pragma("unroll") for (int n = 0; n < 2; ++n) _Pragma("unroll") for (int k = 0; k < 2; ++k) \
;         acc[ai][bj][m][n] = __builtin_amdgcn_mfma_f32_16x16x32_bf16(Bt[n][k], At[m][k], acc[ai][bj][m][n], 0, 0, 0); __builtin_amdgcn_s_setprio(0); } while (0)
; #define PG8_WAIT_L(n) asm volatile("s_waitcnt lgkmcnt(" #n ")" ::: "memory")
; #define PG8_BAR __builtin_amdgcn_s_barrier()
; #define PG8_SCHED __builtin_amdgcn_sched_barrier(0)
; template <class Epi>
; DI void gemm_phase(LAS unsigned char* lds, int wid, int K, int lda, int ldb, bool bperm, const Sched3& S, const Epi& E) {
;     ...
;             PG8_LDB(B0, 0, 0); PG8_SCHED; PG8_LDA(At, 0, 0); PG8_STAGE(PG8_SA(1, 1), a1 + hA, voffA);
;             PG8_WAIT_L(8); PG8_BAR; PG8_WAIT_L(0); PG8_MMA(0, 0, At, B0); PG8_BAR; PG8_SCHED;
	s_add_i32 m0, s58, 0xe000
	s_nop 0
	global_load_lds_dwordx4 v150, s[46:47]
	s_waitcnt lgkmcnt(8)
	s_barrier
	s_waitcnt lgkmcnt(0)
	s_setprio 1
	s_waitcnt lgkmcnt(0)
	v_mfma_f32_16x16x32_bf16 v[124:127], v[128:131], v[160:163], v[124:127]
	v_mfma_f32_16x16x32_bf16 v[120:123], v[136:139], v[160:163], v[120:123]
	v_mfma_f32_16x16x32_bf16 v[108:111], v[128:131], v[168:171], v[108:111]
	v_mfma_f32_16x16x32_bf16 v[104:107], v[136:139], v[168:171], v[104:107]
	v_mfma_f32_16x16x32_bf16 v[92:95], v[128:131], v[176:179], v[92:95]
	v_mfma_f32_16x16x32_bf16 v[88:91], v[136:139], v[176:179], v[88:91]
	v_mfma_f32_16x16x32_bf16 v[76:79], v[128:131], v[184:187], v[76:79]
	v_mfma_f32_16x16x32_bf16 v[72:75], v[136:139], v[184:187], v[72:75]
	v_mfma_f32_16x16x32_bf16 v[124:127], v[132:135], v[164:167], v[124:127]
	v_mfma_f32_16x16x32_bf16 v[120:123], v[156:159], v[164:167], v[120:123]
	v_mfma_f32_16x16x32_bf16 v[108:111], v[132:135], v[172:175], v[108:111]
	v_mfma_f32_16x16x32_bf16 v[104:107], v[156:159], v[172:175], v[104:107]
	v_mfma_f32_16x16x32_bf16 v[92:95], v[132:135], v[180:183], v[92:95]
	v_mfma_f32_16x16x32_bf16 v[88:91], v[156:159], v[180:183], v[88:91]
	v_mfma_f32_16x16x32_bf16 v[76:79], v[132:135], v[188:191], v[76:79]
	v_mfma_f32_16x16x32_bf16 v[72:75], v[156:159], v[188:191], v[72:75]
	s_setprio 0
	s_barrier
	s_add_i32 s75, s67, s57

; #define PG8_STAGE(bufoff, gbase, voff) do { _Pragma("unroll") for (int _i = 0; _i < 2; ++_i) \
;         __builtin_amdgcn_global_load_lds((const unsigned*)((const char*)(gbase) + (voff)[_i]), (LAS unsigned*)(lds + (bufoff) + ldsw + _i * 8192), 16, 0, 0); } while (0)
; #define PG8_LDB(dst, b, h) do { _Pragma("unroll") for (int n = 0; n < 2; ++n) _Pragma("unroll") for (int k = 0; k < 2; ++k) dst[n][k] = *(const LAS bf16x8*)(lds + PG8_SB(b, h) + boff + n * 2048 + k * 1024); } while (0)
; template <class Epi>
; DI void gemm_phase(LAS unsigned char* lds, int wid, int K, int lda, int ldb, bool bperm, const Sched3& S, const Epi& E) {
;     ...
;             PG8_LDB(B1, 0, 1); PG8_STAGE(PG8_SB(0, 0), b2, voffB);
	s_mov_b32 m0, s75
	ds_read_b128 v[192:195], v232
	ds_read_b128 v[196:199], v232 offset:1024
	ds_read_b128 v[200:203], v232 offset:2048
	ds_read_b128 v[204:207], v232 offset:3072
	global_load_lds_dwordx4 v142, s[48:49]

; #define PG8_STAGE(bufoff, gbase, voff) do { _Pragma("unroll") for (int _i = 0; _i < 2; ++_i) \
;         __builtin_amdgcn_global_load_lds((const unsigned*)((const char*)(gbase) + (voff)[_i]), (LAS unsigned*)(lds + (bufoff) + ldsw + _i * 8192), 16, 0, 0); } while (0)
; #define PG8_LDA(dst, b, h) do { _Pragma("unroll") for (int m = 0; m < 4; ++m) _Pragma("unroll") for (int k = 0; k < 2; ++k) dst[m][k] = *(const LAS bf16x8*)(lds + PG8_SA(b, h) + aoff + m * 2048 + k * 1024); } while (0)
; #define PG8_LDB(dst, b, h) do { _Pragma("unroll") for (int n = 0; n < 2; ++n) _Pragma("unroll") for (int k = 0; k < 2; ++k) dst[n][k] = *(const LAS bf16x8*)(lds + PG8_SB(b, h) + boff + n * 2048 + k * 1024); } while (0)
; #define PG8_MMA(ai, bj, At, Bt) do { __builtin_amdgcn_s_setprio(1); _Pragma("unroll") for (int m = 0; m < 4; ++m) _Pragma("unroll") for (int n = 0; n < 2; ++n) _Pragma("unroll") for (int k = 0; k < 2; ++k) \
;         acc[ai][bj][m][n] = __builtin_amdgcn_mfma_f32_16x16x32_bf16(Bt[n][k], At[m][k], acc[ai][bj][m][n], 0, 0, 0); __builtin_amdgcn_s_setprio(0); } while (0)
; #define PG8_WAIT_L(n) asm volatile("s_waitcnt lgkmcnt(" #n ")" ::: "memory")
; #define PG8_BAR __builtin_amdgcn_s_barrier()
; #define PG8_SCHED __builtin_amdgcn_sched_barrier(0)
; template <class Epi>
; DI void gemm_phase(LAS unsigned char* lds, int wid, int K, int lda, int ldb, bool bperm, const Sched3& S, const Epi& E) {
;     ...
;             PG8_LDB(B1, 0, 1); PG8_STAGE(PG8_SB(0, 0), b2, voffB);
;             PG8_BAR; PG8_WAIT_L(0); PG8_MMA(0, 1, At, B1); PG8_BAR;
;             PG8_LDA(At, 0, 1); PG8_STAGE(PG8_SA(0, 0), a2, voffA);
;             PG8_BAR; PG8_WAIT_L(0); if (full) PG8_MMA(1, 0, At, B0); PG8_BAR; PG8_SCHED;
;             PG8_STAGE(PG8_SB(0, 1), b2 + hstepB, voffB);
	s_add_i32 m0, s75, 0x2000
	s_nop 0
	global_load_lds_dwordx4 v146, s[48:49]
	s_barrier
	s_waitcnt lgkmcnt(0)
	s_setprio 1
	s_waitcnt lgkmcnt(0)
	v_mfma_f32_16x16x32_bf16 v[116:119], v[192:195], v[160:163], v[116:119]
	v_mfma_f32_16x16x32_bf16 v[112:115], v[200:203], v[160:163], v[112:115]
	v_mfma_f32_16x16x32_bf16 v[100:103], v[192:195], v[168:171], v[100:103]
	v_mfma_f32_16x16x32_bf16 v[96:99], v[200:203], v[168:171], v[96:99]
	v_mfma_f32_16x16x32_bf16 v[84:87], v[192:195], v[176:179], v[84:87]
	v_mfma_f32_16x16x32_bf16 v[80:83], v[200:203], v[176:179], v[80:83]
	v_mfma_f32_16x16x32_bf16 v[68:71], v[192:195], v[184:187], v[68:71]
	v_mfma_f32_16x16x32_bf16 v[64:67], v[200:203], v[184:187], v[64:67]
	v_mfma_f32_16x16x32_bf16 v[116:119], v[196:199], v[164:167], v[116:119]
	v_mfma_f32_16x16x32_bf16 v[112:115], v[204:207], v[164:167], v[112:115]
	v_mfma_f32_16x16x32_bf16 v[100:103], v[196:199], v[172:175], v[100:103]
	v_mfma_f32_16x16x32_bf16 v[96:99], v[204:207], v[172:175], v[96:99]
	v_mfma_f32_16x16x32_bf16 v[84:87], v[196:199], v[180:183], v[84:87]
	v_mfma_f32_16x16x32_bf16 v[80:83], v[204:207], v[180:183], v[80:83]
	v_mfma_f32_16x16x32_bf16 v[68:71], v[196:199], v[188:191], v[68:71]
	v_mfma_f32_16x16x32_bf16 v[64:67], v[204:207], v[188:191], v[64:67]
	s_setprio 0
	s_mov_b32 m0, s58
	s_mov_b64 s[100:101], s[50:51]
	s_barrier
	ds_read_b128 v[160:163], v231 offset:16384
	ds_read_b128 v[164:167], v231 offset:17408
	ds_read_b128 v[168:171], v231 offset:18432
	ds_read_b128 v[172:175], v231 offset:19456
	ds_read_b128 v[176:179], v231 offset:20480
	ds_read_b128 v[180:183], v231 offset:21504
	ds_read_b128 v[184:187], v231 offset:22528
	ds_read_b128 v[188:191], v231 offset:23552
	global_load_lds_dwordx4 v140, s[50:51]
	s_mov_b64 s[100:101], s[50:51]
	s_mov_b32 m0, s59
	s_nop 0
	global_load_lds_dwordx4 v144, s[50:51]
	s_barrier
	s_waitcnt lgkmcnt(0)
	s_setprio 1
	s_waitcnt lgkmcnt(0)
	v_mfma_f32_16x16x32_bf16 v[60:63], v[128:131], v[160:163], v[60:63]
	v_mfma_f32_16x16x32_bf16 v[56:59], v[136:139], v[160:163], v[56:59]
	v_mfma_f32_16x16x32_bf16 v[44:47], v[128:131], v[168:171], v[44:47]
	v_mfma_f32_16x16x32_bf16 v[40:43], v[136:139], v[168:171], v[40:43]
	v_mfma_f32_16x16x32_bf16 v[28:31], v[128:131], v[176:179], v[28:31]
	v_mfma_f32_16x16x32_bf16 v[24:27], v[136:139], v[176:179], v[24:27]
	v_mfma_f32_16x16x32_bf16 v[12:15], v[128:131], v[184:187], v[12:15]
	v_mfma_f32_16x16x32_bf16 v[8:11], v[136:139], v[184:187], v[8:11]
	v_mfma_f32_16x16x32_bf16 v[60:63], v[132:135], v[164:167], v[60:63]
	v_mfma_f32_16x16x32_bf16 v[56:59], v[156:159], v[164:167], v[56:59]
	v_mfma_f32_16x16x32_bf16 v[44:47], v[132:135], v[172:175], v[44:47]
	v_mfma_f32_16x16x32_bf16 v[40:43], v[156:159], v[172:175], v[40:43]
	v_mfma_f32_16x16x32_bf16 v[28:31], v[132:135], v[180:183], v[28:31]
	v_mfma_f32_16x16x32_bf16 v[24:27], v[156:159], v[180:183], v[24:27]
	v_mfma_f32_16x16x32_bf16 v[12:15], v[132:135], v[188:191], v[12:15]
	v_mfma_f32_16x16x32_bf16 v[8:11], v[156:159], v[188:191], v[8:11]
	s_setprio 0
	s_barrier
	s_add_u32 s76, s48, 0x80000
	s_addc_u32 s77, s49, 0
	s_add_i32 s75, s68, s57

; #define PG8_STAGE(bufoff, gbase, voff) do { _Pragma("unroll") for (int _i = 0; _i < 2; ++_i) \
;         __builtin_amdgcn_global_load_lds((const unsigned*)((const char*)(gbase) + (voff)[_i]), (LAS unsigned*)(lds + (bufoff) + ldsw + _i * 8192), 16, 0, 0); } while (0)
; template <class Epi>
; DI void gemm_phase(LAS unsigned char* lds, int wid, int K, int lda, int ldb, bool bperm, const Sched3& S, const Epi& E) {
;     ...
;             PG8_STAGE(PG8_SB(0, 1), b2 + hstepB, voffB);
	s_mov_b32 m0, s75
	s_nop 0
	global_load_lds_dwordx4 v142, s[76:77]

; #define PG8_STAGE(bufoff, gbase, voff) do { _Pragma("unroll") for (int _i = 0; _i < 2; ++_i) \
;         __builtin_amdgcn_global_load_lds((const unsigned*)((const char*)(gbase) + (voff)[_i]), (LAS unsigned*)(lds + (bufoff) + ldsw + _i * 8192), 16, 0, 0); } while (0)
; #define PG8_LDA(dst, b, h) do { _Pragma("unroll") for (int m = 0; m < 4; ++m) _Pragma("unroll") for (int k = 0; k < 2; ++k) dst[m][k] = *(const LAS bf16x8*)(lds + PG8_SA(b, h) + aoff + m * 2048 + k * 1024); } while (0)
; #define PG8_LDB(dst, b, h) do { _Pragma("unroll") for (int n = 0; n < 2; ++n) _Pragma("unroll") for (int k = 0; k < 2; ++k) dst[n][k] = *(const LAS bf16x8*)(lds + PG8_SB(b, h) + boff + n * 2048 + k * 1024); } while (0)
; #define PG8_MMA(ai, bj, At, Bt) do { __builtin_amdgcn_s_setprio(1); _Pragma("unroll") for (int m = 0; m < 4; ++m) _Pragma("unroll") for (int n = 0; n < 2; ++n) _Pragma("unroll") for (int k = 0; k < 2; ++k) \
;         acc[ai][bj][m][n] = __builtin_amdgcn_mfma_f32_16x16x32_bf16(Bt[n][k], At[m][k], acc[ai][bj][m][n], 0, 0, 0); __builtin_amdgcn_s_setprio(0); } while (0)
; #define PG8_WAIT_V(n) asm volatile("s_waitcnt vmcnt(" #n ")" ::: "memory")
; #define PG8_BAR __builtin_amdgcn_s_barrier()
; #define PG8_SCHED __builtin_amdgcn_sched_barrier(0)
; template <class Epi>
; DI void gemm_phase(LAS unsigned char* lds, int wid, int K, int lda, int ldb, bool bperm, const Sched3& S, const Epi& E) {
;     ...
;             PG8_STAGE(PG8_SB(0, 1), b2 + hstepB, voffB);
;             PG8_WAIT_V(6); PG8_BAR; if (full) PG8_MMA(1, 1, At, B1); PG8_BAR;
;             PG8_LDB(B0, 1, 0); PG8_SCHED; PG8_LDA(At, 1, 0); PG8_STAGE(PG8_SA(0, 1), a2 + h2, voffA);
	s_add_i32 m0, s75, 0x2000
	s_nop 0
	global_load_lds_dwordx4 v146, s[76:77]
	s_waitcnt vmcnt(6)
	s_barrier
	s_setprio 1
	v_mfma_f32_16x16x32_bf16 v[52:55], v[192:195], v[160:163], v[52:55]
	v_mfma_f32_16x16x32_bf16 v[48:51], v[200:203], v[160:163], v[48:51]
	v_mfma_f32_16x16x32_bf16 v[36:39], v[192:195], v[168:171], v[36:39]
	v_mfma_f32_16x16x32_bf16 v[32:35], v[200:203], v[168:171], v[32:35]
	v_mfma_f32_16x16x32_bf16 v[20:23], v[192:195], v[176:179], v[20:23]
	v_mfma_f32_16x16x32_bf16 v[16:19], v[200:203], v[176:179], v[16:19]
	v_mfma_f32_16x16x32_bf16 v[4:7], v[192:195], v[184:187], v[4:7]
	v_mfma_f32_16x16x32_bf16 v[0:3], v[200:203], v[184:187], v[0:3]
	v_mfma_f32_16x16x32_bf16 v[52:55], v[196:199], v[164:167], v[52:55]
	v_mfma_f32_16x16x32_bf16 v[48:51], v[204:207], v[164:167], v[48:51]
	v_mfma_f32_16x16x32_bf16 v[36:39], v[196:199], v[172:175], v[36:39]
	v_mfma_f32_16x16x32_bf16 v[32:35], v[204:207], v[172:175], v[32:35]
	v_mfma_f32_16x16x32_bf16 v[20:23], v[196:199], v[180:183], v[20:23]
	v_mfma_f32_16x16x32_bf16 v[16:19], v[204:207], v[180:183], v[16:19]
	v_mfma_f32_16x16x32_bf16 v[4:7], v[196:199], v[188:191], v[4:7]
	v_mfma_f32_16x16x32_bf16 v[0:3], v[204:207], v[188:191], v[0:3]
	s_setprio 0
	s_add_i32 s75, 0, 0x18000
	v_add_u32_e32 v156, s75, v224
	s_barrier
	ds_read_b128 v[128:131], v156
	ds_read_b128 v[132:135], v156 offset:1024
	ds_read_b128 v[136:139], v156 offset:2048
	ds_read_b128 v[156:159], v156 offset:3072
	s_add_u32 s50, s50, 0x80000
	s_addc_u32 s51, s51, 0
	s_mov_b32 m0, s60

; #define PG8_STAGE(bufoff, gbase, voff) do { _Pragma("unroll") for (int _i = 0; _i < 2; ++_i) \
;         __builtin_amdgcn_global_load_lds((const unsigned*)((const char*)(gbase) + (voff)[_i]), (LAS unsigned*)(lds + (bufoff) + ldsw + _i * 8192), 16, 0, 0); } while (0)
; #define PG8_LDA(dst, b, h) do { _Pragma("unroll") for (int m = 0; m < 4; ++m) _Pragma("unroll") for (int k = 0; k < 2; ++k) dst[m][k] = *(const LAS bf16x8*)(lds + PG8_SA(b, h) + aoff + m * 2048 + k * 1024); } while (0)
; #define PG8_LDB(dst, b, h) do { _Pragma("unroll") for (int n = 0; n < 2; ++n) _Pragma("unroll") for (int k = 0; k < 2; ++k) dst[n][k] = *(const LAS bf16x8*)(lds + PG8_SB(b, h) + boff + n * 2048 + k * 1024); } while (0)
; #define PG8_SCHED __builtin_amdgcn_sched_barrier(0)
; template <class Epi>
; DI void gemm_phase(LAS unsigned char* lds, int wid, int K, int lda, int ldb, bool bperm, const Sched3& S, const Epi& E) {
;     ...
;             PG8_LDB(B0, 1, 0); PG8_SCHED; PG8_LDA(At, 1, 0); PG8_STAGE(PG8_SA(0, 1), a2 + h2, voffA);
	ds_read_b128 v[160:163], v231 offset:32768
	ds_read_b128 v[164:167], v231 offset:33792
	ds_read_b128 v[168:171], v231 offset:34816
	ds_read_b128 v[172:175], v231 offset:35840
	ds_read_b128 v[176:179], v231 offset:36864
	ds_read_b128 v[180:183], v231 offset:37888
	ds_read_b128 v[184:187], v231 offset:38912
	ds_read_b128 v[188:191], v231 offset:39936
	global_load_lds_dwordx4 v140, s[50:51]

; #define PG8_STAGE(bufoff, gbase, voff) do { _Pragma("unroll") for (int _i = 0; _i < 2; ++_i) \
;         __builtin_amdgcn_global_load_lds((const unsigned*)((const char*)(gbase) + (voff)[_i]), (LAS unsigned*)(lds + (bufoff) + ldsw + _i * 8192), 16, 0, 0); } while (0)
; #define PG8_LDA(dst, b, h) do { _Pragma("unroll") for (int m = 0; m < 4; ++m) _Pragma("unroll") for (int k = 0; k < 2; ++k) dst[m][k] = *(const LAS bf16x8*)(lds + PG8_SA(b, h) + aoff + m * 2048 + k * 1024); } while (0)
; #define PG8_LDB(dst, b, h) do { _Pragma("unroll") for (int n = 0; n < 2; ++n) _Pragma("unroll") for (int k = 0; k < 2; ++k) dst[n][k] = *(const LAS bf16x8*)(lds + PG8_SB(b, h) + boff + n * 2048 + k * 1024); } while (0)
; #define PG8_MMA(ai, bj, At, Bt) do { __builtin_amdgcn_s_setprio(1); _Pragma("unroll") for (int m = 0; m < 4; ++m) _Pragma("unroll") for (int n = 0; n < 2; ++n) _Pragma("unroll") for (int k = 0; k < 2; ++k) \
;         acc[ai][bj][m][n] = __builtin_amdgcn_mfma_f32_16x16x32_bf16(Bt[n][k], At[m][k], acc[ai][bj][m][n], 0, 0, 0); __builtin_amdgcn_s_setprio(0); } while (0)
; #define PG8_WAIT_L(n) asm volatile("s_waitcnt lgkmcnt(" #n ")" ::: "memory")
; #define PG8_BAR __builtin_amdgcn_s_barrier()
; #define PG8_SCHED __builtin_amdgcn_sched_barrier(0)
; template <class Epi>
; DI void gemm_phase(LAS unsigned char* lds, int wid, int K, int lda, int ldb, bool bperm, const Sched3& S, const Epi& E) {
;     ...
;             PG8_LDB(B0, 1, 0); PG8_SCHED; PG8_LDA(At, 1, 0); PG8_STAGE(PG8_SA(0, 1), a2 + h2, voffA);
;             PG8_WAIT_L(8); PG8_BAR; PG8_WAIT_L(0); PG8_MMA(0, 0, At, B0); PG8_BAR; PG8_SCHED;
	s_mov_b32 m0, s61
	s_nop 0
	global_load_lds_dwordx4 v144, s[50:51]
	s_waitcnt lgkmcnt(8)
	s_barrier
	s_waitcnt lgkmcnt(0)
	s_setprio 1
	s_waitcnt lgkmcnt(0)
	v_mfma_f32_16x16x32_bf16 v[124:127], v[128:131], v[160:163], v[124:127]
	v_mfma_f32_16x16x32_bf16 v[120:123], v[136:139], v[160:163], v[120:123]
	v_mfma_f32_16x16x32_bf16 v[108:111], v[128:131], v[168:171], v[108:111]
	v_mfma_f32_16x16x32_bf16 v[104:107], v[136:139], v[168:171], v[104:107]
	v_mfma_f32_16x16x32_bf16 v[92:95], v[128:131], v[176:179], v[92:95]
	v_mfma_f32_16x16x32_bf16 v[88:91], v[136:139], v[176:179], v[88:91]
	v_mfma_f32_16x16x32_bf16 v[76:79], v[128:131], v[184:187], v[76:79]
	v_mfma_f32_16x16x32_bf16 v[72:75], v[136:139], v[184:187], v[72:75]
	v_mfma_f32_16x16x32_bf16 v[124:127], v[132:135], v[164:167], v[124:127]
	v_mfma_f32_16x16x32_bf16 v[120:123], v[156:159], v[164:167], v[120:123]
	v_mfma_f32_16x16x32_bf16 v[108:111], v[132:135], v[172:175], v[108:111]
	v_mfma_f32_16x16x32_bf16 v[104:107], v[156:159], v[172:175], v[104:107]
	v_mfma_f32_16x16x32_bf16 v[92:95], v[132:135], v[180:183], v[92:95]
	v_mfma_f32_16x16x32_bf16 v[88:91], v[156:159], v[180:183], v[88:91]
	v_mfma_f32_16x16x32_bf16 v[76:79], v[132:135], v[188:191], v[76:79]
	v_mfma_f32_16x16x32_bf16 v[72:75], v[156:159], v[188:191], v[72:75]
	s_setprio 0
	s_barrier
	s_add_i32 s50, 0, 0x1c000
	s_add_i32 s51, s75, s57
	v_add_u32_e32 v204, s50, v224

; #define PG8_STAGE(bufoff, gbase, voff) do { _Pragma("unroll") for (int _i = 0; _i < 2; ++_i) \
;         __builtin_amdgcn_global_load_lds((const unsigned*)((const char*)(gbase) + (voff)[_i]), (LAS unsigned*)(lds + (bufoff) + ldsw + _i * 8192), 16, 0, 0); } while (0)
; #define PG8_LDB(dst, b, h) do { _Pragma("unroll") for (int n = 0; n < 2; ++n) _Pragma("unroll") for (int k = 0; k < 2; ++k) dst[n][k] = *(const LAS bf16x8*)(lds + PG8_SB(b, h) + boff + n * 2048 + k * 1024); } while (0)
; template <class Epi>
; DI void gemm_phase(LAS unsigned char* lds, int wid, int K, int lda, int ldb, bool bperm, const Sched3& S, const Epi& E) {
;     ...
;             PG8_LDB(B1, 1, 1); PG8_STAGE(PG8_SB(1, 0), b3, voffB);
	s_sub_i32 m0, s51, 0x80
	ds_read_b128 v[192:195], v204
	ds_read_b128 v[196:199], v204 offset:1024
	ds_read_b128 v[200:203], v204 offset:2048
	ds_read_b128 v[204:207], v204 offset:3072
	global_load_lds_dwordx4 v142, s[48:49] offset:128

; #define PG8_STAGE(bufoff, gbase, voff) do { _Pragma("unroll") for (int _i = 0; _i < 2; ++_i) \
;         __builtin_amdgcn_global_load_lds((const unsigned*)((const char*)(gbase) + (voff)[_i]), (LAS unsigned*)(lds + (bufoff) + ldsw + _i * 8192), 16, 0, 0); } while (0)
; #define PG8_LDB(dst, b, h) do { _Pragma("unroll") for (int n = 0; n < 2; ++n) _Pragma("unroll") for (int k = 0; k < 2; ++k) dst[n][k] = *(const LAS bf16x8*)(lds + PG8_SB(b, h) + boff + n * 2048 + k * 1024); } while (0)
; #define PG8_MMA(ai, bj, At, Bt) do { __builtin_amdgcn_s_setprio(1); _Pragma("unroll") for (int m = 0; m < 4; ++m) _Pragma("unroll") for (int n = 0; n < 2; ++n) _Pragma("unroll") for (int k = 0; k < 2; ++k) \
;         acc[ai][bj][m][n] = __builtin_amdgcn_mfma_f32_16x16x32_bf16(Bt[n][k], At[m][k], acc[ai][bj][m][n], 0, 0, 0); __builtin_amdgcn_s_setprio(0); } while (0)
; #define PG8_WAIT_L(n) asm volatile("s_waitcnt lgkmcnt(" #n ")" ::: "memory")
; #define PG8_BAR __builtin_amdgcn_s_barrier()
; template <class Epi>
; DI void gemm_phase(LAS unsigned char* lds, int wid, int K, int lda, int ldb, bool bperm, const Sched3& S, const Epi& E) {
;     ...
;             PG8_LDB(B1, 1, 1); PG8_STAGE(PG8_SB(1, 0), b3, voffB);
;             PG8_BAR; PG8_WAIT_L(0); PG8_MMA(0, 1, At, B1); PG8_BAR;
	s_add_i32 m0, s51, 0x1f80
	s_nop 0
	global_load_lds_dwordx4 v146, s[48:49] offset:128
	s_barrier
	s_waitcnt lgkmcnt(0)
	s_setprio 1
	s_waitcnt lgkmcnt(0)
	v_mfma_f32_16x16x32_bf16 v[116:119], v[192:195], v[160:163], v[116:119]
	v_mfma_f32_16x16x32_bf16 v[112:115], v[200:203], v[160:163], v[112:115]
	v_mfma_f32_16x16x32_bf16 v[100:103], v[192:195], v[168:171], v[100:103]
	v_mfma_f32_16x16x32_bf16 v[96:99], v[200:203], v[168:171], v[96:99]
	v_mfma_f32_16x16x32_bf16 v[84:87], v[192:195], v[176:179], v[84:87]
	v_mfma_f32_16x16x32_bf16 v[80:83], v[200:203], v[176:179], v[80:83]
	v_mfma_f32_16x16x32_bf16 v[68:71], v[192:195], v[184:187], v[68:71]
	v_mfma_f32_16x16x32_bf16 v[64:67], v[200:203], v[184:187], v[64:67]
	v_mfma_f32_16x16x32_bf16 v[116:119], v[196:199], v[164:167], v[116:119]
	v_mfma_f32_16x16x32_bf16 v[112:115], v[204:207], v[164:167], v[112:115]
	v_mfma_f32_16x16x32_bf16 v[100:103], v[196:199], v[172:175], v[100:103]
	v_mfma_f32_16x16x32_bf16 v[96:99], v[204:207], v[172:175], v[96:99]
	v_mfma_f32_16x16x32_bf16 v[84:87], v[196:199], v[180:183], v[84:87]
	v_mfma_f32_16x16x32_bf16 v[80:83], v[204:207], v[180:183], v[80:83]
	v_mfma_f32_16x16x32_bf16 v[68:71], v[196:199], v[188:191], v[68:71]
	v_mfma_f32_16x16x32_bf16 v[64:67], v[204:207], v[188:191], v[64:67]
	s_setprio 0
	s_sub_i32 m0, s63, 0x80

; #define PG8_STAGE(bufoff, gbase, voff) do { _Pragma("unroll") for (int _i = 0; _i < 2; ++_i) \
;         __builtin_amdgcn_global_load_lds((const unsigned*)((const char*)(gbase) + (voff)[_i]), (LAS unsigned*)(lds + (bufoff) + ldsw + _i * 8192), 16, 0, 0); } while (0)
; #define PG8_LDA(dst, b, h) do { _Pragma("unroll") for (int m = 0; m < 4; ++m) _Pragma("unroll") for (int k = 0; k < 2; ++k) dst[m][k] = *(const LAS bf16x8*)(lds + PG8_SA(b, h) + aoff + m * 2048 + k * 1024); } while (0)
; #define PG8_MMA(ai, bj, At, Bt) do { __builtin_amdgcn_s_setprio(1); _Pragma("unroll") for (int m = 0; m < 4; ++m) _Pragma("unroll") for (int n = 0; n < 2; ++n) _Pragma("unroll") for (int k = 0; k < 2; ++k) \
;         acc[ai][bj][m][n] = __builtin_amdgcn_mfma_f32_16x16x32_bf16(Bt[n][k], At[m][k], acc[ai][bj][m][n], 0, 0, 0); __builtin_amdgcn_s_setprio(0); } while (0)
; #define PG8_WAIT_L(n) asm volatile("s_waitcnt lgkmcnt(" #n ")" ::: "memory")
; #define PG8_BAR __builtin_amdgcn_s_barrier()
; template <class Epi>
; DI void gemm_phase(LAS unsigned char* lds, int wid, int K, int lda, int ldb, bool bperm, const Sched3& S, const Epi& E) {
;     ...
;             PG8_BAR; PG8_WAIT_L(0); PG8_MMA(0, 1, At, B1); PG8_BAR;
;             PG8_LDA(At, 1, 1); PG8_STAGE(PG8_SA(1, 0), a3, voffA);
	s_barrier
	ds_read_b128 v[160:163], v231 offset:49152
	ds_read_b128 v[164:167], v231 offset:50176
	ds_read_b128 v[168:171], v231 offset:51200
	ds_read_b128 v[172:175], v231 offset:52224
	ds_read_b128 v[176:179], v231 offset:53248
	ds_read_b128 v[180:183], v231 offset:54272
	ds_read_b128 v[184:187], v231 offset:55296
	ds_read_b128 v[188:191], v231 offset:56320
	global_load_lds_dwordx4 v140, s[100:101] offset:128

; #define PG8_STAGE(bufoff, gbase, voff) do { _Pragma("unroll") for (int _i = 0; _i < 2; ++_i) \
;         __builtin_amdgcn_global_load_lds((const unsigned*)((const char*)(gbase) + (voff)[_i]), (LAS unsigned*)(lds + (bufoff) + ldsw + _i * 8192), 16, 0, 0); } while (0)
; #define PG8_LDA(dst, b, h) do { _Pragma("unroll") for (int m = 0; m < 4; ++m) _Pragma("unroll") for (int k = 0; k < 2; ++k) dst[m][k] = *(const LAS bf16x8*)(lds + PG8_SA(b, h) + aoff + m * 2048 + k * 1024); } while (0)
; #define PG8_MMA(ai, bj, At, Bt) do { __builtin_amdgcn_s_setprio(1); _Pragma("unroll") for (int m = 0; m < 4; ++m) _Pragma("unroll") for (int n = 0; n < 2; ++n) _Pragma("unroll") for (int k = 0; k < 2; ++k) \
;         acc[ai][bj][m][n] = __builtin_amdgcn_mfma_f32_16x16x32_bf16(Bt[n][k], At[m][k], acc[ai][bj][m][n], 0, 0, 0); __builtin_amdgcn_s_setprio(0); } while (0)
; #define PG8_WAIT_L(n) asm volatile("s_waitcnt lgkmcnt(" #n ")" ::: "memory")
; #define PG8_BAR __builtin_amdgcn_s_barrier()
; #define PG8_SCHED __builtin_amdgcn_sched_barrier(0)
; template <class Epi>
; DI void gemm_phase(LAS unsigned char* lds, int wid, int K, int lda, int ldb, bool bperm, const Sched3& S, const Epi& E) {
;     ...
;             PG8_LDA(At, 1, 1); PG8_STAGE(PG8_SA(1, 0), a3, voffA);
;             PG8_BAR; PG8_WAIT_L(0); if (full) PG8_MMA(1, 0, At, B0); PG8_BAR; PG8_SCHED;
;             PG8_STAGE(PG8_SB(1, 1), b3 + hstepB, voffB);
	s_sub_i32 m0, s64, 0x80
	s_nop 0
	global_load_lds_dwordx4 v144, s[100:101] offset:128
	s_barrier
	s_waitcnt lgkmcnt(0)
	s_setprio 1
	s_waitcnt lgkmcnt(0)
	v_mfma_f32_16x16x32_bf16 v[60:63], v[128:131], v[160:163], v[60:63]
	v_mfma_f32_16x16x32_bf16 v[56:59], v[136:139], v[160:163], v[56:59]
	v_mfma_f32_16x16x32_bf16 v[44:47], v[128:131], v[168:171], v[44:47]
	v_mfma_f32_16x16x32_bf16 v[40:43], v[136:139], v[168:171], v[40:43]
	v_mfma_f32_16x16x32_bf16 v[28:31], v[128:131], v[176:179], v[28:31]
	v_mfma_f32_16x16x32_bf16 v[24:27], v[136:139], v[176:179], v[24:27]
	v_mfma_f32_16x16x32_bf16 v[12:15], v[128:131], v[184:187], v[12:15]
	v_mfma_f32_16x16x32_bf16 v[8:11], v[136:139], v[184:187], v[8:11]
	v_mfma_f32_16x16x32_bf16 v[60:63], v[132:135], v[164:167], v[60:63]
	v_mfma_f32_16x16x32_bf16 v[56:59], v[156:159], v[164:167], v[56:59]
	v_mfma_f32_16x16x32_bf16 v[44:47], v[132:135], v[172:175], v[44:47]
	v_mfma_f32_16x16x32_bf16 v[40:43], v[156:159], v[172:175], v[40:43]
	v_mfma_f32_16x16x32_bf16 v[28:31], v[132:135], v[180:183], v[28:31]
	v_mfma_f32_16x16x32_bf16 v[24:27], v[156:159], v[180:183], v[24:27]
	v_mfma_f32_16x16x32_bf16 v[12:15], v[132:135], v[188:191], v[12:15]
	v_mfma_f32_16x16x32_bf16 v[8:11], v[156:159], v[188:191], v[8:11]
	s_setprio 0
	s_barrier
	s_add_u32 s48, s48, 0x80080
	s_addc_u32 s49, s49, 0
	s_add_i32 s50, s50, s57

; #define PG8_STAGE(bufoff, gbase, voff) do { _Pragma("unroll") for (int _i = 0; _i < 2; ++_i) \
;         __builtin_amdgcn_global_load_lds((const unsigned*)((const char*)(gbase) + (voff)[_i]), (LAS unsigned*)(lds + (bufoff) + ldsw + _i * 8192), 16, 0, 0); } while (0)
; template <class Epi>
; DI void gemm_phase(LAS unsigned char* lds, int wid, int K, int lda, int ldb, bool bperm, const Sched3& S, const Epi& E) {
;     ...
;             PG8_STAGE(PG8_SB(1, 1), b3 + hstepB, voffB);
	s_mov_b32 m0, s50
	s_nop 0
	global_load_lds_dwordx4 v142, s[48:49]

; DI float gelu_tanh(float x) { const float t = x * (1.5957691216f + 0.0713548163f * x * x); return x * __builtin_amdgcn_rcpf(1.f + __builtin_amdgcn_exp2f(-1.4426950409f * t)); }
; #define PG8_STAGE(bufoff, gbase, voff) do { _Pragma("unroll") for (int _i = 0; _i < 2; ++_i) \
;         __builtin_amdgcn_global_load_lds((const unsigned*)((const char*)(gbase) + (voff)[_i]), (LAS unsigned*)(lds + (bufoff) + ldsw + _i * 8192), 16, 0, 0); } while (0)
; #define PG8_MMA(ai, bj, At, Bt) do { __builtin_amdgcn_s_setprio(1); _Pragma("unroll") for (int m = 0; m < 4; ++m) _Pragma("unroll") for (int n = 0; n < 2; ++n) _Pragma("unroll") for (int k = 0; k < 2; ++k) \
;         acc[ai][bj][m][n] = __builtin_amdgcn_mfma_f32_16x16x32_bf16(Bt[n][k], At[m][k], acc[ai][bj][m][n], 0, 0, 0); __builtin_amdgcn_s_setprio(0); } while (0)
; #define PG8_WAIT_V(n) asm volatile("s_waitcnt vmcnt(" #n ")" ::: "memory")
; #define PG8_BAR __builtin_amdgcn_s_barrier()
; #define ROWS8 _Pragma("unroll") for (int ai = 0; ai < 2; ++ai) _Pragma("unroll") for (int m = 0; m < 4; ++m) if (ai == 0 || !hf)
; #define PK8(v0, v1) ({ const u32x2 h0_ = pk4(v0), h1_ = pk4(v1); (u32x4){h0_.x, h0_.y, h1_.x, h1_.y}; })
; template <class Epi>
; DI void gemm_phase(LAS unsigned char* lds, int wid, int K, int lda, int ldb, bool bperm, const Sched3& S, const Epi& E) {
;     ...
;             PG8_STAGE(PG8_SB(1, 1), b3 + hstepB, voffB);
;             PG8_WAIT_V(6); PG8_BAR; if (full) PG8_MMA(1, 1, At, B1); PG8_BAR;
;         }
;     DI void operator()(const Acc& acc, const Unit& u, int wr, int wc, int fr, int fq) const {
;     ...
;                 float* ssqv = SSQ(1 + sqo);
;                 LOAD_COLP_RS(rsc, SSQ(0), 1.f / 2048.f);
; #pragma unroll
;                 for (int bj = 0; bj < 2; ++bj) { const int cc = colp + bj * HALF;
;                     f32x4 sq0 = {0.f, 0.f, 0.f, 0.f}, sq1 = {0.f, 0.f, 0.f, 0.f};
;                     ROWS8 { const int r = row0 + ai * HALF + m * 16; f32x4 v0 = acc[ai][bj][m][0] * rsc[bj][0], v1 = acc[ai][bj][m][1] * rsc[bj][1];
;                         v0[0] = gelu_tanh(v0[0]); v0[1] = gelu_tanh(v0[1]); v0[2] = gelu_tanh(v0[2]); v0[3] = gelu_tanh(v0[3]);
;                         v1[0] = gelu_tanh(v1[0]); v1[1] = gelu_tanh(v1[1]); v1[2] = gelu_tanh(v1[2]); v1[3] = gelu_tanh(v1[3]);
;                         sq0 += v0 * v0; sq1 += v1 * v1; *(u32x4*)(WSB(OFF_VT) + (size_t)r * 8192 + cc) = PK8(v0, v1); }
	s_add_i32 m0, s50, 0x2000
	s_nop 0
	global_load_lds_dwordx4 v146, s[48:49]
	s_waitcnt vmcnt(6)
	s_barrier
	s_setprio 1
	v_mfma_f32_16x16x32_bf16 v[52:55], v[192:195], v[160:163], v[52:55]
	v_mfma_f32_16x16x32_bf16 v[48:51], v[200:203], v[160:163], v[48:51]
	v_mfma_f32_16x16x32_bf16 v[36:39], v[192:195], v[168:171], v[36:39]
	v_mfma_f32_16x16x32_bf16 v[32:35], v[200:203], v[168:171], v[32:35]
	v_mfma_f32_16x16x32_bf16 v[20:23], v[192:195], v[176:179], v[20:23]
	v_mfma_f32_16x16x32_bf16 v[16:19], v[200:203], v[176:179], v[16:19]
	v_mfma_f32_16x16x32_bf16 v[4:7], v[192:195], v[184:187], v[4:7]
	v_mfma_f32_16x16x32_bf16 v[0:3], v[200:203], v[184:187], v[0:3]
	v_mfma_f32_16x16x32_bf16 v[52:55], v[196:199], v[164:167], v[52:55]
	v_mfma_f32_16x16x32_bf16 v[48:51], v[204:207], v[164:167], v[48:51]
	v_mfma_f32_16x16x32_bf16 v[36:39], v[196:199], v[172:175], v[36:39]
	v_mfma_f32_16x16x32_bf16 v[32:35], v[204:207], v[172:175], v[32:35]
	v_mfma_f32_16x16x32_bf16 v[20:23], v[196:199], v[180:183], v[20:23]
	v_mfma_f32_16x16x32_bf16 v[16:19], v[204:207], v[180:183], v[16:19]
	v_mfma_f32_16x16x32_bf16 v[4:7], v[196:199], v[188:191], v[4:7]
	v_mfma_f32_16x16x32_bf16 v[0:3], v[204:207], v[188:191], v[0:3]
	s_setprio 0
	s_add_i32 s55, s55, 2
	s_add_u32 s46, s46, 0x100
	s_addc_u32 s47, s47, 0
	s_add_u32 s53, s53, 0x100
	s_addc_u32 s54, s54, 0
	s_cmp_gt_u32 s55, 29
	s_cbranch_scc0 .Lkrot_0_head
.Lkrot_0_exit:
	s_barrier
.Lpeel_0_exit:
	v_lshl_add_u32 v158, s4, 8, v223
	v_lshl_add_u32 v156, s73, 8, v225
	v_or_b32_e32 v164, 16, v158
	v_or_b32_e32 v162, 32, v158
	v_or_b32_e32 v160, 48, v158
	s_cmp_lg_u32 s74, 0
	v_ashrrev_i32_e32 v157, 31, v156
	v_ashrrev_i32_e32 v159, 31, v158
	v_ashrrev_i32_e32 v165, 31, v164
	v_ashrrev_i32_e32 v163, 31, v162
	v_ashrrev_i32_e32 v161, 31, v160
	s_cbranch_scc0 .LBB0_362
	v_lshlrev_b64 v[136:137], 2, v[156:157]
	v_lshl_add_u64 v[132:133], s[16:17], 0, v[136:137]
	global_load_dwordx4 v[166:169], v[132:133], off
	global_load_dwordx4 v[172:175], v[132:133], off offset:16
	v_lshlrev_b64 v[128:129], 14, v[158:159]
	v_lshlrev_b64 v[170:171], 1, v[156:157]
	v_lshl_add_u64 v[138:139], s[20:21], 0, v[128:129]
	v_lshl_add_u64 v[138:139], v[138:139], 0, v[170:171]
	global_load_dwordx4 v[128:131], v[132:133], off offset:528
	s_nop 0
	global_load_dwordx4 v[132:135], v[132:133], off offset:512
	v_lshl_add_u64 v[136:137], s[18:19], 0, v[136:137]
	s_waitcnt vmcnt(0)
	v_fmamk_f32 v166, v166, 0x3a000000, v233
	v_fmamk_f32 v167, v167, 0x3a000000, v233
	v_fmamk_f32 v168, v168, 0x3a000000, v233
	v_fmamk_f32 v169, v169, 0x3a000000, v233
	v_rsq_f32_e32 v190, v166
	v_rsq_f32_e32 v191, v167
	v_rsq_f32_e32 v186, v168
	v_rsq_f32_e32 v187, v169
	v_fmamk_f32 v172, v172, 0x3a000000, v233
	v_fmamk_f32 v173, v173, 0x3a000000, v233
	v_fmamk_f32 v174, v174, 0x3a000000, v233
	v_fmamk_f32 v175, v175, 0x3a000000, v233
	v_rsq_f32_e32 v182, v172
	v_rsq_f32_e32 v184, v174
	v_rsq_f32_e32 v185, v175
	v_rsq_f32_e32 v183, v173
	v_pk_mul_f32 v[168:169], v[124:125], v[190:191]
	v_pk_mul_f32 v[166:167], v[126:127], v[186:187]
	v_mul_f32_e32 v178, 0x3d922279, v168
	v_mul_f32_e32 v179, 0x3d922279, v169
	v_mul_f32_e32 v192, 0x3d922279, v166
	v_mul_f32_e32 v193, 0x3d922279, v167
	v_fmaak_f32 v178, v168, v178, 0x3fcc422a
	v_fmaak_f32 v179, v169, v179, 0x3fcc422a
	v_pk_mul_f32 v[172:173], v[122:123], v[184:185]
	v_pk_mul_f32 v[174:175], v[120:121], v[182:183]
	v_fmaak_f32 v192, v166, v192, 0x3fcc422a
	v_fmaak_f32 v193, v167, v193, 0x3fcc422a
	v_mul_f32_e32 v178, v168, v178
	v_mul_f32_e32 v179, v169, v179
	v_mul_f32_e32 v196, 0x3d922279, v174
	v_mul_f32_e32 v197, 0x3d922279, v175
	v_mul_f32_e32 v198, 0x3d922279, v172
	v_mul_f32_e32 v199, 0x3d922279, v173
	v_mul_f32_e32 v192, v166, v192
	v_mul_f32_e32 v193, v167, v193
	v_mul_f32_e32 v178, 0xbfb8aa3b, v178
	v_mul_f32_e32 v179, 0xbfb8aa3b, v179
	v_fmaak_f32 v196, v174, v196, 0x3fcc422a
	v_fmaak_f32 v197, v175, v197, 0x3fcc422a
	v_fmaak_f32 v198, v172, v198, 0x3fcc422a
	v_fmaak_f32 v199, v173, v199, 0x3fcc422a
	v_mul_f32_e32 v192, 0xbfb8aa3b, v192
	v_mul_f32_e32 v193, 0xbfb8aa3b, v193
	v_exp_f32_e32 v178, v178
	v_exp_f32_e32 v179, v179
	v_mul_f32_e32 v196, v174, v196
	v_mul_f32_e32 v197, v175, v197
	v_mul_f32_e32 v198, v172, v198
	v_mul_f32_e32 v199, v173, v199
	v_exp_f32_e32 v192, v192
	v_exp_f32_e32 v193, v193
	v_mul_f32_e32 v196, 0xbfb8aa3b, v196
	v_mul_f32_e32 v197, 0xbfb8aa3b, v197
	v_mul_f32_e32 v198, 0xbfb8aa3b, v198
	v_mul_f32_e32 v199, 0xbfb8aa3b, v199
	v_exp_f32_e32 v196, v196
	v_exp_f32_e32 v197, v197
	v_exp_f32_e32 v198, v198
	v_exp_f32_e32 v199, v199
	v_add_f32_e32 v178, 1.0, v178
	v_add_f32_e32 v179, 1.0, v179
	v_add_f32_e32 v201, 1.0, v192
	v_add_f32_e32 v202, 1.0, v193
	v_rcp_f32_e32 v192, v178
	v_rcp_f32_e32 v193, v179
	v_add_f32_e32 v196, 1.0, v196
	v_add_f32_e32 v197, 1.0, v197
	v_add_f32_e32 v198, 1.0, v198
	v_add_f32_e32 v199, 1.0, v199
	v_pk_mul_f32 v[194:195], v[104:105], v[182:183]
	v_rcp_f32_e32 v178, v201
	v_rcp_f32_e32 v179, v202
	v_rcp_f32_e32 v196, v196
	v_rcp_f32_e32 v198, v198
	v_rcp_f32_e32 v199, v199
	v_rcp_f32_e32 v197, v197
	v_pk_mul_f32 v[202:203], v[168:169], v[192:193]
	v_mul_f32_e32 v192, 0x3d922279, v194
	v_fmaak_f32 v192, v194, v192, 0x3fcc422a
	v_mul_f32_e32 v192, v194, v192
	v_pk_mul_f32 v[178:179], v[166:167], v[178:179]
	v_pk_mul_f32 v[172:173], v[172:173], v[198:199]
	v_pk_mul_f32 v[174:175], v[174:175], v[196:197]
	v_mul_f32_e32 v192, 0xbfb8aa3b, v192
	v_pk_mul_f32 v[176:177], v[110:111], v[186:187]
	v_pk_mul_f32 v[188:189], v[106:107], v[184:185]
	v_cvt_pk_bf16_f32 v166, v202, v203
	v_cvt_pk_bf16_f32 v167, v178, v179
	v_cvt_pk_bf16_f32 v168, v174, v175
	v_cvt_pk_bf16_f32 v169, v172, v173
; DI float gelu_tanh(float x) { const float t = x * (1.5957691216f + 0.0713548163f * x * x); return x * __builtin_amdgcn_rcpf(1.f + __builtin_amdgcn_exp2f(-1.4426950409f * t)); }
; #define ROWS8 _Pragma("unroll") for (int ai = 0; ai < 2; ++ai) _Pragma("unroll") for (int m = 0; m < 4; ++m) if (ai == 0 || !hf)
; #define PK8(v0, v1) ({ const u32x2 h0_ = pk4(v0), h1_ = pk4(v1); (u32x4){h0_.x, h0_.y, h1_.x, h1_.y}; })
;     DI void operator()(const Acc& acc, const Unit& u, int wr, int wc, int fr, int fq) const {
;     ...
;                 for (int bj = 0; bj < 2; ++bj) { const int cc = colp + bj * HALF;
;                     f32x4 sq0 = {0.f, 0.f, 0.f, 0.f}, sq1 = {0.f, 0.f, 0.f, 0.f};
;                     ROWS8 { const int r = row0 + ai * HALF + m * 16; f32x4 v0 = acc[ai][bj][m][0] * rsc[bj][0], v1 = acc[ai][bj][m][1] * rsc[bj][1];
;                         v0[0] = gelu_tanh(v0[0]); v0[1] = gelu_tanh(v0[1]); v0[2] = gelu_tanh(v0[2]); v0[3] = gelu_tanh(v0[3]);
;                         v1[0] = gelu_tanh(v1[0]); v1[1] = gelu_tanh(v1[1]); v1[2] = gelu_tanh(v1[2]); v1[3] = gelu_tanh(v1[3]);
;                         sq0 += v0 * v0; sq1 += v1 * v1; *(u32x4*)(WSB(OFF_VT) + (size_t)r * 8192 + cc) = PK8(v0, v1); }
	v_exp_f32_e32 v192, v192
	global_store_dwordx4 v[138:139], v[166:169], off
	v_mul_f32_e32 v193, 0x3d922279, v188
	v_fmaak_f32 v193, v188, v193, 0x3fcc422a
	v_mul_f32_e32 v168, 0x3d922279, v176
	v_mul_f32_e32 v169, 0x3d922279, v177
	v_fmaak_f32 v168, v176, v168, 0x3fcc422a
	v_fmaak_f32 v169, v177, v169, 0x3fcc422a
	v_mul_f32_e32 v197, 0x3d922279, v189
	v_mul_f32_e32 v168, v176, v168
	v_mul_f32_e32 v169, v177, v169
	v_mul_f32_e32 v193, v188, v193
	v_fmaak_f32 v197, v189, v197, 0x3fcc422a
	v_mul_f32_e32 v168, 0xbfb8aa3b, v168
	v_mul_f32_e32 v169, 0xbfb8aa3b, v169
	v_add_f32_e32 v192, 1.0, v192
	v_mul_f32_e32 v193, 0xbfb8aa3b, v193
	v_mul_f32_e32 v197, v189, v197
	v_exp_f32_e32 v168, v168
	v_exp_f32_e32 v169, v169
	v_rcp_f32_e32 v196, v192
	v_mul_f32_e32 v192, 0x3d922279, v195
	v_exp_f32_e32 v193, v193
	v_mul_f32_e32 v197, 0xbfb8aa3b, v197
	v_fmaak_f32 v192, v195, v192, 0x3fcc422a
	v_exp_f32_e32 v197, v197
	v_mul_f32_e32 v192, v195, v192
	v_mul_f32_e32 v192, 0xbfb8aa3b, v192
	v_add_f32_e32 v168, 1.0, v168
	v_add_f32_e32 v169, 1.0, v169
	v_exp_f32_e32 v192, v192
	v_add_f32_e32 v193, 1.0, v193
	v_pk_mul_f32 v[180:181], v[108:109], v[190:191]
	v_rcp_f32_e32 v168, v168
	v_rcp_f32_e32 v169, v169
	v_rcp_f32_e32 v198, v193
	v_add_f32_e32 v193, 1.0, v197
	v_mul_f32_e32 v200, 0x3d922279, v180
	v_mul_f32_e32 v167, 0x3d922279, v181
	v_rcp_f32_e32 v199, v193
	v_fmaak_f32 v200, v180, v200, 0x3fcc422a
	v_fmaak_f32 v167, v181, v167, 0x3fcc422a
	v_mul_f32_e32 v200, v180, v200
	v_mul_f32_e32 v167, v181, v167
	v_add_f32_e32 v192, 1.0, v192
	v_mul_f32_e32 v200, 0xbfb8aa3b, v200
	v_mul_f32_e32 v167, 0xbfb8aa3b, v167
	v_rcp_f32_e32 v197, v192
	v_pk_mul_f32 v[192:193], v[176:177], v[168:169]
	v_pk_mul_f32 v[168:169], v[92:93], v[190:191]
	v_exp_f32_e32 v200, v200
	v_exp_f32_e32 v167, v167
	v_pk_mul_f32 v[176:177], v[188:189], v[198:199]
	v_mul_f32_e32 v188, 0x3d922279, v168
	v_fmaak_f32 v188, v168, v188, 0x3fcc422a
	v_mul_f32_e32 v188, v168, v188
	v_mul_f32_e32 v188, 0xbfb8aa3b, v188
	v_add_f32_e32 v166, 1.0, v200
	v_add_f32_e32 v167, 1.0, v167
	v_exp_f32_e32 v198, v188
	v_pk_mul_f32 v[188:189], v[94:95], v[186:187]
	v_mul_f32_e32 v199, 0x3d922279, v169
	v_rcp_f32_e32 v166, v166
	v_rcp_f32_e32 v167, v167
	v_fmaak_f32 v199, v169, v199, 0x3fcc422a
	v_mul_f32_e32 v200, 0x3d922279, v188
	v_mul_f32_e32 v199, v169, v199
	v_fmaak_f32 v200, v188, v200, 0x3fcc422a
	v_mul_f32_e32 v199, 0xbfb8aa3b, v199
	v_mul_f32_e32 v200, v188, v200
	v_exp_f32_e32 v199, v199
	v_mul_f32_e32 v200, 0xbfb8aa3b, v200
	v_pk_mul_f32 v[210:211], v[180:181], v[166:167]
	v_lshlrev_b64 v[166:167], 14, v[164:165]
	v_exp_f32_e32 v204, v200
	v_pk_mul_f32 v[180:181], v[194:195], v[196:197]
	v_lshl_add_u64 v[166:167], s[20:21], 0, v[166:167]
	v_cvt_pk_bf16_f32 v194, v210, v211
	v_cvt_pk_bf16_f32 v195, v192, v193
	v_cvt_pk_bf16_f32 v196, v180, v181
	v_cvt_pk_bf16_f32 v197, v176, v177
	v_lshl_add_u64 v[166:167], v[166:167], 0, v[170:171]
	v_add_f32_e32 v198, 1.0, v198
	global_store_dwordx4 v[166:167], v[194:197], off
	v_rcp_f32_e32 v200, v198
	v_add_f32_e32 v198, 1.0, v199
	v_pk_mul_f32 v[194:195], v[90:91], v[184:185]
	v_pk_mul_f32 v[196:197], v[88:89], v[182:183]
	v_rcp_f32_e32 v201, v198
	v_add_f32_e32 v198, 1.0, v204
	v_mul_f32_e32 v199, 0x3d922279, v189
	v_mul_f32_e32 v204, 0x3d922279, v196
	v_mul_f32_e32 v205, 0x3d922279, v197
	v_mul_f32_e32 v206, 0x3d922279, v194
	v_mul_f32_e32 v207, 0x3d922279, v195
	v_fmaak_f32 v199, v189, v199, 0x3fcc422a
	v_fmaak_f32 v204, v196, v204, 0x3fcc422a
	v_fmaak_f32 v205, v197, v205, 0x3fcc422a
	v_fmaak_f32 v206, v194, v206, 0x3fcc422a
	v_fmaak_f32 v207, v195, v207, 0x3fcc422a
	v_mul_f32_e32 v199, v189, v199
	v_mul_f32_e32 v204, v196, v204
	v_mul_f32_e32 v205, v197, v205
	v_mul_f32_e32 v206, v194, v206
	v_mul_f32_e32 v207, v195, v207
	v_mul_f32_e32 v199, 0xbfb8aa3b, v199
	v_mul_f32_e32 v204, 0xbfb8aa3b, v204
	v_mul_f32_e32 v205, 0xbfb8aa3b, v205
	v_mul_f32_e32 v206, 0xbfb8aa3b, v206
	v_mul_f32_e32 v207, 0xbfb8aa3b, v207
	v_exp_f32_e32 v199, v199
	v_exp_f32_e32 v204, v204
	v_exp_f32_e32 v205, v205
	v_exp_f32_e32 v206, v206
	v_exp_f32_e32 v207, v207
	v_add_f32_e32 v199, 1.0, v199
	v_add_f32_e32 v204, 1.0, v204
	v_add_f32_e32 v205, 1.0, v205
	v_add_f32_e32 v206, 1.0, v206
	v_add_f32_e32 v207, 1.0, v207
	v_rcp_f32_e32 v198, v198
	v_rcp_f32_e32 v199, v199
	v_rcp_f32_e32 v204, v204
	v_rcp_f32_e32 v206, v206
	v_rcp_f32_e32 v207, v207
	v_rcp_f32_e32 v205, v205
	v_pk_mul_f32 v[198:199], v[188:189], v[198:199]
	v_pk_mul_f32 v[212:213], v[168:169], v[200:201]
	v_pk_mul_f32 v[188:189], v[194:195], v[206:207]
	v_pk_mul_f32 v[194:195], v[196:197], v[204:205]
	v_pk_mul_f32 v[196:197], v[76:77], v[190:191]
	v_lshlrev_b64 v[168:169], 14, v[162:163]
	v_mul_f32_e32 v200, 0x3d922279, v196
	v_fmaak_f32 v200, v196, v200, 0x3fcc422a
	v_lshl_add_u64 v[168:169], s[20:21], 0, v[168:169]
	v_mul_f32_e32 v200, v196, v200
	v_cvt_pk_bf16_f32 v204, v212, v213
	v_cvt_pk_bf16_f32 v205, v198, v199
	v_cvt_pk_bf16_f32 v206, v194, v195
	v_cvt_pk_bf16_f32 v207, v188, v189
	v_lshl_add_u64 v[168:169], v[168:169], 0, v[170:171]
	v_mul_f32_e32 v200, 0xbfb8aa3b, v200
	global_store_dwordx4 v[168:169], v[204:207], off
	v_pk_mul_f32 v[208:209], v[72:73], v[182:183]
	s_nop 0
	v_exp_f32_e32 v204, v200
	v_pk_mul_f32 v[200:201], v[78:79], v[186:187]
	v_mul_f32_e32 v205, 0x3d922279, v197
	v_fmaak_f32 v205, v197, v205, 0x3fcc422a
	v_mul_f32_e32 v214, 0x3d922279, v200
	v_mul_f32_e32 v205, v197, v205
	v_fmaak_f32 v214, v200, v214, 0x3fcc422a
	v_mul_f32_e32 v205, 0xbfb8aa3b, v205
	v_mul_f32_e32 v214, v200, v214
	v_exp_f32_e32 v205, v205
	v_mul_f32_e32 v214, 0xbfb8aa3b, v214
	v_exp_f32_e32 v216, v214
	v_add_f32_e32 v204, 1.0, v204
; DI float gelu_tanh(float x) { const float t = x * (1.5957691216f + 0.0713548163f * x * x); return x * __builtin_amdgcn_rcpf(1.f + __builtin_amdgcn_exp2f(-1.4426950409f * t)); }
; #define ROWS8 _Pragma("unroll") for (int ai = 0; ai < 2; ++ai) _Pragma("unroll") for (int m = 0; m < 4; ++m) if (ai == 0 || !hf)
; #define PK8(v0, v1) ({ const u32x2 h0_ = pk4(v0), h1_ = pk4(v1); (u32x4){h0_.x, h0_.y, h1_.x, h1_.y}; })
;     DI void operator()(const Acc& acc, const Unit& u, int wr, int wc, int fr, int fq) const {
;     ...
;                 for (int bj = 0; bj < 2; ++bj) { const int cc = colp + bj * HALF;
;                     f32x4 sq0 = {0.f, 0.f, 0.f, 0.f}, sq1 = {0.f, 0.f, 0.f, 0.f};
;                     ROWS8 { const int r = row0 + ai * HALF + m * 16; f32x4 v0 = acc[ai][bj][m][0] * rsc[bj][0], v1 = acc[ai][bj][m][1] * rsc[bj][1];
;                         v0[0] = gelu_tanh(v0[0]); v0[1] = gelu_tanh(v0[1]); v0[2] = gelu_tanh(v0[2]); v0[3] = gelu_tanh(v0[3]);
;                         v1[0] = gelu_tanh(v1[0]); v1[1] = gelu_tanh(v1[1]); v1[2] = gelu_tanh(v1[2]); v1[3] = gelu_tanh(v1[3]);
;                         sq0 += v0 * v0; sq1 += v1 * v1; *(u32x4*)(WSB(OFF_VT) + (size_t)r * 8192 + cc) = PK8(v0, v1); }
	v_rcp_f32_e32 v214, v204
	v_add_f32_e32 v204, 1.0, v205
	v_pk_mul_f32 v[206:207], v[74:75], v[184:185]
	v_rcp_f32_e32 v215, v204
	v_add_f32_e32 v204, 1.0, v216
	v_mul_f32_e32 v205, 0x3d922279, v201
	v_mul_f32_e32 v216, 0x3d922279, v208
	v_mul_f32_e32 v217, 0x3d922279, v209
	v_fmaak_f32 v205, v201, v205, 0x3fcc422a
	v_fmaak_f32 v216, v208, v216, 0x3fcc422a
	v_fmaak_f32 v217, v209, v217, 0x3fcc422a
	v_mul_f32_e32 v218, 0x3d922279, v206
	v_mul_f32_e32 v219, 0x3d922279, v207
	v_mul_f32_e32 v205, v201, v205
	v_mul_f32_e32 v216, v208, v216
	v_mul_f32_e32 v217, v209, v217
	v_fmaak_f32 v218, v206, v218, 0x3fcc422a
	v_fmaak_f32 v219, v207, v219, 0x3fcc422a
	v_mul_f32_e32 v205, 0xbfb8aa3b, v205
	v_mul_f32_e32 v216, 0xbfb8aa3b, v216
	v_mul_f32_e32 v217, 0xbfb8aa3b, v217
	v_mul_f32_e32 v218, v206, v218
	v_mul_f32_e32 v219, v207, v219
	v_exp_f32_e32 v205, v205
	v_exp_f32_e32 v216, v216
	v_exp_f32_e32 v217, v217
	v_mul_f32_e32 v218, 0xbfb8aa3b, v218
	v_mul_f32_e32 v219, 0xbfb8aa3b, v219
	v_exp_f32_e32 v218, v218
	v_exp_f32_e32 v219, v219
	v_add_f32_e32 v205, 1.0, v205
	v_add_f32_e32 v216, 1.0, v216
	v_add_f32_e32 v217, 1.0, v217
	v_rcp_f32_e32 v204, v204
	v_rcp_f32_e32 v205, v205
	v_rcp_f32_e32 v216, v216
	v_add_f32_e32 v218, 1.0, v218
	v_add_f32_e32 v219, 1.0, v219
	v_rcp_f32_e32 v217, v217
	v_rcp_f32_e32 v218, v218
	v_rcp_f32_e32 v219, v219
	v_pk_mul_f32 v[204:205], v[200:201], v[204:205]
	v_pk_mul_f32 v[200:201], v[208:209], v[216:217]
	v_lshlrev_b64 v[216:217], 14, v[160:161]
	v_pk_mul_f32 v[214:215], v[196:197], v[214:215]
	v_pk_mul_f32 v[196:197], v[206:207], v[218:219]
	v_lshl_add_u64 v[216:217], s[20:21], 0, v[216:217]
	v_cvt_pk_bf16_f32 v206, v214, v215
	v_cvt_pk_bf16_f32 v207, v204, v205
	v_cvt_pk_bf16_f32 v208, v200, v201
	v_cvt_pk_bf16_f32 v209, v196, v197
	v_lshl_add_u64 v[170:171], v[216:217], 0, v[170:171]
	global_store_dwordx4 v[170:171], v[206:209], off
	s_nop 1
	v_pk_mul_f32 v[206:207], v[210:211], v[210:211]
	s_nop 0
	v_pk_fma_f32 v[202:203], v[202:203], v[202:203], v[206:207]
	s_nop 0
	v_pk_fma_f32 v[202:203], v[212:213], v[212:213], v[202:203]
	v_pk_mul_f32 v[212:213], v[58:59], v[184:185]
	v_pk_fma_f32 v[208:209], v[214:215], v[214:215], v[202:203]
	v_pk_mul_f32 v[202:203], v[60:61], v[190:191]
	v_pk_mul_f32 v[214:215], v[56:57], v[182:183]
	v_mul_f32_e32 v206, 0x3d922279, v202
	v_fmaak_f32 v206, v202, v206, 0x3fcc422a
	v_mul_f32_e32 v206, v202, v206
	v_mul_f32_e32 v206, 0xbfb8aa3b, v206
	v_exp_f32_e32 v210, v206
	v_pk_mul_f32 v[206:207], v[62:63], v[186:187]
	v_mul_f32_e32 v211, 0x3d922279, v203
	v_fmaak_f32 v211, v203, v211, 0x3fcc422a
	v_mul_f32_e32 v216, 0x3d922279, v206
	v_mul_f32_e32 v211, v203, v211
	v_fmaak_f32 v216, v206, v216, 0x3fcc422a
	v_mul_f32_e32 v211, 0xbfb8aa3b, v211
	v_mul_f32_e32 v216, v206, v216
	v_exp_f32_e32 v211, v211
	v_mul_f32_e32 v216, 0xbfb8aa3b, v216
	v_exp_f32_e32 v218, v216
	v_add_f32_e32 v210, 1.0, v210
	v_rcp_f32_e32 v216, v210
	v_add_f32_e32 v210, 1.0, v211
	v_rcp_f32_e32 v217, v210
	v_add_f32_e32 v210, 1.0, v218
	v_mul_f32_e32 v211, 0x3d922279, v207
	v_mul_f32_e32 v218, 0x3d922279, v214
	v_mul_f32_e32 v219, 0x3d922279, v215
	v_mul_f32_e32 v220, 0x3d922279, v212
	v_mul_f32_e32 v221, 0x3d922279, v213
	v_fmaak_f32 v211, v207, v211, 0x3fcc422a
	v_fmaak_f32 v218, v214, v218, 0x3fcc422a
	v_fmaak_f32 v219, v215, v219, 0x3fcc422a
	v_fmaak_f32 v220, v212, v220, 0x3fcc422a
	v_fmaak_f32 v221, v213, v221, 0x3fcc422a
	v_mul_f32_e32 v211, v207, v211
	v_mul_f32_e32 v218, v214, v218
	v_mul_f32_e32 v219, v215, v219
	v_mul_f32_e32 v220, v212, v220
	v_mul_f32_e32 v221, v213, v221
	v_mul_f32_e32 v211, 0xbfb8aa3b, v211
	v_mul_f32_e32 v218, 0xbfb8aa3b, v218
	v_mul_f32_e32 v219, 0xbfb8aa3b, v219
	v_mul_f32_e32 v220, 0xbfb8aa3b, v220
	v_mul_f32_e32 v221, 0xbfb8aa3b, v221
	v_exp_f32_e32 v211, v211
	v_exp_f32_e32 v218, v218
	v_exp_f32_e32 v219, v219
	v_exp_f32_e32 v220, v220
	v_exp_f32_e32 v221, v221
	v_add_f32_e32 v211, 1.0, v211
	v_add_f32_e32 v218, 1.0, v218
	v_add_f32_e32 v219, 1.0, v219
	v_add_f32_e32 v220, 1.0, v220
	v_add_f32_e32 v221, 1.0, v221
	v_rcp_f32_e32 v210, v210
	v_rcp_f32_e32 v211, v211
	v_rcp_f32_e32 v218, v218
	v_rcp_f32_e32 v220, v220
	v_rcp_f32_e32 v221, v221
	v_rcp_f32_e32 v219, v219
	v_pk_mul_f32 v[216:217], v[202:203], v[216:217]
	v_pk_mul_f32 v[210:211], v[206:207], v[210:211]
	v_pk_mul_f32 v[202:203], v[212:213], v[220:221]
	v_pk_mul_f32 v[206:207], v[214:215], v[218:219]
	v_pk_fma_f32 v[218:219], v[216:217], v[216:217], v[208:209]
	v_add_co_u32_e32 v208, vcc, s69, v138
	v_cvt_pk_bf16_f32 v212, v216, v217
	v_cvt_pk_bf16_f32 v213, v210, v211
	v_cvt_pk_bf16_f32 v214, v206, v207
	v_cvt_pk_bf16_f32 v215, v202, v203
	v_addc_co_u32_e32 v209, vcc, 0, v139, vcc
	global_store_dwordx4 v[208:209], v[212:215], off
	v_pk_mul_f32 v[208:209], v[44:45], v[190:191]
	v_pk_mul_f32 v[220:221], v[40:41], v[182:183]
	v_mul_f32_e32 v212, 0x3d922279, v208
	v_fmaak_f32 v212, v208, v212, 0x3fcc422a
	v_mul_f32_e32 v212, v208, v212
	v_mul_f32_e32 v212, 0xbfb8aa3b, v212
	v_exp_f32_e32 v216, v212
	v_pk_mul_f32 v[212:213], v[46:47], v[186:187]
	v_pk_mul_f32 v[214:215], v[42:43], v[184:185]
	v_mul_f32_e32 v234, 0x3d922279, v213
	v_fmaak_f32 v234, v213, v234, 0x3fcc422a
	v_mul_f32_e32 v222, 0x3d922279, v212
	v_mul_f32_e32 v234, v213, v234
	v_fmaak_f32 v222, v212, v222, 0x3fcc422a
	v_mul_f32_e32 v234, 0xbfb8aa3b, v234
	v_mul_f32_e32 v222, v212, v222
	v_exp_f32_e32 v235, v234
	v_mul_f32_e32 v234, 0x3d922279, v220
	v_mul_f32_e32 v222, 0xbfb8aa3b, v222
	v_fmaak_f32 v234, v220, v234, 0x3fcc422a
	v_exp_f32_e32 v222, v222
	v_mul_f32_e32 v234, v220, v234
	v_mul_f32_e32 v234, 0xbfb8aa3b, v234
	v_exp_f32_e32 v236, v234
; DI float gelu_tanh(float x) { const float t = x * (1.5957691216f + 0.0713548163f * x * x); return x * __builtin_amdgcn_rcpf(1.f + __builtin_amdgcn_exp2f(-1.4426950409f * t)); }
; #define ROWS8 _Pragma("unroll") for (int ai = 0; ai < 2; ++ai) _Pragma("unroll") for (int m = 0; m < 4; ++m) if (ai == 0 || !hf)
; #define PK8(v0, v1) ({ const u32x2 h0_ = pk4(v0), h1_ = pk4(v1); (u32x4){h0_.x, h0_.y, h1_.x, h1_.y}; })
;     DI void operator()(const Acc& acc, const Unit& u, int wr, int wc, int fr, int fq) const {
;     ...
;                 for (int bj = 0; bj < 2; ++bj) { const int cc = colp + bj * HALF;
;                     f32x4 sq0 = {0.f, 0.f, 0.f, 0.f}, sq1 = {0.f, 0.f, 0.f, 0.f};
;                     ROWS8 { const int r = row0 + ai * HALF + m * 16; f32x4 v0 = acc[ai][bj][m][0] * rsc[bj][0], v1 = acc[ai][bj][m][1] * rsc[bj][1];
;                         v0[0] = gelu_tanh(v0[0]); v0[1] = gelu_tanh(v0[1]); v0[2] = gelu_tanh(v0[2]); v0[3] = gelu_tanh(v0[3]);
;                         v1[0] = gelu_tanh(v1[0]); v1[1] = gelu_tanh(v1[1]); v1[2] = gelu_tanh(v1[2]); v1[3] = gelu_tanh(v1[3]);
;                         sq0 += v0 * v0; sq1 += v1 * v1; *(u32x4*)(WSB(OFF_VT) + (size_t)r * 8192 + cc) = PK8(v0, v1); }
; #pragma unroll
;                     for (int j = 0; j < 8; ++j) { float t = j < 4 ? sq0[j & 3] : sq1[j & 3];
;                         t += __shfl_xor(t, 1); t += __shfl_xor(t, 2); t += __shfl_xor(t, 4); t += __shfl_xor(t, 8);
	v_add_f32_e32 v222, 1.0, v222
	v_rcp_f32_e32 v234, v222
	v_add_f32_e32 v222, 1.0, v235
	v_rcp_f32_e32 v235, v222
	v_add_f32_e32 v222, 1.0, v236
	v_mul_f32_e32 v237, 0x3d922279, v214
	v_mul_f32_e32 v217, 0x3d922279, v209
	v_rcp_f32_e32 v236, v222
	v_mul_f32_e32 v222, 0x3d922279, v221
	v_fmaak_f32 v237, v214, v237, 0x3fcc422a
	v_mul_f32_e32 v238, 0x3d922279, v215
	v_fmaak_f32 v217, v209, v217, 0x3fcc422a
	v_fmaak_f32 v222, v221, v222, 0x3fcc422a
	v_mul_f32_e32 v237, v214, v237
	v_fmaak_f32 v238, v215, v238, 0x3fcc422a
	v_mul_f32_e32 v217, v209, v217
	v_mul_f32_e32 v222, v221, v222
	v_mul_f32_e32 v237, 0xbfb8aa3b, v237
	v_mul_f32_e32 v238, v215, v238
	v_mul_f32_e32 v217, 0xbfb8aa3b, v217
	v_mul_f32_e32 v222, 0xbfb8aa3b, v222
	v_exp_f32_e32 v237, v237
	v_mul_f32_e32 v238, 0xbfb8aa3b, v238
	v_exp_f32_e32 v217, v217
	v_exp_f32_e32 v222, v222
	v_exp_f32_e32 v239, v238
	v_add_f32_e32 v237, 1.0, v237
	v_add_f32_e32 v216, 1.0, v216
	v_add_f32_e32 v217, 1.0, v217
	v_add_f32_e32 v222, 1.0, v222
	v_rcp_f32_e32 v238, v237
	v_add_f32_e32 v237, 1.0, v239
	v_rcp_f32_e32 v216, v216
	v_rcp_f32_e32 v217, v217
	v_rcp_f32_e32 v239, v237
	v_rcp_f32_e32 v237, v222
	v_pk_mul_f32 v[240:241], v[208:209], v[216:217]
	v_pk_mul_f32 v[216:217], v[212:213], v[234:235]
	v_pk_mul_f32 v[208:209], v[214:215], v[238:239]
	v_pk_mul_f32 v[212:213], v[220:221], v[236:237]
	v_add_co_u32_e32 v214, vcc, s70, v138
	v_pk_fma_f32 v[234:235], v[240:241], v[240:241], v[218:219]
	v_cvt_pk_bf16_f32 v218, v240, v241
	v_cvt_pk_bf16_f32 v219, v216, v217
	v_cvt_pk_bf16_f32 v220, v212, v213
	v_cvt_pk_bf16_f32 v221, v208, v209
	v_addc_co_u32_e32 v215, vcc, 0, v139, vcc
	global_store_dwordx4 v[214:215], v[218:221], off
	v_pk_mul_f32 v[214:215], v[28:29], v[190:191]
	v_pk_mul_f32 v[238:239], v[24:25], v[182:183]
	v_mul_f32_e32 v218, 0x3d922279, v214
	v_fmaak_f32 v218, v214, v218, 0x3fcc422a
	v_mul_f32_e32 v218, v214, v218
	v_mul_f32_e32 v218, 0xbfb8aa3b, v218
	v_exp_f32_e32 v220, v218
	v_pk_mul_f32 v[218:219], v[30:31], v[186:187]
	v_mul_f32_e32 v221, 0x3d922279, v215
	v_fmaak_f32 v221, v215, v221, 0x3fcc422a
	v_mul_f32_e32 v222, 0x3d922279, v218
	v_mul_f32_e32 v221, v215, v221
	v_fmaak_f32 v222, v218, v222, 0x3fcc422a
	v_mul_f32_e32 v221, 0xbfb8aa3b, v221
	v_mul_f32_e32 v222, v218, v222
	v_exp_f32_e32 v221, v221
	v_mul_f32_e32 v222, 0xbfb8aa3b, v222
	v_exp_f32_e32 v222, v222
	v_add_f32_e32 v220, 1.0, v220
	v_rcp_f32_e32 v240, v220
	v_add_f32_e32 v220, 1.0, v221
	v_rcp_f32_e32 v241, v220
	v_add_f32_e32 v220, 1.0, v222
	v_mul_f32_e32 v222, 0x3d922279, v238
	v_fmaak_f32 v222, v238, v222, 0x3fcc422a
	v_mul_f32_e32 v222, v238, v222
	v_mul_f32_e32 v222, 0xbfb8aa3b, v222
	v_exp_f32_e32 v222, v222
	v_pk_mul_f32 v[236:237], v[26:27], v[184:185]
	v_mul_f32_e32 v221, 0x3d922279, v219
	v_mul_f32_e32 v243, 0x3d922279, v236
	v_add_f32_e32 v222, 1.0, v222
	v_rcp_f32_e32 v242, v222
	v_mul_f32_e32 v222, 0x3d922279, v239
	v_fmaak_f32 v243, v236, v243, 0x3fcc422a
	v_mul_f32_e32 v244, 0x3d922279, v237
	v_fmaak_f32 v221, v219, v221, 0x3fcc422a
	v_fmaak_f32 v222, v239, v222, 0x3fcc422a
	v_mul_f32_e32 v243, v236, v243
	v_fmaak_f32 v244, v237, v244, 0x3fcc422a
	v_mul_f32_e32 v221, v219, v221
	v_mul_f32_e32 v222, v239, v222
	v_mul_f32_e32 v243, 0xbfb8aa3b, v243
	v_mul_f32_e32 v244, v237, v244
	v_mul_f32_e32 v221, 0xbfb8aa3b, v221
	v_mul_f32_e32 v222, 0xbfb8aa3b, v222
	v_exp_f32_e32 v243, v243
	v_mul_f32_e32 v244, 0xbfb8aa3b, v244
	v_exp_f32_e32 v221, v221
	v_exp_f32_e32 v222, v222
	v_exp_f32_e32 v245, v244
	v_add_f32_e32 v243, 1.0, v243
	v_add_f32_e32 v221, 1.0, v221
	v_add_f32_e32 v222, 1.0, v222
	v_rcp_f32_e32 v244, v243
	v_add_f32_e32 v243, 1.0, v245
	v_rcp_f32_e32 v220, v220
	v_rcp_f32_e32 v221, v221
	v_rcp_f32_e32 v245, v243
	v_rcp_f32_e32 v243, v222
	v_pk_mul_f32 v[240:241], v[214:215], v[240:241]
	v_pk_mul_f32 v[220:221], v[218:219], v[220:221]
	v_pk_mul_f32 v[214:215], v[236:237], v[244:245]
	v_pk_mul_f32 v[218:219], v[238:239], v[242:243]
	v_pk_fma_f32 v[238:239], v[240:241], v[240:241], v[234:235]
	v_cvt_pk_bf16_f32 v234, v240, v241
	v_add_co_u32_e32 v240, vcc, s71, v138
	v_pk_mul_f32 v[190:191], v[12:13], v[190:191]
	v_cvt_pk_bf16_f32 v235, v220, v221
	v_cvt_pk_bf16_f32 v236, v218, v219
	v_cvt_pk_bf16_f32 v237, v214, v215
	v_addc_co_u32_e32 v241, vcc, 0, v139, vcc
	v_mul_f32_e32 v222, 0x3d922279, v190
	global_store_dwordx4 v[240:241], v[234:237], off
	v_fmaak_f32 v222, v190, v222, 0x3fcc422a
	v_mul_f32_e32 v222, v190, v222
	v_mul_f32_e32 v234, 0x3d922279, v191
	v_fmaak_f32 v234, v191, v234, 0x3fcc422a
	v_mul_f32_e32 v222, 0xbfb8aa3b, v222
	v_mul_f32_e32 v234, v191, v234
	v_exp_f32_e32 v222, v222
	v_mul_f32_e32 v234, 0xbfb8aa3b, v234
	v_exp_f32_e32 v235, v234
	v_pk_mul_f32 v[186:187], v[14:15], v[186:187]
	v_add_f32_e32 v222, 1.0, v222
	v_rcp_f32_e32 v234, v222
	v_add_f32_e32 v222, 1.0, v235
	v_mul_f32_e32 v235, 0x3d922279, v186
	v_fmaak_f32 v235, v186, v235, 0x3fcc422a
	v_mul_f32_e32 v235, v186, v235
	v_mul_f32_e32 v235, 0xbfb8aa3b, v235
	v_exp_f32_e32 v236, v235
	v_mul_f32_e32 v235, 0x3d922279, v187
	v_fmaak_f32 v235, v187, v235, 0x3fcc422a
	v_mul_f32_e32 v235, v187, v235
	v_mul_f32_e32 v235, 0xbfb8aa3b, v235
	v_exp_f32_e32 v237, v235
	v_rcp_f32_e32 v235, v222
	v_pk_mul_f32 v[240:241], v[8:9], v[182:183]
	v_pk_mul_f32 v[184:185], v[10:11], v[184:185]
	v_mul_f32_e32 v182, 0x3d922279, v240
	v_pk_mul_f32 v[234:235], v[190:191], v[234:235]
	v_fmaak_f32 v182, v240, v182, 0x3fcc422a
	v_mul_f32_e32 v190, 0x3d922279, v184
	v_mul_f32_e32 v182, v240, v182
	v_fmaak_f32 v190, v184, v190, 0x3fcc422a
	v_add_f32_e32 v222, 1.0, v236
	v_mul_f32_e32 v182, 0xbfb8aa3b, v182
	v_mul_f32_e32 v190, v184, v190
	v_rcp_f32_e32 v236, v222
	v_add_f32_e32 v222, 1.0, v237
	v_exp_f32_e32 v182, v182
	v_mul_f32_e32 v190, 0xbfb8aa3b, v190
	v_rcp_f32_e32 v237, v222
	v_exp_f32_e32 v190, v190
	v_mul_f32_e32 v183, 0x3d922279, v241
	v_fmaak_f32 v183, v241, v183, 0x3fcc422a
	v_add_f32_e32 v182, 1.0, v182
	v_pk_mul_f32 v[186:187], v[186:187], v[236:237]
	v_mul_f32_e32 v183, v241, v183
	v_rcp_f32_e32 v236, v182
	v_add_f32_e32 v182, 1.0, v190
	v_pk_fma_f32 v[190:191], v[234:235], v[234:235], v[238:239]
	v_mul_f32_e32 v183, 0xbfb8aa3b, v183
	ds_bpermute_b32 v238, v226, v190
	v_exp_f32_e32 v183, v183
	v_rcp_f32_e32 v182, v182
	v_add_f32_e32 v222, 1.0, v183
	v_mul_f32_e32 v183, 0x3d922279, v185
	s_waitcnt lgkmcnt(0)
; #define PK8(v0, v1) ({ const u32x2 h0_ = pk4(v0), h1_ = pk4(v1); (u32x4){h0_.x, h0_.y, h1_.x, h1_.y}; })
;     DI void operator()(const Acc& acc, const Unit& u, int wr, int wc, int fr, int fq) const {
;     ...
;                         sq0 += v0 * v0; sq1 += v1 * v1; *(u32x4*)(WSB(OFF_VT) + (size_t)r * 8192 + cc) = PK8(v0, v1); }
; #pragma unroll
;                     for (int j = 0; j < 8; ++j) { float t = j < 4 ? sq0[j & 3] : sq1[j & 3];
;                         t += __shfl_xor(t, 1); t += __shfl_xor(t, 2); t += __shfl_xor(t, 4); t += __shfl_xor(t, 8);
;                         if (fr == 0) unsafeAtomicAdd(ssqv + cc + j, t); }
	v_add_f32_e32 v190, v190, v238
	v_fmaak_f32 v183, v185, v183, 0x3fcc422a
	v_rcp_f32_e32 v237, v222
	ds_bpermute_b32 v222, v227, v190
	v_mul_f32_e32 v183, v185, v183
	v_mul_f32_e32 v183, 0xbfb8aa3b, v183
	v_exp_f32_e32 v183, v183
	s_waitcnt lgkmcnt(0)
	v_add_f32_e32 v190, v190, v222
	ds_bpermute_b32 v222, v228, v190
	v_add_f32_e32 v183, 1.0, v183
	v_rcp_f32_e32 v183, v183
	s_waitcnt lgkmcnt(0)
	v_add_f32_e32 v190, v190, v222
	v_pk_mul_f32 v[182:183], v[184:185], v[182:183]
	v_pk_mul_f32 v[184:185], v[240:241], v[236:237]
	v_cvt_pk_bf16_f32 v236, v234, v235
	ds_bpermute_b32 v234, v229, v190
	v_add_co_u32_e32 v240, vcc, 0x2c0000, v138
	v_cvt_pk_bf16_f32 v237, v186, v187
	v_cvt_pk_bf16_f32 v238, v184, v185
	v_cvt_pk_bf16_f32 v239, v182, v183
	v_addc_co_u32_e32 v241, vcc, 0, v139, vcc
	global_store_dwordx4 v[240:241], v[236:239], off
	s_and_saveexec_b64 s[4:5], s[2:3]
	s_cbranch_execz .LBB0_331
	s_waitcnt lgkmcnt(0)
	v_add_f32_e32 v190, v190, v234
	global_atomic_add_f32 v[136:137], v190, off

; #define PG8_STAGE(bufoff, gbase, voff) do { _Pragma("unroll") for (int _i = 0; _i < 2; ++_i) \
;         __builtin_amdgcn_global_load_lds((const unsigned*)((const char*)(gbase) + (voff)[_i]), (LAS unsigned*)(lds + (bufoff) + ldsw + _i * 8192), 16, 0, 0); } while (0)
; #define PG8_LDA(dst, b, h) do { _Pragma("unroll") for (int m = 0; m < 4; ++m) _Pragma("unroll") for (int k = 0; k < 2; ++k) dst[m][k] = *(const LAS bf16x8*)(lds + PG8_SA(b, h) + aoff + m * 2048 + k * 1024); } while (0)
; #define PG8_LDB(dst, b, h) do { _Pragma("unroll") for (int n = 0; n < 2; ++n) _Pragma("unroll") for (int k = 0; k < 2; ++k) dst[n][k] = *(const LAS bf16x8*)(lds + PG8_SB(b, h) + boff + n * 2048 + k * 1024); } while (0)
; #define PG8_SCHED __builtin_amdgcn_sched_barrier(0)
; template <class Epi>
; DI void gemm_phase(LAS unsigned char* lds, int wid, int K, int lda, int ldb, bool bperm, const Sched3& S, const Epi& E) {
;     ...
;             const char* a1 = cA + (size_t)(t + 1) * kstep;
;             const char* a2 = last ? nA : cA + (size_t)(t + 2) * kstep; const char* b2 = last ? nB : cB + (size_t)(t + 2) * kstep;
;             const char* a3 = a2 + kstep; const char* b3 = b2 + kstep; const size_t h2 = last ? nhA : hA;
;             PG8_LDB(B0, 0, 0); PG8_SCHED; PG8_LDA(At, 0, 0); PG8_STAGE(PG8_SA(1, 1), a1 + hA, voffA);
.LBB0_620:
	s_add_u32 s38, s38, 0x80080
	s_addc_u32 s39, s39, 0
	s_add_u32 s21, s40, 0x100
	s_nop 0
	s_addc_u32 s23, s41, 0
	s_mov_b32 s29, -2
	s_waitcnt lgkmcnt(0)
	ds_read_b128 v[128:131], v203
	ds_read_b128 v[132:135], v203 offset:1024
	ds_read_b128 v[136:139], v203 offset:2048
	ds_read_b128 v[140:143], v203 offset:3072
	s_add_u32 s40, s38, 0xfff80080
	s_addc_u32 s41, s39, -1
	s_cmp_eq_u32 s29, 28
	s_cselect_b32 s43, s31, s41
	s_cselect_b32 s42, s30, s40
	s_cselect_b32 s41, s37, s23
	s_cselect_b32 s40, s36, s21

; #define PG8_STAGE(bufoff, gbase, voff) do { _Pragma("unroll") for (int _i = 0; _i < 2; ++_i) \
;         __builtin_amdgcn_global_load_lds((const unsigned*)((const char*)(gbase) + (voff)[_i]), (LAS unsigned*)(lds + (bufoff) + ldsw + _i * 8192), 16, 0, 0); } while (0)
; #define PG8_LDA(dst, b, h) do { _Pragma("unroll") for (int m = 0; m < 4; ++m) _Pragma("unroll") for (int k = 0; k < 2; ++k) dst[m][k] = *(const LAS bf16x8*)(lds + PG8_SA(b, h) + aoff + m * 2048 + k * 1024); } while (0)
; #define PG8_LDB(dst, b, h) do { _Pragma("unroll") for (int n = 0; n < 2; ++n) _Pragma("unroll") for (int k = 0; k < 2; ++k) dst[n][k] = *(const LAS bf16x8*)(lds + PG8_SB(b, h) + boff + n * 2048 + k * 1024); } while (0)
; #define PG8_SCHED __builtin_amdgcn_sched_barrier(0)
; template <class Epi>
; DI void gemm_phase(LAS unsigned char* lds, int wid, int K, int lda, int ldb, bool bperm, const Sched3& S, const Epi& E) {
;     ...
;             PG8_LDB(B0, 0, 0); PG8_SCHED; PG8_LDA(At, 0, 0); PG8_STAGE(PG8_SA(1, 1), a1 + hA, voffA);
	s_add_i32 m0, s50, 0xc000
	ds_read_b128 v[144:147], v204
	ds_read_b128 v[148:151], v204 offset:1024
	ds_read_b128 v[152:155], v204 offset:2048
	ds_read_b128 v[156:159], v204 offset:3072
	ds_read_b128 v[160:163], v204 offset:4096
	ds_read_b128 v[164:167], v204 offset:5120
	ds_read_b128 v[168:171], v204 offset:6144
	ds_read_b128 v[172:175], v204 offset:7168
	global_load_lds_dwordx4 v180, s[38:39]

; #define PG8_STAGE(bufoff, gbase, voff) do { _Pragma("unroll") for (int _i = 0; _i < 2; ++_i) \
;         __builtin_amdgcn_global_load_lds((const unsigned*)((const char*)(gbase) + (voff)[_i]), (LAS unsigned*)(lds + (bufoff) + ldsw + _i * 8192), 16, 0, 0); } while (0)
; #define PG8_LDA(dst, b, h) do { _Pragma("unroll") for (int m = 0; m < 4; ++m) _Pragma("unroll") for (int k = 0; k < 2; ++k) dst[m][k] = *(const LAS bf16x8*)(lds + PG8_SA(b, h) + aoff + m * 2048 + k * 1024); } while (0)
; #define PG8_LDB(dst, b, h) do { _Pragma("unroll") for (int n = 0; n < 2; ++n) _Pragma("unroll") for (int k = 0; k < 2; ++k) dst[n][k] = *(const LAS bf16x8*)(lds + PG8_SB(b, h) + boff + n * 2048 + k * 1024); } while (0)
; #define PG8_MMA(ai, bj, At, Bt) do { __builtin_amdgcn_s_setprio(1); _Pragma("unroll") for (int m = 0; m < 4; ++m) _Pragma("unroll") for (int n = 0; n < 2; ++n) _Pragma("unroll") for (int k = 0; k < 2; ++k) \
;         acc[ai][bj][m][n] = __builtin_amdgcn_mfma_f32_16x16x32_bf16(Bt[n][k], At[m][k], acc[ai][bj][m][n], 0, 0, 0); __builtin_amdgcn_s_setprio(0); } while (0)
; #define PG8_WAIT_L(n) asm volatile("s_waitcnt lgkmcnt(" #n ")" ::: "memory")
; #define PG8_BAR __builtin_amdgcn_s_barrier()
; #define PG8_SCHED __builtin_amdgcn_sched_barrier(0)
; template <class Epi>
; DI void gemm_phase(LAS unsigned char* lds, int wid, int K, int lda, int ldb, bool bperm, const Sched3& S, const Epi& E) {
;     ...
;             PG8_LDB(B0, 0, 0); PG8_SCHED; PG8_LDA(At, 0, 0); PG8_STAGE(PG8_SA(1, 1), a1 + hA, voffA);
;             PG8_WAIT_L(8); PG8_BAR; PG8_WAIT_L(0); PG8_MMA(0, 0, At, B0); PG8_BAR; PG8_SCHED;
	s_add_i32 m0, s50, 0xe000
	s_nop 0
	global_load_lds_dwordx4 v182, s[38:39]
	s_waitcnt lgkmcnt(8)
	s_barrier
	s_waitcnt lgkmcnt(0)
	s_setprio 1
	s_waitcnt lgkmcnt(0)
	v_mfma_f32_16x16x32_bf16 v[124:127], v[128:131], v[144:147], 0
	v_mfma_f32_16x16x32_bf16 v[120:123], v[136:139], v[144:147], 0
	v_mfma_f32_16x16x32_bf16 v[108:111], v[128:131], v[152:155], 0
	v_mfma_f32_16x16x32_bf16 v[104:107], v[136:139], v[152:155], 0
	v_mfma_f32_16x16x32_bf16 v[92:95], v[128:131], v[160:163], 0
	v_mfma_f32_16x16x32_bf16 v[88:91], v[136:139], v[160:163], 0
	v_mfma_f32_16x16x32_bf16 v[76:79], v[128:131], v[168:171], 0
	v_mfma_f32_16x16x32_bf16 v[72:75], v[136:139], v[168:171], 0
	v_mfma_f32_16x16x32_bf16 v[124:127], v[132:135], v[148:151], v[124:127]
	v_mfma_f32_16x16x32_bf16 v[120:123], v[140:143], v[148:151], v[120:123]
	v_mfma_f32_16x16x32_bf16 v[108:111], v[132:135], v[156:159], v[108:111]
	v_mfma_f32_16x16x32_bf16 v[104:107], v[140:143], v[156:159], v[104:107]
	v_mfma_f32_16x16x32_bf16 v[92:95], v[132:135], v[164:167], v[92:95]
	v_mfma_f32_16x16x32_bf16 v[88:91], v[140:143], v[164:167], v[88:91]
	v_mfma_f32_16x16x32_bf16 v[76:79], v[132:135], v[172:175], v[76:79]
	v_mfma_f32_16x16x32_bf16 v[72:75], v[140:143], v[172:175], v[72:75]
	s_setprio 0
	s_barrier
	s_add_i32 s63, s59, s49

; #define PG8_STAGE(bufoff, gbase, voff) do { _Pragma("unroll") for (int _i = 0; _i < 2; ++_i) \
;         __builtin_amdgcn_global_load_lds((const unsigned*)((const char*)(gbase) + (voff)[_i]), (LAS unsigned*)(lds + (bufoff) + ldsw + _i * 8192), 16, 0, 0); } while (0)
; #define PG8_LDB(dst, b, h) do { _Pragma("unroll") for (int n = 0; n < 2; ++n) _Pragma("unroll") for (int k = 0; k < 2; ++k) dst[n][k] = *(const LAS bf16x8*)(lds + PG8_SB(b, h) + boff + n * 2048 + k * 1024); } while (0)
; template <class Epi>
; DI void gemm_phase(LAS unsigned char* lds, int wid, int K, int lda, int ldb, bool bperm, const Sched3& S, const Epi& E) {
;     ...
;             PG8_LDB(B1, 0, 1); PG8_STAGE(PG8_SB(0, 0), b2, voffB);
	s_mov_b32 m0, s63
	ds_read_b128 v[186:189], v205
	ds_read_b128 v[190:193], v205 offset:1024
	ds_read_b128 v[194:197], v205 offset:2048
	ds_read_b128 v[206:209], v205 offset:3072
	global_load_lds_dwordx4 v176, s[40:41]

; #define PG8_STAGE(bufoff, gbase, voff) do { _Pragma("unroll") for (int _i = 0; _i < 2; ++_i) \
;         __builtin_amdgcn_global_load_lds((const unsigned*)((const char*)(gbase) + (voff)[_i]), (LAS unsigned*)(lds + (bufoff) + ldsw + _i * 8192), 16, 0, 0); } while (0)
; #define PG8_LDA(dst, b, h) do { _Pragma("unroll") for (int m = 0; m < 4; ++m) _Pragma("unroll") for (int k = 0; k < 2; ++k) dst[m][k] = *(const LAS bf16x8*)(lds + PG8_SA(b, h) + aoff + m * 2048 + k * 1024); } while (0)
; #define PG8_LDB(dst, b, h) do { _Pragma("unroll") for (int n = 0; n < 2; ++n) _Pragma("unroll") for (int k = 0; k < 2; ++k) dst[n][k] = *(const LAS bf16x8*)(lds + PG8_SB(b, h) + boff + n * 2048 + k * 1024); } while (0)
; #define PG8_MMA(ai, bj, At, Bt) do { __builtin_amdgcn_s_setprio(1); _Pragma("unroll") for (int m = 0; m < 4; ++m) _Pragma("unroll") for (int n = 0; n < 2; ++n) _Pragma("unroll") for (int k = 0; k < 2; ++k) \
;         acc[ai][bj][m][n] = __builtin_amdgcn_mfma_f32_16x16x32_bf16(Bt[n][k], At[m][k], acc[ai][bj][m][n], 0, 0, 0); __builtin_amdgcn_s_setprio(0); } while (0)
; #define PG8_WAIT_L(n) asm volatile("s_waitcnt lgkmcnt(" #n ")" ::: "memory")
; #define PG8_BAR __builtin_amdgcn_s_barrier()
; #define PG8_SCHED __builtin_amdgcn_sched_barrier(0)
; template <class Epi>
; DI void gemm_phase(LAS unsigned char* lds, int wid, int K, int lda, int ldb, bool bperm, const Sched3& S, const Epi& E) {
;     ...
;             PG8_LDB(B1, 0, 1); PG8_STAGE(PG8_SB(0, 0), b2, voffB);
;             PG8_BAR; PG8_WAIT_L(0); PG8_MMA(0, 1, At, B1); PG8_BAR;
;             PG8_LDA(At, 0, 1); PG8_STAGE(PG8_SA(0, 0), a2, voffA);
;             PG8_BAR; PG8_WAIT_L(0); if (full) PG8_MMA(1, 0, At, B0); PG8_BAR; PG8_SCHED;
;             PG8_STAGE(PG8_SB(0, 1), b2 + hstepB, voffB);
	s_add_i32 m0, s63, 0x2000
	s_nop 0
	global_load_lds_dwordx4 v178, s[40:41]
	s_barrier
	s_waitcnt lgkmcnt(0)
	s_setprio 1
	s_waitcnt lgkmcnt(0)
	v_mfma_f32_16x16x32_bf16 v[116:119], v[186:189], v[144:147], 0
	v_mfma_f32_16x16x32_bf16 v[112:115], v[194:197], v[144:147], 0
	v_mfma_f32_16x16x32_bf16 v[100:103], v[186:189], v[152:155], 0
	v_mfma_f32_16x16x32_bf16 v[96:99], v[194:197], v[152:155], 0
	v_mfma_f32_16x16x32_bf16 v[84:87], v[186:189], v[160:163], 0
	v_mfma_f32_16x16x32_bf16 v[80:83], v[194:197], v[160:163], 0
	v_mfma_f32_16x16x32_bf16 v[68:71], v[186:189], v[168:171], 0
	v_mfma_f32_16x16x32_bf16 v[64:67], v[194:197], v[168:171], 0
	v_mfma_f32_16x16x32_bf16 v[116:119], v[190:193], v[148:151], v[116:119]
	v_mfma_f32_16x16x32_bf16 v[112:115], v[206:209], v[148:151], v[112:115]
	v_mfma_f32_16x16x32_bf16 v[100:103], v[190:193], v[156:159], v[100:103]
	v_mfma_f32_16x16x32_bf16 v[96:99], v[206:209], v[156:159], v[96:99]
	v_mfma_f32_16x16x32_bf16 v[84:87], v[190:193], v[164:167], v[84:87]
	v_mfma_f32_16x16x32_bf16 v[80:83], v[206:209], v[164:167], v[80:83]
	v_mfma_f32_16x16x32_bf16 v[68:71], v[190:193], v[172:175], v[68:71]
	v_mfma_f32_16x16x32_bf16 v[64:67], v[206:209], v[172:175], v[64:67]
	s_setprio 0
	s_mov_b32 m0, s50
	s_mov_b64 s[100:101], s[42:43]
	s_barrier
	ds_read_b128 v[144:147], v204 offset:16384
	ds_read_b128 v[148:151], v204 offset:17408
	ds_read_b128 v[152:155], v204 offset:18432
	ds_read_b128 v[156:159], v204 offset:19456
	ds_read_b128 v[160:163], v204 offset:20480
	ds_read_b128 v[164:167], v204 offset:21504
	ds_read_b128 v[168:171], v204 offset:22528
	ds_read_b128 v[172:175], v204 offset:23552
	global_load_lds_dwordx4 v176, s[42:43]
	s_mov_b64 s[100:101], s[42:43]
	s_mov_b32 m0, s51
	s_nop 0
	global_load_lds_dwordx4 v178, s[42:43]
	s_barrier
	s_waitcnt lgkmcnt(0)
	s_setprio 1
	s_waitcnt lgkmcnt(0)
	v_mfma_f32_16x16x32_bf16 v[60:63], v[128:131], v[144:147], 0
	v_mfma_f32_16x16x32_bf16 v[56:59], v[136:139], v[144:147], 0
	v_mfma_f32_16x16x32_bf16 v[44:47], v[128:131], v[152:155], 0
	v_mfma_f32_16x16x32_bf16 v[40:43], v[136:139], v[152:155], 0
	v_mfma_f32_16x16x32_bf16 v[28:31], v[128:131], v[160:163], 0
	v_mfma_f32_16x16x32_bf16 v[24:27], v[136:139], v[160:163], 0
	v_mfma_f32_16x16x32_bf16 v[12:15], v[128:131], v[168:171], 0
	v_mfma_f32_16x16x32_bf16 v[8:11], v[136:139], v[168:171], 0
	v_mfma_f32_16x16x32_bf16 v[60:63], v[132:135], v[148:151], v[60:63]
	v_mfma_f32_16x16x32_bf16 v[56:59], v[140:143], v[148:151], v[56:59]
	v_mfma_f32_16x16x32_bf16 v[44:47], v[132:135], v[156:159], v[44:47]
	v_mfma_f32_16x16x32_bf16 v[40:43], v[140:143], v[156:159], v[40:43]
	v_mfma_f32_16x16x32_bf16 v[28:31], v[132:135], v[164:167], v[28:31]
	v_mfma_f32_16x16x32_bf16 v[24:27], v[140:143], v[164:167], v[24:27]
	v_mfma_f32_16x16x32_bf16 v[12:15], v[132:135], v[172:175], v[12:15]
	v_mfma_f32_16x16x32_bf16 v[8:11], v[140:143], v[172:175], v[8:11]
	s_setprio 0
	s_barrier
	s_add_u32 s64, s40, 0x80000
	s_addc_u32 s65, s41, 0
	s_add_i32 s63, s60, s49

; #define PG8_STAGE(bufoff, gbase, voff) do { _Pragma("unroll") for (int _i = 0; _i < 2; ++_i) \
;         __builtin_amdgcn_global_load_lds((const unsigned*)((const char*)(gbase) + (voff)[_i]), (LAS unsigned*)(lds + (bufoff) + ldsw + _i * 8192), 16, 0, 0); } while (0)
; template <class Epi>
; DI void gemm_phase(LAS unsigned char* lds, int wid, int K, int lda, int ldb, bool bperm, const Sched3& S, const Epi& E) {
;     ...
;             PG8_STAGE(PG8_SB(0, 1), b2 + hstepB, voffB);
	s_mov_b32 m0, s63
	s_nop 0
	global_load_lds_dwordx4 v176, s[64:65]

; #define PG8_STAGE(bufoff, gbase, voff) do { _Pragma("unroll") for (int _i = 0; _i < 2; ++_i) \
;         __builtin_amdgcn_global_load_lds((const unsigned*)((const char*)(gbase) + (voff)[_i]), (LAS unsigned*)(lds + (bufoff) + ldsw + _i * 8192), 16, 0, 0); } while (0)
; #define PG8_LDA(dst, b, h) do { _Pragma("unroll") for (int m = 0; m < 4; ++m) _Pragma("unroll") for (int k = 0; k < 2; ++k) dst[m][k] = *(const LAS bf16x8*)(lds + PG8_SA(b, h) + aoff + m * 2048 + k * 1024); } while (0)
; #define PG8_LDB(dst, b, h) do { _Pragma("unroll") for (int n = 0; n < 2; ++n) _Pragma("unroll") for (int k = 0; k < 2; ++k) dst[n][k] = *(const LAS bf16x8*)(lds + PG8_SB(b, h) + boff + n * 2048 + k * 1024); } while (0)
; #define PG8_MMA(ai, bj, At, Bt) do { __builtin_amdgcn_s_setprio(1); _Pragma("unroll") for (int m = 0; m < 4; ++m) _Pragma("unroll") for (int n = 0; n < 2; ++n) _Pragma("unroll") for (int k = 0; k < 2; ++k) \
;         acc[ai][bj][m][n] = __builtin_amdgcn_mfma_f32_16x16x32_bf16(Bt[n][k], At[m][k], acc[ai][bj][m][n], 0, 0, 0); __builtin_amdgcn_s_setprio(0); } while (0)
; #define PG8_WAIT_V(n) asm volatile("s_waitcnt vmcnt(" #n ")" ::: "memory")
; #define PG8_BAR __builtin_amdgcn_s_barrier()
; #define PG8_SCHED __builtin_amdgcn_sched_barrier(0)
; template <class Epi>
; DI void gemm_phase(LAS unsigned char* lds, int wid, int K, int lda, int ldb, bool bperm, const Sched3& S, const Epi& E) {
;     ...
;             PG8_STAGE(PG8_SB(0, 1), b2 + hstepB, voffB);
;             PG8_WAIT_V(6); PG8_BAR; if (full) PG8_MMA(1, 1, At, B1); PG8_BAR;
;             PG8_LDB(B0, 1, 0); PG8_SCHED; PG8_LDA(At, 1, 0); PG8_STAGE(PG8_SA(0, 1), a2 + h2, voffA);
	s_add_i32 m0, s63, 0x2000
	s_nop 0
	global_load_lds_dwordx4 v178, s[64:65]
	s_waitcnt vmcnt(6)
	s_barrier
	s_setprio 1
	v_mfma_f32_16x16x32_bf16 v[52:55], v[186:189], v[144:147], 0
	v_mfma_f32_16x16x32_bf16 v[48:51], v[194:197], v[144:147], 0
	v_mfma_f32_16x16x32_bf16 v[36:39], v[186:189], v[152:155], 0
	v_mfma_f32_16x16x32_bf16 v[32:35], v[194:197], v[152:155], 0
	v_mfma_f32_16x16x32_bf16 v[20:23], v[186:189], v[160:163], 0
	v_mfma_f32_16x16x32_bf16 v[16:19], v[194:197], v[160:163], 0
	v_mfma_f32_16x16x32_bf16 v[4:7], v[186:189], v[168:171], 0
	v_mfma_f32_16x16x32_bf16 v[0:3], v[194:197], v[168:171], 0
	v_mfma_f32_16x16x32_bf16 v[52:55], v[190:193], v[148:151], v[52:55]
	v_mfma_f32_16x16x32_bf16 v[48:51], v[206:209], v[148:151], v[48:51]
	v_mfma_f32_16x16x32_bf16 v[36:39], v[190:193], v[156:159], v[36:39]
	v_mfma_f32_16x16x32_bf16 v[32:35], v[206:209], v[156:159], v[32:35]
	v_mfma_f32_16x16x32_bf16 v[20:23], v[190:193], v[164:167], v[20:23]
	v_mfma_f32_16x16x32_bf16 v[16:19], v[206:209], v[164:167], v[16:19]
	v_mfma_f32_16x16x32_bf16 v[4:7], v[190:193], v[172:175], v[4:7]
	v_mfma_f32_16x16x32_bf16 v[0:3], v[206:209], v[172:175], v[0:3]
	s_setprio 0
	s_add_i32 s63, 0, 0x18000
	v_add_u32_e32 v140, s63, v199
	s_barrier
	ds_read_b128 v[128:131], v140
	ds_read_b128 v[132:135], v140 offset:1024
	ds_read_b128 v[136:139], v140 offset:2048
	ds_read_b128 v[140:143], v140 offset:3072
	s_add_u32 s42, s42, 0x80000
	s_addc_u32 s43, s43, 0
	s_mov_b32 m0, s52

; #define PG8_STAGE(bufoff, gbase, voff) do { _Pragma("unroll") for (int _i = 0; _i < 2; ++_i) \
;         __builtin_amdgcn_global_load_lds((const unsigned*)((const char*)(gbase) + (voff)[_i]), (LAS unsigned*)(lds + (bufoff) + ldsw + _i * 8192), 16, 0, 0); } while (0)
; #define PG8_LDA(dst, b, h) do { _Pragma("unroll") for (int m = 0; m < 4; ++m) _Pragma("unroll") for (int k = 0; k < 2; ++k) dst[m][k] = *(const LAS bf16x8*)(lds + PG8_SA(b, h) + aoff + m * 2048 + k * 1024); } while (0)
; #define PG8_LDB(dst, b, h) do { _Pragma("unroll") for (int n = 0; n < 2; ++n) _Pragma("unroll") for (int k = 0; k < 2; ++k) dst[n][k] = *(const LAS bf16x8*)(lds + PG8_SB(b, h) + boff + n * 2048 + k * 1024); } while (0)
; #define PG8_SCHED __builtin_amdgcn_sched_barrier(0)
; template <class Epi>
; DI void gemm_phase(LAS unsigned char* lds, int wid, int K, int lda, int ldb, bool bperm, const Sched3& S, const Epi& E) {
;     ...
;             PG8_LDB(B0, 1, 0); PG8_SCHED; PG8_LDA(At, 1, 0); PG8_STAGE(PG8_SA(0, 1), a2 + h2, voffA);
	ds_read_b128 v[144:147], v204 offset:32768
	ds_read_b128 v[148:151], v204 offset:33792
	ds_read_b128 v[152:155], v204 offset:34816
	ds_read_b128 v[156:159], v204 offset:35840
	ds_read_b128 v[160:163], v204 offset:36864
	ds_read_b128 v[164:167], v204 offset:37888
	ds_read_b128 v[168:171], v204 offset:38912
	ds_read_b128 v[172:175], v204 offset:39936
	global_load_lds_dwordx4 v176, s[42:43]

; #define PG8_STAGE(bufoff, gbase, voff) do { _Pragma("unroll") for (int _i = 0; _i < 2; ++_i) \
;         __builtin_amdgcn_global_load_lds((const unsigned*)((const char*)(gbase) + (voff)[_i]), (LAS unsigned*)(lds + (bufoff) + ldsw + _i * 8192), 16, 0, 0); } while (0)
; #define PG8_LDA(dst, b, h) do { _Pragma("unroll") for (int m = 0; m < 4; ++m) _Pragma("unroll") for (int k = 0; k < 2; ++k) dst[m][k] = *(const LAS bf16x8*)(lds + PG8_SA(b, h) + aoff + m * 2048 + k * 1024); } while (0)
; #define PG8_LDB(dst, b, h) do { _Pragma("unroll") for (int n = 0; n < 2; ++n) _Pragma("unroll") for (int k = 0; k < 2; ++k) dst[n][k] = *(const LAS bf16x8*)(lds + PG8_SB(b, h) + boff + n * 2048 + k * 1024); } while (0)
; #define PG8_MMA(ai, bj, At, Bt) do { __builtin_amdgcn_s_setprio(1); _Pragma("unroll") for (int m = 0; m < 4; ++m) _Pragma("unroll") for (int n = 0; n < 2; ++n) _Pragma("unroll") for (int k = 0; k < 2; ++k) \
;         acc[ai][bj][m][n] = __builtin_amdgcn_mfma_f32_16x16x32_bf16(Bt[n][k], At[m][k], acc[ai][bj][m][n], 0, 0, 0); __builtin_amdgcn_s_setprio(0); } while (0)
; #define PG8_WAIT_L(n) asm volatile("s_waitcnt lgkmcnt(" #n ")" ::: "memory")
; #define PG8_BAR __builtin_amdgcn_s_barrier()
; #define PG8_SCHED __builtin_amdgcn_sched_barrier(0)
; template <class Epi>
; DI void gemm_phase(LAS unsigned char* lds, int wid, int K, int lda, int ldb, bool bperm, const Sched3& S, const Epi& E) {
;     ...
;             PG8_LDB(B0, 1, 0); PG8_SCHED; PG8_LDA(At, 1, 0); PG8_STAGE(PG8_SA(0, 1), a2 + h2, voffA);
;             PG8_WAIT_L(8); PG8_BAR; PG8_WAIT_L(0); PG8_MMA(0, 0, At, B0); PG8_BAR; PG8_SCHED;
;             PG8_LDB(B1, 1, 1); PG8_STAGE(PG8_SB(1, 0), b3, voffB);
	s_mov_b32 m0, s53
	s_nop 0
	global_load_lds_dwordx4 v178, s[42:43]
	s_waitcnt lgkmcnt(8)
	s_barrier
	s_waitcnt lgkmcnt(0)
	s_setprio 1
	s_waitcnt lgkmcnt(0)
	v_mfma_f32_16x16x32_bf16 v[124:127], v[128:131], v[144:147], v[124:127]
	v_mfma_f32_16x16x32_bf16 v[120:123], v[136:139], v[144:147], v[120:123]
	v_mfma_f32_16x16x32_bf16 v[108:111], v[128:131], v[152:155], v[108:111]
	v_mfma_f32_16x16x32_bf16 v[104:107], v[136:139], v[152:155], v[104:107]
	v_mfma_f32_16x16x32_bf16 v[92:95], v[128:131], v[160:163], v[92:95]
	v_mfma_f32_16x16x32_bf16 v[88:91], v[136:139], v[160:163], v[88:91]
	v_mfma_f32_16x16x32_bf16 v[76:79], v[128:131], v[168:171], v[76:79]
	v_mfma_f32_16x16x32_bf16 v[72:75], v[136:139], v[168:171], v[72:75]
	v_mfma_f32_16x16x32_bf16 v[124:127], v[132:135], v[148:151], v[124:127]
	v_mfma_f32_16x16x32_bf16 v[120:123], v[140:143], v[148:151], v[120:123]
	v_mfma_f32_16x16x32_bf16 v[108:111], v[132:135], v[156:159], v[108:111]
	v_mfma_f32_16x16x32_bf16 v[104:107], v[140:143], v[156:159], v[104:107]
	v_mfma_f32_16x16x32_bf16 v[92:95], v[132:135], v[164:167], v[92:95]
	v_mfma_f32_16x16x32_bf16 v[88:91], v[140:143], v[164:167], v[88:91]
	v_mfma_f32_16x16x32_bf16 v[76:79], v[132:135], v[172:175], v[76:79]
	v_mfma_f32_16x16x32_bf16 v[72:75], v[140:143], v[172:175], v[72:75]
	s_setprio 0
	s_barrier
	s_add_i32 s42, 0, 0x1c000
	s_add_i32 s43, s63, s49
	v_add_u32_e32 v206, s42, v199

; #define PG8_STAGE(bufoff, gbase, voff) do { _Pragma("unroll") for (int _i = 0; _i < 2; ++_i) \
;         __builtin_amdgcn_global_load_lds((const unsigned*)((const char*)(gbase) + (voff)[_i]), (LAS unsigned*)(lds + (bufoff) + ldsw + _i * 8192), 16, 0, 0); } while (0)
; #define PG8_LDB(dst, b, h) do { _Pragma("unroll") for (int n = 0; n < 2; ++n) _Pragma("unroll") for (int k = 0; k < 2; ++k) dst[n][k] = *(const LAS bf16x8*)(lds + PG8_SB(b, h) + boff + n * 2048 + k * 1024); } while (0)
; template <class Epi>
; DI void gemm_phase(LAS unsigned char* lds, int wid, int K, int lda, int ldb, bool bperm, const Sched3& S, const Epi& E) {
;     ...
;             PG8_LDB(B1, 1, 1); PG8_STAGE(PG8_SB(1, 0), b3, voffB);
	s_sub_i32 m0, s43, 0x80
	ds_read_b128 v[186:189], v206
	ds_read_b128 v[190:193], v206 offset:1024
	ds_read_b128 v[194:197], v206 offset:2048
	ds_read_b128 v[206:209], v206 offset:3072
	global_load_lds_dwordx4 v176, s[40:41] offset:128

; #define PG8_STAGE(bufoff, gbase, voff) do { _Pragma("unroll") for (int _i = 0; _i < 2; ++_i) \
;         __builtin_amdgcn_global_load_lds((const unsigned*)((const char*)(gbase) + (voff)[_i]), (LAS unsigned*)(lds + (bufoff) + ldsw + _i * 8192), 16, 0, 0); } while (0)
; #define PG8_LDB(dst, b, h) do { _Pragma("unroll") for (int n = 0; n < 2; ++n) _Pragma("unroll") for (int k = 0; k < 2; ++k) dst[n][k] = *(const LAS bf16x8*)(lds + PG8_SB(b, h) + boff + n * 2048 + k * 1024); } while (0)
; #define PG8_MMA(ai, bj, At, Bt) do { __builtin_amdgcn_s_setprio(1); _Pragma("unroll") for (int m = 0; m < 4; ++m) _Pragma("unroll") for (int n = 0; n < 2; ++n) _Pragma("unroll") for (int k = 0; k < 2; ++k) \
;         acc[ai][bj][m][n] = __builtin_amdgcn_mfma_f32_16x16x32_bf16(Bt[n][k], At[m][k], acc[ai][bj][m][n], 0, 0, 0); __builtin_amdgcn_s_setprio(0); } while (0)
; #define PG8_WAIT_L(n) asm volatile("s_waitcnt lgkmcnt(" #n ")" ::: "memory")
; #define PG8_BAR __builtin_amdgcn_s_barrier()
; template <class Epi>
; DI void gemm_phase(LAS unsigned char* lds, int wid, int K, int lda, int ldb, bool bperm, const Sched3& S, const Epi& E) {
;     ...
;             PG8_LDB(B1, 1, 1); PG8_STAGE(PG8_SB(1, 0), b3, voffB);
;             PG8_BAR; PG8_WAIT_L(0); PG8_MMA(0, 1, At, B1); PG8_BAR;
	s_add_i32 m0, s43, 0x1f80
	s_nop 0
	global_load_lds_dwordx4 v178, s[40:41] offset:128
	s_barrier
	s_waitcnt lgkmcnt(0)
	s_setprio 1
	s_waitcnt lgkmcnt(0)
	v_mfma_f32_16x16x32_bf16 v[116:119], v[186:189], v[144:147], v[116:119]
	v_mfma_f32_16x16x32_bf16 v[112:115], v[194:197], v[144:147], v[112:115]
	v_mfma_f32_16x16x32_bf16 v[100:103], v[186:189], v[152:155], v[100:103]
	v_mfma_f32_16x16x32_bf16 v[96:99], v[194:197], v[152:155], v[96:99]
	v_mfma_f32_16x16x32_bf16 v[84:87], v[186:189], v[160:163], v[84:87]
	v_mfma_f32_16x16x32_bf16 v[80:83], v[194:197], v[160:163], v[80:83]
	v_mfma_f32_16x16x32_bf16 v[68:71], v[186:189], v[168:171], v[68:71]
	v_mfma_f32_16x16x32_bf16 v[64:67], v[194:197], v[168:171], v[64:67]
	v_mfma_f32_16x16x32_bf16 v[116:119], v[190:193], v[148:151], v[116:119]
	v_mfma_f32_16x16x32_bf16 v[112:115], v[206:209], v[148:151], v[112:115]
	v_mfma_f32_16x16x32_bf16 v[100:103], v[190:193], v[156:159], v[100:103]
	v_mfma_f32_16x16x32_bf16 v[96:99], v[206:209], v[156:159], v[96:99]
	v_mfma_f32_16x16x32_bf16 v[84:87], v[190:193], v[164:167], v[84:87]
	v_mfma_f32_16x16x32_bf16 v[80:83], v[206:209], v[164:167], v[80:83]
	v_mfma_f32_16x16x32_bf16 v[68:71], v[190:193], v[172:175], v[68:71]
	v_mfma_f32_16x16x32_bf16 v[64:67], v[206:209], v[172:175], v[64:67]
	s_setprio 0
	s_sub_i32 m0, s55, 0x80

; #define PG8_STAGE(bufoff, gbase, voff) do { _Pragma("unroll") for (int _i = 0; _i < 2; ++_i) \
;         __builtin_amdgcn_global_load_lds((const unsigned*)((const char*)(gbase) + (voff)[_i]), (LAS unsigned*)(lds + (bufoff) + ldsw + _i * 8192), 16, 0, 0); } while (0)
; #define PG8_LDA(dst, b, h) do { _Pragma("unroll") for (int m = 0; m < 4; ++m) _Pragma("unroll") for (int k = 0; k < 2; ++k) dst[m][k] = *(const LAS bf16x8*)(lds + PG8_SA(b, h) + aoff + m * 2048 + k * 1024); } while (0)
; template <class Epi>
; DI void gemm_phase(LAS unsigned char* lds, int wid, int K, int lda, int ldb, bool bperm, const Sched3& S, const Epi& E) {
;     ...
;             PG8_LDA(At, 1, 1); PG8_STAGE(PG8_SA(1, 0), a3, voffA);
	s_barrier
	ds_read_b128 v[144:147], v204 offset:49152
	ds_read_b128 v[148:151], v204 offset:50176
	ds_read_b128 v[152:155], v204 offset:51200
	ds_read_b128 v[156:159], v204 offset:52224
	ds_read_b128 v[160:163], v204 offset:53248
	ds_read_b128 v[164:167], v204 offset:54272
	ds_read_b128 v[168:171], v204 offset:55296
	ds_read_b128 v[172:175], v204 offset:56320
	global_load_lds_dwordx4 v176, s[100:101] offset:128

; #define PG8_STAGE(bufoff, gbase, voff) do { _Pragma("unroll") for (int _i = 0; _i < 2; ++_i) \
;         __builtin_amdgcn_global_load_lds((const unsigned*)((const char*)(gbase) + (voff)[_i]), (LAS unsigned*)(lds + (bufoff) + ldsw + _i * 8192), 16, 0, 0); } while (0)
; #define PG8_LDA(dst, b, h) do { _Pragma("unroll") for (int m = 0; m < 4; ++m) _Pragma("unroll") for (int k = 0; k < 2; ++k) dst[m][k] = *(const LAS bf16x8*)(lds + PG8_SA(b, h) + aoff + m * 2048 + k * 1024); } while (0)
; #define PG8_MMA(ai, bj, At, Bt) do { __builtin_amdgcn_s_setprio(1); _Pragma("unroll") for (int m = 0; m < 4; ++m) _Pragma("unroll") for (int n = 0; n < 2; ++n) _Pragma("unroll") for (int k = 0; k < 2; ++k) \
;         acc[ai][bj][m][n] = __builtin_amdgcn_mfma_f32_16x16x32_bf16(Bt[n][k], At[m][k], acc[ai][bj][m][n], 0, 0, 0); __builtin_amdgcn_s_setprio(0); } while (0)
; #define PG8_WAIT_L(n) asm volatile("s_waitcnt lgkmcnt(" #n ")" ::: "memory")
; #define PG8_BAR __builtin_amdgcn_s_barrier()
; #define PG8_SCHED __builtin_amdgcn_sched_barrier(0)
; template <class Epi>
; DI void gemm_phase(LAS unsigned char* lds, int wid, int K, int lda, int ldb, bool bperm, const Sched3& S, const Epi& E) {
;     ...
;             PG8_LDA(At, 1, 1); PG8_STAGE(PG8_SA(1, 0), a3, voffA);
;             PG8_BAR; PG8_WAIT_L(0); if (full) PG8_MMA(1, 0, At, B0); PG8_BAR; PG8_SCHED;
	s_sub_i32 m0, s56, 0x80
	s_nop 0
	global_load_lds_dwordx4 v178, s[100:101] offset:128
	s_barrier
	s_waitcnt lgkmcnt(0)
	s_setprio 1
	s_waitcnt lgkmcnt(0)
	v_mfma_f32_16x16x32_bf16 v[60:63], v[128:131], v[144:147], v[60:63]
	v_mfma_f32_16x16x32_bf16 v[56:59], v[136:139], v[144:147], v[56:59]
	v_mfma_f32_16x16x32_bf16 v[44:47], v[128:131], v[152:155], v[44:47]
	v_mfma_f32_16x16x32_bf16 v[40:43], v[136:139], v[152:155], v[40:43]
	v_mfma_f32_16x16x32_bf16 v[28:31], v[128:131], v[160:163], v[28:31]
	v_mfma_f32_16x16x32_bf16 v[24:27], v[136:139], v[160:163], v[24:27]
	v_mfma_f32_16x16x32_bf16 v[12:15], v[128:131], v[168:171], v[12:15]
	v_mfma_f32_16x16x32_bf16 v[8:11], v[136:139], v[168:171], v[8:11]
	v_mfma_f32_16x16x32_bf16 v[60:63], v[132:135], v[148:151], v[60:63]
	v_mfma_f32_16x16x32_bf16 v[56:59], v[140:143], v[148:151], v[56:59]
	v_mfma_f32_16x16x32_bf16 v[44:47], v[132:135], v[156:159], v[44:47]
	v_mfma_f32_16x16x32_bf16 v[40:43], v[140:143], v[156:159], v[40:43]
	v_mfma_f32_16x16x32_bf16 v[28:31], v[132:135], v[164:167], v[28:31]
	v_mfma_f32_16x16x32_bf16 v[24:27], v[140:143], v[164:167], v[24:27]
	v_mfma_f32_16x16x32_bf16 v[12:15], v[132:135], v[172:175], v[12:15]
	v_mfma_f32_16x16x32_bf16 v[8:11], v[140:143], v[172:175], v[8:11]
	s_setprio 0
	s_barrier
	s_add_u32 s40, s40, 0x80080
	s_addc_u32 s41, s41, 0
	s_add_i32 s42, s42, s49

; #define PG8_STAGE(bufoff, gbase, voff) do { _Pragma("unroll") for (int _i = 0; _i < 2; ++_i) \
;         __builtin_amdgcn_global_load_lds((const unsigned*)((const char*)(gbase) + (voff)[_i]), (LAS unsigned*)(lds + (bufoff) + ldsw + _i * 8192), 16, 0, 0); } while (0)
; template <class Epi>
; DI void gemm_phase(LAS unsigned char* lds, int wid, int K, int lda, int ldb, bool bperm, const Sched3& S, const Epi& E) {
;     ...
;             PG8_STAGE(PG8_SB(1, 1), b3 + hstepB, voffB);
	s_mov_b32 m0, s42
	s_nop 0
	global_load_lds_dwordx4 v176, s[40:41]

; #define PG8_STAGE(bufoff, gbase, voff) do { _Pragma("unroll") for (int _i = 0; _i < 2; ++_i) \
;         __builtin_amdgcn_global_load_lds((const unsigned*)((const char*)(gbase) + (voff)[_i]), (LAS unsigned*)(lds + (bufoff) + ldsw + _i * 8192), 16, 0, 0); } while (0)
; #define PG8_MMA(ai, bj, At, Bt) do { __builtin_amdgcn_s_setprio(1); _Pragma("unroll") for (int m = 0; m < 4; ++m) _Pragma("unroll") for (int n = 0; n < 2; ++n) _Pragma("unroll") for (int k = 0; k < 2; ++k) \
;         acc[ai][bj][m][n] = __builtin_amdgcn_mfma_f32_16x16x32_bf16(Bt[n][k], At[m][k], acc[ai][bj][m][n], 0, 0, 0); __builtin_amdgcn_s_setprio(0); } while (0)
; #define PG8_WAIT_V(n) asm volatile("s_waitcnt vmcnt(" #n ")" ::: "memory")
; #define PG8_BAR __builtin_amdgcn_s_barrier()
; template <class Epi>
; DI void gemm_phase(LAS unsigned char* lds, int wid, int K, int lda, int ldb, bool bperm, const Sched3& S, const Epi& E) {
;     ...
;         for (int t = 0; t < nt; t += 2) {
;     ...
;             PG8_STAGE(PG8_SB(1, 1), b3 + hstepB, voffB);
;             PG8_WAIT_V(6); PG8_BAR; if (full) PG8_MMA(1, 1, At, B1); PG8_BAR;
	s_add_i32 m0, s42, 0x2000
	s_nop 0
	global_load_lds_dwordx4 v178, s[40:41]
	s_waitcnt vmcnt(6)
	s_barrier
	s_setprio 1
	v_mfma_f32_16x16x32_bf16 v[52:55], v[186:189], v[144:147], v[52:55]
	v_mfma_f32_16x16x32_bf16 v[48:51], v[194:197], v[144:147], v[48:51]
	v_mfma_f32_16x16x32_bf16 v[36:39], v[186:189], v[152:155], v[36:39]
	v_mfma_f32_16x16x32_bf16 v[32:35], v[194:197], v[152:155], v[32:35]
	v_mfma_f32_16x16x32_bf16 v[20:23], v[186:189], v[160:163], v[20:23]
	v_mfma_f32_16x16x32_bf16 v[16:19], v[194:197], v[160:163], v[16:19]
	v_mfma_f32_16x16x32_bf16 v[4:7], v[186:189], v[168:171], v[4:7]
	v_mfma_f32_16x16x32_bf16 v[0:3], v[194:197], v[168:171], v[0:3]
	v_mfma_f32_16x16x32_bf16 v[52:55], v[190:193], v[148:151], v[52:55]
	v_mfma_f32_16x16x32_bf16 v[48:51], v[206:209], v[148:151], v[48:51]
	v_mfma_f32_16x16x32_bf16 v[36:39], v[190:193], v[156:159], v[36:39]
	v_mfma_f32_16x16x32_bf16 v[32:35], v[206:209], v[156:159], v[32:35]
	v_mfma_f32_16x16x32_bf16 v[20:23], v[190:193], v[164:167], v[20:23]
	v_mfma_f32_16x16x32_bf16 v[16:19], v[206:209], v[164:167], v[16:19]
	v_mfma_f32_16x16x32_bf16 v[4:7], v[190:193], v[172:175], v[4:7]
	v_mfma_f32_16x16x32_bf16 v[0:3], v[206:209], v[172:175], v[0:3]
	s_setprio 0
	s_add_i32 s29, s29, 2
	s_add_u32 s38, s38, 0x100
	s_addc_u32 s39, s39, 0
	s_add_u32 s21, s21, 0x100
	s_addc_u32 s23, s23, 0
	s_cmp_gt_u32 s29, 29
	s_cbranch_scc1 .Lkrot_1_exit

; #define PG8_STAGE(bufoff, gbase, voff) do { _Pragma("unroll") for (int _i = 0; _i < 2; ++_i) \
;         __builtin_amdgcn_global_load_lds((const unsigned*)((const char*)(gbase) + (voff)[_i]), (LAS unsigned*)(lds + (bufoff) + ldsw + _i * 8192), 16, 0, 0); } while (0)
; #define PG8_LDA(dst, b, h) do { _Pragma("unroll") for (int m = 0; m < 4; ++m) _Pragma("unroll") for (int k = 0; k < 2; ++k) dst[m][k] = *(const LAS bf16x8*)(lds + PG8_SA(b, h) + aoff + m * 2048 + k * 1024); } while (0)
; #define PG8_LDB(dst, b, h) do { _Pragma("unroll") for (int n = 0; n < 2; ++n) _Pragma("unroll") for (int k = 0; k < 2; ++k) dst[n][k] = *(const LAS bf16x8*)(lds + PG8_SB(b, h) + boff + n * 2048 + k * 1024); } while (0)
; #define PG8_SCHED __builtin_amdgcn_sched_barrier(0)
; template <class Epi>
; DI void gemm_phase(LAS unsigned char* lds, int wid, int K, int lda, int ldb, bool bperm, const Sched3& S, const Epi& E) {
;     ...
;             const bool last = (t == nt - 2);
;             const char* a1 = cA + (size_t)(t + 1) * kstep;
;             const char* a2 = last ? nA : cA + (size_t)(t + 2) * kstep; const char* b2 = last ? nB : cB + (size_t)(t + 2) * kstep;
;             const char* a3 = a2 + kstep; const char* b3 = b2 + kstep; const size_t h2 = last ? nhA : hA;
;             PG8_LDB(B0, 0, 0); PG8_SCHED; PG8_LDA(At, 0, 0); PG8_STAGE(PG8_SA(1, 1), a1 + hA, voffA);
.LBB0_621:
	ds_read_b128 v[128:131], v203
	ds_read_b128 v[132:135], v203 offset:1024
	ds_read_b128 v[136:139], v203 offset:2048
	ds_read_b128 v[140:143], v203 offset:3072
	s_add_u32 s40, s38, 0xfff80080
	s_addc_u32 s41, s39, -1
	s_cmp_eq_u32 s29, 28
	s_cselect_b32 s43, s31, s41
	s_cselect_b32 s42, s30, s40
	s_cselect_b32 s41, s37, s23
	s_cselect_b32 s40, s36, s21

; #define PG8_STAGE(bufoff, gbase, voff) do { _Pragma("unroll") for (int _i = 0; _i < 2; ++_i) \
;         __builtin_amdgcn_global_load_lds((const unsigned*)((const char*)(gbase) + (voff)[_i]), (LAS unsigned*)(lds + (bufoff) + ldsw + _i * 8192), 16, 0, 0); } while (0)
; #define PG8_LDA(dst, b, h) do { _Pragma("unroll") for (int m = 0; m < 4; ++m) _Pragma("unroll") for (int k = 0; k < 2; ++k) dst[m][k] = *(const LAS bf16x8*)(lds + PG8_SA(b, h) + aoff + m * 2048 + k * 1024); } while (0)
; #define PG8_LDB(dst, b, h) do { _Pragma("unroll") for (int n = 0; n < 2; ++n) _Pragma("unroll") for (int k = 0; k < 2; ++k) dst[n][k] = *(const LAS bf16x8*)(lds + PG8_SB(b, h) + boff + n * 2048 + k * 1024); } while (0)
; #define PG8_SCHED __builtin_amdgcn_sched_barrier(0)
; template <class Epi>
; DI void gemm_phase(LAS unsigned char* lds, int wid, int K, int lda, int ldb, bool bperm, const Sched3& S, const Epi& E) {
;     ...
;             PG8_LDB(B0, 0, 0); PG8_SCHED; PG8_LDA(At, 0, 0); PG8_STAGE(PG8_SA(1, 1), a1 + hA, voffA);
	s_add_i32 m0, s50, 0xc000
	ds_read_b128 v[144:147], v204
	ds_read_b128 v[148:151], v204 offset:1024
	ds_read_b128 v[152:155], v204 offset:2048
	ds_read_b128 v[156:159], v204 offset:3072
	ds_read_b128 v[160:163], v204 offset:4096
	ds_read_b128 v[164:167], v204 offset:5120
	ds_read_b128 v[168:171], v204 offset:6144
	ds_read_b128 v[172:175], v204 offset:7168
	global_load_lds_dwordx4 v180, s[38:39]

; #define PG8_MMA(ai, bj, At, Bt) do { __builtin_amdgcn_s_setprio(1); _Pragma("unroll") for (int m = 0; m < 4; ++m) _Pragma("unroll") for (int n = 0; n < 2; ++n) _Pragma("unroll") for (int k = 0; k < 2; ++k) \
;         acc[ai][bj][m][n] = __builtin_amdgcn_mfma_f32_16x16x32_bf16(Bt[n][k], At[m][k], acc[ai][bj][m][n], 0, 0, 0); __builtin_amdgcn_s_setprio(0); } while (0)
; #define PG8_WAIT_L(n) asm volatile("s_waitcnt lgkmcnt(" #n ")" ::: "memory")
; #define PG8_BAR __builtin_amdgcn_s_barrier()
; #define PG8_SCHED __builtin_amdgcn_sched_barrier(0)
; template <class Epi>
; DI void gemm_phase(LAS unsigned char* lds, int wid, int K, int lda, int ldb, bool bperm, const Sched3& S, const Epi& E) {
;     ...
;             PG8_WAIT_L(8); PG8_BAR; PG8_WAIT_L(0); PG8_MMA(0, 0, At, B0); PG8_BAR; PG8_SCHED;
	s_add_i32 m0, s50, 0xe000
	s_nop 0
	global_load_lds_dwordx4 v182, s[38:39]
	s_waitcnt lgkmcnt(8)
	s_barrier
	s_waitcnt lgkmcnt(0)
	s_setprio 1
	s_waitcnt lgkmcnt(0)
	v_mfma_f32_16x16x32_bf16 v[124:127], v[128:131], v[144:147], v[124:127]
	v_mfma_f32_16x16x32_bf16 v[120:123], v[136:139], v[144:147], v[120:123]
	v_mfma_f32_16x16x32_bf16 v[108:111], v[128:131], v[152:155], v[108:111]
	v_mfma_f32_16x16x32_bf16 v[104:107], v[136:139], v[152:155], v[104:107]
	v_mfma_f32_16x16x32_bf16 v[92:95], v[128:131], v[160:163], v[92:95]
	v_mfma_f32_16x16x32_bf16 v[88:91], v[136:139], v[160:163], v[88:91]
	v_mfma_f32_16x16x32_bf16 v[76:79], v[128:131], v[168:171], v[76:79]
	v_mfma_f32_16x16x32_bf16 v[72:75], v[136:139], v[168:171], v[72:75]
	v_mfma_f32_16x16x32_bf16 v[124:127], v[132:135], v[148:151], v[124:127]
	v_mfma_f32_16x16x32_bf16 v[120:123], v[140:143], v[148:151], v[120:123]
	v_mfma_f32_16x16x32_bf16 v[108:111], v[132:135], v[156:159], v[108:111]
	v_mfma_f32_16x16x32_bf16 v[104:107], v[140:143], v[156:159], v[104:107]
	v_mfma_f32_16x16x32_bf16 v[92:95], v[132:135], v[164:167], v[92:95]
	v_mfma_f32_16x16x32_bf16 v[88:91], v[140:143], v[164:167], v[88:91]
	v_mfma_f32_16x16x32_bf16 v[76:79], v[132:135], v[172:175], v[76:79]
	v_mfma_f32_16x16x32_bf16 v[72:75], v[140:143], v[172:175], v[72:75]
	s_setprio 0
	s_barrier
	s_add_i32 s63, s59, s49

; #define PG8_STAGE(bufoff, gbase, voff) do { _Pragma("unroll") for (int _i = 0; _i < 2; ++_i) \
;         __builtin_amdgcn_global_load_lds((const unsigned*)((const char*)(gbase) + (voff)[_i]), (LAS unsigned*)(lds + (bufoff) + ldsw + _i * 8192), 16, 0, 0); } while (0)
; #define PG8_LDB(dst, b, h) do { _Pragma("unroll") for (int n = 0; n < 2; ++n) _Pragma("unroll") for (int k = 0; k < 2; ++k) dst[n][k] = *(const LAS bf16x8*)(lds + PG8_SB(b, h) + boff + n * 2048 + k * 1024); } while (0)
; template <class Epi>
; DI void gemm_phase(LAS unsigned char* lds, int wid, int K, int lda, int ldb, bool bperm, const Sched3& S, const Epi& E) {
;     ...
;             PG8_LDB(B1, 0, 1); PG8_STAGE(PG8_SB(0, 0), b2, voffB);
	s_mov_b32 m0, s63
	ds_read_b128 v[186:189], v205
	ds_read_b128 v[190:193], v205 offset:1024
	ds_read_b128 v[194:197], v205 offset:2048
	ds_read_b128 v[206:209], v205 offset:3072
	global_load_lds_dwordx4 v176, s[40:41]

; #define PG8_STAGE(bufoff, gbase, voff) do { _Pragma("unroll") for (int _i = 0; _i < 2; ++_i) \
;         __builtin_amdgcn_global_load_lds((const unsigned*)((const char*)(gbase) + (voff)[_i]), (LAS unsigned*)(lds + (bufoff) + ldsw + _i * 8192), 16, 0, 0); } while (0)
; #define PG8_LDA(dst, b, h) do { _Pragma("unroll") for (int m = 0; m < 4; ++m) _Pragma("unroll") for (int k = 0; k < 2; ++k) dst[m][k] = *(const LAS bf16x8*)(lds + PG8_SA(b, h) + aoff + m * 2048 + k * 1024); } while (0)
; #define PG8_LDB(dst, b, h) do { _Pragma("unroll") for (int n = 0; n < 2; ++n) _Pragma("unroll") for (int k = 0; k < 2; ++k) dst[n][k] = *(const LAS bf16x8*)(lds + PG8_SB(b, h) + boff + n * 2048 + k * 1024); } while (0)
; #define PG8_MMA(ai, bj, At, Bt) do { __builtin_amdgcn_s_setprio(1); _Pragma("unroll") for (int m = 0; m < 4; ++m) _Pragma("unroll") for (int n = 0; n < 2; ++n) _Pragma("unroll") for (int k = 0; k < 2; ++k) \
;         acc[ai][bj][m][n] = __builtin_amdgcn_mfma_f32_16x16x32_bf16(Bt[n][k], At[m][k], acc[ai][bj][m][n], 0, 0, 0); __builtin_amdgcn_s_setprio(0); } while (0)
; #define PG8_WAIT_L(n) asm volatile("s_waitcnt lgkmcnt(" #n ")" ::: "memory")
; #define PG8_BAR __builtin_amdgcn_s_barrier()
; #define PG8_SCHED __builtin_amdgcn_sched_barrier(0)
; template <class Epi>
; DI void gemm_phase(LAS unsigned char* lds, int wid, int K, int lda, int ldb, bool bperm, const Sched3& S, const Epi& E) {
;     ...
;             PG8_LDB(B1, 0, 1); PG8_STAGE(PG8_SB(0, 0), b2, voffB);
;             PG8_BAR; PG8_WAIT_L(0); PG8_MMA(0, 1, At, B1); PG8_BAR;
;             PG8_LDA(At, 0, 1); PG8_STAGE(PG8_SA(0, 0), a2, voffA);
;             PG8_BAR; PG8_WAIT_L(0); if (full) PG8_MMA(1, 0, At, B0); PG8_BAR; PG8_SCHED;
	s_add_i32 m0, s63, 0x2000
	s_nop 0
	global_load_lds_dwordx4 v178, s[40:41]
	s_barrier
	s_waitcnt lgkmcnt(0)
	s_setprio 1
	s_waitcnt lgkmcnt(0)
	v_mfma_f32_16x16x32_bf16 v[116:119], v[186:189], v[144:147], v[116:119]
	v_mfma_f32_16x16x32_bf16 v[112:115], v[194:197], v[144:147], v[112:115]
	v_mfma_f32_16x16x32_bf16 v[100:103], v[186:189], v[152:155], v[100:103]
	v_mfma_f32_16x16x32_bf16 v[96:99], v[194:197], v[152:155], v[96:99]
	v_mfma_f32_16x16x32_bf16 v[84:87], v[186:189], v[160:163], v[84:87]
	v_mfma_f32_16x16x32_bf16 v[80:83], v[194:197], v[160:163], v[80:83]
	v_mfma_f32_16x16x32_bf16 v[68:71], v[186:189], v[168:171], v[68:71]
	v_mfma_f32_16x16x32_bf16 v[64:67], v[194:197], v[168:171], v[64:67]
	v_mfma_f32_16x16x32_bf16 v[116:119], v[190:193], v[148:151], v[116:119]
	v_mfma_f32_16x16x32_bf16 v[112:115], v[206:209], v[148:151], v[112:115]
	v_mfma_f32_16x16x32_bf16 v[100:103], v[190:193], v[156:159], v[100:103]
	v_mfma_f32_16x16x32_bf16 v[96:99], v[206:209], v[156:159], v[96:99]
	v_mfma_f32_16x16x32_bf16 v[84:87], v[190:193], v[164:167], v[84:87]
	v_mfma_f32_16x16x32_bf16 v[80:83], v[206:209], v[164:167], v[80:83]
	v_mfma_f32_16x16x32_bf16 v[68:71], v[190:193], v[172:175], v[68:71]
	v_mfma_f32_16x16x32_bf16 v[64:67], v[206:209], v[172:175], v[64:67]
	s_setprio 0
	s_mov_b32 m0, s50
	s_mov_b64 s[100:101], s[42:43]
	s_barrier
	ds_read_b128 v[144:147], v204 offset:16384
	ds_read_b128 v[148:151], v204 offset:17408
	ds_read_b128 v[152:155], v204 offset:18432
	ds_read_b128 v[156:159], v204 offset:19456
	ds_read_b128 v[160:163], v204 offset:20480
	ds_read_b128 v[164:167], v204 offset:21504
	ds_read_b128 v[168:171], v204 offset:22528
	ds_read_b128 v[172:175], v204 offset:23552
	global_load_lds_dwordx4 v176, s[42:43]
	s_mov_b64 s[100:101], s[42:43]
	s_mov_b32 m0, s51
	s_nop 0
	global_load_lds_dwordx4 v178, s[42:43]
	s_barrier
	s_waitcnt lgkmcnt(0)
	s_setprio 1
	s_waitcnt lgkmcnt(0)
	v_mfma_f32_16x16x32_bf16 v[60:63], v[128:131], v[144:147], v[60:63]
	v_mfma_f32_16x16x32_bf16 v[56:59], v[136:139], v[144:147], v[56:59]
	v_mfma_f32_16x16x32_bf16 v[44:47], v[128:131], v[152:155], v[44:47]
	v_mfma_f32_16x16x32_bf16 v[40:43], v[136:139], v[152:155], v[40:43]
	v_mfma_f32_16x16x32_bf16 v[28:31], v[128:131], v[160:163], v[28:31]
	v_mfma_f32_16x16x32_bf16 v[24:27], v[136:139], v[160:163], v[24:27]
	v_mfma_f32_16x16x32_bf16 v[12:15], v[128:131], v[168:171], v[12:15]
	v_mfma_f32_16x16x32_bf16 v[8:11], v[136:139], v[168:171], v[8:11]
	v_mfma_f32_16x16x32_bf16 v[60:63], v[132:135], v[148:151], v[60:63]
	v_mfma_f32_16x16x32_bf16 v[56:59], v[140:143], v[148:151], v[56:59]
	v_mfma_f32_16x16x32_bf16 v[44:47], v[132:135], v[156:159], v[44:47]
	v_mfma_f32_16x16x32_bf16 v[40:43], v[140:143], v[156:159], v[40:43]
	v_mfma_f32_16x16x32_bf16 v[28:31], v[132:135], v[164:167], v[28:31]
	v_mfma_f32_16x16x32_bf16 v[24:27], v[140:143], v[164:167], v[24:27]
	v_mfma_f32_16x16x32_bf16 v[12:15], v[132:135], v[172:175], v[12:15]
	v_mfma_f32_16x16x32_bf16 v[8:11], v[140:143], v[172:175], v[8:11]
	s_setprio 0
	s_barrier
	s_add_u32 s64, s40, 0x80000
	s_addc_u32 s65, s41, 0
	s_add_i32 s63, s60, s49

; #define PG8_STAGE(bufoff, gbase, voff) do { _Pragma("unroll") for (int _i = 0; _i < 2; ++_i) \
;         __builtin_amdgcn_global_load_lds((const unsigned*)((const char*)(gbase) + (voff)[_i]), (LAS unsigned*)(lds + (bufoff) + ldsw + _i * 8192), 16, 0, 0); } while (0)
; template <class Epi>
; DI void gemm_phase(LAS unsigned char* lds, int wid, int K, int lda, int ldb, bool bperm, const Sched3& S, const Epi& E) {
;     ...
;             PG8_STAGE(PG8_SB(0, 1), b2 + hstepB, voffB);
	s_mov_b32 m0, s63
	s_nop 0
	global_load_lds_dwordx4 v176, s[64:65]

; #define PG8_STAGE(bufoff, gbase, voff) do { _Pragma("unroll") for (int _i = 0; _i < 2; ++_i) \
;         __builtin_amdgcn_global_load_lds((const unsigned*)((const char*)(gbase) + (voff)[_i]), (LAS unsigned*)(lds + (bufoff) + ldsw + _i * 8192), 16, 0, 0); } while (0)
; #define PG8_LDA(dst, b, h) do { _Pragma("unroll") for (int m = 0; m < 4; ++m) _Pragma("unroll") for (int k = 0; k < 2; ++k) dst[m][k] = *(const LAS bf16x8*)(lds + PG8_SA(b, h) + aoff + m * 2048 + k * 1024); } while (0)
; #define PG8_LDB(dst, b, h) do { _Pragma("unroll") for (int n = 0; n < 2; ++n) _Pragma("unroll") for (int k = 0; k < 2; ++k) dst[n][k] = *(const LAS bf16x8*)(lds + PG8_SB(b, h) + boff + n * 2048 + k * 1024); } while (0)
; #define PG8_MMA(ai, bj, At, Bt) do { __builtin_amdgcn_s_setprio(1); _Pragma("unroll") for (int m = 0; m < 4; ++m) _Pragma("unroll") for (int n = 0; n < 2; ++n) _Pragma("unroll") for (int k = 0; k < 2; ++k) \
;         acc[ai][bj][m][n] = __builtin_amdgcn_mfma_f32_16x16x32_bf16(Bt[n][k], At[m][k], acc[ai][bj][m][n], 0, 0, 0); __builtin_amdgcn_s_setprio(0); } while (0)
; #define PG8_WAIT_V(n) asm volatile("s_waitcnt vmcnt(" #n ")" ::: "memory")
; #define PG8_BAR __builtin_amdgcn_s_barrier()
; #define PG8_SCHED __builtin_amdgcn_sched_barrier(0)
; template <class Epi>
; DI void gemm_phase(LAS unsigned char* lds, int wid, int K, int lda, int ldb, bool bperm, const Sched3& S, const Epi& E) {
;     ...
;             PG8_STAGE(PG8_SB(0, 1), b2 + hstepB, voffB);
;             PG8_WAIT_V(6); PG8_BAR; if (full) PG8_MMA(1, 1, At, B1); PG8_BAR;
;             PG8_LDB(B0, 1, 0); PG8_SCHED; PG8_LDA(At, 1, 0); PG8_STAGE(PG8_SA(0, 1), a2 + h2, voffA);
	s_add_i32 m0, s63, 0x2000
	s_nop 0
	global_load_lds_dwordx4 v178, s[64:65]
	s_waitcnt vmcnt(6)
	s_barrier
	s_setprio 1
	v_mfma_f32_16x16x32_bf16 v[52:55], v[186:189], v[144:147], v[52:55]
	v_mfma_f32_16x16x32_bf16 v[48:51], v[194:197], v[144:147], v[48:51]
	v_mfma_f32_16x16x32_bf16 v[36:39], v[186:189], v[152:155], v[36:39]
	v_mfma_f32_16x16x32_bf16 v[32:35], v[194:197], v[152:155], v[32:35]
	v_mfma_f32_16x16x32_bf16 v[20:23], v[186:189], v[160:163], v[20:23]
	v_mfma_f32_16x16x32_bf16 v[16:19], v[194:197], v[160:163], v[16:19]
	v_mfma_f32_16x16x32_bf16 v[4:7], v[186:189], v[168:171], v[4:7]
	v_mfma_f32_16x16x32_bf16 v[0:3], v[194:197], v[168:171], v[0:3]
	v_mfma_f32_16x16x32_bf16 v[52:55], v[190:193], v[148:151], v[52:55]
	v_mfma_f32_16x16x32_bf16 v[48:51], v[206:209], v[148:151], v[48:51]
	v_mfma_f32_16x16x32_bf16 v[36:39], v[190:193], v[156:159], v[36:39]
	v_mfma_f32_16x16x32_bf16 v[32:35], v[206:209], v[156:159], v[32:35]
	v_mfma_f32_16x16x32_bf16 v[20:23], v[190:193], v[164:167], v[20:23]
	v_mfma_f32_16x16x32_bf16 v[16:19], v[206:209], v[164:167], v[16:19]
	v_mfma_f32_16x16x32_bf16 v[4:7], v[190:193], v[172:175], v[4:7]
	v_mfma_f32_16x16x32_bf16 v[0:3], v[206:209], v[172:175], v[0:3]
	s_setprio 0
	s_add_i32 s63, 0, 0x18000
	v_add_u32_e32 v140, s63, v199
	s_barrier
	ds_read_b128 v[128:131], v140
	ds_read_b128 v[132:135], v140 offset:1024
	ds_read_b128 v[136:139], v140 offset:2048
	ds_read_b128 v[140:143], v140 offset:3072
	s_add_u32 s42, s42, 0x80000
	s_addc_u32 s43, s43, 0
	s_mov_b32 m0, s52

; #define PG8_STAGE(bufoff, gbase, voff) do { _Pragma("unroll") for (int _i = 0; _i < 2; ++_i) \
;         __builtin_amdgcn_global_load_lds((const unsigned*)((const char*)(gbase) + (voff)[_i]), (LAS unsigned*)(lds + (bufoff) + ldsw + _i * 8192), 16, 0, 0); } while (0)
; #define PG8_LDA(dst, b, h) do { _Pragma("unroll") for (int m = 0; m < 4; ++m) _Pragma("unroll") for (int k = 0; k < 2; ++k) dst[m][k] = *(const LAS bf16x8*)(lds + PG8_SA(b, h) + aoff + m * 2048 + k * 1024); } while (0)
; #define PG8_LDB(dst, b, h) do { _Pragma("unroll") for (int n = 0; n < 2; ++n) _Pragma("unroll") for (int k = 0; k < 2; ++k) dst[n][k] = *(const LAS bf16x8*)(lds + PG8_SB(b, h) + boff + n * 2048 + k * 1024); } while (0)
; #define PG8_SCHED __builtin_amdgcn_sched_barrier(0)
; template <class Epi>
; DI void gemm_phase(LAS unsigned char* lds, int wid, int K, int lda, int ldb, bool bperm, const Sched3& S, const Epi& E) {
;     ...
;             PG8_LDB(B0, 1, 0); PG8_SCHED; PG8_LDA(At, 1, 0); PG8_STAGE(PG8_SA(0, 1), a2 + h2, voffA);
	ds_read_b128 v[144:147], v204 offset:32768
	ds_read_b128 v[148:151], v204 offset:33792
	ds_read_b128 v[152:155], v204 offset:34816
	ds_read_b128 v[156:159], v204 offset:35840
	ds_read_b128 v[160:163], v204 offset:36864
	ds_read_b128 v[164:167], v204 offset:37888
	ds_read_b128 v[168:171], v204 offset:38912
	ds_read_b128 v[172:175], v204 offset:39936
	global_load_lds_dwordx4 v176, s[42:43]

; #define PG8_MMA(ai, bj, At, Bt) do { __builtin_amdgcn_s_setprio(1); _Pragma("unroll") for (int m = 0; m < 4; ++m) _Pragma("unroll") for (int n = 0; n < 2; ++n) _Pragma("unroll") for (int k = 0; k < 2; ++k) \
;         acc[ai][bj][m][n] = __builtin_amdgcn_mfma_f32_16x16x32_bf16(Bt[n][k], At[m][k], acc[ai][bj][m][n], 0, 0, 0); __builtin_amdgcn_s_setprio(0); } while (0)
; #define PG8_WAIT_L(n) asm volatile("s_waitcnt lgkmcnt(" #n ")" ::: "memory")
; #define PG8_BAR __builtin_amdgcn_s_barrier()
; #define PG8_SCHED __builtin_amdgcn_sched_barrier(0)
; template <class Epi>
; DI void gemm_phase(LAS unsigned char* lds, int wid, int K, int lda, int ldb, bool bperm, const Sched3& S, const Epi& E) {
;     ...
;             PG8_WAIT_L(8); PG8_BAR; PG8_WAIT_L(0); PG8_MMA(0, 0, At, B0); PG8_BAR; PG8_SCHED;
	s_mov_b32 m0, s53
	s_nop 0
	global_load_lds_dwordx4 v178, s[42:43]
	s_waitcnt lgkmcnt(8)
	s_barrier
	s_waitcnt lgkmcnt(0)
	s_setprio 1
	s_waitcnt lgkmcnt(0)
	v_mfma_f32_16x16x32_bf16 v[124:127], v[128:131], v[144:147], v[124:127]
	v_mfma_f32_16x16x32_bf16 v[120:123], v[136:139], v[144:147], v[120:123]
	v_mfma_f32_16x16x32_bf16 v[108:111], v[128:131], v[152:155], v[108:111]
	v_mfma_f32_16x16x32_bf16 v[104:107], v[136:139], v[152:155], v[104:107]
	v_mfma_f32_16x16x32_bf16 v[92:95], v[128:131], v[160:163], v[92:95]
	v_mfma_f32_16x16x32_bf16 v[88:91], v[136:139], v[160:163], v[88:91]
	v_mfma_f32_16x16x32_bf16 v[76:79], v[128:131], v[168:171], v[76:79]
	v_mfma_f32_16x16x32_bf16 v[72:75], v[136:139], v[168:171], v[72:75]
	v_mfma_f32_16x16x32_bf16 v[124:127], v[132:135], v[148:151], v[124:127]
	v_mfma_f32_16x16x32_bf16 v[120:123], v[140:143], v[148:151], v[120:123]
	v_mfma_f32_16x16x32_bf16 v[108:111], v[132:135], v[156:159], v[108:111]
	v_mfma_f32_16x16x32_bf16 v[104:107], v[140:143], v[156:159], v[104:107]
	v_mfma_f32_16x16x32_bf16 v[92:95], v[132:135], v[164:167], v[92:95]
	v_mfma_f32_16x16x32_bf16 v[88:91], v[140:143], v[164:167], v[88:91]
	v_mfma_f32_16x16x32_bf16 v[76:79], v[132:135], v[172:175], v[76:79]
	v_mfma_f32_16x16x32_bf16 v[72:75], v[140:143], v[172:175], v[72:75]
	s_setprio 0
	s_barrier
	s_add_i32 s42, 0, 0x1c000
	s_add_i32 s43, s63, s49
	v_add_u32_e32 v206, s42, v199

; #define PG8_STAGE(bufoff, gbase, voff) do { _Pragma("unroll") for (int _i = 0; _i < 2; ++_i) \
;         __builtin_amdgcn_global_load_lds((const unsigned*)((const char*)(gbase) + (voff)[_i]), (LAS unsigned*)(lds + (bufoff) + ldsw + _i * 8192), 16, 0, 0); } while (0)
; #define PG8_LDB(dst, b, h) do { _Pragma("unroll") for (int n = 0; n < 2; ++n) _Pragma("unroll") for (int k = 0; k < 2; ++k) dst[n][k] = *(const LAS bf16x8*)(lds + PG8_SB(b, h) + boff + n * 2048 + k * 1024); } while (0)
; template <class Epi>
; DI void gemm_phase(LAS unsigned char* lds, int wid, int K, int lda, int ldb, bool bperm, const Sched3& S, const Epi& E) {
;     ...
;             PG8_LDB(B1, 1, 1); PG8_STAGE(PG8_SB(1, 0), b3, voffB);
	s_sub_i32 m0, s43, 0x80
	ds_read_b128 v[186:189], v206
	ds_read_b128 v[190:193], v206 offset:1024
	ds_read_b128 v[194:197], v206 offset:2048
	ds_read_b128 v[206:209], v206 offset:3072
	global_load_lds_dwordx4 v176, s[40:41] offset:128

; #define PG8_STAGE(bufoff, gbase, voff) do { _Pragma("unroll") for (int _i = 0; _i < 2; ++_i) \
;         __builtin_amdgcn_global_load_lds((const unsigned*)((const char*)(gbase) + (voff)[_i]), (LAS unsigned*)(lds + (bufoff) + ldsw + _i * 8192), 16, 0, 0); } while (0)
; #define PG8_LDB(dst, b, h) do { _Pragma("unroll") for (int n = 0; n < 2; ++n) _Pragma("unroll") for (int k = 0; k < 2; ++k) dst[n][k] = *(const LAS bf16x8*)(lds + PG8_SB(b, h) + boff + n * 2048 + k * 1024); } while (0)
; #define PG8_MMA(ai, bj, At, Bt) do { __builtin_amdgcn_s_setprio(1); _Pragma("unroll") for (int m = 0; m < 4; ++m) _Pragma("unroll") for (int n = 0; n < 2; ++n) _Pragma("unroll") for (int k = 0; k < 2; ++k) \
;         acc[ai][bj][m][n] = __builtin_amdgcn_mfma_f32_16x16x32_bf16(Bt[n][k], At[m][k], acc[ai][bj][m][n], 0, 0, 0); __builtin_amdgcn_s_setprio(0); } while (0)
; #define PG8_WAIT_L(n) asm volatile("s_waitcnt lgkmcnt(" #n ")" ::: "memory")
; #define PG8_BAR __builtin_amdgcn_s_barrier()
; template <class Epi>
; DI void gemm_phase(LAS unsigned char* lds, int wid, int K, int lda, int ldb, bool bperm, const Sched3& S, const Epi& E) {
;     ...
;             PG8_LDB(B1, 1, 1); PG8_STAGE(PG8_SB(1, 0), b3, voffB);
;             PG8_BAR; PG8_WAIT_L(0); PG8_MMA(0, 1, At, B1); PG8_BAR;
	s_add_i32 m0, s43, 0x1f80
	s_nop 0
	global_load_lds_dwordx4 v178, s[40:41] offset:128
	s_barrier
	s_waitcnt lgkmcnt(0)
	s_setprio 1
	s_waitcnt lgkmcnt(0)
	v_mfma_f32_16x16x32_bf16 v[116:119], v[186:189], v[144:147], v[116:119]
	v_mfma_f32_16x16x32_bf16 v[112:115], v[194:197], v[144:147], v[112:115]
	v_mfma_f32_16x16x32_bf16 v[100:103], v[186:189], v[152:155], v[100:103]
	v_mfma_f32_16x16x32_bf16 v[96:99], v[194:197], v[152:155], v[96:99]
	v_mfma_f32_16x16x32_bf16 v[84:87], v[186:189], v[160:163], v[84:87]
	v_mfma_f32_16x16x32_bf16 v[80:83], v[194:197], v[160:163], v[80:83]
	v_mfma_f32_16x16x32_bf16 v[68:71], v[186:189], v[168:171], v[68:71]
	v_mfma_f32_16x16x32_bf16 v[64:67], v[194:197], v[168:171], v[64:67]
	v_mfma_f32_16x16x32_bf16 v[116:119], v[190:193], v[148:151], v[116:119]
	v_mfma_f32_16x16x32_bf16 v[112:115], v[206:209], v[148:151], v[112:115]
	v_mfma_f32_16x16x32_bf16 v[100:103], v[190:193], v[156:159], v[100:103]
	v_mfma_f32_16x16x32_bf16 v[96:99], v[206:209], v[156:159], v[96:99]
	v_mfma_f32_16x16x32_bf16 v[84:87], v[190:193], v[164:167], v[84:87]
	v_mfma_f32_16x16x32_bf16 v[80:83], v[206:209], v[164:167], v[80:83]
	v_mfma_f32_16x16x32_bf16 v[68:71], v[190:193], v[172:175], v[68:71]
	v_mfma_f32_16x16x32_bf16 v[64:67], v[206:209], v[172:175], v[64:67]
	s_setprio 0
	s_sub_i32 m0, s55, 0x80

; #define PG8_STAGE(bufoff, gbase, voff) do { _Pragma("unroll") for (int _i = 0; _i < 2; ++_i) \
;         __builtin_amdgcn_global_load_lds((const unsigned*)((const char*)(gbase) + (voff)[_i]), (LAS unsigned*)(lds + (bufoff) + ldsw + _i * 8192), 16, 0, 0); } while (0)
; #define PG8_LDA(dst, b, h) do { _Pragma("unroll") for (int m = 0; m < 4; ++m) _Pragma("unroll") for (int k = 0; k < 2; ++k) dst[m][k] = *(const LAS bf16x8*)(lds + PG8_SA(b, h) + aoff + m * 2048 + k * 1024); } while (0)
; template <class Epi>
; DI void gemm_phase(LAS unsigned char* lds, int wid, int K, int lda, int ldb, bool bperm, const Sched3& S, const Epi& E) {
;     ...
;             PG8_LDA(At, 1, 1); PG8_STAGE(PG8_SA(1, 0), a3, voffA);
	s_barrier
	ds_read_b128 v[144:147], v204 offset:49152
	ds_read_b128 v[148:151], v204 offset:50176
	ds_read_b128 v[152:155], v204 offset:51200
	ds_read_b128 v[156:159], v204 offset:52224
	ds_read_b128 v[160:163], v204 offset:53248
	ds_read_b128 v[164:167], v204 offset:54272
	ds_read_b128 v[168:171], v204 offset:55296
	ds_read_b128 v[172:175], v204 offset:56320
	global_load_lds_dwordx4 v176, s[100:101] offset:128

; #define PG8_STAGE(bufoff, gbase, voff) do { _Pragma("unroll") for (int _i = 0; _i < 2; ++_i) \
;         __builtin_amdgcn_global_load_lds((const unsigned*)((const char*)(gbase) + (voff)[_i]), (LAS unsigned*)(lds + (bufoff) + ldsw + _i * 8192), 16, 0, 0); } while (0)
; #define PG8_LDA(dst, b, h) do { _Pragma("unroll") for (int m = 0; m < 4; ++m) _Pragma("unroll") for (int k = 0; k < 2; ++k) dst[m][k] = *(const LAS bf16x8*)(lds + PG8_SA(b, h) + aoff + m * 2048 + k * 1024); } while (0)
; #define PG8_MMA(ai, bj, At, Bt) do { __builtin_amdgcn_s_setprio(1); _Pragma("unroll") for (int m = 0; m < 4; ++m) _Pragma("unroll") for (int n = 0; n < 2; ++n) _Pragma("unroll") for (int k = 0; k < 2; ++k) \
;         acc[ai][bj][m][n] = __builtin_amdgcn_mfma_f32_16x16x32_bf16(Bt[n][k], At[m][k], acc[ai][bj][m][n], 0, 0, 0); __builtin_amdgcn_s_setprio(0); } while (0)
; #define PG8_WAIT_L(n) asm volatile("s_waitcnt lgkmcnt(" #n ")" ::: "memory")
; #define PG8_BAR __builtin_amdgcn_s_barrier()
; #define PG8_SCHED __builtin_amdgcn_sched_barrier(0)
; template <class Epi>
; DI void gemm_phase(LAS unsigned char* lds, int wid, int K, int lda, int ldb, bool bperm, const Sched3& S, const Epi& E) {
;     ...
;             PG8_LDA(At, 1, 1); PG8_STAGE(PG8_SA(1, 0), a3, voffA);
;             PG8_BAR; PG8_WAIT_L(0); if (full) PG8_MMA(1, 0, At, B0); PG8_BAR; PG8_SCHED;
	s_sub_i32 m0, s56, 0x80
	s_nop 0
	global_load_lds_dwordx4 v178, s[100:101] offset:128
	s_barrier
	s_waitcnt lgkmcnt(0)
	s_setprio 1
	s_waitcnt lgkmcnt(0)
	v_mfma_f32_16x16x32_bf16 v[60:63], v[128:131], v[144:147], v[60:63]
	v_mfma_f32_16x16x32_bf16 v[56:59], v[136:139], v[144:147], v[56:59]
	v_mfma_f32_16x16x32_bf16 v[44:47], v[128:131], v[152:155], v[44:47]
	v_mfma_f32_16x16x32_bf16 v[40:43], v[136:139], v[152:155], v[40:43]
	v_mfma_f32_16x16x32_bf16 v[28:31], v[128:131], v[160:163], v[28:31]
	v_mfma_f32_16x16x32_bf16 v[24:27], v[136:139], v[160:163], v[24:27]
	v_mfma_f32_16x16x32_bf16 v[12:15], v[128:131], v[168:171], v[12:15]
	v_mfma_f32_16x16x32_bf16 v[8:11], v[136:139], v[168:171], v[8:11]
	v_mfma_f32_16x16x32_bf16 v[60:63], v[132:135], v[148:151], v[60:63]
	v_mfma_f32_16x16x32_bf16 v[56:59], v[140:143], v[148:151], v[56:59]
	v_mfma_f32_16x16x32_bf16 v[44:47], v[132:135], v[156:159], v[44:47]
	v_mfma_f32_16x16x32_bf16 v[40:43], v[140:143], v[156:159], v[40:43]
	v_mfma_f32_16x16x32_bf16 v[28:31], v[132:135], v[164:167], v[28:31]
	v_mfma_f32_16x16x32_bf16 v[24:27], v[140:143], v[164:167], v[24:27]
	v_mfma_f32_16x16x32_bf16 v[12:15], v[132:135], v[172:175], v[12:15]
	v_mfma_f32_16x16x32_bf16 v[8:11], v[140:143], v[172:175], v[8:11]
	s_setprio 0
	s_barrier
	s_add_u32 s40, s40, 0x80080
	s_addc_u32 s41, s41, 0
	s_add_i32 s42, s42, s49

; #define PG8_STAGE(bufoff, gbase, voff) do { _Pragma("unroll") for (int _i = 0; _i < 2; ++_i) \
;         __builtin_amdgcn_global_load_lds((const unsigned*)((const char*)(gbase) + (voff)[_i]), (LAS unsigned*)(lds + (bufoff) + ldsw + _i * 8192), 16, 0, 0); } while (0)
; template <class Epi>
; DI void gemm_phase(LAS unsigned char* lds, int wid, int K, int lda, int ldb, bool bperm, const Sched3& S, const Epi& E) {
;     ...
;             PG8_STAGE(PG8_SB(1, 1), b3 + hstepB, voffB);
	s_mov_b32 m0, s42
	s_nop 0
	global_load_lds_dwordx4 v176, s[40:41]

; DI u32x2 pk4(f32x4 v) { u32x2 r; r.x = pk2(v[0], v[1]); r.y = pk2(v[2], v[3]); return r; }
; DI float bf_lo(unsigned w) { return __uint_as_float(w << 16); }
; DI float bf_hi(unsigned w) { return __uint_as_float(w & 0xffff0000u); }
; #define PG8_WAIT_V(n) asm volatile("s_waitcnt vmcnt(" #n ")" ::: "memory")
; #define PG8_BAR __builtin_amdgcn_s_barrier()
; #define COLS4 _Pragma("unroll") for (int bj = 0; bj < 2; ++bj) _Pragma("unroll") for (int n = 0; n < 2; ++n)
; template <class Epi>
; DI void gemm_phase(LAS unsigned char* lds, int wid, int K, int lda, int ldb, bool bperm, const Sched3& S, const Epi& E) {
;     ...
;             PG8_STAGE(PG8_SB(1, 1), b3 + hstepB, voffB);
;             PG8_WAIT_V(6); PG8_BAR; if (full) PG8_MMA(1, 1, At, B1); PG8_BAR;
;         }
;     DI void operator()(const Acc& acc, const Unit& u, int wr, int wc, int fr, int fq) const {
;     ...
;             for (int ai = 0; ai < 2; ++ai) if (ai == 0 || !hf) {
;                 f32x4 xo[4][2][2];
; #pragma unroll
;                 for (int m = 0; m < 4; ++m) { const size_t o = (size_t)(row0 + ai * HALF + m * 16) * 2048 + colp;
;                     if (PH == 4) { COLS4 xo[m][bj][n] = *(const f32x4*)(p.x + o + bj * HALF + n * 4); }
;                     else {
; #pragma unroll
;                         for (int bj = 0; bj < 2; ++bj) { const u32x4 w = *(const u32x4*)(WSB(OFF_XB) + o + bj * HALF);
;                             xo[m][bj][0] = (f32x4){bf_lo(w.x), bf_hi(w.x), bf_lo(w.y), bf_hi(w.y)}; xo[m][bj][1] = (f32x4){bf_lo(w.z), bf_hi(w.z), bf_lo(w.w), bf_hi(w.w)}; } } }
; #pragma unroll
;                 for (int m = 0; m < 4; ++m) { const int r = row0 + ai * HALF + m * 16; const size_t o = (size_t)r * 2048 + colp; float part = 0.f;
; #pragma unroll
;                     for (int bj = 0; bj < 2; ++bj) { const f32x4 x0 = xo[m][bj][0] + acc[ai][bj][m][0], x1 = xo[m][bj][1] + acc[ai][bj][m][1];
;                         const u32x2 h0 = pk4(x0), h1 = pk4(x1);
;                         *(u32x4*)(WSB(OFF_XB) + o + bj * HALF) = (u32x4){h0.x, h0.y, h1.x, h1.y};
;                         part += x0[0] * x0[0] + x0[1] * x0[1] + x0[2] * x0[2] + x0[3] * x0[3] + x1[0] * x1[0] + x1[1] * x1[1] + x1[2] * x1[2] + x1[3] * x1[3]; }
;                     part += __shfl_xor(part, 16); part += __shfl_xor(part, 32);
;                     if (fq == 0) unsafeAtomicAdd(ssq + r, part);
;                 }
	s_add_i32 m0, s42, 0x2000
	s_nop 0
	global_load_lds_dwordx4 v178, s[40:41]
	s_waitcnt vmcnt(6)
	s_barrier
	s_setprio 1
	v_mfma_f32_16x16x32_bf16 v[52:55], v[186:189], v[144:147], v[52:55]
	v_mfma_f32_16x16x32_bf16 v[48:51], v[194:197], v[144:147], v[48:51]
	v_mfma_f32_16x16x32_bf16 v[36:39], v[186:189], v[152:155], v[36:39]
	v_mfma_f32_16x16x32_bf16 v[32:35], v[194:197], v[152:155], v[32:35]
	v_mfma_f32_16x16x32_bf16 v[20:23], v[186:189], v[160:163], v[20:23]
	v_mfma_f32_16x16x32_bf16 v[16:19], v[194:197], v[160:163], v[16:19]
	v_mfma_f32_16x16x32_bf16 v[4:7], v[186:189], v[168:171], v[4:7]
	v_mfma_f32_16x16x32_bf16 v[0:3], v[194:197], v[168:171], v[0:3]
	v_mfma_f32_16x16x32_bf16 v[52:55], v[190:193], v[148:151], v[52:55]
	v_mfma_f32_16x16x32_bf16 v[48:51], v[206:209], v[148:151], v[48:51]
	v_mfma_f32_16x16x32_bf16 v[36:39], v[190:193], v[156:159], v[36:39]
	v_mfma_f32_16x16x32_bf16 v[32:35], v[206:209], v[156:159], v[32:35]
	v_mfma_f32_16x16x32_bf16 v[20:23], v[190:193], v[164:167], v[20:23]
	v_mfma_f32_16x16x32_bf16 v[16:19], v[206:209], v[164:167], v[16:19]
	v_mfma_f32_16x16x32_bf16 v[4:7], v[190:193], v[172:175], v[4:7]
	v_mfma_f32_16x16x32_bf16 v[0:3], v[206:209], v[172:175], v[0:3]
	s_setprio 0
	s_add_i32 s29, s29, 2
	s_add_u32 s38, s38, 0x100
	s_addc_u32 s39, s39, 0
	s_add_u32 s21, s21, 0x100
	s_addc_u32 s23, s23, 0
	s_cmp_gt_u32 s29, 29
	s_cbranch_scc0 .Lkrot_1_head
.Lkrot_1_exit:
	s_barrier
.Lpeel_1_exit:
	v_lshl_add_u32 v190, s28, 8, v198
	v_lshl_add_u32 v186, s62, 8, v200
	v_ashrrev_i32_e32 v187, 31, v186
	v_ashrrev_i32_e32 v191, 31, v190
	v_lshl_add_u64 v[188:189], v[186:187], 2, s[16:17]
	v_lshlrev_b64 v[128:129], 13, v[190:191]
	v_lshl_add_u64 v[128:129], v[188:189], 0, v[128:129]
	global_load_dwordx4 v[206:209], v[128:129], off
	global_load_dwordx4 v[210:213], v[128:129], off offset:16
	global_load_dwordx4 v[214:217], v[128:129], off offset:512
	global_load_dwordx4 v[218:221], v[128:129], off offset:528
	v_or_b32_e32 v196, 16, v190
	v_or_b32_e32 v194, 32, v190
	v_or_b32_e32 v192, 48, v190
	v_ashrrev_i32_e32 v197, 31, v196
	v_ashrrev_i32_e32 v195, 31, v194
	v_ashrrev_i32_e32 v193, 31, v192
	v_lshlrev_b64 v[128:129], 13, v[196:197]
	v_lshlrev_b64 v[130:131], 13, v[194:195]
	v_lshlrev_b64 v[132:133], 13, v[192:193]
	v_lshl_add_u64 v[128:129], v[188:189], 0, v[128:129]
	v_lshl_add_u64 v[130:131], v[188:189], 0, v[130:131]
	v_lshl_add_u64 v[132:133], v[188:189], 0, v[132:133]
	global_load_dwordx4 v[168:171], v[128:129], off offset:16
	global_load_dwordx4 v[172:175], v[128:129], off
	global_load_dwordx4 v[160:163], v[128:129], off offset:528
	global_load_dwordx4 v[164:167], v[128:129], off offset:512
	global_load_dwordx4 v[152:155], v[130:131], off offset:16
	global_load_dwordx4 v[156:159], v[130:131], off
	global_load_dwordx4 v[144:147], v[130:131], off offset:528
	global_load_dwordx4 v[148:151], v[130:131], off offset:512
	global_load_dwordx4 v[136:139], v[132:133], off offset:16
	global_load_dwordx4 v[140:143], v[132:133], off
	s_nop 0
	global_load_dwordx4 v[128:131], v[132:133], off offset:528
	s_nop 0
	global_load_dwordx4 v[132:135], v[132:133], off offset:512
	v_lshlrev_b64 v[222:223], 12, v[190:191]
	v_lshlrev_b64 v[186:187], 1, v[186:187]
	v_lshl_add_u64 v[224:225], s[18:19], 0, v[222:223]
	v_lshl_add_u64 v[224:225], v[224:225], 0, v[186:187]
	v_lshl_add_u64 v[222:223], s[10:11], 0, v[222:223]
	v_lshl_add_u64 v[222:223], v[222:223], 0, v[186:187]
	s_waitcnt vmcnt(0)
	v_pk_add_f32 v[124:125], v[124:125], v[206:207]
	v_pk_add_f32 v[120:121], v[120:121], v[210:211]
	v_pk_add_f32 v[206:207], v[116:117], v[214:215]
	v_pk_add_f32 v[210:211], v[112:113], v[218:219]
	v_cvt_pk_bf16_f32 v112, v124, v125
	v_mul_f32_e32 v117, v125, v125
	v_mul_f32_e32 v125, v207, v207
	v_pk_add_f32 v[126:127], v[126:127], v[208:209]
	v_pk_add_f32 v[118:119], v[118:119], v[216:217]
	v_fmac_f32_e32 v117, v124, v124
	v_fmac_f32_e32 v125, v206, v206
	v_fmac_f32_e32 v117, v126, v126
	v_fmac_f32_e32 v125, v118, v118
	v_fmac_f32_e32 v117, v127, v127
	v_fmac_f32_e32 v125, v119, v119
	v_fmac_f32_e32 v117, v120, v120
	v_fmac_f32_e32 v125, v210, v210
	v_pk_add_f32 v[122:123], v[122:123], v[212:213]
	v_pk_add_f32 v[208:209], v[114:115], v[220:221]
	v_fmac_f32_e32 v117, v121, v121
	v_fmac_f32_e32 v125, v211, v211
	v_fmac_f32_e32 v117, v122, v122
	v_fmac_f32_e32 v125, v208, v208
	v_fmac_f32_e32 v117, v123, v123
	v_fmac_f32_e32 v125, v209, v209
	v_cvt_pk_bf16_f32 v114, v120, v121
	v_add_f32_e32 v120, v117, v125
	ds_bpermute_b32 v121, v201, v120
	v_cvt_pk_bf16_f32 v113, v126, v127
	v_cvt_pk_bf16_f32 v115, v122, v123
	global_store_dwordx4 v[224:225], v[112:115], off sc1
	v_cvt_pk_bf16_f32 v116, v206, v207
	v_cvt_pk_bf16_f32 v117, v118, v119
	s_waitcnt lgkmcnt(0)
	v_add_f32_e32 v112, v120, v121
	ds_bpermute_b32 v113, v202, v112
	v_add_co_u32_e32 v114, vcc, s61, v222
	v_cvt_pk_bf16_f32 v118, v210, v211
	v_cvt_pk_bf16_f32 v119, v208, v209
	v_addc_co_u32_e32 v115, vcc, 0, v223, vcc
	global_store_dwordx4 v[114:115], v[116:119], off offset:256 sc1
	s_and_saveexec_b64 s[28:29], s[2:3]
	s_cbranch_execz .LBB0_624
	s_waitcnt lgkmcnt(0)
	v_add_f32_e32 v114, v112, v113
	v_lshl_add_u64 v[112:113], v[190:191], 2, s[14:15]
	global_atomic_add_f32 v[112:113], v114, off

; #define PG8_STAGE(bufoff, gbase, voff) do { _Pragma("unroll") for (int _i = 0; _i < 2; ++_i) \
;         __builtin_amdgcn_global_load_lds((const unsigned*)((const char*)(gbase) + (voff)[_i]), (LAS unsigned*)(lds + (bufoff) + ldsw + _i * 8192), 16, 0, 0); } while (0)
; #define PG8_LDA(dst, b, h) do { _Pragma("unroll") for (int m = 0; m < 4; ++m) _Pragma("unroll") for (int k = 0; k < 2; ++k) dst[m][k] = *(const LAS bf16x8*)(lds + PG8_SA(b, h) + aoff + m * 2048 + k * 1024); } while (0)
; #define PG8_LDB(dst, b, h) do { _Pragma("unroll") for (int n = 0; n < 2; ++n) _Pragma("unroll") for (int k = 0; k < 2; ++k) dst[n][k] = *(const LAS bf16x8*)(lds + PG8_SB(b, h) + boff + n * 2048 + k * 1024); } while (0)
; #define PG8_SCHED __builtin_amdgcn_sched_barrier(0)
; #define LOAD_ROW_RS(rsv, ssqp, invn) float rsv[2][4]; ROWS8_ALL rsv[ai][m] = (ssqp)[row0 + ai * HALF + m * 16]; ROWS8_ALL rsv[ai][m] = rstd_of(rsv[ai][m], invn)
; template <class Epi>
; DI void gemm_phase(LAS unsigned char* lds, int wid, int K, int lda, int ldb, bool bperm, const Sched3& S, const Epi& E) {
;     ...
;             const bool last = (t == nt - 2);
;             const char* a1 = cA + (size_t)(t + 1) * kstep;
;             const char* a2 = last ? nA : cA + (size_t)(t + 2) * kstep; const char* b2 = last ? nB : cB + (size_t)(t + 2) * kstep;
;             const char* a3 = a2 + kstep; const char* b3 = b2 + kstep; const size_t h2 = last ? nhA : hA;
;             PG8_LDB(B0, 0, 0); PG8_SCHED; PG8_LDA(At, 0, 0); PG8_STAGE(PG8_SA(1, 1), a1 + hA, voffA);
;     DI void operator()(const Acc& acc, const Unit& u, int wr, int wc, int fr, int fq) const {
;     ...
;             LOAD_ROW_RS(rsv, SSQ(PH == 5 ? 2 : 6), 1.f / 2048.f);
.LBB0_704:
	v_lshl_add_u32 v218, s22, 8, v155
	v_lshlrev_b32_e32 v218, 2, v218
	global_load_dword v220, v218, s[10:11]
	global_load_dword v221, v218, s[10:11] offset:64
	global_load_dword v222, v218, s[10:11] offset:128
	global_load_dword v223, v218, s[10:11] offset:192
	global_load_dword v224, v218, s[10:11] offset:512
	global_load_dword v225, v218, s[10:11] offset:576
	global_load_dword v226, v218, s[10:11] offset:640
	global_load_dword v227, v218, s[10:11] offset:704
	s_add_u32 s28, s28, 0x80080
	s_addc_u32 s29, s29, 0
	s_add_u32 s15, s30, 0x100
	s_nop 0
	s_addc_u32 s17, s31, 0
	s_mov_b32 s57, -2
	ds_read_b128 v[138:141], v160
	ds_read_b128 v[142:145], v160 offset:1024
	ds_read_b128 v[146:149], v160 offset:2048
	ds_read_b128 v[150:153], v160 offset:3072
	s_add_u32 s30, s28, 0xfff80080
	s_addc_u32 s31, s29, -1
	s_cmp_eq_u32 s57, 28
	s_cselect_b32 s37, s25, s31
	s_cselect_b32 s36, s24, s30
	s_cselect_b32 s31, s27, s17
	s_cselect_b32 s30, s26, s15

; #define PG8_STAGE(bufoff, gbase, voff) do { _Pragma("unroll") for (int _i = 0; _i < 2; ++_i) \
;         __builtin_amdgcn_global_load_lds((const unsigned*)((const char*)(gbase) + (voff)[_i]), (LAS unsigned*)(lds + (bufoff) + ldsw + _i * 8192), 16, 0, 0); } while (0)
; #define PG8_LDA(dst, b, h) do { _Pragma("unroll") for (int m = 0; m < 4; ++m) _Pragma("unroll") for (int k = 0; k < 2; ++k) dst[m][k] = *(const LAS bf16x8*)(lds + PG8_SA(b, h) + aoff + m * 2048 + k * 1024); } while (0)
; #define PG8_LDB(dst, b, h) do { _Pragma("unroll") for (int n = 0; n < 2; ++n) _Pragma("unroll") for (int k = 0; k < 2; ++k) dst[n][k] = *(const LAS bf16x8*)(lds + PG8_SB(b, h) + boff + n * 2048 + k * 1024); } while (0)
; #define PG8_SCHED __builtin_amdgcn_sched_barrier(0)
; template <class Epi>
; DI void gemm_phase(LAS unsigned char* lds, int wid, int K, int lda, int ldb, bool bperm, const Sched3& S, const Epi& E) {
;     ...
;             PG8_LDB(B0, 0, 0); PG8_SCHED; PG8_LDA(At, 0, 0); PG8_STAGE(PG8_SA(1, 1), a1 + hA, voffA);
	s_add_i32 m0, s23, 0xc000
	ds_read_b128 v[164:167], v161
	ds_read_b128 v[168:171], v161 offset:1024
	ds_read_b128 v[172:175], v161 offset:2048
	ds_read_b128 v[176:179], v161 offset:3072
	ds_read_b128 v[180:183], v161 offset:4096
	ds_read_b128 v[184:187], v161 offset:5120
	ds_read_b128 v[188:191], v161 offset:6144
	ds_read_b128 v[192:195], v161 offset:7168
	global_load_lds_dwordx4 v132, s[28:29]

; #define PG8_MMA(ai, bj, At, Bt) do { __builtin_amdgcn_s_setprio(1); _Pragma("unroll") for (int m = 0; m < 4; ++m) _Pragma("unroll") for (int n = 0; n < 2; ++n) _Pragma("unroll") for (int k = 0; k < 2; ++k) \
;         acc[ai][bj][m][n] = __builtin_amdgcn_mfma_f32_16x16x32_bf16(Bt[n][k], At[m][k], acc[ai][bj][m][n], 0, 0, 0); __builtin_amdgcn_s_setprio(0); } while (0)
; #define PG8_WAIT_L(n) asm volatile("s_waitcnt lgkmcnt(" #n ")" ::: "memory")
; #define PG8_BAR __builtin_amdgcn_s_barrier()
; #define PG8_SCHED __builtin_amdgcn_sched_barrier(0)
; template <class Epi>
; DI void gemm_phase(LAS unsigned char* lds, int wid, int K, int lda, int ldb, bool bperm, const Sched3& S, const Epi& E) {
;     ...
;             PG8_WAIT_L(8); PG8_BAR; PG8_WAIT_L(0); PG8_MMA(0, 0, At, B0); PG8_BAR; PG8_SCHED;
	s_add_i32 m0, s23, 0xe000
	s_nop 0
	global_load_lds_dwordx4 v134, s[28:29]
	s_waitcnt lgkmcnt(8)
	s_barrier
	s_waitcnt lgkmcnt(0)
	s_setprio 1
	s_waitcnt lgkmcnt(0)
	v_mfma_f32_16x16x32_bf16 v[124:127], v[138:141], v[164:167], 0
	v_mfma_f32_16x16x32_bf16 v[120:123], v[146:149], v[164:167], 0
	v_mfma_f32_16x16x32_bf16 v[116:119], v[138:141], v[172:175], 0
	v_mfma_f32_16x16x32_bf16 v[104:107], v[146:149], v[172:175], 0
	v_mfma_f32_16x16x32_bf16 v[96:99], v[138:141], v[180:183], 0
	v_mfma_f32_16x16x32_bf16 v[88:91], v[146:149], v[180:183], 0
	v_mfma_f32_16x16x32_bf16 v[80:83], v[138:141], v[188:191], 0
	v_mfma_f32_16x16x32_bf16 v[72:75], v[146:149], v[188:191], 0
	v_mfma_f32_16x16x32_bf16 v[124:127], v[142:145], v[168:171], v[124:127]
	v_mfma_f32_16x16x32_bf16 v[120:123], v[150:153], v[168:171], v[120:123]
	v_mfma_f32_16x16x32_bf16 v[116:119], v[142:145], v[176:179], v[116:119]
	v_mfma_f32_16x16x32_bf16 v[104:107], v[150:153], v[176:179], v[104:107]
	v_mfma_f32_16x16x32_bf16 v[96:99], v[142:145], v[184:187], v[96:99]
	v_mfma_f32_16x16x32_bf16 v[88:91], v[150:153], v[184:187], v[88:91]
	v_mfma_f32_16x16x32_bf16 v[80:83], v[142:145], v[192:195], v[80:83]
	v_mfma_f32_16x16x32_bf16 v[72:75], v[150:153], v[192:195], v[72:75]
	s_setprio 0
	s_barrier
	s_add_i32 s58, s53, s43

; #define PG8_STAGE(bufoff, gbase, voff) do { _Pragma("unroll") for (int _i = 0; _i < 2; ++_i) \
;         __builtin_amdgcn_global_load_lds((const unsigned*)((const char*)(gbase) + (voff)[_i]), (LAS unsigned*)(lds + (bufoff) + ldsw + _i * 8192), 16, 0, 0); } while (0)
; #define PG8_LDB(dst, b, h) do { _Pragma("unroll") for (int n = 0; n < 2; ++n) _Pragma("unroll") for (int k = 0; k < 2; ++k) dst[n][k] = *(const LAS bf16x8*)(lds + PG8_SB(b, h) + boff + n * 2048 + k * 1024); } while (0)
; template <class Epi>
; DI void gemm_phase(LAS unsigned char* lds, int wid, int K, int lda, int ldb, bool bperm, const Sched3& S, const Epi& E) {
;     ...
;             PG8_LDB(B1, 0, 1); PG8_STAGE(PG8_SB(0, 0), b2, voffB);
	s_mov_b32 m0, s58
	ds_read_b128 v[196:199], v162
	ds_read_b128 v[200:203], v162 offset:1024
	ds_read_b128 v[204:207], v162 offset:2048
	ds_read_b128 v[208:211], v162 offset:3072
	global_load_lds_dwordx4 v130, s[30:31]

; #define PG8_STAGE(bufoff, gbase, voff) do { _Pragma("unroll") for (int _i = 0; _i < 2; ++_i) \
;         __builtin_amdgcn_global_load_lds((const unsigned*)((const char*)(gbase) + (voff)[_i]), (LAS unsigned*)(lds + (bufoff) + ldsw + _i * 8192), 16, 0, 0); } while (0)
; #define PG8_LDA(dst, b, h) do { _Pragma("unroll") for (int m = 0; m < 4; ++m) _Pragma("unroll") for (int k = 0; k < 2; ++k) dst[m][k] = *(const LAS bf16x8*)(lds + PG8_SA(b, h) + aoff + m * 2048 + k * 1024); } while (0)
; #define PG8_LDB(dst, b, h) do { _Pragma("unroll") for (int n = 0; n < 2; ++n) _Pragma("unroll") for (int k = 0; k < 2; ++k) dst[n][k] = *(const LAS bf16x8*)(lds + PG8_SB(b, h) + boff + n * 2048 + k * 1024); } while (0)
; #define PG8_MMA(ai, bj, At, Bt) do { __builtin_amdgcn_s_setprio(1); _Pragma("unroll") for (int m = 0; m < 4; ++m) _Pragma("unroll") for (int n = 0; n < 2; ++n) _Pragma("unroll") for (int k = 0; k < 2; ++k) \
;         acc[ai][bj][m][n] = __builtin_amdgcn_mfma_f32_16x16x32_bf16(Bt[n][k], At[m][k], acc[ai][bj][m][n], 0, 0, 0); __builtin_amdgcn_s_setprio(0); } while (0)
; #define PG8_WAIT_L(n) asm volatile("s_waitcnt lgkmcnt(" #n ")" ::: "memory")
; #define PG8_BAR __builtin_amdgcn_s_barrier()
; #define PG8_SCHED __builtin_amdgcn_sched_barrier(0)
; template <class Epi>
; DI void gemm_phase(LAS unsigned char* lds, int wid, int K, int lda, int ldb, bool bperm, const Sched3& S, const Epi& E) {
;     ...
;             PG8_LDB(B1, 0, 1); PG8_STAGE(PG8_SB(0, 0), b2, voffB);
;             PG8_BAR; PG8_WAIT_L(0); PG8_MMA(0, 1, At, B1); PG8_BAR;
;             PG8_LDA(At, 0, 1); PG8_STAGE(PG8_SA(0, 0), a2, voffA);
;             PG8_BAR; PG8_WAIT_L(0); if (full) PG8_MMA(1, 0, At, B0); PG8_BAR; PG8_SCHED;
	s_add_i32 m0, s58, 0x2000
	s_nop 0
	global_load_lds_dwordx4 v128, s[30:31]
	s_barrier
	s_waitcnt lgkmcnt(0)
	s_setprio 1
	s_waitcnt lgkmcnt(0)
	v_mfma_f32_16x16x32_bf16 v[112:115], v[196:199], v[164:167], 0
	v_mfma_f32_16x16x32_bf16 v[108:111], v[204:207], v[164:167], 0
	v_mfma_f32_16x16x32_bf16 v[100:103], v[196:199], v[172:175], 0
	v_mfma_f32_16x16x32_bf16 v[92:95], v[204:207], v[172:175], 0
	v_mfma_f32_16x16x32_bf16 v[84:87], v[196:199], v[180:183], 0
	v_mfma_f32_16x16x32_bf16 v[76:79], v[204:207], v[180:183], 0
	v_mfma_f32_16x16x32_bf16 v[68:71], v[196:199], v[188:191], 0
	v_mfma_f32_16x16x32_bf16 v[64:67], v[204:207], v[188:191], 0
	v_mfma_f32_16x16x32_bf16 v[112:115], v[200:203], v[168:171], v[112:115]
	v_mfma_f32_16x16x32_bf16 v[108:111], v[208:211], v[168:171], v[108:111]
	v_mfma_f32_16x16x32_bf16 v[100:103], v[200:203], v[176:179], v[100:103]
	v_mfma_f32_16x16x32_bf16 v[92:95], v[208:211], v[176:179], v[92:95]
	v_mfma_f32_16x16x32_bf16 v[84:87], v[200:203], v[184:187], v[84:87]
	v_mfma_f32_16x16x32_bf16 v[76:79], v[208:211], v[184:187], v[76:79]
	v_mfma_f32_16x16x32_bf16 v[68:71], v[200:203], v[192:195], v[68:71]
	v_mfma_f32_16x16x32_bf16 v[64:67], v[208:211], v[192:195], v[64:67]
	s_setprio 0
	s_mov_b32 m0, s23
	s_mov_b64 s[100:101], s[36:37]
	s_barrier
	ds_read_b128 v[164:167], v161 offset:16384
	ds_read_b128 v[168:171], v161 offset:17408
	ds_read_b128 v[172:175], v161 offset:18432
	ds_read_b128 v[176:179], v161 offset:19456
	ds_read_b128 v[180:183], v161 offset:20480
	ds_read_b128 v[184:187], v161 offset:21504
	ds_read_b128 v[188:191], v161 offset:22528
	ds_read_b128 v[192:195], v161 offset:23552
	global_load_lds_dwordx4 v130, s[36:37]
	s_mov_b64 s[100:101], s[36:37]
	s_mov_b32 m0, s46
	s_nop 0
	global_load_lds_dwordx4 v128, s[36:37]
	s_barrier
	s_waitcnt lgkmcnt(0)
	s_setprio 1
	s_waitcnt lgkmcnt(0)
	v_mfma_f32_16x16x32_bf16 v[60:63], v[138:141], v[164:167], 0
	v_mfma_f32_16x16x32_bf16 v[56:59], v[146:149], v[164:167], 0
	v_mfma_f32_16x16x32_bf16 v[48:51], v[138:141], v[172:175], 0
	v_mfma_f32_16x16x32_bf16 v[40:43], v[146:149], v[172:175], 0
	v_mfma_f32_16x16x32_bf16 v[32:35], v[138:141], v[180:183], 0
	v_mfma_f32_16x16x32_bf16 v[24:27], v[146:149], v[180:183], 0
	v_mfma_f32_16x16x32_bf16 v[16:19], v[138:141], v[188:191], 0
	v_mfma_f32_16x16x32_bf16 v[8:11], v[146:149], v[188:191], 0
	v_mfma_f32_16x16x32_bf16 v[60:63], v[142:145], v[168:171], v[60:63]
	v_mfma_f32_16x16x32_bf16 v[56:59], v[150:153], v[168:171], v[56:59]
	v_mfma_f32_16x16x32_bf16 v[48:51], v[142:145], v[176:179], v[48:51]
	v_mfma_f32_16x16x32_bf16 v[40:43], v[150:153], v[176:179], v[40:43]
	v_mfma_f32_16x16x32_bf16 v[32:35], v[142:145], v[184:187], v[32:35]
	v_mfma_f32_16x16x32_bf16 v[24:27], v[150:153], v[184:187], v[24:27]
	v_mfma_f32_16x16x32_bf16 v[16:19], v[142:145], v[192:195], v[16:19]
	v_mfma_f32_16x16x32_bf16 v[8:11], v[150:153], v[192:195], v[8:11]
	s_setprio 0
	s_barrier
	s_add_u32 s58, s30, 0x80000
	s_addc_u32 s59, s31, 0
	s_add_i32 s60, s54, s43

; #define PG8_STAGE(bufoff, gbase, voff) do { _Pragma("unroll") for (int _i = 0; _i < 2; ++_i) \
;         __builtin_amdgcn_global_load_lds((const unsigned*)((const char*)(gbase) + (voff)[_i]), (LAS unsigned*)(lds + (bufoff) + ldsw + _i * 8192), 16, 0, 0); } while (0)
; template <class Epi>
; DI void gemm_phase(LAS unsigned char* lds, int wid, int K, int lda, int ldb, bool bperm, const Sched3& S, const Epi& E) {
;     ...
;             PG8_STAGE(PG8_SB(0, 1), b2 + hstepB, voffB);
	s_mov_b32 m0, s60
	s_nop 0
	global_load_lds_dwordx4 v130, s[58:59]

; #define PG8_STAGE(bufoff, gbase, voff) do { _Pragma("unroll") for (int _i = 0; _i < 2; ++_i) \
;         __builtin_amdgcn_global_load_lds((const unsigned*)((const char*)(gbase) + (voff)[_i]), (LAS unsigned*)(lds + (bufoff) + ldsw + _i * 8192), 16, 0, 0); } while (0)
; #define PG8_LDA(dst, b, h) do { _Pragma("unroll") for (int m = 0; m < 4; ++m) _Pragma("unroll") for (int k = 0; k < 2; ++k) dst[m][k] = *(const LAS bf16x8*)(lds + PG8_SA(b, h) + aoff + m * 2048 + k * 1024); } while (0)
; #define PG8_LDB(dst, b, h) do { _Pragma("unroll") for (int n = 0; n < 2; ++n) _Pragma("unroll") for (int k = 0; k < 2; ++k) dst[n][k] = *(const LAS bf16x8*)(lds + PG8_SB(b, h) + boff + n * 2048 + k * 1024); } while (0)
; #define PG8_MMA(ai, bj, At, Bt) do { __builtin_amdgcn_s_setprio(1); _Pragma("unroll") for (int m = 0; m < 4; ++m) _Pragma("unroll") for (int n = 0; n < 2; ++n) _Pragma("unroll") for (int k = 0; k < 2; ++k) \
;         acc[ai][bj][m][n] = __builtin_amdgcn_mfma_f32_16x16x32_bf16(Bt[n][k], At[m][k], acc[ai][bj][m][n], 0, 0, 0); __builtin_amdgcn_s_setprio(0); } while (0)
; #define PG8_WAIT_V(n) asm volatile("s_waitcnt vmcnt(" #n ")" ::: "memory")
; #define PG8_BAR __builtin_amdgcn_s_barrier()
; #define PG8_SCHED __builtin_amdgcn_sched_barrier(0)
; template <class Epi>
; DI void gemm_phase(LAS unsigned char* lds, int wid, int K, int lda, int ldb, bool bperm, const Sched3& S, const Epi& E) {
;     ...
;             PG8_STAGE(PG8_SB(0, 1), b2 + hstepB, voffB);
;             PG8_WAIT_V(6); PG8_BAR; if (full) PG8_MMA(1, 1, At, B1); PG8_BAR;
;             PG8_LDB(B0, 1, 0); PG8_SCHED; PG8_LDA(At, 1, 0); PG8_STAGE(PG8_SA(0, 1), a2 + h2, voffA);
	s_add_i32 m0, s60, 0x2000
	s_nop 0
	global_load_lds_dwordx4 v128, s[58:59]
	s_waitcnt vmcnt(6)
	s_barrier
	s_setprio 1
	v_mfma_f32_16x16x32_bf16 v[52:55], v[196:199], v[164:167], 0
	v_mfma_f32_16x16x32_bf16 v[44:47], v[204:207], v[164:167], 0
	v_mfma_f32_16x16x32_bf16 v[36:39], v[196:199], v[172:175], 0
	v_mfma_f32_16x16x32_bf16 v[28:31], v[204:207], v[172:175], 0
	v_mfma_f32_16x16x32_bf16 v[20:23], v[196:199], v[180:183], 0
	v_mfma_f32_16x16x32_bf16 v[12:15], v[204:207], v[180:183], 0
	v_mfma_f32_16x16x32_bf16 v[4:7], v[196:199], v[188:191], 0
	v_mfma_f32_16x16x32_bf16 v[0:3], v[204:207], v[188:191], 0
	v_mfma_f32_16x16x32_bf16 v[52:55], v[200:203], v[168:171], v[52:55]
	v_mfma_f32_16x16x32_bf16 v[44:47], v[208:211], v[168:171], v[44:47]
	v_mfma_f32_16x16x32_bf16 v[36:39], v[200:203], v[176:179], v[36:39]
	v_mfma_f32_16x16x32_bf16 v[28:31], v[208:211], v[176:179], v[28:31]
	v_mfma_f32_16x16x32_bf16 v[20:23], v[200:203], v[184:187], v[20:23]
	v_mfma_f32_16x16x32_bf16 v[12:15], v[208:211], v[184:187], v[12:15]
	v_mfma_f32_16x16x32_bf16 v[4:7], v[200:203], v[192:195], v[4:7]
	v_mfma_f32_16x16x32_bf16 v[0:3], v[208:211], v[192:195], v[0:3]
	s_setprio 0
	s_add_i32 s58, 0, 0x18000
	v_add_u32_e32 v150, s58, v158
	s_barrier
	ds_read_b128 v[138:141], v150
	ds_read_b128 v[142:145], v150 offset:1024
	ds_read_b128 v[146:149], v150 offset:2048
	ds_read_b128 v[150:153], v150 offset:3072
	s_add_u32 s36, s36, 0x80000
	s_addc_u32 s37, s37, 0
	s_mov_b32 m0, s47

; #define PG8_STAGE(bufoff, gbase, voff) do { _Pragma("unroll") for (int _i = 0; _i < 2; ++_i) \
;         __builtin_amdgcn_global_load_lds((const unsigned*)((const char*)(gbase) + (voff)[_i]), (LAS unsigned*)(lds + (bufoff) + ldsw + _i * 8192), 16, 0, 0); } while (0)
; #define PG8_LDA(dst, b, h) do { _Pragma("unroll") for (int m = 0; m < 4; ++m) _Pragma("unroll") for (int k = 0; k < 2; ++k) dst[m][k] = *(const LAS bf16x8*)(lds + PG8_SA(b, h) + aoff + m * 2048 + k * 1024); } while (0)
; #define PG8_LDB(dst, b, h) do { _Pragma("unroll") for (int n = 0; n < 2; ++n) _Pragma("unroll") for (int k = 0; k < 2; ++k) dst[n][k] = *(const LAS bf16x8*)(lds + PG8_SB(b, h) + boff + n * 2048 + k * 1024); } while (0)
; #define PG8_SCHED __builtin_amdgcn_sched_barrier(0)
; template <class Epi>
; DI void gemm_phase(LAS unsigned char* lds, int wid, int K, int lda, int ldb, bool bperm, const Sched3& S, const Epi& E) {
;     ...
;             PG8_LDB(B0, 1, 0); PG8_SCHED; PG8_LDA(At, 1, 0); PG8_STAGE(PG8_SA(0, 1), a2 + h2, voffA);
	ds_read_b128 v[164:167], v161 offset:32768
	ds_read_b128 v[168:171], v161 offset:33792
	ds_read_b128 v[172:175], v161 offset:34816
	ds_read_b128 v[176:179], v161 offset:35840
	ds_read_b128 v[180:183], v161 offset:36864
	ds_read_b128 v[184:187], v161 offset:37888
	ds_read_b128 v[188:191], v161 offset:38912
	ds_read_b128 v[192:195], v161 offset:39936
	global_load_lds_dwordx4 v130, s[36:37]

; #define PG8_MMA(ai, bj, At, Bt) do { __builtin_amdgcn_s_setprio(1); _Pragma("unroll") for (int m = 0; m < 4; ++m) _Pragma("unroll") for (int n = 0; n < 2; ++n) _Pragma("unroll") for (int k = 0; k < 2; ++k) \
;         acc[ai][bj][m][n] = __builtin_amdgcn_mfma_f32_16x16x32_bf16(Bt[n][k], At[m][k], acc[ai][bj][m][n], 0, 0, 0); __builtin_amdgcn_s_setprio(0); } while (0)
; #define PG8_WAIT_L(n) asm volatile("s_waitcnt lgkmcnt(" #n ")" ::: "memory")
; #define PG8_BAR __builtin_amdgcn_s_barrier()
; #define PG8_SCHED __builtin_amdgcn_sched_barrier(0)
; template <class Epi>
; DI void gemm_phase(LAS unsigned char* lds, int wid, int K, int lda, int ldb, bool bperm, const Sched3& S, const Epi& E) {
;     ...
;             PG8_WAIT_L(8); PG8_BAR; PG8_WAIT_L(0); PG8_MMA(0, 0, At, B0); PG8_BAR; PG8_SCHED;
	s_mov_b32 m0, s48
	s_nop 0
	global_load_lds_dwordx4 v128, s[36:37]
	s_waitcnt lgkmcnt(8)
	s_barrier
	s_waitcnt lgkmcnt(0)
	s_setprio 1
	s_waitcnt lgkmcnt(0)
	v_mfma_f32_16x16x32_bf16 v[124:127], v[138:141], v[164:167], v[124:127]
	v_mfma_f32_16x16x32_bf16 v[120:123], v[146:149], v[164:167], v[120:123]
	v_mfma_f32_16x16x32_bf16 v[116:119], v[138:141], v[172:175], v[116:119]
	v_mfma_f32_16x16x32_bf16 v[104:107], v[146:149], v[172:175], v[104:107]
	v_mfma_f32_16x16x32_bf16 v[96:99], v[138:141], v[180:183], v[96:99]
	v_mfma_f32_16x16x32_bf16 v[88:91], v[146:149], v[180:183], v[88:91]
	v_mfma_f32_16x16x32_bf16 v[80:83], v[138:141], v[188:191], v[80:83]
	v_mfma_f32_16x16x32_bf16 v[72:75], v[146:149], v[188:191], v[72:75]
	v_mfma_f32_16x16x32_bf16 v[124:127], v[142:145], v[168:171], v[124:127]
	v_mfma_f32_16x16x32_bf16 v[120:123], v[150:153], v[168:171], v[120:123]
	v_mfma_f32_16x16x32_bf16 v[116:119], v[142:145], v[176:179], v[116:119]
	v_mfma_f32_16x16x32_bf16 v[104:107], v[150:153], v[176:179], v[104:107]
	v_mfma_f32_16x16x32_bf16 v[96:99], v[142:145], v[184:187], v[96:99]
	v_mfma_f32_16x16x32_bf16 v[88:91], v[150:153], v[184:187], v[88:91]
	v_mfma_f32_16x16x32_bf16 v[80:83], v[142:145], v[192:195], v[80:83]
	v_mfma_f32_16x16x32_bf16 v[72:75], v[150:153], v[192:195], v[72:75]
	s_setprio 0
	s_barrier
	s_add_i32 s36, 0, 0x1c000
	s_add_i32 s37, s58, s43
	v_add_u32_e32 v154, s36, v158

; #define PG8_STAGE(bufoff, gbase, voff) do { _Pragma("unroll") for (int _i = 0; _i < 2; ++_i) \
;         __builtin_amdgcn_global_load_lds((const unsigned*)((const char*)(gbase) + (voff)[_i]), (LAS unsigned*)(lds + (bufoff) + ldsw + _i * 8192), 16, 0, 0); } while (0)
; #define PG8_LDB(dst, b, h) do { _Pragma("unroll") for (int n = 0; n < 2; ++n) _Pragma("unroll") for (int k = 0; k < 2; ++k) dst[n][k] = *(const LAS bf16x8*)(lds + PG8_SB(b, h) + boff + n * 2048 + k * 1024); } while (0)
; template <class Epi>
; DI void gemm_phase(LAS unsigned char* lds, int wid, int K, int lda, int ldb, bool bperm, const Sched3& S, const Epi& E) {
;     ...
;             PG8_LDB(B1, 1, 1); PG8_STAGE(PG8_SB(1, 0), b3, voffB);
	s_sub_i32 m0, s37, 0x80
	ds_read_b128 v[196:199], v154
	ds_read_b128 v[200:203], v154 offset:1024
	ds_read_b128 v[204:207], v154 offset:2048
	ds_read_b128 v[208:211], v154 offset:3072
	global_load_lds_dwordx4 v130, s[30:31] offset:128

; #define PG8_STAGE(bufoff, gbase, voff) do { _Pragma("unroll") for (int _i = 0; _i < 2; ++_i) \
;         __builtin_amdgcn_global_load_lds((const unsigned*)((const char*)(gbase) + (voff)[_i]), (LAS unsigned*)(lds + (bufoff) + ldsw + _i * 8192), 16, 0, 0); } while (0)
; #define PG8_LDB(dst, b, h) do { _Pragma("unroll") for (int n = 0; n < 2; ++n) _Pragma("unroll") for (int k = 0; k < 2; ++k) dst[n][k] = *(const LAS bf16x8*)(lds + PG8_SB(b, h) + boff + n * 2048 + k * 1024); } while (0)
; #define PG8_MMA(ai, bj, At, Bt) do { __builtin_amdgcn_s_setprio(1); _Pragma("unroll") for (int m = 0; m < 4; ++m) _Pragma("unroll") for (int n = 0; n < 2; ++n) _Pragma("unroll") for (int k = 0; k < 2; ++k) \
;         acc[ai][bj][m][n] = __builtin_amdgcn_mfma_f32_16x16x32_bf16(Bt[n][k], At[m][k], acc[ai][bj][m][n], 0, 0, 0); __builtin_amdgcn_s_setprio(0); } while (0)
; #define PG8_WAIT_L(n) asm volatile("s_waitcnt lgkmcnt(" #n ")" ::: "memory")
; #define PG8_BAR __builtin_amdgcn_s_barrier()
; template <class Epi>
; DI void gemm_phase(LAS unsigned char* lds, int wid, int K, int lda, int ldb, bool bperm, const Sched3& S, const Epi& E) {
;     ...
;             PG8_LDB(B1, 1, 1); PG8_STAGE(PG8_SB(1, 0), b3, voffB);
;             PG8_BAR; PG8_WAIT_L(0); PG8_MMA(0, 1, At, B1); PG8_BAR;
	s_add_i32 m0, s37, 0x1f80
	s_nop 0
	global_load_lds_dwordx4 v128, s[30:31] offset:128
	s_barrier
	s_waitcnt lgkmcnt(0)
	s_setprio 1
	s_waitcnt lgkmcnt(0)
	v_mfma_f32_16x16x32_bf16 v[112:115], v[196:199], v[164:167], v[112:115]
	v_mfma_f32_16x16x32_bf16 v[108:111], v[204:207], v[164:167], v[108:111]
	v_mfma_f32_16x16x32_bf16 v[100:103], v[196:199], v[172:175], v[100:103]
	v_mfma_f32_16x16x32_bf16 v[92:95], v[204:207], v[172:175], v[92:95]
	v_mfma_f32_16x16x32_bf16 v[84:87], v[196:199], v[180:183], v[84:87]
	v_mfma_f32_16x16x32_bf16 v[76:79], v[204:207], v[180:183], v[76:79]
	v_mfma_f32_16x16x32_bf16 v[68:71], v[196:199], v[188:191], v[68:71]
	v_mfma_f32_16x16x32_bf16 v[64:67], v[204:207], v[188:191], v[64:67]
	v_mfma_f32_16x16x32_bf16 v[112:115], v[200:203], v[168:171], v[112:115]
	v_mfma_f32_16x16x32_bf16 v[108:111], v[208:211], v[168:171], v[108:111]
	v_mfma_f32_16x16x32_bf16 v[100:103], v[200:203], v[176:179], v[100:103]
	v_mfma_f32_16x16x32_bf16 v[92:95], v[208:211], v[176:179], v[92:95]
	v_mfma_f32_16x16x32_bf16 v[84:87], v[200:203], v[184:187], v[84:87]
	v_mfma_f32_16x16x32_bf16 v[76:79], v[208:211], v[184:187], v[76:79]
	v_mfma_f32_16x16x32_bf16 v[68:71], v[200:203], v[192:195], v[68:71]
	v_mfma_f32_16x16x32_bf16 v[64:67], v[208:211], v[192:195], v[64:67]
	s_setprio 0
	s_sub_i32 m0, s49, 0x80

; #define PG8_STAGE(bufoff, gbase, voff) do { _Pragma("unroll") for (int _i = 0; _i < 2; ++_i) \
;         __builtin_amdgcn_global_load_lds((const unsigned*)((const char*)(gbase) + (voff)[_i]), (LAS unsigned*)(lds + (bufoff) + ldsw + _i * 8192), 16, 0, 0); } while (0)
; #define PG8_LDA(dst, b, h) do { _Pragma("unroll") for (int m = 0; m < 4; ++m) _Pragma("unroll") for (int k = 0; k < 2; ++k) dst[m][k] = *(const LAS bf16x8*)(lds + PG8_SA(b, h) + aoff + m * 2048 + k * 1024); } while (0)
; template <class Epi>
; DI void gemm_phase(LAS unsigned char* lds, int wid, int K, int lda, int ldb, bool bperm, const Sched3& S, const Epi& E) {
;     ...
;             PG8_LDA(At, 1, 1); PG8_STAGE(PG8_SA(1, 0), a3, voffA);
	s_barrier
	ds_read_b128 v[164:167], v161 offset:49152
	ds_read_b128 v[168:171], v161 offset:50176
	ds_read_b128 v[172:175], v161 offset:51200
	ds_read_b128 v[176:179], v161 offset:52224
	ds_read_b128 v[180:183], v161 offset:53248
	ds_read_b128 v[184:187], v161 offset:54272
	ds_read_b128 v[188:191], v161 offset:55296
	ds_read_b128 v[192:195], v161 offset:56320
	global_load_lds_dwordx4 v130, s[100:101] offset:128

; #define PG8_STAGE(bufoff, gbase, voff) do { _Pragma("unroll") for (int _i = 0; _i < 2; ++_i) \
;         __builtin_amdgcn_global_load_lds((const unsigned*)((const char*)(gbase) + (voff)[_i]), (LAS unsigned*)(lds + (bufoff) + ldsw + _i * 8192), 16, 0, 0); } while (0)
; #define PG8_LDA(dst, b, h) do { _Pragma("unroll") for (int m = 0; m < 4; ++m) _Pragma("unroll") for (int k = 0; k < 2; ++k) dst[m][k] = *(const LAS bf16x8*)(lds + PG8_SA(b, h) + aoff + m * 2048 + k * 1024); } while (0)
; #define PG8_MMA(ai, bj, At, Bt) do { __builtin_amdgcn_s_setprio(1); _Pragma("unroll") for (int m = 0; m < 4; ++m) _Pragma("unroll") for (int n = 0; n < 2; ++n) _Pragma("unroll") for (int k = 0; k < 2; ++k) \
;         acc[ai][bj][m][n] = __builtin_amdgcn_mfma_f32_16x16x32_bf16(Bt[n][k], At[m][k], acc[ai][bj][m][n], 0, 0, 0); __builtin_amdgcn_s_setprio(0); } while (0)
; #define PG8_WAIT_L(n) asm volatile("s_waitcnt lgkmcnt(" #n ")" ::: "memory")
; #define PG8_BAR __builtin_amdgcn_s_barrier()
; #define PG8_SCHED __builtin_amdgcn_sched_barrier(0)
; template <class Epi>
; DI void gemm_phase(LAS unsigned char* lds, int wid, int K, int lda, int ldb, bool bperm, const Sched3& S, const Epi& E) {
;     ...
;             PG8_LDA(At, 1, 1); PG8_STAGE(PG8_SA(1, 0), a3, voffA);
;             PG8_BAR; PG8_WAIT_L(0); if (full) PG8_MMA(1, 0, At, B0); PG8_BAR; PG8_SCHED;
	s_sub_i32 m0, s50, 0x80
	s_nop 0
	global_load_lds_dwordx4 v128, s[100:101] offset:128
	s_barrier
	s_waitcnt lgkmcnt(0)
	s_setprio 1
	s_waitcnt lgkmcnt(0)
	v_mfma_f32_16x16x32_bf16 v[60:63], v[138:141], v[164:167], v[60:63]
	v_mfma_f32_16x16x32_bf16 v[56:59], v[146:149], v[164:167], v[56:59]
	v_mfma_f32_16x16x32_bf16 v[48:51], v[138:141], v[172:175], v[48:51]
	v_mfma_f32_16x16x32_bf16 v[40:43], v[146:149], v[172:175], v[40:43]
	v_mfma_f32_16x16x32_bf16 v[32:35], v[138:141], v[180:183], v[32:35]
	v_mfma_f32_16x16x32_bf16 v[24:27], v[146:149], v[180:183], v[24:27]
	v_mfma_f32_16x16x32_bf16 v[16:19], v[138:141], v[188:191], v[16:19]
	v_mfma_f32_16x16x32_bf16 v[8:11], v[146:149], v[188:191], v[8:11]
	v_mfma_f32_16x16x32_bf16 v[60:63], v[142:145], v[168:171], v[60:63]
	v_mfma_f32_16x16x32_bf16 v[56:59], v[150:153], v[168:171], v[56:59]
	v_mfma_f32_16x16x32_bf16 v[48:51], v[142:145], v[176:179], v[48:51]
	v_mfma_f32_16x16x32_bf16 v[40:43], v[150:153], v[176:179], v[40:43]
	v_mfma_f32_16x16x32_bf16 v[32:35], v[142:145], v[184:187], v[32:35]
	v_mfma_f32_16x16x32_bf16 v[24:27], v[150:153], v[184:187], v[24:27]
	v_mfma_f32_16x16x32_bf16 v[16:19], v[142:145], v[192:195], v[16:19]
	v_mfma_f32_16x16x32_bf16 v[8:11], v[150:153], v[192:195], v[8:11]
	s_setprio 0
	s_barrier
	s_add_u32 s30, s30, 0x80080
	s_addc_u32 s31, s31, 0
	s_add_i32 s36, s36, s43

; #define PG8_STAGE(bufoff, gbase, voff) do { _Pragma("unroll") for (int _i = 0; _i < 2; ++_i) \
;         __builtin_amdgcn_global_load_lds((const unsigned*)((const char*)(gbase) + (voff)[_i]), (LAS unsigned*)(lds + (bufoff) + ldsw + _i * 8192), 16, 0, 0); } while (0)
; template <class Epi>
; DI void gemm_phase(LAS unsigned char* lds, int wid, int K, int lda, int ldb, bool bperm, const Sched3& S, const Epi& E) {
;     ...
;             PG8_STAGE(PG8_SB(1, 1), b3 + hstepB, voffB);
	s_mov_b32 m0, s36
	s_nop 0
	global_load_lds_dwordx4 v130, s[30:31]

; #define PG8_STAGE(bufoff, gbase, voff) do { _Pragma("unroll") for (int _i = 0; _i < 2; ++_i) \
;         __builtin_amdgcn_global_load_lds((const unsigned*)((const char*)(gbase) + (voff)[_i]), (LAS unsigned*)(lds + (bufoff) + ldsw + _i * 8192), 16, 0, 0); } while (0)
; #define PG8_MMA(ai, bj, At, Bt) do { __builtin_amdgcn_s_setprio(1); _Pragma("unroll") for (int m = 0; m < 4; ++m) _Pragma("unroll") for (int n = 0; n < 2; ++n) _Pragma("unroll") for (int k = 0; k < 2; ++k) \
;         acc[ai][bj][m][n] = __builtin_amdgcn_mfma_f32_16x16x32_bf16(Bt[n][k], At[m][k], acc[ai][bj][m][n], 0, 0, 0); __builtin_amdgcn_s_setprio(0); } while (0)
; #define PG8_WAIT_V(n) asm volatile("s_waitcnt vmcnt(" #n ")" ::: "memory")
; #define PG8_BAR __builtin_amdgcn_s_barrier()
; template <class Epi>
; DI void gemm_phase(LAS unsigned char* lds, int wid, int K, int lda, int ldb, bool bperm, const Sched3& S, const Epi& E) {
;     ...
;             PG8_STAGE(PG8_SB(1, 1), b3 + hstepB, voffB);
;             PG8_WAIT_V(6); PG8_BAR; if (full) PG8_MMA(1, 1, At, B1); PG8_BAR;
	s_add_i32 m0, s36, 0x2000
	s_nop 0
	global_load_lds_dwordx4 v128, s[30:31]
	s_waitcnt vmcnt(6)
	s_barrier
	s_setprio 1
	v_mfma_f32_16x16x32_bf16 v[52:55], v[196:199], v[164:167], v[52:55]
	v_mfma_f32_16x16x32_bf16 v[44:47], v[204:207], v[164:167], v[44:47]
	v_mfma_f32_16x16x32_bf16 v[36:39], v[196:199], v[172:175], v[36:39]
	v_mfma_f32_16x16x32_bf16 v[28:31], v[204:207], v[172:175], v[28:31]
	v_mfma_f32_16x16x32_bf16 v[20:23], v[196:199], v[180:183], v[20:23]
	v_mfma_f32_16x16x32_bf16 v[12:15], v[204:207], v[180:183], v[12:15]
	v_mfma_f32_16x16x32_bf16 v[4:7], v[196:199], v[188:191], v[4:7]
	v_mfma_f32_16x16x32_bf16 v[0:3], v[204:207], v[188:191], v[0:3]
	v_mfma_f32_16x16x32_bf16 v[52:55], v[200:203], v[168:171], v[52:55]
	v_mfma_f32_16x16x32_bf16 v[44:47], v[208:211], v[168:171], v[44:47]
	v_mfma_f32_16x16x32_bf16 v[36:39], v[200:203], v[176:179], v[36:39]
	v_mfma_f32_16x16x32_bf16 v[28:31], v[208:211], v[176:179], v[28:31]
	v_mfma_f32_16x16x32_bf16 v[20:23], v[200:203], v[184:187], v[20:23]
	v_mfma_f32_16x16x32_bf16 v[12:15], v[208:211], v[184:187], v[12:15]
	v_mfma_f32_16x16x32_bf16 v[4:7], v[200:203], v[192:195], v[4:7]
	v_mfma_f32_16x16x32_bf16 v[0:3], v[208:211], v[192:195], v[0:3]
	s_setprio 0
	s_add_i32 s57, s57, 2
	s_add_u32 s28, s28, 0x100
	s_addc_u32 s29, s29, 0
	s_add_u32 s15, s15, 0x100
	s_addc_u32 s17, s17, 0
	s_cmp_gt_u32 s57, 29
	s_cbranch_scc1 .Lkrot_2_exit

; #define PG8_STAGE(bufoff, gbase, voff) do { _Pragma("unroll") for (int _i = 0; _i < 2; ++_i) \
;         __builtin_amdgcn_global_load_lds((const unsigned*)((const char*)(gbase) + (voff)[_i]), (LAS unsigned*)(lds + (bufoff) + ldsw + _i * 8192), 16, 0, 0); } while (0)
; #define PG8_LDA(dst, b, h) do { _Pragma("unroll") for (int m = 0; m < 4; ++m) _Pragma("unroll") for (int k = 0; k < 2; ++k) dst[m][k] = *(const LAS bf16x8*)(lds + PG8_SA(b, h) + aoff + m * 2048 + k * 1024); } while (0)
; #define PG8_LDB(dst, b, h) do { _Pragma("unroll") for (int n = 0; n < 2; ++n) _Pragma("unroll") for (int k = 0; k < 2; ++k) dst[n][k] = *(const LAS bf16x8*)(lds + PG8_SB(b, h) + boff + n * 2048 + k * 1024); } while (0)
; #define PG8_SCHED __builtin_amdgcn_sched_barrier(0)
; template <class Epi>
; DI void gemm_phase(LAS unsigned char* lds, int wid, int K, int lda, int ldb, bool bperm, const Sched3& S, const Epi& E) {
;     ...
;             const bool last = (t == nt - 2);
;             const char* a1 = cA + (size_t)(t + 1) * kstep;
;             const char* a2 = last ? nA : cA + (size_t)(t + 2) * kstep; const char* b2 = last ? nB : cB + (size_t)(t + 2) * kstep;
;             const char* a3 = a2 + kstep; const char* b3 = b2 + kstep; const size_t h2 = last ? nhA : hA;
;             PG8_LDB(B0, 0, 0); PG8_SCHED; PG8_LDA(At, 0, 0); PG8_STAGE(PG8_SA(1, 1), a1 + hA, voffA);
.LBB0_705:
	ds_read_b128 v[138:141], v160
	ds_read_b128 v[142:145], v160 offset:1024
	ds_read_b128 v[146:149], v160 offset:2048
	ds_read_b128 v[150:153], v160 offset:3072
	s_add_u32 s30, s28, 0xfff80080
	s_addc_u32 s31, s29, -1
	s_cmp_eq_u32 s57, 28
	s_cselect_b32 s37, s25, s31
	s_cselect_b32 s36, s24, s30
	s_cselect_b32 s31, s27, s17
	s_cselect_b32 s30, s26, s15

; #define PG8_STAGE(bufoff, gbase, voff) do { _Pragma("unroll") for (int _i = 0; _i < 2; ++_i) \
;         __builtin_amdgcn_global_load_lds((const unsigned*)((const char*)(gbase) + (voff)[_i]), (LAS unsigned*)(lds + (bufoff) + ldsw + _i * 8192), 16, 0, 0); } while (0)
; #define PG8_LDA(dst, b, h) do { _Pragma("unroll") for (int m = 0; m < 4; ++m) _Pragma("unroll") for (int k = 0; k < 2; ++k) dst[m][k] = *(const LAS bf16x8*)(lds + PG8_SA(b, h) + aoff + m * 2048 + k * 1024); } while (0)
; #define PG8_LDB(dst, b, h) do { _Pragma("unroll") for (int n = 0; n < 2; ++n) _Pragma("unroll") for (int k = 0; k < 2; ++k) dst[n][k] = *(const LAS bf16x8*)(lds + PG8_SB(b, h) + boff + n * 2048 + k * 1024); } while (0)
; #define PG8_SCHED __builtin_amdgcn_sched_barrier(0)
; template <class Epi>
; DI void gemm_phase(LAS unsigned char* lds, int wid, int K, int lda, int ldb, bool bperm, const Sched3& S, const Epi& E) {
;     ...
;             PG8_LDB(B0, 0, 0); PG8_SCHED; PG8_LDA(At, 0, 0); PG8_STAGE(PG8_SA(1, 1), a1 + hA, voffA);
	s_add_i32 m0, s23, 0xc000
	ds_read_b128 v[164:167], v161
	ds_read_b128 v[168:171], v161 offset:1024
	ds_read_b128 v[172:175], v161 offset:2048
	ds_read_b128 v[176:179], v161 offset:3072
	ds_read_b128 v[180:183], v161 offset:4096
	ds_read_b128 v[184:187], v161 offset:5120
	ds_read_b128 v[188:191], v161 offset:6144
	ds_read_b128 v[192:195], v161 offset:7168
	global_load_lds_dwordx4 v132, s[28:29]

; #define PG8_MMA(ai, bj, At, Bt) do { __builtin_amdgcn_s_setprio(1); _Pragma("unroll") for (int m = 0; m < 4; ++m) _Pragma("unroll") for (int n = 0; n < 2; ++n) _Pragma("unroll") for (int k = 0; k < 2; ++k) \
;         acc[ai][bj][m][n] = __builtin_amdgcn_mfma_f32_16x16x32_bf16(Bt[n][k], At[m][k], acc[ai][bj][m][n], 0, 0, 0); __builtin_amdgcn_s_setprio(0); } while (0)
; #define PG8_WAIT_L(n) asm volatile("s_waitcnt lgkmcnt(" #n ")" ::: "memory")
; #define PG8_BAR __builtin_amdgcn_s_barrier()
; #define PG8_SCHED __builtin_amdgcn_sched_barrier(0)
; template <class Epi>
; DI void gemm_phase(LAS unsigned char* lds, int wid, int K, int lda, int ldb, bool bperm, const Sched3& S, const Epi& E) {
;     ...
;             PG8_WAIT_L(8); PG8_BAR; PG8_WAIT_L(0); PG8_MMA(0, 0, At, B0); PG8_BAR; PG8_SCHED;
	s_add_i32 m0, s23, 0xe000
	s_nop 0
	global_load_lds_dwordx4 v134, s[28:29]
	s_waitcnt lgkmcnt(8)
	s_barrier
	s_waitcnt lgkmcnt(0)
	s_setprio 1
	s_waitcnt lgkmcnt(0)
	v_mfma_f32_16x16x32_bf16 v[124:127], v[138:141], v[164:167], v[124:127]
	v_mfma_f32_16x16x32_bf16 v[120:123], v[146:149], v[164:167], v[120:123]
	v_mfma_f32_16x16x32_bf16 v[116:119], v[138:141], v[172:175], v[116:119]
	v_mfma_f32_16x16x32_bf16 v[104:107], v[146:149], v[172:175], v[104:107]
	v_mfma_f32_16x16x32_bf16 v[96:99], v[138:141], v[180:183], v[96:99]
	v_mfma_f32_16x16x32_bf16 v[88:91], v[146:149], v[180:183], v[88:91]
	v_mfma_f32_16x16x32_bf16 v[80:83], v[138:141], v[188:191], v[80:83]
	v_mfma_f32_16x16x32_bf16 v[72:75], v[146:149], v[188:191], v[72:75]
	v_mfma_f32_16x16x32_bf16 v[124:127], v[142:145], v[168:171], v[124:127]
	v_mfma_f32_16x16x32_bf16 v[120:123], v[150:153], v[168:171], v[120:123]
	v_mfma_f32_16x16x32_bf16 v[116:119], v[142:145], v[176:179], v[116:119]
	v_mfma_f32_16x16x32_bf16 v[104:107], v[150:153], v[176:179], v[104:107]
	v_mfma_f32_16x16x32_bf16 v[96:99], v[142:145], v[184:187], v[96:99]
	v_mfma_f32_16x16x32_bf16 v[88:91], v[150:153], v[184:187], v[88:91]
	v_mfma_f32_16x16x32_bf16 v[80:83], v[142:145], v[192:195], v[80:83]
	v_mfma_f32_16x16x32_bf16 v[72:75], v[150:153], v[192:195], v[72:75]
	s_setprio 0
	s_barrier
	s_add_i32 s58, s53, s43

; #define PG8_STAGE(bufoff, gbase, voff) do { _Pragma("unroll") for (int _i = 0; _i < 2; ++_i) \
;         __builtin_amdgcn_global_load_lds((const unsigned*)((const char*)(gbase) + (voff)[_i]), (LAS unsigned*)(lds + (bufoff) + ldsw + _i * 8192), 16, 0, 0); } while (0)
; #define PG8_LDB(dst, b, h) do { _Pragma("unroll") for (int n = 0; n < 2; ++n) _Pragma("unroll") for (int k = 0; k < 2; ++k) dst[n][k] = *(const LAS bf16x8*)(lds + PG8_SB(b, h) + boff + n * 2048 + k * 1024); } while (0)
; template <class Epi>
; DI void gemm_phase(LAS unsigned char* lds, int wid, int K, int lda, int ldb, bool bperm, const Sched3& S, const Epi& E) {
;     ...
;             PG8_LDB(B1, 0, 1); PG8_STAGE(PG8_SB(0, 0), b2, voffB);
	s_mov_b32 m0, s58
	ds_read_b128 v[196:199], v162
	ds_read_b128 v[200:203], v162 offset:1024
	ds_read_b128 v[204:207], v162 offset:2048
	ds_read_b128 v[208:211], v162 offset:3072
	global_load_lds_dwordx4 v130, s[30:31]

; #define PG8_STAGE(bufoff, gbase, voff) do { _Pragma("unroll") for (int _i = 0; _i < 2; ++_i) \
;         __builtin_amdgcn_global_load_lds((const unsigned*)((const char*)(gbase) + (voff)[_i]), (LAS unsigned*)(lds + (bufoff) + ldsw + _i * 8192), 16, 0, 0); } while (0)
; #define PG8_LDA(dst, b, h) do { _Pragma("unroll") for (int m = 0; m < 4; ++m) _Pragma("unroll") for (int k = 0; k < 2; ++k) dst[m][k] = *(const LAS bf16x8*)(lds + PG8_SA(b, h) + aoff + m * 2048 + k * 1024); } while (0)
; #define PG8_LDB(dst, b, h) do { _Pragma("unroll") for (int n = 0; n < 2; ++n) _Pragma("unroll") for (int k = 0; k < 2; ++k) dst[n][k] = *(const LAS bf16x8*)(lds + PG8_SB(b, h) + boff + n * 2048 + k * 1024); } while (0)
; #define PG8_MMA(ai, bj, At, Bt) do { __builtin_amdgcn_s_setprio(1); _Pragma("unroll") for (int m = 0; m < 4; ++m) _Pragma("unroll") for (int n = 0; n < 2; ++n) _Pragma("unroll") for (int k = 0; k < 2; ++k) \
;         acc[ai][bj][m][n] = __builtin_amdgcn_mfma_f32_16x16x32_bf16(Bt[n][k], At[m][k], acc[ai][bj][m][n], 0, 0, 0); __builtin_amdgcn_s_setprio(0); } while (0)
; #define PG8_WAIT_L(n) asm volatile("s_waitcnt lgkmcnt(" #n ")" ::: "memory")
; #define PG8_BAR __builtin_amdgcn_s_barrier()
; #define PG8_SCHED __builtin_amdgcn_sched_barrier(0)
; template <class Epi>
; DI void gemm_phase(LAS unsigned char* lds, int wid, int K, int lda, int ldb, bool bperm, const Sched3& S, const Epi& E) {
;     ...
;             PG8_LDB(B1, 0, 1); PG8_STAGE(PG8_SB(0, 0), b2, voffB);
;             PG8_BAR; PG8_WAIT_L(0); PG8_MMA(0, 1, At, B1); PG8_BAR;
;             PG8_LDA(At, 0, 1); PG8_STAGE(PG8_SA(0, 0), a2, voffA);
;             PG8_BAR; PG8_WAIT_L(0); if (full) PG8_MMA(1, 0, At, B0); PG8_BAR; PG8_SCHED;
	s_add_i32 m0, s58, 0x2000
	s_nop 0
	global_load_lds_dwordx4 v128, s[30:31]
	s_barrier
	s_waitcnt lgkmcnt(0)
	s_setprio 1
	s_waitcnt lgkmcnt(0)
	v_mfma_f32_16x16x32_bf16 v[112:115], v[196:199], v[164:167], v[112:115]
	v_mfma_f32_16x16x32_bf16 v[108:111], v[204:207], v[164:167], v[108:111]
	v_mfma_f32_16x16x32_bf16 v[100:103], v[196:199], v[172:175], v[100:103]
	v_mfma_f32_16x16x32_bf16 v[92:95], v[204:207], v[172:175], v[92:95]
	v_mfma_f32_16x16x32_bf16 v[84:87], v[196:199], v[180:183], v[84:87]
	v_mfma_f32_16x16x32_bf16 v[76:79], v[204:207], v[180:183], v[76:79]
	v_mfma_f32_16x16x32_bf16 v[68:71], v[196:199], v[188:191], v[68:71]
	v_mfma_f32_16x16x32_bf16 v[64:67], v[204:207], v[188:191], v[64:67]
	v_mfma_f32_16x16x32_bf16 v[112:115], v[200:203], v[168:171], v[112:115]
	v_mfma_f32_16x16x32_bf16 v[108:111], v[208:211], v[168:171], v[108:111]
	v_mfma_f32_16x16x32_bf16 v[100:103], v[200:203], v[176:179], v[100:103]
	v_mfma_f32_16x16x32_bf16 v[92:95], v[208:211], v[176:179], v[92:95]
	v_mfma_f32_16x16x32_bf16 v[84:87], v[200:203], v[184:187], v[84:87]
	v_mfma_f32_16x16x32_bf16 v[76:79], v[208:211], v[184:187], v[76:79]
	v_mfma_f32_16x16x32_bf16 v[68:71], v[200:203], v[192:195], v[68:71]
	v_mfma_f32_16x16x32_bf16 v[64:67], v[208:211], v[192:195], v[64:67]
	s_setprio 0
	s_mov_b32 m0, s23
	s_mov_b64 s[100:101], s[36:37]
	s_barrier
	ds_read_b128 v[164:167], v161 offset:16384
	ds_read_b128 v[168:171], v161 offset:17408
	ds_read_b128 v[172:175], v161 offset:18432
	ds_read_b128 v[176:179], v161 offset:19456
	ds_read_b128 v[180:183], v161 offset:20480
	ds_read_b128 v[184:187], v161 offset:21504
	ds_read_b128 v[188:191], v161 offset:22528
	ds_read_b128 v[192:195], v161 offset:23552
	global_load_lds_dwordx4 v130, s[36:37]
	s_mov_b64 s[100:101], s[36:37]
	s_mov_b32 m0, s46
	s_nop 0
	global_load_lds_dwordx4 v128, s[36:37]
	s_barrier
	s_waitcnt lgkmcnt(0)
	s_setprio 1
	s_waitcnt lgkmcnt(0)
	v_mfma_f32_16x16x32_bf16 v[60:63], v[138:141], v[164:167], v[60:63]
	v_mfma_f32_16x16x32_bf16 v[56:59], v[146:149], v[164:167], v[56:59]
	v_mfma_f32_16x16x32_bf16 v[48:51], v[138:141], v[172:175], v[48:51]
	v_mfma_f32_16x16x32_bf16 v[40:43], v[146:149], v[172:175], v[40:43]
	v_mfma_f32_16x16x32_bf16 v[32:35], v[138:141], v[180:183], v[32:35]
	v_mfma_f32_16x16x32_bf16 v[24:27], v[146:149], v[180:183], v[24:27]
	v_mfma_f32_16x16x32_bf16 v[16:19], v[138:141], v[188:191], v[16:19]
	v_mfma_f32_16x16x32_bf16 v[8:11], v[146:149], v[188:191], v[8:11]
	v_mfma_f32_16x16x32_bf16 v[60:63], v[142:145], v[168:171], v[60:63]
	v_mfma_f32_16x16x32_bf16 v[56:59], v[150:153], v[168:171], v[56:59]
	v_mfma_f32_16x16x32_bf16 v[48:51], v[142:145], v[176:179], v[48:51]
	v_mfma_f32_16x16x32_bf16 v[40:43], v[150:153], v[176:179], v[40:43]
	v_mfma_f32_16x16x32_bf16 v[32:35], v[142:145], v[184:187], v[32:35]
	v_mfma_f32_16x16x32_bf16 v[24:27], v[150:153], v[184:187], v[24:27]
	v_mfma_f32_16x16x32_bf16 v[16:19], v[142:145], v[192:195], v[16:19]
	v_mfma_f32_16x16x32_bf16 v[8:11], v[150:153], v[192:195], v[8:11]
	s_setprio 0
	s_barrier
	s_add_u32 s58, s30, 0x80000
	s_addc_u32 s59, s31, 0
	s_add_i32 s60, s54, s43

; #define PG8_STAGE(bufoff, gbase, voff) do { _Pragma("unroll") for (int _i = 0; _i < 2; ++_i) \
;         __builtin_amdgcn_global_load_lds((const unsigned*)((const char*)(gbase) + (voff)[_i]), (LAS unsigned*)(lds + (bufoff) + ldsw + _i * 8192), 16, 0, 0); } while (0)
; template <class Epi>
; DI void gemm_phase(LAS unsigned char* lds, int wid, int K, int lda, int ldb, bool bperm, const Sched3& S, const Epi& E) {
;     ...
;             PG8_STAGE(PG8_SB(0, 1), b2 + hstepB, voffB);
	s_mov_b32 m0, s60
	s_nop 0
	global_load_lds_dwordx4 v130, s[58:59]

; #define PG8_STAGE(bufoff, gbase, voff) do { _Pragma("unroll") for (int _i = 0; _i < 2; ++_i) \
;         __builtin_amdgcn_global_load_lds((const unsigned*)((const char*)(gbase) + (voff)[_i]), (LAS unsigned*)(lds + (bufoff) + ldsw + _i * 8192), 16, 0, 0); } while (0)
; #define PG8_LDA(dst, b, h) do { _Pragma("unroll") for (int m = 0; m < 4; ++m) _Pragma("unroll") for (int k = 0; k < 2; ++k) dst[m][k] = *(const LAS bf16x8*)(lds + PG8_SA(b, h) + aoff + m * 2048 + k * 1024); } while (0)
; #define PG8_LDB(dst, b, h) do { _Pragma("unroll") for (int n = 0; n < 2; ++n) _Pragma("unroll") for (int k = 0; k < 2; ++k) dst[n][k] = *(const LAS bf16x8*)(lds + PG8_SB(b, h) + boff + n * 2048 + k * 1024); } while (0)
; #define PG8_MMA(ai, bj, At, Bt) do { __builtin_amdgcn_s_setprio(1); _Pragma("unroll") for (int m = 0; m < 4; ++m) _Pragma("unroll") for (int n = 0; n < 2; ++n) _Pragma("unroll") for (int k = 0; k < 2; ++k) \
;         acc[ai][bj][m][n] = __builtin_amdgcn_mfma_f32_16x16x32_bf16(Bt[n][k], At[m][k], acc[ai][bj][m][n], 0, 0, 0); __builtin_amdgcn_s_setprio(0); } while (0)
; #define PG8_WAIT_V(n) asm volatile("s_waitcnt vmcnt(" #n ")" ::: "memory")
; #define PG8_BAR __builtin_amdgcn_s_barrier()
; #define PG8_SCHED __builtin_amdgcn_sched_barrier(0)
; template <class Epi>
; DI void gemm_phase(LAS unsigned char* lds, int wid, int K, int lda, int ldb, bool bperm, const Sched3& S, const Epi& E) {
;     ...
;             PG8_STAGE(PG8_SB(0, 1), b2 + hstepB, voffB);
;             PG8_WAIT_V(6); PG8_BAR; if (full) PG8_MMA(1, 1, At, B1); PG8_BAR;
;             PG8_LDB(B0, 1, 0); PG8_SCHED; PG8_LDA(At, 1, 0); PG8_STAGE(PG8_SA(0, 1), a2 + h2, voffA);
	s_add_i32 m0, s60, 0x2000
	s_nop 0
	global_load_lds_dwordx4 v128, s[58:59]
	s_waitcnt vmcnt(6)
	s_barrier
	s_setprio 1
	v_mfma_f32_16x16x32_bf16 v[52:55], v[196:199], v[164:167], v[52:55]
	v_mfma_f32_16x16x32_bf16 v[44:47], v[204:207], v[164:167], v[44:47]
	v_mfma_f32_16x16x32_bf16 v[36:39], v[196:199], v[172:175], v[36:39]
	v_mfma_f32_16x16x32_bf16 v[28:31], v[204:207], v[172:175], v[28:31]
	v_mfma_f32_16x16x32_bf16 v[20:23], v[196:199], v[180:183], v[20:23]
	v_mfma_f32_16x16x32_bf16 v[12:15], v[204:207], v[180:183], v[12:15]
	v_mfma_f32_16x16x32_bf16 v[4:7], v[196:199], v[188:191], v[4:7]
	v_mfma_f32_16x16x32_bf16 v[0:3], v[204:207], v[188:191], v[0:3]
	v_mfma_f32_16x16x32_bf16 v[52:55], v[200:203], v[168:171], v[52:55]
	v_mfma_f32_16x16x32_bf16 v[44:47], v[208:211], v[168:171], v[44:47]
	v_mfma_f32_16x16x32_bf16 v[36:39], v[200:203], v[176:179], v[36:39]
	v_mfma_f32_16x16x32_bf16 v[28:31], v[208:211], v[176:179], v[28:31]
	v_mfma_f32_16x16x32_bf16 v[20:23], v[200:203], v[184:187], v[20:23]
	v_mfma_f32_16x16x32_bf16 v[12:15], v[208:211], v[184:187], v[12:15]
	v_mfma_f32_16x16x32_bf16 v[4:7], v[200:203], v[192:195], v[4:7]
	v_mfma_f32_16x16x32_bf16 v[0:3], v[208:211], v[192:195], v[0:3]
	s_setprio 0
	s_add_i32 s58, 0, 0x18000
	v_add_u32_e32 v150, s58, v158
	s_barrier
	ds_read_b128 v[138:141], v150
	ds_read_b128 v[142:145], v150 offset:1024
	ds_read_b128 v[146:149], v150 offset:2048
	ds_read_b128 v[150:153], v150 offset:3072
	s_add_u32 s36, s36, 0x80000
	s_addc_u32 s37, s37, 0
	s_mov_b32 m0, s47

; #define PG8_STAGE(bufoff, gbase, voff) do { _Pragma("unroll") for (int _i = 0; _i < 2; ++_i) \
;         __builtin_amdgcn_global_load_lds((const unsigned*)((const char*)(gbase) + (voff)[_i]), (LAS unsigned*)(lds + (bufoff) + ldsw + _i * 8192), 16, 0, 0); } while (0)
; #define PG8_LDA(dst, b, h) do { _Pragma("unroll") for (int m = 0; m < 4; ++m) _Pragma("unroll") for (int k = 0; k < 2; ++k) dst[m][k] = *(const LAS bf16x8*)(lds + PG8_SA(b, h) + aoff + m * 2048 + k * 1024); } while (0)
; #define PG8_LDB(dst, b, h) do { _Pragma("unroll") for (int n = 0; n < 2; ++n) _Pragma("unroll") for (int k = 0; k < 2; ++k) dst[n][k] = *(const LAS bf16x8*)(lds + PG8_SB(b, h) + boff + n * 2048 + k * 1024); } while (0)
; #define PG8_SCHED __builtin_amdgcn_sched_barrier(0)
; template <class Epi>
; DI void gemm_phase(LAS unsigned char* lds, int wid, int K, int lda, int ldb, bool bperm, const Sched3& S, const Epi& E) {
;     ...
;             PG8_LDB(B0, 1, 0); PG8_SCHED; PG8_LDA(At, 1, 0); PG8_STAGE(PG8_SA(0, 1), a2 + h2, voffA);
	ds_read_b128 v[164:167], v161 offset:32768
	ds_read_b128 v[168:171], v161 offset:33792
	ds_read_b128 v[172:175], v161 offset:34816
	ds_read_b128 v[176:179], v161 offset:35840
	ds_read_b128 v[180:183], v161 offset:36864
	ds_read_b128 v[184:187], v161 offset:37888
	ds_read_b128 v[188:191], v161 offset:38912
	ds_read_b128 v[192:195], v161 offset:39936
	global_load_lds_dwordx4 v130, s[36:37]

; #define PG8_MMA(ai, bj, At, Bt) do { __builtin_amdgcn_s_setprio(1); _Pragma("unroll") for (int m = 0; m < 4; ++m) _Pragma("unroll") for (int n = 0; n < 2; ++n) _Pragma("unroll") for (int k = 0; k < 2; ++k) \
;         acc[ai][bj][m][n] = __builtin_amdgcn_mfma_f32_16x16x32_bf16(Bt[n][k], At[m][k], acc[ai][bj][m][n], 0, 0, 0); __builtin_amdgcn_s_setprio(0); } while (0)
; #define PG8_WAIT_L(n) asm volatile("s_waitcnt lgkmcnt(" #n ")" ::: "memory")
; #define PG8_BAR __builtin_amdgcn_s_barrier()
; #define PG8_SCHED __builtin_amdgcn_sched_barrier(0)
; template <class Epi>
; DI void gemm_phase(LAS unsigned char* lds, int wid, int K, int lda, int ldb, bool bperm, const Sched3& S, const Epi& E) {
;     ...
;             PG8_WAIT_L(8); PG8_BAR; PG8_WAIT_L(0); PG8_MMA(0, 0, At, B0); PG8_BAR; PG8_SCHED;
	s_mov_b32 m0, s48
	s_nop 0
	global_load_lds_dwordx4 v128, s[36:37]
	s_waitcnt lgkmcnt(8)
	s_barrier
	s_waitcnt lgkmcnt(0)
	s_setprio 1
	s_waitcnt lgkmcnt(0)
	v_mfma_f32_16x16x32_bf16 v[124:127], v[138:141], v[164:167], v[124:127]
	v_mfma_f32_16x16x32_bf16 v[120:123], v[146:149], v[164:167], v[120:123]
	v_mfma_f32_16x16x32_bf16 v[116:119], v[138:141], v[172:175], v[116:119]
	v_mfma_f32_16x16x32_bf16 v[104:107], v[146:149], v[172:175], v[104:107]
	v_mfma_f32_16x16x32_bf16 v[96:99], v[138:141], v[180:183], v[96:99]
	v_mfma_f32_16x16x32_bf16 v[88:91], v[146:149], v[180:183], v[88:91]
	v_mfma_f32_16x16x32_bf16 v[80:83], v[138:141], v[188:191], v[80:83]
	v_mfma_f32_16x16x32_bf16 v[72:75], v[146:149], v[188:191], v[72:75]
	v_mfma_f32_16x16x32_bf16 v[124:127], v[142:145], v[168:171], v[124:127]
	v_mfma_f32_16x16x32_bf16 v[120:123], v[150:153], v[168:171], v[120:123]
	v_mfma_f32_16x16x32_bf16 v[116:119], v[142:145], v[176:179], v[116:119]
	v_mfma_f32_16x16x32_bf16 v[104:107], v[150:153], v[176:179], v[104:107]
	v_mfma_f32_16x16x32_bf16 v[96:99], v[142:145], v[184:187], v[96:99]
	v_mfma_f32_16x16x32_bf16 v[88:91], v[150:153], v[184:187], v[88:91]
	v_mfma_f32_16x16x32_bf16 v[80:83], v[142:145], v[192:195], v[80:83]
	v_mfma_f32_16x16x32_bf16 v[72:75], v[150:153], v[192:195], v[72:75]
	s_setprio 0
	s_barrier
	s_add_i32 s36, 0, 0x1c000
	s_add_i32 s37, s58, s43
	v_add_u32_e32 v154, s36, v158

; #define PG8_STAGE(bufoff, gbase, voff) do { _Pragma("unroll") for (int _i = 0; _i < 2; ++_i) \
;         __builtin_amdgcn_global_load_lds((const unsigned*)((const char*)(gbase) + (voff)[_i]), (LAS unsigned*)(lds + (bufoff) + ldsw + _i * 8192), 16, 0, 0); } while (0)
; #define PG8_LDB(dst, b, h) do { _Pragma("unroll") for (int n = 0; n < 2; ++n) _Pragma("unroll") for (int k = 0; k < 2; ++k) dst[n][k] = *(const LAS bf16x8*)(lds + PG8_SB(b, h) + boff + n * 2048 + k * 1024); } while (0)
; template <class Epi>
; DI void gemm_phase(LAS unsigned char* lds, int wid, int K, int lda, int ldb, bool bperm, const Sched3& S, const Epi& E) {
;     ...
;             PG8_LDB(B1, 1, 1); PG8_STAGE(PG8_SB(1, 0), b3, voffB);
	s_sub_i32 m0, s37, 0x80
	ds_read_b128 v[196:199], v154
	ds_read_b128 v[200:203], v154 offset:1024
	ds_read_b128 v[204:207], v154 offset:2048
	ds_read_b128 v[208:211], v154 offset:3072
	global_load_lds_dwordx4 v130, s[30:31] offset:128

; #define PG8_STAGE(bufoff, gbase, voff) do { _Pragma("unroll") for (int _i = 0; _i < 2; ++_i) \
;         __builtin_amdgcn_global_load_lds((const unsigned*)((const char*)(gbase) + (voff)[_i]), (LAS unsigned*)(lds + (bufoff) + ldsw + _i * 8192), 16, 0, 0); } while (0)
; #define PG8_LDB(dst, b, h) do { _Pragma("unroll") for (int n = 0; n < 2; ++n) _Pragma("unroll") for (int k = 0; k < 2; ++k) dst[n][k] = *(const LAS bf16x8*)(lds + PG8_SB(b, h) + boff + n * 2048 + k * 1024); } while (0)
; #define PG8_MMA(ai, bj, At, Bt) do { __builtin_amdgcn_s_setprio(1); _Pragma("unroll") for (int m = 0; m < 4; ++m) _Pragma("unroll") for (int n = 0; n < 2; ++n) _Pragma("unroll") for (int k = 0; k < 2; ++k) \
;         acc[ai][bj][m][n] = __builtin_amdgcn_mfma_f32_16x16x32_bf16(Bt[n][k], At[m][k], acc[ai][bj][m][n], 0, 0, 0); __builtin_amdgcn_s_setprio(0); } while (0)
; #define PG8_WAIT_L(n) asm volatile("s_waitcnt lgkmcnt(" #n ")" ::: "memory")
; #define PG8_BAR __builtin_amdgcn_s_barrier()
; template <class Epi>
; DI void gemm_phase(LAS unsigned char* lds, int wid, int K, int lda, int ldb, bool bperm, const Sched3& S, const Epi& E) {
;     ...
;             PG8_LDB(B1, 1, 1); PG8_STAGE(PG8_SB(1, 0), b3, voffB);
;             PG8_BAR; PG8_WAIT_L(0); PG8_MMA(0, 1, At, B1); PG8_BAR;
	s_add_i32 m0, s37, 0x1f80
	s_nop 0
	global_load_lds_dwordx4 v128, s[30:31] offset:128
	s_barrier
	s_waitcnt lgkmcnt(0)
	s_setprio 1
	s_waitcnt lgkmcnt(0)
	v_mfma_f32_16x16x32_bf16 v[112:115], v[196:199], v[164:167], v[112:115]
	v_mfma_f32_16x16x32_bf16 v[108:111], v[204:207], v[164:167], v[108:111]
	v_mfma_f32_16x16x32_bf16 v[100:103], v[196:199], v[172:175], v[100:103]
	v_mfma_f32_16x16x32_bf16 v[92:95], v[204:207], v[172:175], v[92:95]
	v_mfma_f32_16x16x32_bf16 v[84:87], v[196:199], v[180:183], v[84:87]
	v_mfma_f32_16x16x32_bf16 v[76:79], v[204:207], v[180:183], v[76:79]
	v_mfma_f32_16x16x32_bf16 v[68:71], v[196:199], v[188:191], v[68:71]
	v_mfma_f32_16x16x32_bf16 v[64:67], v[204:207], v[188:191], v[64:67]
	v_mfma_f32_16x16x32_bf16 v[112:115], v[200:203], v[168:171], v[112:115]
	v_mfma_f32_16x16x32_bf16 v[108:111], v[208:211], v[168:171], v[108:111]
	v_mfma_f32_16x16x32_bf16 v[100:103], v[200:203], v[176:179], v[100:103]
	v_mfma_f32_16x16x32_bf16 v[92:95], v[208:211], v[176:179], v[92:95]
	v_mfma_f32_16x16x32_bf16 v[84:87], v[200:203], v[184:187], v[84:87]
	v_mfma_f32_16x16x32_bf16 v[76:79], v[208:211], v[184:187], v[76:79]
	v_mfma_f32_16x16x32_bf16 v[68:71], v[200:203], v[192:195], v[68:71]
	v_mfma_f32_16x16x32_bf16 v[64:67], v[208:211], v[192:195], v[64:67]
	s_setprio 0
	s_sub_i32 m0, s49, 0x80

; #define PG8_STAGE(bufoff, gbase, voff) do { _Pragma("unroll") for (int _i = 0; _i < 2; ++_i) \
;         __builtin_amdgcn_global_load_lds((const unsigned*)((const char*)(gbase) + (voff)[_i]), (LAS unsigned*)(lds + (bufoff) + ldsw + _i * 8192), 16, 0, 0); } while (0)
; #define PG8_LDA(dst, b, h) do { _Pragma("unroll") for (int m = 0; m < 4; ++m) _Pragma("unroll") for (int k = 0; k < 2; ++k) dst[m][k] = *(const LAS bf16x8*)(lds + PG8_SA(b, h) + aoff + m * 2048 + k * 1024); } while (0)
; template <class Epi>
; DI void gemm_phase(LAS unsigned char* lds, int wid, int K, int lda, int ldb, bool bperm, const Sched3& S, const Epi& E) {
;     ...
;             PG8_LDA(At, 1, 1); PG8_STAGE(PG8_SA(1, 0), a3, voffA);
	s_barrier
	ds_read_b128 v[164:167], v161 offset:49152
	ds_read_b128 v[168:171], v161 offset:50176
	ds_read_b128 v[172:175], v161 offset:51200
	ds_read_b128 v[176:179], v161 offset:52224
	ds_read_b128 v[180:183], v161 offset:53248
	ds_read_b128 v[184:187], v161 offset:54272
	ds_read_b128 v[188:191], v161 offset:55296
	ds_read_b128 v[192:195], v161 offset:56320
	global_load_lds_dwordx4 v130, s[100:101] offset:128

; #define PG8_STAGE(bufoff, gbase, voff) do { _Pragma("unroll") for (int _i = 0; _i < 2; ++_i) \
;         __builtin_amdgcn_global_load_lds((const unsigned*)((const char*)(gbase) + (voff)[_i]), (LAS unsigned*)(lds + (bufoff) + ldsw + _i * 8192), 16, 0, 0); } while (0)
; #define PG8_LDA(dst, b, h) do { _Pragma("unroll") for (int m = 0; m < 4; ++m) _Pragma("unroll") for (int k = 0; k < 2; ++k) dst[m][k] = *(const LAS bf16x8*)(lds + PG8_SA(b, h) + aoff + m * 2048 + k * 1024); } while (0)
; #define PG8_MMA(ai, bj, At, Bt) do { __builtin_amdgcn_s_setprio(1); _Pragma("unroll") for (int m = 0; m < 4; ++m) _Pragma("unroll") for (int n = 0; n < 2; ++n) _Pragma("unroll") for (int k = 0; k < 2; ++k) \
;         acc[ai][bj][m][n] = __builtin_amdgcn_mfma_f32_16x16x32_bf16(Bt[n][k], At[m][k], acc[ai][bj][m][n], 0, 0, 0); __builtin_amdgcn_s_setprio(0); } while (0)
; #define PG8_WAIT_L(n) asm volatile("s_waitcnt lgkmcnt(" #n ")" ::: "memory")
; #define PG8_BAR __builtin_amdgcn_s_barrier()
; #define PG8_SCHED __builtin_amdgcn_sched_barrier(0)
; template <class Epi>
; DI void gemm_phase(LAS unsigned char* lds, int wid, int K, int lda, int ldb, bool bperm, const Sched3& S, const Epi& E) {
;     ...
;             PG8_LDA(At, 1, 1); PG8_STAGE(PG8_SA(1, 0), a3, voffA);
;             PG8_BAR; PG8_WAIT_L(0); if (full) PG8_MMA(1, 0, At, B0); PG8_BAR; PG8_SCHED;
	s_sub_i32 m0, s50, 0x80
	s_nop 0
	global_load_lds_dwordx4 v128, s[100:101] offset:128
	s_barrier
	s_waitcnt lgkmcnt(0)
	s_setprio 1
	s_waitcnt lgkmcnt(0)
	v_mfma_f32_16x16x32_bf16 v[60:63], v[138:141], v[164:167], v[60:63]
	v_mfma_f32_16x16x32_bf16 v[56:59], v[146:149], v[164:167], v[56:59]
	v_mfma_f32_16x16x32_bf16 v[48:51], v[138:141], v[172:175], v[48:51]
	v_mfma_f32_16x16x32_bf16 v[40:43], v[146:149], v[172:175], v[40:43]
	v_mfma_f32_16x16x32_bf16 v[32:35], v[138:141], v[180:183], v[32:35]
	v_mfma_f32_16x16x32_bf16 v[24:27], v[146:149], v[180:183], v[24:27]
	v_mfma_f32_16x16x32_bf16 v[16:19], v[138:141], v[188:191], v[16:19]
	v_mfma_f32_16x16x32_bf16 v[8:11], v[146:149], v[188:191], v[8:11]
	v_mfma_f32_16x16x32_bf16 v[60:63], v[142:145], v[168:171], v[60:63]
	v_mfma_f32_16x16x32_bf16 v[56:59], v[150:153], v[168:171], v[56:59]
	v_mfma_f32_16x16x32_bf16 v[48:51], v[142:145], v[176:179], v[48:51]
	v_mfma_f32_16x16x32_bf16 v[40:43], v[150:153], v[176:179], v[40:43]
	v_mfma_f32_16x16x32_bf16 v[32:35], v[142:145], v[184:187], v[32:35]
	v_mfma_f32_16x16x32_bf16 v[24:27], v[150:153], v[184:187], v[24:27]
	v_mfma_f32_16x16x32_bf16 v[16:19], v[142:145], v[192:195], v[16:19]
	v_mfma_f32_16x16x32_bf16 v[8:11], v[150:153], v[192:195], v[8:11]
	s_setprio 0
	s_barrier
	s_add_u32 s30, s30, 0x80080
	s_addc_u32 s31, s31, 0
	s_add_i32 s36, s36, s43

; #define PG8_STAGE(bufoff, gbase, voff) do { _Pragma("unroll") for (int _i = 0; _i < 2; ++_i) \
;         __builtin_amdgcn_global_load_lds((const unsigned*)((const char*)(gbase) + (voff)[_i]), (LAS unsigned*)(lds + (bufoff) + ldsw + _i * 8192), 16, 0, 0); } while (0)
; template <class Epi>
; DI void gemm_phase(LAS unsigned char* lds, int wid, int K, int lda, int ldb, bool bperm, const Sched3& S, const Epi& E) {
;     ...
;             PG8_STAGE(PG8_SB(1, 1), b3 + hstepB, voffB);
	s_mov_b32 m0, s36
	s_nop 0
	global_load_lds_dwordx4 v130, s[30:31]

; DI u32x2 pk4(f32x4 v) { u32x2 r; r.x = pk2(v[0], v[1]); r.y = pk2(v[2], v[3]); return r; }
; DI float silu_f(float x) { return x * __builtin_amdgcn_rcpf(1.f + __builtin_amdgcn_exp2f(-1.4426950409f * x)); }
; #define PG8_STAGE(bufoff, gbase, voff) do { _Pragma("unroll") for (int _i = 0; _i < 2; ++_i) \
;         __builtin_amdgcn_global_load_lds((const unsigned*)((const char*)(gbase) + (voff)[_i]), (LAS unsigned*)(lds + (bufoff) + ldsw + _i * 8192), 16, 0, 0); } while (0)
; #define PG8_MMA(ai, bj, At, Bt) do { __builtin_amdgcn_s_setprio(1); _Pragma("unroll") for (int m = 0; m < 4; ++m) _Pragma("unroll") for (int n = 0; n < 2; ++n) _Pragma("unroll") for (int k = 0; k < 2; ++k) \
;         acc[ai][bj][m][n] = __builtin_amdgcn_mfma_f32_16x16x32_bf16(Bt[n][k], At[m][k], acc[ai][bj][m][n], 0, 0, 0); __builtin_amdgcn_s_setprio(0); } while (0)
; #define PG8_WAIT_V(n) asm volatile("s_waitcnt vmcnt(" #n ")" ::: "memory")
; #define PG8_BAR __builtin_amdgcn_s_barrier()
; #define ROWS8 _Pragma("unroll") for (int ai = 0; ai < 2; ++ai) _Pragma("unroll") for (int m = 0; m < 4; ++m) if (ai == 0 || !hf)
; #define LOAD_ROW_RS(rsv, ssqp, invn) float rsv[2][4]; ROWS8_ALL rsv[ai][m] = (ssqp)[row0 + ai * HALF + m * 16]; ROWS8_ALL rsv[ai][m] = rstd_of(rsv[ai][m], invn)
; template <class Epi>
; DI void gemm_phase(LAS unsigned char* lds, int wid, int K, int lda, int ldb, bool bperm, const Sched3& S, const Epi& E) {
;     ...
;             PG8_STAGE(PG8_SB(1, 1), b3 + hstepB, voffB);
;             PG8_WAIT_V(6); PG8_BAR; if (full) PG8_MMA(1, 1, At, B1); PG8_BAR;
;         }
;     DI void operator()(const Acc& acc, const Unit& u, int wr, int wc, int fr, int fq) const {
;     ...
;             LOAD_ROW_RS(rsv, SSQ(PH == 5 ? 2 : 6), 1.f / 2048.f);
;             const int ac0 = u.pn * 128 + wc * 32 + 8 * fq;
;             ROWS8 { const int r = row0 + ai * HALF + m * 16; const float rs = rsv[ai][m];
;                 u32x4 w;
; #pragma unroll
;                 for (int bj = 0; bj < 2; ++bj) { const f32x4 g = acc[ai][bj][m][0] * rs, uu = acc[ai][bj][m][1] * rs;
;                     f32x4 a; a[0] = silu_f(g[0]) * uu[0]; a[1] = silu_f(g[1]) * uu[1]; a[2] = silu_f(g[2]) * uu[2]; a[3] = silu_f(g[3]) * uu[3];
;                     const u32x2 h = pk4(a); if (bj == 0) { w.x = h.x; w.y = h.y; } else { w.z = h.x; w.w = h.y; } }
;                 *(u32x4*)(WSB(OFF_ACT) + (size_t)r * DFF + ac0) = w;
	s_add_i32 m0, s36, 0x2000
	s_nop 0
	global_load_lds_dwordx4 v128, s[30:31]
	s_waitcnt vmcnt(6)
	s_barrier
	s_setprio 1
	v_mfma_f32_16x16x32_bf16 v[52:55], v[196:199], v[164:167], v[52:55]
	v_mfma_f32_16x16x32_bf16 v[44:47], v[204:207], v[164:167], v[44:47]
	v_mfma_f32_16x16x32_bf16 v[36:39], v[196:199], v[172:175], v[36:39]
	v_mfma_f32_16x16x32_bf16 v[28:31], v[204:207], v[172:175], v[28:31]
	v_mfma_f32_16x16x32_bf16 v[20:23], v[196:199], v[180:183], v[20:23]
	v_mfma_f32_16x16x32_bf16 v[12:15], v[204:207], v[180:183], v[12:15]
	v_mfma_f32_16x16x32_bf16 v[4:7], v[196:199], v[188:191], v[4:7]
	v_mfma_f32_16x16x32_bf16 v[0:3], v[204:207], v[188:191], v[0:3]
	v_mfma_f32_16x16x32_bf16 v[52:55], v[200:203], v[168:171], v[52:55]
	v_mfma_f32_16x16x32_bf16 v[44:47], v[208:211], v[168:171], v[44:47]
	v_mfma_f32_16x16x32_bf16 v[36:39], v[200:203], v[176:179], v[36:39]
	v_mfma_f32_16x16x32_bf16 v[28:31], v[208:211], v[176:179], v[28:31]
	v_mfma_f32_16x16x32_bf16 v[20:23], v[200:203], v[184:187], v[20:23]
	v_mfma_f32_16x16x32_bf16 v[12:15], v[208:211], v[184:187], v[12:15]
	v_mfma_f32_16x16x32_bf16 v[4:7], v[200:203], v[192:195], v[4:7]
	v_mfma_f32_16x16x32_bf16 v[0:3], v[208:211], v[192:195], v[0:3]
	s_setprio 0
	s_add_i32 s57, s57, 2
	s_add_u32 s28, s28, 0x100
	s_addc_u32 s29, s29, 0
	s_add_u32 s15, s15, 0x100
	s_addc_u32 s17, s17, 0
	s_cmp_gt_u32 s57, 29
	s_cbranch_scc0 .Lkrot_2_head
.Lkrot_2_exit:
	s_barrier
.Lpeel_2_exit:
	v_lshl_add_u32 v142, s22, 8, v155
	v_or_b32_e32 v156, 16, v142
	v_ashrrev_i32_e32 v157, 31, v156
	v_or_b32_e32 v152, 32, v142
	v_or_b32_e32 v150, 48, v142
	v_lshl_add_u64 v[138:139], v[156:157], 2, s[10:11]
	v_ashrrev_i32_e32 v153, 31, v152
	v_ashrrev_i32_e32 v151, 31, v150
	v_ashrrev_i32_e32 v143, 31, v142
	v_lshl_add_u64 v[140:141], v[152:153], 2, s[10:11]
	v_lshl_add_u64 v[144:145], v[150:151], 2, s[10:11]
	v_lshl_add_u64 v[146:147], v[142:143], 2, s[10:11]
	v_add_u32_e32 v148, 0x80, v142
	v_add_u32_e32 v146, 0x90, v142
	v_add_u32_e32 v144, 0xa0, v142
	v_add_u32_e32 v138, 0xb0, v142
	v_ashrrev_i32_e32 v149, 31, v148
	v_ashrrev_i32_e32 v147, 31, v146
	v_ashrrev_i32_e32 v145, 31, v144
	v_ashrrev_i32_e32 v139, 31, v138
	v_lshl_add_u64 v[140:141], v[148:149], 2, s[10:11]
	v_lshl_add_u64 v[164:165], v[146:147], 2, s[10:11]
	v_lshl_add_u64 v[166:167], v[144:145], 2, s[10:11]
	v_lshl_add_u64 v[168:169], v[138:139], 2, s[10:11]
	v_lshl_add_u32 v164, s56, 7, v159
	v_mov_b64_e32 v[140:141], s[12:13]
	v_ashrrev_i32_e32 v165, 31, v164
	v_mad_i64_i32 v[166:167], s[24:25], v142, s55, v[140:141]
	v_lshlrev_b64 v[142:143], 1, v[164:165]
	v_lshl_add_u64 v[164:165], v[166:167], 0, v[142:143]
	s_and_b64 vcc, exec, s[2:3]
	s_mov_b32 s56, s14
	s_mov_b32 s22, s16
	s_mov_b64 s[30:31], s[18:19]
	s_mov_b64 s[28:29], s[20:21]
	v_mov_b32_e32 v151, v221
	v_mov_b32_e32 v153, v222
	v_mov_b32_e32 v154, v223
	v_mov_b32_e32 v157, v220
	v_mov_b32_e32 v139, v224
	v_mov_b32_e32 v145, v225
	v_mov_b32_e32 v147, v226
	v_mov_b32_e32 v149, v227
	v_fmamk_f32 v151, v151, 0x3a000000, v163
	v_rsq_f32_e32 v168, v151
	v_fmamk_f32 v153, v153, 0x3a000000, v163
	v_fmamk_f32 v157, v157, 0x3a000000, v163
	v_rsq_f32_e32 v166, v157
	v_rsq_f32_e32 v170, v153
	v_pk_mul_f32 v[118:119], v[118:119], v[168:169] op_sel_hi:[1,0]
	v_pk_mul_f32 v[116:117], v[116:117], v[168:169] op_sel_hi:[1,0]
	v_pk_mul_f32 v[126:127], v[126:127], v[166:167] op_sel_hi:[1,0]
	v_pk_mul_f32 v[124:125], v[124:125], v[166:167] op_sel_hi:[1,0]
	v_pk_mul_f32 v[114:115], v[114:115], v[166:167] op_sel_hi:[1,0]
	v_pk_mul_f32 v[112:113], v[112:113], v[166:167] op_sel_hi:[1,0]
	v_pk_mul_f32 v[122:123], v[122:123], v[166:167] op_sel_hi:[1,0]
	v_pk_mul_f32 v[120:121], v[120:121], v[166:167] op_sel_hi:[1,0]
	v_pk_mul_f32 v[110:111], v[110:111], v[166:167] op_sel_hi:[1,0]
	v_pk_mul_f32 v[108:109], v[108:109], v[166:167] op_sel_hi:[1,0]
	v_mul_f32_e32 v151, 0xbfb8aa3b, v124
	v_mul_f32_e32 v153, 0xbfb8aa3b, v125
	v_mul_f32_e32 v157, 0xbfb8aa3b, v126
	v_mul_f32_e32 v166, 0xbfb8aa3b, v127
	v_mul_f32_e32 v167, 0xbfb8aa3b, v112
	v_mul_f32_e32 v169, 0xbfb8aa3b, v113
	v_mul_f32_e32 v171, 0xbfb8aa3b, v114
	v_mul_f32_e32 v172, 0xbfb8aa3b, v115
	v_exp_f32_e32 v151, v151
	v_exp_f32_e32 v153, v153
	v_exp_f32_e32 v157, v157
	v_exp_f32_e32 v166, v166
	v_exp_f32_e32 v167, v167
	v_exp_f32_e32 v169, v169
	v_exp_f32_e32 v171, v171
	v_exp_f32_e32 v172, v172
	v_mul_f32_e32 v173, 0xbfb8aa3b, v116
	v_exp_f32_e32 v178, v173
	v_add_f32_e32 v151, 1.0, v151
	v_add_f32_e32 v153, 1.0, v153
	v_add_f32_e32 v157, 1.0, v157
	v_add_f32_e32 v173, 1.0, v166
	v_add_f32_e32 v174, 1.0, v167
	v_add_f32_e32 v169, 1.0, v169
	v_add_f32_e32 v171, 1.0, v171
	v_add_f32_e32 v177, 1.0, v172
	v_rcp_f32_e32 v166, v151
	v_rcp_f32_e32 v167, v153
	v_rcp_f32_e32 v172, v157
	v_rcp_f32_e32 v173, v173
	v_rcp_f32_e32 v174, v174
	v_rcp_f32_e32 v175, v169
	v_rcp_f32_e32 v176, v171
	v_rcp_f32_e32 v177, v177
	v_pk_mul_f32 v[124:125], v[124:125], v[166:167]
	v_pk_mul_f32 v[126:127], v[126:127], v[172:173]
	v_pk_mul_f32 v[112:113], v[112:113], v[174:175]
	v_pk_mul_f32 v[114:115], v[114:115], v[176:177]
	v_pk_mul_f32 v[120:121], v[120:121], v[124:125]
	v_pk_mul_f32 v[122:123], v[122:123], v[126:127]
	v_pk_mul_f32 v[112:113], v[108:109], v[112:113]
	v_pk_mul_f32 v[114:115], v[110:111], v[114:115]
	v_cvt_pk_bf16_f32 v108, v120, v121
	v_cvt_pk_bf16_f32 v109, v122, v123
	v_cvt_pk_bf16_f32 v110, v112, v113
	v_cvt_pk_bf16_f32 v111, v114, v115
	global_store_dwordx4 v[164:165], v[108:111], off
	v_pk_mul_f32 v[104:105], v[104:105], v[168:169] op_sel_hi:[1,0]
	v_pk_mul_f32 v[106:107], v[106:107], v[168:169] op_sel_hi:[1,0]
	v_mul_f32_e32 v108, 0xbfb8aa3b, v117
	v_exp_f32_e32 v109, v108
; DI u32x2 pk4(f32x4 v) { u32x2 r; r.x = pk2(v[0], v[1]); r.y = pk2(v[2], v[3]); return r; }
; DI float silu_f(float x) { return x * __builtin_amdgcn_rcpf(1.f + __builtin_amdgcn_exp2f(-1.4426950409f * x)); }
; #define ROWS8 _Pragma("unroll") for (int ai = 0; ai < 2; ++ai) _Pragma("unroll") for (int m = 0; m < 4; ++m) if (ai == 0 || !hf)
;     DI void operator()(const Acc& acc, const Unit& u, int wr, int wc, int fr, int fq) const {
;     ...
;             ROWS8 { const int r = row0 + ai * HALF + m * 16; const float rs = rsv[ai][m];
;                 u32x4 w;
; #pragma unroll
;                 for (int bj = 0; bj < 2; ++bj) { const f32x4 g = acc[ai][bj][m][0] * rs, uu = acc[ai][bj][m][1] * rs;
;                     f32x4 a; a[0] = silu_f(g[0]) * uu[0]; a[1] = silu_f(g[1]) * uu[1]; a[2] = silu_f(g[2]) * uu[2]; a[3] = silu_f(g[3]) * uu[3];
;                     const u32x2 h = pk4(a); if (bj == 0) { w.x = h.x; w.y = h.y; } else { w.z = h.x; w.w = h.y; } }
;                 *(u32x4*)(WSB(OFF_ACT) + (size_t)r * DFF + ac0) = w;
	v_mul_f32_e32 v110, 0xbfb8aa3b, v118
	v_mul_f32_e32 v111, 0xbfb8aa3b, v119
	v_exp_f32_e32 v110, v110
	v_exp_f32_e32 v111, v111
	v_add_f32_e32 v108, 1.0, v178
	v_add_f32_e32 v109, 1.0, v109
	v_rcp_f32_e32 v108, v108
	v_rcp_f32_e32 v109, v109
	v_add_f32_e32 v110, 1.0, v110
	v_add_f32_e32 v111, 1.0, v111
	v_rcp_f32_e32 v110, v110
	v_rcp_f32_e32 v111, v111
	v_pk_mul_f32 v[108:109], v[116:117], v[108:109]
	v_pk_mul_f32 v[100:101], v[100:101], v[168:169] op_sel_hi:[1,0]
	v_pk_mul_f32 v[104:105], v[104:105], v[108:109]
	v_pk_mul_f32 v[108:109], v[118:119], v[110:111]
	v_cvt_pk_bf16_f32 v104, v104, v105
	v_pk_mul_f32 v[106:107], v[106:107], v[108:109]
	v_pk_mul_f32 v[102:103], v[102:103], v[168:169] op_sel_hi:[1,0]
	v_cvt_pk_bf16_f32 v105, v106, v107
	v_mul_f32_e32 v106, 0xbfb8aa3b, v100
	v_mul_f32_e32 v107, 0xbfb8aa3b, v101
	v_exp_f32_e32 v106, v106
	v_exp_f32_e32 v107, v107
	v_mul_f32_e32 v108, 0xbfb8aa3b, v102
	v_mul_f32_e32 v109, 0xbfb8aa3b, v103
	v_exp_f32_e32 v108, v108
	v_exp_f32_e32 v109, v109
	v_add_f32_e32 v106, 1.0, v106
	v_add_f32_e32 v107, 1.0, v107
	v_rcp_f32_e32 v106, v106
	v_rcp_f32_e32 v107, v107
	v_add_f32_e32 v108, 1.0, v108
	v_add_f32_e32 v109, 1.0, v109
	v_rcp_f32_e32 v108, v108
	v_rcp_f32_e32 v109, v109
	v_pk_mul_f32 v[92:93], v[92:93], v[168:169] op_sel_hi:[1,0]
	v_pk_mul_f32 v[100:101], v[100:101], v[106:107]
	v_pk_mul_f32 v[94:95], v[94:95], v[168:169] op_sel_hi:[1,0]
	v_pk_mul_f32 v[92:93], v[92:93], v[100:101]
	v_pk_mul_f32 v[100:101], v[102:103], v[108:109]
	v_cvt_pk_bf16_f32 v106, v92, v93
	v_pk_mul_f32 v[94:95], v[94:95], v[100:101]
	v_mad_i64_i32 v[92:93], s[24:25], v156, s55, v[140:141]
	v_cvt_pk_bf16_f32 v107, v94, v95
	v_lshl_add_u64 v[92:93], v[92:93], 0, v[142:143]
	global_store_dwordx4 v[92:93], v[104:107], off
	v_pk_mul_f32 v[92:93], v[98:99], v[170:171] op_sel_hi:[1,0]
	v_pk_mul_f32 v[94:95], v[96:97], v[170:171] op_sel_hi:[1,0]
	v_mul_f32_e32 v98, 0xbfb8aa3b, v92
	v_mul_f32_e32 v96, 0xbfb8aa3b, v94
	v_mul_f32_e32 v97, 0xbfb8aa3b, v95
	v_mul_f32_e32 v99, 0xbfb8aa3b, v93
	v_exp_f32_e32 v96, v96
	v_exp_f32_e32 v97, v97
	v_exp_f32_e32 v98, v98
	v_exp_f32_e32 v99, v99
	v_add_f32_e32 v96, 1.0, v96
	v_add_f32_e32 v97, 1.0, v97
	v_add_f32_e32 v98, 1.0, v98
	v_add_f32_e32 v99, 1.0, v99
	v_rcp_f32_e32 v96, v96
	v_rcp_f32_e32 v97, v97
	v_rcp_f32_e32 v98, v98
	v_rcp_f32_e32 v99, v99
	v_pk_mul_f32 v[90:91], v[90:91], v[170:171] op_sel_hi:[1,0]
	v_pk_mul_f32 v[88:89], v[88:89], v[170:171] op_sel_hi:[1,0]
	v_pk_mul_f32 v[94:95], v[94:95], v[96:97]
	v_pk_mul_f32 v[92:93], v[92:93], v[98:99]
	v_pk_mul_f32 v[88:89], v[88:89], v[94:95]
	v_pk_mul_f32 v[90:91], v[90:91], v[92:93]
	v_pk_mul_f32 v[84:85], v[84:85], v[170:171] op_sel_hi:[1,0]
	v_cvt_pk_bf16_f32 v88, v88, v89
	v_cvt_pk_bf16_f32 v89, v90, v91
	v_pk_mul_f32 v[86:87], v[86:87], v[170:171] op_sel_hi:[1,0]
	v_mul_f32_e32 v90, 0xbfb8aa3b, v84
	v_mul_f32_e32 v91, 0xbfb8aa3b, v85
	v_exp_f32_e32 v90, v90
	v_exp_f32_e32 v91, v91
	v_mul_f32_e32 v92, 0xbfb8aa3b, v86
	v_mul_f32_e32 v93, 0xbfb8aa3b, v87
	v_exp_f32_e32 v92, v92
	v_exp_f32_e32 v93, v93
	v_add_f32_e32 v90, 1.0, v90
	v_add_f32_e32 v91, 1.0, v91
	v_rcp_f32_e32 v90, v90
	v_rcp_f32_e32 v91, v91
	v_add_f32_e32 v92, 1.0, v92
	v_add_f32_e32 v93, 1.0, v93
	v_rcp_f32_e32 v92, v92
	v_rcp_f32_e32 v93, v93
	v_fmamk_f32 v154, v154, 0x3a000000, v163
	v_rsq_f32_e32 v154, v154
	v_pk_mul_f32 v[76:77], v[76:77], v[170:171] op_sel_hi:[1,0]
	v_pk_mul_f32 v[84:85], v[84:85], v[90:91]
	v_pk_mul_f32 v[78:79], v[78:79], v[170:171] op_sel_hi:[1,0]
	v_pk_mul_f32 v[76:77], v[76:77], v[84:85]
	v_pk_mul_f32 v[84:85], v[86:87], v[92:93]
	v_cvt_pk_bf16_f32 v90, v76, v77
	v_pk_mul_f32 v[78:79], v[78:79], v[84:85]
	v_mad_i64_i32 v[76:77], s[24:25], v152, s55, v[140:141]
	v_cvt_pk_bf16_f32 v91, v78, v79
	v_lshl_add_u64 v[76:77], v[76:77], 0, v[142:143]
	global_store_dwordx4 v[76:77], v[88:91], off
	v_pk_mul_f32 v[76:77], v[82:83], v[154:155] op_sel_hi:[1,0]
	v_pk_mul_f32 v[78:79], v[80:81], v[154:155] op_sel_hi:[1,0]
	v_mul_f32_e32 v82, 0xbfb8aa3b, v76
	v_mul_f32_e32 v80, 0xbfb8aa3b, v78
	v_mul_f32_e32 v81, 0xbfb8aa3b, v79
	v_mul_f32_e32 v83, 0xbfb8aa3b, v77
	v_exp_f32_e32 v80, v80
	v_exp_f32_e32 v81, v81
	v_exp_f32_e32 v82, v82
	v_exp_f32_e32 v83, v83
	v_add_f32_e32 v80, 1.0, v80
	v_add_f32_e32 v81, 1.0, v81
	v_add_f32_e32 v82, 1.0, v82
	v_add_f32_e32 v83, 1.0, v83
	v_rcp_f32_e32 v80, v80
	v_rcp_f32_e32 v81, v81
	v_rcp_f32_e32 v82, v82
	v_rcp_f32_e32 v83, v83
	v_pk_mul_f32 v[74:75], v[74:75], v[154:155] op_sel_hi:[1,0]
	v_pk_mul_f32 v[72:73], v[72:73], v[154:155] op_sel_hi:[1,0]
	v_pk_mul_f32 v[78:79], v[78:79], v[80:81]
	v_pk_mul_f32 v[76:77], v[76:77], v[82:83]
	v_pk_mul_f32 v[72:73], v[72:73], v[78:79]
	v_pk_mul_f32 v[74:75], v[74:75], v[76:77]
	v_pk_mul_f32 v[68:69], v[68:69], v[154:155] op_sel_hi:[1,0]
	v_cvt_pk_bf16_f32 v72, v72, v73
	v_cvt_pk_bf16_f32 v73, v74, v75
	v_pk_mul_f32 v[70:71], v[70:71], v[154:155] op_sel_hi:[1,0]
	v_mul_f32_e32 v74, 0xbfb8aa3b, v68
	v_mul_f32_e32 v75, 0xbfb8aa3b, v69
	v_exp_f32_e32 v74, v74
	v_exp_f32_e32 v75, v75
	v_mul_f32_e32 v76, 0xbfb8aa3b, v70
	v_mul_f32_e32 v77, 0xbfb8aa3b, v71
	v_exp_f32_e32 v76, v76
	v_exp_f32_e32 v77, v77
	v_add_f32_e32 v74, 1.0, v74
	v_add_f32_e32 v75, 1.0, v75
	v_rcp_f32_e32 v74, v74
	v_rcp_f32_e32 v75, v75
	v_add_f32_e32 v76, 1.0, v76
	v_add_f32_e32 v77, 1.0, v77
	v_rcp_f32_e32 v76, v76
	v_rcp_f32_e32 v77, v77
	v_pk_mul_f32 v[64:65], v[64:65], v[154:155] op_sel_hi:[1,0]
	v_pk_mul_f32 v[68:69], v[68:69], v[74:75]
	v_pk_mul_f32 v[66:67], v[66:67], v[154:155] op_sel_hi:[1,0]
	v_pk_mul_f32 v[64:65], v[64:65], v[68:69]
	v_pk_mul_f32 v[68:69], v[70:71], v[76:77]
	v_cvt_pk_bf16_f32 v74, v64, v65
; DI u32x2 pk4(f32x4 v) { u32x2 r; r.x = pk2(v[0], v[1]); r.y = pk2(v[2], v[3]); return r; }
; DI float silu_f(float x) { return x * __builtin_amdgcn_rcpf(1.f + __builtin_amdgcn_exp2f(-1.4426950409f * x)); }
; #define ROWS8 _Pragma("unroll") for (int ai = 0; ai < 2; ++ai) _Pragma("unroll") for (int m = 0; m < 4; ++m) if (ai == 0 || !hf)
;     DI void operator()(const Acc& acc, const Unit& u, int wr, int wc, int fr, int fq) const {
;     ...
;             ROWS8 { const int r = row0 + ai * HALF + m * 16; const float rs = rsv[ai][m];
;                 u32x4 w;
; #pragma unroll
;                 for (int bj = 0; bj < 2; ++bj) { const f32x4 g = acc[ai][bj][m][0] * rs, uu = acc[ai][bj][m][1] * rs;
;                     f32x4 a; a[0] = silu_f(g[0]) * uu[0]; a[1] = silu_f(g[1]) * uu[1]; a[2] = silu_f(g[2]) * uu[2]; a[3] = silu_f(g[3]) * uu[3];
;                     const u32x2 h = pk4(a); if (bj == 0) { w.x = h.x; w.y = h.y; } else { w.z = h.x; w.w = h.y; } }
;                 *(u32x4*)(WSB(OFF_ACT) + (size_t)r * DFF + ac0) = w;
	v_pk_mul_f32 v[66:67], v[66:67], v[68:69]
	v_mad_i64_i32 v[64:65], s[24:25], v150, s55, v[140:141]
	v_cvt_pk_bf16_f32 v75, v66, v67
	v_fmamk_f32 v66, v139, 0x3a000000, v163
	v_rsq_f32_e32 v68, v66
	v_lshl_add_u64 v[64:65], v[64:65], 0, v[142:143]
	global_store_dwordx4 v[64:65], v[72:75], off
	v_fmamk_f32 v65, v147, 0x3a000000, v163
	v_rsq_f32_e32 v66, v65
	v_fmamk_f32 v65, v145, 0x3a000000, v163
	v_pk_mul_f32 v[60:61], v[60:61], v[68:69] op_sel_hi:[1,0]
	v_rsq_f32_e32 v70, v65
	v_mul_f32_e32 v65, 0xbfb8aa3b, v60
	v_exp_f32_e32 v65, v65
	v_mul_f32_e32 v67, 0xbfb8aa3b, v61
	v_exp_f32_e32 v67, v67
	v_pk_mul_f32 v[62:63], v[62:63], v[68:69] op_sel_hi:[1,0]
	v_add_f32_e32 v65, 1.0, v65
	v_rcp_f32_e32 v72, v65
	v_add_f32_e32 v65, 1.0, v67
	v_mul_f32_e32 v67, 0xbfb8aa3b, v62
	v_pk_mul_f32 v[58:59], v[58:59], v[68:69] op_sel_hi:[1,0]
	v_exp_f32_e32 v67, v67
	v_mul_f32_e32 v69, 0xbfb8aa3b, v63
	v_exp_f32_e32 v69, v69
	v_rcp_f32_e32 v73, v65
	v_add_f32_e32 v65, 1.0, v67
	v_rcp_f32_e32 v74, v65
	v_add_f32_e32 v65, 1.0, v69
	v_rcp_f32_e32 v75, v65
	v_pk_mul_f32 v[56:57], v[56:57], v[68:69] op_sel_hi:[1,0]
	v_pk_mul_f32 v[60:61], v[60:61], v[72:73]
	v_pk_mul_f32 v[52:53], v[52:53], v[68:69] op_sel_hi:[1,0]
	v_pk_mul_f32 v[56:57], v[56:57], v[60:61]
	v_pk_mul_f32 v[60:61], v[62:63], v[74:75]
	v_cvt_pk_bf16_f32 v56, v56, v57
	v_pk_mul_f32 v[58:59], v[58:59], v[60:61]
	v_pk_mul_f32 v[54:55], v[54:55], v[68:69] op_sel_hi:[1,0]
	v_cvt_pk_bf16_f32 v57, v58, v59
	v_mul_f32_e32 v58, 0xbfb8aa3b, v52
	v_mul_f32_e32 v59, 0xbfb8aa3b, v53
	v_exp_f32_e32 v58, v58
	v_exp_f32_e32 v59, v59
	v_mul_f32_e32 v60, 0xbfb8aa3b, v54
	v_mul_f32_e32 v61, 0xbfb8aa3b, v55
	v_exp_f32_e32 v60, v60
	v_exp_f32_e32 v61, v61
	v_add_f32_e32 v58, 1.0, v58
	v_add_f32_e32 v59, 1.0, v59
	v_rcp_f32_e32 v58, v58
	v_rcp_f32_e32 v59, v59
	v_add_f32_e32 v60, 1.0, v60
	v_add_f32_e32 v61, 1.0, v61
	v_rcp_f32_e32 v60, v60
	v_rcp_f32_e32 v61, v61
	v_pk_mul_f32 v[44:45], v[44:45], v[68:69] op_sel_hi:[1,0]
	v_pk_mul_f32 v[52:53], v[52:53], v[58:59]
	v_pk_mul_f32 v[46:47], v[46:47], v[68:69] op_sel_hi:[1,0]
	v_pk_mul_f32 v[44:45], v[44:45], v[52:53]
	v_pk_mul_f32 v[52:53], v[54:55], v[60:61]
	v_cvt_pk_bf16_f32 v58, v44, v45
	v_pk_mul_f32 v[46:47], v[46:47], v[52:53]
	v_mad_i64_i32 v[44:45], s[24:25], v148, s55, v[140:141]
	v_cvt_pk_bf16_f32 v59, v46, v47
	v_lshl_add_u64 v[44:45], v[44:45], 0, v[142:143]
	global_store_dwordx4 v[44:45], v[56:59], off
	v_pk_mul_f32 v[44:45], v[50:51], v[70:71] op_sel_hi:[1,0]
	v_pk_mul_f32 v[46:47], v[48:49], v[70:71] op_sel_hi:[1,0]
	v_mul_f32_e32 v50, 0xbfb8aa3b, v44
	v_mul_f32_e32 v48, 0xbfb8aa3b, v46
	v_mul_f32_e32 v49, 0xbfb8aa3b, v47
	v_mul_f32_e32 v51, 0xbfb8aa3b, v45
	v_exp_f32_e32 v48, v48
	v_exp_f32_e32 v49, v49
	v_exp_f32_e32 v50, v50
	v_exp_f32_e32 v51, v51
	v_add_f32_e32 v48, 1.0, v48
	v_add_f32_e32 v49, 1.0, v49
	v_add_f32_e32 v50, 1.0, v50
	v_add_f32_e32 v51, 1.0, v51
	v_rcp_f32_e32 v48, v48
	v_rcp_f32_e32 v49, v49
	v_rcp_f32_e32 v50, v50
	v_rcp_f32_e32 v51, v51
	v_pk_mul_f32 v[42:43], v[42:43], v[70:71] op_sel_hi:[1,0]
	v_pk_mul_f32 v[40:41], v[40:41], v[70:71] op_sel_hi:[1,0]
	v_pk_mul_f32 v[46:47], v[46:47], v[48:49]
	v_pk_mul_f32 v[44:45], v[44:45], v[50:51]
	v_pk_mul_f32 v[40:41], v[40:41], v[46:47]
	v_pk_mul_f32 v[42:43], v[42:43], v[44:45]
	v_pk_mul_f32 v[36:37], v[36:37], v[70:71] op_sel_hi:[1,0]
	v_cvt_pk_bf16_f32 v40, v40, v41
	v_cvt_pk_bf16_f32 v41, v42, v43
	v_pk_mul_f32 v[38:39], v[38:39], v[70:71] op_sel_hi:[1,0]
	v_mul_f32_e32 v42, 0xbfb8aa3b, v36
	v_mul_f32_e32 v43, 0xbfb8aa3b, v37
	v_exp_f32_e32 v42, v42
	v_exp_f32_e32 v43, v43
	v_mul_f32_e32 v44, 0xbfb8aa3b, v38
	v_mul_f32_e32 v45, 0xbfb8aa3b, v39
	v_exp_f32_e32 v44, v44
	v_exp_f32_e32 v45, v45
	v_add_f32_e32 v42, 1.0, v42
	v_add_f32_e32 v43, 1.0, v43
	v_rcp_f32_e32 v42, v42
	v_rcp_f32_e32 v43, v43
	v_add_f32_e32 v44, 1.0, v44
	v_add_f32_e32 v45, 1.0, v45
	v_rcp_f32_e32 v44, v44
	v_rcp_f32_e32 v45, v45
	v_pk_mul_f32 v[28:29], v[28:29], v[70:71] op_sel_hi:[1,0]
	v_pk_mul_f32 v[36:37], v[36:37], v[42:43]
	v_pk_mul_f32 v[30:31], v[30:31], v[70:71] op_sel_hi:[1,0]
	v_pk_mul_f32 v[28:29], v[28:29], v[36:37]
	v_pk_mul_f32 v[36:37], v[38:39], v[44:45]
	v_cvt_pk_bf16_f32 v42, v28, v29
	v_pk_mul_f32 v[30:31], v[30:31], v[36:37]
; DI u32x2 pk4(f32x4 v) { u32x2 r; r.x = pk2(v[0], v[1]); r.y = pk2(v[2], v[3]); return r; }
; DI float silu_f(float x) { return x * __builtin_amdgcn_rcpf(1.f + __builtin_amdgcn_exp2f(-1.4426950409f * x)); }
; #define PG8_WAIT_V(n) asm volatile("s_waitcnt vmcnt(" #n ")" ::: "memory")
; #define PG8_BAR __builtin_amdgcn_s_barrier()
; #define ROWS8 _Pragma("unroll") for (int ai = 0; ai < 2; ++ai) _Pragma("unroll") for (int m = 0; m < 4; ++m) if (ai == 0 || !hf)
; template <class Epi>
; DI void gemm_phase(LAS unsigned char* lds, int wid, int K, int lda, int ldb, bool bperm, const Sched3& S, const Epi& E) {
;     ...
;         if (!has_next) break;
; #pragma unroll
;         for (int a = 0; a < 2; ++a)
; #pragma unroll
;             for (int b = 0; b < 2; ++b)
; #pragma unroll
;                 for (int m = 0; m < 4; ++m)
; #pragma unroll
;                     for (int n = 0; n < 2; ++n) acc[a][b][m][n] = (f32x4){0.f, 0.f, 0.f, 0.f};
;         cur = nxt; cA = nA; cB = nB; hA = nhA; ++ui;
;     }
;     PG8_WAIT_V(0);
;     if (wr == 0) PG8_BAR;
;     DI void operator()(const Acc& acc, const Unit& u, int wr, int wc, int fr, int fq) const {
;     ...
;             ROWS8 { const int r = row0 + ai * HALF + m * 16; const float rs = rsv[ai][m];
;                 u32x4 w;
; #pragma unroll
;                 for (int bj = 0; bj < 2; ++bj) { const f32x4 g = acc[ai][bj][m][0] * rs, uu = acc[ai][bj][m][1] * rs;
;                     f32x4 a; a[0] = silu_f(g[0]) * uu[0]; a[1] = silu_f(g[1]) * uu[1]; a[2] = silu_f(g[2]) * uu[2]; a[3] = silu_f(g[3]) * uu[3];
;                     const u32x2 h = pk4(a); if (bj == 0) { w.x = h.x; w.y = h.y; } else { w.z = h.x; w.w = h.y; } }
;                 *(u32x4*)(WSB(OFF_ACT) + (size_t)r * DFF + ac0) = w;
	v_mad_i64_i32 v[28:29], s[24:25], v146, s55, v[140:141]
	v_cvt_pk_bf16_f32 v43, v30, v31
	v_lshl_add_u64 v[28:29], v[28:29], 0, v[142:143]
	global_store_dwordx4 v[28:29], v[40:43], off
	v_pk_mul_f32 v[28:29], v[34:35], v[66:67] op_sel_hi:[1,0]
	v_pk_mul_f32 v[30:31], v[32:33], v[66:67] op_sel_hi:[1,0]
	v_mul_f32_e32 v34, 0xbfb8aa3b, v28
	v_mul_f32_e32 v32, 0xbfb8aa3b, v30
	v_mul_f32_e32 v33, 0xbfb8aa3b, v31
	v_mul_f32_e32 v35, 0xbfb8aa3b, v29
	v_exp_f32_e32 v32, v32
	v_exp_f32_e32 v33, v33
	v_exp_f32_e32 v34, v34
	v_exp_f32_e32 v35, v35
	v_add_f32_e32 v32, 1.0, v32
	v_add_f32_e32 v33, 1.0, v33
	v_add_f32_e32 v34, 1.0, v34
	v_add_f32_e32 v35, 1.0, v35
	v_rcp_f32_e32 v32, v32
	v_rcp_f32_e32 v33, v33
	v_rcp_f32_e32 v34, v34
	v_rcp_f32_e32 v35, v35
	v_pk_mul_f32 v[26:27], v[26:27], v[66:67] op_sel_hi:[1,0]
	v_pk_mul_f32 v[24:25], v[24:25], v[66:67] op_sel_hi:[1,0]
	v_pk_mul_f32 v[30:31], v[30:31], v[32:33]
	v_pk_mul_f32 v[28:29], v[28:29], v[34:35]
	v_pk_mul_f32 v[24:25], v[24:25], v[30:31]
	v_pk_mul_f32 v[26:27], v[26:27], v[28:29]
	v_pk_mul_f32 v[20:21], v[20:21], v[66:67] op_sel_hi:[1,0]
	v_cvt_pk_bf16_f32 v24, v24, v25
	v_cvt_pk_bf16_f32 v25, v26, v27
	v_pk_mul_f32 v[22:23], v[22:23], v[66:67] op_sel_hi:[1,0]
	v_mul_f32_e32 v26, 0xbfb8aa3b, v20
	v_mul_f32_e32 v27, 0xbfb8aa3b, v21
	v_exp_f32_e32 v26, v26
	v_exp_f32_e32 v27, v27
	v_mul_f32_e32 v28, 0xbfb8aa3b, v22
	v_mul_f32_e32 v29, 0xbfb8aa3b, v23
	v_exp_f32_e32 v28, v28
	v_exp_f32_e32 v29, v29
	v_add_f32_e32 v26, 1.0, v26
	v_add_f32_e32 v27, 1.0, v27
	v_rcp_f32_e32 v26, v26
	v_rcp_f32_e32 v27, v27
	v_add_f32_e32 v28, 1.0, v28
	v_add_f32_e32 v29, 1.0, v29
	v_rcp_f32_e32 v28, v28
	v_rcp_f32_e32 v29, v29
	v_fmamk_f32 v64, v149, 0x3a000000, v163
	v_rsq_f32_e32 v64, v64
	v_pk_mul_f32 v[12:13], v[12:13], v[66:67] op_sel_hi:[1,0]
	v_pk_mul_f32 v[20:21], v[20:21], v[26:27]
	v_pk_mul_f32 v[14:15], v[14:15], v[66:67] op_sel_hi:[1,0]
	v_pk_mul_f32 v[12:13], v[12:13], v[20:21]
	v_pk_mul_f32 v[20:21], v[22:23], v[28:29]
	v_cvt_pk_bf16_f32 v26, v12, v13
	v_pk_mul_f32 v[14:15], v[14:15], v[20:21]
	v_mad_i64_i32 v[12:13], s[24:25], v144, s55, v[140:141]
	v_cvt_pk_bf16_f32 v27, v14, v15
	v_lshl_add_u64 v[12:13], v[12:13], 0, v[142:143]
	global_store_dwordx4 v[12:13], v[24:27], off
	v_pk_mul_f32 v[12:13], v[18:19], v[64:65] op_sel_hi:[1,0]
	v_pk_mul_f32 v[14:15], v[16:17], v[64:65] op_sel_hi:[1,0]
	v_mul_f32_e32 v18, 0xbfb8aa3b, v12
	v_mul_f32_e32 v16, 0xbfb8aa3b, v14
	v_mul_f32_e32 v17, 0xbfb8aa3b, v15
	v_mul_f32_e32 v19, 0xbfb8aa3b, v13
	v_exp_f32_e32 v16, v16
	v_exp_f32_e32 v17, v17
	v_exp_f32_e32 v18, v18
	v_exp_f32_e32 v19, v19
	v_add_f32_e32 v16, 1.0, v16
	v_add_f32_e32 v17, 1.0, v17
	v_add_f32_e32 v18, 1.0, v18
	v_add_f32_e32 v19, 1.0, v19
	v_rcp_f32_e32 v16, v16
	v_rcp_f32_e32 v17, v17
	v_rcp_f32_e32 v18, v18
	v_rcp_f32_e32 v19, v19
	v_pk_mul_f32 v[10:11], v[10:11], v[64:65] op_sel_hi:[1,0]
	v_pk_mul_f32 v[8:9], v[8:9], v[64:65] op_sel_hi:[1,0]
	v_pk_mul_f32 v[14:15], v[14:15], v[16:17]
	v_pk_mul_f32 v[12:13], v[12:13], v[18:19]
	v_pk_mul_f32 v[8:9], v[8:9], v[14:15]
	v_pk_mul_f32 v[10:11], v[10:11], v[12:13]
	v_pk_mul_f32 v[4:5], v[4:5], v[64:65] op_sel_hi:[1,0]
	v_cvt_pk_bf16_f32 v8, v8, v9
	v_cvt_pk_bf16_f32 v9, v10, v11
	v_pk_mul_f32 v[6:7], v[6:7], v[64:65] op_sel_hi:[1,0]
	v_mul_f32_e32 v10, 0xbfb8aa3b, v4
	v_mul_f32_e32 v11, 0xbfb8aa3b, v5
	v_exp_f32_e32 v10, v10
	v_exp_f32_e32 v11, v11
	v_mul_f32_e32 v12, 0xbfb8aa3b, v6
	v_mul_f32_e32 v13, 0xbfb8aa3b, v7
	v_exp_f32_e32 v12, v12
	v_exp_f32_e32 v13, v13
	v_add_f32_e32 v10, 1.0, v10
	v_add_f32_e32 v11, 1.0, v11
	v_rcp_f32_e32 v10, v10
	v_rcp_f32_e32 v11, v11
	v_add_f32_e32 v12, 1.0, v12
	v_add_f32_e32 v13, 1.0, v13
	v_rcp_f32_e32 v12, v12
	v_rcp_f32_e32 v13, v13
	v_pk_mul_f32 v[0:1], v[0:1], v[64:65] op_sel_hi:[1,0]
	v_pk_mul_f32 v[4:5], v[4:5], v[10:11]
	v_pk_mul_f32 v[2:3], v[2:3], v[64:65] op_sel_hi:[1,0]
	v_pk_mul_f32 v[0:1], v[0:1], v[4:5]
	v_pk_mul_f32 v[4:5], v[6:7], v[12:13]
	v_cvt_pk_bf16_f32 v10, v0, v1
	v_pk_mul_f32 v[2:3], v[2:3], v[4:5]
	v_mad_i64_i32 v[0:1], s[24:25], v138, s55, v[140:141]
	v_cvt_pk_bf16_f32 v11, v2, v3
	v_lshl_add_u64 v[0:1], v[0:1], 0, v[142:143]
	global_store_dwordx4 v[0:1], v[8:11], off
	s_cbranch_vccz .LBB0_702
	s_waitcnt vmcnt(0)
	s_cmpk_gt_u32 s88, 0xff
	s_cbranch_scc1 .LBB0_709
	s_barrier

; #define PG8_STAGE(bufoff, gbase, voff) do { _Pragma("unroll") for (int _i = 0; _i < 2; ++_i) \
;         __builtin_amdgcn_global_load_lds((const unsigned*)((const char*)(gbase) + (voff)[_i]), (LAS unsigned*)(lds + (bufoff) + ldsw + _i * 8192), 16, 0, 0); } while (0)
; #define PG8_LDA(dst, b, h) do { _Pragma("unroll") for (int m = 0; m < 4; ++m) _Pragma("unroll") for (int k = 0; k < 2; ++k) dst[m][k] = *(const LAS bf16x8*)(lds + PG8_SA(b, h) + aoff + m * 2048 + k * 1024); } while (0)
; #define PG8_LDB(dst, b, h) do { _Pragma("unroll") for (int n = 0; n < 2; ++n) _Pragma("unroll") for (int k = 0; k < 2; ++k) dst[n][k] = *(const LAS bf16x8*)(lds + PG8_SB(b, h) + boff + n * 2048 + k * 1024); } while (0)
; #define PG8_SCHED __builtin_amdgcn_sched_barrier(0)
; template <class Epi>
; DI void gemm_phase(LAS unsigned char* lds, int wid, int K, int lda, int ldb, bool bperm, const Sched3& S, const Epi& E) {
;     ...
;         const bool has_next = S.next(ui + 1, nxt);
;         const char* nA = has_next ? nxt.A : cA; const char* nB = has_next ? nxt.B : cB; const size_t nhA = has_next ? (nxt.half ? (size_t)0 : hstepA) : hA; const bool full = (cur.half == 0);
;         for (int t = 0; t < nt; t += 2) {
;             const bool last = (t == nt - 2);
;             const char* a1 = cA + (size_t)(t + 1) * kstep;
;             const char* a2 = last ? nA : cA + (size_t)(t + 2) * kstep; const char* b2 = last ? nB : cB + (size_t)(t + 2) * kstep;
;             const char* a3 = a2 + kstep; const char* b3 = b2 + kstep; const size_t h2 = last ? nhA : hA;
;             PG8_LDB(B0, 0, 0); PG8_SCHED; PG8_LDA(At, 0, 0); PG8_STAGE(PG8_SA(1, 1), a1 + hA, voffA);
.LBB0_784:
	s_add_u32 s60, s28, 0x100
	s_nop 0
	s_addc_u32 s61, s29, 0
	s_mov_b32 s62, -2
	s_waitcnt lgkmcnt(0)
	ds_read_b128 v[128:131], v185
	ds_read_b128 v[132:135], v185 offset:1024
	ds_read_b128 v[136:139], v185 offset:2048
	ds_read_b128 v[140:143], v185 offset:3072
	s_add_u32 s28, s26, 0x100
	s_addc_u32 s29, s27, 0
	s_cmpk_eq_i32 s62, 0x54
	s_cselect_b32 s37, s23, s29
	s_cselect_b32 s36, s22, s28
	s_cselect_b32 s31, s25, s61
	s_cselect_b32 s30, s24, s60

; #define PG8_STAGE(bufoff, gbase, voff) do { _Pragma("unroll") for (int _i = 0; _i < 2; ++_i) \
;         __builtin_amdgcn_global_load_lds((const unsigned*)((const char*)(gbase) + (voff)[_i]), (LAS unsigned*)(lds + (bufoff) + ldsw + _i * 8192), 16, 0, 0); } while (0)
; #define PG8_LDA(dst, b, h) do { _Pragma("unroll") for (int m = 0; m < 4; ++m) _Pragma("unroll") for (int k = 0; k < 2; ++k) dst[m][k] = *(const LAS bf16x8*)(lds + PG8_SA(b, h) + aoff + m * 2048 + k * 1024); } while (0)
; #define PG8_LDB(dst, b, h) do { _Pragma("unroll") for (int n = 0; n < 2; ++n) _Pragma("unroll") for (int k = 0; k < 2; ++k) dst[n][k] = *(const LAS bf16x8*)(lds + PG8_SB(b, h) + boff + n * 2048 + k * 1024); } while (0)
; #define PG8_SCHED __builtin_amdgcn_sched_barrier(0)
; template <class Epi>
; DI void gemm_phase(LAS unsigned char* lds, int wid, int K, int lda, int ldb, bool bperm, const Sched3& S, const Epi& E) {
;     ...
;             PG8_LDB(B0, 0, 0); PG8_SCHED; PG8_LDA(At, 0, 0); PG8_STAGE(PG8_SA(1, 1), a1 + hA, voffA);
	s_add_i32 m0, s44, 0xc000
	ds_read_b128 v[144:147], v186
	ds_read_b128 v[148:151], v186 offset:1024
	ds_read_b128 v[162:165], v186 offset:2048
	ds_read_b128 v[166:169], v186 offset:3072
	ds_read_b128 v[170:173], v186 offset:4096
	ds_read_b128 v[174:177], v186 offset:5120
	ds_read_b128 v[188:191], v186 offset:6144
	ds_read_b128 v[192:195], v186 offset:7168
	global_load_lds_dwordx4 v156, s[26:27]

; #define PG8_MMA(ai, bj, At, Bt) do { __builtin_amdgcn_s_setprio(1); _Pragma("unroll") for (int m = 0; m < 4; ++m) _Pragma("unroll") for (int n = 0; n < 2; ++n) _Pragma("unroll") for (int k = 0; k < 2; ++k) \
;         acc[ai][bj][m][n] = __builtin_amdgcn_mfma_f32_16x16x32_bf16(Bt[n][k], At[m][k], acc[ai][bj][m][n], 0, 0, 0); __builtin_amdgcn_s_setprio(0); } while (0)
; #define PG8_WAIT_L(n) asm volatile("s_waitcnt lgkmcnt(" #n ")" ::: "memory")
; #define PG8_BAR __builtin_amdgcn_s_barrier()
; #define PG8_SCHED __builtin_amdgcn_sched_barrier(0)
; template <class Epi>
; DI void gemm_phase(LAS unsigned char* lds, int wid, int K, int lda, int ldb, bool bperm, const Sched3& S, const Epi& E) {
;     ...
;             PG8_WAIT_L(8); PG8_BAR; PG8_WAIT_L(0); PG8_MMA(0, 0, At, B0); PG8_BAR; PG8_SCHED;
	s_add_i32 m0, s44, 0xe000
	s_nop 0
	global_load_lds_dwordx4 v158, s[26:27]
	s_waitcnt lgkmcnt(8)
	s_barrier
	s_waitcnt lgkmcnt(0)
	s_setprio 1
	s_waitcnt lgkmcnt(0)
	v_mfma_f32_16x16x32_bf16 v[124:127], v[128:131], v[144:147], 0
	v_mfma_f32_16x16x32_bf16 v[120:123], v[136:139], v[144:147], 0
	v_mfma_f32_16x16x32_bf16 v[108:111], v[128:131], v[162:165], 0
	v_mfma_f32_16x16x32_bf16 v[104:107], v[136:139], v[162:165], 0
	v_mfma_f32_16x16x32_bf16 v[92:95], v[128:131], v[170:173], 0
	v_mfma_f32_16x16x32_bf16 v[88:91], v[136:139], v[170:173], 0
	v_mfma_f32_16x16x32_bf16 v[76:79], v[128:131], v[188:191], 0
	v_mfma_f32_16x16x32_bf16 v[72:75], v[136:139], v[188:191], 0
	v_mfma_f32_16x16x32_bf16 v[124:127], v[132:135], v[148:151], v[124:127]
	v_mfma_f32_16x16x32_bf16 v[120:123], v[140:143], v[148:151], v[120:123]
	v_mfma_f32_16x16x32_bf16 v[108:111], v[132:135], v[166:169], v[108:111]
	v_mfma_f32_16x16x32_bf16 v[104:107], v[140:143], v[166:169], v[104:107]
	v_mfma_f32_16x16x32_bf16 v[92:95], v[132:135], v[174:177], v[92:95]
	v_mfma_f32_16x16x32_bf16 v[88:91], v[140:143], v[174:177], v[88:91]
	v_mfma_f32_16x16x32_bf16 v[76:79], v[132:135], v[192:195], v[76:79]
	v_mfma_f32_16x16x32_bf16 v[72:75], v[140:143], v[192:195], v[72:75]
	s_setprio 0
	s_barrier
	s_add_i32 s26, s53, s43

; #define PG8_STAGE(bufoff, gbase, voff) do { _Pragma("unroll") for (int _i = 0; _i < 2; ++_i) \
;         __builtin_amdgcn_global_load_lds((const unsigned*)((const char*)(gbase) + (voff)[_i]), (LAS unsigned*)(lds + (bufoff) + ldsw + _i * 8192), 16, 0, 0); } while (0)
; #define PG8_LDB(dst, b, h) do { _Pragma("unroll") for (int n = 0; n < 2; ++n) _Pragma("unroll") for (int k = 0; k < 2; ++k) dst[n][k] = *(const LAS bf16x8*)(lds + PG8_SB(b, h) + boff + n * 2048 + k * 1024); } while (0)
; template <class Epi>
; DI void gemm_phase(LAS unsigned char* lds, int wid, int K, int lda, int ldb, bool bperm, const Sched3& S, const Epi& E) {
;     ...
;             PG8_LDB(B1, 0, 1); PG8_STAGE(PG8_SB(0, 0), b2, voffB);
	s_mov_b32 m0, s26
	ds_read_b128 v[196:199], v187
	ds_read_b128 v[200:203], v187 offset:1024
	ds_read_b128 v[204:207], v187 offset:2048
	ds_read_b128 v[208:211], v187 offset:3072
	global_load_lds_dwordx4 v152, s[30:31]

; #define PG8_STAGE(bufoff, gbase, voff) do { _Pragma("unroll") for (int _i = 0; _i < 2; ++_i) \
;         __builtin_amdgcn_global_load_lds((const unsigned*)((const char*)(gbase) + (voff)[_i]), (LAS unsigned*)(lds + (bufoff) + ldsw + _i * 8192), 16, 0, 0); } while (0)
; #define PG8_LDA(dst, b, h) do { _Pragma("unroll") for (int m = 0; m < 4; ++m) _Pragma("unroll") for (int k = 0; k < 2; ++k) dst[m][k] = *(const LAS bf16x8*)(lds + PG8_SA(b, h) + aoff + m * 2048 + k * 1024); } while (0)
; #define PG8_LDB(dst, b, h) do { _Pragma("unroll") for (int n = 0; n < 2; ++n) _Pragma("unroll") for (int k = 0; k < 2; ++k) dst[n][k] = *(const LAS bf16x8*)(lds + PG8_SB(b, h) + boff + n * 2048 + k * 1024); } while (0)
; #define PG8_MMA(ai, bj, At, Bt) do { __builtin_amdgcn_s_setprio(1); _Pragma("unroll") for (int m = 0; m < 4; ++m) _Pragma("unroll") for (int n = 0; n < 2; ++n) _Pragma("unroll") for (int k = 0; k < 2; ++k) \
;         acc[ai][bj][m][n] = __builtin_amdgcn_mfma_f32_16x16x32_bf16(Bt[n][k], At[m][k], acc[ai][bj][m][n], 0, 0, 0); __builtin_amdgcn_s_setprio(0); } while (0)
; #define PG8_WAIT_L(n) asm volatile("s_waitcnt lgkmcnt(" #n ")" ::: "memory")
; #define PG8_BAR __builtin_amdgcn_s_barrier()
; #define PG8_SCHED __builtin_amdgcn_sched_barrier(0)
; template <class Epi>
; DI void gemm_phase(LAS unsigned char* lds, int wid, int K, int lda, int ldb, bool bperm, const Sched3& S, const Epi& E) {
;     ...
;             PG8_LDB(B1, 0, 1); PG8_STAGE(PG8_SB(0, 0), b2, voffB);
;             PG8_BAR; PG8_WAIT_L(0); PG8_MMA(0, 1, At, B1); PG8_BAR;
;             PG8_LDA(At, 0, 1); PG8_STAGE(PG8_SA(0, 0), a2, voffA);
;             PG8_BAR; PG8_WAIT_L(0); if (full) PG8_MMA(1, 0, At, B0); PG8_BAR; PG8_SCHED;
	s_add_i32 m0, s26, 0x2000
	s_nop 0
	global_load_lds_dwordx4 v154, s[30:31]
	s_barrier
	s_waitcnt lgkmcnt(0)
	s_setprio 1
	s_waitcnt lgkmcnt(0)
	v_mfma_f32_16x16x32_bf16 v[116:119], v[196:199], v[144:147], 0
	v_mfma_f32_16x16x32_bf16 v[112:115], v[204:207], v[144:147], 0
	v_mfma_f32_16x16x32_bf16 v[100:103], v[196:199], v[162:165], 0
	v_mfma_f32_16x16x32_bf16 v[96:99], v[204:207], v[162:165], 0
	v_mfma_f32_16x16x32_bf16 v[84:87], v[196:199], v[170:173], 0
	v_mfma_f32_16x16x32_bf16 v[80:83], v[204:207], v[170:173], 0
	v_mfma_f32_16x16x32_bf16 v[68:71], v[196:199], v[188:191], 0
	v_mfma_f32_16x16x32_bf16 v[64:67], v[204:207], v[188:191], 0
	v_mfma_f32_16x16x32_bf16 v[116:119], v[200:203], v[148:151], v[116:119]
	v_mfma_f32_16x16x32_bf16 v[112:115], v[208:211], v[148:151], v[112:115]
	v_mfma_f32_16x16x32_bf16 v[100:103], v[200:203], v[166:169], v[100:103]
	v_mfma_f32_16x16x32_bf16 v[96:99], v[208:211], v[166:169], v[96:99]
	v_mfma_f32_16x16x32_bf16 v[84:87], v[200:203], v[174:177], v[84:87]
	v_mfma_f32_16x16x32_bf16 v[80:83], v[208:211], v[174:177], v[80:83]
	v_mfma_f32_16x16x32_bf16 v[68:71], v[200:203], v[192:195], v[68:71]
	v_mfma_f32_16x16x32_bf16 v[64:67], v[208:211], v[192:195], v[64:67]
	s_setprio 0
	s_mov_b32 m0, s44
	s_mov_b64 s[100:101], s[36:37]
	s_barrier
	ds_read_b128 v[144:147], v186 offset:16384
	ds_read_b128 v[148:151], v186 offset:17408
	ds_read_b128 v[162:165], v186 offset:18432
	ds_read_b128 v[166:169], v186 offset:19456
	ds_read_b128 v[170:173], v186 offset:20480
	ds_read_b128 v[174:177], v186 offset:21504
	ds_read_b128 v[188:191], v186 offset:22528
	ds_read_b128 v[192:195], v186 offset:23552
	global_load_lds_dwordx4 v152, s[36:37]
	s_mov_b64 s[100:101], s[36:37]
	s_mov_b32 m0, s45
	s_nop 0
	global_load_lds_dwordx4 v154, s[36:37]
	s_barrier
	s_waitcnt lgkmcnt(0)
	s_setprio 1
	s_waitcnt lgkmcnt(0)
	v_mfma_f32_16x16x32_bf16 v[60:63], v[128:131], v[144:147], 0
	v_mfma_f32_16x16x32_bf16 v[56:59], v[136:139], v[144:147], 0
	v_mfma_f32_16x16x32_bf16 v[44:47], v[128:131], v[162:165], 0
	v_mfma_f32_16x16x32_bf16 v[40:43], v[136:139], v[162:165], 0
	v_mfma_f32_16x16x32_bf16 v[28:31], v[128:131], v[170:173], 0
	v_mfma_f32_16x16x32_bf16 v[24:27], v[136:139], v[170:173], 0
	v_mfma_f32_16x16x32_bf16 v[12:15], v[128:131], v[188:191], 0
	v_mfma_f32_16x16x32_bf16 v[8:11], v[136:139], v[188:191], 0
	v_mfma_f32_16x16x32_bf16 v[60:63], v[132:135], v[148:151], v[60:63]
	v_mfma_f32_16x16x32_bf16 v[56:59], v[140:143], v[148:151], v[56:59]
	v_mfma_f32_16x16x32_bf16 v[44:47], v[132:135], v[166:169], v[44:47]
	v_mfma_f32_16x16x32_bf16 v[40:43], v[140:143], v[166:169], v[40:43]
	v_mfma_f32_16x16x32_bf16 v[28:31], v[132:135], v[174:177], v[28:31]
	v_mfma_f32_16x16x32_bf16 v[24:27], v[140:143], v[174:177], v[24:27]
	v_mfma_f32_16x16x32_bf16 v[12:15], v[132:135], v[192:195], v[12:15]
	v_mfma_f32_16x16x32_bf16 v[8:11], v[140:143], v[192:195], v[8:11]
	s_setprio 0
	s_barrier
	s_add_u32 s26, s30, 0x160000
	s_addc_u32 s27, s31, 0
	s_add_i32 s63, s54, s43

; #define PG8_STAGE(bufoff, gbase, voff) do { _Pragma("unroll") for (int _i = 0; _i < 2; ++_i) \
;         __builtin_amdgcn_global_load_lds((const unsigned*)((const char*)(gbase) + (voff)[_i]), (LAS unsigned*)(lds + (bufoff) + ldsw + _i * 8192), 16, 0, 0); } while (0)
; template <class Epi>
; DI void gemm_phase(LAS unsigned char* lds, int wid, int K, int lda, int ldb, bool bperm, const Sched3& S, const Epi& E) {
;     ...
;             PG8_STAGE(PG8_SB(0, 1), b2 + hstepB, voffB);
	s_mov_b32 m0, s63
	s_nop 0
	global_load_lds_dwordx4 v152, s[26:27]

; #define PG8_STAGE(bufoff, gbase, voff) do { _Pragma("unroll") for (int _i = 0; _i < 2; ++_i) \
;         __builtin_amdgcn_global_load_lds((const unsigned*)((const char*)(gbase) + (voff)[_i]), (LAS unsigned*)(lds + (bufoff) + ldsw + _i * 8192), 16, 0, 0); } while (0)
; #define PG8_LDA(dst, b, h) do { _Pragma("unroll") for (int m = 0; m < 4; ++m) _Pragma("unroll") for (int k = 0; k < 2; ++k) dst[m][k] = *(const LAS bf16x8*)(lds + PG8_SA(b, h) + aoff + m * 2048 + k * 1024); } while (0)
; #define PG8_LDB(dst, b, h) do { _Pragma("unroll") for (int n = 0; n < 2; ++n) _Pragma("unroll") for (int k = 0; k < 2; ++k) dst[n][k] = *(const LAS bf16x8*)(lds + PG8_SB(b, h) + boff + n * 2048 + k * 1024); } while (0)
; #define PG8_MMA(ai, bj, At, Bt) do { __builtin_amdgcn_s_setprio(1); _Pragma("unroll") for (int m = 0; m < 4; ++m) _Pragma("unroll") for (int n = 0; n < 2; ++n) _Pragma("unroll") for (int k = 0; k < 2; ++k) \
;         acc[ai][bj][m][n] = __builtin_amdgcn_mfma_f32_16x16x32_bf16(Bt[n][k], At[m][k], acc[ai][bj][m][n], 0, 0, 0); __builtin_amdgcn_s_setprio(0); } while (0)
; #define PG8_WAIT_V(n) asm volatile("s_waitcnt vmcnt(" #n ")" ::: "memory")
; #define PG8_BAR __builtin_amdgcn_s_barrier()
; #define PG8_SCHED __builtin_amdgcn_sched_barrier(0)
; template <class Epi>
; DI void gemm_phase(LAS unsigned char* lds, int wid, int K, int lda, int ldb, bool bperm, const Sched3& S, const Epi& E) {
;     ...
;             PG8_STAGE(PG8_SB(0, 1), b2 + hstepB, voffB);
;             PG8_WAIT_V(6); PG8_BAR; if (full) PG8_MMA(1, 1, At, B1); PG8_BAR;
;             PG8_LDB(B0, 1, 0); PG8_SCHED; PG8_LDA(At, 1, 0); PG8_STAGE(PG8_SA(0, 1), a2 + h2, voffA);
	s_add_i32 m0, s63, 0x2000
	s_nop 0
	global_load_lds_dwordx4 v154, s[26:27]
	s_waitcnt vmcnt(6)
	s_barrier
	s_setprio 1
	v_mfma_f32_16x16x32_bf16 v[52:55], v[196:199], v[144:147], 0
	v_mfma_f32_16x16x32_bf16 v[48:51], v[204:207], v[144:147], 0
	v_mfma_f32_16x16x32_bf16 v[36:39], v[196:199], v[162:165], 0
	v_mfma_f32_16x16x32_bf16 v[32:35], v[204:207], v[162:165], 0
	v_mfma_f32_16x16x32_bf16 v[20:23], v[196:199], v[170:173], 0
	v_mfma_f32_16x16x32_bf16 v[16:19], v[204:207], v[170:173], 0
	v_mfma_f32_16x16x32_bf16 v[4:7], v[196:199], v[188:191], 0
	v_mfma_f32_16x16x32_bf16 v[0:3], v[204:207], v[188:191], 0
	v_mfma_f32_16x16x32_bf16 v[52:55], v[200:203], v[148:151], v[52:55]
	v_mfma_f32_16x16x32_bf16 v[48:51], v[208:211], v[148:151], v[48:51]
	v_mfma_f32_16x16x32_bf16 v[36:39], v[200:203], v[166:169], v[36:39]
	v_mfma_f32_16x16x32_bf16 v[32:35], v[208:211], v[166:169], v[32:35]
	v_mfma_f32_16x16x32_bf16 v[20:23], v[200:203], v[174:177], v[20:23]
	v_mfma_f32_16x16x32_bf16 v[16:19], v[208:211], v[174:177], v[16:19]
	v_mfma_f32_16x16x32_bf16 v[4:7], v[200:203], v[192:195], v[4:7]
	v_mfma_f32_16x16x32_bf16 v[0:3], v[208:211], v[192:195], v[0:3]
	s_setprio 0
	s_add_i32 s63, 0, 0x18000
	v_add_u32_e32 v140, s63, v181
	s_barrier
	ds_read_b128 v[128:131], v140
	ds_read_b128 v[132:135], v140 offset:1024
	ds_read_b128 v[136:139], v140 offset:2048
	ds_read_b128 v[140:143], v140 offset:3072
	s_add_u32 s26, s36, 0x160000
	s_addc_u32 s27, s37, 0
	s_mov_b32 m0, s46

; #define PG8_STAGE(bufoff, gbase, voff) do { _Pragma("unroll") for (int _i = 0; _i < 2; ++_i) \
;         __builtin_amdgcn_global_load_lds((const unsigned*)((const char*)(gbase) + (voff)[_i]), (LAS unsigned*)(lds + (bufoff) + ldsw + _i * 8192), 16, 0, 0); } while (0)
; #define PG8_LDA(dst, b, h) do { _Pragma("unroll") for (int m = 0; m < 4; ++m) _Pragma("unroll") for (int k = 0; k < 2; ++k) dst[m][k] = *(const LAS bf16x8*)(lds + PG8_SA(b, h) + aoff + m * 2048 + k * 1024); } while (0)
; #define PG8_LDB(dst, b, h) do { _Pragma("unroll") for (int n = 0; n < 2; ++n) _Pragma("unroll") for (int k = 0; k < 2; ++k) dst[n][k] = *(const LAS bf16x8*)(lds + PG8_SB(b, h) + boff + n * 2048 + k * 1024); } while (0)
; #define PG8_SCHED __builtin_amdgcn_sched_barrier(0)
; template <class Epi>
; DI void gemm_phase(LAS unsigned char* lds, int wid, int K, int lda, int ldb, bool bperm, const Sched3& S, const Epi& E) {
;     ...
;             PG8_LDB(B0, 1, 0); PG8_SCHED; PG8_LDA(At, 1, 0); PG8_STAGE(PG8_SA(0, 1), a2 + h2, voffA);
	ds_read_b128 v[144:147], v186 offset:32768
	ds_read_b128 v[148:151], v186 offset:33792
	ds_read_b128 v[162:165], v186 offset:34816
	ds_read_b128 v[166:169], v186 offset:35840
	ds_read_b128 v[170:173], v186 offset:36864
	ds_read_b128 v[174:177], v186 offset:37888
	ds_read_b128 v[188:191], v186 offset:38912
	ds_read_b128 v[192:195], v186 offset:39936
	global_load_lds_dwordx4 v152, s[26:27]

; #define PG8_STAGE(bufoff, gbase, voff) do { _Pragma("unroll") for (int _i = 0; _i < 2; ++_i) \
;         __builtin_amdgcn_global_load_lds((const unsigned*)((const char*)(gbase) + (voff)[_i]), (LAS unsigned*)(lds + (bufoff) + ldsw + _i * 8192), 16, 0, 0); } while (0)
; #define PG8_LDA(dst, b, h) do { _Pragma("unroll") for (int m = 0; m < 4; ++m) _Pragma("unroll") for (int k = 0; k < 2; ++k) dst[m][k] = *(const LAS bf16x8*)(lds + PG8_SA(b, h) + aoff + m * 2048 + k * 1024); } while (0)
; #define PG8_LDB(dst, b, h) do { _Pragma("unroll") for (int n = 0; n < 2; ++n) _Pragma("unroll") for (int k = 0; k < 2; ++k) dst[n][k] = *(const LAS bf16x8*)(lds + PG8_SB(b, h) + boff + n * 2048 + k * 1024); } while (0)
; #define PG8_MMA(ai, bj, At, Bt) do { __builtin_amdgcn_s_setprio(1); _Pragma("unroll") for (int m = 0; m < 4; ++m) _Pragma("unroll") for (int n = 0; n < 2; ++n) _Pragma("unroll") for (int k = 0; k < 2; ++k) \
;         acc[ai][bj][m][n] = __builtin_amdgcn_mfma_f32_16x16x32_bf16(Bt[n][k], At[m][k], acc[ai][bj][m][n], 0, 0, 0); __builtin_amdgcn_s_setprio(0); } while (0)
; #define PG8_WAIT_L(n) asm volatile("s_waitcnt lgkmcnt(" #n ")" ::: "memory")
; #define PG8_BAR __builtin_amdgcn_s_barrier()
; #define PG8_SCHED __builtin_amdgcn_sched_barrier(0)
; template <class Epi>
; DI void gemm_phase(LAS unsigned char* lds, int wid, int K, int lda, int ldb, bool bperm, const Sched3& S, const Epi& E) {
;     ...
;             PG8_LDB(B0, 1, 0); PG8_SCHED; PG8_LDA(At, 1, 0); PG8_STAGE(PG8_SA(0, 1), a2 + h2, voffA);
;             PG8_WAIT_L(8); PG8_BAR; PG8_WAIT_L(0); PG8_MMA(0, 0, At, B0); PG8_BAR; PG8_SCHED;
	s_mov_b32 m0, s47
	s_nop 0
	global_load_lds_dwordx4 v154, s[26:27]
	s_waitcnt lgkmcnt(8)
	s_barrier
	s_waitcnt lgkmcnt(0)
	s_setprio 1
	s_waitcnt lgkmcnt(0)
	v_mfma_f32_16x16x32_bf16 v[124:127], v[128:131], v[144:147], v[124:127]
	v_mfma_f32_16x16x32_bf16 v[120:123], v[136:139], v[144:147], v[120:123]
	v_mfma_f32_16x16x32_bf16 v[108:111], v[128:131], v[162:165], v[108:111]
	v_mfma_f32_16x16x32_bf16 v[104:107], v[136:139], v[162:165], v[104:107]
	v_mfma_f32_16x16x32_bf16 v[92:95], v[128:131], v[170:173], v[92:95]
	v_mfma_f32_16x16x32_bf16 v[88:91], v[136:139], v[170:173], v[88:91]
	v_mfma_f32_16x16x32_bf16 v[76:79], v[128:131], v[188:191], v[76:79]
	v_mfma_f32_16x16x32_bf16 v[72:75], v[136:139], v[188:191], v[72:75]
	v_mfma_f32_16x16x32_bf16 v[124:127], v[132:135], v[148:151], v[124:127]
	v_mfma_f32_16x16x32_bf16 v[120:123], v[140:143], v[148:151], v[120:123]
	v_mfma_f32_16x16x32_bf16 v[108:111], v[132:135], v[166:169], v[108:111]
	v_mfma_f32_16x16x32_bf16 v[104:107], v[140:143], v[166:169], v[104:107]
	v_mfma_f32_16x16x32_bf16 v[92:95], v[132:135], v[174:177], v[92:95]
	v_mfma_f32_16x16x32_bf16 v[88:91], v[140:143], v[174:177], v[88:91]
	v_mfma_f32_16x16x32_bf16 v[76:79], v[132:135], v[192:195], v[76:79]
	v_mfma_f32_16x16x32_bf16 v[72:75], v[140:143], v[192:195], v[72:75]
	s_setprio 0
	s_barrier
	s_add_i32 s36, 0, 0x1c000
	s_add_i32 s26, s63, s43
	v_add_u32_e32 v208, s36, v181

; #define PG8_STAGE(bufoff, gbase, voff) do { _Pragma("unroll") for (int _i = 0; _i < 2; ++_i) \
;         __builtin_amdgcn_global_load_lds((const unsigned*)((const char*)(gbase) + (voff)[_i]), (LAS unsigned*)(lds + (bufoff) + ldsw + _i * 8192), 16, 0, 0); } while (0)
; #define PG8_LDB(dst, b, h) do { _Pragma("unroll") for (int n = 0; n < 2; ++n) _Pragma("unroll") for (int k = 0; k < 2; ++k) dst[n][k] = *(const LAS bf16x8*)(lds + PG8_SB(b, h) + boff + n * 2048 + k * 1024); } while (0)
; template <class Epi>
; DI void gemm_phase(LAS unsigned char* lds, int wid, int K, int lda, int ldb, bool bperm, const Sched3& S, const Epi& E) {
;     ...
;             PG8_LDB(B1, 1, 1); PG8_STAGE(PG8_SB(1, 0), b3, voffB);
	s_sub_i32 m0, s26, 0x80
	ds_read_b128 v[196:199], v208
	ds_read_b128 v[200:203], v208 offset:1024
	ds_read_b128 v[204:207], v208 offset:2048
	ds_read_b128 v[208:211], v208 offset:3072
	global_load_lds_dwordx4 v152, s[30:31] offset:128

; #define PG8_STAGE(bufoff, gbase, voff) do { _Pragma("unroll") for (int _i = 0; _i < 2; ++_i) \
;         __builtin_amdgcn_global_load_lds((const unsigned*)((const char*)(gbase) + (voff)[_i]), (LAS unsigned*)(lds + (bufoff) + ldsw + _i * 8192), 16, 0, 0); } while (0)
; #define PG8_LDB(dst, b, h) do { _Pragma("unroll") for (int n = 0; n < 2; ++n) _Pragma("unroll") for (int k = 0; k < 2; ++k) dst[n][k] = *(const LAS bf16x8*)(lds + PG8_SB(b, h) + boff + n * 2048 + k * 1024); } while (0)
; #define PG8_MMA(ai, bj, At, Bt) do { __builtin_amdgcn_s_setprio(1); _Pragma("unroll") for (int m = 0; m < 4; ++m) _Pragma("unroll") for (int n = 0; n < 2; ++n) _Pragma("unroll") for (int k = 0; k < 2; ++k) \
;         acc[ai][bj][m][n] = __builtin_amdgcn_mfma_f32_16x16x32_bf16(Bt[n][k], At[m][k], acc[ai][bj][m][n], 0, 0, 0); __builtin_amdgcn_s_setprio(0); } while (0)
; #define PG8_WAIT_L(n) asm volatile("s_waitcnt lgkmcnt(" #n ")" ::: "memory")
; #define PG8_BAR __builtin_amdgcn_s_barrier()
; template <class Epi>
; DI void gemm_phase(LAS unsigned char* lds, int wid, int K, int lda, int ldb, bool bperm, const Sched3& S, const Epi& E) {
;     ...
;             PG8_LDB(B1, 1, 1); PG8_STAGE(PG8_SB(1, 0), b3, voffB);
;             PG8_BAR; PG8_WAIT_L(0); PG8_MMA(0, 1, At, B1); PG8_BAR;
	s_add_i32 m0, s26, 0x1f80
	s_nop 0
	global_load_lds_dwordx4 v154, s[30:31] offset:128
	s_barrier
	s_waitcnt lgkmcnt(0)
	s_setprio 1
	s_waitcnt lgkmcnt(0)
	v_mfma_f32_16x16x32_bf16 v[116:119], v[196:199], v[144:147], v[116:119]
	v_mfma_f32_16x16x32_bf16 v[112:115], v[204:207], v[144:147], v[112:115]
	v_mfma_f32_16x16x32_bf16 v[100:103], v[196:199], v[162:165], v[100:103]
	v_mfma_f32_16x16x32_bf16 v[96:99], v[204:207], v[162:165], v[96:99]
	v_mfma_f32_16x16x32_bf16 v[84:87], v[196:199], v[170:173], v[84:87]
	v_mfma_f32_16x16x32_bf16 v[80:83], v[204:207], v[170:173], v[80:83]
	v_mfma_f32_16x16x32_bf16 v[68:71], v[196:199], v[188:191], v[68:71]
	v_mfma_f32_16x16x32_bf16 v[64:67], v[204:207], v[188:191], v[64:67]
	v_mfma_f32_16x16x32_bf16 v[116:119], v[200:203], v[148:151], v[116:119]
	v_mfma_f32_16x16x32_bf16 v[112:115], v[208:211], v[148:151], v[112:115]
	v_mfma_f32_16x16x32_bf16 v[100:103], v[200:203], v[166:169], v[100:103]
	v_mfma_f32_16x16x32_bf16 v[96:99], v[208:211], v[166:169], v[96:99]
	v_mfma_f32_16x16x32_bf16 v[84:87], v[200:203], v[174:177], v[84:87]
	v_mfma_f32_16x16x32_bf16 v[80:83], v[208:211], v[174:177], v[80:83]
	v_mfma_f32_16x16x32_bf16 v[68:71], v[200:203], v[192:195], v[68:71]
	v_mfma_f32_16x16x32_bf16 v[64:67], v[208:211], v[192:195], v[64:67]
	s_setprio 0
	s_sub_i32 m0, s49, 0x80

; #define PG8_STAGE(bufoff, gbase, voff) do { _Pragma("unroll") for (int _i = 0; _i < 2; ++_i) \
;         __builtin_amdgcn_global_load_lds((const unsigned*)((const char*)(gbase) + (voff)[_i]), (LAS unsigned*)(lds + (bufoff) + ldsw + _i * 8192), 16, 0, 0); } while (0)
; #define PG8_LDA(dst, b, h) do { _Pragma("unroll") for (int m = 0; m < 4; ++m) _Pragma("unroll") for (int k = 0; k < 2; ++k) dst[m][k] = *(const LAS bf16x8*)(lds + PG8_SA(b, h) + aoff + m * 2048 + k * 1024); } while (0)
; template <class Epi>
; DI void gemm_phase(LAS unsigned char* lds, int wid, int K, int lda, int ldb, bool bperm, const Sched3& S, const Epi& E) {
;     ...
;             PG8_LDA(At, 1, 1); PG8_STAGE(PG8_SA(1, 0), a3, voffA);
	s_barrier
	ds_read_b128 v[144:147], v186 offset:49152
	ds_read_b128 v[148:151], v186 offset:50176
	ds_read_b128 v[162:165], v186 offset:51200
	ds_read_b128 v[166:169], v186 offset:52224
	ds_read_b128 v[170:173], v186 offset:53248
	ds_read_b128 v[174:177], v186 offset:54272
	ds_read_b128 v[188:191], v186 offset:55296
	ds_read_b128 v[192:195], v186 offset:56320
	global_load_lds_dwordx4 v152, s[100:101] offset:128

; #define PG8_STAGE(bufoff, gbase, voff) do { _Pragma("unroll") for (int _i = 0; _i < 2; ++_i) \
;         __builtin_amdgcn_global_load_lds((const unsigned*)((const char*)(gbase) + (voff)[_i]), (LAS unsigned*)(lds + (bufoff) + ldsw + _i * 8192), 16, 0, 0); } while (0)
; #define PG8_LDA(dst, b, h) do { _Pragma("unroll") for (int m = 0; m < 4; ++m) _Pragma("unroll") for (int k = 0; k < 2; ++k) dst[m][k] = *(const LAS bf16x8*)(lds + PG8_SA(b, h) + aoff + m * 2048 + k * 1024); } while (0)
; #define PG8_MMA(ai, bj, At, Bt) do { __builtin_amdgcn_s_setprio(1); _Pragma("unroll") for (int m = 0; m < 4; ++m) _Pragma("unroll") for (int n = 0; n < 2; ++n) _Pragma("unroll") for (int k = 0; k < 2; ++k) \
;         acc[ai][bj][m][n] = __builtin_amdgcn_mfma_f32_16x16x32_bf16(Bt[n][k], At[m][k], acc[ai][bj][m][n], 0, 0, 0); __builtin_amdgcn_s_setprio(0); } while (0)
; #define PG8_WAIT_L(n) asm volatile("s_waitcnt lgkmcnt(" #n ")" ::: "memory")
; #define PG8_BAR __builtin_amdgcn_s_barrier()
; #define PG8_SCHED __builtin_amdgcn_sched_barrier(0)
; template <class Epi>
; DI void gemm_phase(LAS unsigned char* lds, int wid, int K, int lda, int ldb, bool bperm, const Sched3& S, const Epi& E) {
;     ...
;             PG8_LDA(At, 1, 1); PG8_STAGE(PG8_SA(1, 0), a3, voffA);
;             PG8_BAR; PG8_WAIT_L(0); if (full) PG8_MMA(1, 0, At, B0); PG8_BAR; PG8_SCHED;
	s_sub_i32 m0, s50, 0x80
	s_nop 0
	global_load_lds_dwordx4 v154, s[100:101] offset:128
	s_barrier
	s_waitcnt lgkmcnt(0)
	s_setprio 1
	s_waitcnt lgkmcnt(0)
	v_mfma_f32_16x16x32_bf16 v[60:63], v[128:131], v[144:147], v[60:63]
	v_mfma_f32_16x16x32_bf16 v[56:59], v[136:139], v[144:147], v[56:59]
	v_mfma_f32_16x16x32_bf16 v[44:47], v[128:131], v[162:165], v[44:47]
	v_mfma_f32_16x16x32_bf16 v[40:43], v[136:139], v[162:165], v[40:43]
	v_mfma_f32_16x16x32_bf16 v[28:31], v[128:131], v[170:173], v[28:31]
	v_mfma_f32_16x16x32_bf16 v[24:27], v[136:139], v[170:173], v[24:27]
	v_mfma_f32_16x16x32_bf16 v[12:15], v[128:131], v[188:191], v[12:15]
	v_mfma_f32_16x16x32_bf16 v[8:11], v[136:139], v[188:191], v[8:11]
	v_mfma_f32_16x16x32_bf16 v[60:63], v[132:135], v[148:151], v[60:63]
	v_mfma_f32_16x16x32_bf16 v[56:59], v[140:143], v[148:151], v[56:59]
	v_mfma_f32_16x16x32_bf16 v[44:47], v[132:135], v[166:169], v[44:47]
	v_mfma_f32_16x16x32_bf16 v[40:43], v[140:143], v[166:169], v[40:43]
	v_mfma_f32_16x16x32_bf16 v[28:31], v[132:135], v[174:177], v[28:31]
	v_mfma_f32_16x16x32_bf16 v[24:27], v[140:143], v[174:177], v[24:27]
	v_mfma_f32_16x16x32_bf16 v[12:15], v[132:135], v[192:195], v[12:15]
	v_mfma_f32_16x16x32_bf16 v[8:11], v[140:143], v[192:195], v[8:11]
	s_setprio 0
	s_barrier
	s_add_u32 s26, s30, 0x160080
	s_addc_u32 s27, s31, 0
	s_add_i32 s30, s36, s43

; #define PG8_STAGE(bufoff, gbase, voff) do { _Pragma("unroll") for (int _i = 0; _i < 2; ++_i) \
;         __builtin_amdgcn_global_load_lds((const unsigned*)((const char*)(gbase) + (voff)[_i]), (LAS unsigned*)(lds + (bufoff) + ldsw + _i * 8192), 16, 0, 0); } while (0)
; template <class Epi>
; DI void gemm_phase(LAS unsigned char* lds, int wid, int K, int lda, int ldb, bool bperm, const Sched3& S, const Epi& E) {
;     ...
;             PG8_STAGE(PG8_SB(1, 1), b3 + hstepB, voffB);
	s_mov_b32 m0, s30
	s_nop 0
	global_load_lds_dwordx4 v152, s[26:27]

; #define PG8_STAGE(bufoff, gbase, voff) do { _Pragma("unroll") for (int _i = 0; _i < 2; ++_i) \
;         __builtin_amdgcn_global_load_lds((const unsigned*)((const char*)(gbase) + (voff)[_i]), (LAS unsigned*)(lds + (bufoff) + ldsw + _i * 8192), 16, 0, 0); } while (0)
; #define PG8_MMA(ai, bj, At, Bt) do { __builtin_amdgcn_s_setprio(1); _Pragma("unroll") for (int m = 0; m < 4; ++m) _Pragma("unroll") for (int n = 0; n < 2; ++n) _Pragma("unroll") for (int k = 0; k < 2; ++k) \
;         acc[ai][bj][m][n] = __builtin_amdgcn_mfma_f32_16x16x32_bf16(Bt[n][k], At[m][k], acc[ai][bj][m][n], 0, 0, 0); __builtin_amdgcn_s_setprio(0); } while (0)
; #define PG8_WAIT_V(n) asm volatile("s_waitcnt vmcnt(" #n ")" ::: "memory")
; #define PG8_BAR __builtin_amdgcn_s_barrier()
; template <class Epi>
; DI void gemm_phase(LAS unsigned char* lds, int wid, int K, int lda, int ldb, bool bperm, const Sched3& S, const Epi& E) {
;     ...
;             PG8_STAGE(PG8_SB(1, 1), b3 + hstepB, voffB);
;             PG8_WAIT_V(6); PG8_BAR; if (full) PG8_MMA(1, 1, At, B1); PG8_BAR;
	s_add_i32 m0, s30, 0x2000
	s_nop 0
	global_load_lds_dwordx4 v154, s[26:27]
	s_waitcnt vmcnt(6)
	s_barrier
	s_setprio 1
	v_mfma_f32_16x16x32_bf16 v[52:55], v[196:199], v[144:147], v[52:55]
	v_mfma_f32_16x16x32_bf16 v[48:51], v[204:207], v[144:147], v[48:51]
	v_mfma_f32_16x16x32_bf16 v[36:39], v[196:199], v[162:165], v[36:39]
	v_mfma_f32_16x16x32_bf16 v[32:35], v[204:207], v[162:165], v[32:35]
	v_mfma_f32_16x16x32_bf16 v[20:23], v[196:199], v[170:173], v[20:23]
	v_mfma_f32_16x16x32_bf16 v[16:19], v[204:207], v[170:173], v[16:19]
	v_mfma_f32_16x16x32_bf16 v[4:7], v[196:199], v[188:191], v[4:7]
	v_mfma_f32_16x16x32_bf16 v[0:3], v[204:207], v[188:191], v[0:3]
	v_mfma_f32_16x16x32_bf16 v[52:55], v[200:203], v[148:151], v[52:55]
	v_mfma_f32_16x16x32_bf16 v[48:51], v[208:211], v[148:151], v[48:51]
	v_mfma_f32_16x16x32_bf16 v[36:39], v[200:203], v[166:169], v[36:39]
	v_mfma_f32_16x16x32_bf16 v[32:35], v[208:211], v[166:169], v[32:35]
	v_mfma_f32_16x16x32_bf16 v[20:23], v[200:203], v[174:177], v[20:23]
	v_mfma_f32_16x16x32_bf16 v[16:19], v[208:211], v[174:177], v[16:19]
	v_mfma_f32_16x16x32_bf16 v[4:7], v[200:203], v[192:195], v[4:7]
	v_mfma_f32_16x16x32_bf16 v[0:3], v[208:211], v[192:195], v[0:3]
	s_setprio 0
	s_add_i32 s62, s62, 2
	s_add_u32 s60, s60, 0x100
	s_addc_u32 s61, s61, 0
	s_cmpk_gt_u32 s62, 0x55
	s_mov_b64 s[26:27], s[28:29]
	s_cbranch_scc1 .Lkrot_3_exit

; #define PG8_STAGE(bufoff, gbase, voff) do { _Pragma("unroll") for (int _i = 0; _i < 2; ++_i) \
;         __builtin_amdgcn_global_load_lds((const unsigned*)((const char*)(gbase) + (voff)[_i]), (LAS unsigned*)(lds + (bufoff) + ldsw + _i * 8192), 16, 0, 0); } while (0)
; #define PG8_LDA(dst, b, h) do { _Pragma("unroll") for (int m = 0; m < 4; ++m) _Pragma("unroll") for (int k = 0; k < 2; ++k) dst[m][k] = *(const LAS bf16x8*)(lds + PG8_SA(b, h) + aoff + m * 2048 + k * 1024); } while (0)
; #define PG8_LDB(dst, b, h) do { _Pragma("unroll") for (int n = 0; n < 2; ++n) _Pragma("unroll") for (int k = 0; k < 2; ++k) dst[n][k] = *(const LAS bf16x8*)(lds + PG8_SB(b, h) + boff + n * 2048 + k * 1024); } while (0)
; #define PG8_SCHED __builtin_amdgcn_sched_barrier(0)
; template <class Epi>
; DI void gemm_phase(LAS unsigned char* lds, int wid, int K, int lda, int ldb, bool bperm, const Sched3& S, const Epi& E) {
;     ...
;             const bool last = (t == nt - 2);
;             const char* a1 = cA + (size_t)(t + 1) * kstep;
;             const char* a2 = last ? nA : cA + (size_t)(t + 2) * kstep; const char* b2 = last ? nB : cB + (size_t)(t + 2) * kstep;
;             const char* a3 = a2 + kstep; const char* b3 = b2 + kstep; const size_t h2 = last ? nhA : hA;
;             PG8_LDB(B0, 0, 0); PG8_SCHED; PG8_LDA(At, 0, 0); PG8_STAGE(PG8_SA(1, 1), a1 + hA, voffA);
.LBB0_785:
	ds_read_b128 v[128:131], v185
	ds_read_b128 v[132:135], v185 offset:1024
	ds_read_b128 v[136:139], v185 offset:2048
	ds_read_b128 v[140:143], v185 offset:3072
	s_add_u32 s28, s26, 0x100
	s_addc_u32 s29, s27, 0
	s_cmpk_eq_i32 s62, 0x54
	s_cselect_b32 s37, s23, s29
	s_cselect_b32 s36, s22, s28
	s_cselect_b32 s31, s25, s61
	s_cselect_b32 s30, s24, s60

; #define PG8_STAGE(bufoff, gbase, voff) do { _Pragma("unroll") for (int _i = 0; _i < 2; ++_i) \
;         __builtin_amdgcn_global_load_lds((const unsigned*)((const char*)(gbase) + (voff)[_i]), (LAS unsigned*)(lds + (bufoff) + ldsw + _i * 8192), 16, 0, 0); } while (0)
; #define PG8_LDA(dst, b, h) do { _Pragma("unroll") for (int m = 0; m < 4; ++m) _Pragma("unroll") for (int k = 0; k < 2; ++k) dst[m][k] = *(const LAS bf16x8*)(lds + PG8_SA(b, h) + aoff + m * 2048 + k * 1024); } while (0)
; #define PG8_LDB(dst, b, h) do { _Pragma("unroll") for (int n = 0; n < 2; ++n) _Pragma("unroll") for (int k = 0; k < 2; ++k) dst[n][k] = *(const LAS bf16x8*)(lds + PG8_SB(b, h) + boff + n * 2048 + k * 1024); } while (0)
; #define PG8_SCHED __builtin_amdgcn_sched_barrier(0)
; template <class Epi>
; DI void gemm_phase(LAS unsigned char* lds, int wid, int K, int lda, int ldb, bool bperm, const Sched3& S, const Epi& E) {
;     ...
;             PG8_LDB(B0, 0, 0); PG8_SCHED; PG8_LDA(At, 0, 0); PG8_STAGE(PG8_SA(1, 1), a1 + hA, voffA);
	s_add_i32 m0, s44, 0xc000
	ds_read_b128 v[144:147], v186
	ds_read_b128 v[148:151], v186 offset:1024
	ds_read_b128 v[162:165], v186 offset:2048
	ds_read_b128 v[166:169], v186 offset:3072
	ds_read_b128 v[170:173], v186 offset:4096
	ds_read_b128 v[174:177], v186 offset:5120
	ds_read_b128 v[188:191], v186 offset:6144
	ds_read_b128 v[192:195], v186 offset:7168
	global_load_lds_dwordx4 v156, s[26:27]

; #define PG8_STAGE(bufoff, gbase, voff) do { _Pragma("unroll") for (int _i = 0; _i < 2; ++_i) \
;         __builtin_amdgcn_global_load_lds((const unsigned*)((const char*)(gbase) + (voff)[_i]), (LAS unsigned*)(lds + (bufoff) + ldsw + _i * 8192), 16, 0, 0); } while (0)
; #define PG8_LDA(dst, b, h) do { _Pragma("unroll") for (int m = 0; m < 4; ++m) _Pragma("unroll") for (int k = 0; k < 2; ++k) dst[m][k] = *(const LAS bf16x8*)(lds + PG8_SA(b, h) + aoff + m * 2048 + k * 1024); } while (0)
; #define PG8_LDB(dst, b, h) do { _Pragma("unroll") for (int n = 0; n < 2; ++n) _Pragma("unroll") for (int k = 0; k < 2; ++k) dst[n][k] = *(const LAS bf16x8*)(lds + PG8_SB(b, h) + boff + n * 2048 + k * 1024); } while (0)
; #define PG8_MMA(ai, bj, At, Bt) do { __builtin_amdgcn_s_setprio(1); _Pragma("unroll") for (int m = 0; m < 4; ++m) _Pragma("unroll") for (int n = 0; n < 2; ++n) _Pragma("unroll") for (int k = 0; k < 2; ++k) \
;         acc[ai][bj][m][n] = __builtin_amdgcn_mfma_f32_16x16x32_bf16(Bt[n][k], At[m][k], acc[ai][bj][m][n], 0, 0, 0); __builtin_amdgcn_s_setprio(0); } while (0)
; #define PG8_WAIT_L(n) asm volatile("s_waitcnt lgkmcnt(" #n ")" ::: "memory")
; #define PG8_BAR __builtin_amdgcn_s_barrier()
; #define PG8_SCHED __builtin_amdgcn_sched_barrier(0)
; template <class Epi>
; DI void gemm_phase(LAS unsigned char* lds, int wid, int K, int lda, int ldb, bool bperm, const Sched3& S, const Epi& E) {
;     ...
;             PG8_LDB(B0, 0, 0); PG8_SCHED; PG8_LDA(At, 0, 0); PG8_STAGE(PG8_SA(1, 1), a1 + hA, voffA);
;             PG8_WAIT_L(8); PG8_BAR; PG8_WAIT_L(0); PG8_MMA(0, 0, At, B0); PG8_BAR; PG8_SCHED;
	s_add_i32 m0, s44, 0xe000
	s_nop 0
	global_load_lds_dwordx4 v158, s[26:27]
	s_waitcnt lgkmcnt(8)
	s_barrier
	s_waitcnt lgkmcnt(0)
	s_setprio 1
	s_waitcnt lgkmcnt(0)
	v_mfma_f32_16x16x32_bf16 v[124:127], v[128:131], v[144:147], v[124:127]
	v_mfma_f32_16x16x32_bf16 v[120:123], v[136:139], v[144:147], v[120:123]
	v_mfma_f32_16x16x32_bf16 v[108:111], v[128:131], v[162:165], v[108:111]
	v_mfma_f32_16x16x32_bf16 v[104:107], v[136:139], v[162:165], v[104:107]
	v_mfma_f32_16x16x32_bf16 v[92:95], v[128:131], v[170:173], v[92:95]
	v_mfma_f32_16x16x32_bf16 v[88:91], v[136:139], v[170:173], v[88:91]
	v_mfma_f32_16x16x32_bf16 v[76:79], v[128:131], v[188:191], v[76:79]
	v_mfma_f32_16x16x32_bf16 v[72:75], v[136:139], v[188:191], v[72:75]
	v_mfma_f32_16x16x32_bf16 v[124:127], v[132:135], v[148:151], v[124:127]
	v_mfma_f32_16x16x32_bf16 v[120:123], v[140:143], v[148:151], v[120:123]
	v_mfma_f32_16x16x32_bf16 v[108:111], v[132:135], v[166:169], v[108:111]
	v_mfma_f32_16x16x32_bf16 v[104:107], v[140:143], v[166:169], v[104:107]
	v_mfma_f32_16x16x32_bf16 v[92:95], v[132:135], v[174:177], v[92:95]
	v_mfma_f32_16x16x32_bf16 v[88:91], v[140:143], v[174:177], v[88:91]
	v_mfma_f32_16x16x32_bf16 v[76:79], v[132:135], v[192:195], v[76:79]
	v_mfma_f32_16x16x32_bf16 v[72:75], v[140:143], v[192:195], v[72:75]
	s_setprio 0
	s_barrier
	s_add_i32 s26, s53, s43

; #define PG8_STAGE(bufoff, gbase, voff) do { _Pragma("unroll") for (int _i = 0; _i < 2; ++_i) \
;         __builtin_amdgcn_global_load_lds((const unsigned*)((const char*)(gbase) + (voff)[_i]), (LAS unsigned*)(lds + (bufoff) + ldsw + _i * 8192), 16, 0, 0); } while (0)
; #define PG8_LDB(dst, b, h) do { _Pragma("unroll") for (int n = 0; n < 2; ++n) _Pragma("unroll") for (int k = 0; k < 2; ++k) dst[n][k] = *(const LAS bf16x8*)(lds + PG8_SB(b, h) + boff + n * 2048 + k * 1024); } while (0)
; template <class Epi>
; DI void gemm_phase(LAS unsigned char* lds, int wid, int K, int lda, int ldb, bool bperm, const Sched3& S, const Epi& E) {
;     ...
;             PG8_LDB(B1, 0, 1); PG8_STAGE(PG8_SB(0, 0), b2, voffB);
	s_mov_b32 m0, s26
	ds_read_b128 v[196:199], v187
	ds_read_b128 v[200:203], v187 offset:1024
	ds_read_b128 v[204:207], v187 offset:2048
	ds_read_b128 v[208:211], v187 offset:3072
	global_load_lds_dwordx4 v152, s[30:31]

; #define PG8_STAGE(bufoff, gbase, voff) do { _Pragma("unroll") for (int _i = 0; _i < 2; ++_i) \
;         __builtin_amdgcn_global_load_lds((const unsigned*)((const char*)(gbase) + (voff)[_i]), (LAS unsigned*)(lds + (bufoff) + ldsw + _i * 8192), 16, 0, 0); } while (0)
; #define PG8_LDA(dst, b, h) do { _Pragma("unroll") for (int m = 0; m < 4; ++m) _Pragma("unroll") for (int k = 0; k < 2; ++k) dst[m][k] = *(const LAS bf16x8*)(lds + PG8_SA(b, h) + aoff + m * 2048 + k * 1024); } while (0)
; #define PG8_LDB(dst, b, h) do { _Pragma("unroll") for (int n = 0; n < 2; ++n) _Pragma("unroll") for (int k = 0; k < 2; ++k) dst[n][k] = *(const LAS bf16x8*)(lds + PG8_SB(b, h) + boff + n * 2048 + k * 1024); } while (0)
; #define PG8_MMA(ai, bj, At, Bt) do { __builtin_amdgcn_s_setprio(1); _Pragma("unroll") for (int m = 0; m < 4; ++m) _Pragma("unroll") for (int n = 0; n < 2; ++n) _Pragma("unroll") for (int k = 0; k < 2; ++k) \
;         acc[ai][bj][m][n] = __builtin_amdgcn_mfma_f32_16x16x32_bf16(Bt[n][k], At[m][k], acc[ai][bj][m][n], 0, 0, 0); __builtin_amdgcn_s_setprio(0); } while (0)
; #define PG8_WAIT_L(n) asm volatile("s_waitcnt lgkmcnt(" #n ")" ::: "memory")
; #define PG8_BAR __builtin_amdgcn_s_barrier()
; #define PG8_SCHED __builtin_amdgcn_sched_barrier(0)
; template <class Epi>
; DI void gemm_phase(LAS unsigned char* lds, int wid, int K, int lda, int ldb, bool bperm, const Sched3& S, const Epi& E) {
;     ...
;             PG8_LDB(B1, 0, 1); PG8_STAGE(PG8_SB(0, 0), b2, voffB);
;             PG8_BAR; PG8_WAIT_L(0); PG8_MMA(0, 1, At, B1); PG8_BAR;
;             PG8_LDA(At, 0, 1); PG8_STAGE(PG8_SA(0, 0), a2, voffA);
;             PG8_BAR; PG8_WAIT_L(0); if (full) PG8_MMA(1, 0, At, B0); PG8_BAR; PG8_SCHED;
;             PG8_STAGE(PG8_SB(0, 1), b2 + hstepB, voffB);
	s_add_i32 m0, s26, 0x2000
	s_nop 0
	global_load_lds_dwordx4 v154, s[30:31]
	s_barrier
	s_waitcnt lgkmcnt(0)
	s_setprio 1
	s_waitcnt lgkmcnt(0)
	v_mfma_f32_16x16x32_bf16 v[116:119], v[196:199], v[144:147], v[116:119]
	v_mfma_f32_16x16x32_bf16 v[112:115], v[204:207], v[144:147], v[112:115]
	v_mfma_f32_16x16x32_bf16 v[100:103], v[196:199], v[162:165], v[100:103]
	v_mfma_f32_16x16x32_bf16 v[96:99], v[204:207], v[162:165], v[96:99]
	v_mfma_f32_16x16x32_bf16 v[84:87], v[196:199], v[170:173], v[84:87]
	v_mfma_f32_16x16x32_bf16 v[80:83], v[204:207], v[170:173], v[80:83]
	v_mfma_f32_16x16x32_bf16 v[68:71], v[196:199], v[188:191], v[68:71]
	v_mfma_f32_16x16x32_bf16 v[64:67], v[204:207], v[188:191], v[64:67]
	v_mfma_f32_16x16x32_bf16 v[116:119], v[200:203], v[148:151], v[116:119]
	v_mfma_f32_16x16x32_bf16 v[112:115], v[208:211], v[148:151], v[112:115]
	v_mfma_f32_16x16x32_bf16 v[100:103], v[200:203], v[166:169], v[100:103]
	v_mfma_f32_16x16x32_bf16 v[96:99], v[208:211], v[166:169], v[96:99]
	v_mfma_f32_16x16x32_bf16 v[84:87], v[200:203], v[174:177], v[84:87]
	v_mfma_f32_16x16x32_bf16 v[80:83], v[208:211], v[174:177], v[80:83]
	v_mfma_f32_16x16x32_bf16 v[68:71], v[200:203], v[192:195], v[68:71]
	v_mfma_f32_16x16x32_bf16 v[64:67], v[208:211], v[192:195], v[64:67]
	s_setprio 0
	s_mov_b32 m0, s44
	s_mov_b64 s[100:101], s[36:37]
	s_barrier
	ds_read_b128 v[144:147], v186 offset:16384
	ds_read_b128 v[148:151], v186 offset:17408
	ds_read_b128 v[162:165], v186 offset:18432
	ds_read_b128 v[166:169], v186 offset:19456
	ds_read_b128 v[170:173], v186 offset:20480
	ds_read_b128 v[174:177], v186 offset:21504
	ds_read_b128 v[188:191], v186 offset:22528
	ds_read_b128 v[192:195], v186 offset:23552
	global_load_lds_dwordx4 v152, s[36:37]
	s_mov_b64 s[100:101], s[36:37]
	s_mov_b32 m0, s45
	s_nop 0
	global_load_lds_dwordx4 v154, s[36:37]
	s_barrier
	s_waitcnt lgkmcnt(0)
	s_setprio 1
	s_waitcnt lgkmcnt(0)
	v_mfma_f32_16x16x32_bf16 v[60:63], v[128:131], v[144:147], v[60:63]
	v_mfma_f32_16x16x32_bf16 v[56:59], v[136:139], v[144:147], v[56:59]
	v_mfma_f32_16x16x32_bf16 v[44:47], v[128:131], v[162:165], v[44:47]
	v_mfma_f32_16x16x32_bf16 v[40:43], v[136:139], v[162:165], v[40:43]
	v_mfma_f32_16x16x32_bf16 v[28:31], v[128:131], v[170:173], v[28:31]
	v_mfma_f32_16x16x32_bf16 v[24:27], v[136:139], v[170:173], v[24:27]
	v_mfma_f32_16x16x32_bf16 v[12:15], v[128:131], v[188:191], v[12:15]
	v_mfma_f32_16x16x32_bf16 v[8:11], v[136:139], v[188:191], v[8:11]
	v_mfma_f32_16x16x32_bf16 v[60:63], v[132:135], v[148:151], v[60:63]
	v_mfma_f32_16x16x32_bf16 v[56:59], v[140:143], v[148:151], v[56:59]
	v_mfma_f32_16x16x32_bf16 v[44:47], v[132:135], v[166:169], v[44:47]
	v_mfma_f32_16x16x32_bf16 v[40:43], v[140:143], v[166:169], v[40:43]
	v_mfma_f32_16x16x32_bf16 v[28:31], v[132:135], v[174:177], v[28:31]
	v_mfma_f32_16x16x32_bf16 v[24:27], v[140:143], v[174:177], v[24:27]
	v_mfma_f32_16x16x32_bf16 v[12:15], v[132:135], v[192:195], v[12:15]
	v_mfma_f32_16x16x32_bf16 v[8:11], v[140:143], v[192:195], v[8:11]
	s_setprio 0
	s_barrier
	s_add_u32 s26, s30, 0x160000
	s_addc_u32 s27, s31, 0
	s_add_i32 s63, s54, s43

; #define PG8_STAGE(bufoff, gbase, voff) do { _Pragma("unroll") for (int _i = 0; _i < 2; ++_i) \
;         __builtin_amdgcn_global_load_lds((const unsigned*)((const char*)(gbase) + (voff)[_i]), (LAS unsigned*)(lds + (bufoff) + ldsw + _i * 8192), 16, 0, 0); } while (0)
; template <class Epi>
; DI void gemm_phase(LAS unsigned char* lds, int wid, int K, int lda, int ldb, bool bperm, const Sched3& S, const Epi& E) {
;     ...
;             PG8_STAGE(PG8_SB(0, 1), b2 + hstepB, voffB);
	s_mov_b32 m0, s63
	s_nop 0
	global_load_lds_dwordx4 v152, s[26:27]

; #define PG8_STAGE(bufoff, gbase, voff) do { _Pragma("unroll") for (int _i = 0; _i < 2; ++_i) \
;         __builtin_amdgcn_global_load_lds((const unsigned*)((const char*)(gbase) + (voff)[_i]), (LAS unsigned*)(lds + (bufoff) + ldsw + _i * 8192), 16, 0, 0); } while (0)
; #define PG8_LDA(dst, b, h) do { _Pragma("unroll") for (int m = 0; m < 4; ++m) _Pragma("unroll") for (int k = 0; k < 2; ++k) dst[m][k] = *(const LAS bf16x8*)(lds + PG8_SA(b, h) + aoff + m * 2048 + k * 1024); } while (0)
; #define PG8_LDB(dst, b, h) do { _Pragma("unroll") for (int n = 0; n < 2; ++n) _Pragma("unroll") for (int k = 0; k < 2; ++k) dst[n][k] = *(const LAS bf16x8*)(lds + PG8_SB(b, h) + boff + n * 2048 + k * 1024); } while (0)
; #define PG8_MMA(ai, bj, At, Bt) do { __builtin_amdgcn_s_setprio(1); _Pragma("unroll") for (int m = 0; m < 4; ++m) _Pragma("unroll") for (int n = 0; n < 2; ++n) _Pragma("unroll") for (int k = 0; k < 2; ++k) \
;         acc[ai][bj][m][n] = __builtin_amdgcn_mfma_f32_16x16x32_bf16(Bt[n][k], At[m][k], acc[ai][bj][m][n], 0, 0, 0); __builtin_amdgcn_s_setprio(0); } while (0)
; #define PG8_WAIT_V(n) asm volatile("s_waitcnt vmcnt(" #n ")" ::: "memory")
; #define PG8_BAR __builtin_amdgcn_s_barrier()
; #define PG8_SCHED __builtin_amdgcn_sched_barrier(0)
; template <class Epi>
; DI void gemm_phase(LAS unsigned char* lds, int wid, int K, int lda, int ldb, bool bperm, const Sched3& S, const Epi& E) {
;     ...
;             PG8_STAGE(PG8_SB(0, 1), b2 + hstepB, voffB);
;             PG8_WAIT_V(6); PG8_BAR; if (full) PG8_MMA(1, 1, At, B1); PG8_BAR;
;             PG8_LDB(B0, 1, 0); PG8_SCHED; PG8_LDA(At, 1, 0); PG8_STAGE(PG8_SA(0, 1), a2 + h2, voffA);
	s_add_i32 m0, s63, 0x2000
	s_nop 0
	global_load_lds_dwordx4 v154, s[26:27]
	s_waitcnt vmcnt(6)
	s_barrier
	s_setprio 1
	v_mfma_f32_16x16x32_bf16 v[52:55], v[196:199], v[144:147], v[52:55]
	v_mfma_f32_16x16x32_bf16 v[48:51], v[204:207], v[144:147], v[48:51]
	v_mfma_f32_16x16x32_bf16 v[36:39], v[196:199], v[162:165], v[36:39]
	v_mfma_f32_16x16x32_bf16 v[32:35], v[204:207], v[162:165], v[32:35]
	v_mfma_f32_16x16x32_bf16 v[20:23], v[196:199], v[170:173], v[20:23]
	v_mfma_f32_16x16x32_bf16 v[16:19], v[204:207], v[170:173], v[16:19]
	v_mfma_f32_16x16x32_bf16 v[4:7], v[196:199], v[188:191], v[4:7]
	v_mfma_f32_16x16x32_bf16 v[0:3], v[204:207], v[188:191], v[0:3]
	v_mfma_f32_16x16x32_bf16 v[52:55], v[200:203], v[148:151], v[52:55]
	v_mfma_f32_16x16x32_bf16 v[48:51], v[208:211], v[148:151], v[48:51]
	v_mfma_f32_16x16x32_bf16 v[36:39], v[200:203], v[166:169], v[36:39]
	v_mfma_f32_16x16x32_bf16 v[32:35], v[208:211], v[166:169], v[32:35]
	v_mfma_f32_16x16x32_bf16 v[20:23], v[200:203], v[174:177], v[20:23]
	v_mfma_f32_16x16x32_bf16 v[16:19], v[208:211], v[174:177], v[16:19]
	v_mfma_f32_16x16x32_bf16 v[4:7], v[200:203], v[192:195], v[4:7]
	v_mfma_f32_16x16x32_bf16 v[0:3], v[208:211], v[192:195], v[0:3]
	s_setprio 0
	s_add_i32 s63, 0, 0x18000
	v_add_u32_e32 v140, s63, v181
	s_barrier
	ds_read_b128 v[128:131], v140
	ds_read_b128 v[132:135], v140 offset:1024
	ds_read_b128 v[136:139], v140 offset:2048
	ds_read_b128 v[140:143], v140 offset:3072
	s_add_u32 s26, s36, 0x160000
	s_addc_u32 s27, s37, 0
	s_mov_b32 m0, s46

; #define PG8_STAGE(bufoff, gbase, voff) do { _Pragma("unroll") for (int _i = 0; _i < 2; ++_i) \
;         __builtin_amdgcn_global_load_lds((const unsigned*)((const char*)(gbase) + (voff)[_i]), (LAS unsigned*)(lds + (bufoff) + ldsw + _i * 8192), 16, 0, 0); } while (0)
; #define PG8_LDA(dst, b, h) do { _Pragma("unroll") for (int m = 0; m < 4; ++m) _Pragma("unroll") for (int k = 0; k < 2; ++k) dst[m][k] = *(const LAS bf16x8*)(lds + PG8_SA(b, h) + aoff + m * 2048 + k * 1024); } while (0)
; #define PG8_LDB(dst, b, h) do { _Pragma("unroll") for (int n = 0; n < 2; ++n) _Pragma("unroll") for (int k = 0; k < 2; ++k) dst[n][k] = *(const LAS bf16x8*)(lds + PG8_SB(b, h) + boff + n * 2048 + k * 1024); } while (0)
; #define PG8_SCHED __builtin_amdgcn_sched_barrier(0)
; template <class Epi>
; DI void gemm_phase(LAS unsigned char* lds, int wid, int K, int lda, int ldb, bool bperm, const Sched3& S, const Epi& E) {
;     ...
;             PG8_LDB(B0, 1, 0); PG8_SCHED; PG8_LDA(At, 1, 0); PG8_STAGE(PG8_SA(0, 1), a2 + h2, voffA);
	ds_read_b128 v[144:147], v186 offset:32768
	ds_read_b128 v[148:151], v186 offset:33792
	ds_read_b128 v[162:165], v186 offset:34816
	ds_read_b128 v[166:169], v186 offset:35840
	ds_read_b128 v[170:173], v186 offset:36864
	ds_read_b128 v[174:177], v186 offset:37888
	ds_read_b128 v[188:191], v186 offset:38912
	ds_read_b128 v[192:195], v186 offset:39936
	global_load_lds_dwordx4 v152, s[26:27]

; #define PG8_STAGE(bufoff, gbase, voff) do { _Pragma("unroll") for (int _i = 0; _i < 2; ++_i) \
;         __builtin_amdgcn_global_load_lds((const unsigned*)((const char*)(gbase) + (voff)[_i]), (LAS unsigned*)(lds + (bufoff) + ldsw + _i * 8192), 16, 0, 0); } while (0)
; #define PG8_LDA(dst, b, h) do { _Pragma("unroll") for (int m = 0; m < 4; ++m) _Pragma("unroll") for (int k = 0; k < 2; ++k) dst[m][k] = *(const LAS bf16x8*)(lds + PG8_SA(b, h) + aoff + m * 2048 + k * 1024); } while (0)
; #define PG8_LDB(dst, b, h) do { _Pragma("unroll") for (int n = 0; n < 2; ++n) _Pragma("unroll") for (int k = 0; k < 2; ++k) dst[n][k] = *(const LAS bf16x8*)(lds + PG8_SB(b, h) + boff + n * 2048 + k * 1024); } while (0)
; #define PG8_MMA(ai, bj, At, Bt) do { __builtin_amdgcn_s_setprio(1); _Pragma("unroll") for (int m = 0; m < 4; ++m) _Pragma("unroll") for (int n = 0; n < 2; ++n) _Pragma("unroll") for (int k = 0; k < 2; ++k) \
;         acc[ai][bj][m][n] = __builtin_amdgcn_mfma_f32_16x16x32_bf16(Bt[n][k], At[m][k], acc[ai][bj][m][n], 0, 0, 0); __builtin_amdgcn_s_setprio(0); } while (0)
; #define PG8_WAIT_L(n) asm volatile("s_waitcnt lgkmcnt(" #n ")" ::: "memory")
; #define PG8_BAR __builtin_amdgcn_s_barrier()
; #define PG8_SCHED __builtin_amdgcn_sched_barrier(0)
; template <class Epi>
; DI void gemm_phase(LAS unsigned char* lds, int wid, int K, int lda, int ldb, bool bperm, const Sched3& S, const Epi& E) {
;     ...
;             PG8_LDB(B0, 1, 0); PG8_SCHED; PG8_LDA(At, 1, 0); PG8_STAGE(PG8_SA(0, 1), a2 + h2, voffA);
;             PG8_WAIT_L(8); PG8_BAR; PG8_WAIT_L(0); PG8_MMA(0, 0, At, B0); PG8_BAR; PG8_SCHED;
	s_mov_b32 m0, s47
	s_nop 0
	global_load_lds_dwordx4 v154, s[26:27]
	s_waitcnt lgkmcnt(8)
	s_barrier
	s_waitcnt lgkmcnt(0)
	s_setprio 1
	s_waitcnt lgkmcnt(0)
	v_mfma_f32_16x16x32_bf16 v[124:127], v[128:131], v[144:147], v[124:127]
	v_mfma_f32_16x16x32_bf16 v[120:123], v[136:139], v[144:147], v[120:123]
	v_mfma_f32_16x16x32_bf16 v[108:111], v[128:131], v[162:165], v[108:111]
	v_mfma_f32_16x16x32_bf16 v[104:107], v[136:139], v[162:165], v[104:107]
	v_mfma_f32_16x16x32_bf16 v[92:95], v[128:131], v[170:173], v[92:95]
	v_mfma_f32_16x16x32_bf16 v[88:91], v[136:139], v[170:173], v[88:91]
	v_mfma_f32_16x16x32_bf16 v[76:79], v[128:131], v[188:191], v[76:79]
	v_mfma_f32_16x16x32_bf16 v[72:75], v[136:139], v[188:191], v[72:75]
	v_mfma_f32_16x16x32_bf16 v[124:127], v[132:135], v[148:151], v[124:127]
	v_mfma_f32_16x16x32_bf16 v[120:123], v[140:143], v[148:151], v[120:123]
	v_mfma_f32_16x16x32_bf16 v[108:111], v[132:135], v[166:169], v[108:111]
	v_mfma_f32_16x16x32_bf16 v[104:107], v[140:143], v[166:169], v[104:107]
	v_mfma_f32_16x16x32_bf16 v[92:95], v[132:135], v[174:177], v[92:95]
	v_mfma_f32_16x16x32_bf16 v[88:91], v[140:143], v[174:177], v[88:91]
	v_mfma_f32_16x16x32_bf16 v[76:79], v[132:135], v[192:195], v[76:79]
	v_mfma_f32_16x16x32_bf16 v[72:75], v[140:143], v[192:195], v[72:75]
	s_setprio 0
	s_barrier
	s_add_i32 s36, 0, 0x1c000
	s_add_i32 s26, s63, s43
	v_add_u32_e32 v208, s36, v181

; #define PG8_STAGE(bufoff, gbase, voff) do { _Pragma("unroll") for (int _i = 0; _i < 2; ++_i) \
;         __builtin_amdgcn_global_load_lds((const unsigned*)((const char*)(gbase) + (voff)[_i]), (LAS unsigned*)(lds + (bufoff) + ldsw + _i * 8192), 16, 0, 0); } while (0)
; #define PG8_LDB(dst, b, h) do { _Pragma("unroll") for (int n = 0; n < 2; ++n) _Pragma("unroll") for (int k = 0; k < 2; ++k) dst[n][k] = *(const LAS bf16x8*)(lds + PG8_SB(b, h) + boff + n * 2048 + k * 1024); } while (0)
; template <class Epi>
; DI void gemm_phase(LAS unsigned char* lds, int wid, int K, int lda, int ldb, bool bperm, const Sched3& S, const Epi& E) {
;     ...
;             PG8_LDB(B1, 1, 1); PG8_STAGE(PG8_SB(1, 0), b3, voffB);
	s_sub_i32 m0, s26, 0x80
	ds_read_b128 v[196:199], v208
	ds_read_b128 v[200:203], v208 offset:1024
	ds_read_b128 v[204:207], v208 offset:2048
	ds_read_b128 v[208:211], v208 offset:3072
	global_load_lds_dwordx4 v152, s[30:31] offset:128

; #define PG8_STAGE(bufoff, gbase, voff) do { _Pragma("unroll") for (int _i = 0; _i < 2; ++_i) \
;         __builtin_amdgcn_global_load_lds((const unsigned*)((const char*)(gbase) + (voff)[_i]), (LAS unsigned*)(lds + (bufoff) + ldsw + _i * 8192), 16, 0, 0); } while (0)
; #define PG8_LDB(dst, b, h) do { _Pragma("unroll") for (int n = 0; n < 2; ++n) _Pragma("unroll") for (int k = 0; k < 2; ++k) dst[n][k] = *(const LAS bf16x8*)(lds + PG8_SB(b, h) + boff + n * 2048 + k * 1024); } while (0)
; #define PG8_MMA(ai, bj, At, Bt) do { __builtin_amdgcn_s_setprio(1); _Pragma("unroll") for (int m = 0; m < 4; ++m) _Pragma("unroll") for (int n = 0; n < 2; ++n) _Pragma("unroll") for (int k = 0; k < 2; ++k) \
;         acc[ai][bj][m][n] = __builtin_amdgcn_mfma_f32_16x16x32_bf16(Bt[n][k], At[m][k], acc[ai][bj][m][n], 0, 0, 0); __builtin_amdgcn_s_setprio(0); } while (0)
; #define PG8_WAIT_L(n) asm volatile("s_waitcnt lgkmcnt(" #n ")" ::: "memory")
; #define PG8_BAR __builtin_amdgcn_s_barrier()
; template <class Epi>
; DI void gemm_phase(LAS unsigned char* lds, int wid, int K, int lda, int ldb, bool bperm, const Sched3& S, const Epi& E) {
;     ...
;             PG8_LDB(B1, 1, 1); PG8_STAGE(PG8_SB(1, 0), b3, voffB);
;             PG8_BAR; PG8_WAIT_L(0); PG8_MMA(0, 1, At, B1); PG8_BAR;
	s_add_i32 m0, s26, 0x1f80
	s_nop 0
	global_load_lds_dwordx4 v154, s[30:31] offset:128
	s_barrier
	s_waitcnt lgkmcnt(0)
	s_setprio 1
	s_waitcnt lgkmcnt(0)
	v_mfma_f32_16x16x32_bf16 v[116:119], v[196:199], v[144:147], v[116:119]
	v_mfma_f32_16x16x32_bf16 v[112:115], v[204:207], v[144:147], v[112:115]
	v_mfma_f32_16x16x32_bf16 v[100:103], v[196:199], v[162:165], v[100:103]
	v_mfma_f32_16x16x32_bf16 v[96:99], v[204:207], v[162:165], v[96:99]
	v_mfma_f32_16x16x32_bf16 v[84:87], v[196:199], v[170:173], v[84:87]
	v_mfma_f32_16x16x32_bf16 v[80:83], v[204:207], v[170:173], v[80:83]
	v_mfma_f32_16x16x32_bf16 v[68:71], v[196:199], v[188:191], v[68:71]
	v_mfma_f32_16x16x32_bf16 v[64:67], v[204:207], v[188:191], v[64:67]
	v_mfma_f32_16x16x32_bf16 v[116:119], v[200:203], v[148:151], v[116:119]
	v_mfma_f32_16x16x32_bf16 v[112:115], v[208:211], v[148:151], v[112:115]
	v_mfma_f32_16x16x32_bf16 v[100:103], v[200:203], v[166:169], v[100:103]
	v_mfma_f32_16x16x32_bf16 v[96:99], v[208:211], v[166:169], v[96:99]
	v_mfma_f32_16x16x32_bf16 v[84:87], v[200:203], v[174:177], v[84:87]
	v_mfma_f32_16x16x32_bf16 v[80:83], v[208:211], v[174:177], v[80:83]
	v_mfma_f32_16x16x32_bf16 v[68:71], v[200:203], v[192:195], v[68:71]
	v_mfma_f32_16x16x32_bf16 v[64:67], v[208:211], v[192:195], v[64:67]
	s_setprio 0
	s_sub_i32 m0, s49, 0x80

; #define PG8_STAGE(bufoff, gbase, voff) do { _Pragma("unroll") for (int _i = 0; _i < 2; ++_i) \
;         __builtin_amdgcn_global_load_lds((const unsigned*)((const char*)(gbase) + (voff)[_i]), (LAS unsigned*)(lds + (bufoff) + ldsw + _i * 8192), 16, 0, 0); } while (0)
; #define PG8_LDA(dst, b, h) do { _Pragma("unroll") for (int m = 0; m < 4; ++m) _Pragma("unroll") for (int k = 0; k < 2; ++k) dst[m][k] = *(const LAS bf16x8*)(lds + PG8_SA(b, h) + aoff + m * 2048 + k * 1024); } while (0)
; template <class Epi>
; DI void gemm_phase(LAS unsigned char* lds, int wid, int K, int lda, int ldb, bool bperm, const Sched3& S, const Epi& E) {
;     ...
;             PG8_LDA(At, 1, 1); PG8_STAGE(PG8_SA(1, 0), a3, voffA);
	s_barrier
	ds_read_b128 v[144:147], v186 offset:49152
	ds_read_b128 v[148:151], v186 offset:50176
	ds_read_b128 v[162:165], v186 offset:51200
	ds_read_b128 v[166:169], v186 offset:52224
	ds_read_b128 v[170:173], v186 offset:53248
	ds_read_b128 v[174:177], v186 offset:54272
	ds_read_b128 v[188:191], v186 offset:55296
	ds_read_b128 v[192:195], v186 offset:56320
	global_load_lds_dwordx4 v152, s[100:101] offset:128

; #define PG8_STAGE(bufoff, gbase, voff) do { _Pragma("unroll") for (int _i = 0; _i < 2; ++_i) \
;         __builtin_amdgcn_global_load_lds((const unsigned*)((const char*)(gbase) + (voff)[_i]), (LAS unsigned*)(lds + (bufoff) + ldsw + _i * 8192), 16, 0, 0); } while (0)
; #define PG8_LDA(dst, b, h) do { _Pragma("unroll") for (int m = 0; m < 4; ++m) _Pragma("unroll") for (int k = 0; k < 2; ++k) dst[m][k] = *(const LAS bf16x8*)(lds + PG8_SA(b, h) + aoff + m * 2048 + k * 1024); } while (0)
; #define PG8_MMA(ai, bj, At, Bt) do { __builtin_amdgcn_s_setprio(1); _Pragma("unroll") for (int m = 0; m < 4; ++m) _Pragma("unroll") for (int n = 0; n < 2; ++n) _Pragma("unroll") for (int k = 0; k < 2; ++k) \
;         acc[ai][bj][m][n] = __builtin_amdgcn_mfma_f32_16x16x32_bf16(Bt[n][k], At[m][k], acc[ai][bj][m][n], 0, 0, 0); __builtin_amdgcn_s_setprio(0); } while (0)
; #define PG8_WAIT_L(n) asm volatile("s_waitcnt lgkmcnt(" #n ")" ::: "memory")
; #define PG8_BAR __builtin_amdgcn_s_barrier()
; #define PG8_SCHED __builtin_amdgcn_sched_barrier(0)
; template <class Epi>
; DI void gemm_phase(LAS unsigned char* lds, int wid, int K, int lda, int ldb, bool bperm, const Sched3& S, const Epi& E) {
;     ...
;             PG8_LDA(At, 1, 1); PG8_STAGE(PG8_SA(1, 0), a3, voffA);
;             PG8_BAR; PG8_WAIT_L(0); if (full) PG8_MMA(1, 0, At, B0); PG8_BAR; PG8_SCHED;
	s_sub_i32 m0, s50, 0x80
	s_nop 0
	global_load_lds_dwordx4 v154, s[100:101] offset:128
	s_barrier
	s_waitcnt lgkmcnt(0)
	s_setprio 1
	s_waitcnt lgkmcnt(0)
	v_mfma_f32_16x16x32_bf16 v[60:63], v[128:131], v[144:147], v[60:63]
	v_mfma_f32_16x16x32_bf16 v[56:59], v[136:139], v[144:147], v[56:59]
	v_mfma_f32_16x16x32_bf16 v[44:47], v[128:131], v[162:165], v[44:47]
	v_mfma_f32_16x16x32_bf16 v[40:43], v[136:139], v[162:165], v[40:43]
	v_mfma_f32_16x16x32_bf16 v[28:31], v[128:131], v[170:173], v[28:31]
	v_mfma_f32_16x16x32_bf16 v[24:27], v[136:139], v[170:173], v[24:27]
	v_mfma_f32_16x16x32_bf16 v[12:15], v[128:131], v[188:191], v[12:15]
	v_mfma_f32_16x16x32_bf16 v[8:11], v[136:139], v[188:191], v[8:11]
	v_mfma_f32_16x16x32_bf16 v[60:63], v[132:135], v[148:151], v[60:63]
	v_mfma_f32_16x16x32_bf16 v[56:59], v[140:143], v[148:151], v[56:59]
	v_mfma_f32_16x16x32_bf16 v[44:47], v[132:135], v[166:169], v[44:47]
	v_mfma_f32_16x16x32_bf16 v[40:43], v[140:143], v[166:169], v[40:43]
	v_mfma_f32_16x16x32_bf16 v[28:31], v[132:135], v[174:177], v[28:31]
	v_mfma_f32_16x16x32_bf16 v[24:27], v[140:143], v[174:177], v[24:27]
	v_mfma_f32_16x16x32_bf16 v[12:15], v[132:135], v[192:195], v[12:15]
	v_mfma_f32_16x16x32_bf16 v[8:11], v[140:143], v[192:195], v[8:11]
	s_setprio 0
	s_barrier
	s_add_u32 s26, s30, 0x160080
	s_addc_u32 s27, s31, 0
	s_add_i32 s30, s36, s43

; #define PG8_STAGE(bufoff, gbase, voff) do { _Pragma("unroll") for (int _i = 0; _i < 2; ++_i) \
;         __builtin_amdgcn_global_load_lds((const unsigned*)((const char*)(gbase) + (voff)[_i]), (LAS unsigned*)(lds + (bufoff) + ldsw + _i * 8192), 16, 0, 0); } while (0)
; template <class Epi>
; DI void gemm_phase(LAS unsigned char* lds, int wid, int K, int lda, int ldb, bool bperm, const Sched3& S, const Epi& E) {
;     ...
;             PG8_STAGE(PG8_SB(1, 1), b3 + hstepB, voffB);
	s_mov_b32 m0, s30
	s_nop 0
	global_load_lds_dwordx4 v152, s[26:27]

; DI u32x2 pk4(f32x4 v) { u32x2 r; r.x = pk2(v[0], v[1]); r.y = pk2(v[2], v[3]); return r; }
; DI float bf_lo(unsigned w) { return __uint_as_float(w << 16); }
; DI float bf_hi(unsigned w) { return __uint_as_float(w & 0xffff0000u); }
; #define PG8_STAGE(bufoff, gbase, voff) do { _Pragma("unroll") for (int _i = 0; _i < 2; ++_i) \
;         __builtin_amdgcn_global_load_lds((const unsigned*)((const char*)(gbase) + (voff)[_i]), (LAS unsigned*)(lds + (bufoff) + ldsw + _i * 8192), 16, 0, 0); } while (0)
; #define PG8_WAIT_V(n) asm volatile("s_waitcnt vmcnt(" #n ")" ::: "memory")
; #define PG8_BAR __builtin_amdgcn_s_barrier()
; template <class Epi>
; DI void gemm_phase(LAS unsigned char* lds, int wid, int K, int lda, int ldb, bool bperm, const Sched3& S, const Epi& E) {
;     ...
;             PG8_STAGE(PG8_SB(1, 1), b3 + hstepB, voffB);
;             PG8_WAIT_V(6); PG8_BAR; if (full) PG8_MMA(1, 1, At, B1); PG8_BAR;
;     DI void operator()(const Acc& acc, const Unit& u, int wr, int wc, int fr, int fq) const {
;     ...
;                 for (int m = 0; m < 4; ++m) { const size_t o = (size_t)(row0 + ai * HALF + m * 16) * 2048 + colp;
;                     if (PH == 4) { COLS4 xo[m][bj][n] = *(const f32x4*)(p.x + o + bj * HALF + n * 4); }
;                     else {
; #pragma unroll
;                         for (int bj = 0; bj < 2; ++bj) { const u32x4 w = *(const u32x4*)(WSB(OFF_XB) + o + bj * HALF);
;                             xo[m][bj][0] = (f32x4){bf_lo(w.x), bf_hi(w.x), bf_lo(w.y), bf_hi(w.y)}; xo[m][bj][1] = (f32x4){bf_lo(w.z), bf_hi(w.z), bf_lo(w.w), bf_hi(w.w)}; } } }
; #pragma unroll
;                 for (int m = 0; m < 4; ++m) { const int r = row0 + ai * HALF + m * 16; const size_t o = (size_t)r * 2048 + colp; float part = 0.f;
; #pragma unroll
;                     for (int bj = 0; bj < 2; ++bj) { const f32x4 x0 = xo[m][bj][0] + acc[ai][bj][m][0], x1 = xo[m][bj][1] + acc[ai][bj][m][1];
;                         const u32x2 h0 = pk4(x0), h1 = pk4(x1);
;                         *(u32x4*)(WSB(OFF_XB) + o + bj * HALF) = (u32x4){h0.x, h0.y, h1.x, h1.y};
;                         part += x0[0] * x0[0] + x0[1] * x0[1] + x0[2] * x0[2] + x0[3] * x0[3] + x1[0] * x1[0] + x1[1] * x1[1] + x1[2] * x1[2] + x1[3] * x1[3]; }
;                     part += __shfl_xor(part, 16); part += __shfl_xor(part, 32);
;                     if (fq == 0) unsafeAtomicAdd(ssq + r, part);
	s_add_i32 m0, s30, 0x2000
	s_nop 0
	global_load_lds_dwordx4 v154, s[26:27]
	s_waitcnt vmcnt(6)
	s_barrier
	s_setprio 1
	v_mfma_f32_16x16x32_bf16 v[52:55], v[196:199], v[144:147], v[52:55]
	v_mfma_f32_16x16x32_bf16 v[48:51], v[204:207], v[144:147], v[48:51]
	v_mfma_f32_16x16x32_bf16 v[36:39], v[196:199], v[162:165], v[36:39]
	v_mfma_f32_16x16x32_bf16 v[32:35], v[204:207], v[162:165], v[32:35]
	v_mfma_f32_16x16x32_bf16 v[20:23], v[196:199], v[170:173], v[20:23]
	v_mfma_f32_16x16x32_bf16 v[16:19], v[204:207], v[170:173], v[16:19]
	v_mfma_f32_16x16x32_bf16 v[4:7], v[196:199], v[188:191], v[4:7]
	v_mfma_f32_16x16x32_bf16 v[0:3], v[204:207], v[188:191], v[0:3]
	v_mfma_f32_16x16x32_bf16 v[52:55], v[200:203], v[148:151], v[52:55]
	v_mfma_f32_16x16x32_bf16 v[48:51], v[208:211], v[148:151], v[48:51]
	v_mfma_f32_16x16x32_bf16 v[36:39], v[200:203], v[166:169], v[36:39]
	v_mfma_f32_16x16x32_bf16 v[32:35], v[208:211], v[166:169], v[32:35]
	v_mfma_f32_16x16x32_bf16 v[20:23], v[200:203], v[174:177], v[20:23]
	v_mfma_f32_16x16x32_bf16 v[16:19], v[208:211], v[174:177], v[16:19]
	v_mfma_f32_16x16x32_bf16 v[4:7], v[200:203], v[192:195], v[4:7]
	v_mfma_f32_16x16x32_bf16 v[0:3], v[208:211], v[192:195], v[0:3]
	s_setprio 0
	s_add_i32 s62, s62, 2
	s_add_u32 s60, s60, 0x100
	s_addc_u32 s61, s61, 0
	s_cmpk_gt_u32 s62, 0x55
	s_mov_b64 s[26:27], s[28:29]
	s_cbranch_scc0 .Lkrot_3_head
.Lkrot_3_exit:
	s_barrier
.Lpeel_3_exit:
	v_lshl_add_u32 v128, s58, 8, v182
	v_lshl_add_u32 v166, s59, 8, v180
	v_ashrrev_i32_e32 v129, 31, v128
	v_lshlrev_b64 v[162:163], 1, v[128:129]
	v_ashrrev_i32_e32 v167, 31, v166
	v_lshl_add_u64 v[164:165], s[16:17], 0, v[162:163]
	v_lshlrev_b64 v[196:197], 12, v[166:167]
	v_lshl_add_u64 v[128:129], v[164:165], 0, v[196:197]
	global_load_dwordx4 v[188:191], v[128:129], off
	global_load_dwordx4 v[192:195], v[128:129], off offset:256
	v_or_b32_e32 v176, 16, v166
	v_or_b32_e32 v172, 32, v166
	v_or_b32_e32 v168, 48, v166
	v_ashrrev_i32_e32 v177, 31, v176
	v_ashrrev_i32_e32 v173, 31, v172
	v_ashrrev_i32_e32 v169, 31, v168
	v_lshlrev_b64 v[178:179], 12, v[176:177]
	v_lshlrev_b64 v[174:175], 12, v[172:173]
	v_lshlrev_b64 v[170:171], 12, v[168:169]
	v_lshl_add_u64 v[128:129], v[164:165], 0, v[178:179]
	v_lshl_add_u64 v[130:131], v[164:165], 0, v[174:175]
	v_lshl_add_u64 v[198:199], v[164:165], 0, v[170:171]
	global_load_dwordx4 v[148:151], v[128:129], off
	global_load_dwordx4 v[144:147], v[128:129], off offset:256
	global_load_dwordx4 v[140:143], v[130:131], off
	global_load_dwordx4 v[136:139], v[130:131], off offset:256
	global_load_dwordx4 v[132:135], v[198:199], off
	s_nop 0
	global_load_dwordx4 v[128:131], v[198:199], off offset:256
	v_lshl_add_u64 v[198:199], s[16:17], 0, v[196:197]
	v_lshl_add_u64 v[198:199], v[198:199], 0, v[162:163]
	v_lshl_add_u64 v[196:197], s[10:11], 0, v[196:197]
	v_lshl_add_u64 v[196:197], v[196:197], 0, v[162:163]
	s_waitcnt vmcnt(0)
	v_lshlrev_b32_e32 v200, 16, v188
	v_and_b32_e32 v201, 0xffff0000, v188
	v_lshlrev_b32_e32 v188, 16, v189
	v_and_b32_e32 v189, 0xffff0000, v189
	v_lshlrev_b32_e32 v204, 16, v192
	v_and_b32_e32 v205, 0xffff0000, v192
	v_lshlrev_b32_e32 v192, 16, v193
	v_and_b32_e32 v193, 0xffff0000, v193
	v_lshlrev_b32_e32 v206, 16, v194
	v_and_b32_e32 v207, 0xffff0000, v194
	v_pk_add_f32 v[126:127], v[126:127], v[188:189]
	v_pk_add_f32 v[124:125], v[124:125], v[200:201]
	v_pk_add_f32 v[188:189], v[116:117], v[204:205]
	v_pk_add_f32 v[118:119], v[118:119], v[192:193]
	v_pk_add_f32 v[192:193], v[112:113], v[206:207]
	v_cvt_pk_bf16_f32 v112, v124, v125
	v_mul_f32_e32 v117, v125, v125
	v_mul_f32_e32 v125, v189, v189
	v_fmac_f32_e32 v117, v124, v124
	v_fmac_f32_e32 v125, v188, v188
	v_lshlrev_b32_e32 v202, 16, v190
	v_and_b32_e32 v203, 0xffff0000, v190
	v_fmac_f32_e32 v117, v126, v126
	v_fmac_f32_e32 v125, v118, v118
	v_pk_add_f32 v[120:121], v[120:121], v[202:203]
	v_fmac_f32_e32 v117, v127, v127
	v_fmac_f32_e32 v125, v119, v119
	v_lshlrev_b32_e32 v190, 16, v191
	v_and_b32_e32 v191, 0xffff0000, v191
	v_lshlrev_b32_e32 v194, 16, v195
	v_and_b32_e32 v195, 0xffff0000, v195
	v_fmac_f32_e32 v117, v120, v120
	v_fmac_f32_e32 v125, v192, v192
	v_pk_add_f32 v[122:123], v[122:123], v[190:191]
	v_pk_add_f32 v[190:191], v[114:115], v[194:195]
	v_fmac_f32_e32 v117, v121, v121
	v_fmac_f32_e32 v125, v193, v193
	v_fmac_f32_e32 v117, v122, v122
	v_fmac_f32_e32 v125, v190, v190
	v_fmac_f32_e32 v117, v123, v123
	v_fmac_f32_e32 v125, v191, v191
	v_cvt_pk_bf16_f32 v114, v120, v121
	v_add_f32_e32 v120, v117, v125
	ds_bpermute_b32 v121, v183, v120
	v_cvt_pk_bf16_f32 v113, v126, v127
	v_cvt_pk_bf16_f32 v115, v122, v123
	global_store_dwordx4 v[198:199], v[112:115], off sc1
	v_cvt_pk_bf16_f32 v116, v188, v189
	v_cvt_pk_bf16_f32 v117, v118, v119
	s_waitcnt lgkmcnt(0)
	v_add_f32_e32 v112, v120, v121
	ds_bpermute_b32 v113, v184, v112
	v_add_co_u32_e32 v114, vcc, s55, v196
	v_cvt_pk_bf16_f32 v118, v192, v193
	v_cvt_pk_bf16_f32 v119, v190, v191
	v_addc_co_u32_e32 v115, vcc, 0, v197, vcc
	global_store_dwordx4 v[114:115], v[116:119], off offset:256 sc1
	s_and_saveexec_b64 s[22:23], s[2:3]
	s_cbranch_execz .LBB0_788
	s_waitcnt lgkmcnt(0)
	v_add_f32_e32 v114, v112, v113
	v_lshl_add_u64 v[112:113], v[166:167], 2, s[14:15]
	global_atomic_add_f32 v[112:113], v114, off

; #define PG8_STAGE(bufoff, gbase, voff) do { _Pragma("unroll") for (int _i = 0; _i < 2; ++_i) \
;         __builtin_amdgcn_global_load_lds((const unsigned*)((const char*)(gbase) + (voff)[_i]), (LAS unsigned*)(lds + (bufoff) + ldsw + _i * 8192), 16, 0, 0); } while (0)
; #define PG8_LDA(dst, b, h) do { _Pragma("unroll") for (int m = 0; m < 4; ++m) _Pragma("unroll") for (int k = 0; k < 2; ++k) dst[m][k] = *(const LAS bf16x8*)(lds + PG8_SA(b, h) + aoff + m * 2048 + k * 1024); } while (0)
; #define PG8_LDB(dst, b, h) do { _Pragma("unroll") for (int n = 0; n < 2; ++n) _Pragma("unroll") for (int k = 0; k < 2; ++k) dst[n][k] = *(const LAS bf16x8*)(lds + PG8_SB(b, h) + boff + n * 2048 + k * 1024); } while (0)
; #define PG8_SCHED __builtin_amdgcn_sched_barrier(0)
; template <class Epi>
; DI void gemm_phase(LAS unsigned char* lds, int wid, int K, int lda, int ldb, bool bperm, const Sched3& S, const Epi& E) {
;     ...
;         const char* nA = has_next ? nxt.A : cA; const char* nB = has_next ? nxt.B : cB; const size_t nhA = has_next ? (nxt.half ? (size_t)0 : hstepA) : hA; const bool full = (cur.half == 0);
;         for (int t = 0; t < nt; t += 2) {
;             const bool last = (t == nt - 2);
;             const char* a1 = cA + (size_t)(t + 1) * kstep;
;             const char* a2 = last ? nA : cA + (size_t)(t + 2) * kstep; const char* b2 = last ? nB : cB + (size_t)(t + 2) * kstep;
;             const char* a3 = a2 + kstep; const char* b3 = b2 + kstep; const size_t h2 = last ? nhA : hA;
;             PG8_LDB(B0, 0, 0); PG8_SCHED; PG8_LDA(At, 0, 0); PG8_STAGE(PG8_SA(1, 1), a1 + hA, voffA);
.LBB0_872:
	s_add_u32 s36, s36, 0x80080
	s_addc_u32 s37, s37, 0
	s_add_u32 s19, s38, 0x100
	s_nop 0
	s_addc_u32 s21, s39, 0
	s_mov_b32 s27, -2
	s_waitcnt lgkmcnt(0)
	ds_read_b128 v[128:131], v189
	ds_read_b128 v[132:135], v189 offset:1024
	ds_read_b128 v[136:139], v189 offset:2048
	ds_read_b128 v[140:143], v189 offset:3072
	s_add_u32 s38, s36, 0xfff80080
	s_addc_u32 s39, s37, -1
	s_cmp_eq_u32 s27, 28
	s_cselect_b32 s41, s29, s39
	s_cselect_b32 s40, s28, s38
	s_cselect_b32 s39, s31, s21
	s_cselect_b32 s38, s30, s19

; #define PG8_STAGE(bufoff, gbase, voff) do { _Pragma("unroll") for (int _i = 0; _i < 2; ++_i) \
;         __builtin_amdgcn_global_load_lds((const unsigned*)((const char*)(gbase) + (voff)[_i]), (LAS unsigned*)(lds + (bufoff) + ldsw + _i * 8192), 16, 0, 0); } while (0)
; #define PG8_LDA(dst, b, h) do { _Pragma("unroll") for (int m = 0; m < 4; ++m) _Pragma("unroll") for (int k = 0; k < 2; ++k) dst[m][k] = *(const LAS bf16x8*)(lds + PG8_SA(b, h) + aoff + m * 2048 + k * 1024); } while (0)
; #define PG8_LDB(dst, b, h) do { _Pragma("unroll") for (int n = 0; n < 2; ++n) _Pragma("unroll") for (int k = 0; k < 2; ++k) dst[n][k] = *(const LAS bf16x8*)(lds + PG8_SB(b, h) + boff + n * 2048 + k * 1024); } while (0)
; #define PG8_SCHED __builtin_amdgcn_sched_barrier(0)
; template <class Epi>
; DI void gemm_phase(LAS unsigned char* lds, int wid, int K, int lda, int ldb, bool bperm, const Sched3& S, const Epi& E) {
;     ...
;             PG8_LDB(B0, 0, 0); PG8_SCHED; PG8_LDA(At, 0, 0); PG8_STAGE(PG8_SA(1, 1), a1 + hA, voffA);
	s_add_i32 m0, s48, 0xc000
	ds_read_b128 v[180:183], v195
	ds_read_b128 v[190:193], v195 offset:1024
	ds_read_b128 v[200:203], v195 offset:2048
	ds_read_b128 v[204:207], v195 offset:3072
	ds_read_b128 v[208:211], v195 offset:4096
	ds_read_b128 v[212:215], v195 offset:5120
	ds_read_b128 v[216:219], v195 offset:6144
	ds_read_b128 v[224:227], v195 offset:7168
	global_load_lds_dwordx4 v160, s[36:37]

; #define PG8_STAGE(bufoff, gbase, voff) do { _Pragma("unroll") for (int _i = 0; _i < 2; ++_i) \
;         __builtin_amdgcn_global_load_lds((const unsigned*)((const char*)(gbase) + (voff)[_i]), (LAS unsigned*)(lds + (bufoff) + ldsw + _i * 8192), 16, 0, 0); } while (0)
; #define PG8_LDA(dst, b, h) do { _Pragma("unroll") for (int m = 0; m < 4; ++m) _Pragma("unroll") for (int k = 0; k < 2; ++k) dst[m][k] = *(const LAS bf16x8*)(lds + PG8_SA(b, h) + aoff + m * 2048 + k * 1024); } while (0)
; #define PG8_LDB(dst, b, h) do { _Pragma("unroll") for (int n = 0; n < 2; ++n) _Pragma("unroll") for (int k = 0; k < 2; ++k) dst[n][k] = *(const LAS bf16x8*)(lds + PG8_SB(b, h) + boff + n * 2048 + k * 1024); } while (0)
; #define PG8_MMA(ai, bj, At, Bt) do { __builtin_amdgcn_s_setprio(1); _Pragma("unroll") for (int m = 0; m < 4; ++m) _Pragma("unroll") for (int n = 0; n < 2; ++n) _Pragma("unroll") for (int k = 0; k < 2; ++k) \
;         acc[ai][bj][m][n] = __builtin_amdgcn_mfma_f32_16x16x32_bf16(Bt[n][k], At[m][k], acc[ai][bj][m][n], 0, 0, 0); __builtin_amdgcn_s_setprio(0); } while (0)
; #define PG8_WAIT_L(n) asm volatile("s_waitcnt lgkmcnt(" #n ")" ::: "memory")
; #define PG8_BAR __builtin_amdgcn_s_barrier()
; #define PG8_SCHED __builtin_amdgcn_sched_barrier(0)
; template <class Epi>
; DI void gemm_phase(LAS unsigned char* lds, int wid, int K, int lda, int ldb, bool bperm, const Sched3& S, const Epi& E) {
;     ...
;             PG8_LDB(B0, 0, 0); PG8_SCHED; PG8_LDA(At, 0, 0); PG8_STAGE(PG8_SA(1, 1), a1 + hA, voffA);
;             PG8_WAIT_L(8); PG8_BAR; PG8_WAIT_L(0); PG8_MMA(0, 0, At, B0); PG8_BAR; PG8_SCHED;
	s_add_i32 m0, s48, 0xe000
	s_nop 0
	global_load_lds_dwordx4 v162, s[36:37]
	s_waitcnt lgkmcnt(8)
	s_barrier
	s_waitcnt lgkmcnt(0)
	s_setprio 1
	s_waitcnt lgkmcnt(0)
	v_mfma_f32_16x16x32_bf16 v[124:127], v[128:131], v[180:183], 0
	v_mfma_f32_16x16x32_bf16 v[120:123], v[136:139], v[180:183], 0
	v_mfma_f32_16x16x32_bf16 v[108:111], v[128:131], v[200:203], 0
	v_mfma_f32_16x16x32_bf16 v[104:107], v[136:139], v[200:203], 0
	v_mfma_f32_16x16x32_bf16 v[92:95], v[128:131], v[208:211], 0
	v_mfma_f32_16x16x32_bf16 v[88:91], v[136:139], v[208:211], 0
	v_mfma_f32_16x16x32_bf16 v[76:79], v[128:131], v[216:219], 0
	v_mfma_f32_16x16x32_bf16 v[72:75], v[136:139], v[216:219], 0
	v_mfma_f32_16x16x32_bf16 v[124:127], v[132:135], v[190:193], v[124:127]
	v_mfma_f32_16x16x32_bf16 v[120:123], v[140:143], v[190:193], v[120:123]
	v_mfma_f32_16x16x32_bf16 v[108:111], v[132:135], v[204:207], v[108:111]
	v_mfma_f32_16x16x32_bf16 v[104:107], v[140:143], v[204:207], v[104:107]
	v_mfma_f32_16x16x32_bf16 v[92:95], v[132:135], v[212:215], v[92:95]
	v_mfma_f32_16x16x32_bf16 v[88:91], v[140:143], v[212:215], v[88:91]
	v_mfma_f32_16x16x32_bf16 v[76:79], v[132:135], v[224:227], v[76:79]
	v_mfma_f32_16x16x32_bf16 v[72:75], v[140:143], v[224:227], v[72:75]
	s_setprio 0
	s_barrier
	s_add_i32 s64, s59, s47

; #define PG8_STAGE(bufoff, gbase, voff) do { _Pragma("unroll") for (int _i = 0; _i < 2; ++_i) \
;         __builtin_amdgcn_global_load_lds((const unsigned*)((const char*)(gbase) + (voff)[_i]), (LAS unsigned*)(lds + (bufoff) + ldsw + _i * 8192), 16, 0, 0); } while (0)
; #define PG8_LDB(dst, b, h) do { _Pragma("unroll") for (int n = 0; n < 2; ++n) _Pragma("unroll") for (int k = 0; k < 2; ++k) dst[n][k] = *(const LAS bf16x8*)(lds + PG8_SB(b, h) + boff + n * 2048 + k * 1024); } while (0)
; template <class Epi>
; DI void gemm_phase(LAS unsigned char* lds, int wid, int K, int lda, int ldb, bool bperm, const Sched3& S, const Epi& E) {
;     ...
;             PG8_LDB(B1, 0, 1); PG8_STAGE(PG8_SB(0, 0), b2, voffB);
	s_mov_b32 m0, s64
	ds_read_b128 v[228:231], v197
	ds_read_b128 v[232:235], v197 offset:1024
	ds_read_b128 v[236:239], v197 offset:2048
	ds_read_b128 v[240:243], v197 offset:3072
	global_load_lds_dwordx4 v146, s[38:39]

; #define PG8_STAGE(bufoff, gbase, voff) do { _Pragma("unroll") for (int _i = 0; _i < 2; ++_i) \
;         __builtin_amdgcn_global_load_lds((const unsigned*)((const char*)(gbase) + (voff)[_i]), (LAS unsigned*)(lds + (bufoff) + ldsw + _i * 8192), 16, 0, 0); } while (0)
; #define PG8_LDA(dst, b, h) do { _Pragma("unroll") for (int m = 0; m < 4; ++m) _Pragma("unroll") for (int k = 0; k < 2; ++k) dst[m][k] = *(const LAS bf16x8*)(lds + PG8_SA(b, h) + aoff + m * 2048 + k * 1024); } while (0)
; #define PG8_LDB(dst, b, h) do { _Pragma("unroll") for (int n = 0; n < 2; ++n) _Pragma("unroll") for (int k = 0; k < 2; ++k) dst[n][k] = *(const LAS bf16x8*)(lds + PG8_SB(b, h) + boff + n * 2048 + k * 1024); } while (0)
; #define PG8_MMA(ai, bj, At, Bt) do { __builtin_amdgcn_s_setprio(1); _Pragma("unroll") for (int m = 0; m < 4; ++m) _Pragma("unroll") for (int n = 0; n < 2; ++n) _Pragma("unroll") for (int k = 0; k < 2; ++k) \
;         acc[ai][bj][m][n] = __builtin_amdgcn_mfma_f32_16x16x32_bf16(Bt[n][k], At[m][k], acc[ai][bj][m][n], 0, 0, 0); __builtin_amdgcn_s_setprio(0); } while (0)
; #define PG8_WAIT_L(n) asm volatile("s_waitcnt lgkmcnt(" #n ")" ::: "memory")
; #define PG8_BAR __builtin_amdgcn_s_barrier()
; #define PG8_SCHED __builtin_amdgcn_sched_barrier(0)
; template <class Epi>
; DI void gemm_phase(LAS unsigned char* lds, int wid, int K, int lda, int ldb, bool bperm, const Sched3& S, const Epi& E) {
;     ...
;             PG8_LDB(B1, 0, 1); PG8_STAGE(PG8_SB(0, 0), b2, voffB);
;             PG8_BAR; PG8_WAIT_L(0); PG8_MMA(0, 1, At, B1); PG8_BAR;
;             PG8_LDA(At, 0, 1); PG8_STAGE(PG8_SA(0, 0), a2, voffA);
;             PG8_BAR; PG8_WAIT_L(0); if (full) PG8_MMA(1, 0, At, B0); PG8_BAR; PG8_SCHED;
;             PG8_STAGE(PG8_SB(0, 1), b2 + hstepB, voffB);
	s_add_i32 m0, s64, 0x2000
	s_nop 0
	global_load_lds_dwordx4 v150, s[38:39]
	s_barrier
	s_waitcnt lgkmcnt(0)
	s_setprio 1
	s_waitcnt lgkmcnt(0)
	v_mfma_f32_16x16x32_bf16 v[116:119], v[228:231], v[180:183], 0
	v_mfma_f32_16x16x32_bf16 v[112:115], v[236:239], v[180:183], 0
	v_mfma_f32_16x16x32_bf16 v[100:103], v[228:231], v[200:203], 0
	v_mfma_f32_16x16x32_bf16 v[96:99], v[236:239], v[200:203], 0
	v_mfma_f32_16x16x32_bf16 v[84:87], v[228:231], v[208:211], 0
	v_mfma_f32_16x16x32_bf16 v[80:83], v[236:239], v[208:211], 0
	v_mfma_f32_16x16x32_bf16 v[68:71], v[228:231], v[216:219], 0
	v_mfma_f32_16x16x32_bf16 v[64:67], v[236:239], v[216:219], 0
	v_mfma_f32_16x16x32_bf16 v[116:119], v[232:235], v[190:193], v[116:119]
	v_mfma_f32_16x16x32_bf16 v[112:115], v[240:243], v[190:193], v[112:115]
	v_mfma_f32_16x16x32_bf16 v[100:103], v[232:235], v[204:207], v[100:103]
	v_mfma_f32_16x16x32_bf16 v[96:99], v[240:243], v[204:207], v[96:99]
	v_mfma_f32_16x16x32_bf16 v[84:87], v[232:235], v[212:215], v[84:87]
	v_mfma_f32_16x16x32_bf16 v[80:83], v[240:243], v[212:215], v[80:83]
	v_mfma_f32_16x16x32_bf16 v[68:71], v[232:235], v[224:227], v[68:71]
	v_mfma_f32_16x16x32_bf16 v[64:67], v[240:243], v[224:227], v[64:67]
	s_setprio 0
	s_mov_b32 m0, s48
	s_mov_b64 s[100:101], s[40:41]
	s_barrier
	ds_read_b128 v[180:183], v195 offset:16384
	ds_read_b128 v[190:193], v195 offset:17408
	ds_read_b128 v[200:203], v195 offset:18432
	ds_read_b128 v[204:207], v195 offset:19456
	ds_read_b128 v[208:211], v195 offset:20480
	ds_read_b128 v[212:215], v195 offset:21504
	ds_read_b128 v[216:219], v195 offset:22528
	ds_read_b128 v[224:227], v195 offset:23552
	global_load_lds_dwordx4 v144, s[40:41]
	s_mov_b64 s[100:101], s[40:41]
	s_mov_b32 m0, s49
	s_nop 0
	global_load_lds_dwordx4 v148, s[40:41]
	s_barrier
	s_waitcnt lgkmcnt(0)
	s_setprio 1
	s_waitcnt lgkmcnt(0)
	v_mfma_f32_16x16x32_bf16 v[60:63], v[128:131], v[180:183], 0
	v_mfma_f32_16x16x32_bf16 v[56:59], v[136:139], v[180:183], 0
	v_mfma_f32_16x16x32_bf16 v[44:47], v[128:131], v[200:203], 0
	v_mfma_f32_16x16x32_bf16 v[40:43], v[136:139], v[200:203], 0
	v_mfma_f32_16x16x32_bf16 v[28:31], v[128:131], v[208:211], 0
	v_mfma_f32_16x16x32_bf16 v[24:27], v[136:139], v[208:211], 0
	v_mfma_f32_16x16x32_bf16 v[12:15], v[128:131], v[216:219], 0
	v_mfma_f32_16x16x32_bf16 v[8:11], v[136:139], v[216:219], 0
	v_mfma_f32_16x16x32_bf16 v[60:63], v[132:135], v[190:193], v[60:63]
	v_mfma_f32_16x16x32_bf16 v[56:59], v[140:143], v[190:193], v[56:59]
	v_mfma_f32_16x16x32_bf16 v[44:47], v[132:135], v[204:207], v[44:47]
	v_mfma_f32_16x16x32_bf16 v[40:43], v[140:143], v[204:207], v[40:43]
	v_mfma_f32_16x16x32_bf16 v[28:31], v[132:135], v[212:215], v[28:31]
	v_mfma_f32_16x16x32_bf16 v[24:27], v[140:143], v[212:215], v[24:27]
	v_mfma_f32_16x16x32_bf16 v[12:15], v[132:135], v[224:227], v[12:15]
	v_mfma_f32_16x16x32_bf16 v[8:11], v[140:143], v[224:227], v[8:11]
	s_setprio 0
	s_barrier
	s_add_u32 s64, s38, 0x80000
	s_addc_u32 s65, s39, 0
	s_add_i32 s66, s60, s47

; #define PG8_STAGE(bufoff, gbase, voff) do { _Pragma("unroll") for (int _i = 0; _i < 2; ++_i) \
;         __builtin_amdgcn_global_load_lds((const unsigned*)((const char*)(gbase) + (voff)[_i]), (LAS unsigned*)(lds + (bufoff) + ldsw + _i * 8192), 16, 0, 0); } while (0)
; template <class Epi>
; DI void gemm_phase(LAS unsigned char* lds, int wid, int K, int lda, int ldb, bool bperm, const Sched3& S, const Epi& E) {
;     ...
;             PG8_STAGE(PG8_SB(0, 1), b2 + hstepB, voffB);
	s_mov_b32 m0, s66
	s_nop 0
	global_load_lds_dwordx4 v146, s[64:65]

; #define PG8_STAGE(bufoff, gbase, voff) do { _Pragma("unroll") for (int _i = 0; _i < 2; ++_i) \
;         __builtin_amdgcn_global_load_lds((const unsigned*)((const char*)(gbase) + (voff)[_i]), (LAS unsigned*)(lds + (bufoff) + ldsw + _i * 8192), 16, 0, 0); } while (0)
; #define PG8_LDA(dst, b, h) do { _Pragma("unroll") for (int m = 0; m < 4; ++m) _Pragma("unroll") for (int k = 0; k < 2; ++k) dst[m][k] = *(const LAS bf16x8*)(lds + PG8_SA(b, h) + aoff + m * 2048 + k * 1024); } while (0)
; #define PG8_LDB(dst, b, h) do { _Pragma("unroll") for (int n = 0; n < 2; ++n) _Pragma("unroll") for (int k = 0; k < 2; ++k) dst[n][k] = *(const LAS bf16x8*)(lds + PG8_SB(b, h) + boff + n * 2048 + k * 1024); } while (0)
; #define PG8_MMA(ai, bj, At, Bt) do { __builtin_amdgcn_s_setprio(1); _Pragma("unroll") for (int m = 0; m < 4; ++m) _Pragma("unroll") for (int n = 0; n < 2; ++n) _Pragma("unroll") for (int k = 0; k < 2; ++k) \
;         acc[ai][bj][m][n] = __builtin_amdgcn_mfma_f32_16x16x32_bf16(Bt[n][k], At[m][k], acc[ai][bj][m][n], 0, 0, 0); __builtin_amdgcn_s_setprio(0); } while (0)
; #define PG8_WAIT_V(n) asm volatile("s_waitcnt vmcnt(" #n ")" ::: "memory")
; #define PG8_BAR __builtin_amdgcn_s_barrier()
; #define PG8_SCHED __builtin_amdgcn_sched_barrier(0)
; template <class Epi>
; DI void gemm_phase(LAS unsigned char* lds, int wid, int K, int lda, int ldb, bool bperm, const Sched3& S, const Epi& E) {
;     ...
;             PG8_STAGE(PG8_SB(0, 1), b2 + hstepB, voffB);
;             PG8_WAIT_V(6); PG8_BAR; if (full) PG8_MMA(1, 1, At, B1); PG8_BAR;
;             PG8_LDB(B0, 1, 0); PG8_SCHED; PG8_LDA(At, 1, 0); PG8_STAGE(PG8_SA(0, 1), a2 + h2, voffA);
	s_add_i32 m0, s66, 0x2000
	s_nop 0
	global_load_lds_dwordx4 v150, s[64:65]
	s_waitcnt vmcnt(6)
	s_barrier
	s_setprio 1
	v_mfma_f32_16x16x32_bf16 v[52:55], v[228:231], v[180:183], 0
	v_mfma_f32_16x16x32_bf16 v[48:51], v[236:239], v[180:183], 0
	v_mfma_f32_16x16x32_bf16 v[36:39], v[228:231], v[200:203], 0
	v_mfma_f32_16x16x32_bf16 v[32:35], v[236:239], v[200:203], 0
	v_mfma_f32_16x16x32_bf16 v[20:23], v[228:231], v[208:211], 0
	v_mfma_f32_16x16x32_bf16 v[16:19], v[236:239], v[208:211], 0
	v_mfma_f32_16x16x32_bf16 v[4:7], v[228:231], v[216:219], 0
	v_mfma_f32_16x16x32_bf16 v[0:3], v[236:239], v[216:219], 0
	v_mfma_f32_16x16x32_bf16 v[52:55], v[232:235], v[190:193], v[52:55]
	v_mfma_f32_16x16x32_bf16 v[48:51], v[240:243], v[190:193], v[48:51]
	v_mfma_f32_16x16x32_bf16 v[36:39], v[232:235], v[204:207], v[36:39]
	v_mfma_f32_16x16x32_bf16 v[32:35], v[240:243], v[204:207], v[32:35]
	v_mfma_f32_16x16x32_bf16 v[20:23], v[232:235], v[212:215], v[20:23]
	v_mfma_f32_16x16x32_bf16 v[16:19], v[240:243], v[212:215], v[16:19]
	v_mfma_f32_16x16x32_bf16 v[4:7], v[232:235], v[224:227], v[4:7]
	v_mfma_f32_16x16x32_bf16 v[0:3], v[240:243], v[224:227], v[0:3]
	s_setprio 0
	s_add_i32 s64, 0, 0x18000
	v_add_u32_e32 v140, s64, v171
	s_barrier
	ds_read_b128 v[128:131], v140
	ds_read_b128 v[132:135], v140 offset:1024
	ds_read_b128 v[136:139], v140 offset:2048
	ds_read_b128 v[140:143], v140 offset:3072
	s_add_u32 s40, s40, 0x80000
	s_addc_u32 s41, s41, 0
	s_mov_b32 m0, s50

; #define PG8_STAGE(bufoff, gbase, voff) do { _Pragma("unroll") for (int _i = 0; _i < 2; ++_i) \
;         __builtin_amdgcn_global_load_lds((const unsigned*)((const char*)(gbase) + (voff)[_i]), (LAS unsigned*)(lds + (bufoff) + ldsw + _i * 8192), 16, 0, 0); } while (0)
; #define PG8_LDA(dst, b, h) do { _Pragma("unroll") for (int m = 0; m < 4; ++m) _Pragma("unroll") for (int k = 0; k < 2; ++k) dst[m][k] = *(const LAS bf16x8*)(lds + PG8_SA(b, h) + aoff + m * 2048 + k * 1024); } while (0)
; #define PG8_LDB(dst, b, h) do { _Pragma("unroll") for (int n = 0; n < 2; ++n) _Pragma("unroll") for (int k = 0; k < 2; ++k) dst[n][k] = *(const LAS bf16x8*)(lds + PG8_SB(b, h) + boff + n * 2048 + k * 1024); } while (0)
; #define PG8_SCHED __builtin_amdgcn_sched_barrier(0)
; template <class Epi>
; DI void gemm_phase(LAS unsigned char* lds, int wid, int K, int lda, int ldb, bool bperm, const Sched3& S, const Epi& E) {
;     ...
;             PG8_LDB(B0, 1, 0); PG8_SCHED; PG8_LDA(At, 1, 0); PG8_STAGE(PG8_SA(0, 1), a2 + h2, voffA);
	ds_read_b128 v[180:183], v195 offset:32768
	ds_read_b128 v[190:193], v195 offset:33792
	ds_read_b128 v[200:203], v195 offset:34816
	ds_read_b128 v[204:207], v195 offset:35840
	ds_read_b128 v[208:211], v195 offset:36864
	ds_read_b128 v[212:215], v195 offset:37888
	ds_read_b128 v[216:219], v195 offset:38912
	ds_read_b128 v[224:227], v195 offset:39936
	global_load_lds_dwordx4 v144, s[40:41]

; #define PG8_STAGE(bufoff, gbase, voff) do { _Pragma("unroll") for (int _i = 0; _i < 2; ++_i) \
;         __builtin_amdgcn_global_load_lds((const unsigned*)((const char*)(gbase) + (voff)[_i]), (LAS unsigned*)(lds + (bufoff) + ldsw + _i * 8192), 16, 0, 0); } while (0)
; #define PG8_LDA(dst, b, h) do { _Pragma("unroll") for (int m = 0; m < 4; ++m) _Pragma("unroll") for (int k = 0; k < 2; ++k) dst[m][k] = *(const LAS bf16x8*)(lds + PG8_SA(b, h) + aoff + m * 2048 + k * 1024); } while (0)
; #define PG8_LDB(dst, b, h) do { _Pragma("unroll") for (int n = 0; n < 2; ++n) _Pragma("unroll") for (int k = 0; k < 2; ++k) dst[n][k] = *(const LAS bf16x8*)(lds + PG8_SB(b, h) + boff + n * 2048 + k * 1024); } while (0)
; #define PG8_MMA(ai, bj, At, Bt) do { __builtin_amdgcn_s_setprio(1); _Pragma("unroll") for (int m = 0; m < 4; ++m) _Pragma("unroll") for (int n = 0; n < 2; ++n) _Pragma("unroll") for (int k = 0; k < 2; ++k) \
;         acc[ai][bj][m][n] = __builtin_amdgcn_mfma_f32_16x16x32_bf16(Bt[n][k], At[m][k], acc[ai][bj][m][n], 0, 0, 0); __builtin_amdgcn_s_setprio(0); } while (0)
; #define PG8_WAIT_L(n) asm volatile("s_waitcnt lgkmcnt(" #n ")" ::: "memory")
; #define PG8_BAR __builtin_amdgcn_s_barrier()
; #define PG8_SCHED __builtin_amdgcn_sched_barrier(0)
; template <class Epi>
; DI void gemm_phase(LAS unsigned char* lds, int wid, int K, int lda, int ldb, bool bperm, const Sched3& S, const Epi& E) {
;     ...
;             PG8_LDB(B0, 1, 0); PG8_SCHED; PG8_LDA(At, 1, 0); PG8_STAGE(PG8_SA(0, 1), a2 + h2, voffA);
;             PG8_WAIT_L(8); PG8_BAR; PG8_WAIT_L(0); PG8_MMA(0, 0, At, B0); PG8_BAR; PG8_SCHED;
	s_mov_b32 m0, s51
	s_nop 0
	global_load_lds_dwordx4 v148, s[40:41]
	s_waitcnt lgkmcnt(8)
	s_barrier
	s_waitcnt lgkmcnt(0)
	s_setprio 1
	s_waitcnt lgkmcnt(0)
	v_mfma_f32_16x16x32_bf16 v[124:127], v[128:131], v[180:183], v[124:127]
	v_mfma_f32_16x16x32_bf16 v[120:123], v[136:139], v[180:183], v[120:123]
	v_mfma_f32_16x16x32_bf16 v[108:111], v[128:131], v[200:203], v[108:111]
	v_mfma_f32_16x16x32_bf16 v[104:107], v[136:139], v[200:203], v[104:107]
	v_mfma_f32_16x16x32_bf16 v[92:95], v[128:131], v[208:211], v[92:95]
	v_mfma_f32_16x16x32_bf16 v[88:91], v[136:139], v[208:211], v[88:91]
	v_mfma_f32_16x16x32_bf16 v[76:79], v[128:131], v[216:219], v[76:79]
	v_mfma_f32_16x16x32_bf16 v[72:75], v[136:139], v[216:219], v[72:75]
	v_mfma_f32_16x16x32_bf16 v[124:127], v[132:135], v[190:193], v[124:127]
	v_mfma_f32_16x16x32_bf16 v[120:123], v[140:143], v[190:193], v[120:123]
	v_mfma_f32_16x16x32_bf16 v[108:111], v[132:135], v[204:207], v[108:111]
	v_mfma_f32_16x16x32_bf16 v[104:107], v[140:143], v[204:207], v[104:107]
	v_mfma_f32_16x16x32_bf16 v[92:95], v[132:135], v[212:215], v[92:95]
	v_mfma_f32_16x16x32_bf16 v[88:91], v[140:143], v[212:215], v[88:91]
	v_mfma_f32_16x16x32_bf16 v[76:79], v[132:135], v[224:227], v[76:79]
	v_mfma_f32_16x16x32_bf16 v[72:75], v[140:143], v[224:227], v[72:75]
	s_setprio 0
	s_barrier
	s_add_i32 s40, 0, 0x1c000
	s_add_i32 s41, s64, s47
	v_add_u32_e32 v152, s40, v171

; #define PG8_STAGE(bufoff, gbase, voff) do { _Pragma("unroll") for (int _i = 0; _i < 2; ++_i) \
;         __builtin_amdgcn_global_load_lds((const unsigned*)((const char*)(gbase) + (voff)[_i]), (LAS unsigned*)(lds + (bufoff) + ldsw + _i * 8192), 16, 0, 0); } while (0)
; #define PG8_LDB(dst, b, h) do { _Pragma("unroll") for (int n = 0; n < 2; ++n) _Pragma("unroll") for (int k = 0; k < 2; ++k) dst[n][k] = *(const LAS bf16x8*)(lds + PG8_SB(b, h) + boff + n * 2048 + k * 1024); } while (0)
; template <class Epi>
; DI void gemm_phase(LAS unsigned char* lds, int wid, int K, int lda, int ldb, bool bperm, const Sched3& S, const Epi& E) {
;     ...
;             PG8_LDB(B1, 1, 1); PG8_STAGE(PG8_SB(1, 0), b3, voffB);
	s_sub_i32 m0, s41, 0x80
	ds_read_b128 v[228:231], v152
	ds_read_b128 v[232:235], v152 offset:1024
	ds_read_b128 v[236:239], v152 offset:2048
	ds_read_b128 v[240:243], v152 offset:3072
	global_load_lds_dwordx4 v146, s[38:39] offset:128

; #define PG8_STAGE(bufoff, gbase, voff) do { _Pragma("unroll") for (int _i = 0; _i < 2; ++_i) \
;         __builtin_amdgcn_global_load_lds((const unsigned*)((const char*)(gbase) + (voff)[_i]), (LAS unsigned*)(lds + (bufoff) + ldsw + _i * 8192), 16, 0, 0); } while (0)
; #define PG8_LDB(dst, b, h) do { _Pragma("unroll") for (int n = 0; n < 2; ++n) _Pragma("unroll") for (int k = 0; k < 2; ++k) dst[n][k] = *(const LAS bf16x8*)(lds + PG8_SB(b, h) + boff + n * 2048 + k * 1024); } while (0)
; #define PG8_MMA(ai, bj, At, Bt) do { __builtin_amdgcn_s_setprio(1); _Pragma("unroll") for (int m = 0; m < 4; ++m) _Pragma("unroll") for (int n = 0; n < 2; ++n) _Pragma("unroll") for (int k = 0; k < 2; ++k) \
;         acc[ai][bj][m][n] = __builtin_amdgcn_mfma_f32_16x16x32_bf16(Bt[n][k], At[m][k], acc[ai][bj][m][n], 0, 0, 0); __builtin_amdgcn_s_setprio(0); } while (0)
; #define PG8_WAIT_L(n) asm volatile("s_waitcnt lgkmcnt(" #n ")" ::: "memory")
; #define PG8_BAR __builtin_amdgcn_s_barrier()
; template <class Epi>
; DI void gemm_phase(LAS unsigned char* lds, int wid, int K, int lda, int ldb, bool bperm, const Sched3& S, const Epi& E) {
;     ...
;             PG8_LDB(B1, 1, 1); PG8_STAGE(PG8_SB(1, 0), b3, voffB);
;             PG8_BAR; PG8_WAIT_L(0); PG8_MMA(0, 1, At, B1); PG8_BAR;
	s_add_i32 m0, s41, 0x1f80
	s_nop 0
	global_load_lds_dwordx4 v150, s[38:39] offset:128
	s_barrier
	s_waitcnt lgkmcnt(0)
	s_setprio 1
	s_waitcnt lgkmcnt(0)
	v_mfma_f32_16x16x32_bf16 v[116:119], v[228:231], v[180:183], v[116:119]
	v_mfma_f32_16x16x32_bf16 v[112:115], v[236:239], v[180:183], v[112:115]
	v_mfma_f32_16x16x32_bf16 v[100:103], v[228:231], v[200:203], v[100:103]
	v_mfma_f32_16x16x32_bf16 v[96:99], v[236:239], v[200:203], v[96:99]
	v_mfma_f32_16x16x32_bf16 v[84:87], v[228:231], v[208:211], v[84:87]
	v_mfma_f32_16x16x32_bf16 v[80:83], v[236:239], v[208:211], v[80:83]
	v_mfma_f32_16x16x32_bf16 v[68:71], v[228:231], v[216:219], v[68:71]
	v_mfma_f32_16x16x32_bf16 v[64:67], v[236:239], v[216:219], v[64:67]
	v_mfma_f32_16x16x32_bf16 v[116:119], v[232:235], v[190:193], v[116:119]
	v_mfma_f32_16x16x32_bf16 v[112:115], v[240:243], v[190:193], v[112:115]
	v_mfma_f32_16x16x32_bf16 v[100:103], v[232:235], v[204:207], v[100:103]
	v_mfma_f32_16x16x32_bf16 v[96:99], v[240:243], v[204:207], v[96:99]
	v_mfma_f32_16x16x32_bf16 v[84:87], v[232:235], v[212:215], v[84:87]
	v_mfma_f32_16x16x32_bf16 v[80:83], v[240:243], v[212:215], v[80:83]
	v_mfma_f32_16x16x32_bf16 v[68:71], v[232:235], v[224:227], v[68:71]
	v_mfma_f32_16x16x32_bf16 v[64:67], v[240:243], v[224:227], v[64:67]
	s_setprio 0
	s_sub_i32 m0, s53, 0x80

; #define PG8_STAGE(bufoff, gbase, voff) do { _Pragma("unroll") for (int _i = 0; _i < 2; ++_i) \
;         __builtin_amdgcn_global_load_lds((const unsigned*)((const char*)(gbase) + (voff)[_i]), (LAS unsigned*)(lds + (bufoff) + ldsw + _i * 8192), 16, 0, 0); } while (0)
; #define PG8_LDA(dst, b, h) do { _Pragma("unroll") for (int m = 0; m < 4; ++m) _Pragma("unroll") for (int k = 0; k < 2; ++k) dst[m][k] = *(const LAS bf16x8*)(lds + PG8_SA(b, h) + aoff + m * 2048 + k * 1024); } while (0)
; template <class Epi>
; DI void gemm_phase(LAS unsigned char* lds, int wid, int K, int lda, int ldb, bool bperm, const Sched3& S, const Epi& E) {
;     ...
;             PG8_LDA(At, 1, 1); PG8_STAGE(PG8_SA(1, 0), a3, voffA);
	s_barrier
	ds_read_b128 v[180:183], v195 offset:49152
	ds_read_b128 v[190:193], v195 offset:50176
	ds_read_b128 v[200:203], v195 offset:51200
	ds_read_b128 v[204:207], v195 offset:52224
	ds_read_b128 v[208:211], v195 offset:53248
	ds_read_b128 v[212:215], v195 offset:54272
	ds_read_b128 v[216:219], v195 offset:55296
	ds_read_b128 v[224:227], v195 offset:56320
	global_load_lds_dwordx4 v144, s[100:101] offset:128

; #define PG8_STAGE(bufoff, gbase, voff) do { _Pragma("unroll") for (int _i = 0; _i < 2; ++_i) \
;         __builtin_amdgcn_global_load_lds((const unsigned*)((const char*)(gbase) + (voff)[_i]), (LAS unsigned*)(lds + (bufoff) + ldsw + _i * 8192), 16, 0, 0); } while (0)
; #define PG8_LDA(dst, b, h) do { _Pragma("unroll") for (int m = 0; m < 4; ++m) _Pragma("unroll") for (int k = 0; k < 2; ++k) dst[m][k] = *(const LAS bf16x8*)(lds + PG8_SA(b, h) + aoff + m * 2048 + k * 1024); } while (0)
; #define PG8_MMA(ai, bj, At, Bt) do { __builtin_amdgcn_s_setprio(1); _Pragma("unroll") for (int m = 0; m < 4; ++m) _Pragma("unroll") for (int n = 0; n < 2; ++n) _Pragma("unroll") for (int k = 0; k < 2; ++k) \
;         acc[ai][bj][m][n] = __builtin_amdgcn_mfma_f32_16x16x32_bf16(Bt[n][k], At[m][k], acc[ai][bj][m][n], 0, 0, 0); __builtin_amdgcn_s_setprio(0); } while (0)
; #define PG8_WAIT_L(n) asm volatile("s_waitcnt lgkmcnt(" #n ")" ::: "memory")
; #define PG8_BAR __builtin_amdgcn_s_barrier()
; #define PG8_SCHED __builtin_amdgcn_sched_barrier(0)
; template <class Epi>
; DI void gemm_phase(LAS unsigned char* lds, int wid, int K, int lda, int ldb, bool bperm, const Sched3& S, const Epi& E) {
;     ...
;             PG8_LDA(At, 1, 1); PG8_STAGE(PG8_SA(1, 0), a3, voffA);
;             PG8_BAR; PG8_WAIT_L(0); if (full) PG8_MMA(1, 0, At, B0); PG8_BAR; PG8_SCHED;
	s_sub_i32 m0, s54, 0x80
	s_nop 0
	global_load_lds_dwordx4 v148, s[100:101] offset:128
	s_barrier
	s_waitcnt lgkmcnt(0)
	s_setprio 1
	s_waitcnt lgkmcnt(0)
	v_mfma_f32_16x16x32_bf16 v[60:63], v[128:131], v[180:183], v[60:63]
	v_mfma_f32_16x16x32_bf16 v[56:59], v[136:139], v[180:183], v[56:59]
	v_mfma_f32_16x16x32_bf16 v[44:47], v[128:131], v[200:203], v[44:47]
	v_mfma_f32_16x16x32_bf16 v[40:43], v[136:139], v[200:203], v[40:43]
	v_mfma_f32_16x16x32_bf16 v[28:31], v[128:131], v[208:211], v[28:31]
	v_mfma_f32_16x16x32_bf16 v[24:27], v[136:139], v[208:211], v[24:27]
	v_mfma_f32_16x16x32_bf16 v[12:15], v[128:131], v[216:219], v[12:15]
	v_mfma_f32_16x16x32_bf16 v[8:11], v[136:139], v[216:219], v[8:11]
	v_mfma_f32_16x16x32_bf16 v[60:63], v[132:135], v[190:193], v[60:63]
	v_mfma_f32_16x16x32_bf16 v[56:59], v[140:143], v[190:193], v[56:59]
	v_mfma_f32_16x16x32_bf16 v[44:47], v[132:135], v[204:207], v[44:47]
	v_mfma_f32_16x16x32_bf16 v[40:43], v[140:143], v[204:207], v[40:43]
	v_mfma_f32_16x16x32_bf16 v[28:31], v[132:135], v[212:215], v[28:31]
	v_mfma_f32_16x16x32_bf16 v[24:27], v[140:143], v[212:215], v[24:27]
	v_mfma_f32_16x16x32_bf16 v[12:15], v[132:135], v[224:227], v[12:15]
	v_mfma_f32_16x16x32_bf16 v[8:11], v[140:143], v[224:227], v[8:11]
	s_setprio 0
	s_barrier
	s_add_u32 s38, s38, 0x80080
	s_addc_u32 s39, s39, 0
	s_add_i32 s40, s40, s47

; #define PG8_STAGE(bufoff, gbase, voff) do { _Pragma("unroll") for (int _i = 0; _i < 2; ++_i) \
;         __builtin_amdgcn_global_load_lds((const unsigned*)((const char*)(gbase) + (voff)[_i]), (LAS unsigned*)(lds + (bufoff) + ldsw + _i * 8192), 16, 0, 0); } while (0)
; template <class Epi>
; DI void gemm_phase(LAS unsigned char* lds, int wid, int K, int lda, int ldb, bool bperm, const Sched3& S, const Epi& E) {
;     ...
;             PG8_STAGE(PG8_SB(1, 1), b3 + hstepB, voffB);
	s_mov_b32 m0, s40
	s_nop 0
	global_load_lds_dwordx4 v146, s[38:39]

; #define PG8_STAGE(bufoff, gbase, voff) do { _Pragma("unroll") for (int _i = 0; _i < 2; ++_i) \
;         __builtin_amdgcn_global_load_lds((const unsigned*)((const char*)(gbase) + (voff)[_i]), (LAS unsigned*)(lds + (bufoff) + ldsw + _i * 8192), 16, 0, 0); } while (0)
; #define PG8_MMA(ai, bj, At, Bt) do { __builtin_amdgcn_s_setprio(1); _Pragma("unroll") for (int m = 0; m < 4; ++m) _Pragma("unroll") for (int n = 0; n < 2; ++n) _Pragma("unroll") for (int k = 0; k < 2; ++k) \
;         acc[ai][bj][m][n] = __builtin_amdgcn_mfma_f32_16x16x32_bf16(Bt[n][k], At[m][k], acc[ai][bj][m][n], 0, 0, 0); __builtin_amdgcn_s_setprio(0); } while (0)
; #define PG8_WAIT_V(n) asm volatile("s_waitcnt vmcnt(" #n ")" ::: "memory")
; #define PG8_BAR __builtin_amdgcn_s_barrier()
; template <class Epi>
; DI void gemm_phase(LAS unsigned char* lds, int wid, int K, int lda, int ldb, bool bperm, const Sched3& S, const Epi& E) {
;     ...
;             PG8_STAGE(PG8_SB(1, 1), b3 + hstepB, voffB);
;             PG8_WAIT_V(6); PG8_BAR; if (full) PG8_MMA(1, 1, At, B1); PG8_BAR;
	s_add_i32 m0, s40, 0x2000
	s_nop 0
	global_load_lds_dwordx4 v150, s[38:39]
	s_waitcnt vmcnt(6)
	s_barrier
	s_setprio 1
	v_mfma_f32_16x16x32_bf16 v[52:55], v[228:231], v[180:183], v[52:55]
	v_mfma_f32_16x16x32_bf16 v[48:51], v[236:239], v[180:183], v[48:51]
	v_mfma_f32_16x16x32_bf16 v[36:39], v[228:231], v[200:203], v[36:39]
	v_mfma_f32_16x16x32_bf16 v[32:35], v[236:239], v[200:203], v[32:35]
	v_mfma_f32_16x16x32_bf16 v[20:23], v[228:231], v[208:211], v[20:23]
	v_mfma_f32_16x16x32_bf16 v[16:19], v[236:239], v[208:211], v[16:19]
	v_mfma_f32_16x16x32_bf16 v[4:7], v[228:231], v[216:219], v[4:7]
	v_mfma_f32_16x16x32_bf16 v[0:3], v[236:239], v[216:219], v[0:3]
	v_mfma_f32_16x16x32_bf16 v[52:55], v[232:235], v[190:193], v[52:55]
	v_mfma_f32_16x16x32_bf16 v[48:51], v[240:243], v[190:193], v[48:51]
	v_mfma_f32_16x16x32_bf16 v[36:39], v[232:235], v[204:207], v[36:39]
	v_mfma_f32_16x16x32_bf16 v[32:35], v[240:243], v[204:207], v[32:35]
	v_mfma_f32_16x16x32_bf16 v[20:23], v[232:235], v[212:215], v[20:23]
	v_mfma_f32_16x16x32_bf16 v[16:19], v[240:243], v[212:215], v[16:19]
	v_mfma_f32_16x16x32_bf16 v[4:7], v[232:235], v[224:227], v[4:7]
	v_mfma_f32_16x16x32_bf16 v[0:3], v[240:243], v[224:227], v[0:3]
	s_setprio 0
	s_add_i32 s27, s27, 2
	s_add_u32 s36, s36, 0x100
	s_addc_u32 s37, s37, 0
	s_add_u32 s19, s19, 0x100
	s_addc_u32 s21, s21, 0
	s_cmp_gt_u32 s27, 29
	s_cbranch_scc1 .Lkrot_4_exit

; #define PG8_STAGE(bufoff, gbase, voff) do { _Pragma("unroll") for (int _i = 0; _i < 2; ++_i) \
;         __builtin_amdgcn_global_load_lds((const unsigned*)((const char*)(gbase) + (voff)[_i]), (LAS unsigned*)(lds + (bufoff) + ldsw + _i * 8192), 16, 0, 0); } while (0)
; #define PG8_LDA(dst, b, h) do { _Pragma("unroll") for (int m = 0; m < 4; ++m) _Pragma("unroll") for (int k = 0; k < 2; ++k) dst[m][k] = *(const LAS bf16x8*)(lds + PG8_SA(b, h) + aoff + m * 2048 + k * 1024); } while (0)
; #define PG8_LDB(dst, b, h) do { _Pragma("unroll") for (int n = 0; n < 2; ++n) _Pragma("unroll") for (int k = 0; k < 2; ++k) dst[n][k] = *(const LAS bf16x8*)(lds + PG8_SB(b, h) + boff + n * 2048 + k * 1024); } while (0)
; #define PG8_SCHED __builtin_amdgcn_sched_barrier(0)
; template <class Epi>
; DI void gemm_phase(LAS unsigned char* lds, int wid, int K, int lda, int ldb, bool bperm, const Sched3& S, const Epi& E) {
;     ...
;             const bool last = (t == nt - 2);
;             const char* a1 = cA + (size_t)(t + 1) * kstep;
;             const char* a2 = last ? nA : cA + (size_t)(t + 2) * kstep; const char* b2 = last ? nB : cB + (size_t)(t + 2) * kstep;
;             const char* a3 = a2 + kstep; const char* b3 = b2 + kstep; const size_t h2 = last ? nhA : hA;
;             PG8_LDB(B0, 0, 0); PG8_SCHED; PG8_LDA(At, 0, 0); PG8_STAGE(PG8_SA(1, 1), a1 + hA, voffA);
.LBB0_873:
	ds_read_b128 v[128:131], v189
	ds_read_b128 v[132:135], v189 offset:1024
	ds_read_b128 v[136:139], v189 offset:2048
	ds_read_b128 v[140:143], v189 offset:3072
	s_add_u32 s38, s36, 0xfff80080
	s_addc_u32 s39, s37, -1
	s_cmp_eq_u32 s27, 28
	s_cselect_b32 s41, s29, s39
	s_cselect_b32 s40, s28, s38
	s_cselect_b32 s39, s31, s21
	s_cselect_b32 s38, s30, s19

; #define PG8_STAGE(bufoff, gbase, voff) do { _Pragma("unroll") for (int _i = 0; _i < 2; ++_i) \
;         __builtin_amdgcn_global_load_lds((const unsigned*)((const char*)(gbase) + (voff)[_i]), (LAS unsigned*)(lds + (bufoff) + ldsw + _i * 8192), 16, 0, 0); } while (0)
; #define PG8_LDA(dst, b, h) do { _Pragma("unroll") for (int m = 0; m < 4; ++m) _Pragma("unroll") for (int k = 0; k < 2; ++k) dst[m][k] = *(const LAS bf16x8*)(lds + PG8_SA(b, h) + aoff + m * 2048 + k * 1024); } while (0)
; #define PG8_LDB(dst, b, h) do { _Pragma("unroll") for (int n = 0; n < 2; ++n) _Pragma("unroll") for (int k = 0; k < 2; ++k) dst[n][k] = *(const LAS bf16x8*)(lds + PG8_SB(b, h) + boff + n * 2048 + k * 1024); } while (0)
; #define PG8_SCHED __builtin_amdgcn_sched_barrier(0)
; template <class Epi>
; DI void gemm_phase(LAS unsigned char* lds, int wid, int K, int lda, int ldb, bool bperm, const Sched3& S, const Epi& E) {
;     ...
;             PG8_LDB(B0, 0, 0); PG8_SCHED; PG8_LDA(At, 0, 0); PG8_STAGE(PG8_SA(1, 1), a1 + hA, voffA);
	s_add_i32 m0, s48, 0xc000
	ds_read_b128 v[180:183], v195
	ds_read_b128 v[190:193], v195 offset:1024
	ds_read_b128 v[200:203], v195 offset:2048
	ds_read_b128 v[204:207], v195 offset:3072
	ds_read_b128 v[208:211], v195 offset:4096
	ds_read_b128 v[212:215], v195 offset:5120
	ds_read_b128 v[216:219], v195 offset:6144
	ds_read_b128 v[224:227], v195 offset:7168
	global_load_lds_dwordx4 v160, s[36:37]

; #define PG8_STAGE(bufoff, gbase, voff) do { _Pragma("unroll") for (int _i = 0; _i < 2; ++_i) \
;         __builtin_amdgcn_global_load_lds((const unsigned*)((const char*)(gbase) + (voff)[_i]), (LAS unsigned*)(lds + (bufoff) + ldsw + _i * 8192), 16, 0, 0); } while (0)
; #define PG8_LDA(dst, b, h) do { _Pragma("unroll") for (int m = 0; m < 4; ++m) _Pragma("unroll") for (int k = 0; k < 2; ++k) dst[m][k] = *(const LAS bf16x8*)(lds + PG8_SA(b, h) + aoff + m * 2048 + k * 1024); } while (0)
; #define PG8_LDB(dst, b, h) do { _Pragma("unroll") for (int n = 0; n < 2; ++n) _Pragma("unroll") for (int k = 0; k < 2; ++k) dst[n][k] = *(const LAS bf16x8*)(lds + PG8_SB(b, h) + boff + n * 2048 + k * 1024); } while (0)
; #define PG8_MMA(ai, bj, At, Bt) do { __builtin_amdgcn_s_setprio(1); _Pragma("unroll") for (int m = 0; m < 4; ++m) _Pragma("unroll") for (int n = 0; n < 2; ++n) _Pragma("unroll") for (int k = 0; k < 2; ++k) \
;         acc[ai][bj][m][n] = __builtin_amdgcn_mfma_f32_16x16x32_bf16(Bt[n][k], At[m][k], acc[ai][bj][m][n], 0, 0, 0); __builtin_amdgcn_s_setprio(0); } while (0)
; #define PG8_WAIT_L(n) asm volatile("s_waitcnt lgkmcnt(" #n ")" ::: "memory")
; #define PG8_BAR __builtin_amdgcn_s_barrier()
; #define PG8_SCHED __builtin_amdgcn_sched_barrier(0)
; template <class Epi>
; DI void gemm_phase(LAS unsigned char* lds, int wid, int K, int lda, int ldb, bool bperm, const Sched3& S, const Epi& E) {
;     ...
;             PG8_LDB(B0, 0, 0); PG8_SCHED; PG8_LDA(At, 0, 0); PG8_STAGE(PG8_SA(1, 1), a1 + hA, voffA);
;             PG8_WAIT_L(8); PG8_BAR; PG8_WAIT_L(0); PG8_MMA(0, 0, At, B0); PG8_BAR; PG8_SCHED;
	s_add_i32 m0, s48, 0xe000
	s_nop 0
	global_load_lds_dwordx4 v162, s[36:37]
	s_waitcnt lgkmcnt(8)
	s_barrier
	s_waitcnt lgkmcnt(0)
	s_setprio 1
	s_waitcnt lgkmcnt(0)
	v_mfma_f32_16x16x32_bf16 v[124:127], v[128:131], v[180:183], v[124:127]
	v_mfma_f32_16x16x32_bf16 v[120:123], v[136:139], v[180:183], v[120:123]
	v_mfma_f32_16x16x32_bf16 v[108:111], v[128:131], v[200:203], v[108:111]
	v_mfma_f32_16x16x32_bf16 v[104:107], v[136:139], v[200:203], v[104:107]
	v_mfma_f32_16x16x32_bf16 v[92:95], v[128:131], v[208:211], v[92:95]
	v_mfma_f32_16x16x32_bf16 v[88:91], v[136:139], v[208:211], v[88:91]
	v_mfma_f32_16x16x32_bf16 v[76:79], v[128:131], v[216:219], v[76:79]
	v_mfma_f32_16x16x32_bf16 v[72:75], v[136:139], v[216:219], v[72:75]
	v_mfma_f32_16x16x32_bf16 v[124:127], v[132:135], v[190:193], v[124:127]
	v_mfma_f32_16x16x32_bf16 v[120:123], v[140:143], v[190:193], v[120:123]
	v_mfma_f32_16x16x32_bf16 v[108:111], v[132:135], v[204:207], v[108:111]
	v_mfma_f32_16x16x32_bf16 v[104:107], v[140:143], v[204:207], v[104:107]
	v_mfma_f32_16x16x32_bf16 v[92:95], v[132:135], v[212:215], v[92:95]
	v_mfma_f32_16x16x32_bf16 v[88:91], v[140:143], v[212:215], v[88:91]
	v_mfma_f32_16x16x32_bf16 v[76:79], v[132:135], v[224:227], v[76:79]
	v_mfma_f32_16x16x32_bf16 v[72:75], v[140:143], v[224:227], v[72:75]
	s_setprio 0
	s_barrier
	s_add_i32 s64, s59, s47

; #define PG8_STAGE(bufoff, gbase, voff) do { _Pragma("unroll") for (int _i = 0; _i < 2; ++_i) \
;         __builtin_amdgcn_global_load_lds((const unsigned*)((const char*)(gbase) + (voff)[_i]), (LAS unsigned*)(lds + (bufoff) + ldsw + _i * 8192), 16, 0, 0); } while (0)
; #define PG8_LDB(dst, b, h) do { _Pragma("unroll") for (int n = 0; n < 2; ++n) _Pragma("unroll") for (int k = 0; k < 2; ++k) dst[n][k] = *(const LAS bf16x8*)(lds + PG8_SB(b, h) + boff + n * 2048 + k * 1024); } while (0)
; template <class Epi>
; DI void gemm_phase(LAS unsigned char* lds, int wid, int K, int lda, int ldb, bool bperm, const Sched3& S, const Epi& E) {
;     ...
;             PG8_LDB(B1, 0, 1); PG8_STAGE(PG8_SB(0, 0), b2, voffB);
	s_mov_b32 m0, s64
	ds_read_b128 v[228:231], v197
	ds_read_b128 v[232:235], v197 offset:1024
	ds_read_b128 v[236:239], v197 offset:2048
	ds_read_b128 v[240:243], v197 offset:3072
	global_load_lds_dwordx4 v146, s[38:39]

; #define PG8_STAGE(bufoff, gbase, voff) do { _Pragma("unroll") for (int _i = 0; _i < 2; ++_i) \
;         __builtin_amdgcn_global_load_lds((const unsigned*)((const char*)(gbase) + (voff)[_i]), (LAS unsigned*)(lds + (bufoff) + ldsw + _i * 8192), 16, 0, 0); } while (0)
; #define PG8_LDA(dst, b, h) do { _Pragma("unroll") for (int m = 0; m < 4; ++m) _Pragma("unroll") for (int k = 0; k < 2; ++k) dst[m][k] = *(const LAS bf16x8*)(lds + PG8_SA(b, h) + aoff + m * 2048 + k * 1024); } while (0)
; #define PG8_LDB(dst, b, h) do { _Pragma("unroll") for (int n = 0; n < 2; ++n) _Pragma("unroll") for (int k = 0; k < 2; ++k) dst[n][k] = *(const LAS bf16x8*)(lds + PG8_SB(b, h) + boff + n * 2048 + k * 1024); } while (0)
; #define PG8_MMA(ai, bj, At, Bt) do { __builtin_amdgcn_s_setprio(1); _Pragma("unroll") for (int m = 0; m < 4; ++m) _Pragma("unroll") for (int n = 0; n < 2; ++n) _Pragma("unroll") for (int k = 0; k < 2; ++k) \
;         acc[ai][bj][m][n] = __builtin_amdgcn_mfma_f32_16x16x32_bf16(Bt[n][k], At[m][k], acc[ai][bj][m][n], 0, 0, 0); __builtin_amdgcn_s_setprio(0); } while (0)
; #define PG8_WAIT_L(n) asm volatile("s_waitcnt lgkmcnt(" #n ")" ::: "memory")
; #define PG8_BAR __builtin_amdgcn_s_barrier()
; #define PG8_SCHED __builtin_amdgcn_sched_barrier(0)
; template <class Epi>
; DI void gemm_phase(LAS unsigned char* lds, int wid, int K, int lda, int ldb, bool bperm, const Sched3& S, const Epi& E) {
;     ...
;             PG8_LDB(B1, 0, 1); PG8_STAGE(PG8_SB(0, 0), b2, voffB);
;             PG8_BAR; PG8_WAIT_L(0); PG8_MMA(0, 1, At, B1); PG8_BAR;
;             PG8_LDA(At, 0, 1); PG8_STAGE(PG8_SA(0, 0), a2, voffA);
;             PG8_BAR; PG8_WAIT_L(0); if (full) PG8_MMA(1, 0, At, B0); PG8_BAR; PG8_SCHED;
;             PG8_STAGE(PG8_SB(0, 1), b2 + hstepB, voffB);
	s_add_i32 m0, s64, 0x2000
	s_nop 0
	global_load_lds_dwordx4 v150, s[38:39]
	s_barrier
	s_waitcnt lgkmcnt(0)
	s_setprio 1
	s_waitcnt lgkmcnt(0)
	v_mfma_f32_16x16x32_bf16 v[116:119], v[228:231], v[180:183], v[116:119]
	v_mfma_f32_16x16x32_bf16 v[112:115], v[236:239], v[180:183], v[112:115]
	v_mfma_f32_16x16x32_bf16 v[100:103], v[228:231], v[200:203], v[100:103]
	v_mfma_f32_16x16x32_bf16 v[96:99], v[236:239], v[200:203], v[96:99]
	v_mfma_f32_16x16x32_bf16 v[84:87], v[228:231], v[208:211], v[84:87]
	v_mfma_f32_16x16x32_bf16 v[80:83], v[236:239], v[208:211], v[80:83]
	v_mfma_f32_16x16x32_bf16 v[68:71], v[228:231], v[216:219], v[68:71]
	v_mfma_f32_16x16x32_bf16 v[64:67], v[236:239], v[216:219], v[64:67]
	v_mfma_f32_16x16x32_bf16 v[116:119], v[232:235], v[190:193], v[116:119]
	v_mfma_f32_16x16x32_bf16 v[112:115], v[240:243], v[190:193], v[112:115]
	v_mfma_f32_16x16x32_bf16 v[100:103], v[232:235], v[204:207], v[100:103]
	v_mfma_f32_16x16x32_bf16 v[96:99], v[240:243], v[204:207], v[96:99]
	v_mfma_f32_16x16x32_bf16 v[84:87], v[232:235], v[212:215], v[84:87]
	v_mfma_f32_16x16x32_bf16 v[80:83], v[240:243], v[212:215], v[80:83]
	v_mfma_f32_16x16x32_bf16 v[68:71], v[232:235], v[224:227], v[68:71]
	v_mfma_f32_16x16x32_bf16 v[64:67], v[240:243], v[224:227], v[64:67]
	s_setprio 0
	s_mov_b32 m0, s48
	s_mov_b64 s[100:101], s[40:41]
	s_barrier
	ds_read_b128 v[180:183], v195 offset:16384
	ds_read_b128 v[190:193], v195 offset:17408
	ds_read_b128 v[200:203], v195 offset:18432
	ds_read_b128 v[204:207], v195 offset:19456
	ds_read_b128 v[208:211], v195 offset:20480
	ds_read_b128 v[212:215], v195 offset:21504
	ds_read_b128 v[216:219], v195 offset:22528
	ds_read_b128 v[224:227], v195 offset:23552
	global_load_lds_dwordx4 v144, s[40:41]
	s_mov_b64 s[100:101], s[40:41]
	s_mov_b32 m0, s49
	s_nop 0
	global_load_lds_dwordx4 v148, s[40:41]
	s_barrier
	s_waitcnt lgkmcnt(0)
	s_setprio 1
	s_waitcnt lgkmcnt(0)
	v_mfma_f32_16x16x32_bf16 v[60:63], v[128:131], v[180:183], v[60:63]
	v_mfma_f32_16x16x32_bf16 v[56:59], v[136:139], v[180:183], v[56:59]
	v_mfma_f32_16x16x32_bf16 v[44:47], v[128:131], v[200:203], v[44:47]
	v_mfma_f32_16x16x32_bf16 v[40:43], v[136:139], v[200:203], v[40:43]
	v_mfma_f32_16x16x32_bf16 v[28:31], v[128:131], v[208:211], v[28:31]
	v_mfma_f32_16x16x32_bf16 v[24:27], v[136:139], v[208:211], v[24:27]
	v_mfma_f32_16x16x32_bf16 v[12:15], v[128:131], v[216:219], v[12:15]
	v_mfma_f32_16x16x32_bf16 v[8:11], v[136:139], v[216:219], v[8:11]
	v_mfma_f32_16x16x32_bf16 v[60:63], v[132:135], v[190:193], v[60:63]
	v_mfma_f32_16x16x32_bf16 v[56:59], v[140:143], v[190:193], v[56:59]
	v_mfma_f32_16x16x32_bf16 v[44:47], v[132:135], v[204:207], v[44:47]
	v_mfma_f32_16x16x32_bf16 v[40:43], v[140:143], v[204:207], v[40:43]
	v_mfma_f32_16x16x32_bf16 v[28:31], v[132:135], v[212:215], v[28:31]
	v_mfma_f32_16x16x32_bf16 v[24:27], v[140:143], v[212:215], v[24:27]
	v_mfma_f32_16x16x32_bf16 v[12:15], v[132:135], v[224:227], v[12:15]
	v_mfma_f32_16x16x32_bf16 v[8:11], v[140:143], v[224:227], v[8:11]
	s_setprio 0
	s_barrier
	s_add_u32 s64, s38, 0x80000
	s_addc_u32 s65, s39, 0
	s_add_i32 s66, s60, s47

; #define PG8_STAGE(bufoff, gbase, voff) do { _Pragma("unroll") for (int _i = 0; _i < 2; ++_i) \
;         __builtin_amdgcn_global_load_lds((const unsigned*)((const char*)(gbase) + (voff)[_i]), (LAS unsigned*)(lds + (bufoff) + ldsw + _i * 8192), 16, 0, 0); } while (0)
; template <class Epi>
; DI void gemm_phase(LAS unsigned char* lds, int wid, int K, int lda, int ldb, bool bperm, const Sched3& S, const Epi& E) {
;     ...
;             PG8_STAGE(PG8_SB(0, 1), b2 + hstepB, voffB);
	s_mov_b32 m0, s66
	s_nop 0
	global_load_lds_dwordx4 v146, s[64:65]

; #define PG8_STAGE(bufoff, gbase, voff) do { _Pragma("unroll") for (int _i = 0; _i < 2; ++_i) \
;         __builtin_amdgcn_global_load_lds((const unsigned*)((const char*)(gbase) + (voff)[_i]), (LAS unsigned*)(lds + (bufoff) + ldsw + _i * 8192), 16, 0, 0); } while (0)
; #define PG8_LDA(dst, b, h) do { _Pragma("unroll") for (int m = 0; m < 4; ++m) _Pragma("unroll") for (int k = 0; k < 2; ++k) dst[m][k] = *(const LAS bf16x8*)(lds + PG8_SA(b, h) + aoff + m * 2048 + k * 1024); } while (0)
; #define PG8_LDB(dst, b, h) do { _Pragma("unroll") for (int n = 0; n < 2; ++n) _Pragma("unroll") for (int k = 0; k < 2; ++k) dst[n][k] = *(const LAS bf16x8*)(lds + PG8_SB(b, h) + boff + n * 2048 + k * 1024); } while (0)
; #define PG8_MMA(ai, bj, At, Bt) do { __builtin_amdgcn_s_setprio(1); _Pragma("unroll") for (int m = 0; m < 4; ++m) _Pragma("unroll") for (int n = 0; n < 2; ++n) _Pragma("unroll") for (int k = 0; k < 2; ++k) \
;         acc[ai][bj][m][n] = __builtin_amdgcn_mfma_f32_16x16x32_bf16(Bt[n][k], At[m][k], acc[ai][bj][m][n], 0, 0, 0); __builtin_amdgcn_s_setprio(0); } while (0)
; #define PG8_WAIT_V(n) asm volatile("s_waitcnt vmcnt(" #n ")" ::: "memory")
; #define PG8_BAR __builtin_amdgcn_s_barrier()
; #define PG8_SCHED __builtin_amdgcn_sched_barrier(0)
; template <class Epi>
; DI void gemm_phase(LAS unsigned char* lds, int wid, int K, int lda, int ldb, bool bperm, const Sched3& S, const Epi& E) {
;     ...
;             PG8_STAGE(PG8_SB(0, 1), b2 + hstepB, voffB);
;             PG8_WAIT_V(6); PG8_BAR; if (full) PG8_MMA(1, 1, At, B1); PG8_BAR;
;             PG8_LDB(B0, 1, 0); PG8_SCHED; PG8_LDA(At, 1, 0); PG8_STAGE(PG8_SA(0, 1), a2 + h2, voffA);
	s_add_i32 m0, s66, 0x2000
	s_nop 0
	global_load_lds_dwordx4 v150, s[64:65]
	s_waitcnt vmcnt(6)
	s_barrier
	s_setprio 1
	v_mfma_f32_16x16x32_bf16 v[52:55], v[228:231], v[180:183], v[52:55]
	v_mfma_f32_16x16x32_bf16 v[48:51], v[236:239], v[180:183], v[48:51]
	v_mfma_f32_16x16x32_bf16 v[36:39], v[228:231], v[200:203], v[36:39]
	v_mfma_f32_16x16x32_bf16 v[32:35], v[236:239], v[200:203], v[32:35]
	v_mfma_f32_16x16x32_bf16 v[20:23], v[228:231], v[208:211], v[20:23]
	v_mfma_f32_16x16x32_bf16 v[16:19], v[236:239], v[208:211], v[16:19]
	v_mfma_f32_16x16x32_bf16 v[4:7], v[228:231], v[216:219], v[4:7]
	v_mfma_f32_16x16x32_bf16 v[0:3], v[236:239], v[216:219], v[0:3]
	v_mfma_f32_16x16x32_bf16 v[52:55], v[232:235], v[190:193], v[52:55]
	v_mfma_f32_16x16x32_bf16 v[48:51], v[240:243], v[190:193], v[48:51]
	v_mfma_f32_16x16x32_bf16 v[36:39], v[232:235], v[204:207], v[36:39]
	v_mfma_f32_16x16x32_bf16 v[32:35], v[240:243], v[204:207], v[32:35]
	v_mfma_f32_16x16x32_bf16 v[20:23], v[232:235], v[212:215], v[20:23]
	v_mfma_f32_16x16x32_bf16 v[16:19], v[240:243], v[212:215], v[16:19]
	v_mfma_f32_16x16x32_bf16 v[4:7], v[232:235], v[224:227], v[4:7]
	v_mfma_f32_16x16x32_bf16 v[0:3], v[240:243], v[224:227], v[0:3]
	s_setprio 0
	s_add_i32 s64, 0, 0x18000
	v_add_u32_e32 v140, s64, v171
	s_barrier
	ds_read_b128 v[128:131], v140
	ds_read_b128 v[132:135], v140 offset:1024
	ds_read_b128 v[136:139], v140 offset:2048
	ds_read_b128 v[140:143], v140 offset:3072
	s_add_u32 s40, s40, 0x80000
	s_addc_u32 s41, s41, 0
	s_mov_b32 m0, s50

; #define PG8_STAGE(bufoff, gbase, voff) do { _Pragma("unroll") for (int _i = 0; _i < 2; ++_i) \
;         __builtin_amdgcn_global_load_lds((const unsigned*)((const char*)(gbase) + (voff)[_i]), (LAS unsigned*)(lds + (bufoff) + ldsw + _i * 8192), 16, 0, 0); } while (0)
; #define PG8_LDA(dst, b, h) do { _Pragma("unroll") for (int m = 0; m < 4; ++m) _Pragma("unroll") for (int k = 0; k < 2; ++k) dst[m][k] = *(const LAS bf16x8*)(lds + PG8_SA(b, h) + aoff + m * 2048 + k * 1024); } while (0)
; #define PG8_LDB(dst, b, h) do { _Pragma("unroll") for (int n = 0; n < 2; ++n) _Pragma("unroll") for (int k = 0; k < 2; ++k) dst[n][k] = *(const LAS bf16x8*)(lds + PG8_SB(b, h) + boff + n * 2048 + k * 1024); } while (0)
; #define PG8_SCHED __builtin_amdgcn_sched_barrier(0)
; template <class Epi>
; DI void gemm_phase(LAS unsigned char* lds, int wid, int K, int lda, int ldb, bool bperm, const Sched3& S, const Epi& E) {
;     ...
;             PG8_LDB(B0, 1, 0); PG8_SCHED; PG8_LDA(At, 1, 0); PG8_STAGE(PG8_SA(0, 1), a2 + h2, voffA);
	ds_read_b128 v[180:183], v195 offset:32768
	ds_read_b128 v[190:193], v195 offset:33792
	ds_read_b128 v[200:203], v195 offset:34816
	ds_read_b128 v[204:207], v195 offset:35840
	ds_read_b128 v[208:211], v195 offset:36864
	ds_read_b128 v[212:215], v195 offset:37888
	ds_read_b128 v[216:219], v195 offset:38912
	ds_read_b128 v[224:227], v195 offset:39936
	global_load_lds_dwordx4 v144, s[40:41]

; #define PG8_STAGE(bufoff, gbase, voff) do { _Pragma("unroll") for (int _i = 0; _i < 2; ++_i) \
;         __builtin_amdgcn_global_load_lds((const unsigned*)((const char*)(gbase) + (voff)[_i]), (LAS unsigned*)(lds + (bufoff) + ldsw + _i * 8192), 16, 0, 0); } while (0)
; #define PG8_LDA(dst, b, h) do { _Pragma("unroll") for (int m = 0; m < 4; ++m) _Pragma("unroll") for (int k = 0; k < 2; ++k) dst[m][k] = *(const LAS bf16x8*)(lds + PG8_SA(b, h) + aoff + m * 2048 + k * 1024); } while (0)
; #define PG8_LDB(dst, b, h) do { _Pragma("unroll") for (int n = 0; n < 2; ++n) _Pragma("unroll") for (int k = 0; k < 2; ++k) dst[n][k] = *(const LAS bf16x8*)(lds + PG8_SB(b, h) + boff + n * 2048 + k * 1024); } while (0)
; #define PG8_MMA(ai, bj, At, Bt) do { __builtin_amdgcn_s_setprio(1); _Pragma("unroll") for (int m = 0; m < 4; ++m) _Pragma("unroll") for (int n = 0; n < 2; ++n) _Pragma("unroll") for (int k = 0; k < 2; ++k) \
;         acc[ai][bj][m][n] = __builtin_amdgcn_mfma_f32_16x16x32_bf16(Bt[n][k], At[m][k], acc[ai][bj][m][n], 0, 0, 0); __builtin_amdgcn_s_setprio(0); } while (0)
; #define PG8_WAIT_L(n) asm volatile("s_waitcnt lgkmcnt(" #n ")" ::: "memory")
; #define PG8_BAR __builtin_amdgcn_s_barrier()
; #define PG8_SCHED __builtin_amdgcn_sched_barrier(0)
; template <class Epi>
; DI void gemm_phase(LAS unsigned char* lds, int wid, int K, int lda, int ldb, bool bperm, const Sched3& S, const Epi& E) {
;     ...
;             PG8_LDB(B0, 1, 0); PG8_SCHED; PG8_LDA(At, 1, 0); PG8_STAGE(PG8_SA(0, 1), a2 + h2, voffA);
;             PG8_WAIT_L(8); PG8_BAR; PG8_WAIT_L(0); PG8_MMA(0, 0, At, B0); PG8_BAR; PG8_SCHED;
	s_mov_b32 m0, s51
	s_nop 0
	global_load_lds_dwordx4 v148, s[40:41]
	s_waitcnt lgkmcnt(8)
	s_barrier
	s_waitcnt lgkmcnt(0)
	s_setprio 1
	s_waitcnt lgkmcnt(0)
	v_mfma_f32_16x16x32_bf16 v[124:127], v[128:131], v[180:183], v[124:127]
	v_mfma_f32_16x16x32_bf16 v[120:123], v[136:139], v[180:183], v[120:123]
	v_mfma_f32_16x16x32_bf16 v[108:111], v[128:131], v[200:203], v[108:111]
	v_mfma_f32_16x16x32_bf16 v[104:107], v[136:139], v[200:203], v[104:107]
	v_mfma_f32_16x16x32_bf16 v[92:95], v[128:131], v[208:211], v[92:95]
	v_mfma_f32_16x16x32_bf16 v[88:91], v[136:139], v[208:211], v[88:91]
	v_mfma_f32_16x16x32_bf16 v[76:79], v[128:131], v[216:219], v[76:79]
	v_mfma_f32_16x16x32_bf16 v[72:75], v[136:139], v[216:219], v[72:75]
	v_mfma_f32_16x16x32_bf16 v[124:127], v[132:135], v[190:193], v[124:127]
	v_mfma_f32_16x16x32_bf16 v[120:123], v[140:143], v[190:193], v[120:123]
	v_mfma_f32_16x16x32_bf16 v[108:111], v[132:135], v[204:207], v[108:111]
	v_mfma_f32_16x16x32_bf16 v[104:107], v[140:143], v[204:207], v[104:107]
	v_mfma_f32_16x16x32_bf16 v[92:95], v[132:135], v[212:215], v[92:95]
	v_mfma_f32_16x16x32_bf16 v[88:91], v[140:143], v[212:215], v[88:91]
	v_mfma_f32_16x16x32_bf16 v[76:79], v[132:135], v[224:227], v[76:79]
	v_mfma_f32_16x16x32_bf16 v[72:75], v[140:143], v[224:227], v[72:75]
	s_setprio 0
	s_barrier
	s_add_i32 s40, 0, 0x1c000
	s_add_i32 s41, s64, s47
	v_add_u32_e32 v152, s40, v171

; #define PG8_STAGE(bufoff, gbase, voff) do { _Pragma("unroll") for (int _i = 0; _i < 2; ++_i) \
;         __builtin_amdgcn_global_load_lds((const unsigned*)((const char*)(gbase) + (voff)[_i]), (LAS unsigned*)(lds + (bufoff) + ldsw + _i * 8192), 16, 0, 0); } while (0)
; #define PG8_LDB(dst, b, h) do { _Pragma("unroll") for (int n = 0; n < 2; ++n) _Pragma("unroll") for (int k = 0; k < 2; ++k) dst[n][k] = *(const LAS bf16x8*)(lds + PG8_SB(b, h) + boff + n * 2048 + k * 1024); } while (0)
; template <class Epi>
; DI void gemm_phase(LAS unsigned char* lds, int wid, int K, int lda, int ldb, bool bperm, const Sched3& S, const Epi& E) {
;     ...
;             PG8_LDB(B1, 1, 1); PG8_STAGE(PG8_SB(1, 0), b3, voffB);
	s_sub_i32 m0, s41, 0x80
	ds_read_b128 v[228:231], v152
	ds_read_b128 v[232:235], v152 offset:1024
	ds_read_b128 v[236:239], v152 offset:2048
	ds_read_b128 v[240:243], v152 offset:3072
	global_load_lds_dwordx4 v146, s[38:39] offset:128

; #define PG8_STAGE(bufoff, gbase, voff) do { _Pragma("unroll") for (int _i = 0; _i < 2; ++_i) \
;         __builtin_amdgcn_global_load_lds((const unsigned*)((const char*)(gbase) + (voff)[_i]), (LAS unsigned*)(lds + (bufoff) + ldsw + _i * 8192), 16, 0, 0); } while (0)
; #define PG8_LDB(dst, b, h) do { _Pragma("unroll") for (int n = 0; n < 2; ++n) _Pragma("unroll") for (int k = 0; k < 2; ++k) dst[n][k] = *(const LAS bf16x8*)(lds + PG8_SB(b, h) + boff + n * 2048 + k * 1024); } while (0)
; #define PG8_MMA(ai, bj, At, Bt) do { __builtin_amdgcn_s_setprio(1); _Pragma("unroll") for (int m = 0; m < 4; ++m) _Pragma("unroll") for (int n = 0; n < 2; ++n) _Pragma("unroll") for (int k = 0; k < 2; ++k) \
;         acc[ai][bj][m][n] = __builtin_amdgcn_mfma_f32_16x16x32_bf16(Bt[n][k], At[m][k], acc[ai][bj][m][n], 0, 0, 0); __builtin_amdgcn_s_setprio(0); } while (0)
; #define PG8_WAIT_L(n) asm volatile("s_waitcnt lgkmcnt(" #n ")" ::: "memory")
; #define PG8_BAR __builtin_amdgcn_s_barrier()
; template <class Epi>
; DI void gemm_phase(LAS unsigned char* lds, int wid, int K, int lda, int ldb, bool bperm, const Sched3& S, const Epi& E) {
;     ...
;             PG8_LDB(B1, 1, 1); PG8_STAGE(PG8_SB(1, 0), b3, voffB);
;             PG8_BAR; PG8_WAIT_L(0); PG8_MMA(0, 1, At, B1); PG8_BAR;
	s_add_i32 m0, s41, 0x1f80
	s_nop 0
	global_load_lds_dwordx4 v150, s[38:39] offset:128
	s_barrier
	s_waitcnt lgkmcnt(0)
	s_setprio 1
	s_waitcnt lgkmcnt(0)
	v_mfma_f32_16x16x32_bf16 v[116:119], v[228:231], v[180:183], v[116:119]
	v_mfma_f32_16x16x32_bf16 v[112:115], v[236:239], v[180:183], v[112:115]
	v_mfma_f32_16x16x32_bf16 v[100:103], v[228:231], v[200:203], v[100:103]
	v_mfma_f32_16x16x32_bf16 v[96:99], v[236:239], v[200:203], v[96:99]
	v_mfma_f32_16x16x32_bf16 v[84:87], v[228:231], v[208:211], v[84:87]
	v_mfma_f32_16x16x32_bf16 v[80:83], v[236:239], v[208:211], v[80:83]
	v_mfma_f32_16x16x32_bf16 v[68:71], v[228:231], v[216:219], v[68:71]
	v_mfma_f32_16x16x32_bf16 v[64:67], v[236:239], v[216:219], v[64:67]
	v_mfma_f32_16x16x32_bf16 v[116:119], v[232:235], v[190:193], v[116:119]
	v_mfma_f32_16x16x32_bf16 v[112:115], v[240:243], v[190:193], v[112:115]
	v_mfma_f32_16x16x32_bf16 v[100:103], v[232:235], v[204:207], v[100:103]
	v_mfma_f32_16x16x32_bf16 v[96:99], v[240:243], v[204:207], v[96:99]
	v_mfma_f32_16x16x32_bf16 v[84:87], v[232:235], v[212:215], v[84:87]
	v_mfma_f32_16x16x32_bf16 v[80:83], v[240:243], v[212:215], v[80:83]
	v_mfma_f32_16x16x32_bf16 v[68:71], v[232:235], v[224:227], v[68:71]
	v_mfma_f32_16x16x32_bf16 v[64:67], v[240:243], v[224:227], v[64:67]
	s_setprio 0
	s_sub_i32 m0, s53, 0x80

; #define PG8_STAGE(bufoff, gbase, voff) do { _Pragma("unroll") for (int _i = 0; _i < 2; ++_i) \
;         __builtin_amdgcn_global_load_lds((const unsigned*)((const char*)(gbase) + (voff)[_i]), (LAS unsigned*)(lds + (bufoff) + ldsw + _i * 8192), 16, 0, 0); } while (0)
; #define PG8_LDA(dst, b, h) do { _Pragma("unroll") for (int m = 0; m < 4; ++m) _Pragma("unroll") for (int k = 0; k < 2; ++k) dst[m][k] = *(const LAS bf16x8*)(lds + PG8_SA(b, h) + aoff + m * 2048 + k * 1024); } while (0)
; template <class Epi>
; DI void gemm_phase(LAS unsigned char* lds, int wid, int K, int lda, int ldb, bool bperm, const Sched3& S, const Epi& E) {
;     ...
;             PG8_LDA(At, 1, 1); PG8_STAGE(PG8_SA(1, 0), a3, voffA);
	s_barrier
	ds_read_b128 v[180:183], v195 offset:49152
	ds_read_b128 v[190:193], v195 offset:50176
	ds_read_b128 v[200:203], v195 offset:51200
	ds_read_b128 v[204:207], v195 offset:52224
	ds_read_b128 v[208:211], v195 offset:53248
	ds_read_b128 v[212:215], v195 offset:54272
	ds_read_b128 v[216:219], v195 offset:55296
	ds_read_b128 v[224:227], v195 offset:56320
	global_load_lds_dwordx4 v144, s[100:101] offset:128

; #define PG8_STAGE(bufoff, gbase, voff) do { _Pragma("unroll") for (int _i = 0; _i < 2; ++_i) \
;         __builtin_amdgcn_global_load_lds((const unsigned*)((const char*)(gbase) + (voff)[_i]), (LAS unsigned*)(lds + (bufoff) + ldsw + _i * 8192), 16, 0, 0); } while (0)
; #define PG8_LDA(dst, b, h) do { _Pragma("unroll") for (int m = 0; m < 4; ++m) _Pragma("unroll") for (int k = 0; k < 2; ++k) dst[m][k] = *(const LAS bf16x8*)(lds + PG8_SA(b, h) + aoff + m * 2048 + k * 1024); } while (0)
; #define PG8_MMA(ai, bj, At, Bt) do { __builtin_amdgcn_s_setprio(1); _Pragma("unroll") for (int m = 0; m < 4; ++m) _Pragma("unroll") for (int n = 0; n < 2; ++n) _Pragma("unroll") for (int k = 0; k < 2; ++k) \
;         acc[ai][bj][m][n] = __builtin_amdgcn_mfma_f32_16x16x32_bf16(Bt[n][k], At[m][k], acc[ai][bj][m][n], 0, 0, 0); __builtin_amdgcn_s_setprio(0); } while (0)
; #define PG8_WAIT_L(n) asm volatile("s_waitcnt lgkmcnt(" #n ")" ::: "memory")
; #define PG8_BAR __builtin_amdgcn_s_barrier()
; #define PG8_SCHED __builtin_amdgcn_sched_barrier(0)
; template <class Epi>
; DI void gemm_phase(LAS unsigned char* lds, int wid, int K, int lda, int ldb, bool bperm, const Sched3& S, const Epi& E) {
;     ...
;             PG8_LDA(At, 1, 1); PG8_STAGE(PG8_SA(1, 0), a3, voffA);
;             PG8_BAR; PG8_WAIT_L(0); if (full) PG8_MMA(1, 0, At, B0); PG8_BAR; PG8_SCHED;
	s_sub_i32 m0, s54, 0x80
	s_nop 0
	global_load_lds_dwordx4 v148, s[100:101] offset:128
	s_barrier
	s_waitcnt lgkmcnt(0)
	s_setprio 1
	s_waitcnt lgkmcnt(0)
	v_mfma_f32_16x16x32_bf16 v[60:63], v[128:131], v[180:183], v[60:63]
	v_mfma_f32_16x16x32_bf16 v[56:59], v[136:139], v[180:183], v[56:59]
	v_mfma_f32_16x16x32_bf16 v[44:47], v[128:131], v[200:203], v[44:47]
	v_mfma_f32_16x16x32_bf16 v[40:43], v[136:139], v[200:203], v[40:43]
	v_mfma_f32_16x16x32_bf16 v[28:31], v[128:131], v[208:211], v[28:31]
	v_mfma_f32_16x16x32_bf16 v[24:27], v[136:139], v[208:211], v[24:27]
	v_mfma_f32_16x16x32_bf16 v[12:15], v[128:131], v[216:219], v[12:15]
	v_mfma_f32_16x16x32_bf16 v[8:11], v[136:139], v[216:219], v[8:11]
	v_mfma_f32_16x16x32_bf16 v[60:63], v[132:135], v[190:193], v[60:63]
	v_mfma_f32_16x16x32_bf16 v[56:59], v[140:143], v[190:193], v[56:59]
	v_mfma_f32_16x16x32_bf16 v[44:47], v[132:135], v[204:207], v[44:47]
	v_mfma_f32_16x16x32_bf16 v[40:43], v[140:143], v[204:207], v[40:43]
	v_mfma_f32_16x16x32_bf16 v[28:31], v[132:135], v[212:215], v[28:31]
	v_mfma_f32_16x16x32_bf16 v[24:27], v[140:143], v[212:215], v[24:27]
	v_mfma_f32_16x16x32_bf16 v[12:15], v[132:135], v[224:227], v[12:15]
	v_mfma_f32_16x16x32_bf16 v[8:11], v[140:143], v[224:227], v[8:11]
	s_setprio 0
	s_barrier
	s_add_u32 s38, s38, 0x80080
	s_addc_u32 s39, s39, 0
	s_add_i32 s40, s40, s47

; #define PG8_STAGE(bufoff, gbase, voff) do { _Pragma("unroll") for (int _i = 0; _i < 2; ++_i) \
;         __builtin_amdgcn_global_load_lds((const unsigned*)((const char*)(gbase) + (voff)[_i]), (LAS unsigned*)(lds + (bufoff) + ldsw + _i * 8192), 16, 0, 0); } while (0)
; template <class Epi>
; DI void gemm_phase(LAS unsigned char* lds, int wid, int K, int lda, int ldb, bool bperm, const Sched3& S, const Epi& E) {
;     ...
;             PG8_STAGE(PG8_SB(1, 1), b3 + hstepB, voffB);
	s_mov_b32 m0, s40
	s_nop 0
	global_load_lds_dwordx4 v146, s[38:39]

; #define PG8_STAGE(bufoff, gbase, voff) do { _Pragma("unroll") for (int _i = 0; _i < 2; ++_i) \
;         __builtin_amdgcn_global_load_lds((const unsigned*)((const char*)(gbase) + (voff)[_i]), (LAS unsigned*)(lds + (bufoff) + ldsw + _i * 8192), 16, 0, 0); } while (0)
; #define PG8_WAIT_V(n) asm volatile("s_waitcnt vmcnt(" #n ")" ::: "memory")
; #define PG8_BAR __builtin_amdgcn_s_barrier()
; #define ROWS8 _Pragma("unroll") for (int ai = 0; ai < 2; ++ai) _Pragma("unroll") for (int m = 0; m < 4; ++m) if (ai == 0 || !hf)
; template <class Epi>
; DI void gemm_phase(LAS unsigned char* lds, int wid, int K, int lda, int ldb, bool bperm, const Sched3& S, const Epi& E) {
;     ...
;             PG8_STAGE(PG8_SB(1, 1), b3 + hstepB, voffB);
;             PG8_WAIT_V(6); PG8_BAR; if (full) PG8_MMA(1, 1, At, B1); PG8_BAR;
;     DI void operator()(const Acc& acc, const Unit& u, int wr, int wc, int fr, int fq) const {
;     ...
;             LOAD_ROW_RS(rsv, SSQ(3), 1.f / 2048.f);
;             if (u.pn < 4) {
;                 bf16_t* dbase = (u.pn < 2) ? WSB(OFF_CQ) : WSB(OFF_CKV); float* sdst = (u.pn < 2) ? SSQ(4 + sqo) : SSQ(5 + sqo);
;                 const int cb = (u.pn & 1) * 256 + wc * 32 + 8 * fq;
;                 ROWS8 { const int r = row0 + ai * HALF + m * 16; const float rs = rsv[ai][m]; float part = 0.f;
;                     bf16_t* dst = dbase + (size_t)r * 512 + cb;
; #pragma unroll
;                     for (int bj = 0; bj < 2; ++bj) { const f32x4 v0 = acc[ai][bj][m][0] * rs, v1 = acc[ai][bj][m][1] * rs; *(u32x4*)(dst + bj * HALF) = PK8(v0, v1);
;                         part += v0[0] * v0[0] + v0[1] * v0[1] + v0[2] * v0[2] + v0[3] * v0[3] + v1[0] * v1[0] + v1[1] * v1[1] + v1[2] * v1[2] + v1[3] * v1[3]; }
;                     part += __shfl_xor(part, 16); part += __shfl_xor(part, 32);
;                     if (fq == 0) unsafeAtomicAdd(sdst + r, part);
;                 }
;             } else if (wc < 2) {
;                 const int j0 = 16 * wc + 4 * fq; const float* cs = WSF(OFF_CS);
; #pragma unroll
;                 for (int ai = 0; ai < 2; ++ai) if (ai == 0 || !hf) {
;                     f32x4 c4[4], s4[4];
; #pragma unroll
;                     for (int m = 0; m < 4; ++m) { const int pos = (row0 + ai * HALF + m * 16) & (SEQ - 1); c4[m] = *(const f32x4*)(cs + pos * 32 + j0); s4[m] = *(const f32x4*)(cs + 4096 * 32 + pos * 32 + j0); }
	s_add_i32 m0, s40, 0x2000
	s_nop 0
	global_load_lds_dwordx4 v150, s[38:39]
	s_waitcnt vmcnt(6)
	s_barrier
	s_setprio 1
	v_mfma_f32_16x16x32_bf16 v[52:55], v[228:231], v[180:183], v[52:55]
	v_mfma_f32_16x16x32_bf16 v[48:51], v[236:239], v[180:183], v[48:51]
	v_mfma_f32_16x16x32_bf16 v[36:39], v[228:231], v[200:203], v[36:39]
	v_mfma_f32_16x16x32_bf16 v[32:35], v[236:239], v[200:203], v[32:35]
	v_mfma_f32_16x16x32_bf16 v[20:23], v[228:231], v[208:211], v[20:23]
	v_mfma_f32_16x16x32_bf16 v[16:19], v[236:239], v[208:211], v[16:19]
	v_mfma_f32_16x16x32_bf16 v[4:7], v[228:231], v[216:219], v[4:7]
	v_mfma_f32_16x16x32_bf16 v[0:3], v[236:239], v[216:219], v[0:3]
	v_mfma_f32_16x16x32_bf16 v[52:55], v[232:235], v[190:193], v[52:55]
	v_mfma_f32_16x16x32_bf16 v[48:51], v[240:243], v[190:193], v[48:51]
	v_mfma_f32_16x16x32_bf16 v[36:39], v[232:235], v[204:207], v[36:39]
	v_mfma_f32_16x16x32_bf16 v[32:35], v[240:243], v[204:207], v[32:35]
	v_mfma_f32_16x16x32_bf16 v[20:23], v[232:235], v[212:215], v[20:23]
	v_mfma_f32_16x16x32_bf16 v[16:19], v[240:243], v[212:215], v[16:19]
	v_mfma_f32_16x16x32_bf16 v[4:7], v[232:235], v[224:227], v[4:7]
	v_mfma_f32_16x16x32_bf16 v[0:3], v[240:243], v[224:227], v[0:3]
	s_setprio 0
	s_add_i32 s27, s27, 2
	s_add_u32 s36, s36, 0x100
	s_addc_u32 s37, s37, 0
	s_add_u32 s19, s19, 0x100
	s_addc_u32 s21, s21, 0
	s_cmp_gt_u32 s27, 29
	s_cbranch_scc0 .Lkrot_4_head
.Lkrot_4_exit:
	s_barrier
.Lpeel_4_exit:
	v_lshl_add_u32 v192, s26, 8, v167
	v_or_b32_e32 v190, 16, v192
	v_or_b32_e32 v186, 32, v192
	v_ashrrev_i32_e32 v193, 31, v192
	v_ashrrev_i32_e32 v191, 31, v190
	v_ashrrev_i32_e32 v187, 31, v186
	v_or_b32_e32 v182, 48, v192
	v_lshl_add_u64 v[128:129], v[192:193], 2, s[16:17]
	v_lshl_add_u64 v[130:131], v[190:191], 2, s[16:17]
	v_lshl_add_u64 v[132:133], v[186:187], 2, s[16:17]
	v_ashrrev_i32_e32 v183, 31, v182
	global_load_dword v136, v[128:129], off
	global_load_dword v137, v[128:129], off offset:512
	global_load_dword v138, v[128:129], off offset:576
	global_load_dword v139, v[128:129], off offset:640
	v_lshl_add_u64 v[134:135], v[182:183], 2, s[16:17]
	global_load_dword v130, v[130:131], off
	s_nop 0
	global_load_dword v131, v[132:133], off
	s_nop 0
	global_load_dword v132, v[134:135], off
	s_nop 0
	global_load_dword v128, v[128:129], off offset:704
	v_add_u32_e32 v180, 0x80, v192
	v_add_u32_e32 v176, 0x90, v192
	v_add_u32_e32 v172, 0xa0, v192
	v_add_u32_e32 v168, 0xb0, v192
	v_ashrrev_i32_e32 v181, 31, v180
	v_ashrrev_i32_e32 v177, 31, v176
	v_ashrrev_i32_e32 v173, 31, v172
	v_ashrrev_i32_e32 v169, 31, v168
	s_cmp_gt_i32 s63, 3
	s_mov_b64 s[26:27], -1
	s_waitcnt vmcnt(0)
	v_fmamk_f32 v129, v136, 0x3a000000, v198
	v_fmamk_f32 v133, v137, 0x3a000000, v198
	v_fmamk_f32 v134, v138, 0x3a000000, v198
	v_fmamk_f32 v135, v139, 0x3a000000, v198
	v_rsq_f32_e32 v196, v129
	v_fmamk_f32 v129, v130, 0x3a000000, v198
	v_fmamk_f32 v130, v131, 0x3a000000, v198
	v_fmamk_f32 v131, v132, 0x3a000000, v198
	v_fmamk_f32 v128, v128, 0x3a000000, v198
	v_rsq_f32_e32 v178, v133
	v_rsq_f32_e32 v174, v134
	v_rsq_f32_e32 v170, v135
	v_rsq_f32_e32 v194, v129
	v_rsq_f32_e32 v188, v130
	v_rsq_f32_e32 v184, v131
	v_rsq_f32_e32 v166, v128
	s_cbranch_scc0 .LBB0_878
	s_andn2_b64 vcc, exec, s[14:15]
	s_cbranch_vccnz .LBB0_877
	v_lshlrev_b32_e32 v128, 7, v192
	v_and_b32_e32 v152, 0x7e780, v128
	v_lshl_add_u64 v[128:129], v[154:155], 0, v[152:153]
	global_load_dwordx4 v[136:139], v[128:129], off
	v_lshl_add_u64 v[130:131], v[156:157], 0, v[152:153]
	global_load_dwordx4 v[140:143], v[130:131], off
	global_load_dwordx4 v[200:203], v[128:129], off offset:2048
	global_load_dwordx4 v[204:207], v[130:131], off offset:2048
	v_or_b32_e32 v128, 0x1000, v152
	v_mov_b32_e32 v129, v153
	v_lshl_add_u64 v[130:131], v[154:155], 0, v[128:129]
	v_lshl_add_u64 v[128:129], v[156:157], 0, v[128:129]
	global_load_dwordx4 v[208:211], v[130:131], off
	global_load_dwordx4 v[212:215], v[128:129], off
	v_or_b32_e32 v152, 0x1800, v152
	v_lshl_add_u64 v[128:129], v[154:155], 0, v[152:153]
	v_lshl_add_u64 v[132:133], v[156:157], 0, v[152:153]
	global_load_dwordx4 v[128:131], v[128:129], off
	v_pk_mul_f32 v[216:217], v[126:127], v[196:197] op_sel_hi:[1,0]
	global_load_dwordx4 v[132:135], v[132:133], off
	v_pk_mul_f32 v[218:219], v[124:125], v[196:197] op_sel_hi:[1,0]
	v_pk_mul_f32 v[220:221], v[122:123], v[196:197] op_sel_hi:[1,0]
	v_pk_mul_f32 v[222:223], v[120:121], v[196:197] op_sel_hi:[1,0]
	v_lshlrev_b64 v[224:225], 7, v[192:193]
	v_lshl_add_u64 v[224:225], v[158:159], 0, v[224:225]
	s_waitcnt vmcnt(0)
; DI u32x2 pk4(f32x4 v) { u32x2 r; r.x = pk2(v[0], v[1]); r.y = pk2(v[2], v[3]); return r; }
;     DI void operator()(const Acc& acc, const Unit& u, int wr, int wc, int fr, int fq) const {
;     ...
;                     for (int m = 0; m < 4; ++m) { const int pos = (row0 + ai * HALF + m * 16) & (SEQ - 1); c4[m] = *(const f32x4*)(cs + pos * 32 + j0); s4[m] = *(const f32x4*)(cs + 4096 * 32 + pos * 32 + j0); }
; #pragma unroll
;                     for (int m = 0; m < 4; ++m) { const int r = row0 + ai * HALF + m * 16; const float rs = rsv[ai][m];
;                         const f32x4 x1 = acc[ai][0][m][0] * rs, x2 = acc[ai][0][m][1] * rs;
;                         bf16_t* dst = WSB(OFF_KR) + (size_t)r * 64 + j0;
;                         *(u32x2*)(dst) = pk4(x1 * c4[m] - x2 * s4[m]); *(u32x2*)(dst + 32) = pk4(x2 * c4[m] + x1 * s4[m]); }
	v_pk_mul_f32 v[226:227], v[220:221], v[142:143]
	v_pk_mul_f32 v[228:229], v[222:223], v[140:141]
	v_pk_mul_f32 v[142:143], v[216:217], v[142:143]
	v_pk_mul_f32 v[140:141], v[218:219], v[140:141]
	v_pk_fma_f32 v[226:227], v[216:217], v[138:139], v[226:227] neg_lo:[0,0,1] neg_hi:[0,0,1]
	v_pk_fma_f32 v[228:229], v[218:219], v[136:137], v[228:229] neg_lo:[0,0,1] neg_hi:[0,0,1]
	v_pk_fma_f32 v[138:139], v[220:221], v[138:139], v[142:143]
	v_pk_fma_f32 v[136:137], v[222:223], v[136:137], v[140:141]
	v_pk_mul_f32 v[140:141], v[106:107], v[194:195] op_sel_hi:[1,0]
	v_cvt_pk_bf16_f32 v136, v136, v137
	v_cvt_pk_bf16_f32 v137, v138, v139
	v_pk_mul_f32 v[142:143], v[104:105], v[194:195] op_sel_hi:[1,0]
	global_store_dwordx2 v[224:225], v[136:137], off offset:64
	v_pk_mul_f32 v[136:137], v[110:111], v[194:195] op_sel_hi:[1,0]
	v_pk_mul_f32 v[138:139], v[108:109], v[194:195] op_sel_hi:[1,0]
	v_pk_mul_f32 v[218:219], v[140:141], v[206:207]
	v_pk_mul_f32 v[220:221], v[142:143], v[204:205]
	v_pk_fma_f32 v[218:219], v[136:137], v[202:203], v[218:219] neg_lo:[0,0,1] neg_hi:[0,0,1]
	v_pk_fma_f32 v[220:221], v[138:139], v[200:201], v[220:221] neg_lo:[0,0,1] neg_hi:[0,0,1]
	v_pk_mul_f32 v[136:137], v[136:137], v[206:207]
	v_pk_mul_f32 v[138:139], v[138:139], v[204:205]
	v_lshlrev_b64 v[216:217], 7, v[190:191]
	v_pk_fma_f32 v[136:137], v[140:141], v[202:203], v[136:137]
	v_pk_fma_f32 v[138:139], v[142:143], v[200:201], v[138:139]
	v_lshl_add_u64 v[216:217], v[158:159], 0, v[216:217]
	v_cvt_pk_bf16_f32 v138, v138, v139
	v_cvt_pk_bf16_f32 v139, v136, v137
	v_pk_mul_f32 v[140:141], v[90:91], v[188:189] op_sel_hi:[1,0]
	v_pk_mul_f32 v[142:143], v[88:89], v[188:189] op_sel_hi:[1,0]
	global_store_dwordx2 v[216:217], v[138:139], off offset:64
	v_pk_mul_f32 v[136:137], v[94:95], v[188:189] op_sel_hi:[1,0]
	v_pk_mul_f32 v[138:139], v[92:93], v[188:189] op_sel_hi:[1,0]
	v_pk_mul_f32 v[202:203], v[140:141], v[214:215]
	v_pk_mul_f32 v[204:205], v[142:143], v[212:213]
	v_pk_fma_f32 v[202:203], v[136:137], v[210:211], v[202:203] neg_lo:[0,0,1] neg_hi:[0,0,1]
	v_pk_fma_f32 v[204:205], v[138:139], v[208:209], v[204:205] neg_lo:[0,0,1] neg_hi:[0,0,1]
	v_pk_mul_f32 v[136:137], v[136:137], v[214:215]
	v_pk_mul_f32 v[138:139], v[138:139], v[212:213]
	v_lshlrev_b64 v[200:201], 7, v[186:187]
	v_pk_fma_f32 v[136:137], v[140:141], v[210:211], v[136:137]
	v_pk_fma_f32 v[138:139], v[142:143], v[208:209], v[138:139]
	v_lshl_add_u64 v[200:201], v[158:159], 0, v[200:201]
	v_cvt_pk_bf16_f32 v138, v138, v139
	v_cvt_pk_bf16_f32 v139, v136, v137
	v_cvt_pk_bf16_f32 v204, v204, v205
	v_cvt_pk_bf16_f32 v205, v202, v203
	global_store_dwordx2 v[200:201], v[138:139], off offset:64
	v_pk_mul_f32 v[136:137], v[78:79], v[184:185] op_sel_hi:[1,0]
	v_pk_mul_f32 v[138:139], v[76:77], v[184:185] op_sel_hi:[1,0]
	v_pk_mul_f32 v[140:141], v[74:75], v[184:185] op_sel_hi:[1,0]
	v_pk_mul_f32 v[142:143], v[72:73], v[184:185] op_sel_hi:[1,0]
	global_store_dwordx2 v[200:201], v[204:205], off
	v_pk_mul_f32 v[202:203], v[140:141], v[134:135]
	v_pk_mul_f32 v[204:205], v[142:143], v[132:133]
	v_pk_mul_f32 v[134:135], v[136:137], v[134:135]
	v_pk_mul_f32 v[132:133], v[138:139], v[132:133]
	v_lshlrev_b64 v[200:201], 7, v[182:183]
	v_pk_fma_f32 v[202:203], v[136:137], v[130:131], v[202:203] neg_lo:[0,0,1] neg_hi:[0,0,1]
	v_pk_fma_f32 v[204:205], v[138:139], v[128:129], v[204:205] neg_lo:[0,0,1] neg_hi:[0,0,1]
	v_pk_fma_f32 v[130:131], v[140:141], v[130:131], v[134:135]
	v_pk_fma_f32 v[128:129], v[142:143], v[128:129], v[132:133]
	v_lshl_add_u64 v[200:201], v[158:159], 0, v[200:201]
	v_cvt_pk_bf16_f32 v128, v128, v129
	v_cvt_pk_bf16_f32 v129, v130, v131
	global_store_dwordx2 v[200:201], v[128:129], off offset:64
	v_lshl_add_u32 v128, v192, 5, v199
	v_and_b32_e32 v128, 0x1f9e0, v128
	v_cvt_pk_bf16_f32 v228, v228, v229
	v_cvt_pk_bf16_f32 v229, v226, v227
	v_cvt_pk_bf16_f32 v220, v220, v221
	v_cvt_pk_bf16_f32 v221, v218, v219
	v_cvt_pk_bf16_f32 v204, v204, v205
	v_cvt_pk_bf16_f32 v205, v202, v203
	v_lshlrev_b32_e32 v152, 2, v128
	global_store_dwordx2 v[224:225], v[228:229], off
	global_store_dwordx2 v[216:217], v[220:221], off
	global_store_dwordx2 v[200:201], v[204:205], off
	v_lshl_add_u64 v[128:129], v[154:155], 0, v[152:153]
	global_load_dwordx4 v[200:203], v[128:129], off
	v_lshl_add_u64 v[130:131], v[156:157], 0, v[152:153]
	global_load_dwordx4 v[204:207], v[130:131], off
	global_load_dwordx4 v[208:211], v[128:129], off offset:2048
	global_load_dwordx4 v[212:215], v[130:131], off offset:2048
	v_or_b32_e32 v128, 0x1000, v152
	v_mov_b32_e32 v129, v153
	v_lshl_add_u64 v[130:131], v[154:155], 0, v[128:129]
	v_lshl_add_u64 v[128:129], v[156:157], 0, v[128:129]
	global_load_dwordx4 v[132:135], v[130:131], off
	global_load_dwordx4 v[140:143], v[128:129], off
	v_or_b32_e32 v152, 0x1800, v152
	v_lshl_add_u64 v[128:129], v[154:155], 0, v[152:153]
	v_lshl_add_u64 v[136:137], v[156:157], 0, v[152:153]
	global_load_dwordx4 v[128:131], v[128:129], off
	v_pk_mul_f32 v[216:217], v[62:63], v[178:179] op_sel_hi:[1,0]
	global_load_dwordx4 v[136:139], v[136:137], off
	v_pk_mul_f32 v[218:219], v[60:61], v[178:179] op_sel_hi:[1,0]
	v_pk_mul_f32 v[220:221], v[58:59], v[178:179] op_sel_hi:[1,0]
	v_pk_mul_f32 v[222:223], v[56:57], v[178:179] op_sel_hi:[1,0]
	v_lshlrev_b64 v[224:225], 7, v[180:181]
	v_lshl_add_u64 v[224:225], v[158:159], 0, v[224:225]
	s_waitcnt vmcnt(0)
; DI u32x2 pk4(f32x4 v) { u32x2 r; r.x = pk2(v[0], v[1]); r.y = pk2(v[2], v[3]); return r; }
;     DI void operator()(const Acc& acc, const Unit& u, int wr, int wc, int fr, int fq) const {
;     ...
;                     for (int m = 0; m < 4; ++m) { const int r = row0 + ai * HALF + m * 16; const float rs = rsv[ai][m];
;                         const f32x4 x1 = acc[ai][0][m][0] * rs, x2 = acc[ai][0][m][1] * rs;
;                         bf16_t* dst = WSB(OFF_KR) + (size_t)r * 64 + j0;
;                         *(u32x2*)(dst) = pk4(x1 * c4[m] - x2 * s4[m]); *(u32x2*)(dst + 32) = pk4(x2 * c4[m] + x1 * s4[m]); }
	v_pk_mul_f32 v[226:227], v[220:221], v[206:207]
	v_pk_mul_f32 v[228:229], v[222:223], v[204:205]
	v_pk_mul_f32 v[206:207], v[216:217], v[206:207]
	v_pk_mul_f32 v[204:205], v[218:219], v[204:205]
	v_pk_fma_f32 v[226:227], v[216:217], v[202:203], v[226:227] neg_lo:[0,0,1] neg_hi:[0,0,1]
	v_pk_fma_f32 v[228:229], v[218:219], v[200:201], v[228:229] neg_lo:[0,0,1] neg_hi:[0,0,1]
	v_pk_fma_f32 v[202:203], v[220:221], v[202:203], v[206:207]
	v_pk_fma_f32 v[200:201], v[222:223], v[200:201], v[204:205]
	v_pk_mul_f32 v[204:205], v[42:43], v[174:175] op_sel_hi:[1,0]
	v_cvt_pk_bf16_f32 v200, v200, v201
	v_cvt_pk_bf16_f32 v201, v202, v203
	v_pk_mul_f32 v[206:207], v[40:41], v[174:175] op_sel_hi:[1,0]
	global_store_dwordx2 v[224:225], v[200:201], off offset:64
	v_pk_mul_f32 v[200:201], v[46:47], v[174:175] op_sel_hi:[1,0]
	v_pk_mul_f32 v[202:203], v[44:45], v[174:175] op_sel_hi:[1,0]
	v_pk_mul_f32 v[218:219], v[204:205], v[214:215]
	v_pk_mul_f32 v[220:221], v[206:207], v[212:213]
	v_pk_fma_f32 v[218:219], v[200:201], v[210:211], v[218:219] neg_lo:[0,0,1] neg_hi:[0,0,1]
	v_pk_fma_f32 v[220:221], v[202:203], v[208:209], v[220:221] neg_lo:[0,0,1] neg_hi:[0,0,1]
	v_pk_mul_f32 v[200:201], v[200:201], v[214:215]
	v_pk_mul_f32 v[202:203], v[202:203], v[212:213]
	v_lshlrev_b64 v[216:217], 7, v[176:177]
	v_pk_fma_f32 v[200:201], v[204:205], v[210:211], v[200:201]
	v_pk_fma_f32 v[202:203], v[206:207], v[208:209], v[202:203]
	v_lshl_add_u64 v[216:217], v[158:159], 0, v[216:217]
	v_cvt_pk_bf16_f32 v202, v202, v203
	v_cvt_pk_bf16_f32 v203, v200, v201
	global_store_dwordx2 v[216:217], v[202:203], off offset:64
	v_pk_mul_f32 v[200:201], v[30:31], v[170:171] op_sel_hi:[1,0]
	v_pk_mul_f32 v[202:203], v[28:29], v[170:171] op_sel_hi:[1,0]
	v_pk_mul_f32 v[204:205], v[26:27], v[170:171] op_sel_hi:[1,0]
	v_pk_mul_f32 v[206:207], v[24:25], v[170:171] op_sel_hi:[1,0]
	v_pk_mul_f32 v[210:211], v[204:205], v[142:143]
	v_pk_mul_f32 v[212:213], v[206:207], v[140:141]
	v_pk_mul_f32 v[142:143], v[200:201], v[142:143]
	v_pk_mul_f32 v[140:141], v[202:203], v[140:141]
	v_lshlrev_b64 v[208:209], 7, v[172:173]
	v_pk_fma_f32 v[210:211], v[200:201], v[134:135], v[210:211] neg_lo:[0,0,1] neg_hi:[0,0,1]
	v_pk_fma_f32 v[212:213], v[202:203], v[132:133], v[212:213] neg_lo:[0,0,1] neg_hi:[0,0,1]
	v_pk_fma_f32 v[134:135], v[204:205], v[134:135], v[142:143]
	v_pk_fma_f32 v[132:133], v[206:207], v[132:133], v[140:141]
	v_lshl_add_u64 v[208:209], v[158:159], 0, v[208:209]
	v_cvt_pk_bf16_f32 v132, v132, v133
	v_cvt_pk_bf16_f32 v133, v134, v135
	v_pk_mul_f32 v[140:141], v[10:11], v[166:167] op_sel_hi:[1,0]
	v_pk_mul_f32 v[142:143], v[8:9], v[166:167] op_sel_hi:[1,0]
	global_store_dwordx2 v[208:209], v[132:133], off offset:64
	v_pk_mul_f32 v[132:133], v[14:15], v[166:167] op_sel_hi:[1,0]
	v_pk_mul_f32 v[134:135], v[12:13], v[166:167] op_sel_hi:[1,0]
	v_pk_mul_f32 v[202:203], v[140:141], v[138:139]
	v_pk_mul_f32 v[204:205], v[142:143], v[136:137]
	v_pk_fma_f32 v[202:203], v[132:133], v[130:131], v[202:203] neg_lo:[0,0,1] neg_hi:[0,0,1]
	v_pk_fma_f32 v[204:205], v[134:135], v[128:129], v[204:205] neg_lo:[0,0,1] neg_hi:[0,0,1]
	v_pk_mul_f32 v[132:133], v[132:133], v[138:139]
	v_pk_mul_f32 v[134:135], v[134:135], v[136:137]
	v_lshlrev_b64 v[200:201], 7, v[168:169]
	v_pk_fma_f32 v[130:131], v[140:141], v[130:131], v[132:133]
	v_pk_fma_f32 v[128:129], v[142:143], v[128:129], v[134:135]
	v_cvt_pk_bf16_f32 v228, v228, v229
	v_cvt_pk_bf16_f32 v229, v226, v227
	v_cvt_pk_bf16_f32 v220, v220, v221
	v_cvt_pk_bf16_f32 v221, v218, v219
	v_cvt_pk_bf16_f32 v212, v212, v213
	v_cvt_pk_bf16_f32 v213, v210, v211
	v_lshl_add_u64 v[200:201], v[158:159], 0, v[200:201]
	v_cvt_pk_bf16_f32 v204, v204, v205
	v_cvt_pk_bf16_f32 v205, v202, v203
	v_cvt_pk_bf16_f32 v128, v128, v129
	v_cvt_pk_bf16_f32 v129, v130, v131
	global_store_dwordx2 v[224:225], v[228:229], off
	global_store_dwordx2 v[216:217], v[220:221], off
	global_store_dwordx2 v[208:209], v[212:213], off
	global_store_dwordx2 v[200:201], v[204:205], off
	global_store_dwordx2 v[200:201], v[128:129], off offset:64

; #define PG8_STAGE(bufoff, gbase, voff) do { _Pragma("unroll") for (int _i = 0; _i < 2; ++_i) \
;         __builtin_amdgcn_global_load_lds((const unsigned*)((const char*)(gbase) + (voff)[_i]), (LAS unsigned*)(lds + (bufoff) + ldsw + _i * 8192), 16, 0, 0); } while (0)
; #define PG8_LDA(dst, b, h) do { _Pragma("unroll") for (int m = 0; m < 4; ++m) _Pragma("unroll") for (int k = 0; k < 2; ++k) dst[m][k] = *(const LAS bf16x8*)(lds + PG8_SA(b, h) + aoff + m * 2048 + k * 1024); } while (0)
; #define PG8_LDB(dst, b, h) do { _Pragma("unroll") for (int n = 0; n < 2; ++n) _Pragma("unroll") for (int k = 0; k < 2; ++k) dst[n][k] = *(const LAS bf16x8*)(lds + PG8_SB(b, h) + boff + n * 2048 + k * 1024); } while (0)
; #define PG8_SCHED __builtin_amdgcn_sched_barrier(0)
; template <class Epi>
; DI void gemm_phase(LAS unsigned char* lds, int wid, int K, int lda, int ldb, bool bperm, const Sched3& S, const Epi& E) {
;     ...
;         const bool has_next = S.next(ui + 1, nxt);
;         const char* nA = has_next ? nxt.A : cA; const char* nB = has_next ? nxt.B : cB; const size_t nhA = has_next ? (nxt.half ? (size_t)0 : hstepA) : hA; const bool full = (cur.half == 0);
;         for (int t = 0; t < nt; t += 2) {
;             const bool last = (t == nt - 2);
;             const char* a1 = cA + (size_t)(t + 1) * kstep;
;             const char* a2 = last ? nA : cA + (size_t)(t + 2) * kstep; const char* b2 = last ? nB : cB + (size_t)(t + 2) * kstep;
;             const char* a3 = a2 + kstep; const char* b3 = b2 + kstep; const size_t h2 = last ? nhA : hA;
;             PG8_LDB(B0, 0, 0); PG8_SCHED; PG8_LDA(At, 0, 0); PG8_STAGE(PG8_SA(1, 1), a1 + hA, voffA);
.LBB0_995:
	s_xor_b64 s[48:49], s[56:57], -1
	s_and_b64 s[56:57], s[56:57], exec
	s_cselect_b32 s41, s45, s53
	s_cselect_b32 s43, s44, s52
	s_cselect_b32 s51, s47, s55
	s_cselect_b32 s58, s46, s54
	s_add_u32 s52, s52, 0x20080
	s_addc_u32 s53, s53, 0
	s_add_u32 s59, s54, 0x100
	s_nop 0
	s_addc_u32 s60, s55, 0
	s_mov_b32 s61, -2
	ds_read_b128 v[156:159], v182
	ds_read_b128 v[160:163], v182 offset:1024
	ds_read_b128 v[164:167], v182 offset:2048
	ds_read_b128 v[168:171], v182 offset:3072
	s_add_u32 s54, s52, 0xfffe0080
	s_addc_u32 s55, s53, -1
	s_cmp_eq_u32 s61, 4
	s_cselect_b32 s57, s41, s55
	s_cselect_b32 s56, s43, s54
	s_cselect_b32 s55, s51, s60
	s_cselect_b32 s54, s58, s59

; #define PG8_STAGE(bufoff, gbase, voff) do { _Pragma("unroll") for (int _i = 0; _i < 2; ++_i) \
;         __builtin_amdgcn_global_load_lds((const unsigned*)((const char*)(gbase) + (voff)[_i]), (LAS unsigned*)(lds + (bufoff) + ldsw + _i * 8192), 16, 0, 0); } while (0)
; #define PG8_LDA(dst, b, h) do { _Pragma("unroll") for (int m = 0; m < 4; ++m) _Pragma("unroll") for (int k = 0; k < 2; ++k) dst[m][k] = *(const LAS bf16x8*)(lds + PG8_SA(b, h) + aoff + m * 2048 + k * 1024); } while (0)
; #define PG8_LDB(dst, b, h) do { _Pragma("unroll") for (int n = 0; n < 2; ++n) _Pragma("unroll") for (int k = 0; k < 2; ++k) dst[n][k] = *(const LAS bf16x8*)(lds + PG8_SB(b, h) + boff + n * 2048 + k * 1024); } while (0)
; #define PG8_SCHED __builtin_amdgcn_sched_barrier(0)
; template <class Epi>
; DI void gemm_phase(LAS unsigned char* lds, int wid, int K, int lda, int ldb, bool bperm, const Sched3& S, const Epi& E) {
;     ...
;             PG8_LDB(B0, 0, 0); PG8_SCHED; PG8_LDA(At, 0, 0); PG8_STAGE(PG8_SA(1, 1), a1 + hA, voffA);
	s_add_i32 m0, s66, 0xc000
	ds_read_b128 v[172:175], v183
	ds_read_b128 v[186:189], v183 offset:1024
	ds_read_b128 v[190:193], v183 offset:2048
	ds_read_b128 v[194:197], v183 offset:3072
	ds_read_b128 v[198:201], v183 offset:4096
	ds_read_b128 v[202:205], v183 offset:5120
	ds_read_b128 v[206:209], v183 offset:6144
	ds_read_b128 v[210:213], v183 offset:7168
	global_load_lds_dwordx4 v144, s[52:53]

; #define PG8_STAGE(bufoff, gbase, voff) do { _Pragma("unroll") for (int _i = 0; _i < 2; ++_i) \
;         __builtin_amdgcn_global_load_lds((const unsigned*)((const char*)(gbase) + (voff)[_i]), (LAS unsigned*)(lds + (bufoff) + ldsw + _i * 8192), 16, 0, 0); } while (0)
; #define PG8_LDA(dst, b, h) do { _Pragma("unroll") for (int m = 0; m < 4; ++m) _Pragma("unroll") for (int k = 0; k < 2; ++k) dst[m][k] = *(const LAS bf16x8*)(lds + PG8_SA(b, h) + aoff + m * 2048 + k * 1024); } while (0)
; #define PG8_LDB(dst, b, h) do { _Pragma("unroll") for (int n = 0; n < 2; ++n) _Pragma("unroll") for (int k = 0; k < 2; ++k) dst[n][k] = *(const LAS bf16x8*)(lds + PG8_SB(b, h) + boff + n * 2048 + k * 1024); } while (0)
; #define PG8_MMA(ai, bj, At, Bt) do { __builtin_amdgcn_s_setprio(1); _Pragma("unroll") for (int m = 0; m < 4; ++m) _Pragma("unroll") for (int n = 0; n < 2; ++n) _Pragma("unroll") for (int k = 0; k < 2; ++k) \
;         acc[ai][bj][m][n] = __builtin_amdgcn_mfma_f32_16x16x32_bf16(Bt[n][k], At[m][k], acc[ai][bj][m][n], 0, 0, 0); __builtin_amdgcn_s_setprio(0); } while (0)
; #define PG8_WAIT_L(n) asm volatile("s_waitcnt lgkmcnt(" #n ")" ::: "memory")
; #define PG8_BAR __builtin_amdgcn_s_barrier()
; #define PG8_SCHED __builtin_amdgcn_sched_barrier(0)
; template <class Epi>
; DI void gemm_phase(LAS unsigned char* lds, int wid, int K, int lda, int ldb, bool bperm, const Sched3& S, const Epi& E) {
;     ...
;             PG8_LDB(B0, 0, 0); PG8_SCHED; PG8_LDA(At, 0, 0); PG8_STAGE(PG8_SA(1, 1), a1 + hA, voffA);
;             PG8_WAIT_L(8); PG8_BAR; PG8_WAIT_L(0); PG8_MMA(0, 0, At, B0); PG8_BAR; PG8_SCHED;
	s_add_i32 m0, s66, 0xe000
	s_nop 0
	global_load_lds_dwordx4 v146, s[52:53]
	s_waitcnt lgkmcnt(8)
	s_barrier
	s_waitcnt lgkmcnt(0)
	s_setprio 1
	s_waitcnt lgkmcnt(0)
	v_mfma_f32_16x16x32_bf16 v[124:127], v[156:159], v[172:175], 0
	v_mfma_f32_16x16x32_bf16 v[120:123], v[164:167], v[172:175], 0
	v_mfma_f32_16x16x32_bf16 v[116:119], v[156:159], v[190:193], 0
	v_mfma_f32_16x16x32_bf16 v[112:115], v[164:167], v[190:193], 0
	v_mfma_f32_16x16x32_bf16 v[108:111], v[156:159], v[198:201], 0
	v_mfma_f32_16x16x32_bf16 v[104:107], v[164:167], v[198:201], 0
	v_mfma_f32_16x16x32_bf16 v[100:103], v[156:159], v[206:209], 0
	v_mfma_f32_16x16x32_bf16 v[96:99], v[164:167], v[206:209], 0
	v_mfma_f32_16x16x32_bf16 v[124:127], v[160:163], v[186:189], v[124:127]
	v_mfma_f32_16x16x32_bf16 v[120:123], v[168:171], v[186:189], v[120:123]
	v_mfma_f32_16x16x32_bf16 v[116:119], v[160:163], v[194:197], v[116:119]
	v_mfma_f32_16x16x32_bf16 v[112:115], v[168:171], v[194:197], v[112:115]
	v_mfma_f32_16x16x32_bf16 v[108:111], v[160:163], v[202:205], v[108:111]
	v_mfma_f32_16x16x32_bf16 v[104:107], v[168:171], v[202:205], v[104:107]
	v_mfma_f32_16x16x32_bf16 v[100:103], v[160:163], v[210:213], v[100:103]
	v_mfma_f32_16x16x32_bf16 v[96:99], v[168:171], v[210:213], v[96:99]
	s_setprio 0
	s_barrier
	s_add_i32 s62, s76, s65

; #define PG8_STAGE(bufoff, gbase, voff) do { _Pragma("unroll") for (int _i = 0; _i < 2; ++_i) \
;         __builtin_amdgcn_global_load_lds((const unsigned*)((const char*)(gbase) + (voff)[_i]), (LAS unsigned*)(lds + (bufoff) + ldsw + _i * 8192), 16, 0, 0); } while (0)
; #define PG8_LDB(dst, b, h) do { _Pragma("unroll") for (int n = 0; n < 2; ++n) _Pragma("unroll") for (int k = 0; k < 2; ++k) dst[n][k] = *(const LAS bf16x8*)(lds + PG8_SB(b, h) + boff + n * 2048 + k * 1024); } while (0)
; template <class Epi>
; DI void gemm_phase(LAS unsigned char* lds, int wid, int K, int lda, int ldb, bool bperm, const Sched3& S, const Epi& E) {
;     ...
;             PG8_LDB(B1, 0, 1); PG8_STAGE(PG8_SB(0, 0), b2, voffB);
	s_mov_b32 m0, s62
	ds_read_b128 v[214:217], v184
	ds_read_b128 v[218:221], v184 offset:1024
	ds_read_b128 v[224:227], v184 offset:2048
	ds_read_b128 v[228:231], v184 offset:3072
	global_load_lds_dwordx4 v130, s[54:55]

; #define PG8_STAGE(bufoff, gbase, voff) do { _Pragma("unroll") for (int _i = 0; _i < 2; ++_i) \
;         __builtin_amdgcn_global_load_lds((const unsigned*)((const char*)(gbase) + (voff)[_i]), (LAS unsigned*)(lds + (bufoff) + ldsw + _i * 8192), 16, 0, 0); } while (0)
; #define PG8_LDA(dst, b, h) do { _Pragma("unroll") for (int m = 0; m < 4; ++m) _Pragma("unroll") for (int k = 0; k < 2; ++k) dst[m][k] = *(const LAS bf16x8*)(lds + PG8_SA(b, h) + aoff + m * 2048 + k * 1024); } while (0)
; #define PG8_LDB(dst, b, h) do { _Pragma("unroll") for (int n = 0; n < 2; ++n) _Pragma("unroll") for (int k = 0; k < 2; ++k) dst[n][k] = *(const LAS bf16x8*)(lds + PG8_SB(b, h) + boff + n * 2048 + k * 1024); } while (0)
; #define PG8_MMA(ai, bj, At, Bt) do { __builtin_amdgcn_s_setprio(1); _Pragma("unroll") for (int m = 0; m < 4; ++m) _Pragma("unroll") for (int n = 0; n < 2; ++n) _Pragma("unroll") for (int k = 0; k < 2; ++k) \
;         acc[ai][bj][m][n] = __builtin_amdgcn_mfma_f32_16x16x32_bf16(Bt[n][k], At[m][k], acc[ai][bj][m][n], 0, 0, 0); __builtin_amdgcn_s_setprio(0); } while (0)
; #define PG8_WAIT_L(n) asm volatile("s_waitcnt lgkmcnt(" #n ")" ::: "memory")
; #define PG8_BAR __builtin_amdgcn_s_barrier()
; #define PG8_SCHED __builtin_amdgcn_sched_barrier(0)
; template <class Epi>
; DI void gemm_phase(LAS unsigned char* lds, int wid, int K, int lda, int ldb, bool bperm, const Sched3& S, const Epi& E) {
;     ...
;             PG8_LDB(B1, 0, 1); PG8_STAGE(PG8_SB(0, 0), b2, voffB);
;             PG8_BAR; PG8_WAIT_L(0); PG8_MMA(0, 1, At, B1); PG8_BAR;
;             PG8_LDA(At, 0, 1); PG8_STAGE(PG8_SA(0, 0), a2, voffA);
;             PG8_BAR; PG8_WAIT_L(0); if (full) PG8_MMA(1, 0, At, B0); PG8_BAR; PG8_SCHED;
;             PG8_STAGE(PG8_SB(0, 1), b2 + hstepB, voffB);
	s_add_i32 m0, s62, 0x2000
	s_nop 0
	global_load_lds_dwordx4 v134, s[54:55]
	s_barrier
	s_waitcnt lgkmcnt(0)
	s_setprio 1
	s_waitcnt lgkmcnt(0)
	v_mfma_f32_16x16x32_bf16 v[60:63], v[214:217], v[172:175], 0
	v_mfma_f32_16x16x32_bf16 v[56:59], v[224:227], v[172:175], 0
	v_mfma_f32_16x16x32_bf16 v[52:55], v[214:217], v[190:193], 0
	v_mfma_f32_16x16x32_bf16 v[48:51], v[224:227], v[190:193], 0
	v_mfma_f32_16x16x32_bf16 v[44:47], v[214:217], v[198:201], 0
	v_mfma_f32_16x16x32_bf16 v[40:43], v[224:227], v[198:201], 0
	v_mfma_f32_16x16x32_bf16 v[36:39], v[214:217], v[206:209], 0
	v_mfma_f32_16x16x32_bf16 v[32:35], v[224:227], v[206:209], 0
	v_mfma_f32_16x16x32_bf16 v[60:63], v[218:221], v[186:189], v[60:63]
	v_mfma_f32_16x16x32_bf16 v[56:59], v[228:231], v[186:189], v[56:59]
	v_mfma_f32_16x16x32_bf16 v[52:55], v[218:221], v[194:197], v[52:55]
	v_mfma_f32_16x16x32_bf16 v[48:51], v[228:231], v[194:197], v[48:51]
	v_mfma_f32_16x16x32_bf16 v[44:47], v[218:221], v[202:205], v[44:47]
	v_mfma_f32_16x16x32_bf16 v[40:43], v[228:231], v[202:205], v[40:43]
	v_mfma_f32_16x16x32_bf16 v[36:39], v[218:221], v[210:213], v[36:39]
	v_mfma_f32_16x16x32_bf16 v[32:35], v[228:231], v[210:213], v[32:35]
	s_setprio 0
	s_mov_b32 m0, s66
	s_mov_b64 s[100:101], s[56:57]
	s_barrier
	ds_read_b128 v[172:175], v183 offset:16384
	ds_read_b128 v[186:189], v183 offset:17408
	ds_read_b128 v[190:193], v183 offset:18432
	ds_read_b128 v[194:197], v183 offset:19456
	ds_read_b128 v[198:201], v183 offset:20480
	ds_read_b128 v[202:205], v183 offset:21504
	ds_read_b128 v[206:209], v183 offset:22528
	ds_read_b128 v[210:213], v183 offset:23552
	global_load_lds_dwordx4 v128, s[56:57]
	s_mov_b64 s[100:101], s[56:57]
	s_mov_b32 m0, s67
	s_nop 0
	global_load_lds_dwordx4 v132, s[56:57]
	s_barrier
	s_waitcnt lgkmcnt(0)
	s_setprio 1
	s_waitcnt lgkmcnt(0)
	v_mfma_f32_16x16x32_bf16 v[92:95], v[156:159], v[172:175], 0
	v_mfma_f32_16x16x32_bf16 v[88:91], v[164:167], v[172:175], 0
	v_mfma_f32_16x16x32_bf16 v[84:87], v[156:159], v[190:193], 0
	v_mfma_f32_16x16x32_bf16 v[80:83], v[164:167], v[190:193], 0
	v_mfma_f32_16x16x32_bf16 v[76:79], v[156:159], v[198:201], 0
	v_mfma_f32_16x16x32_bf16 v[72:75], v[164:167], v[198:201], 0
	v_mfma_f32_16x16x32_bf16 v[68:71], v[156:159], v[206:209], 0
	v_mfma_f32_16x16x32_bf16 v[64:67], v[164:167], v[206:209], 0
	v_mfma_f32_16x16x32_bf16 v[92:95], v[160:163], v[186:189], v[92:95]
	v_mfma_f32_16x16x32_bf16 v[88:91], v[168:171], v[186:189], v[88:91]
	v_mfma_f32_16x16x32_bf16 v[84:87], v[160:163], v[194:197], v[84:87]
	v_mfma_f32_16x16x32_bf16 v[80:83], v[168:171], v[194:197], v[80:83]
	v_mfma_f32_16x16x32_bf16 v[76:79], v[160:163], v[202:205], v[76:79]
	v_mfma_f32_16x16x32_bf16 v[72:75], v[168:171], v[202:205], v[72:75]
	v_mfma_f32_16x16x32_bf16 v[68:71], v[160:163], v[210:213], v[68:71]
	v_mfma_f32_16x16x32_bf16 v[64:67], v[168:171], v[210:213], v[64:67]
	s_setprio 0
	s_barrier
	s_add_u32 s62, s54, 0x20000
	s_addc_u32 s63, s55, 0
	s_add_i32 s86, s77, s65

; #define PG8_STAGE(bufoff, gbase, voff) do { _Pragma("unroll") for (int _i = 0; _i < 2; ++_i) \
;         __builtin_amdgcn_global_load_lds((const unsigned*)((const char*)(gbase) + (voff)[_i]), (LAS unsigned*)(lds + (bufoff) + ldsw + _i * 8192), 16, 0, 0); } while (0)
; template <class Epi>
; DI void gemm_phase(LAS unsigned char* lds, int wid, int K, int lda, int ldb, bool bperm, const Sched3& S, const Epi& E) {
;     ...
;             PG8_STAGE(PG8_SB(0, 1), b2 + hstepB, voffB);
	s_mov_b32 m0, s86
	s_nop 0
	global_load_lds_dwordx4 v130, s[62:63]

; #define PG8_STAGE(bufoff, gbase, voff) do { _Pragma("unroll") for (int _i = 0; _i < 2; ++_i) \
;         __builtin_amdgcn_global_load_lds((const unsigned*)((const char*)(gbase) + (voff)[_i]), (LAS unsigned*)(lds + (bufoff) + ldsw + _i * 8192), 16, 0, 0); } while (0)
; #define PG8_LDA(dst, b, h) do { _Pragma("unroll") for (int m = 0; m < 4; ++m) _Pragma("unroll") for (int k = 0; k < 2; ++k) dst[m][k] = *(const LAS bf16x8*)(lds + PG8_SA(b, h) + aoff + m * 2048 + k * 1024); } while (0)
; #define PG8_LDB(dst, b, h) do { _Pragma("unroll") for (int n = 0; n < 2; ++n) _Pragma("unroll") for (int k = 0; k < 2; ++k) dst[n][k] = *(const LAS bf16x8*)(lds + PG8_SB(b, h) + boff + n * 2048 + k * 1024); } while (0)
; #define PG8_MMA(ai, bj, At, Bt) do { __builtin_amdgcn_s_setprio(1); _Pragma("unroll") for (int m = 0; m < 4; ++m) _Pragma("unroll") for (int n = 0; n < 2; ++n) _Pragma("unroll") for (int k = 0; k < 2; ++k) \
;         acc[ai][bj][m][n] = __builtin_amdgcn_mfma_f32_16x16x32_bf16(Bt[n][k], At[m][k], acc[ai][bj][m][n], 0, 0, 0); __builtin_amdgcn_s_setprio(0); } while (0)
; #define PG8_WAIT_V(n) asm volatile("s_waitcnt vmcnt(" #n ")" ::: "memory")
; #define PG8_BAR __builtin_amdgcn_s_barrier()
; #define PG8_SCHED __builtin_amdgcn_sched_barrier(0)
; template <class Epi>
; DI void gemm_phase(LAS unsigned char* lds, int wid, int K, int lda, int ldb, bool bperm, const Sched3& S, const Epi& E) {
;     ...
;             PG8_STAGE(PG8_SB(0, 1), b2 + hstepB, voffB);
;             PG8_WAIT_V(6); PG8_BAR; if (full) PG8_MMA(1, 1, At, B1); PG8_BAR;
;             PG8_LDB(B0, 1, 0); PG8_SCHED; PG8_LDA(At, 1, 0); PG8_STAGE(PG8_SA(0, 1), a2 + h2, voffA);
	s_add_i32 m0, s86, 0x2000
	s_nop 0
	global_load_lds_dwordx4 v134, s[62:63]
	s_waitcnt vmcnt(6)
	s_barrier
	s_setprio 1
	v_mfma_f32_16x16x32_bf16 v[28:31], v[214:217], v[172:175], 0
	v_mfma_f32_16x16x32_bf16 v[24:27], v[224:227], v[172:175], 0
	v_mfma_f32_16x16x32_bf16 v[20:23], v[214:217], v[190:193], 0
	v_mfma_f32_16x16x32_bf16 v[16:19], v[224:227], v[190:193], 0
	v_mfma_f32_16x16x32_bf16 v[12:15], v[214:217], v[198:201], 0
	v_mfma_f32_16x16x32_bf16 v[8:11], v[224:227], v[198:201], 0
	v_mfma_f32_16x16x32_bf16 v[4:7], v[214:217], v[206:209], 0
	v_mfma_f32_16x16x32_bf16 v[0:3], v[224:227], v[206:209], 0
	v_mfma_f32_16x16x32_bf16 v[28:31], v[218:221], v[186:189], v[28:31]
	v_mfma_f32_16x16x32_bf16 v[24:27], v[228:231], v[186:189], v[24:27]
	v_mfma_f32_16x16x32_bf16 v[20:23], v[218:221], v[194:197], v[20:23]
	v_mfma_f32_16x16x32_bf16 v[16:19], v[228:231], v[194:197], v[16:19]
	v_mfma_f32_16x16x32_bf16 v[12:15], v[218:221], v[202:205], v[12:15]
	v_mfma_f32_16x16x32_bf16 v[8:11], v[228:231], v[202:205], v[8:11]
	v_mfma_f32_16x16x32_bf16 v[4:7], v[218:221], v[210:213], v[4:7]
	v_mfma_f32_16x16x32_bf16 v[0:3], v[228:231], v[210:213], v[0:3]
	s_setprio 0
	s_add_i32 s62, 0, 0x18000
	v_add_u32_e32 v136, s62, v179
	s_barrier
	ds_read_b128 v[156:159], v136
	ds_read_b128 v[160:163], v136 offset:1024
	ds_read_b128 v[164:167], v136 offset:2048
	ds_read_b128 v[168:171], v136 offset:3072
	s_add_u32 s56, s56, 0x20000
	s_addc_u32 s57, s57, 0
	s_mov_b32 m0, s68

; #define PG8_STAGE(bufoff, gbase, voff) do { _Pragma("unroll") for (int _i = 0; _i < 2; ++_i) \
;         __builtin_amdgcn_global_load_lds((const unsigned*)((const char*)(gbase) + (voff)[_i]), (LAS unsigned*)(lds + (bufoff) + ldsw + _i * 8192), 16, 0, 0); } while (0)
; #define PG8_LDA(dst, b, h) do { _Pragma("unroll") for (int m = 0; m < 4; ++m) _Pragma("unroll") for (int k = 0; k < 2; ++k) dst[m][k] = *(const LAS bf16x8*)(lds + PG8_SA(b, h) + aoff + m * 2048 + k * 1024); } while (0)
; #define PG8_LDB(dst, b, h) do { _Pragma("unroll") for (int n = 0; n < 2; ++n) _Pragma("unroll") for (int k = 0; k < 2; ++k) dst[n][k] = *(const LAS bf16x8*)(lds + PG8_SB(b, h) + boff + n * 2048 + k * 1024); } while (0)
; #define PG8_SCHED __builtin_amdgcn_sched_barrier(0)
; template <class Epi>
; DI void gemm_phase(LAS unsigned char* lds, int wid, int K, int lda, int ldb, bool bperm, const Sched3& S, const Epi& E) {
;     ...
;             PG8_LDB(B0, 1, 0); PG8_SCHED; PG8_LDA(At, 1, 0); PG8_STAGE(PG8_SA(0, 1), a2 + h2, voffA);
	ds_read_b128 v[172:175], v183 offset:32768
	ds_read_b128 v[186:189], v183 offset:33792
	ds_read_b128 v[190:193], v183 offset:34816
	ds_read_b128 v[194:197], v183 offset:35840
	ds_read_b128 v[198:201], v183 offset:36864
	ds_read_b128 v[202:205], v183 offset:37888
	ds_read_b128 v[206:209], v183 offset:38912
	ds_read_b128 v[210:213], v183 offset:39936
	global_load_lds_dwordx4 v128, s[56:57]

; #define PG8_STAGE(bufoff, gbase, voff) do { _Pragma("unroll") for (int _i = 0; _i < 2; ++_i) \
;         __builtin_amdgcn_global_load_lds((const unsigned*)((const char*)(gbase) + (voff)[_i]), (LAS unsigned*)(lds + (bufoff) + ldsw + _i * 8192), 16, 0, 0); } while (0)
; #define PG8_LDA(dst, b, h) do { _Pragma("unroll") for (int m = 0; m < 4; ++m) _Pragma("unroll") for (int k = 0; k < 2; ++k) dst[m][k] = *(const LAS bf16x8*)(lds + PG8_SA(b, h) + aoff + m * 2048 + k * 1024); } while (0)
; #define PG8_LDB(dst, b, h) do { _Pragma("unroll") for (int n = 0; n < 2; ++n) _Pragma("unroll") for (int k = 0; k < 2; ++k) dst[n][k] = *(const LAS bf16x8*)(lds + PG8_SB(b, h) + boff + n * 2048 + k * 1024); } while (0)
; #define PG8_MMA(ai, bj, At, Bt) do { __builtin_amdgcn_s_setprio(1); _Pragma("unroll") for (int m = 0; m < 4; ++m) _Pragma("unroll") for (int n = 0; n < 2; ++n) _Pragma("unroll") for (int k = 0; k < 2; ++k) \
;         acc[ai][bj][m][n] = __builtin_amdgcn_mfma_f32_16x16x32_bf16(Bt[n][k], At[m][k], acc[ai][bj][m][n], 0, 0, 0); __builtin_amdgcn_s_setprio(0); } while (0)
; #define PG8_WAIT_L(n) asm volatile("s_waitcnt lgkmcnt(" #n ")" ::: "memory")
; #define PG8_BAR __builtin_amdgcn_s_barrier()
; #define PG8_SCHED __builtin_amdgcn_sched_barrier(0)
; template <class Epi>
; DI void gemm_phase(LAS unsigned char* lds, int wid, int K, int lda, int ldb, bool bperm, const Sched3& S, const Epi& E) {
;     ...
;             PG8_LDB(B0, 1, 0); PG8_SCHED; PG8_LDA(At, 1, 0); PG8_STAGE(PG8_SA(0, 1), a2 + h2, voffA);
;             PG8_WAIT_L(8); PG8_BAR; PG8_WAIT_L(0); PG8_MMA(0, 0, At, B0); PG8_BAR; PG8_SCHED;
	s_mov_b32 m0, s69
	s_nop 0
	global_load_lds_dwordx4 v132, s[56:57]
	s_waitcnt lgkmcnt(8)
	s_barrier
	s_waitcnt lgkmcnt(0)
	s_setprio 1
	s_waitcnt lgkmcnt(0)
	v_mfma_f32_16x16x32_bf16 v[124:127], v[156:159], v[172:175], v[124:127]
	v_mfma_f32_16x16x32_bf16 v[120:123], v[164:167], v[172:175], v[120:123]
	v_mfma_f32_16x16x32_bf16 v[116:119], v[156:159], v[190:193], v[116:119]
	v_mfma_f32_16x16x32_bf16 v[112:115], v[164:167], v[190:193], v[112:115]
	v_mfma_f32_16x16x32_bf16 v[108:111], v[156:159], v[198:201], v[108:111]
	v_mfma_f32_16x16x32_bf16 v[104:107], v[164:167], v[198:201], v[104:107]
	v_mfma_f32_16x16x32_bf16 v[100:103], v[156:159], v[206:209], v[100:103]
	v_mfma_f32_16x16x32_bf16 v[96:99], v[164:167], v[206:209], v[96:99]
	v_mfma_f32_16x16x32_bf16 v[124:127], v[160:163], v[186:189], v[124:127]
	v_mfma_f32_16x16x32_bf16 v[120:123], v[168:171], v[186:189], v[120:123]
	v_mfma_f32_16x16x32_bf16 v[116:119], v[160:163], v[194:197], v[116:119]
	v_mfma_f32_16x16x32_bf16 v[112:115], v[168:171], v[194:197], v[112:115]
	v_mfma_f32_16x16x32_bf16 v[108:111], v[160:163], v[202:205], v[108:111]
	v_mfma_f32_16x16x32_bf16 v[104:107], v[168:171], v[202:205], v[104:107]
	v_mfma_f32_16x16x32_bf16 v[100:103], v[160:163], v[210:213], v[100:103]
	v_mfma_f32_16x16x32_bf16 v[96:99], v[168:171], v[210:213], v[96:99]
	s_setprio 0
	s_barrier
	s_add_i32 s56, 0, 0x1c000
	s_add_i32 s57, s62, s65
	v_add_u32_e32 v136, s56, v179

; #define PG8_STAGE(bufoff, gbase, voff) do { _Pragma("unroll") for (int _i = 0; _i < 2; ++_i) \
;         __builtin_amdgcn_global_load_lds((const unsigned*)((const char*)(gbase) + (voff)[_i]), (LAS unsigned*)(lds + (bufoff) + ldsw + _i * 8192), 16, 0, 0); } while (0)
; #define PG8_LDB(dst, b, h) do { _Pragma("unroll") for (int n = 0; n < 2; ++n) _Pragma("unroll") for (int k = 0; k < 2; ++k) dst[n][k] = *(const LAS bf16x8*)(lds + PG8_SB(b, h) + boff + n * 2048 + k * 1024); } while (0)
; template <class Epi>
; DI void gemm_phase(LAS unsigned char* lds, int wid, int K, int lda, int ldb, bool bperm, const Sched3& S, const Epi& E) {
;     ...
;             PG8_LDB(B1, 1, 1); PG8_STAGE(PG8_SB(1, 0), b3, voffB);
	s_sub_i32 m0, s57, 0x80
	ds_read_b128 v[214:217], v136
	ds_read_b128 v[218:221], v136 offset:1024
	ds_read_b128 v[224:227], v136 offset:2048
	ds_read_b128 v[228:231], v136 offset:3072
	global_load_lds_dwordx4 v130, s[54:55] offset:128

; #define PG8_STAGE(bufoff, gbase, voff) do { _Pragma("unroll") for (int _i = 0; _i < 2; ++_i) \
;         __builtin_amdgcn_global_load_lds((const unsigned*)((const char*)(gbase) + (voff)[_i]), (LAS unsigned*)(lds + (bufoff) + ldsw + _i * 8192), 16, 0, 0); } while (0)
; #define PG8_LDB(dst, b, h) do { _Pragma("unroll") for (int n = 0; n < 2; ++n) _Pragma("unroll") for (int k = 0; k < 2; ++k) dst[n][k] = *(const LAS bf16x8*)(lds + PG8_SB(b, h) + boff + n * 2048 + k * 1024); } while (0)
; #define PG8_MMA(ai, bj, At, Bt) do { __builtin_amdgcn_s_setprio(1); _Pragma("unroll") for (int m = 0; m < 4; ++m) _Pragma("unroll") for (int n = 0; n < 2; ++n) _Pragma("unroll") for (int k = 0; k < 2; ++k) \
;         acc[ai][bj][m][n] = __builtin_amdgcn_mfma_f32_16x16x32_bf16(Bt[n][k], At[m][k], acc[ai][bj][m][n], 0, 0, 0); __builtin_amdgcn_s_setprio(0); } while (0)
; #define PG8_WAIT_L(n) asm volatile("s_waitcnt lgkmcnt(" #n ")" ::: "memory")
; #define PG8_BAR __builtin_amdgcn_s_barrier()
; template <class Epi>
; DI void gemm_phase(LAS unsigned char* lds, int wid, int K, int lda, int ldb, bool bperm, const Sched3& S, const Epi& E) {
;     ...
;             PG8_LDB(B1, 1, 1); PG8_STAGE(PG8_SB(1, 0), b3, voffB);
;             PG8_BAR; PG8_WAIT_L(0); PG8_MMA(0, 1, At, B1); PG8_BAR;
	s_add_i32 m0, s57, 0x1f80
	s_nop 0
	global_load_lds_dwordx4 v134, s[54:55] offset:128
	s_barrier
	s_waitcnt lgkmcnt(0)
	s_setprio 1
	s_waitcnt lgkmcnt(0)
	v_mfma_f32_16x16x32_bf16 v[60:63], v[214:217], v[172:175], v[60:63]
	v_mfma_f32_16x16x32_bf16 v[56:59], v[224:227], v[172:175], v[56:59]
	v_mfma_f32_16x16x32_bf16 v[52:55], v[214:217], v[190:193], v[52:55]
	v_mfma_f32_16x16x32_bf16 v[48:51], v[224:227], v[190:193], v[48:51]
	v_mfma_f32_16x16x32_bf16 v[44:47], v[214:217], v[198:201], v[44:47]
	v_mfma_f32_16x16x32_bf16 v[40:43], v[224:227], v[198:201], v[40:43]
	v_mfma_f32_16x16x32_bf16 v[36:39], v[214:217], v[206:209], v[36:39]
	v_mfma_f32_16x16x32_bf16 v[32:35], v[224:227], v[206:209], v[32:35]
	v_mfma_f32_16x16x32_bf16 v[60:63], v[218:221], v[186:189], v[60:63]
	v_mfma_f32_16x16x32_bf16 v[56:59], v[228:231], v[186:189], v[56:59]
	v_mfma_f32_16x16x32_bf16 v[52:55], v[218:221], v[194:197], v[52:55]
	v_mfma_f32_16x16x32_bf16 v[48:51], v[228:231], v[194:197], v[48:51]
	v_mfma_f32_16x16x32_bf16 v[44:47], v[218:221], v[202:205], v[44:47]
	v_mfma_f32_16x16x32_bf16 v[40:43], v[228:231], v[202:205], v[40:43]
	v_mfma_f32_16x16x32_bf16 v[36:39], v[218:221], v[210:213], v[36:39]
	v_mfma_f32_16x16x32_bf16 v[32:35], v[228:231], v[210:213], v[32:35]
	s_setprio 0
	s_sub_i32 m0, s72, 0x80

; #define PG8_STAGE(bufoff, gbase, voff) do { _Pragma("unroll") for (int _i = 0; _i < 2; ++_i) \
;         __builtin_amdgcn_global_load_lds((const unsigned*)((const char*)(gbase) + (voff)[_i]), (LAS unsigned*)(lds + (bufoff) + ldsw + _i * 8192), 16, 0, 0); } while (0)
; #define PG8_LDA(dst, b, h) do { _Pragma("unroll") for (int m = 0; m < 4; ++m) _Pragma("unroll") for (int k = 0; k < 2; ++k) dst[m][k] = *(const LAS bf16x8*)(lds + PG8_SA(b, h) + aoff + m * 2048 + k * 1024); } while (0)
; #define PG8_MMA(ai, bj, At, Bt) do { __builtin_amdgcn_s_setprio(1); _Pragma("unroll") for (int m = 0; m < 4; ++m) _Pragma("unroll") for (int n = 0; n < 2; ++n) _Pragma("unroll") for (int k = 0; k < 2; ++k) \
;         acc[ai][bj][m][n] = __builtin_amdgcn_mfma_f32_16x16x32_bf16(Bt[n][k], At[m][k], acc[ai][bj][m][n], 0, 0, 0); __builtin_amdgcn_s_setprio(0); } while (0)
; #define PG8_WAIT_L(n) asm volatile("s_waitcnt lgkmcnt(" #n ")" ::: "memory")
; #define PG8_BAR __builtin_amdgcn_s_barrier()
; template <class Epi>
; DI void gemm_phase(LAS unsigned char* lds, int wid, int K, int lda, int ldb, bool bperm, const Sched3& S, const Epi& E) {
;     ...
;             PG8_BAR; PG8_WAIT_L(0); PG8_MMA(0, 1, At, B1); PG8_BAR;
;             PG8_LDA(At, 1, 1); PG8_STAGE(PG8_SA(1, 0), a3, voffA);
	s_barrier
	ds_read_b128 v[172:175], v183 offset:49152
	ds_read_b128 v[186:189], v183 offset:50176
	ds_read_b128 v[190:193], v183 offset:51200
	ds_read_b128 v[194:197], v183 offset:52224
	ds_read_b128 v[198:201], v183 offset:53248
	ds_read_b128 v[202:205], v183 offset:54272
	ds_read_b128 v[206:209], v183 offset:55296
	ds_read_b128 v[210:213], v183 offset:56320
	global_load_lds_dwordx4 v128, s[100:101] offset:128

; #define PG8_MMA(ai, bj, At, Bt) do { __builtin_amdgcn_s_setprio(1); _Pragma("unroll") for (int m = 0; m < 4; ++m) _Pragma("unroll") for (int n = 0; n < 2; ++n) _Pragma("unroll") for (int k = 0; k < 2; ++k) \
;         acc[ai][bj][m][n] = __builtin_amdgcn_mfma_f32_16x16x32_bf16(Bt[n][k], At[m][k], acc[ai][bj][m][n], 0, 0, 0); __builtin_amdgcn_s_setprio(0); } while (0)
; #define PG8_WAIT_L(n) asm volatile("s_waitcnt lgkmcnt(" #n ")" ::: "memory")
; #define PG8_BAR __builtin_amdgcn_s_barrier()
; #define PG8_SCHED __builtin_amdgcn_sched_barrier(0)
; template <class Epi>
; DI void gemm_phase(LAS unsigned char* lds, int wid, int K, int lda, int ldb, bool bperm, const Sched3& S, const Epi& E) {
;     ...
;             PG8_BAR; PG8_WAIT_L(0); if (full) PG8_MMA(1, 0, At, B0); PG8_BAR; PG8_SCHED;
	s_sub_i32 m0, s73, 0x80
	s_nop 0
	global_load_lds_dwordx4 v132, s[100:101] offset:128
	s_barrier
	s_waitcnt lgkmcnt(0)
	s_setprio 1
	s_waitcnt lgkmcnt(0)
	v_mfma_f32_16x16x32_bf16 v[92:95], v[156:159], v[172:175], v[92:95]
	v_mfma_f32_16x16x32_bf16 v[88:91], v[164:167], v[172:175], v[88:91]
	v_mfma_f32_16x16x32_bf16 v[84:87], v[156:159], v[190:193], v[84:87]
	v_mfma_f32_16x16x32_bf16 v[80:83], v[164:167], v[190:193], v[80:83]
	v_mfma_f32_16x16x32_bf16 v[76:79], v[156:159], v[198:201], v[76:79]
	v_mfma_f32_16x16x32_bf16 v[72:75], v[164:167], v[198:201], v[72:75]
	v_mfma_f32_16x16x32_bf16 v[68:71], v[156:159], v[206:209], v[68:71]
	v_mfma_f32_16x16x32_bf16 v[64:67], v[164:167], v[206:209], v[64:67]
	v_mfma_f32_16x16x32_bf16 v[92:95], v[160:163], v[186:189], v[92:95]
	v_mfma_f32_16x16x32_bf16 v[88:91], v[168:171], v[186:189], v[88:91]
	v_mfma_f32_16x16x32_bf16 v[84:87], v[160:163], v[194:197], v[84:87]
	v_mfma_f32_16x16x32_bf16 v[80:83], v[168:171], v[194:197], v[80:83]
	v_mfma_f32_16x16x32_bf16 v[76:79], v[160:163], v[202:205], v[76:79]
	v_mfma_f32_16x16x32_bf16 v[72:75], v[168:171], v[202:205], v[72:75]
	v_mfma_f32_16x16x32_bf16 v[68:71], v[160:163], v[210:213], v[68:71]
	v_mfma_f32_16x16x32_bf16 v[64:67], v[168:171], v[210:213], v[64:67]
	s_setprio 0
	s_barrier
	s_add_u32 s54, s54, 0x20080
	s_addc_u32 s55, s55, 0
	s_add_i32 s56, s56, s65

; #define PG8_STAGE(bufoff, gbase, voff) do { _Pragma("unroll") for (int _i = 0; _i < 2; ++_i) \
;         __builtin_amdgcn_global_load_lds((const unsigned*)((const char*)(gbase) + (voff)[_i]), (LAS unsigned*)(lds + (bufoff) + ldsw + _i * 8192), 16, 0, 0); } while (0)
; template <class Epi>
; DI void gemm_phase(LAS unsigned char* lds, int wid, int K, int lda, int ldb, bool bperm, const Sched3& S, const Epi& E) {
;     ...
;             PG8_STAGE(PG8_SB(1, 1), b3 + hstepB, voffB);
	s_mov_b32 m0, s56
	s_nop 0
	global_load_lds_dwordx4 v130, s[54:55]

; #define PG8_STAGE(bufoff, gbase, voff) do { _Pragma("unroll") for (int _i = 0; _i < 2; ++_i) \
;         __builtin_amdgcn_global_load_lds((const unsigned*)((const char*)(gbase) + (voff)[_i]), (LAS unsigned*)(lds + (bufoff) + ldsw + _i * 8192), 16, 0, 0); } while (0)
; #define PG8_MMA(ai, bj, At, Bt) do { __builtin_amdgcn_s_setprio(1); _Pragma("unroll") for (int m = 0; m < 4; ++m) _Pragma("unroll") for (int n = 0; n < 2; ++n) _Pragma("unroll") for (int k = 0; k < 2; ++k) \
;         acc[ai][bj][m][n] = __builtin_amdgcn_mfma_f32_16x16x32_bf16(Bt[n][k], At[m][k], acc[ai][bj][m][n], 0, 0, 0); __builtin_amdgcn_s_setprio(0); } while (0)
; #define PG8_WAIT_V(n) asm volatile("s_waitcnt vmcnt(" #n ")" ::: "memory")
; #define PG8_BAR __builtin_amdgcn_s_barrier()
; template <class Epi>
; DI void gemm_phase(LAS unsigned char* lds, int wid, int K, int lda, int ldb, bool bperm, const Sched3& S, const Epi& E) {
;     ...
;             PG8_STAGE(PG8_SB(1, 1), b3 + hstepB, voffB);
;             PG8_WAIT_V(6); PG8_BAR; if (full) PG8_MMA(1, 1, At, B1); PG8_BAR;
	s_add_i32 m0, s56, 0x2000
	s_nop 0
	global_load_lds_dwordx4 v134, s[54:55]
	s_waitcnt vmcnt(6)
	s_barrier
	s_setprio 1
	v_mfma_f32_16x16x32_bf16 v[28:31], v[214:217], v[172:175], v[28:31]
	v_mfma_f32_16x16x32_bf16 v[24:27], v[224:227], v[172:175], v[24:27]
	v_mfma_f32_16x16x32_bf16 v[20:23], v[214:217], v[190:193], v[20:23]
	v_mfma_f32_16x16x32_bf16 v[16:19], v[224:227], v[190:193], v[16:19]
	v_mfma_f32_16x16x32_bf16 v[12:15], v[214:217], v[198:201], v[12:15]
	v_mfma_f32_16x16x32_bf16 v[8:11], v[224:227], v[198:201], v[8:11]
	v_mfma_f32_16x16x32_bf16 v[4:7], v[214:217], v[206:209], v[4:7]
	v_mfma_f32_16x16x32_bf16 v[0:3], v[224:227], v[206:209], v[0:3]
	v_mfma_f32_16x16x32_bf16 v[28:31], v[218:221], v[186:189], v[28:31]
	v_mfma_f32_16x16x32_bf16 v[24:27], v[228:231], v[186:189], v[24:27]
	v_mfma_f32_16x16x32_bf16 v[20:23], v[218:221], v[194:197], v[20:23]
	v_mfma_f32_16x16x32_bf16 v[16:19], v[228:231], v[194:197], v[16:19]
	v_mfma_f32_16x16x32_bf16 v[12:15], v[218:221], v[202:205], v[12:15]
	v_mfma_f32_16x16x32_bf16 v[8:11], v[228:231], v[202:205], v[8:11]
	v_mfma_f32_16x16x32_bf16 v[4:7], v[218:221], v[210:213], v[4:7]
	v_mfma_f32_16x16x32_bf16 v[0:3], v[228:231], v[210:213], v[0:3]
	s_setprio 0
	s_add_i32 s61, s61, 2
	s_add_u32 s52, s52, 0x100
	s_addc_u32 s53, s53, 0
	s_add_u32 s59, s59, 0x100
	s_addc_u32 s60, s60, 0
	s_cmp_gt_u32 s61, 5
	s_cbranch_scc1 .Lkrot_5_exit

; #define PG8_STAGE(bufoff, gbase, voff) do { _Pragma("unroll") for (int _i = 0; _i < 2; ++_i) \
;         __builtin_amdgcn_global_load_lds((const unsigned*)((const char*)(gbase) + (voff)[_i]), (LAS unsigned*)(lds + (bufoff) + ldsw + _i * 8192), 16, 0, 0); } while (0)
; #define PG8_LDA(dst, b, h) do { _Pragma("unroll") for (int m = 0; m < 4; ++m) _Pragma("unroll") for (int k = 0; k < 2; ++k) dst[m][k] = *(const LAS bf16x8*)(lds + PG8_SA(b, h) + aoff + m * 2048 + k * 1024); } while (0)
; #define PG8_LDB(dst, b, h) do { _Pragma("unroll") for (int n = 0; n < 2; ++n) _Pragma("unroll") for (int k = 0; k < 2; ++k) dst[n][k] = *(const LAS bf16x8*)(lds + PG8_SB(b, h) + boff + n * 2048 + k * 1024); } while (0)
; #define PG8_SCHED __builtin_amdgcn_sched_barrier(0)
; template <class Epi>
; DI void gemm_phase(LAS unsigned char* lds, int wid, int K, int lda, int ldb, bool bperm, const Sched3& S, const Epi& E) {
;     ...
;             const bool last = (t == nt - 2);
;             const char* a1 = cA + (size_t)(t + 1) * kstep;
;             const char* a2 = last ? nA : cA + (size_t)(t + 2) * kstep; const char* b2 = last ? nB : cB + (size_t)(t + 2) * kstep;
;             const char* a3 = a2 + kstep; const char* b3 = b2 + kstep; const size_t h2 = last ? nhA : hA;
;             PG8_LDB(B0, 0, 0); PG8_SCHED; PG8_LDA(At, 0, 0); PG8_STAGE(PG8_SA(1, 1), a1 + hA, voffA);
.LBB0_996:
	ds_read_b128 v[156:159], v182
	ds_read_b128 v[160:163], v182 offset:1024
	ds_read_b128 v[164:167], v182 offset:2048
	ds_read_b128 v[168:171], v182 offset:3072
	s_add_u32 s54, s52, 0xfffe0080
	s_addc_u32 s55, s53, -1
	s_cmp_eq_u32 s61, 4
	s_cselect_b32 s57, s41, s55
	s_cselect_b32 s56, s43, s54
	s_cselect_b32 s55, s51, s60
	s_cselect_b32 s54, s58, s59

; #define PG8_STAGE(bufoff, gbase, voff) do { _Pragma("unroll") for (int _i = 0; _i < 2; ++_i) \
;         __builtin_amdgcn_global_load_lds((const unsigned*)((const char*)(gbase) + (voff)[_i]), (LAS unsigned*)(lds + (bufoff) + ldsw + _i * 8192), 16, 0, 0); } while (0)
; #define PG8_LDA(dst, b, h) do { _Pragma("unroll") for (int m = 0; m < 4; ++m) _Pragma("unroll") for (int k = 0; k < 2; ++k) dst[m][k] = *(const LAS bf16x8*)(lds + PG8_SA(b, h) + aoff + m * 2048 + k * 1024); } while (0)
; #define PG8_LDB(dst, b, h) do { _Pragma("unroll") for (int n = 0; n < 2; ++n) _Pragma("unroll") for (int k = 0; k < 2; ++k) dst[n][k] = *(const LAS bf16x8*)(lds + PG8_SB(b, h) + boff + n * 2048 + k * 1024); } while (0)
; #define PG8_SCHED __builtin_amdgcn_sched_barrier(0)
; template <class Epi>
; DI void gemm_phase(LAS unsigned char* lds, int wid, int K, int lda, int ldb, bool bperm, const Sched3& S, const Epi& E) {
;     ...
;             PG8_LDB(B0, 0, 0); PG8_SCHED; PG8_LDA(At, 0, 0); PG8_STAGE(PG8_SA(1, 1), a1 + hA, voffA);
	s_add_i32 m0, s66, 0xc000
	ds_read_b128 v[172:175], v183
	ds_read_b128 v[186:189], v183 offset:1024
	ds_read_b128 v[190:193], v183 offset:2048
	ds_read_b128 v[194:197], v183 offset:3072
	ds_read_b128 v[198:201], v183 offset:4096
	ds_read_b128 v[202:205], v183 offset:5120
	ds_read_b128 v[206:209], v183 offset:6144
	ds_read_b128 v[210:213], v183 offset:7168
	global_load_lds_dwordx4 v144, s[52:53]

; #define PG8_STAGE(bufoff, gbase, voff) do { _Pragma("unroll") for (int _i = 0; _i < 2; ++_i) \
;         __builtin_amdgcn_global_load_lds((const unsigned*)((const char*)(gbase) + (voff)[_i]), (LAS unsigned*)(lds + (bufoff) + ldsw + _i * 8192), 16, 0, 0); } while (0)
; #define PG8_LDA(dst, b, h) do { _Pragma("unroll") for (int m = 0; m < 4; ++m) _Pragma("unroll") for (int k = 0; k < 2; ++k) dst[m][k] = *(const LAS bf16x8*)(lds + PG8_SA(b, h) + aoff + m * 2048 + k * 1024); } while (0)
; #define PG8_LDB(dst, b, h) do { _Pragma("unroll") for (int n = 0; n < 2; ++n) _Pragma("unroll") for (int k = 0; k < 2; ++k) dst[n][k] = *(const LAS bf16x8*)(lds + PG8_SB(b, h) + boff + n * 2048 + k * 1024); } while (0)
; #define PG8_MMA(ai, bj, At, Bt) do { __builtin_amdgcn_s_setprio(1); _Pragma("unroll") for (int m = 0; m < 4; ++m) _Pragma("unroll") for (int n = 0; n < 2; ++n) _Pragma("unroll") for (int k = 0; k < 2; ++k) \
;         acc[ai][bj][m][n] = __builtin_amdgcn_mfma_f32_16x16x32_bf16(Bt[n][k], At[m][k], acc[ai][bj][m][n], 0, 0, 0); __builtin_amdgcn_s_setprio(0); } while (0)
; #define PG8_WAIT_L(n) asm volatile("s_waitcnt lgkmcnt(" #n ")" ::: "memory")
; #define PG8_BAR __builtin_amdgcn_s_barrier()
; #define PG8_SCHED __builtin_amdgcn_sched_barrier(0)
; template <class Epi>
; DI void gemm_phase(LAS unsigned char* lds, int wid, int K, int lda, int ldb, bool bperm, const Sched3& S, const Epi& E) {
;     ...
;             PG8_LDB(B0, 0, 0); PG8_SCHED; PG8_LDA(At, 0, 0); PG8_STAGE(PG8_SA(1, 1), a1 + hA, voffA);
;             PG8_WAIT_L(8); PG8_BAR; PG8_WAIT_L(0); PG8_MMA(0, 0, At, B0); PG8_BAR; PG8_SCHED;
	s_add_i32 m0, s66, 0xe000
	s_nop 0
	global_load_lds_dwordx4 v146, s[52:53]
	s_waitcnt lgkmcnt(8)
	s_barrier
	s_waitcnt lgkmcnt(0)
	s_setprio 1
	s_waitcnt lgkmcnt(0)
	v_mfma_f32_16x16x32_bf16 v[124:127], v[156:159], v[172:175], v[124:127]
	v_mfma_f32_16x16x32_bf16 v[120:123], v[164:167], v[172:175], v[120:123]
	v_mfma_f32_16x16x32_bf16 v[116:119], v[156:159], v[190:193], v[116:119]
	v_mfma_f32_16x16x32_bf16 v[112:115], v[164:167], v[190:193], v[112:115]
	v_mfma_f32_16x16x32_bf16 v[108:111], v[156:159], v[198:201], v[108:111]
	v_mfma_f32_16x16x32_bf16 v[104:107], v[164:167], v[198:201], v[104:107]
	v_mfma_f32_16x16x32_bf16 v[100:103], v[156:159], v[206:209], v[100:103]
	v_mfma_f32_16x16x32_bf16 v[96:99], v[164:167], v[206:209], v[96:99]
	v_mfma_f32_16x16x32_bf16 v[124:127], v[160:163], v[186:189], v[124:127]
	v_mfma_f32_16x16x32_bf16 v[120:123], v[168:171], v[186:189], v[120:123]
	v_mfma_f32_16x16x32_bf16 v[116:119], v[160:163], v[194:197], v[116:119]
	v_mfma_f32_16x16x32_bf16 v[112:115], v[168:171], v[194:197], v[112:115]
	v_mfma_f32_16x16x32_bf16 v[108:111], v[160:163], v[202:205], v[108:111]
	v_mfma_f32_16x16x32_bf16 v[104:107], v[168:171], v[202:205], v[104:107]
	v_mfma_f32_16x16x32_bf16 v[100:103], v[160:163], v[210:213], v[100:103]
	v_mfma_f32_16x16x32_bf16 v[96:99], v[168:171], v[210:213], v[96:99]
	s_setprio 0
	s_barrier
	s_add_i32 s62, s76, s65

; #define PG8_STAGE(bufoff, gbase, voff) do { _Pragma("unroll") for (int _i = 0; _i < 2; ++_i) \
;         __builtin_amdgcn_global_load_lds((const unsigned*)((const char*)(gbase) + (voff)[_i]), (LAS unsigned*)(lds + (bufoff) + ldsw + _i * 8192), 16, 0, 0); } while (0)
; #define PG8_LDB(dst, b, h) do { _Pragma("unroll") for (int n = 0; n < 2; ++n) _Pragma("unroll") for (int k = 0; k < 2; ++k) dst[n][k] = *(const LAS bf16x8*)(lds + PG8_SB(b, h) + boff + n * 2048 + k * 1024); } while (0)
; template <class Epi>
; DI void gemm_phase(LAS unsigned char* lds, int wid, int K, int lda, int ldb, bool bperm, const Sched3& S, const Epi& E) {
;     ...
;             PG8_LDB(B1, 0, 1); PG8_STAGE(PG8_SB(0, 0), b2, voffB);
	s_mov_b32 m0, s62
	ds_read_b128 v[214:217], v184
	ds_read_b128 v[218:221], v184 offset:1024
	ds_read_b128 v[224:227], v184 offset:2048
	ds_read_b128 v[228:231], v184 offset:3072
	global_load_lds_dwordx4 v130, s[54:55]

; #define PG8_STAGE(bufoff, gbase, voff) do { _Pragma("unroll") for (int _i = 0; _i < 2; ++_i) \
;         __builtin_amdgcn_global_load_lds((const unsigned*)((const char*)(gbase) + (voff)[_i]), (LAS unsigned*)(lds + (bufoff) + ldsw + _i * 8192), 16, 0, 0); } while (0)
; #define PG8_LDA(dst, b, h) do { _Pragma("unroll") for (int m = 0; m < 4; ++m) _Pragma("unroll") for (int k = 0; k < 2; ++k) dst[m][k] = *(const LAS bf16x8*)(lds + PG8_SA(b, h) + aoff + m * 2048 + k * 1024); } while (0)
; #define PG8_LDB(dst, b, h) do { _Pragma("unroll") for (int n = 0; n < 2; ++n) _Pragma("unroll") for (int k = 0; k < 2; ++k) dst[n][k] = *(const LAS bf16x8*)(lds + PG8_SB(b, h) + boff + n * 2048 + k * 1024); } while (0)
; #define PG8_MMA(ai, bj, At, Bt) do { __builtin_amdgcn_s_setprio(1); _Pragma("unroll") for (int m = 0; m < 4; ++m) _Pragma("unroll") for (int n = 0; n < 2; ++n) _Pragma("unroll") for (int k = 0; k < 2; ++k) \
;         acc[ai][bj][m][n] = __builtin_amdgcn_mfma_f32_16x16x32_bf16(Bt[n][k], At[m][k], acc[ai][bj][m][n], 0, 0, 0); __builtin_amdgcn_s_setprio(0); } while (0)
; #define PG8_WAIT_L(n) asm volatile("s_waitcnt lgkmcnt(" #n ")" ::: "memory")
; #define PG8_BAR __builtin_amdgcn_s_barrier()
; #define PG8_SCHED __builtin_amdgcn_sched_barrier(0)
; template <class Epi>
; DI void gemm_phase(LAS unsigned char* lds, int wid, int K, int lda, int ldb, bool bperm, const Sched3& S, const Epi& E) {
;     ...
;             PG8_LDB(B1, 0, 1); PG8_STAGE(PG8_SB(0, 0), b2, voffB);
;             PG8_BAR; PG8_WAIT_L(0); PG8_MMA(0, 1, At, B1); PG8_BAR;
;             PG8_LDA(At, 0, 1); PG8_STAGE(PG8_SA(0, 0), a2, voffA);
;             PG8_BAR; PG8_WAIT_L(0); if (full) PG8_MMA(1, 0, At, B0); PG8_BAR; PG8_SCHED;
	s_add_i32 m0, s62, 0x2000
	s_nop 0
	global_load_lds_dwordx4 v134, s[54:55]
	s_barrier
	s_waitcnt lgkmcnt(0)
	s_setprio 1
	s_waitcnt lgkmcnt(0)
	v_mfma_f32_16x16x32_bf16 v[60:63], v[214:217], v[172:175], v[60:63]
	v_mfma_f32_16x16x32_bf16 v[56:59], v[224:227], v[172:175], v[56:59]
	v_mfma_f32_16x16x32_bf16 v[52:55], v[214:217], v[190:193], v[52:55]
	v_mfma_f32_16x16x32_bf16 v[48:51], v[224:227], v[190:193], v[48:51]
	v_mfma_f32_16x16x32_bf16 v[44:47], v[214:217], v[198:201], v[44:47]
	v_mfma_f32_16x16x32_bf16 v[40:43], v[224:227], v[198:201], v[40:43]
	v_mfma_f32_16x16x32_bf16 v[36:39], v[214:217], v[206:209], v[36:39]
	v_mfma_f32_16x16x32_bf16 v[32:35], v[224:227], v[206:209], v[32:35]
	v_mfma_f32_16x16x32_bf16 v[60:63], v[218:221], v[186:189], v[60:63]
	v_mfma_f32_16x16x32_bf16 v[56:59], v[228:231], v[186:189], v[56:59]
	v_mfma_f32_16x16x32_bf16 v[52:55], v[218:221], v[194:197], v[52:55]
	v_mfma_f32_16x16x32_bf16 v[48:51], v[228:231], v[194:197], v[48:51]
	v_mfma_f32_16x16x32_bf16 v[44:47], v[218:221], v[202:205], v[44:47]
	v_mfma_f32_16x16x32_bf16 v[40:43], v[228:231], v[202:205], v[40:43]
	v_mfma_f32_16x16x32_bf16 v[36:39], v[218:221], v[210:213], v[36:39]
	v_mfma_f32_16x16x32_bf16 v[32:35], v[228:231], v[210:213], v[32:35]
	s_setprio 0
	s_mov_b32 m0, s66
	s_mov_b64 s[100:101], s[56:57]
	s_barrier
	ds_read_b128 v[172:175], v183 offset:16384
	ds_read_b128 v[186:189], v183 offset:17408
	ds_read_b128 v[190:193], v183 offset:18432
	ds_read_b128 v[194:197], v183 offset:19456
	ds_read_b128 v[198:201], v183 offset:20480
	ds_read_b128 v[202:205], v183 offset:21504
	ds_read_b128 v[206:209], v183 offset:22528
	ds_read_b128 v[210:213], v183 offset:23552
	global_load_lds_dwordx4 v128, s[56:57]
	s_mov_b64 s[100:101], s[56:57]
	s_mov_b32 m0, s67
	s_nop 0
	global_load_lds_dwordx4 v132, s[56:57]
	s_barrier
	s_waitcnt lgkmcnt(0)
	s_setprio 1
	s_waitcnt lgkmcnt(0)
	v_mfma_f32_16x16x32_bf16 v[92:95], v[156:159], v[172:175], v[92:95]
	v_mfma_f32_16x16x32_bf16 v[88:91], v[164:167], v[172:175], v[88:91]
	v_mfma_f32_16x16x32_bf16 v[84:87], v[156:159], v[190:193], v[84:87]
	v_mfma_f32_16x16x32_bf16 v[80:83], v[164:167], v[190:193], v[80:83]
	v_mfma_f32_16x16x32_bf16 v[76:79], v[156:159], v[198:201], v[76:79]
	v_mfma_f32_16x16x32_bf16 v[72:75], v[164:167], v[198:201], v[72:75]
	v_mfma_f32_16x16x32_bf16 v[68:71], v[156:159], v[206:209], v[68:71]
	v_mfma_f32_16x16x32_bf16 v[64:67], v[164:167], v[206:209], v[64:67]
	v_mfma_f32_16x16x32_bf16 v[92:95], v[160:163], v[186:189], v[92:95]
	v_mfma_f32_16x16x32_bf16 v[88:91], v[168:171], v[186:189], v[88:91]
	v_mfma_f32_16x16x32_bf16 v[84:87], v[160:163], v[194:197], v[84:87]
	v_mfma_f32_16x16x32_bf16 v[80:83], v[168:171], v[194:197], v[80:83]
	v_mfma_f32_16x16x32_bf16 v[76:79], v[160:163], v[202:205], v[76:79]
	v_mfma_f32_16x16x32_bf16 v[72:75], v[168:171], v[202:205], v[72:75]
	v_mfma_f32_16x16x32_bf16 v[68:71], v[160:163], v[210:213], v[68:71]
	v_mfma_f32_16x16x32_bf16 v[64:67], v[168:171], v[210:213], v[64:67]
	s_setprio 0
	s_barrier
	s_add_u32 s62, s54, 0x20000
	s_addc_u32 s63, s55, 0
	s_add_i32 s86, s77, s65

; #define PG8_STAGE(bufoff, gbase, voff) do { _Pragma("unroll") for (int _i = 0; _i < 2; ++_i) \
;         __builtin_amdgcn_global_load_lds((const unsigned*)((const char*)(gbase) + (voff)[_i]), (LAS unsigned*)(lds + (bufoff) + ldsw + _i * 8192), 16, 0, 0); } while (0)
; template <class Epi>
; DI void gemm_phase(LAS unsigned char* lds, int wid, int K, int lda, int ldb, bool bperm, const Sched3& S, const Epi& E) {
;     ...
;             PG8_STAGE(PG8_SB(0, 1), b2 + hstepB, voffB);
	s_mov_b32 m0, s86
	s_nop 0
	global_load_lds_dwordx4 v130, s[62:63]

; #define PG8_STAGE(bufoff, gbase, voff) do { _Pragma("unroll") for (int _i = 0; _i < 2; ++_i) \
;         __builtin_amdgcn_global_load_lds((const unsigned*)((const char*)(gbase) + (voff)[_i]), (LAS unsigned*)(lds + (bufoff) + ldsw + _i * 8192), 16, 0, 0); } while (0)
; #define PG8_LDA(dst, b, h) do { _Pragma("unroll") for (int m = 0; m < 4; ++m) _Pragma("unroll") for (int k = 0; k < 2; ++k) dst[m][k] = *(const LAS bf16x8*)(lds + PG8_SA(b, h) + aoff + m * 2048 + k * 1024); } while (0)
; #define PG8_LDB(dst, b, h) do { _Pragma("unroll") for (int n = 0; n < 2; ++n) _Pragma("unroll") for (int k = 0; k < 2; ++k) dst[n][k] = *(const LAS bf16x8*)(lds + PG8_SB(b, h) + boff + n * 2048 + k * 1024); } while (0)
; #define PG8_MMA(ai, bj, At, Bt) do { __builtin_amdgcn_s_setprio(1); _Pragma("unroll") for (int m = 0; m < 4; ++m) _Pragma("unroll") for (int n = 0; n < 2; ++n) _Pragma("unroll") for (int k = 0; k < 2; ++k) \
;         acc[ai][bj][m][n] = __builtin_amdgcn_mfma_f32_16x16x32_bf16(Bt[n][k], At[m][k], acc[ai][bj][m][n], 0, 0, 0); __builtin_amdgcn_s_setprio(0); } while (0)
; #define PG8_WAIT_V(n) asm volatile("s_waitcnt vmcnt(" #n ")" ::: "memory")
; #define PG8_BAR __builtin_amdgcn_s_barrier()
; #define PG8_SCHED __builtin_amdgcn_sched_barrier(0)
; template <class Epi>
; DI void gemm_phase(LAS unsigned char* lds, int wid, int K, int lda, int ldb, bool bperm, const Sched3& S, const Epi& E) {
;     ...
;             PG8_STAGE(PG8_SB(0, 1), b2 + hstepB, voffB);
;             PG8_WAIT_V(6); PG8_BAR; if (full) PG8_MMA(1, 1, At, B1); PG8_BAR;
;             PG8_LDB(B0, 1, 0); PG8_SCHED; PG8_LDA(At, 1, 0); PG8_STAGE(PG8_SA(0, 1), a2 + h2, voffA);
	s_add_i32 m0, s86, 0x2000
	s_nop 0
	global_load_lds_dwordx4 v134, s[62:63]
	s_waitcnt vmcnt(6)
	s_barrier
	s_setprio 1
	v_mfma_f32_16x16x32_bf16 v[28:31], v[214:217], v[172:175], v[28:31]
	v_mfma_f32_16x16x32_bf16 v[24:27], v[224:227], v[172:175], v[24:27]
	v_mfma_f32_16x16x32_bf16 v[20:23], v[214:217], v[190:193], v[20:23]
	v_mfma_f32_16x16x32_bf16 v[16:19], v[224:227], v[190:193], v[16:19]
	v_mfma_f32_16x16x32_bf16 v[12:15], v[214:217], v[198:201], v[12:15]
	v_mfma_f32_16x16x32_bf16 v[8:11], v[224:227], v[198:201], v[8:11]
	v_mfma_f32_16x16x32_bf16 v[4:7], v[214:217], v[206:209], v[4:7]
	v_mfma_f32_16x16x32_bf16 v[0:3], v[224:227], v[206:209], v[0:3]
	v_mfma_f32_16x16x32_bf16 v[28:31], v[218:221], v[186:189], v[28:31]
	v_mfma_f32_16x16x32_bf16 v[24:27], v[228:231], v[186:189], v[24:27]
	v_mfma_f32_16x16x32_bf16 v[20:23], v[218:221], v[194:197], v[20:23]
	v_mfma_f32_16x16x32_bf16 v[16:19], v[228:231], v[194:197], v[16:19]
	v_mfma_f32_16x16x32_bf16 v[12:15], v[218:221], v[202:205], v[12:15]
	v_mfma_f32_16x16x32_bf16 v[8:11], v[228:231], v[202:205], v[8:11]
	v_mfma_f32_16x16x32_bf16 v[4:7], v[218:221], v[210:213], v[4:7]
	v_mfma_f32_16x16x32_bf16 v[0:3], v[228:231], v[210:213], v[0:3]
	s_setprio 0
	s_add_i32 s62, 0, 0x18000
	v_add_u32_e32 v136, s62, v179
	s_barrier
	ds_read_b128 v[156:159], v136
	ds_read_b128 v[160:163], v136 offset:1024
	ds_read_b128 v[164:167], v136 offset:2048
	ds_read_b128 v[168:171], v136 offset:3072
	s_add_u32 s56, s56, 0x20000
	s_addc_u32 s57, s57, 0
	s_mov_b32 m0, s68

; #define PG8_STAGE(bufoff, gbase, voff) do { _Pragma("unroll") for (int _i = 0; _i < 2; ++_i) \
;         __builtin_amdgcn_global_load_lds((const unsigned*)((const char*)(gbase) + (voff)[_i]), (LAS unsigned*)(lds + (bufoff) + ldsw + _i * 8192), 16, 0, 0); } while (0)
; #define PG8_LDA(dst, b, h) do { _Pragma("unroll") for (int m = 0; m < 4; ++m) _Pragma("unroll") for (int k = 0; k < 2; ++k) dst[m][k] = *(const LAS bf16x8*)(lds + PG8_SA(b, h) + aoff + m * 2048 + k * 1024); } while (0)
; #define PG8_LDB(dst, b, h) do { _Pragma("unroll") for (int n = 0; n < 2; ++n) _Pragma("unroll") for (int k = 0; k < 2; ++k) dst[n][k] = *(const LAS bf16x8*)(lds + PG8_SB(b, h) + boff + n * 2048 + k * 1024); } while (0)
; #define PG8_SCHED __builtin_amdgcn_sched_barrier(0)
; template <class Epi>
; DI void gemm_phase(LAS unsigned char* lds, int wid, int K, int lda, int ldb, bool bperm, const Sched3& S, const Epi& E) {
;     ...
;             PG8_LDB(B0, 1, 0); PG8_SCHED; PG8_LDA(At, 1, 0); PG8_STAGE(PG8_SA(0, 1), a2 + h2, voffA);
	ds_read_b128 v[172:175], v183 offset:32768
	ds_read_b128 v[186:189], v183 offset:33792
	ds_read_b128 v[190:193], v183 offset:34816
	ds_read_b128 v[194:197], v183 offset:35840
	ds_read_b128 v[198:201], v183 offset:36864
	ds_read_b128 v[202:205], v183 offset:37888
	ds_read_b128 v[206:209], v183 offset:38912
	ds_read_b128 v[210:213], v183 offset:39936
	global_load_lds_dwordx4 v128, s[56:57]

; #define PG8_STAGE(bufoff, gbase, voff) do { _Pragma("unroll") for (int _i = 0; _i < 2; ++_i) \
;         __builtin_amdgcn_global_load_lds((const unsigned*)((const char*)(gbase) + (voff)[_i]), (LAS unsigned*)(lds + (bufoff) + ldsw + _i * 8192), 16, 0, 0); } while (0)
; #define PG8_LDA(dst, b, h) do { _Pragma("unroll") for (int m = 0; m < 4; ++m) _Pragma("unroll") for (int k = 0; k < 2; ++k) dst[m][k] = *(const LAS bf16x8*)(lds + PG8_SA(b, h) + aoff + m * 2048 + k * 1024); } while (0)
; #define PG8_LDB(dst, b, h) do { _Pragma("unroll") for (int n = 0; n < 2; ++n) _Pragma("unroll") for (int k = 0; k < 2; ++k) dst[n][k] = *(const LAS bf16x8*)(lds + PG8_SB(b, h) + boff + n * 2048 + k * 1024); } while (0)
; #define PG8_MMA(ai, bj, At, Bt) do { __builtin_amdgcn_s_setprio(1); _Pragma("unroll") for (int m = 0; m < 4; ++m) _Pragma("unroll") for (int n = 0; n < 2; ++n) _Pragma("unroll") for (int k = 0; k < 2; ++k) \
;         acc[ai][bj][m][n] = __builtin_amdgcn_mfma_f32_16x16x32_bf16(Bt[n][k], At[m][k], acc[ai][bj][m][n], 0, 0, 0); __builtin_amdgcn_s_setprio(0); } while (0)
; #define PG8_WAIT_L(n) asm volatile("s_waitcnt lgkmcnt(" #n ")" ::: "memory")
; #define PG8_BAR __builtin_amdgcn_s_barrier()
; #define PG8_SCHED __builtin_amdgcn_sched_barrier(0)
; template <class Epi>
; DI void gemm_phase(LAS unsigned char* lds, int wid, int K, int lda, int ldb, bool bperm, const Sched3& S, const Epi& E) {
;     ...
;             PG8_LDB(B0, 1, 0); PG8_SCHED; PG8_LDA(At, 1, 0); PG8_STAGE(PG8_SA(0, 1), a2 + h2, voffA);
;             PG8_WAIT_L(8); PG8_BAR; PG8_WAIT_L(0); PG8_MMA(0, 0, At, B0); PG8_BAR; PG8_SCHED;
	s_mov_b32 m0, s69
	s_nop 0
	global_load_lds_dwordx4 v132, s[56:57]
	s_waitcnt lgkmcnt(8)
	s_barrier
	s_waitcnt lgkmcnt(0)
	s_setprio 1
	s_waitcnt lgkmcnt(0)
	v_mfma_f32_16x16x32_bf16 v[124:127], v[156:159], v[172:175], v[124:127]
	v_mfma_f32_16x16x32_bf16 v[120:123], v[164:167], v[172:175], v[120:123]
	v_mfma_f32_16x16x32_bf16 v[116:119], v[156:159], v[190:193], v[116:119]
	v_mfma_f32_16x16x32_bf16 v[112:115], v[164:167], v[190:193], v[112:115]
	v_mfma_f32_16x16x32_bf16 v[108:111], v[156:159], v[198:201], v[108:111]
	v_mfma_f32_16x16x32_bf16 v[104:107], v[164:167], v[198:201], v[104:107]
	v_mfma_f32_16x16x32_bf16 v[100:103], v[156:159], v[206:209], v[100:103]
	v_mfma_f32_16x16x32_bf16 v[96:99], v[164:167], v[206:209], v[96:99]
	v_mfma_f32_16x16x32_bf16 v[124:127], v[160:163], v[186:189], v[124:127]
	v_mfma_f32_16x16x32_bf16 v[120:123], v[168:171], v[186:189], v[120:123]
	v_mfma_f32_16x16x32_bf16 v[116:119], v[160:163], v[194:197], v[116:119]
	v_mfma_f32_16x16x32_bf16 v[112:115], v[168:171], v[194:197], v[112:115]
	v_mfma_f32_16x16x32_bf16 v[108:111], v[160:163], v[202:205], v[108:111]
	v_mfma_f32_16x16x32_bf16 v[104:107], v[168:171], v[202:205], v[104:107]
	v_mfma_f32_16x16x32_bf16 v[100:103], v[160:163], v[210:213], v[100:103]
	v_mfma_f32_16x16x32_bf16 v[96:99], v[168:171], v[210:213], v[96:99]
	s_setprio 0
	s_barrier
	s_add_i32 s56, 0, 0x1c000
	s_add_i32 s57, s62, s65
	v_add_u32_e32 v136, s56, v179

; #define PG8_STAGE(bufoff, gbase, voff) do { _Pragma("unroll") for (int _i = 0; _i < 2; ++_i) \
;         __builtin_amdgcn_global_load_lds((const unsigned*)((const char*)(gbase) + (voff)[_i]), (LAS unsigned*)(lds + (bufoff) + ldsw + _i * 8192), 16, 0, 0); } while (0)
; #define PG8_LDB(dst, b, h) do { _Pragma("unroll") for (int n = 0; n < 2; ++n) _Pragma("unroll") for (int k = 0; k < 2; ++k) dst[n][k] = *(const LAS bf16x8*)(lds + PG8_SB(b, h) + boff + n * 2048 + k * 1024); } while (0)
; template <class Epi>
; DI void gemm_phase(LAS unsigned char* lds, int wid, int K, int lda, int ldb, bool bperm, const Sched3& S, const Epi& E) {
;     ...
;             PG8_LDB(B1, 1, 1); PG8_STAGE(PG8_SB(1, 0), b3, voffB);
	s_sub_i32 m0, s57, 0x80
	ds_read_b128 v[214:217], v136
	ds_read_b128 v[218:221], v136 offset:1024
	ds_read_b128 v[224:227], v136 offset:2048
	ds_read_b128 v[228:231], v136 offset:3072
	global_load_lds_dwordx4 v130, s[54:55] offset:128

; #define PG8_STAGE(bufoff, gbase, voff) do { _Pragma("unroll") for (int _i = 0; _i < 2; ++_i) \
;         __builtin_amdgcn_global_load_lds((const unsigned*)((const char*)(gbase) + (voff)[_i]), (LAS unsigned*)(lds + (bufoff) + ldsw + _i * 8192), 16, 0, 0); } while (0)
; #define PG8_LDB(dst, b, h) do { _Pragma("unroll") for (int n = 0; n < 2; ++n) _Pragma("unroll") for (int k = 0; k < 2; ++k) dst[n][k] = *(const LAS bf16x8*)(lds + PG8_SB(b, h) + boff + n * 2048 + k * 1024); } while (0)
; #define PG8_MMA(ai, bj, At, Bt) do { __builtin_amdgcn_s_setprio(1); _Pragma("unroll") for (int m = 0; m < 4; ++m) _Pragma("unroll") for (int n = 0; n < 2; ++n) _Pragma("unroll") for (int k = 0; k < 2; ++k) \
;         acc[ai][bj][m][n] = __builtin_amdgcn_mfma_f32_16x16x32_bf16(Bt[n][k], At[m][k], acc[ai][bj][m][n], 0, 0, 0); __builtin_amdgcn_s_setprio(0); } while (0)
; #define PG8_WAIT_L(n) asm volatile("s_waitcnt lgkmcnt(" #n ")" ::: "memory")
; #define PG8_BAR __builtin_amdgcn_s_barrier()
; template <class Epi>
; DI void gemm_phase(LAS unsigned char* lds, int wid, int K, int lda, int ldb, bool bperm, const Sched3& S, const Epi& E) {
;     ...
;             PG8_LDB(B1, 1, 1); PG8_STAGE(PG8_SB(1, 0), b3, voffB);
;             PG8_BAR; PG8_WAIT_L(0); PG8_MMA(0, 1, At, B1); PG8_BAR;
	s_add_i32 m0, s57, 0x1f80
	s_nop 0
	global_load_lds_dwordx4 v134, s[54:55] offset:128
	s_barrier
	s_waitcnt lgkmcnt(0)
	s_setprio 1
	s_waitcnt lgkmcnt(0)
	v_mfma_f32_16x16x32_bf16 v[60:63], v[214:217], v[172:175], v[60:63]
	v_mfma_f32_16x16x32_bf16 v[56:59], v[224:227], v[172:175], v[56:59]
	v_mfma_f32_16x16x32_bf16 v[52:55], v[214:217], v[190:193], v[52:55]
	v_mfma_f32_16x16x32_bf16 v[48:51], v[224:227], v[190:193], v[48:51]
	v_mfma_f32_16x16x32_bf16 v[44:47], v[214:217], v[198:201], v[44:47]
	v_mfma_f32_16x16x32_bf16 v[40:43], v[224:227], v[198:201], v[40:43]
	v_mfma_f32_16x16x32_bf16 v[36:39], v[214:217], v[206:209], v[36:39]
	v_mfma_f32_16x16x32_bf16 v[32:35], v[224:227], v[206:209], v[32:35]
	v_mfma_f32_16x16x32_bf16 v[60:63], v[218:221], v[186:189], v[60:63]
	v_mfma_f32_16x16x32_bf16 v[56:59], v[228:231], v[186:189], v[56:59]
	v_mfma_f32_16x16x32_bf16 v[52:55], v[218:221], v[194:197], v[52:55]
	v_mfma_f32_16x16x32_bf16 v[48:51], v[228:231], v[194:197], v[48:51]
	v_mfma_f32_16x16x32_bf16 v[44:47], v[218:221], v[202:205], v[44:47]
	v_mfma_f32_16x16x32_bf16 v[40:43], v[228:231], v[202:205], v[40:43]
	v_mfma_f32_16x16x32_bf16 v[36:39], v[218:221], v[210:213], v[36:39]
	v_mfma_f32_16x16x32_bf16 v[32:35], v[228:231], v[210:213], v[32:35]
	s_setprio 0
	s_sub_i32 m0, s72, 0x80

; #define PG8_STAGE(bufoff, gbase, voff) do { _Pragma("unroll") for (int _i = 0; _i < 2; ++_i) \
;         __builtin_amdgcn_global_load_lds((const unsigned*)((const char*)(gbase) + (voff)[_i]), (LAS unsigned*)(lds + (bufoff) + ldsw + _i * 8192), 16, 0, 0); } while (0)
; #define PG8_LDA(dst, b, h) do { _Pragma("unroll") for (int m = 0; m < 4; ++m) _Pragma("unroll") for (int k = 0; k < 2; ++k) dst[m][k] = *(const LAS bf16x8*)(lds + PG8_SA(b, h) + aoff + m * 2048 + k * 1024); } while (0)
; #define PG8_MMA(ai, bj, At, Bt) do { __builtin_amdgcn_s_setprio(1); _Pragma("unroll") for (int m = 0; m < 4; ++m) _Pragma("unroll") for (int n = 0; n < 2; ++n) _Pragma("unroll") for (int k = 0; k < 2; ++k) \
;         acc[ai][bj][m][n] = __builtin_amdgcn_mfma_f32_16x16x32_bf16(Bt[n][k], At[m][k], acc[ai][bj][m][n], 0, 0, 0); __builtin_amdgcn_s_setprio(0); } while (0)
; #define PG8_WAIT_L(n) asm volatile("s_waitcnt lgkmcnt(" #n ")" ::: "memory")
; #define PG8_BAR __builtin_amdgcn_s_barrier()
; template <class Epi>
; DI void gemm_phase(LAS unsigned char* lds, int wid, int K, int lda, int ldb, bool bperm, const Sched3& S, const Epi& E) {
;     ...
;             PG8_BAR; PG8_WAIT_L(0); PG8_MMA(0, 1, At, B1); PG8_BAR;
;             PG8_LDA(At, 1, 1); PG8_STAGE(PG8_SA(1, 0), a3, voffA);
	s_barrier
	ds_read_b128 v[172:175], v183 offset:49152
	ds_read_b128 v[186:189], v183 offset:50176
	ds_read_b128 v[190:193], v183 offset:51200
	ds_read_b128 v[194:197], v183 offset:52224
	ds_read_b128 v[198:201], v183 offset:53248
	ds_read_b128 v[202:205], v183 offset:54272
	ds_read_b128 v[206:209], v183 offset:55296
	ds_read_b128 v[210:213], v183 offset:56320
	global_load_lds_dwordx4 v128, s[100:101] offset:128

; #define PG8_MMA(ai, bj, At, Bt) do { __builtin_amdgcn_s_setprio(1); _Pragma("unroll") for (int m = 0; m < 4; ++m) _Pragma("unroll") for (int n = 0; n < 2; ++n) _Pragma("unroll") for (int k = 0; k < 2; ++k) \
;         acc[ai][bj][m][n] = __builtin_amdgcn_mfma_f32_16x16x32_bf16(Bt[n][k], At[m][k], acc[ai][bj][m][n], 0, 0, 0); __builtin_amdgcn_s_setprio(0); } while (0)
; #define PG8_WAIT_L(n) asm volatile("s_waitcnt lgkmcnt(" #n ")" ::: "memory")
; #define PG8_BAR __builtin_amdgcn_s_barrier()
; #define PG8_SCHED __builtin_amdgcn_sched_barrier(0)
; template <class Epi>
; DI void gemm_phase(LAS unsigned char* lds, int wid, int K, int lda, int ldb, bool bperm, const Sched3& S, const Epi& E) {
;     ...
;             PG8_BAR; PG8_WAIT_L(0); if (full) PG8_MMA(1, 0, At, B0); PG8_BAR; PG8_SCHED;
	s_sub_i32 m0, s73, 0x80
	s_nop 0
	global_load_lds_dwordx4 v132, s[100:101] offset:128
	s_barrier
	s_waitcnt lgkmcnt(0)
	s_setprio 1
	s_waitcnt lgkmcnt(0)
	v_mfma_f32_16x16x32_bf16 v[92:95], v[156:159], v[172:175], v[92:95]
	v_mfma_f32_16x16x32_bf16 v[88:91], v[164:167], v[172:175], v[88:91]
	v_mfma_f32_16x16x32_bf16 v[84:87], v[156:159], v[190:193], v[84:87]
	v_mfma_f32_16x16x32_bf16 v[80:83], v[164:167], v[190:193], v[80:83]
	v_mfma_f32_16x16x32_bf16 v[76:79], v[156:159], v[198:201], v[76:79]
	v_mfma_f32_16x16x32_bf16 v[72:75], v[164:167], v[198:201], v[72:75]
	v_mfma_f32_16x16x32_bf16 v[68:71], v[156:159], v[206:209], v[68:71]
	v_mfma_f32_16x16x32_bf16 v[64:67], v[164:167], v[206:209], v[64:67]
	v_mfma_f32_16x16x32_bf16 v[92:95], v[160:163], v[186:189], v[92:95]
	v_mfma_f32_16x16x32_bf16 v[88:91], v[168:171], v[186:189], v[88:91]
	v_mfma_f32_16x16x32_bf16 v[84:87], v[160:163], v[194:197], v[84:87]
	v_mfma_f32_16x16x32_bf16 v[80:83], v[168:171], v[194:197], v[80:83]
	v_mfma_f32_16x16x32_bf16 v[76:79], v[160:163], v[202:205], v[76:79]
	v_mfma_f32_16x16x32_bf16 v[72:75], v[168:171], v[202:205], v[72:75]
	v_mfma_f32_16x16x32_bf16 v[68:71], v[160:163], v[210:213], v[68:71]
	v_mfma_f32_16x16x32_bf16 v[64:67], v[168:171], v[210:213], v[64:67]
	s_setprio 0
	s_barrier
	s_add_u32 s54, s54, 0x20080
	s_addc_u32 s55, s55, 0
	s_add_i32 s56, s56, s65

; #define PG8_STAGE(bufoff, gbase, voff) do { _Pragma("unroll") for (int _i = 0; _i < 2; ++_i) \
;         __builtin_amdgcn_global_load_lds((const unsigned*)((const char*)(gbase) + (voff)[_i]), (LAS unsigned*)(lds + (bufoff) + ldsw + _i * 8192), 16, 0, 0); } while (0)
; template <class Epi>
; DI void gemm_phase(LAS unsigned char* lds, int wid, int K, int lda, int ldb, bool bperm, const Sched3& S, const Epi& E) {
;     ...
;             PG8_STAGE(PG8_SB(1, 1), b3 + hstepB, voffB);
	s_mov_b32 m0, s56
	s_nop 0
	global_load_lds_dwordx4 v130, s[54:55]

; #define PG8_BAR __builtin_amdgcn_s_barrier()
; template <class Epi>
; DI void gemm_phase(LAS unsigned char* lds, int wid, int K, int lda, int ldb, bool bperm, const Sched3& S, const Epi& E) {
;     ...
;             PG8_STAGE(PG8_SB(1, 1), b3 + hstepB, voffB);
;             PG8_WAIT_V(6); PG8_BAR; if (full) PG8_MMA(1, 1, At, B1); PG8_BAR;
;     DI void operator()(const Acc& acc, const Unit& u, int wr, int wc, int fr, int fq) const {
;     ...
;             if (u.kind == K_Q) {
;                 LOAD_ROW_RS(rsv, SSQ(4), 1.f / 512.f);
;                 const float* cs = WSF(OFF_CS);
; #pragma unroll
;                 for (int bj = 0; bj < 2; ++bj) {
;                     const int g32 = u.pn * 8 + bj * 4 + wc, g64 = g32 >> 1; const bool rope = (g64 % 3) == 2;
;                     if (!rope) {
;                         ROWS8 { const int r = row0 + ai * HALF + m * 16; const float rs = rsv[ai][m] * QSCALE;
;                             bf16_t* dst = WSB(OFF_Q) + (size_t)r * 3072 + g32 * 32 + 8 * fq; *(u32x4*)(dst) = PK8(acc[ai][bj][m][0] * rs, acc[ai][bj][m][1] * rs); }
;                     } else {
;                         const int j0 = 16 * (g32 & 1) + 4 * fq;
; #pragma unroll
;                         for (int ai = 0; ai < 2; ++ai) if (ai == 0 || !hf) {
;                             f32x4 c4[4], s4[4];
; #pragma unroll
;                             for (int m = 0; m < 4; ++m) { const int pos = (row0 + ai * HALF + m * 16) & (SEQ - 1); c4[m] = *(const f32x4*)(cs + pos * 32 + j0); s4[m] = *(const f32x4*)(cs + 4096 * 32 + pos * 32 + j0); }
; #pragma unroll
;                             for (int m = 0; m < 4; ++m) { const int r = row0 + ai * HALF + m * 16; const float rs = rsv[ai][m] * QSCALE;
;                                 const f32x4 v0 = acc[ai][bj][m][0] * rs, v1 = acc[ai][bj][m][1] * rs;
;                                 bf16_t* dst = WSB(OFF_Q) + (size_t)r * 3072 + g64 * 64 + j0;
;                                 *(u32x2*)(dst) = pk4(v0 * c4[m] - v1 * s4[m]); *(u32x2*)(dst + 32) = pk4(v1 * c4[m] + v0 * s4[m]); }
;                         }
;                     }
;                 }
;             } else if (u.kind == K_KN) {
;                 LOAD_ROW_RS(rsv, SSQ(5), 1.f / 512.f);
;                 ROWS8 { const int r = row0 + ai * HALF + m * 16; const float rs = rsv[ai][m];
;                     bf16_t* dst = WSB(OFF_KN) + (size_t)r * 2048 + colp;
; #pragma unroll
	s_add_i32 m0, s56, 0x2000
	s_nop 0
	global_load_lds_dwordx4 v134, s[54:55]
	s_waitcnt vmcnt(6)
	s_barrier
	s_setprio 1
	v_mfma_f32_16x16x32_bf16 v[28:31], v[214:217], v[172:175], v[28:31]
	v_mfma_f32_16x16x32_bf16 v[24:27], v[224:227], v[172:175], v[24:27]
	v_mfma_f32_16x16x32_bf16 v[20:23], v[214:217], v[190:193], v[20:23]
	v_mfma_f32_16x16x32_bf16 v[16:19], v[224:227], v[190:193], v[16:19]
	v_mfma_f32_16x16x32_bf16 v[12:15], v[214:217], v[198:201], v[12:15]
	v_mfma_f32_16x16x32_bf16 v[8:11], v[224:227], v[198:201], v[8:11]
	v_mfma_f32_16x16x32_bf16 v[4:7], v[214:217], v[206:209], v[4:7]
	v_mfma_f32_16x16x32_bf16 v[0:3], v[224:227], v[206:209], v[0:3]
	v_mfma_f32_16x16x32_bf16 v[28:31], v[218:221], v[186:189], v[28:31]
	v_mfma_f32_16x16x32_bf16 v[24:27], v[228:231], v[186:189], v[24:27]
	v_mfma_f32_16x16x32_bf16 v[20:23], v[218:221], v[194:197], v[20:23]
	v_mfma_f32_16x16x32_bf16 v[16:19], v[228:231], v[194:197], v[16:19]
	v_mfma_f32_16x16x32_bf16 v[12:15], v[218:221], v[202:205], v[12:15]
	v_mfma_f32_16x16x32_bf16 v[8:11], v[228:231], v[202:205], v[8:11]
	v_mfma_f32_16x16x32_bf16 v[4:7], v[218:221], v[210:213], v[4:7]
	v_mfma_f32_16x16x32_bf16 v[0:3], v[228:231], v[210:213], v[0:3]
	s_setprio 0
	s_add_i32 s61, s61, 2
	s_add_u32 s52, s52, 0x100
	s_addc_u32 s53, s53, 0
	s_add_u32 s59, s59, 0x100
	s_addc_u32 s60, s60, 0
	s_cmp_gt_u32 s61, 5
	s_cbranch_scc0 .Lkrot_5_head
.Lkrot_5_exit:
	s_barrier
.Lpeel_5_exit:
	v_lshl_add_u32 v156, s50, 8, v177
	v_lshl_add_u32 v164, s84, 8, v181
	s_mov_b64 s[54:55], -1
	s_mov_b64 s[50:51], 0
	s_cmp_lt_i32 s85, 7
	s_mov_b64 s[52:53], 0
	s_cbranch_scc1 .LBB0_1001
	s_cmp_eq_u32 s85, 7
	s_mov_b64 s[52:53], -1
	s_cbranch_scc0 .LBB0_1000
	v_or_b32_e32 v168, 16, v156
	v_ashrrev_i32_e32 v169, 31, v168
	v_or_b32_e32 v170, 32, v156
	v_or_b32_e32 v198, 48, v156
	v_lshl_add_u64 v[158:159], v[168:169], 2, s[18:19]
	v_ashrrev_i32_e32 v171, 31, v170
	v_ashrrev_i32_e32 v199, 31, v198
	v_ashrrev_i32_e32 v157, 31, v156
	v_lshl_add_u64 v[160:161], v[170:171], 2, s[18:19]
	v_lshl_add_u64 v[162:163], v[198:199], 2, s[18:19]
	v_lshl_add_u64 v[166:167], v[156:157], 2, s[18:19]
	global_load_dword v136, v[158:159], off
	global_load_dword v176, v[160:161], off
	global_load_dword v178, v[162:163], off
	global_load_dword v180, v[166:167], off
	v_add_u32_e32 v200, 0x80, v156
	v_add_u32_e32 v166, 0x90, v156
	v_add_u32_e32 v162, 0xa0, v156
	v_add_u32_e32 v158, 0xb0, v156
	v_ashrrev_i32_e32 v201, 31, v200
	v_ashrrev_i32_e32 v167, 31, v166
	v_ashrrev_i32_e32 v163, 31, v162
	v_ashrrev_i32_e32 v159, 31, v158
	v_lshl_add_u64 v[160:161], v[200:201], 2, s[18:19]
	v_lshl_add_u64 v[172:173], v[166:167], 2, s[18:19]
	v_lshl_add_u64 v[174:175], v[162:163], 2, s[18:19]
	v_lshl_add_u64 v[186:187], v[158:159], 2, s[18:19]
	global_load_dword v228, v[160:161], off
	global_load_dword v229, v[172:173], off
	global_load_dword v230, v[174:175], off
	global_load_dword v231, v[186:187], off
	v_ashrrev_i32_e32 v165, 31, v164
	v_lshlrev_b64 v[172:173], 12, v[156:157]
	v_lshlrev_b64 v[168:169], 12, v[168:169]
	v_lshlrev_b64 v[160:161], 1, v[164:165]
	v_lshl_add_u64 v[168:169], s[20:21], 0, v[168:169]
	v_lshl_add_u64 v[202:203], v[168:169], 0, v[160:161]
	v_lshlrev_b64 v[170:171], 12, v[170:171]
	v_lshl_add_u64 v[172:173], s[20:21], 0, v[172:173]
	v_lshl_add_u64 v[170:171], s[20:21], 0, v[170:171]
	v_lshl_add_u64 v[196:197], v[172:173], 0, v[160:161]
	v_lshl_add_u64 v[204:205], v[170:171], 0, v[160:161]
	v_lshlrev_b64 v[166:167], 12, v[166:167]
	v_lshl_add_u64 v[166:167], s[20:21], 0, v[166:167]
	v_lshlrev_b64 v[162:163], 12, v[162:163]
	v_lshl_add_u64 v[162:163], s[20:21], 0, v[162:163]
	v_lshl_add_u64 v[162:163], v[162:163], 0, v[160:161]
	v_lshlrev_b64 v[158:159], 12, v[158:159]
	v_lshl_add_u64 v[158:159], s[20:21], 0, v[158:159]
	s_mov_b64 s[52:53], 0
	s_waitcnt vmcnt(0)
	v_fmamk_f32 v157, v136, 0x3b000000, v185
	v_fmamk_f32 v165, v176, 0x3b000000, v185
	v_rsq_f32_e32 v168, v157
	v_fmamk_f32 v136, v180, 0x3b000000, v185
	v_rsq_f32_e32 v136, v136
	v_rsq_f32_e32 v176, v165
	v_fmamk_f32 v169, v178, 0x3b000000, v185
	v_rsq_f32_e32 v178, v169
	v_pk_mul_f32 v[170:171], v[126:127], v[136:137] op_sel_hi:[1,0]
	v_pk_mul_f32 v[172:173], v[124:125], v[136:137] op_sel_hi:[1,0]
	v_pk_mul_f32 v[174:175], v[122:123], v[136:137] op_sel_hi:[1,0]
	v_pk_mul_f32 v[186:187], v[120:121], v[136:137] op_sel_hi:[1,0]
	v_pk_mul_f32 v[188:189], v[62:63], v[136:137] op_sel_hi:[1,0]
	v_pk_mul_f32 v[190:191], v[60:61], v[136:137] op_sel_hi:[1,0]
	v_pk_mul_f32 v[192:193], v[58:59], v[136:137] op_sel_hi:[1,0]
	v_pk_mul_f32 v[194:195], v[56:57], v[136:137] op_sel_hi:[1,0]
	v_pk_mul_f32 v[206:207], v[118:119], v[168:169] op_sel_hi:[1,0]
	v_pk_mul_f32 v[208:209], v[116:117], v[168:169] op_sel_hi:[1,0]
	v_pk_mul_f32 v[210:211], v[114:115], v[168:169] op_sel_hi:[1,0]
	v_pk_mul_f32 v[212:213], v[112:113], v[168:169] op_sel_hi:[1,0]
	v_pk_mul_f32 v[214:215], v[54:55], v[168:169] op_sel_hi:[1,0]
	v_pk_mul_f32 v[216:217], v[52:53], v[168:169] op_sel_hi:[1,0]
	v_pk_mul_f32 v[218:219], v[50:51], v[168:169] op_sel_hi:[1,0]
	v_pk_mul_f32 v[220:221], v[48:49], v[168:169] op_sel_hi:[1,0]
	v_cvt_pk_bf16_f32 v168, v172, v173
	v_cvt_pk_bf16_f32 v169, v170, v171
	v_cvt_pk_bf16_f32 v170, v186, v187
	v_cvt_pk_bf16_f32 v171, v174, v175
	v_cvt_pk_bf16_f32 v172, v190, v191
	v_cvt_pk_bf16_f32 v173, v188, v189
	v_cvt_pk_bf16_f32 v174, v194, v195
	v_cvt_pk_bf16_f32 v175, v192, v193
	v_cvt_pk_bf16_f32 v186, v208, v209
	v_cvt_pk_bf16_f32 v187, v206, v207
	v_cvt_pk_bf16_f32 v188, v212, v213
	v_cvt_pk_bf16_f32 v189, v210, v211
	v_cvt_pk_bf16_f32 v190, v216, v217
	v_cvt_pk_bf16_f32 v191, v214, v215
; #define ROWS8 _Pragma("unroll") for (int ai = 0; ai < 2; ++ai) _Pragma("unroll") for (int m = 0; m < 4; ++m) if (ai == 0 || !hf)
; #define LOAD_ROW_RS(rsv, ssqp, invn) float rsv[2][4]; ROWS8_ALL rsv[ai][m] = (ssqp)[row0 + ai * HALF + m * 16]; ROWS8_ALL rsv[ai][m] = rstd_of(rsv[ai][m], invn)
; #define PK8(v0, v1) ({ const u32x2 h0_ = pk4(v0), h1_ = pk4(v1); (u32x4){h0_.x, h0_.y, h1_.x, h1_.y}; })
;     DI void operator()(const Acc& acc, const Unit& u, int wr, int wc, int fr, int fq) const {
;     ...
;             } else if (u.kind == K_KN) {
;                 LOAD_ROW_RS(rsv, SSQ(5), 1.f / 512.f);
;                 ROWS8 { const int r = row0 + ai * HALF + m * 16; const float rs = rsv[ai][m];
;                     bf16_t* dst = WSB(OFF_KN) + (size_t)r * 2048 + colp;
; #pragma unroll
;                     for (int bj = 0; bj < 2; ++bj) *(u32x4*)(dst + bj * HALF) = PK8(acc[ai][bj][m][0] * rs, acc[ai][bj][m][1] * rs); }
	v_cvt_pk_bf16_f32 v192, v220, v221
	v_cvt_pk_bf16_f32 v193, v218, v219
	global_store_dwordx4 v[196:197], v[168:171], off
	global_store_dwordx4 v[196:197], v[172:175], off offset:256
	global_store_dwordx4 v[202:203], v[186:189], off
	global_store_dwordx4 v[202:203], v[190:193], off offset:256
	v_pk_mul_f32 v[168:169], v[104:105], v[176:177] op_sel_hi:[1,0]
	v_pk_mul_f32 v[170:171], v[46:47], v[176:177] op_sel_hi:[1,0]
	v_cvt_pk_bf16_f32 v196, v168, v169
	v_pk_mul_f32 v[168:169], v[44:45], v[176:177] op_sel_hi:[1,0]
	v_pk_mul_f32 v[172:173], v[42:43], v[176:177] op_sel_hi:[1,0]
	v_cvt_pk_bf16_f32 v168, v168, v169
	v_cvt_pk_bf16_f32 v169, v170, v171
	v_pk_mul_f32 v[170:171], v[40:41], v[176:177] op_sel_hi:[1,0]
	v_pk_mul_f32 v[174:175], v[98:99], v[178:179] op_sel_hi:[1,0]
	v_cvt_pk_bf16_f32 v170, v170, v171
	v_cvt_pk_bf16_f32 v171, v172, v173
	global_store_dwordx4 v[204:205], v[168:171], off offset:256
	v_fmamk_f32 v157, v230, 0x3b000000, v185
	v_pk_mul_f32 v[222:223], v[110:111], v[176:177] op_sel_hi:[1,0]
	v_lshlrev_b64 v[168:169], 12, v[198:199]
	v_lshl_add_u64 v[168:169], s[20:21], 0, v[168:169]
	v_lshl_add_u64 v[172:173], v[168:169], 0, v[160:161]
	v_pk_mul_f32 v[170:171], v[102:103], v[178:179] op_sel_hi:[1,0]
	v_pk_mul_f32 v[168:169], v[100:101], v[178:179] op_sel_hi:[1,0]
	v_pk_mul_f32 v[224:225], v[108:109], v[176:177] op_sel_hi:[1,0]
	v_cvt_pk_bf16_f32 v168, v168, v169
	v_cvt_pk_bf16_f32 v169, v170, v171
	v_pk_mul_f32 v[170:171], v[96:97], v[178:179] op_sel_hi:[1,0]
	v_pk_mul_f32 v[226:227], v[106:107], v[176:177] op_sel_hi:[1,0]
	v_cvt_pk_bf16_f32 v170, v170, v171
	v_cvt_pk_bf16_f32 v171, v174, v175
	global_store_dwordx4 v[172:173], v[168:171], off
	v_pk_mul_f32 v[174:175], v[34:35], v[178:179] op_sel_hi:[1,0]
	v_fmamk_f32 v136, v231, 0x3b000000, v185
	v_pk_mul_f32 v[170:171], v[38:39], v[178:179] op_sel_hi:[1,0]
	v_pk_mul_f32 v[168:169], v[36:37], v[178:179] op_sel_hi:[1,0]
	v_rsq_f32_e32 v136, v136
	v_cvt_pk_bf16_f32 v168, v168, v169
	v_cvt_pk_bf16_f32 v169, v170, v171
	v_pk_mul_f32 v[170:171], v[32:33], v[178:179] op_sel_hi:[1,0]
	v_cvt_pk_bf16_f32 v194, v224, v225
	v_cvt_pk_bf16_f32 v170, v170, v171
	v_cvt_pk_bf16_f32 v171, v174, v175
	global_store_dwordx4 v[172:173], v[168:171], off offset:256
	v_rsq_f32_e32 v172, v157
	v_fmamk_f32 v157, v229, 0x3b000000, v185
	v_rsq_f32_e32 v174, v157
	v_fmamk_f32 v157, v228, 0x3b000000, v185
	v_rsq_f32_e32 v176, v157
	v_lshlrev_b64 v[168:169], 12, v[200:201]
	v_lshl_add_u64 v[168:169], s[20:21], 0, v[168:169]
	v_lshl_add_u64 v[186:187], v[168:169], 0, v[160:161]
	v_pk_mul_f32 v[170:171], v[94:95], v[176:177] op_sel_hi:[1,0]
	v_pk_mul_f32 v[168:169], v[92:93], v[176:177] op_sel_hi:[1,0]
	v_pk_mul_f32 v[188:189], v[90:91], v[176:177] op_sel_hi:[1,0]
	v_cvt_pk_bf16_f32 v168, v168, v169
	v_cvt_pk_bf16_f32 v169, v170, v171
	v_pk_mul_f32 v[170:171], v[88:89], v[176:177] op_sel_hi:[1,0]
	v_cvt_pk_bf16_f32 v195, v222, v223
	v_cvt_pk_bf16_f32 v170, v170, v171
	v_cvt_pk_bf16_f32 v171, v188, v189
	global_store_dwordx4 v[186:187], v[168:171], off
	v_pk_mul_f32 v[188:189], v[26:27], v[176:177] op_sel_hi:[1,0]
	v_cvt_pk_bf16_f32 v197, v226, v227
	v_pk_mul_f32 v[170:171], v[30:31], v[176:177] op_sel_hi:[1,0]
	v_pk_mul_f32 v[168:169], v[28:29], v[176:177] op_sel_hi:[1,0]
	global_store_dwordx4 v[204:205], v[194:197], off
	v_cvt_pk_bf16_f32 v168, v168, v169
	v_cvt_pk_bf16_f32 v169, v170, v171
	v_pk_mul_f32 v[170:171], v[24:25], v[176:177] op_sel_hi:[1,0]
	s_nop 0
	v_cvt_pk_bf16_f32 v170, v170, v171
	v_cvt_pk_bf16_f32 v171, v188, v189
	global_store_dwordx4 v[186:187], v[168:171], off offset:256
	v_pk_mul_f32 v[186:187], v[82:83], v[174:175] op_sel_hi:[1,0]
	s_nop 0
	v_lshl_add_u64 v[170:171], v[166:167], 0, v[160:161]
	v_pk_mul_f32 v[168:169], v[86:87], v[174:175] op_sel_hi:[1,0]
	v_pk_mul_f32 v[166:167], v[84:85], v[174:175] op_sel_hi:[1,0]
	s_nop 0
	v_cvt_pk_bf16_f32 v166, v166, v167
	v_cvt_pk_bf16_f32 v167, v168, v169
	v_pk_mul_f32 v[168:169], v[80:81], v[174:175] op_sel_hi:[1,0]
	s_nop 0
	v_cvt_pk_bf16_f32 v168, v168, v169
	v_cvt_pk_bf16_f32 v169, v186, v187
	global_store_dwordx4 v[170:171], v[166:169], off
	v_pk_mul_f32 v[186:187], v[18:19], v[174:175] op_sel_hi:[1,0]
	s_nop 0
	v_pk_mul_f32 v[168:169], v[22:23], v[174:175] op_sel_hi:[1,0]
	v_pk_mul_f32 v[166:167], v[20:21], v[174:175] op_sel_hi:[1,0]
	s_nop 0
	v_cvt_pk_bf16_f32 v166, v166, v167
	v_cvt_pk_bf16_f32 v167, v168, v169
	v_pk_mul_f32 v[168:169], v[16:17], v[174:175] op_sel_hi:[1,0]
	s_nop 0
	v_cvt_pk_bf16_f32 v168, v168, v169
	v_cvt_pk_bf16_f32 v169, v186, v187
	global_store_dwordx4 v[170:171], v[166:169], off offset:256
	v_pk_mul_f32 v[170:171], v[74:75], v[172:173] op_sel_hi:[1,0]
	s_nop 0
	v_pk_mul_f32 v[168:169], v[78:79], v[172:173] op_sel_hi:[1,0]
	v_pk_mul_f32 v[166:167], v[76:77], v[172:173] op_sel_hi:[1,0]
	s_nop 0
	v_cvt_pk_bf16_f32 v166, v166, v167
	v_cvt_pk_bf16_f32 v167, v168, v169
	v_pk_mul_f32 v[168:169], v[72:73], v[172:173] op_sel_hi:[1,0]
	s_nop 0
	v_cvt_pk_bf16_f32 v168, v168, v169
	v_cvt_pk_bf16_f32 v169, v170, v171
	global_store_dwordx4 v[162:163], v[166:169], off
	v_pk_mul_f32 v[170:171], v[10:11], v[172:173] op_sel_hi:[1,0]
	s_nop 0
	v_pk_mul_f32 v[168:169], v[14:15], v[172:173] op_sel_hi:[1,0]
	v_pk_mul_f32 v[166:167], v[12:13], v[172:173] op_sel_hi:[1,0]
	s_nop 0
	v_cvt_pk_bf16_f32 v166, v166, v167
	v_cvt_pk_bf16_f32 v167, v168, v169
	v_pk_mul_f32 v[168:169], v[8:9], v[172:173] op_sel_hi:[1,0]
	s_nop 0
	v_cvt_pk_bf16_f32 v168, v168, v169
	v_cvt_pk_bf16_f32 v169, v170, v171
	global_store_dwordx4 v[162:163], v[166:169], off offset:256
	v_lshl_add_u64 v[162:163], v[158:159], 0, v[160:161]
	v_pk_mul_f32 v[160:161], v[70:71], v[136:137] op_sel_hi:[1,0]
	v_pk_mul_f32 v[158:159], v[68:69], v[136:137] op_sel_hi:[1,0]
	v_pk_mul_f32 v[166:167], v[66:67], v[136:137] op_sel_hi:[1,0]
	v_cvt_pk_bf16_f32 v158, v158, v159
	v_cvt_pk_bf16_f32 v159, v160, v161
	v_pk_mul_f32 v[160:161], v[64:65], v[136:137] op_sel_hi:[1,0]
	s_nop 0
	v_cvt_pk_bf16_f32 v160, v160, v161
	v_cvt_pk_bf16_f32 v161, v166, v167
	global_store_dwordx4 v[162:163], v[158:161], off
	v_pk_mul_f32 v[166:167], v[2:3], v[136:137] op_sel_hi:[1,0]
	s_nop 0
	v_pk_mul_f32 v[160:161], v[6:7], v[136:137] op_sel_hi:[1,0]
	v_pk_mul_f32 v[158:159], v[4:5], v[136:137] op_sel_hi:[1,0]
	s_nop 0
	v_cvt_pk_bf16_f32 v158, v158, v159
	v_cvt_pk_bf16_f32 v159, v160, v161
	v_pk_mul_f32 v[160:161], v[0:1], v[136:137] op_sel_hi:[1,0]
	s_nop 0
	v_cvt_pk_bf16_f32 v160, v160, v161
	v_cvt_pk_bf16_f32 v161, v166, v167
	global_store_dwordx4 v[162:163], v[158:161], off offset:256

; #define PG8_STAGE(bufoff, gbase, voff) do { _Pragma("unroll") for (int _i = 0; _i < 2; ++_i) \
;         __builtin_amdgcn_global_load_lds((const unsigned*)((const char*)(gbase) + (voff)[_i]), (LAS unsigned*)(lds + (bufoff) + ldsw + _i * 8192), 16, 0, 0); } while (0)
; #define PG8_LDA(dst, b, h) do { _Pragma("unroll") for (int m = 0; m < 4; ++m) _Pragma("unroll") for (int k = 0; k < 2; ++k) dst[m][k] = *(const LAS bf16x8*)(lds + PG8_SA(b, h) + aoff + m * 2048 + k * 1024); } while (0)
; #define PG8_LDB(dst, b, h) do { _Pragma("unroll") for (int n = 0; n < 2; ++n) _Pragma("unroll") for (int k = 0; k < 2; ++k) dst[n][k] = *(const LAS bf16x8*)(lds + PG8_SB(b, h) + boff + n * 2048 + k * 1024); } while (0)
; #define PG8_WAIT_V(n) asm volatile("s_waitcnt vmcnt(" #n ")" ::: "memory")
; #define PG8_BAR __builtin_amdgcn_s_barrier()
; #define PG8_SCHED __builtin_amdgcn_sched_barrier(0)
; template <class Epi>
; DI void gemm_phase(LAS unsigned char* lds, int wid, int K, int lda, int ldb, bool bperm, const Sched3& S, const Epi& E) {
;     ...
;     const char* cA = cur.A; const char* cB = cur.B; size_t hA = cur.half ? (size_t)0 : hstepA;
;     PG8_STAGE(PG8_SB(0, 0), cB, voffB); PG8_STAGE(PG8_SA(0, 0), cA, voffA); PG8_STAGE(PG8_SB(0, 1), cB + hstepB, voffB); PG8_STAGE(PG8_SA(0, 1), cA + hA, voffA);
;     if (wr == 1) PG8_BAR;
;     PG8_WAIT_V(4); PG8_BAR;
;     PG8_STAGE(PG8_SB(1, 0), cB + kstep, voffB); PG8_STAGE(PG8_SA(1, 0), cA + kstep, voffA); PG8_STAGE(PG8_SB(1, 1), cB + hstepB + kstep, voffB);
;     PG8_WAIT_V(6); PG8_BAR;
;     for (;;) {
;         const bool has_next = S.next(ui + 1, nxt);
;         const char* nA = has_next ? nxt.A : cA; const char* nB = has_next ? nxt.B : cB; const size_t nhA = has_next ? (nxt.half ? (size_t)0 : hstepA) : hA; const bool full = (cur.half == 0);
;         for (int t = 0; t < nt; t += 2) {
;             const bool last = (t == nt - 2);
;             const char* a1 = cA + (size_t)(t + 1) * kstep;
;             const char* a2 = last ? nA : cA + (size_t)(t + 2) * kstep; const char* b2 = last ? nB : cB + (size_t)(t + 2) * kstep;
;             const char* a3 = a2 + kstep; const char* b3 = b2 + kstep; const size_t h2 = last ? nhA : hA;
;             PG8_LDB(B0, 0, 0); PG8_SCHED; PG8_LDA(At, 0, 0); PG8_STAGE(PG8_SA(1, 1), a1 + hA, voffA);
.LBB0_1175:
	s_add_u32 s36, s36, 0x80080
	s_addc_u32 s37, s37, 0
	s_add_u32 s19, s38, 0x100
	s_nop 0
	s_addc_u32 s21, s39, 0
	s_mov_b32 s27, -2
	s_waitcnt lgkmcnt(0)
	ds_read_b128 v[128:131], v185
	ds_read_b128 v[132:135], v185 offset:1024
	ds_read_b128 v[136:139], v185 offset:2048
	ds_read_b128 v[140:143], v185 offset:3072
	s_add_u32 s38, s36, 0xfff80080
	s_addc_u32 s39, s37, -1
	s_cmp_eq_u32 s27, 28
	s_cselect_b32 s41, s29, s39
	s_cselect_b32 s40, s28, s38
	s_cselect_b32 s39, s31, s21
	s_cselect_b32 s38, s30, s19

; #define PG8_STAGE(bufoff, gbase, voff) do { _Pragma("unroll") for (int _i = 0; _i < 2; ++_i) \
;         __builtin_amdgcn_global_load_lds((const unsigned*)((const char*)(gbase) + (voff)[_i]), (LAS unsigned*)(lds + (bufoff) + ldsw + _i * 8192), 16, 0, 0); } while (0)
; #define PG8_LDA(dst, b, h) do { _Pragma("unroll") for (int m = 0; m < 4; ++m) _Pragma("unroll") for (int k = 0; k < 2; ++k) dst[m][k] = *(const LAS bf16x8*)(lds + PG8_SA(b, h) + aoff + m * 2048 + k * 1024); } while (0)
; #define PG8_LDB(dst, b, h) do { _Pragma("unroll") for (int n = 0; n < 2; ++n) _Pragma("unroll") for (int k = 0; k < 2; ++k) dst[n][k] = *(const LAS bf16x8*)(lds + PG8_SB(b, h) + boff + n * 2048 + k * 1024); } while (0)
; #define PG8_SCHED __builtin_amdgcn_sched_barrier(0)
; template <class Epi>
; DI void gemm_phase(LAS unsigned char* lds, int wid, int K, int lda, int ldb, bool bperm, const Sched3& S, const Epi& E) {
;     ...
;             PG8_LDB(B0, 0, 0); PG8_SCHED; PG8_LDA(At, 0, 0); PG8_STAGE(PG8_SA(1, 1), a1 + hA, voffA);
	s_add_i32 m0, s48, 0xc000
	ds_read_b128 v[144:147], v186
	ds_read_b128 v[148:151], v186 offset:1024
	ds_read_b128 v[162:165], v186 offset:2048
	ds_read_b128 v[166:169], v186 offset:3072
	ds_read_b128 v[170:173], v186 offset:4096
	ds_read_b128 v[174:177], v186 offset:5120
	ds_read_b128 v[188:191], v186 offset:6144
	ds_read_b128 v[192:195], v186 offset:7168
	global_load_lds_dwordx4 v156, s[36:37]

; #define PG8_STAGE(bufoff, gbase, voff) do { _Pragma("unroll") for (int _i = 0; _i < 2; ++_i) \
;         __builtin_amdgcn_global_load_lds((const unsigned*)((const char*)(gbase) + (voff)[_i]), (LAS unsigned*)(lds + (bufoff) + ldsw + _i * 8192), 16, 0, 0); } while (0)
; #define PG8_LDA(dst, b, h) do { _Pragma("unroll") for (int m = 0; m < 4; ++m) _Pragma("unroll") for (int k = 0; k < 2; ++k) dst[m][k] = *(const LAS bf16x8*)(lds + PG8_SA(b, h) + aoff + m * 2048 + k * 1024); } while (0)
; #define PG8_LDB(dst, b, h) do { _Pragma("unroll") for (int n = 0; n < 2; ++n) _Pragma("unroll") for (int k = 0; k < 2; ++k) dst[n][k] = *(const LAS bf16x8*)(lds + PG8_SB(b, h) + boff + n * 2048 + k * 1024); } while (0)
; #define PG8_MMA(ai, bj, At, Bt) do { __builtin_amdgcn_s_setprio(1); _Pragma("unroll") for (int m = 0; m < 4; ++m) _Pragma("unroll") for (int n = 0; n < 2; ++n) _Pragma("unroll") for (int k = 0; k < 2; ++k) \
;         acc[ai][bj][m][n] = __builtin_amdgcn_mfma_f32_16x16x32_bf16(Bt[n][k], At[m][k], acc[ai][bj][m][n], 0, 0, 0); __builtin_amdgcn_s_setprio(0); } while (0)
; #define PG8_WAIT_L(n) asm volatile("s_waitcnt lgkmcnt(" #n ")" ::: "memory")
; #define PG8_BAR __builtin_amdgcn_s_barrier()
; #define PG8_SCHED __builtin_amdgcn_sched_barrier(0)
; template <class Epi>
; DI void gemm_phase(LAS unsigned char* lds, int wid, int K, int lda, int ldb, bool bperm, const Sched3& S, const Epi& E) {
;     ...
;             PG8_LDB(B0, 0, 0); PG8_SCHED; PG8_LDA(At, 0, 0); PG8_STAGE(PG8_SA(1, 1), a1 + hA, voffA);
;             PG8_WAIT_L(8); PG8_BAR; PG8_WAIT_L(0); PG8_MMA(0, 0, At, B0); PG8_BAR; PG8_SCHED;
	s_add_i32 m0, s48, 0xe000
	s_nop 0
	global_load_lds_dwordx4 v158, s[36:37]
	s_waitcnt lgkmcnt(8)
	s_barrier
	s_waitcnt lgkmcnt(0)
	s_setprio 1
	s_waitcnt lgkmcnt(0)
	v_mfma_f32_16x16x32_bf16 v[124:127], v[128:131], v[144:147], 0
	v_mfma_f32_16x16x32_bf16 v[120:123], v[136:139], v[144:147], 0
	v_mfma_f32_16x16x32_bf16 v[108:111], v[128:131], v[162:165], 0
	v_mfma_f32_16x16x32_bf16 v[104:107], v[136:139], v[162:165], 0
	v_mfma_f32_16x16x32_bf16 v[92:95], v[128:131], v[170:173], 0
	v_mfma_f32_16x16x32_bf16 v[88:91], v[136:139], v[170:173], 0
	v_mfma_f32_16x16x32_bf16 v[76:79], v[128:131], v[188:191], 0
	v_mfma_f32_16x16x32_bf16 v[72:75], v[136:139], v[188:191], 0
	v_mfma_f32_16x16x32_bf16 v[124:127], v[132:135], v[148:151], v[124:127]
	v_mfma_f32_16x16x32_bf16 v[120:123], v[140:143], v[148:151], v[120:123]
	v_mfma_f32_16x16x32_bf16 v[108:111], v[132:135], v[166:169], v[108:111]
	v_mfma_f32_16x16x32_bf16 v[104:107], v[140:143], v[166:169], v[104:107]
	v_mfma_f32_16x16x32_bf16 v[92:95], v[132:135], v[174:177], v[92:95]
	v_mfma_f32_16x16x32_bf16 v[88:91], v[140:143], v[174:177], v[88:91]
	v_mfma_f32_16x16x32_bf16 v[76:79], v[132:135], v[192:195], v[76:79]
	v_mfma_f32_16x16x32_bf16 v[72:75], v[140:143], v[192:195], v[72:75]
	s_setprio 0
	s_barrier
	s_add_i32 s61, s57, s47

; #define PG8_STAGE(bufoff, gbase, voff) do { _Pragma("unroll") for (int _i = 0; _i < 2; ++_i) \
;         __builtin_amdgcn_global_load_lds((const unsigned*)((const char*)(gbase) + (voff)[_i]), (LAS unsigned*)(lds + (bufoff) + ldsw + _i * 8192), 16, 0, 0); } while (0)
; #define PG8_LDB(dst, b, h) do { _Pragma("unroll") for (int n = 0; n < 2; ++n) _Pragma("unroll") for (int k = 0; k < 2; ++k) dst[n][k] = *(const LAS bf16x8*)(lds + PG8_SB(b, h) + boff + n * 2048 + k * 1024); } while (0)
; template <class Epi>
; DI void gemm_phase(LAS unsigned char* lds, int wid, int K, int lda, int ldb, bool bperm, const Sched3& S, const Epi& E) {
;     ...
;             PG8_LDB(B1, 0, 1); PG8_STAGE(PG8_SB(0, 0), b2, voffB);
	s_mov_b32 m0, s61
	ds_read_b128 v[196:199], v187
	ds_read_b128 v[200:203], v187 offset:1024
	ds_read_b128 v[204:207], v187 offset:2048
	ds_read_b128 v[208:211], v187 offset:3072
	global_load_lds_dwordx4 v152, s[38:39]

; #define PG8_STAGE(bufoff, gbase, voff) do { _Pragma("unroll") for (int _i = 0; _i < 2; ++_i) \
;         __builtin_amdgcn_global_load_lds((const unsigned*)((const char*)(gbase) + (voff)[_i]), (LAS unsigned*)(lds + (bufoff) + ldsw + _i * 8192), 16, 0, 0); } while (0)
; #define PG8_LDA(dst, b, h) do { _Pragma("unroll") for (int m = 0; m < 4; ++m) _Pragma("unroll") for (int k = 0; k < 2; ++k) dst[m][k] = *(const LAS bf16x8*)(lds + PG8_SA(b, h) + aoff + m * 2048 + k * 1024); } while (0)
; #define PG8_LDB(dst, b, h) do { _Pragma("unroll") for (int n = 0; n < 2; ++n) _Pragma("unroll") for (int k = 0; k < 2; ++k) dst[n][k] = *(const LAS bf16x8*)(lds + PG8_SB(b, h) + boff + n * 2048 + k * 1024); } while (0)
; #define PG8_MMA(ai, bj, At, Bt) do { __builtin_amdgcn_s_setprio(1); _Pragma("unroll") for (int m = 0; m < 4; ++m) _Pragma("unroll") for (int n = 0; n < 2; ++n) _Pragma("unroll") for (int k = 0; k < 2; ++k) \
;         acc[ai][bj][m][n] = __builtin_amdgcn_mfma_f32_16x16x32_bf16(Bt[n][k], At[m][k], acc[ai][bj][m][n], 0, 0, 0); __builtin_amdgcn_s_setprio(0); } while (0)
; #define PG8_WAIT_L(n) asm volatile("s_waitcnt lgkmcnt(" #n ")" ::: "memory")
; #define PG8_BAR __builtin_amdgcn_s_barrier()
; #define PG8_SCHED __builtin_amdgcn_sched_barrier(0)
; template <class Epi>
; DI void gemm_phase(LAS unsigned char* lds, int wid, int K, int lda, int ldb, bool bperm, const Sched3& S, const Epi& E) {
;     ...
;             PG8_LDB(B1, 0, 1); PG8_STAGE(PG8_SB(0, 0), b2, voffB);
;             PG8_BAR; PG8_WAIT_L(0); PG8_MMA(0, 1, At, B1); PG8_BAR;
;             PG8_LDA(At, 0, 1); PG8_STAGE(PG8_SA(0, 0), a2, voffA);
;             PG8_BAR; PG8_WAIT_L(0); if (full) PG8_MMA(1, 0, At, B0); PG8_BAR; PG8_SCHED;
;             PG8_STAGE(PG8_SB(0, 1), b2 + hstepB, voffB);
	s_add_i32 m0, s61, 0x2000
	s_nop 0
	global_load_lds_dwordx4 v154, s[38:39]
	s_barrier
	s_waitcnt lgkmcnt(0)
	s_setprio 1
	s_waitcnt lgkmcnt(0)
	v_mfma_f32_16x16x32_bf16 v[116:119], v[196:199], v[144:147], 0
	v_mfma_f32_16x16x32_bf16 v[112:115], v[204:207], v[144:147], 0
	v_mfma_f32_16x16x32_bf16 v[100:103], v[196:199], v[162:165], 0
	v_mfma_f32_16x16x32_bf16 v[96:99], v[204:207], v[162:165], 0
	v_mfma_f32_16x16x32_bf16 v[84:87], v[196:199], v[170:173], 0
	v_mfma_f32_16x16x32_bf16 v[80:83], v[204:207], v[170:173], 0
	v_mfma_f32_16x16x32_bf16 v[68:71], v[196:199], v[188:191], 0
	v_mfma_f32_16x16x32_bf16 v[64:67], v[204:207], v[188:191], 0
	v_mfma_f32_16x16x32_bf16 v[116:119], v[200:203], v[148:151], v[116:119]
	v_mfma_f32_16x16x32_bf16 v[112:115], v[208:211], v[148:151], v[112:115]
	v_mfma_f32_16x16x32_bf16 v[100:103], v[200:203], v[166:169], v[100:103]
	v_mfma_f32_16x16x32_bf16 v[96:99], v[208:211], v[166:169], v[96:99]
	v_mfma_f32_16x16x32_bf16 v[84:87], v[200:203], v[174:177], v[84:87]
	v_mfma_f32_16x16x32_bf16 v[80:83], v[208:211], v[174:177], v[80:83]
	v_mfma_f32_16x16x32_bf16 v[68:71], v[200:203], v[192:195], v[68:71]
	v_mfma_f32_16x16x32_bf16 v[64:67], v[208:211], v[192:195], v[64:67]
	s_setprio 0
	s_mov_b32 m0, s48
	s_mov_b64 s[100:101], s[40:41]
	s_barrier
	ds_read_b128 v[144:147], v186 offset:16384
	ds_read_b128 v[148:151], v186 offset:17408
	ds_read_b128 v[162:165], v186 offset:18432
	ds_read_b128 v[166:169], v186 offset:19456
	ds_read_b128 v[170:173], v186 offset:20480
	ds_read_b128 v[174:177], v186 offset:21504
	ds_read_b128 v[188:191], v186 offset:22528
	ds_read_b128 v[192:195], v186 offset:23552
	global_load_lds_dwordx4 v152, s[40:41]
	s_mov_b64 s[100:101], s[40:41]
	s_mov_b32 m0, s49
	s_nop 0
	global_load_lds_dwordx4 v154, s[40:41]
	s_barrier
	s_waitcnt lgkmcnt(0)
	s_setprio 1
	s_waitcnt lgkmcnt(0)
	v_mfma_f32_16x16x32_bf16 v[60:63], v[128:131], v[144:147], 0
	v_mfma_f32_16x16x32_bf16 v[56:59], v[136:139], v[144:147], 0
	v_mfma_f32_16x16x32_bf16 v[44:47], v[128:131], v[162:165], 0
	v_mfma_f32_16x16x32_bf16 v[40:43], v[136:139], v[162:165], 0
	v_mfma_f32_16x16x32_bf16 v[28:31], v[128:131], v[170:173], 0
	v_mfma_f32_16x16x32_bf16 v[24:27], v[136:139], v[170:173], 0
	v_mfma_f32_16x16x32_bf16 v[12:15], v[128:131], v[188:191], 0
	v_mfma_f32_16x16x32_bf16 v[8:11], v[136:139], v[188:191], 0
	v_mfma_f32_16x16x32_bf16 v[60:63], v[132:135], v[148:151], v[60:63]
	v_mfma_f32_16x16x32_bf16 v[56:59], v[140:143], v[148:151], v[56:59]
	v_mfma_f32_16x16x32_bf16 v[44:47], v[132:135], v[166:169], v[44:47]
	v_mfma_f32_16x16x32_bf16 v[40:43], v[140:143], v[166:169], v[40:43]
	v_mfma_f32_16x16x32_bf16 v[28:31], v[132:135], v[174:177], v[28:31]
	v_mfma_f32_16x16x32_bf16 v[24:27], v[140:143], v[174:177], v[24:27]
	v_mfma_f32_16x16x32_bf16 v[12:15], v[132:135], v[192:195], v[12:15]
	v_mfma_f32_16x16x32_bf16 v[8:11], v[140:143], v[192:195], v[8:11]
	s_setprio 0
	s_barrier
	s_add_u32 s62, s38, 0x80000
	s_addc_u32 s63, s39, 0
	s_add_i32 s61, s58, s47

; #define PG8_STAGE(bufoff, gbase, voff) do { _Pragma("unroll") for (int _i = 0; _i < 2; ++_i) \
;         __builtin_amdgcn_global_load_lds((const unsigned*)((const char*)(gbase) + (voff)[_i]), (LAS unsigned*)(lds + (bufoff) + ldsw + _i * 8192), 16, 0, 0); } while (0)
; template <class Epi>
; DI void gemm_phase(LAS unsigned char* lds, int wid, int K, int lda, int ldb, bool bperm, const Sched3& S, const Epi& E) {
;     ...
;             PG8_STAGE(PG8_SB(0, 1), b2 + hstepB, voffB);
	s_mov_b32 m0, s61
	s_nop 0
	global_load_lds_dwordx4 v152, s[62:63]

; #define PG8_STAGE(bufoff, gbase, voff) do { _Pragma("unroll") for (int _i = 0; _i < 2; ++_i) \
;         __builtin_amdgcn_global_load_lds((const unsigned*)((const char*)(gbase) + (voff)[_i]), (LAS unsigned*)(lds + (bufoff) + ldsw + _i * 8192), 16, 0, 0); } while (0)
; #define PG8_LDA(dst, b, h) do { _Pragma("unroll") for (int m = 0; m < 4; ++m) _Pragma("unroll") for (int k = 0; k < 2; ++k) dst[m][k] = *(const LAS bf16x8*)(lds + PG8_SA(b, h) + aoff + m * 2048 + k * 1024); } while (0)
; #define PG8_LDB(dst, b, h) do { _Pragma("unroll") for (int n = 0; n < 2; ++n) _Pragma("unroll") for (int k = 0; k < 2; ++k) dst[n][k] = *(const LAS bf16x8*)(lds + PG8_SB(b, h) + boff + n * 2048 + k * 1024); } while (0)
; #define PG8_MMA(ai, bj, At, Bt) do { __builtin_amdgcn_s_setprio(1); _Pragma("unroll") for (int m = 0; m < 4; ++m) _Pragma("unroll") for (int n = 0; n < 2; ++n) _Pragma("unroll") for (int k = 0; k < 2; ++k) \
;         acc[ai][bj][m][n] = __builtin_amdgcn_mfma_f32_16x16x32_bf16(Bt[n][k], At[m][k], acc[ai][bj][m][n], 0, 0, 0); __builtin_amdgcn_s_setprio(0); } while (0)
; #define PG8_WAIT_V(n) asm volatile("s_waitcnt vmcnt(" #n ")" ::: "memory")
; #define PG8_BAR __builtin_amdgcn_s_barrier()
; #define PG8_SCHED __builtin_amdgcn_sched_barrier(0)
; template <class Epi>
; DI void gemm_phase(LAS unsigned char* lds, int wid, int K, int lda, int ldb, bool bperm, const Sched3& S, const Epi& E) {
;     ...
;             PG8_STAGE(PG8_SB(0, 1), b2 + hstepB, voffB);
;             PG8_WAIT_V(6); PG8_BAR; if (full) PG8_MMA(1, 1, At, B1); PG8_BAR;
;             PG8_LDB(B0, 1, 0); PG8_SCHED; PG8_LDA(At, 1, 0); PG8_STAGE(PG8_SA(0, 1), a2 + h2, voffA);
	s_add_i32 m0, s61, 0x2000
	s_nop 0
	global_load_lds_dwordx4 v154, s[62:63]
	s_waitcnt vmcnt(6)
	s_barrier
	s_setprio 1
	v_mfma_f32_16x16x32_bf16 v[52:55], v[196:199], v[144:147], 0
	v_mfma_f32_16x16x32_bf16 v[48:51], v[204:207], v[144:147], 0
	v_mfma_f32_16x16x32_bf16 v[36:39], v[196:199], v[162:165], 0
	v_mfma_f32_16x16x32_bf16 v[32:35], v[204:207], v[162:165], 0
	v_mfma_f32_16x16x32_bf16 v[20:23], v[196:199], v[170:173], 0
	v_mfma_f32_16x16x32_bf16 v[16:19], v[204:207], v[170:173], 0
	v_mfma_f32_16x16x32_bf16 v[4:7], v[196:199], v[188:191], 0
	v_mfma_f32_16x16x32_bf16 v[0:3], v[204:207], v[188:191], 0
	v_mfma_f32_16x16x32_bf16 v[52:55], v[200:203], v[148:151], v[52:55]
	v_mfma_f32_16x16x32_bf16 v[48:51], v[208:211], v[148:151], v[48:51]
	v_mfma_f32_16x16x32_bf16 v[36:39], v[200:203], v[166:169], v[36:39]
	v_mfma_f32_16x16x32_bf16 v[32:35], v[208:211], v[166:169], v[32:35]
	v_mfma_f32_16x16x32_bf16 v[20:23], v[200:203], v[174:177], v[20:23]
	v_mfma_f32_16x16x32_bf16 v[16:19], v[208:211], v[174:177], v[16:19]
	v_mfma_f32_16x16x32_bf16 v[4:7], v[200:203], v[192:195], v[4:7]
	v_mfma_f32_16x16x32_bf16 v[0:3], v[208:211], v[192:195], v[0:3]
	s_setprio 0
	s_add_i32 s61, 0, 0x18000
	v_add_u32_e32 v140, s61, v181
	s_barrier
	ds_read_b128 v[128:131], v140
	ds_read_b128 v[132:135], v140 offset:1024
	ds_read_b128 v[136:139], v140 offset:2048
	ds_read_b128 v[140:143], v140 offset:3072
	s_add_u32 s40, s40, 0x80000
	s_addc_u32 s41, s41, 0
	s_mov_b32 m0, s50

; #define PG8_STAGE(bufoff, gbase, voff) do { _Pragma("unroll") for (int _i = 0; _i < 2; ++_i) \
;         __builtin_amdgcn_global_load_lds((const unsigned*)((const char*)(gbase) + (voff)[_i]), (LAS unsigned*)(lds + (bufoff) + ldsw + _i * 8192), 16, 0, 0); } while (0)
; #define PG8_LDA(dst, b, h) do { _Pragma("unroll") for (int m = 0; m < 4; ++m) _Pragma("unroll") for (int k = 0; k < 2; ++k) dst[m][k] = *(const LAS bf16x8*)(lds + PG8_SA(b, h) + aoff + m * 2048 + k * 1024); } while (0)
; #define PG8_LDB(dst, b, h) do { _Pragma("unroll") for (int n = 0; n < 2; ++n) _Pragma("unroll") for (int k = 0; k < 2; ++k) dst[n][k] = *(const LAS bf16x8*)(lds + PG8_SB(b, h) + boff + n * 2048 + k * 1024); } while (0)
; #define PG8_SCHED __builtin_amdgcn_sched_barrier(0)
; template <class Epi>
; DI void gemm_phase(LAS unsigned char* lds, int wid, int K, int lda, int ldb, bool bperm, const Sched3& S, const Epi& E) {
;     ...
;             PG8_LDB(B0, 1, 0); PG8_SCHED; PG8_LDA(At, 1, 0); PG8_STAGE(PG8_SA(0, 1), a2 + h2, voffA);
	ds_read_b128 v[144:147], v186 offset:32768
	ds_read_b128 v[148:151], v186 offset:33792
	ds_read_b128 v[162:165], v186 offset:34816
	ds_read_b128 v[166:169], v186 offset:35840
	ds_read_b128 v[170:173], v186 offset:36864
	ds_read_b128 v[174:177], v186 offset:37888
	ds_read_b128 v[188:191], v186 offset:38912
	ds_read_b128 v[192:195], v186 offset:39936
	global_load_lds_dwordx4 v152, s[40:41]

; #define PG8_STAGE(bufoff, gbase, voff) do { _Pragma("unroll") for (int _i = 0; _i < 2; ++_i) \
;         __builtin_amdgcn_global_load_lds((const unsigned*)((const char*)(gbase) + (voff)[_i]), (LAS unsigned*)(lds + (bufoff) + ldsw + _i * 8192), 16, 0, 0); } while (0)
; #define PG8_LDA(dst, b, h) do { _Pragma("unroll") for (int m = 0; m < 4; ++m) _Pragma("unroll") for (int k = 0; k < 2; ++k) dst[m][k] = *(const LAS bf16x8*)(lds + PG8_SA(b, h) + aoff + m * 2048 + k * 1024); } while (0)
; #define PG8_LDB(dst, b, h) do { _Pragma("unroll") for (int n = 0; n < 2; ++n) _Pragma("unroll") for (int k = 0; k < 2; ++k) dst[n][k] = *(const LAS bf16x8*)(lds + PG8_SB(b, h) + boff + n * 2048 + k * 1024); } while (0)
; #define PG8_MMA(ai, bj, At, Bt) do { __builtin_amdgcn_s_setprio(1); _Pragma("unroll") for (int m = 0; m < 4; ++m) _Pragma("unroll") for (int n = 0; n < 2; ++n) _Pragma("unroll") for (int k = 0; k < 2; ++k) \
;         acc[ai][bj][m][n] = __builtin_amdgcn_mfma_f32_16x16x32_bf16(Bt[n][k], At[m][k], acc[ai][bj][m][n], 0, 0, 0); __builtin_amdgcn_s_setprio(0); } while (0)
; #define PG8_WAIT_L(n) asm volatile("s_waitcnt lgkmcnt(" #n ")" ::: "memory")
; #define PG8_BAR __builtin_amdgcn_s_barrier()
; #define PG8_SCHED __builtin_amdgcn_sched_barrier(0)
; template <class Epi>
; DI void gemm_phase(LAS unsigned char* lds, int wid, int K, int lda, int ldb, bool bperm, const Sched3& S, const Epi& E) {
;     ...
;             PG8_LDB(B0, 1, 0); PG8_SCHED; PG8_LDA(At, 1, 0); PG8_STAGE(PG8_SA(0, 1), a2 + h2, voffA);
;             PG8_WAIT_L(8); PG8_BAR; PG8_WAIT_L(0); PG8_MMA(0, 0, At, B0); PG8_BAR; PG8_SCHED;
	s_mov_b32 m0, s51
	s_nop 0
	global_load_lds_dwordx4 v154, s[40:41]
	s_waitcnt lgkmcnt(8)
	s_barrier
	s_waitcnt lgkmcnt(0)
	s_setprio 1
	s_waitcnt lgkmcnt(0)
	v_mfma_f32_16x16x32_bf16 v[124:127], v[128:131], v[144:147], v[124:127]
	v_mfma_f32_16x16x32_bf16 v[120:123], v[136:139], v[144:147], v[120:123]
	v_mfma_f32_16x16x32_bf16 v[108:111], v[128:131], v[162:165], v[108:111]
	v_mfma_f32_16x16x32_bf16 v[104:107], v[136:139], v[162:165], v[104:107]
	v_mfma_f32_16x16x32_bf16 v[92:95], v[128:131], v[170:173], v[92:95]
	v_mfma_f32_16x16x32_bf16 v[88:91], v[136:139], v[170:173], v[88:91]
	v_mfma_f32_16x16x32_bf16 v[76:79], v[128:131], v[188:191], v[76:79]
	v_mfma_f32_16x16x32_bf16 v[72:75], v[136:139], v[188:191], v[72:75]
	v_mfma_f32_16x16x32_bf16 v[124:127], v[132:135], v[148:151], v[124:127]
	v_mfma_f32_16x16x32_bf16 v[120:123], v[140:143], v[148:151], v[120:123]
	v_mfma_f32_16x16x32_bf16 v[108:111], v[132:135], v[166:169], v[108:111]
	v_mfma_f32_16x16x32_bf16 v[104:107], v[140:143], v[166:169], v[104:107]
	v_mfma_f32_16x16x32_bf16 v[92:95], v[132:135], v[174:177], v[92:95]
	v_mfma_f32_16x16x32_bf16 v[88:91], v[140:143], v[174:177], v[88:91]
	v_mfma_f32_16x16x32_bf16 v[76:79], v[132:135], v[192:195], v[76:79]
	v_mfma_f32_16x16x32_bf16 v[72:75], v[140:143], v[192:195], v[72:75]
	s_setprio 0
	s_barrier
	s_add_i32 s40, 0, 0x1c000
	s_add_i32 s41, s61, s47
	v_add_u32_e32 v208, s40, v181

; #define PG8_STAGE(bufoff, gbase, voff) do { _Pragma("unroll") for (int _i = 0; _i < 2; ++_i) \
;         __builtin_amdgcn_global_load_lds((const unsigned*)((const char*)(gbase) + (voff)[_i]), (LAS unsigned*)(lds + (bufoff) + ldsw + _i * 8192), 16, 0, 0); } while (0)
; #define PG8_LDB(dst, b, h) do { _Pragma("unroll") for (int n = 0; n < 2; ++n) _Pragma("unroll") for (int k = 0; k < 2; ++k) dst[n][k] = *(const LAS bf16x8*)(lds + PG8_SB(b, h) + boff + n * 2048 + k * 1024); } while (0)
; template <class Epi>
; DI void gemm_phase(LAS unsigned char* lds, int wid, int K, int lda, int ldb, bool bperm, const Sched3& S, const Epi& E) {
;     ...
;             PG8_LDB(B1, 1, 1); PG8_STAGE(PG8_SB(1, 0), b3, voffB);
	s_sub_i32 m0, s41, 0x80
	ds_read_b128 v[196:199], v208
	ds_read_b128 v[200:203], v208 offset:1024
	ds_read_b128 v[204:207], v208 offset:2048
	ds_read_b128 v[208:211], v208 offset:3072
	global_load_lds_dwordx4 v152, s[38:39] offset:128

; #define PG8_STAGE(bufoff, gbase, voff) do { _Pragma("unroll") for (int _i = 0; _i < 2; ++_i) \
;         __builtin_amdgcn_global_load_lds((const unsigned*)((const char*)(gbase) + (voff)[_i]), (LAS unsigned*)(lds + (bufoff) + ldsw + _i * 8192), 16, 0, 0); } while (0)
; #define PG8_LDB(dst, b, h) do { _Pragma("unroll") for (int n = 0; n < 2; ++n) _Pragma("unroll") for (int k = 0; k < 2; ++k) dst[n][k] = *(const LAS bf16x8*)(lds + PG8_SB(b, h) + boff + n * 2048 + k * 1024); } while (0)
; #define PG8_MMA(ai, bj, At, Bt) do { __builtin_amdgcn_s_setprio(1); _Pragma("unroll") for (int m = 0; m < 4; ++m) _Pragma("unroll") for (int n = 0; n < 2; ++n) _Pragma("unroll") for (int k = 0; k < 2; ++k) \
;         acc[ai][bj][m][n] = __builtin_amdgcn_mfma_f32_16x16x32_bf16(Bt[n][k], At[m][k], acc[ai][bj][m][n], 0, 0, 0); __builtin_amdgcn_s_setprio(0); } while (0)
; #define PG8_WAIT_L(n) asm volatile("s_waitcnt lgkmcnt(" #n ")" ::: "memory")
; #define PG8_BAR __builtin_amdgcn_s_barrier()
; template <class Epi>
; DI void gemm_phase(LAS unsigned char* lds, int wid, int K, int lda, int ldb, bool bperm, const Sched3& S, const Epi& E) {
;     ...
;             PG8_LDB(B1, 1, 1); PG8_STAGE(PG8_SB(1, 0), b3, voffB);
;             PG8_BAR; PG8_WAIT_L(0); PG8_MMA(0, 1, At, B1); PG8_BAR;
	s_add_i32 m0, s41, 0x1f80
	s_nop 0
	global_load_lds_dwordx4 v154, s[38:39] offset:128
	s_barrier
	s_waitcnt lgkmcnt(0)
	s_setprio 1
	s_waitcnt lgkmcnt(0)
	v_mfma_f32_16x16x32_bf16 v[116:119], v[196:199], v[144:147], v[116:119]
	v_mfma_f32_16x16x32_bf16 v[112:115], v[204:207], v[144:147], v[112:115]
	v_mfma_f32_16x16x32_bf16 v[100:103], v[196:199], v[162:165], v[100:103]
	v_mfma_f32_16x16x32_bf16 v[96:99], v[204:207], v[162:165], v[96:99]
	v_mfma_f32_16x16x32_bf16 v[84:87], v[196:199], v[170:173], v[84:87]
	v_mfma_f32_16x16x32_bf16 v[80:83], v[204:207], v[170:173], v[80:83]
	v_mfma_f32_16x16x32_bf16 v[68:71], v[196:199], v[188:191], v[68:71]
	v_mfma_f32_16x16x32_bf16 v[64:67], v[204:207], v[188:191], v[64:67]
	v_mfma_f32_16x16x32_bf16 v[116:119], v[200:203], v[148:151], v[116:119]
	v_mfma_f32_16x16x32_bf16 v[112:115], v[208:211], v[148:151], v[112:115]
	v_mfma_f32_16x16x32_bf16 v[100:103], v[200:203], v[166:169], v[100:103]
	v_mfma_f32_16x16x32_bf16 v[96:99], v[208:211], v[166:169], v[96:99]
	v_mfma_f32_16x16x32_bf16 v[84:87], v[200:203], v[174:177], v[84:87]
	v_mfma_f32_16x16x32_bf16 v[80:83], v[208:211], v[174:177], v[80:83]
	v_mfma_f32_16x16x32_bf16 v[68:71], v[200:203], v[192:195], v[68:71]
	v_mfma_f32_16x16x32_bf16 v[64:67], v[208:211], v[192:195], v[64:67]
	s_setprio 0
	s_sub_i32 m0, s53, 0x80

; #define PG8_STAGE(bufoff, gbase, voff) do { _Pragma("unroll") for (int _i = 0; _i < 2; ++_i) \
;         __builtin_amdgcn_global_load_lds((const unsigned*)((const char*)(gbase) + (voff)[_i]), (LAS unsigned*)(lds + (bufoff) + ldsw + _i * 8192), 16, 0, 0); } while (0)
; #define PG8_LDA(dst, b, h) do { _Pragma("unroll") for (int m = 0; m < 4; ++m) _Pragma("unroll") for (int k = 0; k < 2; ++k) dst[m][k] = *(const LAS bf16x8*)(lds + PG8_SA(b, h) + aoff + m * 2048 + k * 1024); } while (0)
; #define PG8_MMA(ai, bj, At, Bt) do { __builtin_amdgcn_s_setprio(1); _Pragma("unroll") for (int m = 0; m < 4; ++m) _Pragma("unroll") for (int n = 0; n < 2; ++n) _Pragma("unroll") for (int k = 0; k < 2; ++k) \
;         acc[ai][bj][m][n] = __builtin_amdgcn_mfma_f32_16x16x32_bf16(Bt[n][k], At[m][k], acc[ai][bj][m][n], 0, 0, 0); __builtin_amdgcn_s_setprio(0); } while (0)
; #define PG8_WAIT_L(n) asm volatile("s_waitcnt lgkmcnt(" #n ")" ::: "memory")
; #define PG8_BAR __builtin_amdgcn_s_barrier()
; template <class Epi>
; DI void gemm_phase(LAS unsigned char* lds, int wid, int K, int lda, int ldb, bool bperm, const Sched3& S, const Epi& E) {
;     ...
;             PG8_BAR; PG8_WAIT_L(0); PG8_MMA(0, 1, At, B1); PG8_BAR;
;             PG8_LDA(At, 1, 1); PG8_STAGE(PG8_SA(1, 0), a3, voffA);
	s_barrier
	ds_read_b128 v[144:147], v186 offset:49152
	ds_read_b128 v[148:151], v186 offset:50176
	ds_read_b128 v[162:165], v186 offset:51200
	ds_read_b128 v[166:169], v186 offset:52224
	ds_read_b128 v[170:173], v186 offset:53248
	ds_read_b128 v[174:177], v186 offset:54272
	ds_read_b128 v[188:191], v186 offset:55296
	ds_read_b128 v[192:195], v186 offset:56320
	global_load_lds_dwordx4 v152, s[100:101] offset:128

; #define PG8_MMA(ai, bj, At, Bt) do { __builtin_amdgcn_s_setprio(1); _Pragma("unroll") for (int m = 0; m < 4; ++m) _Pragma("unroll") for (int n = 0; n < 2; ++n) _Pragma("unroll") for (int k = 0; k < 2; ++k) \
;         acc[ai][bj][m][n] = __builtin_amdgcn_mfma_f32_16x16x32_bf16(Bt[n][k], At[m][k], acc[ai][bj][m][n], 0, 0, 0); __builtin_amdgcn_s_setprio(0); } while (0)
; #define PG8_WAIT_L(n) asm volatile("s_waitcnt lgkmcnt(" #n ")" ::: "memory")
; #define PG8_BAR __builtin_amdgcn_s_barrier()
; #define PG8_SCHED __builtin_amdgcn_sched_barrier(0)
; template <class Epi>
; DI void gemm_phase(LAS unsigned char* lds, int wid, int K, int lda, int ldb, bool bperm, const Sched3& S, const Epi& E) {
;     ...
;             PG8_BAR; PG8_WAIT_L(0); if (full) PG8_MMA(1, 0, At, B0); PG8_BAR; PG8_SCHED;
	s_sub_i32 m0, s54, 0x80
	s_nop 0
	global_load_lds_dwordx4 v154, s[100:101] offset:128
	s_barrier
	s_waitcnt lgkmcnt(0)
	s_setprio 1
	s_waitcnt lgkmcnt(0)
	v_mfma_f32_16x16x32_bf16 v[60:63], v[128:131], v[144:147], v[60:63]
	v_mfma_f32_16x16x32_bf16 v[56:59], v[136:139], v[144:147], v[56:59]
	v_mfma_f32_16x16x32_bf16 v[44:47], v[128:131], v[162:165], v[44:47]
	v_mfma_f32_16x16x32_bf16 v[40:43], v[136:139], v[162:165], v[40:43]
	v_mfma_f32_16x16x32_bf16 v[28:31], v[128:131], v[170:173], v[28:31]
	v_mfma_f32_16x16x32_bf16 v[24:27], v[136:139], v[170:173], v[24:27]
	v_mfma_f32_16x16x32_bf16 v[12:15], v[128:131], v[188:191], v[12:15]
	v_mfma_f32_16x16x32_bf16 v[8:11], v[136:139], v[188:191], v[8:11]
	v_mfma_f32_16x16x32_bf16 v[60:63], v[132:135], v[148:151], v[60:63]
	v_mfma_f32_16x16x32_bf16 v[56:59], v[140:143], v[148:151], v[56:59]
	v_mfma_f32_16x16x32_bf16 v[44:47], v[132:135], v[166:169], v[44:47]
	v_mfma_f32_16x16x32_bf16 v[40:43], v[140:143], v[166:169], v[40:43]
	v_mfma_f32_16x16x32_bf16 v[28:31], v[132:135], v[174:177], v[28:31]
	v_mfma_f32_16x16x32_bf16 v[24:27], v[140:143], v[174:177], v[24:27]
	v_mfma_f32_16x16x32_bf16 v[12:15], v[132:135], v[192:195], v[12:15]
	v_mfma_f32_16x16x32_bf16 v[8:11], v[140:143], v[192:195], v[8:11]
	s_setprio 0
	s_barrier
	s_add_u32 s38, s38, 0x80080
	s_addc_u32 s39, s39, 0
	s_add_i32 s40, s40, s47

; #define PG8_STAGE(bufoff, gbase, voff) do { _Pragma("unroll") for (int _i = 0; _i < 2; ++_i) \
;         __builtin_amdgcn_global_load_lds((const unsigned*)((const char*)(gbase) + (voff)[_i]), (LAS unsigned*)(lds + (bufoff) + ldsw + _i * 8192), 16, 0, 0); } while (0)
; template <class Epi>
; DI void gemm_phase(LAS unsigned char* lds, int wid, int K, int lda, int ldb, bool bperm, const Sched3& S, const Epi& E) {
;     ...
;             PG8_STAGE(PG8_SB(1, 1), b3 + hstepB, voffB);
	s_mov_b32 m0, s40
	s_nop 0
	global_load_lds_dwordx4 v152, s[38:39]

; #define PG8_STAGE(bufoff, gbase, voff) do { _Pragma("unroll") for (int _i = 0; _i < 2; ++_i) \
;         __builtin_amdgcn_global_load_lds((const unsigned*)((const char*)(gbase) + (voff)[_i]), (LAS unsigned*)(lds + (bufoff) + ldsw + _i * 8192), 16, 0, 0); } while (0)
; #define PG8_MMA(ai, bj, At, Bt) do { __builtin_amdgcn_s_setprio(1); _Pragma("unroll") for (int m = 0; m < 4; ++m) _Pragma("unroll") for (int n = 0; n < 2; ++n) _Pragma("unroll") for (int k = 0; k < 2; ++k) \
;         acc[ai][bj][m][n] = __builtin_amdgcn_mfma_f32_16x16x32_bf16(Bt[n][k], At[m][k], acc[ai][bj][m][n], 0, 0, 0); __builtin_amdgcn_s_setprio(0); } while (0)
; #define PG8_WAIT_V(n) asm volatile("s_waitcnt vmcnt(" #n ")" ::: "memory")
; #define PG8_BAR __builtin_amdgcn_s_barrier()
; template <class Epi>
; DI void gemm_phase(LAS unsigned char* lds, int wid, int K, int lda, int ldb, bool bperm, const Sched3& S, const Epi& E) {
;     ...
;             PG8_STAGE(PG8_SB(1, 1), b3 + hstepB, voffB);
;             PG8_WAIT_V(6); PG8_BAR; if (full) PG8_MMA(1, 1, At, B1); PG8_BAR;
	s_add_i32 m0, s40, 0x2000
	s_nop 0
	global_load_lds_dwordx4 v154, s[38:39]
	s_waitcnt vmcnt(6)
	s_barrier
	s_setprio 1
	v_mfma_f32_16x16x32_bf16 v[52:55], v[196:199], v[144:147], v[52:55]
	v_mfma_f32_16x16x32_bf16 v[48:51], v[204:207], v[144:147], v[48:51]
	v_mfma_f32_16x16x32_bf16 v[36:39], v[196:199], v[162:165], v[36:39]
	v_mfma_f32_16x16x32_bf16 v[32:35], v[204:207], v[162:165], v[32:35]
	v_mfma_f32_16x16x32_bf16 v[20:23], v[196:199], v[170:173], v[20:23]
	v_mfma_f32_16x16x32_bf16 v[16:19], v[204:207], v[170:173], v[16:19]
	v_mfma_f32_16x16x32_bf16 v[4:7], v[196:199], v[188:191], v[4:7]
	v_mfma_f32_16x16x32_bf16 v[0:3], v[204:207], v[188:191], v[0:3]
	v_mfma_f32_16x16x32_bf16 v[52:55], v[200:203], v[148:151], v[52:55]
	v_mfma_f32_16x16x32_bf16 v[48:51], v[208:211], v[148:151], v[48:51]
	v_mfma_f32_16x16x32_bf16 v[36:39], v[200:203], v[166:169], v[36:39]
	v_mfma_f32_16x16x32_bf16 v[32:35], v[208:211], v[166:169], v[32:35]
	v_mfma_f32_16x16x32_bf16 v[20:23], v[200:203], v[174:177], v[20:23]
	v_mfma_f32_16x16x32_bf16 v[16:19], v[208:211], v[174:177], v[16:19]
	v_mfma_f32_16x16x32_bf16 v[4:7], v[200:203], v[192:195], v[4:7]
	v_mfma_f32_16x16x32_bf16 v[0:3], v[208:211], v[192:195], v[0:3]
	s_setprio 0
	s_add_i32 s27, s27, 2
	s_add_u32 s36, s36, 0x100
	s_addc_u32 s37, s37, 0
	s_add_u32 s19, s19, 0x100
	s_addc_u32 s21, s21, 0
	s_cmp_gt_u32 s27, 29
	s_cbranch_scc1 .Lkrot_6_exit

; #define PG8_STAGE(bufoff, gbase, voff) do { _Pragma("unroll") for (int _i = 0; _i < 2; ++_i) \
;         __builtin_amdgcn_global_load_lds((const unsigned*)((const char*)(gbase) + (voff)[_i]), (LAS unsigned*)(lds + (bufoff) + ldsw + _i * 8192), 16, 0, 0); } while (0)
; #define PG8_LDA(dst, b, h) do { _Pragma("unroll") for (int m = 0; m < 4; ++m) _Pragma("unroll") for (int k = 0; k < 2; ++k) dst[m][k] = *(const LAS bf16x8*)(lds + PG8_SA(b, h) + aoff + m * 2048 + k * 1024); } while (0)
; #define PG8_LDB(dst, b, h) do { _Pragma("unroll") for (int n = 0; n < 2; ++n) _Pragma("unroll") for (int k = 0; k < 2; ++k) dst[n][k] = *(const LAS bf16x8*)(lds + PG8_SB(b, h) + boff + n * 2048 + k * 1024); } while (0)
; #define PG8_SCHED __builtin_amdgcn_sched_barrier(0)
; template <class Epi>
; DI void gemm_phase(LAS unsigned char* lds, int wid, int K, int lda, int ldb, bool bperm, const Sched3& S, const Epi& E) {
;     ...
;             const bool last = (t == nt - 2);
;             const char* a1 = cA + (size_t)(t + 1) * kstep;
;             const char* a2 = last ? nA : cA + (size_t)(t + 2) * kstep; const char* b2 = last ? nB : cB + (size_t)(t + 2) * kstep;
;             const char* a3 = a2 + kstep; const char* b3 = b2 + kstep; const size_t h2 = last ? nhA : hA;
;             PG8_LDB(B0, 0, 0); PG8_SCHED; PG8_LDA(At, 0, 0); PG8_STAGE(PG8_SA(1, 1), a1 + hA, voffA);
.LBB0_1176:
	ds_read_b128 v[128:131], v185
	ds_read_b128 v[132:135], v185 offset:1024
	ds_read_b128 v[136:139], v185 offset:2048
	ds_read_b128 v[140:143], v185 offset:3072
	s_add_u32 s38, s36, 0xfff80080
	s_addc_u32 s39, s37, -1
	s_cmp_eq_u32 s27, 28
	s_cselect_b32 s41, s29, s39
	s_cselect_b32 s40, s28, s38
	s_cselect_b32 s39, s31, s21
	s_cselect_b32 s38, s30, s19

; #define PG8_STAGE(bufoff, gbase, voff) do { _Pragma("unroll") for (int _i = 0; _i < 2; ++_i) \
;         __builtin_amdgcn_global_load_lds((const unsigned*)((const char*)(gbase) + (voff)[_i]), (LAS unsigned*)(lds + (bufoff) + ldsw + _i * 8192), 16, 0, 0); } while (0)
; #define PG8_LDA(dst, b, h) do { _Pragma("unroll") for (int m = 0; m < 4; ++m) _Pragma("unroll") for (int k = 0; k < 2; ++k) dst[m][k] = *(const LAS bf16x8*)(lds + PG8_SA(b, h) + aoff + m * 2048 + k * 1024); } while (0)
; #define PG8_LDB(dst, b, h) do { _Pragma("unroll") for (int n = 0; n < 2; ++n) _Pragma("unroll") for (int k = 0; k < 2; ++k) dst[n][k] = *(const LAS bf16x8*)(lds + PG8_SB(b, h) + boff + n * 2048 + k * 1024); } while (0)
; #define PG8_SCHED __builtin_amdgcn_sched_barrier(0)
; template <class Epi>
; DI void gemm_phase(LAS unsigned char* lds, int wid, int K, int lda, int ldb, bool bperm, const Sched3& S, const Epi& E) {
;     ...
;             PG8_LDB(B0, 0, 0); PG8_SCHED; PG8_LDA(At, 0, 0); PG8_STAGE(PG8_SA(1, 1), a1 + hA, voffA);
	s_add_i32 m0, s48, 0xc000
	ds_read_b128 v[144:147], v186
	ds_read_b128 v[148:151], v186 offset:1024
	ds_read_b128 v[162:165], v186 offset:2048
	ds_read_b128 v[166:169], v186 offset:3072
	ds_read_b128 v[170:173], v186 offset:4096
	ds_read_b128 v[174:177], v186 offset:5120
	ds_read_b128 v[188:191], v186 offset:6144
	ds_read_b128 v[192:195], v186 offset:7168
	global_load_lds_dwordx4 v156, s[36:37]

; #define PG8_STAGE(bufoff, gbase, voff) do { _Pragma("unroll") for (int _i = 0; _i < 2; ++_i) \
;         __builtin_amdgcn_global_load_lds((const unsigned*)((const char*)(gbase) + (voff)[_i]), (LAS unsigned*)(lds + (bufoff) + ldsw + _i * 8192), 16, 0, 0); } while (0)
; #define PG8_LDA(dst, b, h) do { _Pragma("unroll") for (int m = 0; m < 4; ++m) _Pragma("unroll") for (int k = 0; k < 2; ++k) dst[m][k] = *(const LAS bf16x8*)(lds + PG8_SA(b, h) + aoff + m * 2048 + k * 1024); } while (0)
; #define PG8_LDB(dst, b, h) do { _Pragma("unroll") for (int n = 0; n < 2; ++n) _Pragma("unroll") for (int k = 0; k < 2; ++k) dst[n][k] = *(const LAS bf16x8*)(lds + PG8_SB(b, h) + boff + n * 2048 + k * 1024); } while (0)
; #define PG8_MMA(ai, bj, At, Bt) do { __builtin_amdgcn_s_setprio(1); _Pragma("unroll") for (int m = 0; m < 4; ++m) _Pragma("unroll") for (int n = 0; n < 2; ++n) _Pragma("unroll") for (int k = 0; k < 2; ++k) \
;         acc[ai][bj][m][n] = __builtin_amdgcn_mfma_f32_16x16x32_bf16(Bt[n][k], At[m][k], acc[ai][bj][m][n], 0, 0, 0); __builtin_amdgcn_s_setprio(0); } while (0)
; #define PG8_WAIT_L(n) asm volatile("s_waitcnt lgkmcnt(" #n ")" ::: "memory")
; #define PG8_BAR __builtin_amdgcn_s_barrier()
; #define PG8_SCHED __builtin_amdgcn_sched_barrier(0)
; template <class Epi>
; DI void gemm_phase(LAS unsigned char* lds, int wid, int K, int lda, int ldb, bool bperm, const Sched3& S, const Epi& E) {
;     ...
;             PG8_LDB(B0, 0, 0); PG8_SCHED; PG8_LDA(At, 0, 0); PG8_STAGE(PG8_SA(1, 1), a1 + hA, voffA);
;             PG8_WAIT_L(8); PG8_BAR; PG8_WAIT_L(0); PG8_MMA(0, 0, At, B0); PG8_BAR; PG8_SCHED;
	s_add_i32 m0, s48, 0xe000
	s_nop 0
	global_load_lds_dwordx4 v158, s[36:37]
	s_waitcnt lgkmcnt(8)
	s_barrier
	s_waitcnt lgkmcnt(0)
	s_setprio 1
	s_waitcnt lgkmcnt(0)
	v_mfma_f32_16x16x32_bf16 v[124:127], v[128:131], v[144:147], v[124:127]
	v_mfma_f32_16x16x32_bf16 v[120:123], v[136:139], v[144:147], v[120:123]
	v_mfma_f32_16x16x32_bf16 v[108:111], v[128:131], v[162:165], v[108:111]
	v_mfma_f32_16x16x32_bf16 v[104:107], v[136:139], v[162:165], v[104:107]
	v_mfma_f32_16x16x32_bf16 v[92:95], v[128:131], v[170:173], v[92:95]
	v_mfma_f32_16x16x32_bf16 v[88:91], v[136:139], v[170:173], v[88:91]
	v_mfma_f32_16x16x32_bf16 v[76:79], v[128:131], v[188:191], v[76:79]
	v_mfma_f32_16x16x32_bf16 v[72:75], v[136:139], v[188:191], v[72:75]
	v_mfma_f32_16x16x32_bf16 v[124:127], v[132:135], v[148:151], v[124:127]
	v_mfma_f32_16x16x32_bf16 v[120:123], v[140:143], v[148:151], v[120:123]
	v_mfma_f32_16x16x32_bf16 v[108:111], v[132:135], v[166:169], v[108:111]
	v_mfma_f32_16x16x32_bf16 v[104:107], v[140:143], v[166:169], v[104:107]
	v_mfma_f32_16x16x32_bf16 v[92:95], v[132:135], v[174:177], v[92:95]
	v_mfma_f32_16x16x32_bf16 v[88:91], v[140:143], v[174:177], v[88:91]
	v_mfma_f32_16x16x32_bf16 v[76:79], v[132:135], v[192:195], v[76:79]
	v_mfma_f32_16x16x32_bf16 v[72:75], v[140:143], v[192:195], v[72:75]
	s_setprio 0
	s_barrier
	s_add_i32 s61, s57, s47

; #define PG8_STAGE(bufoff, gbase, voff) do { _Pragma("unroll") for (int _i = 0; _i < 2; ++_i) \
;         __builtin_amdgcn_global_load_lds((const unsigned*)((const char*)(gbase) + (voff)[_i]), (LAS unsigned*)(lds + (bufoff) + ldsw + _i * 8192), 16, 0, 0); } while (0)
; #define PG8_LDB(dst, b, h) do { _Pragma("unroll") for (int n = 0; n < 2; ++n) _Pragma("unroll") for (int k = 0; k < 2; ++k) dst[n][k] = *(const LAS bf16x8*)(lds + PG8_SB(b, h) + boff + n * 2048 + k * 1024); } while (0)
; template <class Epi>
; DI void gemm_phase(LAS unsigned char* lds, int wid, int K, int lda, int ldb, bool bperm, const Sched3& S, const Epi& E) {
;     ...
;             PG8_LDB(B1, 0, 1); PG8_STAGE(PG8_SB(0, 0), b2, voffB);
	s_mov_b32 m0, s61
	ds_read_b128 v[196:199], v187
	ds_read_b128 v[200:203], v187 offset:1024
	ds_read_b128 v[204:207], v187 offset:2048
	ds_read_b128 v[208:211], v187 offset:3072
	global_load_lds_dwordx4 v152, s[38:39]

; #define PG8_STAGE(bufoff, gbase, voff) do { _Pragma("unroll") for (int _i = 0; _i < 2; ++_i) \
;         __builtin_amdgcn_global_load_lds((const unsigned*)((const char*)(gbase) + (voff)[_i]), (LAS unsigned*)(lds + (bufoff) + ldsw + _i * 8192), 16, 0, 0); } while (0)
; #define PG8_LDA(dst, b, h) do { _Pragma("unroll") for (int m = 0; m < 4; ++m) _Pragma("unroll") for (int k = 0; k < 2; ++k) dst[m][k] = *(const LAS bf16x8*)(lds + PG8_SA(b, h) + aoff + m * 2048 + k * 1024); } while (0)
; #define PG8_LDB(dst, b, h) do { _Pragma("unroll") for (int n = 0; n < 2; ++n) _Pragma("unroll") for (int k = 0; k < 2; ++k) dst[n][k] = *(const LAS bf16x8*)(lds + PG8_SB(b, h) + boff + n * 2048 + k * 1024); } while (0)
; #define PG8_MMA(ai, bj, At, Bt) do { __builtin_amdgcn_s_setprio(1); _Pragma("unroll") for (int m = 0; m < 4; ++m) _Pragma("unroll") for (int n = 0; n < 2; ++n) _Pragma("unroll") for (int k = 0; k < 2; ++k) \
;         acc[ai][bj][m][n] = __builtin_amdgcn_mfma_f32_16x16x32_bf16(Bt[n][k], At[m][k], acc[ai][bj][m][n], 0, 0, 0); __builtin_amdgcn_s_setprio(0); } while (0)
; #define PG8_WAIT_L(n) asm volatile("s_waitcnt lgkmcnt(" #n ")" ::: "memory")
; #define PG8_BAR __builtin_amdgcn_s_barrier()
; #define PG8_SCHED __builtin_amdgcn_sched_barrier(0)
; template <class Epi>
; DI void gemm_phase(LAS unsigned char* lds, int wid, int K, int lda, int ldb, bool bperm, const Sched3& S, const Epi& E) {
;     ...
;             PG8_LDB(B1, 0, 1); PG8_STAGE(PG8_SB(0, 0), b2, voffB);
;             PG8_BAR; PG8_WAIT_L(0); PG8_MMA(0, 1, At, B1); PG8_BAR;
;             PG8_LDA(At, 0, 1); PG8_STAGE(PG8_SA(0, 0), a2, voffA);
;             PG8_BAR; PG8_WAIT_L(0); if (full) PG8_MMA(1, 0, At, B0); PG8_BAR; PG8_SCHED;
	s_add_i32 m0, s61, 0x2000
	s_nop 0
	global_load_lds_dwordx4 v154, s[38:39]
	s_barrier
	s_waitcnt lgkmcnt(0)
	s_setprio 1
	s_waitcnt lgkmcnt(0)
	v_mfma_f32_16x16x32_bf16 v[116:119], v[196:199], v[144:147], v[116:119]
	v_mfma_f32_16x16x32_bf16 v[112:115], v[204:207], v[144:147], v[112:115]
	v_mfma_f32_16x16x32_bf16 v[100:103], v[196:199], v[162:165], v[100:103]
	v_mfma_f32_16x16x32_bf16 v[96:99], v[204:207], v[162:165], v[96:99]
	v_mfma_f32_16x16x32_bf16 v[84:87], v[196:199], v[170:173], v[84:87]
	v_mfma_f32_16x16x32_bf16 v[80:83], v[204:207], v[170:173], v[80:83]
	v_mfma_f32_16x16x32_bf16 v[68:71], v[196:199], v[188:191], v[68:71]
	v_mfma_f32_16x16x32_bf16 v[64:67], v[204:207], v[188:191], v[64:67]
	v_mfma_f32_16x16x32_bf16 v[116:119], v[200:203], v[148:151], v[116:119]
	v_mfma_f32_16x16x32_bf16 v[112:115], v[208:211], v[148:151], v[112:115]
	v_mfma_f32_16x16x32_bf16 v[100:103], v[200:203], v[166:169], v[100:103]
	v_mfma_f32_16x16x32_bf16 v[96:99], v[208:211], v[166:169], v[96:99]
	v_mfma_f32_16x16x32_bf16 v[84:87], v[200:203], v[174:177], v[84:87]
	v_mfma_f32_16x16x32_bf16 v[80:83], v[208:211], v[174:177], v[80:83]
	v_mfma_f32_16x16x32_bf16 v[68:71], v[200:203], v[192:195], v[68:71]
	v_mfma_f32_16x16x32_bf16 v[64:67], v[208:211], v[192:195], v[64:67]
	s_setprio 0
	s_mov_b32 m0, s48
	s_mov_b64 s[100:101], s[40:41]
	s_barrier
	ds_read_b128 v[144:147], v186 offset:16384
	ds_read_b128 v[148:151], v186 offset:17408
	ds_read_b128 v[162:165], v186 offset:18432
	ds_read_b128 v[166:169], v186 offset:19456
	ds_read_b128 v[170:173], v186 offset:20480
	ds_read_b128 v[174:177], v186 offset:21504
	ds_read_b128 v[188:191], v186 offset:22528
	ds_read_b128 v[192:195], v186 offset:23552
	global_load_lds_dwordx4 v152, s[40:41]
	s_mov_b64 s[100:101], s[40:41]
	s_mov_b32 m0, s49
	s_nop 0
	global_load_lds_dwordx4 v154, s[40:41]
	s_barrier
	s_waitcnt lgkmcnt(0)
	s_setprio 1
	s_waitcnt lgkmcnt(0)
	v_mfma_f32_16x16x32_bf16 v[60:63], v[128:131], v[144:147], v[60:63]
	v_mfma_f32_16x16x32_bf16 v[56:59], v[136:139], v[144:147], v[56:59]
	v_mfma_f32_16x16x32_bf16 v[44:47], v[128:131], v[162:165], v[44:47]
	v_mfma_f32_16x16x32_bf16 v[40:43], v[136:139], v[162:165], v[40:43]
	v_mfma_f32_16x16x32_bf16 v[28:31], v[128:131], v[170:173], v[28:31]
	v_mfma_f32_16x16x32_bf16 v[24:27], v[136:139], v[170:173], v[24:27]
	v_mfma_f32_16x16x32_bf16 v[12:15], v[128:131], v[188:191], v[12:15]
	v_mfma_f32_16x16x32_bf16 v[8:11], v[136:139], v[188:191], v[8:11]
	v_mfma_f32_16x16x32_bf16 v[60:63], v[132:135], v[148:151], v[60:63]
	v_mfma_f32_16x16x32_bf16 v[56:59], v[140:143], v[148:151], v[56:59]
	v_mfma_f32_16x16x32_bf16 v[44:47], v[132:135], v[166:169], v[44:47]
	v_mfma_f32_16x16x32_bf16 v[40:43], v[140:143], v[166:169], v[40:43]
	v_mfma_f32_16x16x32_bf16 v[28:31], v[132:135], v[174:177], v[28:31]
	v_mfma_f32_16x16x32_bf16 v[24:27], v[140:143], v[174:177], v[24:27]
	v_mfma_f32_16x16x32_bf16 v[12:15], v[132:135], v[192:195], v[12:15]
	v_mfma_f32_16x16x32_bf16 v[8:11], v[140:143], v[192:195], v[8:11]
	s_setprio 0
	s_barrier
	s_add_u32 s62, s38, 0x80000
	s_addc_u32 s63, s39, 0
	s_add_i32 s61, s58, s47

; #define PG8_STAGE(bufoff, gbase, voff) do { _Pragma("unroll") for (int _i = 0; _i < 2; ++_i) \
;         __builtin_amdgcn_global_load_lds((const unsigned*)((const char*)(gbase) + (voff)[_i]), (LAS unsigned*)(lds + (bufoff) + ldsw + _i * 8192), 16, 0, 0); } while (0)
; template <class Epi>
; DI void gemm_phase(LAS unsigned char* lds, int wid, int K, int lda, int ldb, bool bperm, const Sched3& S, const Epi& E) {
;     ...
;             PG8_STAGE(PG8_SB(0, 1), b2 + hstepB, voffB);
	s_mov_b32 m0, s61
	s_nop 0
	global_load_lds_dwordx4 v152, s[62:63]

; #define PG8_STAGE(bufoff, gbase, voff) do { _Pragma("unroll") for (int _i = 0; _i < 2; ++_i) \
;         __builtin_amdgcn_global_load_lds((const unsigned*)((const char*)(gbase) + (voff)[_i]), (LAS unsigned*)(lds + (bufoff) + ldsw + _i * 8192), 16, 0, 0); } while (0)
; #define PG8_LDA(dst, b, h) do { _Pragma("unroll") for (int m = 0; m < 4; ++m) _Pragma("unroll") for (int k = 0; k < 2; ++k) dst[m][k] = *(const LAS bf16x8*)(lds + PG8_SA(b, h) + aoff + m * 2048 + k * 1024); } while (0)
; #define PG8_LDB(dst, b, h) do { _Pragma("unroll") for (int n = 0; n < 2; ++n) _Pragma("unroll") for (int k = 0; k < 2; ++k) dst[n][k] = *(const LAS bf16x8*)(lds + PG8_SB(b, h) + boff + n * 2048 + k * 1024); } while (0)
; #define PG8_MMA(ai, bj, At, Bt) do { __builtin_amdgcn_s_setprio(1); _Pragma("unroll") for (int m = 0; m < 4; ++m) _Pragma("unroll") for (int n = 0; n < 2; ++n) _Pragma("unroll") for (int k = 0; k < 2; ++k) \
;         acc[ai][bj][m][n] = __builtin_amdgcn_mfma_f32_16x16x32_bf16(Bt[n][k], At[m][k], acc[ai][bj][m][n], 0, 0, 0); __builtin_amdgcn_s_setprio(0); } while (0)
; #define PG8_WAIT_V(n) asm volatile("s_waitcnt vmcnt(" #n ")" ::: "memory")
; #define PG8_BAR __builtin_amdgcn_s_barrier()
; #define PG8_SCHED __builtin_amdgcn_sched_barrier(0)
; template <class Epi>
; DI void gemm_phase(LAS unsigned char* lds, int wid, int K, int lda, int ldb, bool bperm, const Sched3& S, const Epi& E) {
;     ...
;             PG8_STAGE(PG8_SB(0, 1), b2 + hstepB, voffB);
;             PG8_WAIT_V(6); PG8_BAR; if (full) PG8_MMA(1, 1, At, B1); PG8_BAR;
;             PG8_LDB(B0, 1, 0); PG8_SCHED; PG8_LDA(At, 1, 0); PG8_STAGE(PG8_SA(0, 1), a2 + h2, voffA);
	s_add_i32 m0, s61, 0x2000
	s_nop 0
	global_load_lds_dwordx4 v154, s[62:63]
	s_waitcnt vmcnt(6)
	s_barrier
	s_setprio 1
	v_mfma_f32_16x16x32_bf16 v[52:55], v[196:199], v[144:147], v[52:55]
	v_mfma_f32_16x16x32_bf16 v[48:51], v[204:207], v[144:147], v[48:51]
	v_mfma_f32_16x16x32_bf16 v[36:39], v[196:199], v[162:165], v[36:39]
	v_mfma_f32_16x16x32_bf16 v[32:35], v[204:207], v[162:165], v[32:35]
	v_mfma_f32_16x16x32_bf16 v[20:23], v[196:199], v[170:173], v[20:23]
	v_mfma_f32_16x16x32_bf16 v[16:19], v[204:207], v[170:173], v[16:19]
	v_mfma_f32_16x16x32_bf16 v[4:7], v[196:199], v[188:191], v[4:7]
	v_mfma_f32_16x16x32_bf16 v[0:3], v[204:207], v[188:191], v[0:3]
	v_mfma_f32_16x16x32_bf16 v[52:55], v[200:203], v[148:151], v[52:55]
	v_mfma_f32_16x16x32_bf16 v[48:51], v[208:211], v[148:151], v[48:51]
	v_mfma_f32_16x16x32_bf16 v[36:39], v[200:203], v[166:169], v[36:39]
	v_mfma_f32_16x16x32_bf16 v[32:35], v[208:211], v[166:169], v[32:35]
	v_mfma_f32_16x16x32_bf16 v[20:23], v[200:203], v[174:177], v[20:23]
	v_mfma_f32_16x16x32_bf16 v[16:19], v[208:211], v[174:177], v[16:19]
	v_mfma_f32_16x16x32_bf16 v[4:7], v[200:203], v[192:195], v[4:7]
	v_mfma_f32_16x16x32_bf16 v[0:3], v[208:211], v[192:195], v[0:3]
	s_setprio 0
	s_add_i32 s61, 0, 0x18000
	v_add_u32_e32 v140, s61, v181
	s_barrier
	ds_read_b128 v[128:131], v140
	ds_read_b128 v[132:135], v140 offset:1024
	ds_read_b128 v[136:139], v140 offset:2048
	ds_read_b128 v[140:143], v140 offset:3072
	s_add_u32 s40, s40, 0x80000
	s_addc_u32 s41, s41, 0
	s_mov_b32 m0, s50

; #define PG8_STAGE(bufoff, gbase, voff) do { _Pragma("unroll") for (int _i = 0; _i < 2; ++_i) \
;         __builtin_amdgcn_global_load_lds((const unsigned*)((const char*)(gbase) + (voff)[_i]), (LAS unsigned*)(lds + (bufoff) + ldsw + _i * 8192), 16, 0, 0); } while (0)
; #define PG8_LDA(dst, b, h) do { _Pragma("unroll") for (int m = 0; m < 4; ++m) _Pragma("unroll") for (int k = 0; k < 2; ++k) dst[m][k] = *(const LAS bf16x8*)(lds + PG8_SA(b, h) + aoff + m * 2048 + k * 1024); } while (0)
; #define PG8_LDB(dst, b, h) do { _Pragma("unroll") for (int n = 0; n < 2; ++n) _Pragma("unroll") for (int k = 0; k < 2; ++k) dst[n][k] = *(const LAS bf16x8*)(lds + PG8_SB(b, h) + boff + n * 2048 + k * 1024); } while (0)
; #define PG8_SCHED __builtin_amdgcn_sched_barrier(0)
; template <class Epi>
; DI void gemm_phase(LAS unsigned char* lds, int wid, int K, int lda, int ldb, bool bperm, const Sched3& S, const Epi& E) {
;     ...
;             PG8_LDB(B0, 1, 0); PG8_SCHED; PG8_LDA(At, 1, 0); PG8_STAGE(PG8_SA(0, 1), a2 + h2, voffA);
	ds_read_b128 v[144:147], v186 offset:32768
	ds_read_b128 v[148:151], v186 offset:33792
	ds_read_b128 v[162:165], v186 offset:34816
	ds_read_b128 v[166:169], v186 offset:35840
	ds_read_b128 v[170:173], v186 offset:36864
	ds_read_b128 v[174:177], v186 offset:37888
	ds_read_b128 v[188:191], v186 offset:38912
	ds_read_b128 v[192:195], v186 offset:39936
	global_load_lds_dwordx4 v152, s[40:41]

; #define PG8_STAGE(bufoff, gbase, voff) do { _Pragma("unroll") for (int _i = 0; _i < 2; ++_i) \
;         __builtin_amdgcn_global_load_lds((const unsigned*)((const char*)(gbase) + (voff)[_i]), (LAS unsigned*)(lds + (bufoff) + ldsw + _i * 8192), 16, 0, 0); } while (0)
; #define PG8_LDA(dst, b, h) do { _Pragma("unroll") for (int m = 0; m < 4; ++m) _Pragma("unroll") for (int k = 0; k < 2; ++k) dst[m][k] = *(const LAS bf16x8*)(lds + PG8_SA(b, h) + aoff + m * 2048 + k * 1024); } while (0)
; #define PG8_LDB(dst, b, h) do { _Pragma("unroll") for (int n = 0; n < 2; ++n) _Pragma("unroll") for (int k = 0; k < 2; ++k) dst[n][k] = *(const LAS bf16x8*)(lds + PG8_SB(b, h) + boff + n * 2048 + k * 1024); } while (0)
; #define PG8_MMA(ai, bj, At, Bt) do { __builtin_amdgcn_s_setprio(1); _Pragma("unroll") for (int m = 0; m < 4; ++m) _Pragma("unroll") for (int n = 0; n < 2; ++n) _Pragma("unroll") for (int k = 0; k < 2; ++k) \
;         acc[ai][bj][m][n] = __builtin_amdgcn_mfma_f32_16x16x32_bf16(Bt[n][k], At[m][k], acc[ai][bj][m][n], 0, 0, 0); __builtin_amdgcn_s_setprio(0); } while (0)
; #define PG8_WAIT_L(n) asm volatile("s_waitcnt lgkmcnt(" #n ")" ::: "memory")
; #define PG8_BAR __builtin_amdgcn_s_barrier()
; #define PG8_SCHED __builtin_amdgcn_sched_barrier(0)
; template <class Epi>
; DI void gemm_phase(LAS unsigned char* lds, int wid, int K, int lda, int ldb, bool bperm, const Sched3& S, const Epi& E) {
;     ...
;             PG8_LDB(B0, 1, 0); PG8_SCHED; PG8_LDA(At, 1, 0); PG8_STAGE(PG8_SA(0, 1), a2 + h2, voffA);
;             PG8_WAIT_L(8); PG8_BAR; PG8_WAIT_L(0); PG8_MMA(0, 0, At, B0); PG8_BAR; PG8_SCHED;
	s_mov_b32 m0, s51
	s_nop 0
	global_load_lds_dwordx4 v154, s[40:41]
	s_waitcnt lgkmcnt(8)
	s_barrier
	s_waitcnt lgkmcnt(0)
	s_setprio 1
	s_waitcnt lgkmcnt(0)
	v_mfma_f32_16x16x32_bf16 v[124:127], v[128:131], v[144:147], v[124:127]
	v_mfma_f32_16x16x32_bf16 v[120:123], v[136:139], v[144:147], v[120:123]
	v_mfma_f32_16x16x32_bf16 v[108:111], v[128:131], v[162:165], v[108:111]
	v_mfma_f32_16x16x32_bf16 v[104:107], v[136:139], v[162:165], v[104:107]
	v_mfma_f32_16x16x32_bf16 v[92:95], v[128:131], v[170:173], v[92:95]
	v_mfma_f32_16x16x32_bf16 v[88:91], v[136:139], v[170:173], v[88:91]
	v_mfma_f32_16x16x32_bf16 v[76:79], v[128:131], v[188:191], v[76:79]
	v_mfma_f32_16x16x32_bf16 v[72:75], v[136:139], v[188:191], v[72:75]
	v_mfma_f32_16x16x32_bf16 v[124:127], v[132:135], v[148:151], v[124:127]
	v_mfma_f32_16x16x32_bf16 v[120:123], v[140:143], v[148:151], v[120:123]
	v_mfma_f32_16x16x32_bf16 v[108:111], v[132:135], v[166:169], v[108:111]
	v_mfma_f32_16x16x32_bf16 v[104:107], v[140:143], v[166:169], v[104:107]
	v_mfma_f32_16x16x32_bf16 v[92:95], v[132:135], v[174:177], v[92:95]
	v_mfma_f32_16x16x32_bf16 v[88:91], v[140:143], v[174:177], v[88:91]
	v_mfma_f32_16x16x32_bf16 v[76:79], v[132:135], v[192:195], v[76:79]
	v_mfma_f32_16x16x32_bf16 v[72:75], v[140:143], v[192:195], v[72:75]
	s_setprio 0
	s_barrier
	s_add_i32 s40, 0, 0x1c000
	s_add_i32 s41, s61, s47
	v_add_u32_e32 v208, s40, v181

; #define PG8_STAGE(bufoff, gbase, voff) do { _Pragma("unroll") for (int _i = 0; _i < 2; ++_i) \
;         __builtin_amdgcn_global_load_lds((const unsigned*)((const char*)(gbase) + (voff)[_i]), (LAS unsigned*)(lds + (bufoff) + ldsw + _i * 8192), 16, 0, 0); } while (0)
; #define PG8_LDB(dst, b, h) do { _Pragma("unroll") for (int n = 0; n < 2; ++n) _Pragma("unroll") for (int k = 0; k < 2; ++k) dst[n][k] = *(const LAS bf16x8*)(lds + PG8_SB(b, h) + boff + n * 2048 + k * 1024); } while (0)
; template <class Epi>
; DI void gemm_phase(LAS unsigned char* lds, int wid, int K, int lda, int ldb, bool bperm, const Sched3& S, const Epi& E) {
;     ...
;             PG8_LDB(B1, 1, 1); PG8_STAGE(PG8_SB(1, 0), b3, voffB);
	s_sub_i32 m0, s41, 0x80
	ds_read_b128 v[196:199], v208
	ds_read_b128 v[200:203], v208 offset:1024
	ds_read_b128 v[204:207], v208 offset:2048
	ds_read_b128 v[208:211], v208 offset:3072
	global_load_lds_dwordx4 v152, s[38:39] offset:128

; #define PG8_STAGE(bufoff, gbase, voff) do { _Pragma("unroll") for (int _i = 0; _i < 2; ++_i) \
;         __builtin_amdgcn_global_load_lds((const unsigned*)((const char*)(gbase) + (voff)[_i]), (LAS unsigned*)(lds + (bufoff) + ldsw + _i * 8192), 16, 0, 0); } while (0)
; #define PG8_LDB(dst, b, h) do { _Pragma("unroll") for (int n = 0; n < 2; ++n) _Pragma("unroll") for (int k = 0; k < 2; ++k) dst[n][k] = *(const LAS bf16x8*)(lds + PG8_SB(b, h) + boff + n * 2048 + k * 1024); } while (0)
; #define PG8_MMA(ai, bj, At, Bt) do { __builtin_amdgcn_s_setprio(1); _Pragma("unroll") for (int m = 0; m < 4; ++m) _Pragma("unroll") for (int n = 0; n < 2; ++n) _Pragma("unroll") for (int k = 0; k < 2; ++k) \
;         acc[ai][bj][m][n] = __builtin_amdgcn_mfma_f32_16x16x32_bf16(Bt[n][k], At[m][k], acc[ai][bj][m][n], 0, 0, 0); __builtin_amdgcn_s_setprio(0); } while (0)
; #define PG8_WAIT_L(n) asm volatile("s_waitcnt lgkmcnt(" #n ")" ::: "memory")
; #define PG8_BAR __builtin_amdgcn_s_barrier()
; template <class Epi>
; DI void gemm_phase(LAS unsigned char* lds, int wid, int K, int lda, int ldb, bool bperm, const Sched3& S, const Epi& E) {
;     ...
;             PG8_LDB(B1, 1, 1); PG8_STAGE(PG8_SB(1, 0), b3, voffB);
;             PG8_BAR; PG8_WAIT_L(0); PG8_MMA(0, 1, At, B1); PG8_BAR;
	s_add_i32 m0, s41, 0x1f80
	s_nop 0
	global_load_lds_dwordx4 v154, s[38:39] offset:128
	s_barrier
	s_waitcnt lgkmcnt(0)
	s_setprio 1
	s_waitcnt lgkmcnt(0)
	v_mfma_f32_16x16x32_bf16 v[116:119], v[196:199], v[144:147], v[116:119]
	v_mfma_f32_16x16x32_bf16 v[112:115], v[204:207], v[144:147], v[112:115]
	v_mfma_f32_16x16x32_bf16 v[100:103], v[196:199], v[162:165], v[100:103]
	v_mfma_f32_16x16x32_bf16 v[96:99], v[204:207], v[162:165], v[96:99]
	v_mfma_f32_16x16x32_bf16 v[84:87], v[196:199], v[170:173], v[84:87]
	v_mfma_f32_16x16x32_bf16 v[80:83], v[204:207], v[170:173], v[80:83]
	v_mfma_f32_16x16x32_bf16 v[68:71], v[196:199], v[188:191], v[68:71]
	v_mfma_f32_16x16x32_bf16 v[64:67], v[204:207], v[188:191], v[64:67]
	v_mfma_f32_16x16x32_bf16 v[116:119], v[200:203], v[148:151], v[116:119]
	v_mfma_f32_16x16x32_bf16 v[112:115], v[208:211], v[148:151], v[112:115]
	v_mfma_f32_16x16x32_bf16 v[100:103], v[200:203], v[166:169], v[100:103]
	v_mfma_f32_16x16x32_bf16 v[96:99], v[208:211], v[166:169], v[96:99]
	v_mfma_f32_16x16x32_bf16 v[84:87], v[200:203], v[174:177], v[84:87]
	v_mfma_f32_16x16x32_bf16 v[80:83], v[208:211], v[174:177], v[80:83]
	v_mfma_f32_16x16x32_bf16 v[68:71], v[200:203], v[192:195], v[68:71]
	v_mfma_f32_16x16x32_bf16 v[64:67], v[208:211], v[192:195], v[64:67]
	s_setprio 0
	s_sub_i32 m0, s53, 0x80

; #define PG8_STAGE(bufoff, gbase, voff) do { _Pragma("unroll") for (int _i = 0; _i < 2; ++_i) \
;         __builtin_amdgcn_global_load_lds((const unsigned*)((const char*)(gbase) + (voff)[_i]), (LAS unsigned*)(lds + (bufoff) + ldsw + _i * 8192), 16, 0, 0); } while (0)
; #define PG8_LDA(dst, b, h) do { _Pragma("unroll") for (int m = 0; m < 4; ++m) _Pragma("unroll") for (int k = 0; k < 2; ++k) dst[m][k] = *(const LAS bf16x8*)(lds + PG8_SA(b, h) + aoff + m * 2048 + k * 1024); } while (0)
; #define PG8_MMA(ai, bj, At, Bt) do { __builtin_amdgcn_s_setprio(1); _Pragma("unroll") for (int m = 0; m < 4; ++m) _Pragma("unroll") for (int n = 0; n < 2; ++n) _Pragma("unroll") for (int k = 0; k < 2; ++k) \
;         acc[ai][bj][m][n] = __builtin_amdgcn_mfma_f32_16x16x32_bf16(Bt[n][k], At[m][k], acc[ai][bj][m][n], 0, 0, 0); __builtin_amdgcn_s_setprio(0); } while (0)
; #define PG8_WAIT_L(n) asm volatile("s_waitcnt lgkmcnt(" #n ")" ::: "memory")
; #define PG8_BAR __builtin_amdgcn_s_barrier()
; template <class Epi>
; DI void gemm_phase(LAS unsigned char* lds, int wid, int K, int lda, int ldb, bool bperm, const Sched3& S, const Epi& E) {
;     ...
;             PG8_BAR; PG8_WAIT_L(0); PG8_MMA(0, 1, At, B1); PG8_BAR;
;             PG8_LDA(At, 1, 1); PG8_STAGE(PG8_SA(1, 0), a3, voffA);
	s_barrier
	ds_read_b128 v[144:147], v186 offset:49152
	ds_read_b128 v[148:151], v186 offset:50176
	ds_read_b128 v[162:165], v186 offset:51200
	ds_read_b128 v[166:169], v186 offset:52224
	ds_read_b128 v[170:173], v186 offset:53248
	ds_read_b128 v[174:177], v186 offset:54272
	ds_read_b128 v[188:191], v186 offset:55296
	ds_read_b128 v[192:195], v186 offset:56320
	global_load_lds_dwordx4 v152, s[100:101] offset:128

; #define PG8_MMA(ai, bj, At, Bt) do { __builtin_amdgcn_s_setprio(1); _Pragma("unroll") for (int m = 0; m < 4; ++m) _Pragma("unroll") for (int n = 0; n < 2; ++n) _Pragma("unroll") for (int k = 0; k < 2; ++k) \
;         acc[ai][bj][m][n] = __builtin_amdgcn_mfma_f32_16x16x32_bf16(Bt[n][k], At[m][k], acc[ai][bj][m][n], 0, 0, 0); __builtin_amdgcn_s_setprio(0); } while (0)
; #define PG8_WAIT_L(n) asm volatile("s_waitcnt lgkmcnt(" #n ")" ::: "memory")
; #define PG8_BAR __builtin_amdgcn_s_barrier()
; #define PG8_SCHED __builtin_amdgcn_sched_barrier(0)
; template <class Epi>
; DI void gemm_phase(LAS unsigned char* lds, int wid, int K, int lda, int ldb, bool bperm, const Sched3& S, const Epi& E) {
;     ...
;             PG8_BAR; PG8_WAIT_L(0); if (full) PG8_MMA(1, 0, At, B0); PG8_BAR; PG8_SCHED;
	s_sub_i32 m0, s54, 0x80
	s_nop 0
	global_load_lds_dwordx4 v154, s[100:101] offset:128
	s_barrier
	s_waitcnt lgkmcnt(0)
	s_setprio 1
	s_waitcnt lgkmcnt(0)
	v_mfma_f32_16x16x32_bf16 v[60:63], v[128:131], v[144:147], v[60:63]
	v_mfma_f32_16x16x32_bf16 v[56:59], v[136:139], v[144:147], v[56:59]
	v_mfma_f32_16x16x32_bf16 v[44:47], v[128:131], v[162:165], v[44:47]
	v_mfma_f32_16x16x32_bf16 v[40:43], v[136:139], v[162:165], v[40:43]
	v_mfma_f32_16x16x32_bf16 v[28:31], v[128:131], v[170:173], v[28:31]
	v_mfma_f32_16x16x32_bf16 v[24:27], v[136:139], v[170:173], v[24:27]
	v_mfma_f32_16x16x32_bf16 v[12:15], v[128:131], v[188:191], v[12:15]
	v_mfma_f32_16x16x32_bf16 v[8:11], v[136:139], v[188:191], v[8:11]
	v_mfma_f32_16x16x32_bf16 v[60:63], v[132:135], v[148:151], v[60:63]
	v_mfma_f32_16x16x32_bf16 v[56:59], v[140:143], v[148:151], v[56:59]
	v_mfma_f32_16x16x32_bf16 v[44:47], v[132:135], v[166:169], v[44:47]
	v_mfma_f32_16x16x32_bf16 v[40:43], v[140:143], v[166:169], v[40:43]
	v_mfma_f32_16x16x32_bf16 v[28:31], v[132:135], v[174:177], v[28:31]
	v_mfma_f32_16x16x32_bf16 v[24:27], v[140:143], v[174:177], v[24:27]
	v_mfma_f32_16x16x32_bf16 v[12:15], v[132:135], v[192:195], v[12:15]
	v_mfma_f32_16x16x32_bf16 v[8:11], v[140:143], v[192:195], v[8:11]
	s_setprio 0
	s_barrier
	s_add_u32 s38, s38, 0x80080
	s_addc_u32 s39, s39, 0
	s_add_i32 s40, s40, s47

; #define PG8_STAGE(bufoff, gbase, voff) do { _Pragma("unroll") for (int _i = 0; _i < 2; ++_i) \
;         __builtin_amdgcn_global_load_lds((const unsigned*)((const char*)(gbase) + (voff)[_i]), (LAS unsigned*)(lds + (bufoff) + ldsw + _i * 8192), 16, 0, 0); } while (0)
; template <class Epi>
; DI void gemm_phase(LAS unsigned char* lds, int wid, int K, int lda, int ldb, bool bperm, const Sched3& S, const Epi& E) {
;     ...
;             PG8_STAGE(PG8_SB(1, 1), b3 + hstepB, voffB);
	s_mov_b32 m0, s40
	s_nop 0
	global_load_lds_dwordx4 v152, s[38:39]

; DI u32x2 pk4(f32x4 v) { u32x2 r; r.x = pk2(v[0], v[1]); r.y = pk2(v[2], v[3]); return r; }
; DI float bf_lo(unsigned w) { return __uint_as_float(w << 16); }
; DI float bf_hi(unsigned w) { return __uint_as_float(w & 0xffff0000u); }
; template <class Epi>
; DI void gemm_phase(LAS unsigned char* lds, int wid, int K, int lda, int ldb, bool bperm, const Sched3& S, const Epi& E) {
;     ...
;             PG8_STAGE(PG8_SB(1, 1), b3 + hstepB, voffB);
;             PG8_WAIT_V(6); PG8_BAR; if (full) PG8_MMA(1, 1, At, B1); PG8_BAR;
;     DI void operator()(const Acc& acc, const Unit& u, int wr, int wc, int fr, int fq) const {
;     ...
;         } else if constexpr (PH == 4 || PH == 6 || PH == 10 || PH == 12) {
;             float* ssq = SSQ((PH == 4 ? 2 : PH == 6 ? 3 : PH == 10 ? 6 : 7) + sqo);
;             const int colp = u.pn * BM + wc * 32 + 8 * fq;
; #pragma unroll
;             for (int ai = 0; ai < 2; ++ai) if (ai == 0 || !hf) {
;                 f32x4 xo[4][2][2];
; #pragma unroll
;                 for (int m = 0; m < 4; ++m) { const size_t o = (size_t)(row0 + ai * HALF + m * 16) * 2048 + colp;
;                     if (PH == 4) { COLS4 xo[m][bj][n] = *(const f32x4*)(p.x + o + bj * HALF + n * 4); }
;                     else {
; #pragma unroll
;                         for (int bj = 0; bj < 2; ++bj) { const u32x4 w = *(const u32x4*)(WSB(OFF_XB) + o + bj * HALF);
;                             xo[m][bj][0] = (f32x4){bf_lo(w.x), bf_hi(w.x), bf_lo(w.y), bf_hi(w.y)}; xo[m][bj][1] = (f32x4){bf_lo(w.z), bf_hi(w.z), bf_lo(w.w), bf_hi(w.w)}; } } }
; #pragma unroll
;                 for (int m = 0; m < 4; ++m) { const int r = row0 + ai * HALF + m * 16; const size_t o = (size_t)r * 2048 + colp; float part = 0.f;
; #pragma unroll
;                     for (int bj = 0; bj < 2; ++bj) { const f32x4 x0 = xo[m][bj][0] + acc[ai][bj][m][0], x1 = xo[m][bj][1] + acc[ai][bj][m][1];
;                         const u32x2 h0 = pk4(x0), h1 = pk4(x1);
;                         *(u32x4*)(WSB(OFF_XB) + o + bj * HALF) = (u32x4){h0.x, h0.y, h1.x, h1.y};
;                         part += x0[0] * x0[0] + x0[1] * x0[1] + x0[2] * x0[2] + x0[3] * x0[3] + x1[0] * x1[0] + x1[1] * x1[1] + x1[2] * x1[2] + x1[3] * x1[3]; }
;                     part += __shfl_xor(part, 16); part += __shfl_xor(part, 32);
;                     if (fq == 0) unsafeAtomicAdd(ssq + r, part);
;                 }
	s_add_i32 m0, s40, 0x2000
	s_nop 0
	global_load_lds_dwordx4 v154, s[38:39]
	s_waitcnt vmcnt(6)
	s_barrier
	s_setprio 1
	v_mfma_f32_16x16x32_bf16 v[52:55], v[196:199], v[144:147], v[52:55]
	v_mfma_f32_16x16x32_bf16 v[48:51], v[204:207], v[144:147], v[48:51]
	v_mfma_f32_16x16x32_bf16 v[36:39], v[196:199], v[162:165], v[36:39]
	v_mfma_f32_16x16x32_bf16 v[32:35], v[204:207], v[162:165], v[32:35]
	v_mfma_f32_16x16x32_bf16 v[20:23], v[196:199], v[170:173], v[20:23]
	v_mfma_f32_16x16x32_bf16 v[16:19], v[204:207], v[170:173], v[16:19]
	v_mfma_f32_16x16x32_bf16 v[4:7], v[196:199], v[188:191], v[4:7]
	v_mfma_f32_16x16x32_bf16 v[0:3], v[204:207], v[188:191], v[0:3]
	v_mfma_f32_16x16x32_bf16 v[52:55], v[200:203], v[148:151], v[52:55]
	v_mfma_f32_16x16x32_bf16 v[48:51], v[208:211], v[148:151], v[48:51]
	v_mfma_f32_16x16x32_bf16 v[36:39], v[200:203], v[166:169], v[36:39]
	v_mfma_f32_16x16x32_bf16 v[32:35], v[208:211], v[166:169], v[32:35]
	v_mfma_f32_16x16x32_bf16 v[20:23], v[200:203], v[174:177], v[20:23]
	v_mfma_f32_16x16x32_bf16 v[16:19], v[208:211], v[174:177], v[16:19]
	v_mfma_f32_16x16x32_bf16 v[4:7], v[200:203], v[192:195], v[4:7]
	v_mfma_f32_16x16x32_bf16 v[0:3], v[208:211], v[192:195], v[0:3]
	s_setprio 0
	s_add_i32 s27, s27, 2
	s_add_u32 s36, s36, 0x100
	s_addc_u32 s37, s37, 0
	s_add_u32 s19, s19, 0x100
	s_addc_u32 s21, s21, 0
	s_cmp_gt_u32 s27, 29
	s_cbranch_scc0 .Lkrot_6_head
.Lkrot_6_exit:
	s_barrier
.Lpeel_6_exit:
	v_lshl_add_u32 v128, s60, 8, v182
	v_lshl_add_u32 v166, s26, 8, v180
	v_ashrrev_i32_e32 v129, 31, v128
	v_lshlrev_b64 v[162:163], 1, v[128:129]
	v_ashrrev_i32_e32 v167, 31, v166
	v_lshl_add_u64 v[164:165], s[16:17], 0, v[162:163]
	v_lshlrev_b64 v[196:197], 12, v[166:167]
	v_lshl_add_u64 v[128:129], v[164:165], 0, v[196:197]
	global_load_dwordx4 v[188:191], v[128:129], off
	global_load_dwordx4 v[192:195], v[128:129], off offset:256
	v_or_b32_e32 v176, 16, v166
	v_or_b32_e32 v172, 32, v166
	v_or_b32_e32 v168, 48, v166
	v_ashrrev_i32_e32 v177, 31, v176
	v_ashrrev_i32_e32 v173, 31, v172
	v_ashrrev_i32_e32 v169, 31, v168
	v_lshlrev_b64 v[178:179], 12, v[176:177]
	v_lshlrev_b64 v[174:175], 12, v[172:173]
	v_lshlrev_b64 v[170:171], 12, v[168:169]
	v_lshl_add_u64 v[128:129], v[164:165], 0, v[178:179]
	v_lshl_add_u64 v[130:131], v[164:165], 0, v[174:175]
	v_lshl_add_u64 v[198:199], v[164:165], 0, v[170:171]
	global_load_dwordx4 v[148:151], v[128:129], off
	global_load_dwordx4 v[144:147], v[128:129], off offset:256
	global_load_dwordx4 v[140:143], v[130:131], off
	global_load_dwordx4 v[136:139], v[130:131], off offset:256
	global_load_dwordx4 v[132:135], v[198:199], off
	s_nop 0
	global_load_dwordx4 v[128:131], v[198:199], off offset:256
	v_lshl_add_u64 v[198:199], s[16:17], 0, v[196:197]
	v_lshl_add_u64 v[198:199], v[198:199], 0, v[162:163]
	v_lshl_add_u64 v[196:197], s[10:11], 0, v[196:197]
	v_lshl_add_u64 v[196:197], v[196:197], 0, v[162:163]
	s_waitcnt vmcnt(0)
	v_lshlrev_b32_e32 v200, 16, v188
	v_and_b32_e32 v201, 0xffff0000, v188
	v_lshlrev_b32_e32 v188, 16, v189
	v_and_b32_e32 v189, 0xffff0000, v189
	v_lshlrev_b32_e32 v204, 16, v192
	v_and_b32_e32 v205, 0xffff0000, v192
	v_lshlrev_b32_e32 v192, 16, v193
	v_and_b32_e32 v193, 0xffff0000, v193
	v_lshlrev_b32_e32 v206, 16, v194
	v_and_b32_e32 v207, 0xffff0000, v194
	v_pk_add_f32 v[126:127], v[126:127], v[188:189]
	v_pk_add_f32 v[124:125], v[124:125], v[200:201]
	v_pk_add_f32 v[188:189], v[116:117], v[204:205]
	v_pk_add_f32 v[118:119], v[118:119], v[192:193]
	v_pk_add_f32 v[192:193], v[112:113], v[206:207]
	v_cvt_pk_bf16_f32 v112, v124, v125
	v_mul_f32_e32 v117, v125, v125
	v_mul_f32_e32 v125, v189, v189
	v_fmac_f32_e32 v117, v124, v124
	v_fmac_f32_e32 v125, v188, v188
	v_lshlrev_b32_e32 v202, 16, v190
	v_and_b32_e32 v203, 0xffff0000, v190
	v_fmac_f32_e32 v117, v126, v126
	v_fmac_f32_e32 v125, v118, v118
	v_pk_add_f32 v[120:121], v[120:121], v[202:203]
	v_fmac_f32_e32 v117, v127, v127
	v_fmac_f32_e32 v125, v119, v119
	v_lshlrev_b32_e32 v190, 16, v191
	v_and_b32_e32 v191, 0xffff0000, v191
	v_lshlrev_b32_e32 v194, 16, v195
	v_and_b32_e32 v195, 0xffff0000, v195
	v_fmac_f32_e32 v117, v120, v120
	v_fmac_f32_e32 v125, v192, v192
	v_pk_add_f32 v[122:123], v[122:123], v[190:191]
	v_pk_add_f32 v[190:191], v[114:115], v[194:195]
	v_fmac_f32_e32 v117, v121, v121
	v_fmac_f32_e32 v125, v193, v193
	v_fmac_f32_e32 v117, v122, v122
	v_fmac_f32_e32 v125, v190, v190
	v_fmac_f32_e32 v117, v123, v123
	v_fmac_f32_e32 v125, v191, v191
	v_cvt_pk_bf16_f32 v114, v120, v121
	v_add_f32_e32 v120, v117, v125
	ds_bpermute_b32 v121, v183, v120
	v_cvt_pk_bf16_f32 v113, v126, v127
	v_cvt_pk_bf16_f32 v115, v122, v123
	global_store_dwordx4 v[198:199], v[112:115], off sc1
	v_cvt_pk_bf16_f32 v116, v188, v189
	v_cvt_pk_bf16_f32 v117, v118, v119
	s_waitcnt lgkmcnt(0)
	v_add_f32_e32 v112, v120, v121
	ds_bpermute_b32 v113, v184, v112
	v_add_co_u32_e32 v114, vcc, s59, v196
	v_cvt_pk_bf16_f32 v118, v192, v193
	v_cvt_pk_bf16_f32 v119, v190, v191
	v_addc_co_u32_e32 v115, vcc, 0, v197, vcc
	global_store_dwordx4 v[114:115], v[116:119], off offset:256 sc1
	s_and_saveexec_b64 s[26:27], s[2:3]
	s_cbranch_execz .LBB0_1179
	s_waitcnt lgkmcnt(0)
	v_add_f32_e32 v114, v112, v113
	v_lshl_add_u64 v[112:113], v[166:167], 2, s[14:15]
	global_atomic_add_f32 v[112:113], v114, off

; DI u32x2 pk4(f32x4 v) { u32x2 r; r.x = pk2(v[0], v[1]); r.y = pk2(v[2], v[3]); return r; }
; DI float silu_f(float x) { return x * __builtin_amdgcn_rcpf(1.f + __builtin_amdgcn_exp2f(-1.4426950409f * x)); }
; #define PG8_MMA(ai, bj, At, Bt) do { __builtin_amdgcn_s_setprio(1); _Pragma("unroll") for (int m = 0; m < 4; ++m) _Pragma("unroll") for (int n = 0; n < 2; ++n) _Pragma("unroll") for (int k = 0; k < 2; ++k) \
;         acc[ai][bj][m][n] = __builtin_amdgcn_mfma_f32_16x16x32_bf16(Bt[n][k], At[m][k], acc[ai][bj][m][n], 0, 0, 0); __builtin_amdgcn_s_setprio(0); } while (0)
; #define PG8_WAIT_V(n) asm volatile("s_waitcnt vmcnt(" #n ")" ::: "memory")
; #define PG8_BAR __builtin_amdgcn_s_barrier()
; #define ROWS8 _Pragma("unroll") for (int ai = 0; ai < 2; ++ai) _Pragma("unroll") for (int m = 0; m < 4; ++m) if (ai == 0 || !hf)
; #define LOAD_ROW_RS(rsv, ssqp, invn) float rsv[2][4]; ROWS8_ALL rsv[ai][m] = (ssqp)[row0 + ai * HALF + m * 16]; ROWS8_ALL rsv[ai][m] = rstd_of(rsv[ai][m], invn)
; template <class Epi>
; DI void gemm_phase(LAS unsigned char* lds, int wid, int K, int lda, int ldb, bool bperm, const Sched3& S, const Epi& E) {
;     ...
;             PG8_WAIT_V(6); PG8_BAR; if (full) PG8_MMA(1, 1, At, B1); PG8_BAR;
;     DI void operator()(const Acc& acc, const Unit& u, int wr, int wc, int fr, int fq) const {
;     ...
;         } else if constexpr (PH == 5 || PH == 11) {
;             LOAD_ROW_RS(rsv, SSQ(PH == 5 ? 2 : 6), 1.f / 2048.f);
;             const int ac0 = u.pn * 128 + wc * 32 + 8 * fq;
;             ROWS8 { const int r = row0 + ai * HALF + m * 16; const float rs = rsv[ai][m];
;                 u32x4 w;
; #pragma unroll
;                 for (int bj = 0; bj < 2; ++bj) { const f32x4 g = acc[ai][bj][m][0] * rs, uu = acc[ai][bj][m][1] * rs;
;                     f32x4 a; a[0] = silu_f(g[0]) * uu[0]; a[1] = silu_f(g[1]) * uu[1]; a[2] = silu_f(g[2]) * uu[2]; a[3] = silu_f(g[3]) * uu[3];
;                     const u32x2 h = pk4(a); if (bj == 0) { w.x = h.x; w.y = h.y; } else { w.z = h.x; w.w = h.y; } }
;                 *(u32x4*)(WSB(OFF_ACT) + (size_t)r * DFF + ac0) = w;
;             }
.Lkrot_7_exit:
	s_barrier
.Lpeel_7_exit:
	v_lshl_add_u32 v142, s22, 8, v155
	v_or_b32_e32 v156, 16, v142
	v_ashrrev_i32_e32 v157, 31, v156
	v_or_b32_e32 v152, 32, v142
	v_or_b32_e32 v150, 48, v142
	v_lshl_add_u64 v[138:139], v[156:157], 2, s[10:11]
	v_ashrrev_i32_e32 v153, 31, v152
	v_ashrrev_i32_e32 v151, 31, v150
	v_ashrrev_i32_e32 v143, 31, v142
	v_lshl_add_u64 v[140:141], v[152:153], 2, s[10:11]
	v_lshl_add_u64 v[144:145], v[150:151], 2, s[10:11]
	v_lshl_add_u64 v[146:147], v[142:143], 2, s[10:11]
	v_add_u32_e32 v148, 0x80, v142
	v_add_u32_e32 v146, 0x90, v142
	v_add_u32_e32 v144, 0xa0, v142
	v_add_u32_e32 v138, 0xb0, v142
	v_ashrrev_i32_e32 v149, 31, v148
	v_ashrrev_i32_e32 v147, 31, v146
	v_ashrrev_i32_e32 v145, 31, v144
	v_ashrrev_i32_e32 v139, 31, v138
	v_lshl_add_u64 v[140:141], v[148:149], 2, s[10:11]
	v_lshl_add_u64 v[164:165], v[146:147], 2, s[10:11]
	v_lshl_add_u64 v[166:167], v[144:145], 2, s[10:11]
	v_lshl_add_u64 v[168:169], v[138:139], 2, s[10:11]
	v_lshl_add_u32 v164, s56, 7, v159
	v_mov_b64_e32 v[140:141], s[12:13]
	v_ashrrev_i32_e32 v165, 31, v164
	v_mad_i64_i32 v[166:167], s[24:25], v142, s55, v[140:141]
	v_lshlrev_b64 v[142:143], 1, v[164:165]
	v_lshl_add_u64 v[164:165], v[166:167], 0, v[142:143]
	s_and_b64 vcc, exec, s[2:3]
	s_mov_b32 s56, s14
	s_mov_b32 s22, s16
	s_mov_b64 s[30:31], s[18:19]
	s_mov_b64 s[28:29], s[20:21]
	v_mov_b32_e32 v151, v221
	v_mov_b32_e32 v153, v222
	v_mov_b32_e32 v154, v223
	v_mov_b32_e32 v157, v220
	v_mov_b32_e32 v139, v224
	v_mov_b32_e32 v145, v225
	v_mov_b32_e32 v147, v226
	v_mov_b32_e32 v149, v227
	v_fmamk_f32 v151, v151, 0x3a000000, v163
	v_rsq_f32_e32 v168, v151
	v_fmamk_f32 v153, v153, 0x3a000000, v163
	v_fmamk_f32 v157, v157, 0x3a000000, v163
	v_rsq_f32_e32 v166, v157
	v_rsq_f32_e32 v170, v153
	v_pk_mul_f32 v[118:119], v[118:119], v[168:169] op_sel_hi:[1,0]
	v_pk_mul_f32 v[116:117], v[116:117], v[168:169] op_sel_hi:[1,0]
	v_pk_mul_f32 v[126:127], v[126:127], v[166:167] op_sel_hi:[1,0]
	v_pk_mul_f32 v[124:125], v[124:125], v[166:167] op_sel_hi:[1,0]
	v_pk_mul_f32 v[114:115], v[114:115], v[166:167] op_sel_hi:[1,0]
	v_pk_mul_f32 v[112:113], v[112:113], v[166:167] op_sel_hi:[1,0]
	v_pk_mul_f32 v[122:123], v[122:123], v[166:167] op_sel_hi:[1,0]
	v_pk_mul_f32 v[120:121], v[120:121], v[166:167] op_sel_hi:[1,0]
	v_pk_mul_f32 v[110:111], v[110:111], v[166:167] op_sel_hi:[1,0]
	v_pk_mul_f32 v[108:109], v[108:109], v[166:167] op_sel_hi:[1,0]
	v_mul_f32_e32 v151, 0xbfb8aa3b, v124
	v_mul_f32_e32 v153, 0xbfb8aa3b, v125
	v_mul_f32_e32 v157, 0xbfb8aa3b, v126
	v_mul_f32_e32 v166, 0xbfb8aa3b, v127
	v_mul_f32_e32 v167, 0xbfb8aa3b, v112
	v_mul_f32_e32 v169, 0xbfb8aa3b, v113
	v_mul_f32_e32 v171, 0xbfb8aa3b, v114
	v_mul_f32_e32 v172, 0xbfb8aa3b, v115
	v_exp_f32_e32 v151, v151
	v_exp_f32_e32 v153, v153
	v_exp_f32_e32 v157, v157
	v_exp_f32_e32 v166, v166
	v_exp_f32_e32 v167, v167
	v_exp_f32_e32 v169, v169
	v_exp_f32_e32 v171, v171
	v_exp_f32_e32 v172, v172
	v_mul_f32_e32 v173, 0xbfb8aa3b, v116
	v_exp_f32_e32 v178, v173
	v_add_f32_e32 v151, 1.0, v151
	v_add_f32_e32 v153, 1.0, v153
	v_add_f32_e32 v157, 1.0, v157
	v_add_f32_e32 v173, 1.0, v166
	v_add_f32_e32 v174, 1.0, v167
	v_add_f32_e32 v169, 1.0, v169
	v_add_f32_e32 v171, 1.0, v171
	v_add_f32_e32 v177, 1.0, v172
	v_rcp_f32_e32 v166, v151
	v_rcp_f32_e32 v167, v153
	v_rcp_f32_e32 v172, v157
	v_rcp_f32_e32 v173, v173
	v_rcp_f32_e32 v174, v174
	v_rcp_f32_e32 v175, v169
	v_rcp_f32_e32 v176, v171
	v_rcp_f32_e32 v177, v177
	v_pk_mul_f32 v[124:125], v[124:125], v[166:167]
	v_pk_mul_f32 v[126:127], v[126:127], v[172:173]
	v_pk_mul_f32 v[112:113], v[112:113], v[174:175]
	v_pk_mul_f32 v[114:115], v[114:115], v[176:177]
	v_pk_mul_f32 v[120:121], v[120:121], v[124:125]
	v_pk_mul_f32 v[122:123], v[122:123], v[126:127]
	v_pk_mul_f32 v[112:113], v[108:109], v[112:113]
	v_pk_mul_f32 v[114:115], v[110:111], v[114:115]
	v_cvt_pk_bf16_f32 v108, v120, v121
	v_cvt_pk_bf16_f32 v109, v122, v123
	v_cvt_pk_bf16_f32 v110, v112, v113
	v_cvt_pk_bf16_f32 v111, v114, v115
	global_store_dwordx4 v[164:165], v[108:111], off
	v_pk_mul_f32 v[104:105], v[104:105], v[168:169] op_sel_hi:[1,0]
	v_pk_mul_f32 v[106:107], v[106:107], v[168:169] op_sel_hi:[1,0]
	v_mul_f32_e32 v108, 0xbfb8aa3b, v117
	v_exp_f32_e32 v109, v108
	v_mul_f32_e32 v110, 0xbfb8aa3b, v118
	v_mul_f32_e32 v111, 0xbfb8aa3b, v119
	v_exp_f32_e32 v110, v110
	v_exp_f32_e32 v111, v111
	v_add_f32_e32 v108, 1.0, v178
	v_add_f32_e32 v109, 1.0, v109
	v_rcp_f32_e32 v108, v108
	v_rcp_f32_e32 v109, v109
	v_add_f32_e32 v110, 1.0, v110
	v_add_f32_e32 v111, 1.0, v111
	v_rcp_f32_e32 v110, v110
	v_rcp_f32_e32 v111, v111
	v_pk_mul_f32 v[108:109], v[116:117], v[108:109]
	v_pk_mul_f32 v[100:101], v[100:101], v[168:169] op_sel_hi:[1,0]
	v_pk_mul_f32 v[104:105], v[104:105], v[108:109]
	v_pk_mul_f32 v[108:109], v[118:119], v[110:111]
	v_cvt_pk_bf16_f32 v104, v104, v105
	v_pk_mul_f32 v[106:107], v[106:107], v[108:109]
	v_pk_mul_f32 v[102:103], v[102:103], v[168:169] op_sel_hi:[1,0]
	v_cvt_pk_bf16_f32 v105, v106, v107
	v_mul_f32_e32 v106, 0xbfb8aa3b, v100
	v_mul_f32_e32 v107, 0xbfb8aa3b, v101
	v_exp_f32_e32 v106, v106
	v_exp_f32_e32 v107, v107
	v_mul_f32_e32 v108, 0xbfb8aa3b, v102
	v_mul_f32_e32 v109, 0xbfb8aa3b, v103
	v_exp_f32_e32 v108, v108
	v_exp_f32_e32 v109, v109
	v_add_f32_e32 v106, 1.0, v106
	v_add_f32_e32 v107, 1.0, v107
	v_rcp_f32_e32 v106, v106
	v_rcp_f32_e32 v107, v107
	v_add_f32_e32 v108, 1.0, v108
	v_add_f32_e32 v109, 1.0, v109
	v_rcp_f32_e32 v108, v108
	v_rcp_f32_e32 v109, v109
	v_pk_mul_f32 v[92:93], v[92:93], v[168:169] op_sel_hi:[1,0]
	v_pk_mul_f32 v[100:101], v[100:101], v[106:107]
	v_pk_mul_f32 v[94:95], v[94:95], v[168:169] op_sel_hi:[1,0]
; DI u32x2 pk4(f32x4 v) { u32x2 r; r.x = pk2(v[0], v[1]); r.y = pk2(v[2], v[3]); return r; }
; DI float silu_f(float x) { return x * __builtin_amdgcn_rcpf(1.f + __builtin_amdgcn_exp2f(-1.4426950409f * x)); }
; #define ROWS8 _Pragma("unroll") for (int ai = 0; ai < 2; ++ai) _Pragma("unroll") for (int m = 0; m < 4; ++m) if (ai == 0 || !hf)
; #define LOAD_ROW_RS(rsv, ssqp, invn) float rsv[2][4]; ROWS8_ALL rsv[ai][m] = (ssqp)[row0 + ai * HALF + m * 16]; ROWS8_ALL rsv[ai][m] = rstd_of(rsv[ai][m], invn)
;     DI void operator()(const Acc& acc, const Unit& u, int wr, int wc, int fr, int fq) const {
;     ...
;         } else if constexpr (PH == 5 || PH == 11) {
;             LOAD_ROW_RS(rsv, SSQ(PH == 5 ? 2 : 6), 1.f / 2048.f);
;             const int ac0 = u.pn * 128 + wc * 32 + 8 * fq;
;             ROWS8 { const int r = row0 + ai * HALF + m * 16; const float rs = rsv[ai][m];
;                 u32x4 w;
; #pragma unroll
;                 for (int bj = 0; bj < 2; ++bj) { const f32x4 g = acc[ai][bj][m][0] * rs, uu = acc[ai][bj][m][1] * rs;
;                     f32x4 a; a[0] = silu_f(g[0]) * uu[0]; a[1] = silu_f(g[1]) * uu[1]; a[2] = silu_f(g[2]) * uu[2]; a[3] = silu_f(g[3]) * uu[3];
;                     const u32x2 h = pk4(a); if (bj == 0) { w.x = h.x; w.y = h.y; } else { w.z = h.x; w.w = h.y; } }
;                 *(u32x4*)(WSB(OFF_ACT) + (size_t)r * DFF + ac0) = w;
;             }
	v_pk_mul_f32 v[92:93], v[92:93], v[100:101]
	v_pk_mul_f32 v[100:101], v[102:103], v[108:109]
	v_cvt_pk_bf16_f32 v106, v92, v93
	v_pk_mul_f32 v[94:95], v[94:95], v[100:101]
	v_mad_i64_i32 v[92:93], s[24:25], v156, s55, v[140:141]
	v_cvt_pk_bf16_f32 v107, v94, v95
	v_lshl_add_u64 v[92:93], v[92:93], 0, v[142:143]
	global_store_dwordx4 v[92:93], v[104:107], off
	v_pk_mul_f32 v[92:93], v[98:99], v[170:171] op_sel_hi:[1,0]
	v_pk_mul_f32 v[94:95], v[96:97], v[170:171] op_sel_hi:[1,0]
	v_mul_f32_e32 v98, 0xbfb8aa3b, v92
	v_mul_f32_e32 v96, 0xbfb8aa3b, v94
	v_mul_f32_e32 v97, 0xbfb8aa3b, v95
	v_mul_f32_e32 v99, 0xbfb8aa3b, v93
	v_exp_f32_e32 v96, v96
	v_exp_f32_e32 v97, v97
	v_exp_f32_e32 v98, v98
	v_exp_f32_e32 v99, v99
	v_add_f32_e32 v96, 1.0, v96
	v_add_f32_e32 v97, 1.0, v97
	v_add_f32_e32 v98, 1.0, v98
	v_add_f32_e32 v99, 1.0, v99
	v_rcp_f32_e32 v96, v96
	v_rcp_f32_e32 v97, v97
	v_rcp_f32_e32 v98, v98
	v_rcp_f32_e32 v99, v99
	v_pk_mul_f32 v[90:91], v[90:91], v[170:171] op_sel_hi:[1,0]
	v_pk_mul_f32 v[88:89], v[88:89], v[170:171] op_sel_hi:[1,0]
	v_pk_mul_f32 v[94:95], v[94:95], v[96:97]
	v_pk_mul_f32 v[92:93], v[92:93], v[98:99]
	v_pk_mul_f32 v[88:89], v[88:89], v[94:95]
	v_pk_mul_f32 v[90:91], v[90:91], v[92:93]
	v_pk_mul_f32 v[84:85], v[84:85], v[170:171] op_sel_hi:[1,0]
	v_cvt_pk_bf16_f32 v88, v88, v89
	v_cvt_pk_bf16_f32 v89, v90, v91
	v_pk_mul_f32 v[86:87], v[86:87], v[170:171] op_sel_hi:[1,0]
	v_mul_f32_e32 v90, 0xbfb8aa3b, v84
	v_mul_f32_e32 v91, 0xbfb8aa3b, v85
	v_exp_f32_e32 v90, v90
	v_exp_f32_e32 v91, v91
	v_mul_f32_e32 v92, 0xbfb8aa3b, v86
	v_mul_f32_e32 v93, 0xbfb8aa3b, v87
	v_exp_f32_e32 v92, v92
	v_exp_f32_e32 v93, v93
	v_add_f32_e32 v90, 1.0, v90
	v_add_f32_e32 v91, 1.0, v91
	v_rcp_f32_e32 v90, v90
	v_rcp_f32_e32 v91, v91
	v_add_f32_e32 v92, 1.0, v92
	v_add_f32_e32 v93, 1.0, v93
	v_rcp_f32_e32 v92, v92
	v_rcp_f32_e32 v93, v93
	v_fmamk_f32 v154, v154, 0x3a000000, v163
	v_rsq_f32_e32 v154, v154
	v_pk_mul_f32 v[76:77], v[76:77], v[170:171] op_sel_hi:[1,0]
	v_pk_mul_f32 v[84:85], v[84:85], v[90:91]
	v_pk_mul_f32 v[78:79], v[78:79], v[170:171] op_sel_hi:[1,0]
	v_pk_mul_f32 v[76:77], v[76:77], v[84:85]
	v_pk_mul_f32 v[84:85], v[86:87], v[92:93]
	v_cvt_pk_bf16_f32 v90, v76, v77
	v_pk_mul_f32 v[78:79], v[78:79], v[84:85]
	v_mad_i64_i32 v[76:77], s[24:25], v152, s55, v[140:141]
	v_cvt_pk_bf16_f32 v91, v78, v79
	v_lshl_add_u64 v[76:77], v[76:77], 0, v[142:143]
	global_store_dwordx4 v[76:77], v[88:91], off
	v_pk_mul_f32 v[76:77], v[82:83], v[154:155] op_sel_hi:[1,0]
	v_pk_mul_f32 v[78:79], v[80:81], v[154:155] op_sel_hi:[1,0]
	v_mul_f32_e32 v82, 0xbfb8aa3b, v76
	v_mul_f32_e32 v80, 0xbfb8aa3b, v78
	v_mul_f32_e32 v81, 0xbfb8aa3b, v79
	v_mul_f32_e32 v83, 0xbfb8aa3b, v77
	v_exp_f32_e32 v80, v80
	v_exp_f32_e32 v81, v81
	v_exp_f32_e32 v82, v82
	v_exp_f32_e32 v83, v83
	v_add_f32_e32 v80, 1.0, v80
	v_add_f32_e32 v81, 1.0, v81
	v_add_f32_e32 v82, 1.0, v82
	v_add_f32_e32 v83, 1.0, v83
	v_rcp_f32_e32 v80, v80
	v_rcp_f32_e32 v81, v81
	v_rcp_f32_e32 v82, v82
	v_rcp_f32_e32 v83, v83
	v_pk_mul_f32 v[74:75], v[74:75], v[154:155] op_sel_hi:[1,0]
	v_pk_mul_f32 v[72:73], v[72:73], v[154:155] op_sel_hi:[1,0]
	v_pk_mul_f32 v[78:79], v[78:79], v[80:81]
	v_pk_mul_f32 v[76:77], v[76:77], v[82:83]
	v_pk_mul_f32 v[72:73], v[72:73], v[78:79]
	v_pk_mul_f32 v[74:75], v[74:75], v[76:77]
	v_pk_mul_f32 v[68:69], v[68:69], v[154:155] op_sel_hi:[1,0]
	v_cvt_pk_bf16_f32 v72, v72, v73
	v_cvt_pk_bf16_f32 v73, v74, v75
	v_pk_mul_f32 v[70:71], v[70:71], v[154:155] op_sel_hi:[1,0]
	v_mul_f32_e32 v74, 0xbfb8aa3b, v68
	v_mul_f32_e32 v75, 0xbfb8aa3b, v69
	v_exp_f32_e32 v74, v74
	v_exp_f32_e32 v75, v75
	v_mul_f32_e32 v76, 0xbfb8aa3b, v70
	v_mul_f32_e32 v77, 0xbfb8aa3b, v71
	v_exp_f32_e32 v76, v76
	v_exp_f32_e32 v77, v77
	v_add_f32_e32 v74, 1.0, v74
	v_add_f32_e32 v75, 1.0, v75
	v_rcp_f32_e32 v74, v74
	v_rcp_f32_e32 v75, v75
	v_add_f32_e32 v76, 1.0, v76
	v_add_f32_e32 v77, 1.0, v77
	v_rcp_f32_e32 v76, v76
	v_rcp_f32_e32 v77, v77
	v_pk_mul_f32 v[64:65], v[64:65], v[154:155] op_sel_hi:[1,0]
	v_pk_mul_f32 v[68:69], v[68:69], v[74:75]
	v_pk_mul_f32 v[66:67], v[66:67], v[154:155] op_sel_hi:[1,0]
	v_pk_mul_f32 v[64:65], v[64:65], v[68:69]
	v_pk_mul_f32 v[68:69], v[70:71], v[76:77]
	v_cvt_pk_bf16_f32 v74, v64, v65
	v_pk_mul_f32 v[66:67], v[66:67], v[68:69]
	v_mad_i64_i32 v[64:65], s[24:25], v150, s55, v[140:141]
	v_cvt_pk_bf16_f32 v75, v66, v67
	v_fmamk_f32 v66, v139, 0x3a000000, v163
	v_rsq_f32_e32 v68, v66
	v_lshl_add_u64 v[64:65], v[64:65], 0, v[142:143]
	global_store_dwordx4 v[64:65], v[72:75], off
	v_fmamk_f32 v65, v147, 0x3a000000, v163
	v_rsq_f32_e32 v66, v65
	v_fmamk_f32 v65, v145, 0x3a000000, v163
	v_pk_mul_f32 v[60:61], v[60:61], v[68:69] op_sel_hi:[1,0]
	v_rsq_f32_e32 v70, v65
	v_mul_f32_e32 v65, 0xbfb8aa3b, v60
	v_exp_f32_e32 v65, v65
	v_mul_f32_e32 v67, 0xbfb8aa3b, v61
	v_exp_f32_e32 v67, v67
	v_pk_mul_f32 v[62:63], v[62:63], v[68:69] op_sel_hi:[1,0]
	v_add_f32_e32 v65, 1.0, v65
	v_rcp_f32_e32 v72, v65
	v_add_f32_e32 v65, 1.0, v67
	v_mul_f32_e32 v67, 0xbfb8aa3b, v62
	v_pk_mul_f32 v[58:59], v[58:59], v[68:69] op_sel_hi:[1,0]
	v_exp_f32_e32 v67, v67
	v_mul_f32_e32 v69, 0xbfb8aa3b, v63
	v_exp_f32_e32 v69, v69
	v_rcp_f32_e32 v73, v65
	v_add_f32_e32 v65, 1.0, v67
	v_rcp_f32_e32 v74, v65
	v_add_f32_e32 v65, 1.0, v69
	v_rcp_f32_e32 v75, v65
	v_pk_mul_f32 v[56:57], v[56:57], v[68:69] op_sel_hi:[1,0]
	v_pk_mul_f32 v[60:61], v[60:61], v[72:73]
	v_pk_mul_f32 v[52:53], v[52:53], v[68:69] op_sel_hi:[1,0]
	v_pk_mul_f32 v[56:57], v[56:57], v[60:61]
	v_pk_mul_f32 v[60:61], v[62:63], v[74:75]
	v_cvt_pk_bf16_f32 v56, v56, v57
	v_pk_mul_f32 v[58:59], v[58:59], v[60:61]
; DI u32x2 pk4(f32x4 v) { u32x2 r; r.x = pk2(v[0], v[1]); r.y = pk2(v[2], v[3]); return r; }
; DI float silu_f(float x) { return x * __builtin_amdgcn_rcpf(1.f + __builtin_amdgcn_exp2f(-1.4426950409f * x)); }
; #define ROWS8 _Pragma("unroll") for (int ai = 0; ai < 2; ++ai) _Pragma("unroll") for (int m = 0; m < 4; ++m) if (ai == 0 || !hf)
; #define LOAD_ROW_RS(rsv, ssqp, invn) float rsv[2][4]; ROWS8_ALL rsv[ai][m] = (ssqp)[row0 + ai * HALF + m * 16]; ROWS8_ALL rsv[ai][m] = rstd_of(rsv[ai][m], invn)
;     DI void operator()(const Acc& acc, const Unit& u, int wr, int wc, int fr, int fq) const {
;     ...
;         } else if constexpr (PH == 5 || PH == 11) {
;             LOAD_ROW_RS(rsv, SSQ(PH == 5 ? 2 : 6), 1.f / 2048.f);
;             const int ac0 = u.pn * 128 + wc * 32 + 8 * fq;
;             ROWS8 { const int r = row0 + ai * HALF + m * 16; const float rs = rsv[ai][m];
;                 u32x4 w;
; #pragma unroll
;                 for (int bj = 0; bj < 2; ++bj) { const f32x4 g = acc[ai][bj][m][0] * rs, uu = acc[ai][bj][m][1] * rs;
;                     f32x4 a; a[0] = silu_f(g[0]) * uu[0]; a[1] = silu_f(g[1]) * uu[1]; a[2] = silu_f(g[2]) * uu[2]; a[3] = silu_f(g[3]) * uu[3];
;                     const u32x2 h = pk4(a); if (bj == 0) { w.x = h.x; w.y = h.y; } else { w.z = h.x; w.w = h.y; } }
;                 *(u32x4*)(WSB(OFF_ACT) + (size_t)r * DFF + ac0) = w;
;             }
	v_pk_mul_f32 v[54:55], v[54:55], v[68:69] op_sel_hi:[1,0]
	v_cvt_pk_bf16_f32 v57, v58, v59
	v_mul_f32_e32 v58, 0xbfb8aa3b, v52
	v_mul_f32_e32 v59, 0xbfb8aa3b, v53
	v_exp_f32_e32 v58, v58
	v_exp_f32_e32 v59, v59
	v_mul_f32_e32 v60, 0xbfb8aa3b, v54
	v_mul_f32_e32 v61, 0xbfb8aa3b, v55
	v_exp_f32_e32 v60, v60
	v_exp_f32_e32 v61, v61
	v_add_f32_e32 v58, 1.0, v58
	v_add_f32_e32 v59, 1.0, v59
	v_rcp_f32_e32 v58, v58
	v_rcp_f32_e32 v59, v59
	v_add_f32_e32 v60, 1.0, v60
	v_add_f32_e32 v61, 1.0, v61
	v_rcp_f32_e32 v60, v60
	v_rcp_f32_e32 v61, v61
	v_pk_mul_f32 v[44:45], v[44:45], v[68:69] op_sel_hi:[1,0]
	v_pk_mul_f32 v[52:53], v[52:53], v[58:59]
	v_pk_mul_f32 v[46:47], v[46:47], v[68:69] op_sel_hi:[1,0]
	v_pk_mul_f32 v[44:45], v[44:45], v[52:53]
	v_pk_mul_f32 v[52:53], v[54:55], v[60:61]
	v_cvt_pk_bf16_f32 v58, v44, v45
	v_pk_mul_f32 v[46:47], v[46:47], v[52:53]
	v_mad_i64_i32 v[44:45], s[24:25], v148, s55, v[140:141]
	v_cvt_pk_bf16_f32 v59, v46, v47
	v_lshl_add_u64 v[44:45], v[44:45], 0, v[142:143]
	global_store_dwordx4 v[44:45], v[56:59], off
	v_pk_mul_f32 v[44:45], v[50:51], v[70:71] op_sel_hi:[1,0]
	v_pk_mul_f32 v[46:47], v[48:49], v[70:71] op_sel_hi:[1,0]
	v_mul_f32_e32 v50, 0xbfb8aa3b, v44
	v_mul_f32_e32 v48, 0xbfb8aa3b, v46
	v_mul_f32_e32 v49, 0xbfb8aa3b, v47
	v_mul_f32_e32 v51, 0xbfb8aa3b, v45
	v_exp_f32_e32 v48, v48
	v_exp_f32_e32 v49, v49
	v_exp_f32_e32 v50, v50
	v_exp_f32_e32 v51, v51
	v_add_f32_e32 v48, 1.0, v48
	v_add_f32_e32 v49, 1.0, v49
	v_add_f32_e32 v50, 1.0, v50
	v_add_f32_e32 v51, 1.0, v51
	v_rcp_f32_e32 v48, v48
	v_rcp_f32_e32 v49, v49
	v_rcp_f32_e32 v50, v50
	v_rcp_f32_e32 v51, v51
	v_pk_mul_f32 v[42:43], v[42:43], v[70:71] op_sel_hi:[1,0]
	v_pk_mul_f32 v[40:41], v[40:41], v[70:71] op_sel_hi:[1,0]
	v_pk_mul_f32 v[46:47], v[46:47], v[48:49]
	v_pk_mul_f32 v[44:45], v[44:45], v[50:51]
	v_pk_mul_f32 v[40:41], v[40:41], v[46:47]
	v_pk_mul_f32 v[42:43], v[42:43], v[44:45]
	v_pk_mul_f32 v[36:37], v[36:37], v[70:71] op_sel_hi:[1,0]
	v_cvt_pk_bf16_f32 v40, v40, v41
	v_cvt_pk_bf16_f32 v41, v42, v43
	v_pk_mul_f32 v[38:39], v[38:39], v[70:71] op_sel_hi:[1,0]
	v_mul_f32_e32 v42, 0xbfb8aa3b, v36
	v_mul_f32_e32 v43, 0xbfb8aa3b, v37
	v_exp_f32_e32 v42, v42
	v_exp_f32_e32 v43, v43
	v_mul_f32_e32 v44, 0xbfb8aa3b, v38
	v_mul_f32_e32 v45, 0xbfb8aa3b, v39
	v_exp_f32_e32 v44, v44
	v_exp_f32_e32 v45, v45
	v_add_f32_e32 v42, 1.0, v42
	v_add_f32_e32 v43, 1.0, v43
	v_rcp_f32_e32 v42, v42
	v_rcp_f32_e32 v43, v43
	v_add_f32_e32 v44, 1.0, v44
	v_add_f32_e32 v45, 1.0, v45
	v_rcp_f32_e32 v44, v44
	v_rcp_f32_e32 v45, v45
	v_pk_mul_f32 v[28:29], v[28:29], v[70:71] op_sel_hi:[1,0]
	v_pk_mul_f32 v[36:37], v[36:37], v[42:43]
	v_pk_mul_f32 v[30:31], v[30:31], v[70:71] op_sel_hi:[1,0]
	v_pk_mul_f32 v[28:29], v[28:29], v[36:37]
	v_pk_mul_f32 v[36:37], v[38:39], v[44:45]
	v_cvt_pk_bf16_f32 v42, v28, v29
	v_pk_mul_f32 v[30:31], v[30:31], v[36:37]
	v_mad_i64_i32 v[28:29], s[24:25], v146, s55, v[140:141]
	v_cvt_pk_bf16_f32 v43, v30, v31
	v_lshl_add_u64 v[28:29], v[28:29], 0, v[142:143]
	global_store_dwordx4 v[28:29], v[40:43], off
	v_pk_mul_f32 v[28:29], v[34:35], v[66:67] op_sel_hi:[1,0]
	v_pk_mul_f32 v[30:31], v[32:33], v[66:67] op_sel_hi:[1,0]
	v_mul_f32_e32 v34, 0xbfb8aa3b, v28
	v_mul_f32_e32 v32, 0xbfb8aa3b, v30
	v_mul_f32_e32 v33, 0xbfb8aa3b, v31
	v_mul_f32_e32 v35, 0xbfb8aa3b, v29
	v_exp_f32_e32 v32, v32
	v_exp_f32_e32 v33, v33
	v_exp_f32_e32 v34, v34
	v_exp_f32_e32 v35, v35
	v_add_f32_e32 v32, 1.0, v32
	v_add_f32_e32 v33, 1.0, v33
	v_add_f32_e32 v34, 1.0, v34
	v_add_f32_e32 v35, 1.0, v35
	v_rcp_f32_e32 v32, v32
	v_rcp_f32_e32 v33, v33
; DI u32x2 pk4(f32x4 v) { u32x2 r; r.x = pk2(v[0], v[1]); r.y = pk2(v[2], v[3]); return r; }
; DI float silu_f(float x) { return x * __builtin_amdgcn_rcpf(1.f + __builtin_amdgcn_exp2f(-1.4426950409f * x)); }
; #define PG8_WAIT_V(n) asm volatile("s_waitcnt vmcnt(" #n ")" ::: "memory")
; #define PG8_BAR __builtin_amdgcn_s_barrier()
; #define ROWS8 _Pragma("unroll") for (int ai = 0; ai < 2; ++ai) _Pragma("unroll") for (int m = 0; m < 4; ++m) if (ai == 0 || !hf)
; template <class Epi>
; DI void gemm_phase(LAS unsigned char* lds, int wid, int K, int lda, int ldb, bool bperm, const Sched3& S, const Epi& E) {
;     ...
;     PG8_WAIT_V(0);
;     if (wr == 0) PG8_BAR;
;     PG8_BAR;
;     DI void operator()(const Acc& acc, const Unit& u, int wr, int wc, int fr, int fq) const {
;     ...
;             ROWS8 { const int r = row0 + ai * HALF + m * 16; const float rs = rsv[ai][m];
;                 u32x4 w;
; #pragma unroll
;                 for (int bj = 0; bj < 2; ++bj) { const f32x4 g = acc[ai][bj][m][0] * rs, uu = acc[ai][bj][m][1] * rs;
;                     f32x4 a; a[0] = silu_f(g[0]) * uu[0]; a[1] = silu_f(g[1]) * uu[1]; a[2] = silu_f(g[2]) * uu[2]; a[3] = silu_f(g[3]) * uu[3];
;                     const u32x2 h = pk4(a); if (bj == 0) { w.x = h.x; w.y = h.y; } else { w.z = h.x; w.w = h.y; } }
;                 *(u32x4*)(WSB(OFF_ACT) + (size_t)r * DFF + ac0) = w;
;             }
	v_rcp_f32_e32 v34, v34
	v_rcp_f32_e32 v35, v35
	v_pk_mul_f32 v[26:27], v[26:27], v[66:67] op_sel_hi:[1,0]
	v_pk_mul_f32 v[24:25], v[24:25], v[66:67] op_sel_hi:[1,0]
	v_pk_mul_f32 v[30:31], v[30:31], v[32:33]
	v_pk_mul_f32 v[28:29], v[28:29], v[34:35]
	v_pk_mul_f32 v[24:25], v[24:25], v[30:31]
	v_pk_mul_f32 v[26:27], v[26:27], v[28:29]
	v_pk_mul_f32 v[20:21], v[20:21], v[66:67] op_sel_hi:[1,0]
	v_cvt_pk_bf16_f32 v24, v24, v25
	v_cvt_pk_bf16_f32 v25, v26, v27
	v_pk_mul_f32 v[22:23], v[22:23], v[66:67] op_sel_hi:[1,0]
	v_mul_f32_e32 v26, 0xbfb8aa3b, v20
	v_mul_f32_e32 v27, 0xbfb8aa3b, v21
	v_exp_f32_e32 v26, v26
	v_exp_f32_e32 v27, v27
	v_mul_f32_e32 v28, 0xbfb8aa3b, v22
	v_mul_f32_e32 v29, 0xbfb8aa3b, v23
	v_exp_f32_e32 v28, v28
	v_exp_f32_e32 v29, v29
	v_add_f32_e32 v26, 1.0, v26
	v_add_f32_e32 v27, 1.0, v27
	v_rcp_f32_e32 v26, v26
	v_rcp_f32_e32 v27, v27
	v_add_f32_e32 v28, 1.0, v28
	v_add_f32_e32 v29, 1.0, v29
	v_rcp_f32_e32 v28, v28
	v_rcp_f32_e32 v29, v29
	v_fmamk_f32 v64, v149, 0x3a000000, v163
	v_rsq_f32_e32 v64, v64
	v_pk_mul_f32 v[12:13], v[12:13], v[66:67] op_sel_hi:[1,0]
	v_pk_mul_f32 v[20:21], v[20:21], v[26:27]
	v_pk_mul_f32 v[14:15], v[14:15], v[66:67] op_sel_hi:[1,0]
	v_pk_mul_f32 v[12:13], v[12:13], v[20:21]
	v_pk_mul_f32 v[20:21], v[22:23], v[28:29]
	v_cvt_pk_bf16_f32 v26, v12, v13
	v_pk_mul_f32 v[14:15], v[14:15], v[20:21]
	v_mad_i64_i32 v[12:13], s[24:25], v144, s55, v[140:141]
	v_cvt_pk_bf16_f32 v27, v14, v15
	v_lshl_add_u64 v[12:13], v[12:13], 0, v[142:143]
	global_store_dwordx4 v[12:13], v[24:27], off
	v_pk_mul_f32 v[12:13], v[18:19], v[64:65] op_sel_hi:[1,0]
	v_pk_mul_f32 v[14:15], v[16:17], v[64:65] op_sel_hi:[1,0]
	v_mul_f32_e32 v18, 0xbfb8aa3b, v12
	v_mul_f32_e32 v16, 0xbfb8aa3b, v14
	v_mul_f32_e32 v17, 0xbfb8aa3b, v15
	v_mul_f32_e32 v19, 0xbfb8aa3b, v13
	v_exp_f32_e32 v16, v16
	v_exp_f32_e32 v17, v17
	v_exp_f32_e32 v18, v18
	v_exp_f32_e32 v19, v19
	v_add_f32_e32 v16, 1.0, v16
	v_add_f32_e32 v17, 1.0, v17
	v_add_f32_e32 v18, 1.0, v18
	v_add_f32_e32 v19, 1.0, v19
	v_rcp_f32_e32 v16, v16
	v_rcp_f32_e32 v17, v17
	v_rcp_f32_e32 v18, v18
	v_rcp_f32_e32 v19, v19
	v_pk_mul_f32 v[10:11], v[10:11], v[64:65] op_sel_hi:[1,0]
	v_pk_mul_f32 v[8:9], v[8:9], v[64:65] op_sel_hi:[1,0]
	v_pk_mul_f32 v[14:15], v[14:15], v[16:17]
	v_pk_mul_f32 v[12:13], v[12:13], v[18:19]
	v_pk_mul_f32 v[8:9], v[8:9], v[14:15]
	v_pk_mul_f32 v[10:11], v[10:11], v[12:13]
	v_pk_mul_f32 v[4:5], v[4:5], v[64:65] op_sel_hi:[1,0]
	v_cvt_pk_bf16_f32 v8, v8, v9
	v_cvt_pk_bf16_f32 v9, v10, v11
	v_pk_mul_f32 v[6:7], v[6:7], v[64:65] op_sel_hi:[1,0]
	v_mul_f32_e32 v10, 0xbfb8aa3b, v4
	v_mul_f32_e32 v11, 0xbfb8aa3b, v5
	v_exp_f32_e32 v10, v10
	v_exp_f32_e32 v11, v11
	v_mul_f32_e32 v12, 0xbfb8aa3b, v6
	v_mul_f32_e32 v13, 0xbfb8aa3b, v7
	v_exp_f32_e32 v12, v12
	v_exp_f32_e32 v13, v13
	v_add_f32_e32 v10, 1.0, v10
	v_add_f32_e32 v11, 1.0, v11
	v_rcp_f32_e32 v10, v10
	v_rcp_f32_e32 v11, v11
	v_add_f32_e32 v12, 1.0, v12
	v_add_f32_e32 v13, 1.0, v13
	v_rcp_f32_e32 v12, v12
	v_rcp_f32_e32 v13, v13
	v_pk_mul_f32 v[0:1], v[0:1], v[64:65] op_sel_hi:[1,0]
	v_pk_mul_f32 v[4:5], v[4:5], v[10:11]
	v_pk_mul_f32 v[2:3], v[2:3], v[64:65] op_sel_hi:[1,0]
	v_pk_mul_f32 v[0:1], v[0:1], v[4:5]
	v_pk_mul_f32 v[4:5], v[6:7], v[12:13]
	v_cvt_pk_bf16_f32 v10, v0, v1
	v_pk_mul_f32 v[2:3], v[2:3], v[4:5]
	v_mad_i64_i32 v[0:1], s[24:25], v138, s55, v[140:141]
	v_cvt_pk_bf16_f32 v11, v2, v3
	v_lshl_add_u64 v[0:1], v[0:1], 0, v[142:143]
	global_store_dwordx4 v[0:1], v[8:11], off
	s_cbranch_vccz .LBB0_1257
	s_waitcnt vmcnt(0)
	s_cmpk_gt_u32 s88, 0xff
	s_cbranch_scc1 .LBB0_1264
	s_barrier

; DI u32x2 pk4(f32x4 v) { u32x2 r; r.x = pk2(v[0], v[1]); r.y = pk2(v[2], v[3]); return r; }
; DI float bf_lo(unsigned w) { return __uint_as_float(w << 16); }
; DI float bf_hi(unsigned w) { return __uint_as_float(w & 0xffff0000u); }
; #define COLS4 _Pragma("unroll") for (int bj = 0; bj < 2; ++bj) _Pragma("unroll") for (int n = 0; n < 2; ++n)
;     DI void operator()(const Acc& acc, const Unit& u, int wr, int wc, int fr, int fq) const {
;     ...
;             for (int ai = 0; ai < 2; ++ai) if (ai == 0 || !hf) {
;                 f32x4 xo[4][2][2];
; #pragma unroll
;                 for (int m = 0; m < 4; ++m) { const size_t o = (size_t)(row0 + ai * HALF + m * 16) * 2048 + colp;
;                     if (PH == 4) { COLS4 xo[m][bj][n] = *(const f32x4*)(p.x + o + bj * HALF + n * 4); }
;                     else {
; #pragma unroll
;                         for (int bj = 0; bj < 2; ++bj) { const u32x4 w = *(const u32x4*)(WSB(OFF_XB) + o + bj * HALF);
;                             xo[m][bj][0] = (f32x4){bf_lo(w.x), bf_hi(w.x), bf_lo(w.y), bf_hi(w.y)}; xo[m][bj][1] = (f32x4){bf_lo(w.z), bf_hi(w.z), bf_lo(w.w), bf_hi(w.w)}; } } }
; #pragma unroll
;                 for (int m = 0; m < 4; ++m) { const int r = row0 + ai * HALF + m * 16; const size_t o = (size_t)r * 2048 + colp; float part = 0.f;
; #pragma unroll
;                     for (int bj = 0; bj < 2; ++bj) { const f32x4 x0 = xo[m][bj][0] + acc[ai][bj][m][0], x1 = xo[m][bj][1] + acc[ai][bj][m][1];
;                         const u32x2 h0 = pk4(x0), h1 = pk4(x1);
;                         *(u32x4*)(WSB(OFF_XB) + o + bj * HALF) = (u32x4){h0.x, h0.y, h1.x, h1.y};
;                         part += x0[0] * x0[0] + x0[1] * x0[1] + x0[2] * x0[2] + x0[3] * x0[3] + x1[0] * x1[0] + x1[1] * x1[1] + x1[2] * x1[2] + x1[3] * x1[3]; }
;                     part += __shfl_xor(part, 16); part += __shfl_xor(part, 32);
;                     if (fq == 0) unsafeAtomicAdd(ssq + r, part);
.Lkrot_8_exit:
	s_barrier
.Lpeel_8_exit:
	v_lshl_add_u32 v128, s58, 8, v182
	v_lshl_add_u32 v166, s59, 8, v180
	v_ashrrev_i32_e32 v129, 31, v128
	v_lshlrev_b64 v[162:163], 1, v[128:129]
	v_ashrrev_i32_e32 v167, 31, v166
	v_lshl_add_u64 v[164:165], s[16:17], 0, v[162:163]
	v_lshlrev_b64 v[196:197], 12, v[166:167]
	v_lshl_add_u64 v[128:129], v[164:165], 0, v[196:197]
	global_load_dwordx4 v[188:191], v[128:129], off
	global_load_dwordx4 v[192:195], v[128:129], off offset:256
	v_or_b32_e32 v176, 16, v166
	v_or_b32_e32 v172, 32, v166
	v_or_b32_e32 v168, 48, v166
	v_ashrrev_i32_e32 v177, 31, v176
	v_ashrrev_i32_e32 v173, 31, v172
	v_ashrrev_i32_e32 v169, 31, v168
	v_lshlrev_b64 v[178:179], 12, v[176:177]
	v_lshlrev_b64 v[174:175], 12, v[172:173]
	v_lshlrev_b64 v[170:171], 12, v[168:169]
	v_lshl_add_u64 v[128:129], v[164:165], 0, v[178:179]
	v_lshl_add_u64 v[130:131], v[164:165], 0, v[174:175]
	v_lshl_add_u64 v[198:199], v[164:165], 0, v[170:171]
	global_load_dwordx4 v[148:151], v[128:129], off
	global_load_dwordx4 v[144:147], v[128:129], off offset:256
	global_load_dwordx4 v[140:143], v[130:131], off
	global_load_dwordx4 v[136:139], v[130:131], off offset:256
	global_load_dwordx4 v[132:135], v[198:199], off
	s_nop 0
	global_load_dwordx4 v[128:131], v[198:199], off offset:256
	v_lshl_add_u64 v[198:199], s[16:17], 0, v[196:197]
	v_lshl_add_u64 v[198:199], v[198:199], 0, v[162:163]
	v_lshl_add_u64 v[196:197], s[10:11], 0, v[196:197]
	v_lshl_add_u64 v[196:197], v[196:197], 0, v[162:163]
	s_waitcnt vmcnt(0)
	v_lshlrev_b32_e32 v200, 16, v188
	v_and_b32_e32 v201, 0xffff0000, v188
	v_lshlrev_b32_e32 v188, 16, v189
	v_and_b32_e32 v189, 0xffff0000, v189
	v_lshlrev_b32_e32 v204, 16, v192
	v_and_b32_e32 v205, 0xffff0000, v192
	v_lshlrev_b32_e32 v192, 16, v193
	v_and_b32_e32 v193, 0xffff0000, v193
	v_lshlrev_b32_e32 v206, 16, v194
	v_and_b32_e32 v207, 0xffff0000, v194
	v_pk_add_f32 v[126:127], v[126:127], v[188:189]
	v_pk_add_f32 v[124:125], v[124:125], v[200:201]
	v_pk_add_f32 v[188:189], v[116:117], v[204:205]
	v_pk_add_f32 v[118:119], v[118:119], v[192:193]
	v_pk_add_f32 v[192:193], v[112:113], v[206:207]
	v_cvt_pk_bf16_f32 v112, v124, v125
	v_mul_f32_e32 v117, v125, v125
	v_mul_f32_e32 v125, v189, v189
	v_fmac_f32_e32 v117, v124, v124
	v_fmac_f32_e32 v125, v188, v188
	v_lshlrev_b32_e32 v202, 16, v190
	v_and_b32_e32 v203, 0xffff0000, v190
	v_fmac_f32_e32 v117, v126, v126
	v_fmac_f32_e32 v125, v118, v118
	v_pk_add_f32 v[120:121], v[120:121], v[202:203]
	v_fmac_f32_e32 v117, v127, v127
	v_fmac_f32_e32 v125, v119, v119
	v_lshlrev_b32_e32 v190, 16, v191
	v_and_b32_e32 v191, 0xffff0000, v191
	v_lshlrev_b32_e32 v194, 16, v195
	v_and_b32_e32 v195, 0xffff0000, v195
	v_fmac_f32_e32 v117, v120, v120
	v_fmac_f32_e32 v125, v192, v192
	v_pk_add_f32 v[122:123], v[122:123], v[190:191]
	v_pk_add_f32 v[190:191], v[114:115], v[194:195]
	v_fmac_f32_e32 v117, v121, v121
	v_fmac_f32_e32 v125, v193, v193
	v_fmac_f32_e32 v117, v122, v122
	v_fmac_f32_e32 v125, v190, v190
	v_fmac_f32_e32 v117, v123, v123
	v_fmac_f32_e32 v125, v191, v191
	v_cvt_pk_bf16_f32 v114, v120, v121
	v_add_f32_e32 v120, v117, v125
	ds_bpermute_b32 v121, v183, v120
	v_cvt_pk_bf16_f32 v113, v126, v127
	v_cvt_pk_bf16_f32 v115, v122, v123
	global_store_dwordx4 v[198:199], v[112:115], off sc1
	v_cvt_pk_bf16_f32 v116, v188, v189
	v_cvt_pk_bf16_f32 v117, v118, v119
	s_waitcnt lgkmcnt(0)
	v_add_f32_e32 v112, v120, v121
	ds_bpermute_b32 v113, v184, v112
	v_add_co_u32_e32 v114, vcc, s55, v196
	v_cvt_pk_bf16_f32 v118, v192, v193
	v_cvt_pk_bf16_f32 v119, v190, v191
	v_addc_co_u32_e32 v115, vcc, 0, v197, vcc
	global_store_dwordx4 v[114:115], v[116:119], off offset:256 sc1
	s_and_saveexec_b64 s[22:23], s[2:3]
	s_cbranch_execz .LBB0_1343
	s_waitcnt lgkmcnt(0)
	v_add_f32_e32 v114, v112, v113
	v_lshl_add_u64 v[112:113], v[166:167], 2, s[14:15]
	global_atomic_add_f32 v[112:113], v114, off
